# sel body + imp DPP shuffles + flat->global + write-through (sc0 sc1) for 16-byte stores
# speedup vs baseline: 1.0181x; 1.0181x over previous
; #define LAS __attribute__((address_space(3)))
; __global__ void __launch_bounds__(NTHREADS, 2) mega_fwd(Args a_unused) {
;     ...
;     {
;         LAS float* sc = (LAS float*)(lds + 131072);
;         for (int i = tid; i < 2 * D; i += NTHREADS) { const float cv = ap->in[1][i]; sc[i] = cv / (1.f + expf(-cv)); }
;         __syncthreads();
;         LAS float* red = (LAS float*)lds;
;         for (int cb = bx; cb < 256; cb += G) {
;             const int col = tid % 36, kc = tid / 36, j = 36 * cb + col;
.LBB0_7:
	s_or_b64 exec, exec, s[4:5]
	s_mov_b64 s[38:39], s[0:1]
	v_lshlrev_b32_e32 v180, 2, v144
	v_mov_b64_e32 v[0:1], s[38:39]
	global_load_dwordx2 v[0:1], v[0:1], off offset:200
	v_mov_b64_e32 v[2:3], s[38:39]
	v_add_u32_e32 v178, 0xfffffe00, v144
	v_mov_b32_e32 v145, 0
	v_add_u32_e32 v179, 0, v180
	v_readfirstlane_b32 s3, v144
	s_mov_b64 s[4:5], 0
	s_mov_b32 s8, 0xbfb8aa3b
	s_mov_b32 s9, 0x42ce8ed0
	s_mov_b32 s10, 0xc2b17218
	s_mov_b64 s[6:7], 0x800
	s_movk_i32 s11, 0x5ff
	v_mov_b32_e32 v4, v178
	s_waitcnt vmcnt(0) lgkmcnt(0)
	v_readfirstlane_b32 s31, v1
	v_readfirstlane_b32 s30, v0
	global_load_dwordx2 v[0:1], v[2:3], off offset:8
	v_mov_b32_e32 v2, 0x7f800000
	v_add_u32_e32 v3, 0x20000, v179
	s_waitcnt vmcnt(0) lgkmcnt(0)
	v_lshl_add_u64 v[0:1], v[144:145], 2, v[0:1]
.LBB0_8:
	global_load_dword v5, v[0:1], off
	v_add_u32_e32 v4, 0x200, v4
	v_cmp_lt_u32_e32 vcc, s11, v4
	s_or_b64 s[4:5], vcc, s[4:5]
	v_lshl_add_u64 v[0:1], v[0:1], 0, s[6:7]
	s_waitcnt vmcnt(0) lgkmcnt(0)
	v_mul_f32_e32 v6, 0xbfb8aa3b, v5
	v_rndne_f32_e32 v7, v6
	v_fma_f32 v8, v5, s8, -v6
	v_sub_f32_e32 v6, v6, v7
	v_fmac_f32_e32 v8, 0xb2a5705f, v5
	v_add_f32_e32 v6, v6, v8
	v_cvt_i32_f32_e32 v7, v7
	v_exp_f32_e32 v6, v6
	v_cmp_nlt_f32_e32 vcc, s9, v5
	v_ldexp_f32 v6, v6, v7
	s_nop 0
	v_cndmask_b32_e32 v6, 0, v6, vcc
	v_cmp_ngt_f32_e32 vcc, s10, v5
	s_nop 1
	v_cndmask_b32_e32 v6, v2, v6, vcc
	v_add_f32_e32 v6, 1.0, v6
	v_div_scale_f32 v7, s[12:13], v6, v6, v5
	v_rcp_f32_e32 v8, v7
	v_div_scale_f32 v9, vcc, v5, v6, v5
	v_fma_f32 v10, -v7, v8, 1.0
	v_fmac_f32_e32 v8, v10, v8
	v_mul_f32_e32 v10, v9, v8
	v_fma_f32 v11, -v7, v10, v9
	v_fmac_f32_e32 v10, v11, v8
	v_fma_f32 v7, -v7, v10, v9
	v_div_fmas_f32 v7, v7, v8, v10
	v_div_fixup_f32 v5, v7, v6, v5
	ds_write_b32 v3, v5
	v_add_u32_e32 v3, 0x800, v3
	s_andn2_b64 exec, exec, s[4:5]
	s_cbranch_execnz .LBB0_8
	s_or_b64 exec, exec, s[4:5]
	s_cmpk_lt_i32 s2, 0x100
	v_lshlrev_b32_e32 v11, 3, v144
	s_cselect_b64 s[36:37], -1, 0
	s_cmpk_gt_i32 s2, 0xff
	v_lshrrev_b32_e32 v140, 1, v144
	s_waitcnt lgkmcnt(0)
	s_barrier
	s_cbranch_scc1 .LBB0_34
	v_and_b32_e32 v5, 1, v144
	v_mul_u32_u24_e32 v0, 0x2400, v5
	v_lshlrev_b32_e32 v0, 2, v0
	v_mov_b32_e32 v1, 0
	v_lshl_add_u64 v[2:3], s[30:31], 0, v[0:1]
	v_mov_b32_e32 v141, v1
	s_mov_b32 s6, 0xe38f
	v_lshl_add_u64 v[0:1], v[140:141], 2, v[2:3]
	v_mul_u32_u24_sdwa v2, v144, s6 dst_sel:DWORD dst_unused:UNUSED_PAD src0_sel:WORD_0 src1_sel:DWORD
	v_lshrrev_b32_e32 v2, 21, v2
	s_mov_b32 s8, 0x38e38e39
	v_mul_lo_u16_e32 v3, 36, v2
	v_add_u32_e32 v13, 0x62, v2
	v_mul_hi_u32 v2, v144, s8
	s_movk_i32 s4, 0x1f8
	v_sub_u16_e32 v4, v144, v3
	s_movk_i32 s6, 0x48
	v_lshl_add_u32 v6, v5, 2, 0
	v_lshlrev_b32_e32 v7, 3, v140
	v_lshrrev_b32_e32 v5, 3, v2
	s_mov_b32 s8, 0x9000
	v_mov_b64_e32 v[2:3], 0x372000
	v_cmp_gt_u32_e64 s[4:5], s4, v144
	v_cmp_gt_u32_e64 s[6:7], s6, v144
	v_mad_u64_u32 v[2:3], s[8:9], v5, s8, v[2:3]
	v_mad_u64_u32 v[4:5], s[8:9], s2, 36, v[4:5]
	s_mul_i32 s44, s28, 36
	s_movk_i32 s45, 0x400
	s_add_i32 s46, 0, 0x20000
	s_mov_b64 s[34:35], 0x3f0000
	v_add_u32_e32 v15, v6, v7
	s_mov_b32 s47, s2
	s_branch .LBB0_12

; __global__ void __launch_bounds__(NTHREADS, 2) mega_fwd(Args a_unused) {
;     ...
;         for (int cb = bx; cb < 256; cb += G) {
;             const int col = tid % 36, kc = tid / 36, j = 36 * cb + col;
;             if (kc < 14) {
;                 float a0 = 0.f, a1 = 0.f;
;                 const float* wcol = ap->in[2] + j;
; #pragma nounroll
.LBB0_12:
	s_and_saveexec_b64 s[40:41], s[4:5]
	s_cbranch_execz .LBB0_32
	v_mov_b64_e32 v[6:7], s[38:39]
	global_load_dwordx2 v[6:7], v[6:7], off offset:16
	v_ashrrev_i32_e32 v5, 31, v4
	v_mov_b32_e32 v8, 0
	s_mov_b32 s48, 0
	v_mov_b32_e32 v17, v13
	v_mov_b32_e32 v9, v8
	s_waitcnt vmcnt(0) lgkmcnt(0)
	v_lshl_add_u64 v[6:7], v[6:7], 0, v[2:3]
	v_lshl_add_u64 v[6:7], v[4:5], 2, v[6:7]
	s_branch .LBB0_15

; __global__ void __launch_bounds__(NTHREADS, 2) mega_fwd(Args a_unused) {
;     ...
;                 for (int i0 = 0; i0 < 80; i0 += 8) {
;                     float w[8];
; #pragma unroll
;                     for (int u_ = 0; u_ < 8; ++u_) { const int k = kc + 14 * (i0 + u_); w[u_] = (k < D) ? wcol[(size_t)k * NMOD] : 0.f; }
.LBB0_15:
	s_cmpk_lt_u32 s48, 0x4a
	s_cselect_b64 s[8:9], -1, 0
	s_cmpk_gt_u32 s48, 0x49
	v_mov_b32_e32 v10, 0
	s_cbranch_scc1 .LBB0_17
	v_add_co_u32_e32 v18, vcc, 0xffc8e000, v6
	s_nop 1
	v_addc_co_u32_e32 v19, vcc, -1, v7, vcc
	global_load_dword v10, v[18:19], off
.LBB0_17:
	v_add_u32_e32 v5, 0xffffffac, v17
	v_cmp_gt_u32_e64 s[10:11], s45, v5
	v_mov_b32_e32 v12, 0
	v_mov_b32_e32 v14, 0
	s_and_saveexec_b64 s[12:13], s[10:11]
	s_cbranch_execz .LBB0_19
	v_add_co_u32_e32 v18, vcc, 0xffd0c000, v6
	s_nop 1
	v_addc_co_u32_e32 v19, vcc, -1, v7, vcc
	global_load_dword v14, v[18:19], off
.LBB0_19:
	s_or_b64 exec, exec, s[12:13]
	v_add_u32_e32 v19, 0xffffffba, v17
	v_cmp_gt_u32_e64 s[12:13], s45, v19
	s_and_saveexec_b64 s[14:15], s[12:13]
	s_cbranch_execz .LBB0_21
	v_add_co_u32_e32 v20, vcc, 0xffd8a000, v6
	s_nop 1
	v_addc_co_u32_e32 v21, vcc, -1, v7, vcc
	global_load_dword v12, v[20:21], off
.LBB0_21:
	s_or_b64 exec, exec, s[14:15]
	v_subrev_u32_e32 v21, 56, v17
	v_cmp_gt_u32_e64 s[14:15], s45, v21
	v_mov_b32_e32 v16, 0
	v_mov_b32_e32 v18, 0
	s_and_saveexec_b64 s[16:17], s[14:15]
	s_cbranch_execz .LBB0_23
	v_add_co_u32_e32 v22, vcc, 0xffe08000, v6
	s_nop 1
	v_addc_co_u32_e32 v23, vcc, -1, v7, vcc
	global_load_dword v18, v[22:23], off
.LBB0_23:
	s_or_b64 exec, exec, s[16:17]
	v_subrev_u32_e32 v23, 42, v17
	v_cmp_gt_u32_e64 s[16:17], s45, v23
	s_and_saveexec_b64 s[18:19], s[16:17]
	s_cbranch_execz .LBB0_25
	v_add_co_u32_e32 v24, vcc, 0xffe86000, v6
	s_nop 1
	v_addc_co_u32_e32 v25, vcc, -1, v7, vcc
	global_load_dword v16, v[24:25], off
.LBB0_25:
	s_or_b64 exec, exec, s[18:19]
	v_subrev_u32_e32 v25, 28, v17
	v_cmp_gt_u32_e64 s[18:19], s45, v25
	v_mov_b32_e32 v20, 0
	v_mov_b32_e32 v22, 0
	s_and_saveexec_b64 s[20:21], s[18:19]
	s_cbranch_execz .LBB0_27
	v_add_co_u32_e32 v26, vcc, 0xfff04000, v6
	s_nop 1
	v_addc_co_u32_e32 v27, vcc, -1, v7, vcc
	global_load_dword v22, v[26:27], off
.LBB0_27:
	s_or_b64 exec, exec, s[20:21]
	v_add_u32_e32 v26, -14, v17
	v_cmp_gt_u32_e64 s[20:21], s45, v26
	s_and_saveexec_b64 s[42:43], s[20:21]
	s_cbranch_execz .LBB0_29
	v_add_co_u32_e32 v28, vcc, 0xfff82000, v6
	s_nop 1
	v_addc_co_u32_e32 v29, vcc, -1, v7, vcc
	global_load_dword v20, v[28:29], off
.LBB0_29:
	s_or_b64 exec, exec, s[42:43]
	v_cmp_gt_u32_e32 vcc, s45, v17
	v_mov_b32_e32 v24, 0
	v_mov_b32_e32 v27, 0
	s_and_saveexec_b64 s[42:43], vcc
	s_cbranch_execz .LBB0_14
	global_load_dword v24, v[6:7], off
	v_mov_b32_e32 v27, v17
	s_branch .LBB0_14

; __global__ void __launch_bounds__(NTHREADS, 2) mega_fwd(Args a_unused) {
;     ...
;             __syncthreads();
;             if (tid < 72) { const int c2 = tid >> 1, bb = tid & 1; float s = ap->in[3][36 * cb + c2];
;                 for (int q = 0; q < 14; ++q) s += red[(q * 36 + c2) * 2 + bb];
;                 mod[(size_t)bb * NMOD + 36 * cb + c2] = s; }
;             __syncthreads();
;         }
;         { asm volatile("s_waitcnt vmcnt(0)" ::: "memory"); __syncthreads();
;           if (tid == 0) { __builtin_amdgcn_fence(__ATOMIC_RELEASE, "agent"); asm volatile("s_waitcnt vmcnt(0)" ::: "memory");
;                           __hip_atomic_fetch_add((unsigned*)(ws + WS_CTL) + MODCNT_WORD, 1u, __ATOMIC_RELAXED, __HIP_MEMORY_SCOPE_AGENT); } }
.LBB0_32:
	s_or_b64 exec, exec, s[40:41]
	s_waitcnt lgkmcnt(0)
	s_barrier
	s_and_saveexec_b64 s[8:9], s[6:7]
	s_cbranch_execz .LBB0_11
	v_mov_b64_e32 v[6:7], s[38:39]
	global_load_dwordx2 v[6:7], v[6:7], off offset:24
	s_mul_i32 s10, s47, 36
	v_add_u32_e32 v8, s10, v140
	v_ashrrev_i32_e32 v9, 31, v8
	v_add_u32_e32 v10, 0x400, v15
	v_add_u32_e32 v24, 0xc00, v15
	v_add_u32_e32 v12, 0x800, v15
	v_add_u32_e32 v14, 0xa00, v15
	s_ashr_i32 s11, s10, 31
	s_waitcnt vmcnt(0) lgkmcnt(0)
	v_lshl_add_u64 v[6:7], v[8:9], 2, v[6:7]
	global_load_dword v5, v[6:7], off
	ds_read2_b32 v[6:7], v15 offset1:72
	ds_read2_b32 v[8:9], v15 offset0:144 offset1:216
	ds_read2_b32 v[16:17], v10 offset0:32 offset1:104
	ds_read2_b32 v[18:19], v10 offset0:176 offset1:248
	ds_read2_b32 v[20:21], v12 offset0:64 offset1:136
	ds_read2_b32 v[22:23], v14 offset0:80 offset1:152
	ds_read2_b32 v[24:25], v24 offset0:96 offset1:168
	s_waitcnt vmcnt(0) lgkmcnt(0)
	v_add_f32_e32 v5, v5, v6
	v_add_f32_e32 v5, v5, v7
	v_add_f32_e32 v5, v5, v8
	v_add_f32_e32 v5, v5, v9
	v_add_f32_e32 v5, v5, v16
	v_add_f32_e32 v5, v5, v17
	v_add_f32_e32 v5, v5, v18
	v_add_f32_e32 v5, v5, v19
	v_add_f32_e32 v5, v5, v20
	v_add_f32_e32 v5, v5, v21
	v_add_f32_e32 v5, v5, v22
	v_add_f32_e32 v5, v5, v23
	v_add_f32_e32 v5, v5, v24
	v_add_f32_e32 v5, v5, v25
	v_lshl_add_u64 v[6:7], s[10:11], 2, v[0:1]
	global_store_dword v[6:7], v5, off
	s_branch .LBB0_11
.LBB0_34:
	s_waitcnt vmcnt(0)
	s_add_u32 s8, s30, 0xd3800
	s_addc_u32 s9, s31, 0
	s_barrier
	s_and_saveexec_b64 s[4:5], s[22:23]
	s_cbranch_execz .LBB0_36
	buffer_wbl2 sc1
	s_waitcnt vmcnt(0)
	s_waitcnt vmcnt(0)
	v_mov_b32_e32 v2, 1
	v_mov_b64_e32 v[0:1], s[8:9]
	global_atomic_add v[0:1], v2, off

; __global__ void __launch_bounds__(NTHREADS, 2) mega_fwd(Args a_unused) {
;     ...
;         for (int o = gw; o < 512; o += NGW) {
;             const int which = o >> 8, j = o & 255; const float* pe = ap->in[which ? 13 : 10]; const float* w1 = ap->in[which ? 14 : 11];
;             float s = 0.f;
; #pragma unroll 8
;             for (int k = lane; k < 2048; k += 64) s += pe[k] * w1[(size_t)k * 256 + j];
;             s = wave_sum(s);
;             if (lane == 0) posb[which * 256 + j] = s;
;         }
.LBB0_39:
	s_and_b32 s10, s35, 0xff
	s_lshl_b32 s10, s10, 2
	s_cmpk_lt_u32 s16, 0x100
	s_cselect_b32 s17, s40, 0x68
	s_cselect_b32 s43, s41, 0x70
	s_add_u32 s18, s38, s17
	s_addc_u32 s19, s39, 0
	s_waitcnt lgkmcnt(0)
	v_mov_b64_e32 v[2:3], s[18:19]
	s_add_u32 s18, s38, s43
	s_addc_u32 s19, s39, 0
	v_mov_b64_e32 v[4:5], s[18:19]
	global_load_dwordx2 v[16:17], v[2:3], off
	global_load_dwordx2 v[18:19], v[4:5], off
	v_mov_b32_e32 v14, 0
	s_mov_b64 s[18:19], 0
	v_mov_b32_e32 v15, v13
	s_waitcnt vmcnt(0) lgkmcnt(0)
	v_lshl_add_u64 v[2:3], v[16:17], 0, v[142:143]
	v_lshl_add_u64 v[4:5], v[18:19], 0, v[0:1]
	v_lshl_add_u64 v[4:5], v[4:5], 0, s[10:11]
.LBB0_40:
	v_add_co_u32_e32 v16, vcc, 0xfff90000, v4
	global_load_dword v22, v[2:3], off
	global_load_dword v23, v[2:3], off offset:256
	global_load_dword v24, v[2:3], off offset:512
	global_load_dword v25, v[2:3], off offset:768
	global_load_dword v26, v[2:3], off offset:1024
	global_load_dword v27, v[2:3], off offset:1280
	global_load_dword v28, v[2:3], off offset:1536
	global_load_dword v29, v[2:3], off offset:1792
	v_addc_co_u32_e32 v17, vcc, -1, v5, vcc
	v_add_co_u32_e32 v18, vcc, 0xfffa0000, v4
	global_load_dword v30, v[16:17], off
	s_nop 0
	v_addc_co_u32_e32 v19, vcc, -1, v5, vcc
	v_add_co_u32_e32 v16, vcc, 0xfffb0000, v4
	v_add_u32_e32 v15, 0x200, v15
	s_nop 0
	v_addc_co_u32_e32 v17, vcc, -1, v5, vcc
	v_add_co_u32_e32 v20, vcc, 0xfffc0000, v4
	global_load_dword v31, v[18:19], off
	global_load_dword v32, v[16:17], off
	v_addc_co_u32_e32 v21, vcc, -1, v5, vcc
	v_add_co_u32_e32 v16, vcc, 0xfffd0000, v4
	v_lshl_add_u64 v[2:3], v[2:3], 0, s[14:15]
	s_nop 0
	v_addc_co_u32_e32 v17, vcc, -1, v5, vcc
	v_add_co_u32_e32 v18, vcc, 0xfffe0000, v4
	global_load_dword v33, v[20:21], off
	global_load_dword v34, v[16:17], off
	v_addc_co_u32_e32 v19, vcc, -1, v5, vcc
	v_add_co_u32_e32 v16, vcc, 0xffff0000, v4
	s_waitcnt vmcnt(0) lgkmcnt(0)
	v_fmac_f32_e32 v14, v22, v30
	v_addc_co_u32_e32 v17, vcc, -1, v5, vcc
	global_load_dword v20, v[18:19], off
	global_load_dword v21, v[16:17], off
	global_load_dword v35, v[4:5], off
	v_cmp_lt_u32_e32 vcc, s42, v15
	s_or_b64 s[18:19], vcc, s[18:19]
	v_lshl_add_u64 v[4:5], v[4:5], 0, s[12:13]
	v_fmac_f32_e32 v14, v23, v31
	v_fmac_f32_e32 v14, v24, v32
	v_fmac_f32_e32 v14, v25, v33
	v_fmac_f32_e32 v14, v26, v34
	s_waitcnt vmcnt(0) lgkmcnt(0)
	v_fmac_f32_e32 v14, v27, v20
	v_fmac_f32_e32 v14, v28, v21
	v_fmac_f32_e32 v14, v29, v35
	s_andn2_b64 exec, exec, s[18:19]
	s_cbranch_execnz .LBB0_40
	s_or_b64 exec, exec, s[18:19]
	ds_bpermute_b32 v2, v6, v14
	s_waitcnt lgkmcnt(0)
	v_add_f32_e32 v2, v14, v2
	ds_bpermute_b32 v3, v7, v2
	s_waitcnt lgkmcnt(0)
	v_add_f32_e32 v2, v2, v3
	ds_bpermute_b32 v3, v8, v2
	s_waitcnt lgkmcnt(0)
	v_add_f32_e32 v2, v2, v3
	ds_bpermute_b32 v3, v9, v2
	s_waitcnt lgkmcnt(0)
	v_add_f32_e32 v2, v2, v3
	ds_bpermute_b32 v3, v10, v2
	s_waitcnt lgkmcnt(0)
	v_add_f32_e32 v2, v2, v3
	ds_bpermute_b32 v3, v12, v2
	s_and_saveexec_b64 s[18:19], s[4:5]
	s_cbranch_execz .LBB0_38
	s_ashr_i32 s17, s16, 31
	s_lshl_b64 s[44:45], s[16:17], 2
	s_add_u32 s44, s20, s44
	s_addc_u32 s45, s21, s45
	s_waitcnt lgkmcnt(0)
	v_add_f32_e32 v4, v2, v3
	v_mov_b64_e32 v[2:3], s[44:45]
	global_store_dword v[2:3], v4, off
	s_branch .LBB0_38

; __global__ void __launch_bounds__(NTHREADS, 2) mega_fwd(Args a_unused) {
;     ...
;         for (int e = bx * NTHREADS + tid; e < 8192 * 24; e += G * NTHREADS) {
;             const int pos = e / 24, i = e % 24; double iv = 0.0;
; #pragma unroll
;             for (int q = 0; q < 8; ++q) if (i == q) iv = ap->inv8[q];
; #pragma unroll
;             for (int q = 0; q < 16; ++q) if (i == 8 + q) iv = ap->inv16[q];
;             float c_, s_; rope_cs(pos, iv, c_, s_);
;             if (i < 8) { CS8[pos * 16 + i] = c_; CS8[pos * 16 + 8 + i] = s_; } else { CS16[pos * 32 + (i - 8)] = c_; CS16[pos * 32 + 16 + (i - 8)] = s_; }
.LBB0_45:
	s_or_b64 exec, exec, s[16:17]
	v_sin_f32_e32 v1, v3
	v_add_u32_e32 v0, s18, v0
	v_lshl_add_u64 v[4:5], s[30:31], 0, v[4:5]
	v_ashrrev_i32_e32 v3, 31, v2
	v_cmp_lt_i32_e32 vcc, s21, v0
	v_lshl_add_u64 v[2:3], v[2:3], 2, v[4:5]
	s_or_b64 s[14:15], vcc, s[14:15]
	global_store_dword v[2:3], v1, off
	s_andn2_b64 exec, exec, s[14:15]
	s_cbranch_execz .LBB0_98

; __device__ __forceinline__ void rope_cs(int pos, double invrev, float& c, float& s) {
;     double a = (double)pos * invrev; a -= __builtin_floor(a); const float f = (float)a;
;     s = __builtin_amdgcn_sinf(f); c = __builtin_amdgcn_cosf(f);
; }
; __global__ void __launch_bounds__(NTHREADS, 2) mega_fwd(Args a_unused) {
;     ...
;             const int pos = e / 24, i = e % 24; double iv = 0.0;
; #pragma unroll
;             for (int q = 0; q < 8; ++q) if (i == q) iv = ap->inv8[q];
; #pragma unroll
;             for (int q = 0; q < 16; ++q) if (i == 8 + q) iv = ap->inv16[q];
;             float c_, s_; rope_cs(pos, iv, c_, s_);
;             if (i < 8) { CS8[pos * 16 + i] = c_; CS8[pos * 16 + 8 + i] = s_; } else { CS16[pos * 32 + (i - 8)] = c_; CS16[pos * 32 + 16 + (i - 8)] = s_; }
.LBB0_70:
	s_waitcnt vmcnt(0) lgkmcnt(0)
	v_mov_b64_e32 v[4:5], s[38:39]
	global_load_dwordx2 v[4:5], v[4:5], off offset:392
.LBB0_71:
	s_or_b64 exec, exec, s[16:17]
	v_cvt_f64_i32_e32 v[6:7], v1
	s_waitcnt vmcnt(0) lgkmcnt(0)
	v_mul_f64 v[8:9], v[4:5], v[6:7]
	v_floor_f64_e32 v[8:9], v[8:9]
	v_fma_f64 v[4:5], v[4:5], v[6:7], -v[8:9]
	v_cvt_f32_f64_e32 v3, v[4:5]
	v_cos_f32_e32 v6, v3
	v_cmp_lt_i32_e32 vcc, 7, v2
	v_lshlrev_b32_e32 v7, 3, v1
	s_and_saveexec_b64 s[16:17], vcc
	s_xor_b64 s[16:17], exec, s[16:17]
	s_cbranch_execz .LBB0_73
	v_add3_u32 v4, v0, v7, -8
	v_mul_lo_u32 v2, v1, 24
	v_ashrrev_i32_e32 v5, 31, v4
	v_sub_u32_e32 v2, v0, v2
	v_lshlrev_b32_e32 v1, 5, v1
	v_lshl_add_u64 v[4:5], v[4:5], 2, s[10:11]
	global_store_dword v[4:5], v6, off
	v_add3_u32 v2, v2, v1, 8
.LBB0_73:
	s_or_saveexec_b64 s[16:17], s[16:17]
	v_mov_b64_e32 v[4:5], 0x3900000
	s_xor_b64 exec, exec, s[16:17]
	s_cbranch_execz .LBB0_45
	v_sub_u32_e32 v4, v0, v7
	v_ashrrev_i32_e32 v5, 31, v4
	v_lshl_add_u64 v[8:9], v[4:5], 2, s[12:13]
	v_add_u32_e32 v2, 8, v4
	v_mov_b64_e32 v[4:5], 0x40000
	global_store_dword v[8:9], v6, off
	s_branch .LBB0_45
.LBB0_75:
	v_mov_b64_e32 v[4:5], s[38:39]
	global_load_dwordx2 v[4:5], v[4:5], off offset:208
	s_or_b64 exec, exec, s[16:17]
	v_cmp_eq_u32_e32 vcc, 0, v3
	s_and_saveexec_b64 s[16:17], vcc
	s_cbranch_execz .LBB0_48
.LBB0_76:
	s_waitcnt vmcnt(0) lgkmcnt(0)
	v_mov_b64_e32 v[4:5], s[38:39]
	global_load_dwordx2 v[4:5], v[4:5], off offset:216
	s_or_b64 exec, exec, s[16:17]
	v_cmp_eq_u32_e32 vcc, 2, v2
	s_and_saveexec_b64 s[16:17], vcc
	s_cbranch_execz .LBB0_49
.LBB0_77:
	s_waitcnt vmcnt(0) lgkmcnt(0)
	v_mov_b64_e32 v[4:5], s[38:39]
	global_load_dwordx2 v[4:5], v[4:5], off offset:224
	s_or_b64 exec, exec, s[16:17]
	v_cmp_eq_u32_e32 vcc, 3, v2
	s_and_saveexec_b64 s[16:17], vcc
	s_cbranch_execz .LBB0_50
.LBB0_78:
	s_waitcnt vmcnt(0) lgkmcnt(0)
	v_mov_b64_e32 v[4:5], s[38:39]
	global_load_dwordx2 v[4:5], v[4:5], off offset:232
	s_or_b64 exec, exec, s[16:17]
	v_cmp_eq_u32_e32 vcc, 4, v2
	s_and_saveexec_b64 s[16:17], vcc
	s_cbranch_execz .LBB0_51
.LBB0_79:
	s_waitcnt vmcnt(0) lgkmcnt(0)
	v_mov_b64_e32 v[4:5], s[38:39]
	global_load_dwordx2 v[4:5], v[4:5], off offset:240
	s_or_b64 exec, exec, s[16:17]
	v_cmp_eq_u32_e32 vcc, 5, v2
	s_and_saveexec_b64 s[16:17], vcc
	s_cbranch_execz .LBB0_52
.LBB0_80:
	s_waitcnt vmcnt(0) lgkmcnt(0)
	v_mov_b64_e32 v[4:5], s[38:39]
	global_load_dwordx2 v[4:5], v[4:5], off offset:248
	s_or_b64 exec, exec, s[16:17]
	v_cmp_eq_u32_e32 vcc, 6, v2
	s_and_saveexec_b64 s[16:17], vcc
	s_cbranch_execz .LBB0_53
.LBB0_81:
	s_waitcnt vmcnt(0) lgkmcnt(0)
	v_mov_b64_e32 v[4:5], s[38:39]
	global_load_dwordx2 v[4:5], v[4:5], off offset:256
	s_or_b64 exec, exec, s[16:17]
	v_cmp_eq_u32_e32 vcc, 7, v2
	s_and_saveexec_b64 s[16:17], vcc
	s_cbranch_execz .LBB0_54
.LBB0_82:
	s_waitcnt vmcnt(0) lgkmcnt(0)
	v_mov_b64_e32 v[4:5], s[38:39]
	global_load_dwordx2 v[4:5], v[4:5], off offset:264
	s_or_b64 exec, exec, s[16:17]
	v_cmp_eq_u32_e32 vcc, 8, v2
	s_and_saveexec_b64 s[16:17], vcc
	s_cbranch_execz .LBB0_55
.LBB0_83:
	s_waitcnt vmcnt(0) lgkmcnt(0)
	v_mov_b64_e32 v[4:5], s[38:39]
	global_load_dwordx2 v[4:5], v[4:5], off offset:272
	s_or_b64 exec, exec, s[16:17]
	v_cmp_eq_u32_e32 vcc, 9, v2
	s_and_saveexec_b64 s[16:17], vcc
	s_cbranch_execz .LBB0_56
.LBB0_84:
	s_waitcnt vmcnt(0) lgkmcnt(0)
	v_mov_b64_e32 v[4:5], s[38:39]
	global_load_dwordx2 v[4:5], v[4:5], off offset:280
	s_or_b64 exec, exec, s[16:17]
	v_cmp_eq_u32_e32 vcc, 10, v2
	s_and_saveexec_b64 s[16:17], vcc
	s_cbranch_execz .LBB0_57
.LBB0_85:
	s_waitcnt vmcnt(0) lgkmcnt(0)
	v_mov_b64_e32 v[4:5], s[38:39]
	global_load_dwordx2 v[4:5], v[4:5], off offset:288
	s_or_b64 exec, exec, s[16:17]
	v_cmp_eq_u32_e32 vcc, 11, v2
	s_and_saveexec_b64 s[16:17], vcc
	s_cbranch_execz .LBB0_58
.LBB0_86:
	s_waitcnt vmcnt(0) lgkmcnt(0)
	v_mov_b64_e32 v[4:5], s[38:39]
	global_load_dwordx2 v[4:5], v[4:5], off offset:296
	s_or_b64 exec, exec, s[16:17]
	v_cmp_eq_u32_e32 vcc, 12, v2
	s_and_saveexec_b64 s[16:17], vcc
	s_cbranch_execz .LBB0_59
.LBB0_87:
	s_waitcnt vmcnt(0) lgkmcnt(0)
	v_mov_b64_e32 v[4:5], s[38:39]
	global_load_dwordx2 v[4:5], v[4:5], off offset:304
	s_or_b64 exec, exec, s[16:17]
	v_cmp_eq_u32_e32 vcc, 13, v2
	s_and_saveexec_b64 s[16:17], vcc
	s_cbranch_execz .LBB0_60
.LBB0_88:
	s_waitcnt vmcnt(0) lgkmcnt(0)
	v_mov_b64_e32 v[4:5], s[38:39]
	global_load_dwordx2 v[4:5], v[4:5], off offset:312
	s_or_b64 exec, exec, s[16:17]
	v_cmp_eq_u32_e32 vcc, 14, v2
	s_and_saveexec_b64 s[16:17], vcc
	s_cbranch_execz .LBB0_61
.LBB0_89:
	s_waitcnt vmcnt(0) lgkmcnt(0)
	v_mov_b64_e32 v[4:5], s[38:39]
	global_load_dwordx2 v[4:5], v[4:5], off offset:320
	s_or_b64 exec, exec, s[16:17]
	v_cmp_eq_u32_e32 vcc, 15, v2
	s_and_saveexec_b64 s[16:17], vcc
	s_cbranch_execz .LBB0_62
.LBB0_90:
	s_waitcnt vmcnt(0) lgkmcnt(0)
	v_mov_b64_e32 v[4:5], s[38:39]
	global_load_dwordx2 v[4:5], v[4:5], off offset:328
	s_or_b64 exec, exec, s[16:17]
	v_cmp_eq_u32_e32 vcc, 16, v2
	s_and_saveexec_b64 s[16:17], vcc
	s_cbranch_execz .LBB0_63
.LBB0_91:
	s_waitcnt vmcnt(0) lgkmcnt(0)
	v_mov_b64_e32 v[4:5], s[38:39]
	global_load_dwordx2 v[4:5], v[4:5], off offset:336
	s_or_b64 exec, exec, s[16:17]
	v_cmp_eq_u32_e32 vcc, 17, v2
	s_and_saveexec_b64 s[16:17], vcc
	s_cbranch_execz .LBB0_64
.LBB0_92:
	s_waitcnt vmcnt(0) lgkmcnt(0)
	v_mov_b64_e32 v[4:5], s[38:39]
	global_load_dwordx2 v[4:5], v[4:5], off offset:344
	s_or_b64 exec, exec, s[16:17]
	v_cmp_eq_u32_e32 vcc, 18, v2
	s_and_saveexec_b64 s[16:17], vcc
	s_cbranch_execz .LBB0_65
.LBB0_93:
	s_waitcnt vmcnt(0) lgkmcnt(0)
	v_mov_b64_e32 v[4:5], s[38:39]
	global_load_dwordx2 v[4:5], v[4:5], off offset:352
	s_or_b64 exec, exec, s[16:17]
	v_cmp_eq_u32_e32 vcc, 19, v2
	s_and_saveexec_b64 s[16:17], vcc
	s_cbranch_execz .LBB0_66
.LBB0_94:
	s_waitcnt vmcnt(0) lgkmcnt(0)
	v_mov_b64_e32 v[4:5], s[38:39]
	global_load_dwordx2 v[4:5], v[4:5], off offset:360
	s_or_b64 exec, exec, s[16:17]
	v_cmp_eq_u32_e32 vcc, 20, v2
	s_and_saveexec_b64 s[16:17], vcc
	s_cbranch_execz .LBB0_67
.LBB0_95:
	s_waitcnt vmcnt(0) lgkmcnt(0)
	v_mov_b64_e32 v[4:5], s[38:39]
	global_load_dwordx2 v[4:5], v[4:5], off offset:368
	s_or_b64 exec, exec, s[16:17]
	v_cmp_eq_u32_e32 vcc, 21, v2
	s_and_saveexec_b64 s[16:17], vcc
	s_cbranch_execz .LBB0_68
.LBB0_96:
	s_waitcnt vmcnt(0) lgkmcnt(0)
	v_mov_b64_e32 v[4:5], s[38:39]
	global_load_dwordx2 v[4:5], v[4:5], off offset:376
	s_or_b64 exec, exec, s[16:17]
	v_cmp_eq_u32_e32 vcc, 22, v2
	s_and_saveexec_b64 s[16:17], vcc
	s_cbranch_execz .LBB0_69
.LBB0_97:
	s_waitcnt vmcnt(0) lgkmcnt(0)
	v_mov_b64_e32 v[4:5], s[38:39]
	global_load_dwordx2 v[4:5], v[4:5], off offset:384
	s_or_b64 exec, exec, s[16:17]
	v_cmp_eq_u32_e32 vcc, 23, v2
	s_and_saveexec_b64 s[16:17], vcc
	s_cbranch_execnz .LBB0_70
	s_branch .LBB0_71

; #define LAS __attribute__((address_space(3)))
; #define LDS_WAIT() asm volatile("s_waitcnt lgkmcnt(0)" ::: "memory")
; #define TR_TRY(CNT, NBLK, ...) if (r < (CNT)) { const int k0 = 64 * (r / (NBLK)), n0 = 32 * (r % (NBLK)); (void)k0; (void)n0; __VA_ARGS__; continue; } r -= (CNT);
; #define TR_TRY(CNT, NBLK, ...) if (r < (CNT)) { const int k0 = 64 * (r / (NBLK)), n0 = 32 * (r % (NBLK)); (void)k0; (void)n0; __VA_ARGS__; continue; } r -= (CNT);
; __device__ __forceinline__ void tr_item(const float* W, int N, int k0, int n0, bf16* WT, int Kd, int drow0, int dk0, LAS float* scr, int lane) {
;     {
;         float wv[32]; const int n = n0 + (lane & 31); const float* wp = W + (size_t)(k0 + (lane >> 5)) * N + n;
; #pragma unroll
;         for (int i = 0; i < 32; ++i) wv[i] = (n < N) ? wp[(size_t)(2 * i) * N] : 0.f;
; #pragma unroll
;         for (int i = 0; i < 32; ++i) scr[(2 * i + (lane >> 5)) * 33 + (lane & 31)] = wv[i];
;     }
;     LDS_WAIT();
; __global__ void __launch_bounds__(NTHREADS, 2) mega_fwd(Args a_unused) {
;     ...
;         for (int it = gw; it < NITEMS; it += NGW) {
;             int r = it;
;     ...
;             TR_TRY(I_GU, FF / 32, tr_item(ap->in[6], FF, k0, n0, Wgu1, D, (n0 / 128) * 256 + (n0 % 128), k0, scr, lane))
;             TR_TRY(I_GU, FF / 32, tr_item(ap->in[7], FF, k0, n0, Wgu1, D, (n0 / 128) * 256 + 128 + (n0 % 128), k0, scr, lane))
;             TR_TRY(I_WD, D / 32, tr_item(ap->in[8], D, k0, n0, Wd1, FF, n0, k0, scr, lane))
;             TR_TRY(I_IN, DINP / 32, tr_item(ap->in[9], DIN, k0, n0, Win, D, n0, k0, scr, lane))
;             TR_TRY(I_W1, 256 / 32, tr_item(ap->in[11], 256, k0, n0, W1k, 1024, (k0 >= 1024 ? 256 : 0) + n0, k0 & 1023, scr, lane))
;             TR_TRY(I_W1, 256 / 32, tr_item(ap->in[14], 256, k0, n0, W1v, 1024, (k0 >= 1024 ? 256 : 0) + n0, k0 & 1023, scr, lane))
;             TR_TRY(I_UQ, 768 / 32, { const int hq = n0 / 96, jq = (n0 % 96) / 32; tr_item(ap->in[18], 768, k0, n0, Wuq, 384, jq < 2 ? hq * 64 + 32 * jq : 512 + hq * 32, k0, scr, lane); })
;             TR_TRY(I_UKV, 1024 / 32, { const int hk = n0 / 128, ek = n0 % 128; tr_item(ap->in[19], 1024, k0, n0, Wukv, 256, ek < 64 ? hk * 64 + ek : 512 + hk * 64 + (ek - 64), k0, scr, lane); })
.LBB0_101:
	s_cmpk_gt_i32 s97, 0x57f
	s_mov_b64 s[4:5], -1
	s_cbranch_scc0 .LBB0_191
	s_cmpk_gt_u32 s97, 0xaff
	s_cbranch_scc0 .LBB0_188
	s_cmpk_gt_u32 s97, 0x107f
	s_cbranch_scc0 .LBB0_185
	s_cmpk_gt_u32 s97, 0x147f
	s_cbranch_scc0 .LBB0_118
	s_cmpk_gt_u32 s97, 0x157f
	s_cbranch_scc0 .LBB0_115
	s_cmpk_gt_u32 s97, 0x167f
	s_cbranch_scc0 .LBB0_112
	s_cmpk_gt_u32 s97, 0x170f
	s_cbranch_scc0 .LBB0_109
	v_mov_b64_e32 v[16:17], s[38:39]
	global_load_dwordx2 v[16:17], v[16:17], off offset:152
	s_and_b32 s5, s17, 0x7fffffc0
	s_add_i32 s4, s7, 0xfffd1e00
	s_and_b32 s13, s4, 0x3e0
	v_or_b32_e32 v0, s5, v159
	v_or_b32_e32 v27, s13, v158
	v_lshlrev_b64 v[28:29], 12, v[0:1]
	v_lshlrev_b32_e32 v0, 2, v27
	s_mov_b32 s10, 0x14000
	s_mov_b32 s12, 0x1a000
	s_and_b32 s4, s4, 0x60
	s_waitcnt vmcnt(0) lgkmcnt(0)
	v_lshl_add_u64 v[16:17], v[16:17], 0, v[28:29]
	v_lshl_add_u64 v[16:17], v[16:17], 0, v[0:1]
	v_add_co_u32_e32 v28, vcc, s21, v16
	s_nop 1
	v_addc_co_u32_e32 v29, vcc, 0, v17, vcc
	v_add_co_u32_e32 v30, vcc, s35, v16
	s_nop 1
	v_addc_co_u32_e32 v31, vcc, 0, v17, vcc
	v_add_co_u32_e32 v32, vcc, s40, v16
	s_nop 1
	v_addc_co_u32_e32 v33, vcc, 0, v17, vcc
	v_add_co_u32_e32 v34, vcc, s41, v16
	s_nop 1
	v_addc_co_u32_e32 v35, vcc, 0, v17, vcc
	v_add_co_u32_e32 v36, vcc, s42, v16
	s_nop 1
	v_addc_co_u32_e32 v37, vcc, 0, v17, vcc
	v_add_co_u32_e32 v38, vcc, s43, v16
	s_nop 1
	v_addc_co_u32_e32 v39, vcc, 0, v17, vcc
	v_add_co_u32_e32 v40, vcc, s44, v16
	s_nop 1
	v_addc_co_u32_e32 v41, vcc, 0, v17, vcc
	v_add_co_u32_e32 v42, vcc, s45, v16
	s_nop 1
	v_addc_co_u32_e32 v43, vcc, 0, v17, vcc
	v_add_co_u32_e32 v44, vcc, s46, v16
	s_nop 1
	v_addc_co_u32_e32 v45, vcc, 0, v17, vcc
	v_add_co_u32_e32 v46, vcc, s10, v16
	s_mov_b32 s10, 0x20000
	s_nop 0
	v_addc_co_u32_e32 v47, vcc, 0, v17, vcc
	v_add_co_u32_e32 v48, vcc, s47, v16
	s_nop 1
	v_addc_co_u32_e32 v49, vcc, 0, v17, vcc
	v_add_co_u32_e32 v50, vcc, s48, v16
	s_nop 1
	v_addc_co_u32_e32 v51, vcc, 0, v17, vcc
	v_add_co_u32_e32 v52, vcc, s12, v16
	s_nop 1
	v_addc_co_u32_e32 v53, vcc, 0, v17, vcc
	v_add_co_u32_e32 v54, vcc, s49, v16
	s_nop 1
	v_addc_co_u32_e32 v55, vcc, 0, v17, vcc
	v_add_co_u32_e32 v56, vcc, s50, v16
	s_nop 1
	v_addc_co_u32_e32 v57, vcc, 0, v17, vcc
	global_load_dword v0, v[16:17], off
	global_load_dword v27, v[28:29], off
	global_load_dword v58, v[30:31], off
	global_load_dword v59, v[32:33], off
	global_load_dword v60, v[34:35], off
	global_load_dword v61, v[36:37], off
	global_load_dword v62, v[38:39], off
	global_load_dword v63, v[40:41], off
	global_load_dword v64, v[42:43], off
	s_nop 0
	global_load_dword v44, v[44:45], off
	s_nop 0
	global_load_dword v45, v[46:47], off
	s_nop 0
	global_load_dword v46, v[48:49], off
	global_load_dword v47, v[50:51], off
	s_nop 0
	global_load_dword v48, v[52:53], off
	global_load_dword v49, v[54:55], off
	global_load_dword v50, v[56:57], off
	v_add_co_u32_e32 v28, vcc, s10, v16
	s_mov_b32 s10, 0x30000
	s_nop 0
	v_addc_co_u32_e32 v29, vcc, 0, v17, vcc
	v_add_co_u32_e32 v30, vcc, s51, v16
	s_nop 1
	v_addc_co_u32_e32 v31, vcc, 0, v17, vcc
	v_add_co_u32_e32 v32, vcc, s52, v16
	s_nop 1
	v_addc_co_u32_e32 v33, vcc, 0, v17, vcc
	v_add_co_u32_e32 v34, vcc, s53, v16
	s_nop 1
	v_addc_co_u32_e32 v35, vcc, 0, v17, vcc
	v_add_co_u32_e32 v36, vcc, s54, v16
	s_nop 1
	v_addc_co_u32_e32 v37, vcc, 0, v17, vcc
	v_add_co_u32_e32 v38, vcc, s55, v16
	s_nop 1
	v_addc_co_u32_e32 v39, vcc, 0, v17, vcc
	v_add_co_u32_e32 v40, vcc, s56, v16
	s_nop 1
	v_addc_co_u32_e32 v41, vcc, 0, v17, vcc
	v_add_co_u32_e32 v42, vcc, s57, v16
	s_nop 1
	v_addc_co_u32_e32 v43, vcc, 0, v17, vcc
	global_load_dword v51, v[28:29], off
	global_load_dword v52, v[30:31], off
	global_load_dword v53, v[32:33], off
	global_load_dword v54, v[34:35], off
	global_load_dword v55, v[36:37], off
	global_load_dword v56, v[38:39], off
	global_load_dword v57, v[40:41], off
	s_nop 0
	global_load_dword v42, v[42:43], off
	v_add_co_u32_e32 v28, vcc, s10, v16
	s_mov_b32 s10, 0x32000
	s_nop 0
	v_addc_co_u32_e32 v29, vcc, 0, v17, vcc
	v_add_co_u32_e32 v30, vcc, s10, v16
	s_mov_b32 s10, 0x34000
	s_nop 0
	v_addc_co_u32_e32 v31, vcc, 0, v17, vcc
	v_add_co_u32_e32 v32, vcc, s10, v16
	s_mov_b32 s10, 0x36000
	s_nop 0
	v_addc_co_u32_e32 v33, vcc, 0, v17, vcc
	v_add_co_u32_e32 v34, vcc, s10, v16
	s_mov_b32 s10, 0x38000
	s_nop 0
	v_addc_co_u32_e32 v35, vcc, 0, v17, vcc
	v_add_co_u32_e32 v36, vcc, s10, v16
	s_mov_b32 s10, 0x3a000
	s_nop 0
	v_addc_co_u32_e32 v37, vcc, 0, v17, vcc
	v_add_co_u32_e32 v38, vcc, s10, v16
	s_mov_b32 s10, 0x3e000
	s_nop 0
	v_addc_co_u32_e32 v39, vcc, 0, v17, vcc
	v_add_co_u32_e32 v40, vcc, s58, v16
	s_nop 1
	v_addc_co_u32_e32 v41, vcc, 0, v17, vcc
	v_add_co_u32_e32 v16, vcc, s10, v16
	s_and_b32 s10, s15, 0x1c0
	s_nop 0
	v_addc_co_u32_e32 v17, vcc, 0, v17, vcc
	global_load_dword v28, v[28:29], off
	s_nop 0
	global_load_dword v29, v[30:31], off
	s_nop 0
	global_load_dword v30, v[32:33], off
	global_load_dword v31, v[34:35], off
	s_nop 0
	global_load_dword v32, v[36:37], off
	global_load_dword v33, v[38:39], off
	global_load_dword v34, v[40:41], off
	s_nop 0
	global_load_dword v16, v[16:17], off
	s_waitcnt vmcnt(0) lgkmcnt(0)
	ds_write2_b32 v18, v0, v27 offset1:66
	ds_write2_b32 v18, v58, v59 offset0:132 offset1:198
	ds_write2_b32 v20, v60, v61 offset0:8 offset1:74
	ds_write2_b32 v20, v62, v63 offset0:140 offset1:206
	ds_write2_b32 v21, v64, v44 offset0:16 offset1:82
	ds_write2_b32 v21, v45, v46 offset0:148 offset1:214
	ds_write2_b32 v22, v47, v48 offset0:24 offset1:90
	ds_write2_b32 v22, v49, v50 offset0:156 offset1:222
	ds_write2_b32 v23, v51, v52 offset0:32 offset1:98
	ds_write2_b32 v23, v53, v54 offset0:164 offset1:230
	ds_write2_b32 v24, v55, v56 offset0:40 offset1:106
	ds_write2_b32 v24, v57, v42 offset0:172 offset1:238
	ds_write2_b32 v25, v28, v29 offset0:48 offset1:114
	ds_write2_b32 v25, v30, v31 offset0:180 offset1:246
	ds_write2_b32 v26, v32, v33 offset0:56 offset1:122
	ds_write2_b32 v26, v34, v16 offset0:188 offset1:254
	s_waitcnt lgkmcnt(0)
; #define LAS __attribute__((address_space(3)))
; #define LDS_WAIT() asm volatile("s_waitcnt lgkmcnt(0)" ::: "memory")
; __device__ __forceinline__ unsigned pk2(float lo, float hi) { return f2bf(lo) | (f2bf(hi) << 16); }
; __device__ __forceinline__ void tr_item(const float* W, int N, int k0, int n0, bf16* WT, int Kd, int drow0, int dk0, LAS float* scr, int lane) {
;     ...
;     LDS_WAIT();
;     const int c = lane & 7;
; #pragma unroll
;     for (int j = 0; j < 4; ++j) { const int n = (lane >> 3) + 8 * j; const LAS float* s = scr + (8 * c) * 33 + n;
;         v4u o; o.x = pk2(s[0 * 33], s[1 * 33]); o.y = pk2(s[2 * 33], s[3 * 33]); o.z = pk2(s[4 * 33], s[5 * 33]); o.w = pk2(s[6 * 33], s[7 * 33]);
;         *(v4u*)(WT + (size_t)(drow0 + n) * Kd + dk0 + 8 * c) = o; }
;     LDS_WAIT();
	ds_read_b32 v0, v19
	ds_read_b32 v27, v19 offset:132
	ds_read_b32 v29, v19 offset:264
	ds_read_b32 v30, v19 offset:396
	ds_read_b32 v31, v19 offset:528
	ds_read_b32 v32, v19 offset:660
	ds_read_b32 v33, v19 offset:792
	ds_read_b32 v34, v19 offset:924
	s_waitcnt lgkmcnt(7)
	v_bfe_u32 v28, v0, 16, 1
	v_add3_u32 v0, v0, v28, s59
	s_waitcnt lgkmcnt(6)
	v_bfe_u32 v28, v27, 16, 1
	v_lshrrev_b32_e32 v0, 16, v0
	v_add3_u32 v27, v27, v28, s59
	v_and_or_b32 v28, v27, s60, v0
	s_waitcnt lgkmcnt(5)
	v_bfe_u32 v0, v29, 16, 1
	v_add3_u32 v0, v29, v0, s59
	s_waitcnt lgkmcnt(4)
	v_bfe_u32 v27, v30, 16, 1
	v_lshrrev_b32_e32 v0, 16, v0
	v_add3_u32 v27, v30, v27, s59
	v_and_or_b32 v29, v27, s60, v0
	s_waitcnt lgkmcnt(3)
	v_bfe_u32 v0, v31, 16, 1
	v_add3_u32 v0, v31, v0, s59
	s_waitcnt lgkmcnt(2)
	v_bfe_u32 v27, v32, 16, 1
	s_or_b32 s12, s10, s4
	s_add_i32 s10, s4, s10
	v_lshrrev_b32_e32 v0, 16, v0
	v_add3_u32 v27, v32, v27, s59
	s_addk_i32 s10, 0x1c0
	v_and_or_b32 v30, v27, s60, v0
	s_waitcnt lgkmcnt(1)
	v_bfe_u32 v0, v33, 16, 1
	s_cmp_lt_u32 s4, 64
	v_add3_u32 v0, v33, v0, s59
	s_waitcnt lgkmcnt(0)
	v_bfe_u32 v27, v34, 16, 1
	s_cselect_b32 s4, s12, s10
	v_lshrrev_b32_e32 v0, 16, v0
	v_add3_u32 v27, v34, v27, s59
	s_lshl_b32 s10, s5, 1
	v_and_or_b32 v31, v27, s60, v0
	v_or_b32_e32 v0, s4, v160
	v_lshl_add_u64 v[16:17], v[2:3], 0, s[10:11]
	v_lshlrev_b32_e32 v0, 9, v0
	v_lshl_add_u64 v[32:33], v[16:17], 0, v[0:1]
	global_store_dwordx4 v[32:33], v[28:31], off sc0 sc1
	ds_read_b32 v0, v19 offset:32
	ds_read_b32 v27, v19 offset:164
	ds_read_b32 v29, v19 offset:296
	ds_read_b32 v30, v19 offset:428
	ds_read_b32 v31, v19 offset:560
	ds_read_b32 v32, v19 offset:692
	ds_read_b32 v33, v19 offset:824
	ds_read_b32 v34, v19 offset:956
	s_waitcnt lgkmcnt(0)
	v_bfe_u32 v28, v0, 16, 1
	v_add3_u32 v0, v0, v28, s59
	v_bfe_u32 v28, v27, 16, 1
	v_lshrrev_b32_e32 v0, 16, v0
	v_add3_u32 v27, v27, v28, s59
	v_and_or_b32 v28, v27, s60, v0
	v_bfe_u32 v0, v29, 16, 1
	v_add3_u32 v0, v29, v0, s59
	v_bfe_u32 v27, v30, 16, 1
	v_lshrrev_b32_e32 v0, 16, v0
	v_add3_u32 v27, v30, v27, s59
	v_and_or_b32 v29, v27, s60, v0
	v_bfe_u32 v0, v31, 16, 1
	v_add3_u32 v0, v31, v0, s59
	v_bfe_u32 v27, v32, 16, 1
	v_lshrrev_b32_e32 v0, 16, v0
	v_add3_u32 v27, v32, v27, s59
	v_and_or_b32 v30, v27, s60, v0
	v_bfe_u32 v0, v33, 16, 1
	v_add3_u32 v0, v33, v0, s59
	v_bfe_u32 v27, v34, 16, 1
	v_lshrrev_b32_e32 v0, 16, v0
	v_add3_u32 v27, v34, v27, s59
	v_and_or_b32 v31, v27, s60, v0
	v_or_b32_e32 v0, s4, v161
	v_lshlrev_b32_e32 v0, 9, v0
	v_lshl_add_u64 v[32:33], v[16:17], 0, v[0:1]
	global_store_dwordx4 v[32:33], v[28:31], off sc0 sc1
	ds_read_b32 v0, v19 offset:64
	ds_read_b32 v27, v19 offset:196
	ds_read_b32 v29, v19 offset:328
	ds_read_b32 v30, v19 offset:460
	ds_read_b32 v31, v19 offset:592
	ds_read_b32 v32, v19 offset:724
	ds_read_b32 v33, v19 offset:856
	ds_read_b32 v34, v19 offset:988
	s_waitcnt lgkmcnt(0)
	v_bfe_u32 v28, v0, 16, 1
	v_add3_u32 v0, v0, v28, s59
	v_bfe_u32 v28, v27, 16, 1
	v_lshrrev_b32_e32 v0, 16, v0
	v_add3_u32 v27, v27, v28, s59
	v_and_or_b32 v28, v27, s60, v0
	v_bfe_u32 v0, v29, 16, 1
	v_add3_u32 v0, v29, v0, s59
	v_bfe_u32 v27, v30, 16, 1
	v_lshrrev_b32_e32 v0, 16, v0
	v_add3_u32 v27, v30, v27, s59
	v_and_or_b32 v29, v27, s60, v0
	v_bfe_u32 v0, v31, 16, 1
	v_add3_u32 v0, v31, v0, s59
	v_bfe_u32 v27, v32, 16, 1
	v_lshrrev_b32_e32 v0, 16, v0
	v_add3_u32 v27, v32, v27, s59
	v_and_or_b32 v30, v27, s60, v0
	v_bfe_u32 v0, v33, 16, 1
	v_add3_u32 v0, v33, v0, s59
	v_bfe_u32 v27, v34, 16, 1
	v_lshrrev_b32_e32 v0, 16, v0
	v_add3_u32 v27, v34, v27, s59
	v_and_or_b32 v31, v27, s60, v0
	v_or_b32_e32 v0, s4, v162
	v_lshlrev_b32_e32 v0, 9, v0
	v_lshl_add_u64 v[32:33], v[16:17], 0, v[0:1]
	global_store_dwordx4 v[32:33], v[28:31], off sc0 sc1
	ds_read_b32 v0, v19 offset:96
	ds_read_b32 v27, v19 offset:228
	ds_read_b32 v29, v19 offset:360
	ds_read_b32 v30, v19 offset:492
	ds_read_b32 v31, v19 offset:624
	ds_read_b32 v32, v19 offset:756
	ds_read_b32 v33, v19 offset:888
	ds_read_b32 v34, v19 offset:1020
	s_waitcnt lgkmcnt(0)
	v_bfe_u32 v28, v0, 16, 1
	v_add3_u32 v0, v0, v28, s59
	v_bfe_u32 v28, v27, 16, 1
	v_lshrrev_b32_e32 v0, 16, v0
	v_add3_u32 v27, v27, v28, s59
	v_and_or_b32 v28, v27, s60, v0
	v_bfe_u32 v0, v29, 16, 1
	v_add3_u32 v0, v29, v0, s59
	v_bfe_u32 v27, v30, 16, 1
	v_lshrrev_b32_e32 v0, 16, v0
	v_add3_u32 v27, v30, v27, s59
	v_and_or_b32 v29, v27, s60, v0
	v_bfe_u32 v0, v31, 16, 1
	v_add3_u32 v0, v31, v0, s59
	v_bfe_u32 v27, v32, 16, 1
	v_lshrrev_b32_e32 v0, 16, v0
	v_add3_u32 v27, v32, v27, s59
	v_and_or_b32 v30, v27, s60, v0
	v_bfe_u32 v0, v33, 16, 1
	v_add3_u32 v0, v33, v0, s59
	v_bfe_u32 v27, v34, 16, 1
	v_lshrrev_b32_e32 v0, 16, v0
	v_add3_u32 v27, v34, v27, s59
	v_and_or_b32 v31, v27, s60, v0
	v_or_b32_e32 v0, s4, v163
	v_lshlrev_b32_e32 v0, 9, v0
	v_lshl_add_u64 v[16:17], v[16:17], 0, v[0:1]
	global_store_dwordx4 v[16:17], v[28:31], off sc0 sc1
	s_waitcnt lgkmcnt(0)
	s_mov_b64 s[4:5], 0
; #define LAS __attribute__((address_space(3)))
; #define TR_TRY(CNT, NBLK, ...) if (r < (CNT)) { const int k0 = 64 * (r / (NBLK)), n0 = 32 * (r % (NBLK)); (void)k0; (void)n0; __VA_ARGS__; continue; } r -= (CNT);
; #define TR_TRY(CNT, NBLK, ...) if (r < (CNT)) { const int k0 = 64 * (r / (NBLK)), n0 = 32 * (r % (NBLK)); (void)k0; (void)n0; __VA_ARGS__; continue; } r -= (CNT);
; __device__ __forceinline__ void tr_item(const float* W, int N, int k0, int n0, bf16* WT, int Kd, int drow0, int dk0, LAS float* scr, int lane) {
;     {
;         float wv[32]; const int n = n0 + (lane & 31); const float* wp = W + (size_t)(k0 + (lane >> 5)) * N + n;
; #pragma unroll
;         for (int i = 0; i < 32; ++i) wv[i] = (n < N) ? wp[(size_t)(2 * i) * N] : 0.f;
; #pragma unroll
;         for (int i = 0; i < 32; ++i) scr[(2 * i + (lane >> 5)) * 33 + (lane & 31)] = wv[i];
;     }
; __global__ void __launch_bounds__(NTHREADS, 2) mega_fwd(Args a_unused) {
;     ...
;             TR_TRY(I_UQ, 768 / 32, { const int hq = n0 / 96, jq = (n0 % 96) / 32; tr_item(ap->in[18], 768, k0, n0, Wuq, 384, jq < 2 ? hq * 64 + 32 * jq : 512 + hq * 32, k0, scr, lane); })
.LBB0_109:
	s_andn2_b64 vcc, exec, s[4:5]
	s_cbranch_vccnz .LBB0_111
	v_mov_b64_e32 v[16:17], s[38:39]
	global_load_dwordx2 v[16:17], v[16:17], off offset:144
	s_xor_b32 s4, s97, 0xff80
	s_and_b32 s5, s4, 0xff
	s_mulk_i32 s5, 0xab
	s_bfe_u32 s5, s5, 0x4000c
	s_mul_i32 s10, s5, 24
	s_sub_i32 s4, s4, s10
	v_lshl_or_b32 v0, s5, 6, v159
	s_and_b32 s10, s4, 0xff
	v_mul_u32_u24_e32 v0, 0x300, v0
	s_lshl_b32 s4, s10, 5
	v_lshlrev_b32_e32 v0, 2, v0
	v_or_b32_e32 v27, s4, v158
	s_mov_b32 s12, 0x13000
	s_mov_b32 s13, 0x15000
	s_waitcnt vmcnt(0) lgkmcnt(0)
	v_lshl_add_u64 v[16:17], v[16:17], 0, v[0:1]
	v_lshlrev_b32_e32 v0, 2, v27
	v_lshl_add_u64 v[16:17], v[16:17], 0, v[0:1]
	v_add_co_u32_e32 v28, vcc, s61, v16
	s_nop 1
	v_addc_co_u32_e32 v29, vcc, 0, v17, vcc
	v_add_co_u32_e32 v30, vcc, s62, v16
	s_nop 1
	v_addc_co_u32_e32 v31, vcc, 0, v17, vcc
	v_add_co_u32_e32 v32, vcc, s35, v16
	s_nop 1
	v_addc_co_u32_e32 v33, vcc, 0, v17, vcc
	v_add_co_u32_e32 v34, vcc, s40, v16
	s_nop 1
	v_addc_co_u32_e32 v35, vcc, 0, v17, vcc
	v_add_co_u32_e32 v36, vcc, s63, v16
	s_nop 1
	v_addc_co_u32_e32 v37, vcc, 0, v17, vcc
	v_add_co_u32_e32 v38, vcc, s64, v16
	s_nop 1
	v_addc_co_u32_e32 v39, vcc, 0, v17, vcc
	v_add_co_u32_e32 v40, vcc, s42, v16
	s_nop 1
	v_addc_co_u32_e32 v41, vcc, 0, v17, vcc
	v_add_co_u32_e32 v42, vcc, s43, v16
	global_load_dword v0, v[16:17], off
	global_load_dword v27, v[28:29], off offset:2048
	global_load_dword v56, v[30:31], off
	global_load_dword v57, v[32:33], off offset:2048
	global_load_dword v58, v[34:35], off
	global_load_dword v59, v[36:37], off offset:2048
	global_load_dword v60, v[38:39], off
	global_load_dword v61, v[40:41], off offset:2048
	v_addc_co_u32_e32 v43, vcc, 0, v17, vcc
	v_add_co_u32_e32 v44, vcc, s65, v16
	s_nop 1
	v_addc_co_u32_e32 v45, vcc, 0, v17, vcc
	v_add_co_u32_e32 v46, vcc, s66, v16
	s_nop 1
	v_addc_co_u32_e32 v47, vcc, 0, v17, vcc
	v_add_co_u32_e32 v48, vcc, s45, v16
	s_nop 1
	v_addc_co_u32_e32 v49, vcc, 0, v17, vcc
	v_add_co_u32_e32 v50, vcc, s46, v16
	s_nop 1
	v_addc_co_u32_e32 v51, vcc, 0, v17, vcc
	v_add_co_u32_e32 v52, vcc, s12, v16
	s_mov_b32 s12, 0x19000
	s_nop 0
	v_addc_co_u32_e32 v53, vcc, 0, v17, vcc
	v_add_co_u32_e32 v54, vcc, s13, v16
	s_nop 1
	v_addc_co_u32_e32 v55, vcc, 0, v17, vcc
	v_add_co_u32_e32 v28, vcc, s47, v16
	s_nop 1
	v_addc_co_u32_e32 v29, vcc, 0, v17, vcc
	global_load_dword v62, v[42:43], off
	s_nop 0
	global_load_dword v44, v[44:45], off offset:2048
	s_nop 0
	global_load_dword v45, v[46:47], off
	s_nop 0
	global_load_dword v46, v[48:49], off offset:2048
	global_load_dword v47, v[50:51], off
	s_nop 0
	global_load_dword v48, v[52:53], off offset:2048
	global_load_dword v49, v[54:55], off
	global_load_dword v50, v[28:29], off offset:2048
	v_add_co_u32_e32 v28, vcc, s48, v16
	s_nop 1
	v_addc_co_u32_e32 v29, vcc, 0, v17, vcc
	v_add_co_u32_e32 v30, vcc, s12, v16
	s_mov_b32 s12, 0x1f000
	s_nop 0
	v_addc_co_u32_e32 v31, vcc, 0, v17, vcc
	v_add_co_u32_e32 v32, vcc, s67, v16
	s_nop 1
	v_addc_co_u32_e32 v33, vcc, 0, v17, vcc
	v_add_co_u32_e32 v34, vcc, s49, v16
	s_nop 1
	v_addc_co_u32_e32 v35, vcc, 0, v17, vcc
	v_add_co_u32_e32 v36, vcc, s50, v16
	s_nop 1
	v_addc_co_u32_e32 v37, vcc, 0, v17, vcc
	v_add_co_u32_e32 v38, vcc, s12, v16
	s_mov_b32 s12, 0x25000
	s_nop 0
	v_addc_co_u32_e32 v39, vcc, 0, v17, vcc
	v_add_co_u32_e32 v40, vcc, s68, v16
	s_nop 1
	v_addc_co_u32_e32 v41, vcc, 0, v17, vcc
	v_add_co_u32_e32 v42, vcc, s51, v16
	s_nop 1
	v_addc_co_u32_e32 v43, vcc, 0, v17, vcc
	global_load_dword v51, v[28:29], off
	global_load_dword v52, v[30:31], off offset:2048
	global_load_dword v53, v[32:33], off
	global_load_dword v54, v[34:35], off offset:2048
	global_load_dword v55, v[36:37], off
	global_load_dword v63, v[38:39], off offset:2048
	global_load_dword v64, v[40:41], off
	s_nop 0
	global_load_dword v42, v[42:43], off offset:2048
	v_add_co_u32_e32 v28, vcc, s52, v16
	s_nop 1
	v_addc_co_u32_e32 v29, vcc, 0, v17, vcc
	v_add_co_u32_e32 v30, vcc, s12, v16
	s_mov_b32 s12, 0x27000
	s_nop 0
	v_addc_co_u32_e32 v31, vcc, 0, v17, vcc
	v_add_co_u32_e32 v32, vcc, s12, v16
	s_mov_b32 s12, 0x2b000
	s_nop 0
	v_addc_co_u32_e32 v33, vcc, 0, v17, vcc
	v_add_co_u32_e32 v34, vcc, s54, v16
	s_nop 1
	v_addc_co_u32_e32 v35, vcc, 0, v17, vcc
	v_add_co_u32_e32 v36, vcc, s55, v16
	s_nop 1
	v_addc_co_u32_e32 v37, vcc, 0, v17, vcc
	v_add_co_u32_e32 v38, vcc, s12, v16
	s_mov_b32 s12, 0x2d000
	s_nop 0
	v_addc_co_u32_e32 v39, vcc, 0, v17, vcc
	v_add_co_u32_e32 v40, vcc, s12, v16
	s_mul_i32 s12, s10, 0xab
	s_nop 0
	v_addc_co_u32_e32 v41, vcc, 0, v17, vcc
	v_add_co_u32_e32 v16, vcc, s57, v16
	s_mul_i32 s10, s10, 0x15560
	s_nop 0
	v_addc_co_u32_e32 v17, vcc, 0, v17, vcc
	global_load_dword v28, v[28:29], off
	s_nop 0
	global_load_dword v29, v[30:31], off offset:2048
	s_nop 0
	global_load_dword v30, v[32:33], off
	global_load_dword v31, v[34:35], off offset:2048
	s_nop 0
	global_load_dword v32, v[36:37], off
	global_load_dword v33, v[38:39], off offset:2048
	global_load_dword v34, v[40:41], off
	s_nop 0
	global_load_dword v16, v[16:17], off offset:2048
	s_waitcnt vmcnt(0) lgkmcnt(0)
; #define LAS __attribute__((address_space(3)))
; #define LDS_WAIT() asm volatile("s_waitcnt lgkmcnt(0)" ::: "memory")
; __device__ __forceinline__ unsigned pk2(float lo, float hi) { return f2bf(lo) | (f2bf(hi) << 16); }
; __device__ __forceinline__ void tr_item(const float* W, int N, int k0, int n0, bf16* WT, int Kd, int drow0, int dk0, LAS float* scr, int lane) {
;     ...
;     LDS_WAIT();
;     const int c = lane & 7;
; #pragma unroll
;     for (int j = 0; j < 4; ++j) { const int n = (lane >> 3) + 8 * j; const LAS float* s = scr + (8 * c) * 33 + n;
;         v4u o; o.x = pk2(s[0 * 33], s[1 * 33]); o.y = pk2(s[2 * 33], s[3 * 33]); o.z = pk2(s[4 * 33], s[5 * 33]); o.w = pk2(s[6 * 33], s[7 * 33]);
;         *(v4u*)(WT + (size_t)(drow0 + n) * Kd + dk0 + 8 * c) = o; }
;     LDS_WAIT();
	ds_write2_b32 v18, v0, v27 offset1:66
	ds_write2_b32 v18, v56, v57 offset0:132 offset1:198
	ds_write2_b32 v20, v58, v59 offset0:8 offset1:74
	ds_write2_b32 v20, v60, v61 offset0:140 offset1:206
	ds_write2_b32 v21, v62, v44 offset0:16 offset1:82
	ds_write2_b32 v21, v45, v46 offset0:148 offset1:214
	ds_write2_b32 v22, v47, v48 offset0:24 offset1:90
	ds_write2_b32 v22, v49, v50 offset0:156 offset1:222
	ds_write2_b32 v23, v51, v52 offset0:32 offset1:98
	ds_write2_b32 v23, v53, v54 offset0:164 offset1:230
	ds_write2_b32 v24, v55, v63 offset0:40 offset1:106
	ds_write2_b32 v24, v64, v42 offset0:172 offset1:238
	ds_write2_b32 v25, v28, v29 offset0:48 offset1:114
	ds_write2_b32 v25, v30, v31 offset0:180 offset1:246
	ds_write2_b32 v26, v32, v33 offset0:56 offset1:122
	ds_write2_b32 v26, v34, v16 offset0:188 offset1:254
	s_waitcnt lgkmcnt(0)
	ds_read_b32 v0, v19
	ds_read_b32 v27, v19 offset:132
	ds_read_b32 v29, v19 offset:264
	ds_read_b32 v30, v19 offset:396
	ds_read_b32 v31, v19 offset:528
	ds_read_b32 v32, v19 offset:660
	ds_read_b32 v33, v19 offset:792
	ds_read_b32 v34, v19 offset:924
	s_waitcnt lgkmcnt(7)
	v_bfe_u32 v28, v0, 16, 1
	v_add3_u32 v0, v0, v28, s59
	s_waitcnt lgkmcnt(6)
	v_bfe_u32 v28, v27, 16, 1
	v_lshrrev_b32_e32 v0, 16, v0
	v_add3_u32 v27, v27, v28, s59
	v_and_or_b32 v28, v27, s60, v0
	s_waitcnt lgkmcnt(5)
	v_bfe_u32 v0, v29, 16, 1
	v_add3_u32 v0, v29, v0, s59
	s_waitcnt lgkmcnt(4)
	v_bfe_u32 v27, v30, 16, 1
	s_lshr_b32 s10, s10, 18
	v_lshrrev_b32_e32 v0, 16, v0
	v_add3_u32 v27, v30, v27, s59
	s_mulk_i32 s10, 0x60
	v_and_or_b32 v29, v27, s60, v0
	s_waitcnt lgkmcnt(3)
	v_bfe_u32 v0, v31, 16, 1
	s_bfe_u32 s12, s12, 0x70009
	s_sub_i32 s4, s4, s10
	v_add3_u32 v0, v31, v0, s59
	s_waitcnt lgkmcnt(2)
	v_bfe_u32 v27, v32, 16, 1
	s_and_b32 s4, s4, 0xffe0
	s_lshl_b32 s10, s12, 6
	s_lshl_b32 s12, s12, 5
	v_lshrrev_b32_e32 v0, 16, v0
	v_add3_u32 v27, v32, v27, s59
	s_add_i32 s10, s10, s4
	s_bitset1_b32 s12, 9
	v_and_or_b32 v30, v27, s60, v0
	s_waitcnt lgkmcnt(1)
	v_bfe_u32 v0, v33, 16, 1
	s_cmp_lt_u32 s4, 64
	v_add3_u32 v0, v33, v0, s59
	s_waitcnt lgkmcnt(0)
	v_bfe_u32 v27, v34, 16, 1
	s_cselect_b32 s4, s10, s12
	v_lshrrev_b32_e32 v0, 16, v0
	v_add3_u32 v27, v34, v27, s59
	s_lshl_b32 s10, s5, 7
	v_and_or_b32 v31, v27, s60, v0
	v_or_b32_e32 v0, s4, v160
	v_lshl_add_u64 v[16:17], v[4:5], 0, s[10:11]
	v_mul_u32_u24_e32 v0, 0x180, v0
	v_lshl_add_u64 v[32:33], v[0:1], 1, v[16:17]
	global_store_dwordx4 v[32:33], v[28:31], off sc0 sc1
	ds_read_b32 v0, v19 offset:32
	ds_read_b32 v27, v19 offset:164
	ds_read_b32 v29, v19 offset:296
	ds_read_b32 v30, v19 offset:428
	ds_read_b32 v31, v19 offset:560
	ds_read_b32 v32, v19 offset:692
	ds_read_b32 v33, v19 offset:824
	ds_read_b32 v34, v19 offset:956
	s_waitcnt lgkmcnt(0)
	v_bfe_u32 v28, v0, 16, 1
	v_add3_u32 v0, v0, v28, s59
	v_bfe_u32 v28, v27, 16, 1
	v_lshrrev_b32_e32 v0, 16, v0
	v_add3_u32 v27, v27, v28, s59
	v_and_or_b32 v28, v27, s60, v0
	v_bfe_u32 v0, v29, 16, 1
	v_add3_u32 v0, v29, v0, s59
	v_bfe_u32 v27, v30, 16, 1
	v_lshrrev_b32_e32 v0, 16, v0
	v_add3_u32 v27, v30, v27, s59
	v_and_or_b32 v29, v27, s60, v0
	v_bfe_u32 v0, v31, 16, 1
	v_add3_u32 v0, v31, v0, s59
	v_bfe_u32 v27, v32, 16, 1
	v_lshrrev_b32_e32 v0, 16, v0
	v_add3_u32 v27, v32, v27, s59
	v_and_or_b32 v30, v27, s60, v0
	v_bfe_u32 v0, v33, 16, 1
	v_add3_u32 v0, v33, v0, s59
	v_bfe_u32 v27, v34, 16, 1
	v_lshrrev_b32_e32 v0, 16, v0
	v_add3_u32 v27, v34, v27, s59
	v_and_or_b32 v31, v27, s60, v0
	v_or_b32_e32 v0, s4, v161
	v_mul_u32_u24_e32 v0, 0x180, v0
	v_lshl_add_u64 v[32:33], v[0:1], 1, v[16:17]
	global_store_dwordx4 v[32:33], v[28:31], off sc0 sc1
	ds_read_b32 v0, v19 offset:64
	ds_read_b32 v27, v19 offset:196
	ds_read_b32 v29, v19 offset:328
	ds_read_b32 v30, v19 offset:460
	ds_read_b32 v31, v19 offset:592
	ds_read_b32 v32, v19 offset:724
	ds_read_b32 v33, v19 offset:856
	ds_read_b32 v34, v19 offset:988
	s_waitcnt lgkmcnt(0)
	v_bfe_u32 v28, v0, 16, 1
	v_add3_u32 v0, v0, v28, s59
	v_bfe_u32 v28, v27, 16, 1
	v_lshrrev_b32_e32 v0, 16, v0
	v_add3_u32 v27, v27, v28, s59
	v_and_or_b32 v28, v27, s60, v0
	v_bfe_u32 v0, v29, 16, 1
	v_add3_u32 v0, v29, v0, s59
	v_bfe_u32 v27, v30, 16, 1
	v_lshrrev_b32_e32 v0, 16, v0
	v_add3_u32 v27, v30, v27, s59
	v_and_or_b32 v29, v27, s60, v0
	v_bfe_u32 v0, v31, 16, 1
	v_add3_u32 v0, v31, v0, s59
	v_bfe_u32 v27, v32, 16, 1
	v_lshrrev_b32_e32 v0, 16, v0
	v_add3_u32 v27, v32, v27, s59
	v_and_or_b32 v30, v27, s60, v0
	v_bfe_u32 v0, v33, 16, 1
	v_add3_u32 v0, v33, v0, s59
	v_bfe_u32 v27, v34, 16, 1
	v_lshrrev_b32_e32 v0, 16, v0
	v_add3_u32 v27, v34, v27, s59
	v_and_or_b32 v31, v27, s60, v0
	v_or_b32_e32 v0, s4, v162
	v_mul_u32_u24_e32 v0, 0x180, v0
	v_lshl_add_u64 v[32:33], v[0:1], 1, v[16:17]
	global_store_dwordx4 v[32:33], v[28:31], off sc0 sc1
	ds_read_b32 v0, v19 offset:96
	ds_read_b32 v27, v19 offset:228
	ds_read_b32 v29, v19 offset:360
	ds_read_b32 v30, v19 offset:492
	ds_read_b32 v31, v19 offset:624
	ds_read_b32 v32, v19 offset:756
	ds_read_b32 v33, v19 offset:888
	ds_read_b32 v34, v19 offset:1020
	s_waitcnt lgkmcnt(0)
	v_bfe_u32 v28, v0, 16, 1
	v_add3_u32 v0, v0, v28, s59
	v_bfe_u32 v28, v27, 16, 1
	v_lshrrev_b32_e32 v0, 16, v0
	v_add3_u32 v27, v27, v28, s59
	v_and_or_b32 v28, v27, s60, v0
	v_bfe_u32 v0, v29, 16, 1
	v_add3_u32 v0, v29, v0, s59
	v_bfe_u32 v27, v30, 16, 1
	v_lshrrev_b32_e32 v0, 16, v0
	v_add3_u32 v27, v30, v27, s59
	v_and_or_b32 v29, v27, s60, v0
	v_bfe_u32 v0, v31, 16, 1
	v_add3_u32 v0, v31, v0, s59
	v_bfe_u32 v27, v32, 16, 1
	v_lshrrev_b32_e32 v0, 16, v0
	v_add3_u32 v27, v32, v27, s59
	v_and_or_b32 v30, v27, s60, v0
	v_bfe_u32 v0, v33, 16, 1
	v_add3_u32 v0, v33, v0, s59
	v_bfe_u32 v27, v34, 16, 1
	v_lshrrev_b32_e32 v0, 16, v0
	v_add3_u32 v27, v34, v27, s59
	v_and_or_b32 v31, v27, s60, v0
	v_or_b32_e32 v0, s4, v163
	v_mul_u32_u24_e32 v0, 0x180, v0
	v_lshl_add_u64 v[16:17], v[0:1], 1, v[16:17]
	global_store_dwordx4 v[16:17], v[28:31], off sc0 sc1
	s_waitcnt lgkmcnt(0)

; #define LAS __attribute__((address_space(3)))
; #define TR_TRY(CNT, NBLK, ...) if (r < (CNT)) { const int k0 = 64 * (r / (NBLK)), n0 = 32 * (r % (NBLK)); (void)k0; (void)n0; __VA_ARGS__; continue; } r -= (CNT);
; #define TR_TRY(CNT, NBLK, ...) if (r < (CNT)) { const int k0 = 64 * (r / (NBLK)), n0 = 32 * (r % (NBLK)); (void)k0; (void)n0; __VA_ARGS__; continue; } r -= (CNT);
; __device__ __forceinline__ void tr_item(const float* W, int N, int k0, int n0, bf16* WT, int Kd, int drow0, int dk0, LAS float* scr, int lane) {
;     {
;         float wv[32]; const int n = n0 + (lane & 31); const float* wp = W + (size_t)(k0 + (lane >> 5)) * N + n;
; #pragma unroll
;         for (int i = 0; i < 32; ++i) wv[i] = (n < N) ? wp[(size_t)(2 * i) * N] : 0.f;
; #pragma unroll
;         for (int i = 0; i < 32; ++i) scr[(2 * i + (lane >> 5)) * 33 + (lane & 31)] = wv[i];
;     }
; __global__ void __launch_bounds__(NTHREADS, 2) mega_fwd(Args a_unused) {
;     ...
;             TR_TRY(I_W1, 256 / 32, tr_item(ap->in[14], 256, k0, n0, W1v, 1024, (k0 >= 1024 ? 256 : 0) + n0, k0 & 1023, scr, lane))
.LBB0_112:
	s_andn2_b64 vcc, exec, s[4:5]
	s_cbranch_vccnz .LBB0_114
	v_mov_b64_e32 v[16:17], s[38:39]
	global_load_dwordx2 v[16:17], v[16:17], off offset:112
	s_add_i32 s5, s19, 0x7fff5400
	s_and_b32 s5, s5, 0x7fffffc0
	s_and_b32 s4, s7, 0xe0
	v_or_b32_e32 v0, s5, v159
	v_or_b32_e32 v27, s4, v158
	v_lshlrev_b64 v[28:29], 10, v[0:1]
	v_lshlrev_b32_e32 v0, 2, v27
	s_cmpk_gt_u32 s5, 0x3ff
	s_cselect_b32 s5, 0x100, 0
	s_and_b32 s10, s19, 0x3c0
	s_or_b32 s4, s5, s4
	s_lshl_b32 s10, s10, 1
	s_waitcnt vmcnt(0) lgkmcnt(0)
	v_lshl_add_u64 v[16:17], v[16:17], 0, v[28:29]
	v_lshl_add_u64 v[16:17], v[16:17], 0, v[0:1]
	v_add_co_u32_e32 v28, vcc, s61, v16
	v_or_b32_e32 v0, s4, v160
	s_nop 0
	v_addc_co_u32_e32 v29, vcc, 0, v17, vcc
	v_add_co_u32_e32 v30, vcc, s21, v16
	v_lshlrev_b32_e32 v0, 11, v0
	s_nop 0
	v_addc_co_u32_e32 v31, vcc, 0, v17, vcc
	v_add_co_u32_e32 v32, vcc, s62, v16
	s_nop 1
	v_addc_co_u32_e32 v33, vcc, 0, v17, vcc
	v_add_co_u32_e32 v34, vcc, s35, v16
	s_nop 1
	v_addc_co_u32_e32 v35, vcc, 0, v17, vcc
	v_add_co_u32_e32 v36, vcc, s70, v16
	s_nop 1
	v_addc_co_u32_e32 v37, vcc, 0, v17, vcc
	v_add_co_u32_e32 v38, vcc, s40, v16
	s_nop 1
	v_addc_co_u32_e32 v39, vcc, 0, v17, vcc
	v_add_co_u32_e32 v40, vcc, s63, v16
	s_nop 1
	v_addc_co_u32_e32 v41, vcc, 0, v17, vcc
	v_add_co_u32_e32 v42, vcc, s41, v16
	s_nop 1
	v_addc_co_u32_e32 v43, vcc, 0, v17, vcc
	v_add_co_u32_e32 v44, vcc, s64, v16
	s_nop 1
	v_addc_co_u32_e32 v45, vcc, 0, v17, vcc
	v_add_co_u32_e32 v46, vcc, s42, v16
	s_nop 1
	v_addc_co_u32_e32 v47, vcc, 0, v17, vcc
	v_add_co_u32_e32 v48, vcc, s71, v16
	s_nop 1
	v_addc_co_u32_e32 v49, vcc, 0, v17, vcc
	v_add_co_u32_e32 v50, vcc, s43, v16
	global_load_dword v27, v[16:17], off
	global_load_dword v52, v[16:17], off offset:2048
	global_load_dword v53, v[28:29], off
	global_load_dword v54, v[28:29], off offset:2048
	global_load_dword v55, v[30:31], off
	global_load_dword v56, v[30:31], off offset:2048
	global_load_dword v57, v[32:33], off
	global_load_dword v58, v[32:33], off offset:2048
	global_load_dword v59, v[34:35], off
	s_nop 0
	global_load_dword v34, v[34:35], off offset:2048
	s_nop 0
	global_load_dword v35, v[36:37], off
	s_nop 0
	global_load_dword v36, v[36:37], off offset:2048
	s_nop 0
	global_load_dword v37, v[38:39], off
	s_nop 0
	global_load_dword v38, v[38:39], off offset:2048
	s_nop 0
	global_load_dword v39, v[40:41], off
	s_nop 0
	global_load_dword v40, v[40:41], off offset:2048
	s_nop 0
	global_load_dword v41, v[42:43], off
	s_nop 0
	global_load_dword v42, v[42:43], off offset:2048
	s_nop 0
	global_load_dword v43, v[44:45], off
	s_nop 0
	global_load_dword v44, v[44:45], off offset:2048
	s_nop 0
	global_load_dword v45, v[46:47], off
	s_nop 0
	global_load_dword v46, v[46:47], off offset:2048
	s_nop 0
	global_load_dword v47, v[48:49], off
	s_nop 0
	global_load_dword v48, v[48:49], off offset:2048
	v_addc_co_u32_e32 v51, vcc, 0, v17, vcc
	v_add_co_u32_e32 v28, vcc, s65, v16
	s_nop 1
	v_addc_co_u32_e32 v29, vcc, 0, v17, vcc
	v_add_co_u32_e32 v30, vcc, s44, v16
	s_nop 1
	v_addc_co_u32_e32 v31, vcc, 0, v17, vcc
	v_add_co_u32_e32 v16, vcc, s66, v16
	s_nop 1
	v_addc_co_u32_e32 v17, vcc, 0, v17, vcc
	global_load_dword v49, v[50:51], off
	s_nop 0
	global_load_dword v50, v[50:51], off offset:2048
	s_nop 0
	global_load_dword v51, v[28:29], off
	s_nop 0
	global_load_dword v28, v[28:29], off offset:2048
	s_nop 0
	global_load_dword v29, v[30:31], off
	s_nop 0
	global_load_dword v30, v[30:31], off offset:2048
	s_nop 0
	global_load_dword v31, v[16:17], off
	global_load_dword v60, v[16:17], off offset:2048
	v_lshl_add_u64 v[16:17], v[6:7], 0, s[10:11]
	v_lshl_add_u64 v[32:33], v[16:17], 0, v[0:1]
	s_waitcnt vmcnt(0) lgkmcnt(0)
	ds_write2_b32 v18, v27, v52 offset1:66
	ds_write2_b32 v18, v53, v54 offset0:132 offset1:198
	ds_write2_b32 v20, v55, v56 offset0:8 offset1:74
	ds_write2_b32 v20, v57, v58 offset0:140 offset1:206
	ds_write2_b32 v21, v59, v34 offset0:16 offset1:82
	ds_write2_b32 v21, v35, v36 offset0:148 offset1:214
	ds_write2_b32 v22, v37, v38 offset0:24 offset1:90
	ds_write2_b32 v22, v39, v40 offset0:156 offset1:222
	ds_write2_b32 v23, v41, v42 offset0:32 offset1:98
	ds_write2_b32 v23, v43, v44 offset0:164 offset1:230
	ds_write2_b32 v24, v45, v46 offset0:40 offset1:106
	ds_write2_b32 v24, v47, v48 offset0:172 offset1:238
	ds_write2_b32 v25, v49, v50 offset0:48 offset1:114
	ds_write2_b32 v25, v51, v28 offset0:180 offset1:246
	ds_write2_b32 v26, v29, v30 offset0:56 offset1:122
	ds_write2_b32 v26, v31, v60 offset0:188 offset1:254
	s_waitcnt lgkmcnt(0)
; #define LAS __attribute__((address_space(3)))
; #define LDS_WAIT() asm volatile("s_waitcnt lgkmcnt(0)" ::: "memory")
; __device__ __forceinline__ unsigned pk2(float lo, float hi) { return f2bf(lo) | (f2bf(hi) << 16); }
; __device__ __forceinline__ void tr_item(const float* W, int N, int k0, int n0, bf16* WT, int Kd, int drow0, int dk0, LAS float* scr, int lane) {
;     ...
;     LDS_WAIT();
;     const int c = lane & 7;
; #pragma unroll
;     for (int j = 0; j < 4; ++j) { const int n = (lane >> 3) + 8 * j; const LAS float* s = scr + (8 * c) * 33 + n;
;         v4u o; o.x = pk2(s[0 * 33], s[1 * 33]); o.y = pk2(s[2 * 33], s[3 * 33]); o.z = pk2(s[4 * 33], s[5 * 33]); o.w = pk2(s[6 * 33], s[7 * 33]);
;         *(v4u*)(WT + (size_t)(drow0 + n) * Kd + dk0 + 8 * c) = o; }
;     LDS_WAIT();
	ds_read_b32 v0, v19
	ds_read_b32 v27, v19 offset:132
	ds_read_b32 v28, v19 offset:264
	ds_read_b32 v29, v19 offset:396
	ds_read_b32 v30, v19 offset:528
	ds_read_b32 v31, v19 offset:660
	ds_read_b32 v34, v19 offset:792
	ds_read_b32 v35, v19 offset:924
	s_waitcnt lgkmcnt(7)
	v_bfe_u32 v36, v0, 16, 1
	s_waitcnt lgkmcnt(5)
	v_bfe_u32 v38, v28, 16, 1
	s_waitcnt lgkmcnt(3)
	v_bfe_u32 v40, v30, 16, 1
	s_waitcnt lgkmcnt(1)
	v_bfe_u32 v42, v34, 16, 1
	v_bfe_u32 v37, v27, 16, 1
	v_bfe_u32 v39, v29, 16, 1
	v_bfe_u32 v41, v31, 16, 1
	s_waitcnt lgkmcnt(0)
	v_bfe_u32 v43, v35, 16, 1
	v_add3_u32 v0, v0, v36, s59
	v_add3_u32 v28, v28, v38, s59
	v_add3_u32 v30, v30, v40, s59
	v_add3_u32 v34, v34, v42, s59
	v_add3_u32 v27, v27, v37, s59
	v_add3_u32 v29, v29, v39, s59
	v_add3_u32 v31, v31, v41, s59
	v_add3_u32 v35, v35, v43, s59
	v_lshrrev_b32_e32 v0, 16, v0
	v_lshrrev_b32_e32 v36, 16, v28
	v_lshrrev_b32_e32 v30, 16, v30
	v_lshrrev_b32_e32 v34, 16, v34
	v_and_or_b32 v28, v27, s60, v0
	v_and_or_b32 v29, v29, s60, v36
	v_and_or_b32 v30, v31, s60, v30
	v_and_or_b32 v31, v35, s60, v34
	global_store_dwordx4 v[32:33], v[28:31], off sc0 sc1
	ds_read_b32 v0, v19 offset:32
	ds_read_b32 v27, v19 offset:164
	ds_read_b32 v28, v19 offset:296
	ds_read_b32 v29, v19 offset:428
	ds_read_b32 v30, v19 offset:560
	ds_read_b32 v31, v19 offset:692
	ds_read_b32 v32, v19 offset:824
	ds_read_b32 v33, v19 offset:956
	s_waitcnt lgkmcnt(0)
	v_bfe_u32 v34, v0, 16, 1
	v_bfe_u32 v35, v27, 16, 1
	v_bfe_u32 v36, v28, 16, 1
	v_add3_u32 v0, v0, v34, s59
	v_bfe_u32 v38, v30, 16, 1
	v_add3_u32 v27, v27, v35, s59
	v_add3_u32 v28, v28, v36, s59
	v_lshrrev_b32_e32 v0, 16, v0
	v_add3_u32 v30, v30, v38, s59
	v_lshrrev_b32_e32 v34, 16, v28
	v_and_or_b32 v28, v27, s60, v0
	v_bfe_u32 v0, v31, 16, 1
	v_lshrrev_b32_e32 v30, 16, v30
	v_add3_u32 v0, v31, v0, s59
	v_and_or_b32 v30, v0, s60, v30
	v_bfe_u32 v0, v32, 16, 1
	v_add3_u32 v0, v32, v0, s59
	v_bfe_u32 v27, v33, 16, 1
	v_lshrrev_b32_e32 v0, 16, v0
	v_add3_u32 v27, v33, v27, s59
	v_bfe_u32 v37, v29, 16, 1
	v_and_or_b32 v31, v27, s60, v0
	v_or_b32_e32 v0, s4, v161
	v_add3_u32 v29, v29, v37, s59
	v_lshlrev_b32_e32 v0, 11, v0
	v_and_or_b32 v29, v29, s60, v34
	v_lshl_add_u64 v[32:33], v[16:17], 0, v[0:1]
	global_store_dwordx4 v[32:33], v[28:31], off sc0 sc1
	ds_read_b32 v0, v19 offset:64
	ds_read_b32 v27, v19 offset:196
	ds_read_b32 v29, v19 offset:328
	ds_read_b32 v30, v19 offset:460
	ds_read_b32 v31, v19 offset:592
	ds_read_b32 v32, v19 offset:724
	ds_read_b32 v33, v19 offset:856
	ds_read_b32 v34, v19 offset:988
	s_waitcnt lgkmcnt(0)
	v_bfe_u32 v28, v0, 16, 1
	v_add3_u32 v0, v0, v28, s59
	v_bfe_u32 v28, v27, 16, 1
	v_lshrrev_b32_e32 v0, 16, v0
	v_add3_u32 v27, v27, v28, s59
	v_and_or_b32 v28, v27, s60, v0
	v_bfe_u32 v0, v29, 16, 1
	v_add3_u32 v0, v29, v0, s59
	v_bfe_u32 v27, v30, 16, 1
	v_lshrrev_b32_e32 v0, 16, v0
	v_add3_u32 v27, v30, v27, s59
	v_and_or_b32 v29, v27, s60, v0
	v_bfe_u32 v0, v31, 16, 1
	v_add3_u32 v0, v31, v0, s59
	v_bfe_u32 v27, v32, 16, 1
	v_lshrrev_b32_e32 v0, 16, v0
	v_add3_u32 v27, v32, v27, s59
	v_and_or_b32 v30, v27, s60, v0
	v_bfe_u32 v0, v33, 16, 1
	v_add3_u32 v0, v33, v0, s59
	v_bfe_u32 v27, v34, 16, 1
	v_lshrrev_b32_e32 v0, 16, v0
	v_add3_u32 v27, v34, v27, s59
	v_and_or_b32 v31, v27, s60, v0
	v_or_b32_e32 v0, s4, v162
	v_lshlrev_b32_e32 v0, 11, v0
	v_lshl_add_u64 v[32:33], v[16:17], 0, v[0:1]
	global_store_dwordx4 v[32:33], v[28:31], off sc0 sc1
	ds_read_b32 v0, v19 offset:96
	ds_read_b32 v27, v19 offset:228
	ds_read_b32 v29, v19 offset:360
	ds_read_b32 v30, v19 offset:492
	ds_read_b32 v31, v19 offset:624
	ds_read_b32 v32, v19 offset:756
	ds_read_b32 v33, v19 offset:888
	ds_read_b32 v34, v19 offset:1020
	s_waitcnt lgkmcnt(0)
	v_bfe_u32 v28, v0, 16, 1
	v_add3_u32 v0, v0, v28, s59
	v_bfe_u32 v28, v27, 16, 1
	v_lshrrev_b32_e32 v0, 16, v0
	v_add3_u32 v27, v27, v28, s59
	v_and_or_b32 v28, v27, s60, v0
	v_bfe_u32 v0, v29, 16, 1
	v_add3_u32 v0, v29, v0, s59
	v_bfe_u32 v27, v30, 16, 1
	v_lshrrev_b32_e32 v0, 16, v0
	v_add3_u32 v27, v30, v27, s59
	v_and_or_b32 v29, v27, s60, v0
	v_bfe_u32 v0, v31, 16, 1
	v_add3_u32 v0, v31, v0, s59
	v_bfe_u32 v27, v32, 16, 1
	v_lshrrev_b32_e32 v0, 16, v0
	v_add3_u32 v27, v32, v27, s59
	v_and_or_b32 v30, v27, s60, v0
	v_bfe_u32 v0, v33, 16, 1
	v_add3_u32 v0, v33, v0, s59
	v_bfe_u32 v27, v34, 16, 1
	v_lshrrev_b32_e32 v0, 16, v0
	v_add3_u32 v27, v34, v27, s59
	v_and_or_b32 v31, v27, s60, v0
	v_or_b32_e32 v0, s4, v163
	v_lshlrev_b32_e32 v0, 11, v0
	v_lshl_add_u64 v[16:17], v[16:17], 0, v[0:1]
	global_store_dwordx4 v[16:17], v[28:31], off sc0 sc1
	s_waitcnt lgkmcnt(0)

; #define LAS __attribute__((address_space(3)))
; #define TR_TRY(CNT, NBLK, ...) if (r < (CNT)) { const int k0 = 64 * (r / (NBLK)), n0 = 32 * (r % (NBLK)); (void)k0; (void)n0; __VA_ARGS__; continue; } r -= (CNT);
; #define TR_TRY(CNT, NBLK, ...) if (r < (CNT)) { const int k0 = 64 * (r / (NBLK)), n0 = 32 * (r % (NBLK)); (void)k0; (void)n0; __VA_ARGS__; continue; } r -= (CNT);
; __device__ __forceinline__ void tr_item(const float* W, int N, int k0, int n0, bf16* WT, int Kd, int drow0, int dk0, LAS float* scr, int lane) {
;     {
;         float wv[32]; const int n = n0 + (lane & 31); const float* wp = W + (size_t)(k0 + (lane >> 5)) * N + n;
; #pragma unroll
;         for (int i = 0; i < 32; ++i) wv[i] = (n < N) ? wp[(size_t)(2 * i) * N] : 0.f;
; #pragma unroll
;         for (int i = 0; i < 32; ++i) scr[(2 * i + (lane >> 5)) * 33 + (lane & 31)] = wv[i];
;     }
; __global__ void __launch_bounds__(NTHREADS, 2) mega_fwd(Args a_unused) {
;     ...
;             TR_TRY(I_W1, 256 / 32, tr_item(ap->in[11], 256, k0, n0, W1k, 1024, (k0 >= 1024 ? 256 : 0) + n0, k0 & 1023, scr, lane))
.LBB0_115:
	s_andn2_b64 vcc, exec, s[4:5]
	s_cbranch_vccnz .LBB0_117
	v_mov_b64_e32 v[16:17], s[38:39]
	global_load_dwordx2 v[16:17], v[16:17], off offset:88
	s_add_i32 s5, s19, 0x7fff5c00
	s_and_b32 s5, s5, 0x7fffffc0
	s_and_b32 s4, s7, 0xe0
	v_or_b32_e32 v0, s5, v159
	v_or_b32_e32 v27, s4, v158
	v_lshlrev_b64 v[28:29], 10, v[0:1]
	v_lshlrev_b32_e32 v0, 2, v27
	s_cmpk_gt_u32 s5, 0x3ff
	s_cselect_b32 s5, 0x100, 0
	s_and_b32 s10, s19, 0x3c0
	s_or_b32 s4, s5, s4
	s_lshl_b32 s10, s10, 1
	s_waitcnt vmcnt(0) lgkmcnt(0)
	v_lshl_add_u64 v[16:17], v[16:17], 0, v[28:29]
	v_lshl_add_u64 v[16:17], v[16:17], 0, v[0:1]
	v_add_co_u32_e32 v28, vcc, s61, v16
	v_or_b32_e32 v0, s4, v160
	s_nop 0
	v_addc_co_u32_e32 v29, vcc, 0, v17, vcc
	v_add_co_u32_e32 v30, vcc, s21, v16
	v_lshlrev_b32_e32 v0, 11, v0
	s_nop 0
	v_addc_co_u32_e32 v31, vcc, 0, v17, vcc
	v_add_co_u32_e32 v32, vcc, s62, v16
	s_nop 1
	v_addc_co_u32_e32 v33, vcc, 0, v17, vcc
	v_add_co_u32_e32 v34, vcc, s35, v16
	s_nop 1
	v_addc_co_u32_e32 v35, vcc, 0, v17, vcc
	v_add_co_u32_e32 v36, vcc, s70, v16
	s_nop 1
	v_addc_co_u32_e32 v37, vcc, 0, v17, vcc
	v_add_co_u32_e32 v38, vcc, s40, v16
	s_nop 1
	v_addc_co_u32_e32 v39, vcc, 0, v17, vcc
	v_add_co_u32_e32 v40, vcc, s63, v16
	s_nop 1
	v_addc_co_u32_e32 v41, vcc, 0, v17, vcc
	v_add_co_u32_e32 v42, vcc, s41, v16
	s_nop 1
	v_addc_co_u32_e32 v43, vcc, 0, v17, vcc
	v_add_co_u32_e32 v44, vcc, s64, v16
	s_nop 1
	v_addc_co_u32_e32 v45, vcc, 0, v17, vcc
	v_add_co_u32_e32 v46, vcc, s42, v16
	s_nop 1
	v_addc_co_u32_e32 v47, vcc, 0, v17, vcc
	v_add_co_u32_e32 v48, vcc, s71, v16
	s_nop 1
	v_addc_co_u32_e32 v49, vcc, 0, v17, vcc
	v_add_co_u32_e32 v50, vcc, s43, v16
	global_load_dword v27, v[16:17], off
	global_load_dword v52, v[16:17], off offset:2048
	global_load_dword v53, v[28:29], off
	global_load_dword v54, v[28:29], off offset:2048
	global_load_dword v55, v[30:31], off
	global_load_dword v56, v[30:31], off offset:2048
	global_load_dword v57, v[32:33], off
	global_load_dword v58, v[32:33], off offset:2048
	global_load_dword v59, v[34:35], off
	s_nop 0
	global_load_dword v34, v[34:35], off offset:2048
	s_nop 0
	global_load_dword v35, v[36:37], off
	s_nop 0
	global_load_dword v36, v[36:37], off offset:2048
	s_nop 0
	global_load_dword v37, v[38:39], off
	s_nop 0
	global_load_dword v38, v[38:39], off offset:2048
	s_nop 0
	global_load_dword v39, v[40:41], off
	s_nop 0
	global_load_dword v40, v[40:41], off offset:2048
	s_nop 0
	global_load_dword v41, v[42:43], off
	s_nop 0
	global_load_dword v42, v[42:43], off offset:2048
	s_nop 0
	global_load_dword v43, v[44:45], off
	s_nop 0
	global_load_dword v44, v[44:45], off offset:2048
	s_nop 0
	global_load_dword v45, v[46:47], off
	s_nop 0
	global_load_dword v46, v[46:47], off offset:2048
	s_nop 0
	global_load_dword v47, v[48:49], off
	s_nop 0
	global_load_dword v48, v[48:49], off offset:2048
	v_addc_co_u32_e32 v51, vcc, 0, v17, vcc
	v_add_co_u32_e32 v28, vcc, s65, v16
	s_nop 1
	v_addc_co_u32_e32 v29, vcc, 0, v17, vcc
	v_add_co_u32_e32 v30, vcc, s44, v16
	s_nop 1
	v_addc_co_u32_e32 v31, vcc, 0, v17, vcc
	v_add_co_u32_e32 v16, vcc, s66, v16
	s_nop 1
	v_addc_co_u32_e32 v17, vcc, 0, v17, vcc
	global_load_dword v49, v[50:51], off
	s_nop 0
	global_load_dword v50, v[50:51], off offset:2048
	s_nop 0
	global_load_dword v51, v[28:29], off
	s_nop 0
	global_load_dword v28, v[28:29], off offset:2048
	s_nop 0
	global_load_dword v29, v[30:31], off
	s_nop 0
	global_load_dword v30, v[30:31], off offset:2048
	s_nop 0
	global_load_dword v31, v[16:17], off
	global_load_dword v60, v[16:17], off offset:2048
	v_lshl_add_u64 v[16:17], v[8:9], 0, s[10:11]
	v_lshl_add_u64 v[32:33], v[16:17], 0, v[0:1]
	s_waitcnt vmcnt(0) lgkmcnt(0)
	ds_write2_b32 v18, v27, v52 offset1:66
	ds_write2_b32 v18, v53, v54 offset0:132 offset1:198
	ds_write2_b32 v20, v55, v56 offset0:8 offset1:74
	ds_write2_b32 v20, v57, v58 offset0:140 offset1:206
	ds_write2_b32 v21, v59, v34 offset0:16 offset1:82
	ds_write2_b32 v21, v35, v36 offset0:148 offset1:214
	ds_write2_b32 v22, v37, v38 offset0:24 offset1:90
	ds_write2_b32 v22, v39, v40 offset0:156 offset1:222
	ds_write2_b32 v23, v41, v42 offset0:32 offset1:98
	ds_write2_b32 v23, v43, v44 offset0:164 offset1:230
	ds_write2_b32 v24, v45, v46 offset0:40 offset1:106
	ds_write2_b32 v24, v47, v48 offset0:172 offset1:238
	ds_write2_b32 v25, v49, v50 offset0:48 offset1:114
	ds_write2_b32 v25, v51, v28 offset0:180 offset1:246
	ds_write2_b32 v26, v29, v30 offset0:56 offset1:122
	ds_write2_b32 v26, v31, v60 offset0:188 offset1:254
	s_waitcnt lgkmcnt(0)
; #define LAS __attribute__((address_space(3)))
; #define LDS_WAIT() asm volatile("s_waitcnt lgkmcnt(0)" ::: "memory")
; __device__ __forceinline__ unsigned pk2(float lo, float hi) { return f2bf(lo) | (f2bf(hi) << 16); }
; __device__ __forceinline__ void tr_item(const float* W, int N, int k0, int n0, bf16* WT, int Kd, int drow0, int dk0, LAS float* scr, int lane) {
;     ...
;     LDS_WAIT();
;     const int c = lane & 7;
; #pragma unroll
;     for (int j = 0; j < 4; ++j) { const int n = (lane >> 3) + 8 * j; const LAS float* s = scr + (8 * c) * 33 + n;
;         v4u o; o.x = pk2(s[0 * 33], s[1 * 33]); o.y = pk2(s[2 * 33], s[3 * 33]); o.z = pk2(s[4 * 33], s[5 * 33]); o.w = pk2(s[6 * 33], s[7 * 33]);
;         *(v4u*)(WT + (size_t)(drow0 + n) * Kd + dk0 + 8 * c) = o; }
;     LDS_WAIT();
	ds_read_b32 v0, v19
	ds_read_b32 v27, v19 offset:132
	ds_read_b32 v28, v19 offset:264
	ds_read_b32 v29, v19 offset:396
	ds_read_b32 v30, v19 offset:528
	ds_read_b32 v31, v19 offset:660
	ds_read_b32 v34, v19 offset:792
	ds_read_b32 v35, v19 offset:924
	s_waitcnt lgkmcnt(7)
	v_bfe_u32 v36, v0, 16, 1
	s_waitcnt lgkmcnt(5)
	v_bfe_u32 v38, v28, 16, 1
	s_waitcnt lgkmcnt(3)
	v_bfe_u32 v40, v30, 16, 1
	s_waitcnt lgkmcnt(1)
	v_bfe_u32 v42, v34, 16, 1
	v_bfe_u32 v37, v27, 16, 1
	v_bfe_u32 v39, v29, 16, 1
	v_bfe_u32 v41, v31, 16, 1
	s_waitcnt lgkmcnt(0)
	v_bfe_u32 v43, v35, 16, 1
	v_add3_u32 v0, v0, v36, s59
	v_add3_u32 v28, v28, v38, s59
	v_add3_u32 v30, v30, v40, s59
	v_add3_u32 v34, v34, v42, s59
	v_add3_u32 v27, v27, v37, s59
	v_add3_u32 v29, v29, v39, s59
	v_add3_u32 v31, v31, v41, s59
	v_add3_u32 v35, v35, v43, s59
	v_lshrrev_b32_e32 v0, 16, v0
	v_lshrrev_b32_e32 v36, 16, v28
	v_lshrrev_b32_e32 v30, 16, v30
	v_lshrrev_b32_e32 v34, 16, v34
	v_and_or_b32 v28, v27, s60, v0
	v_and_or_b32 v29, v29, s60, v36
	v_and_or_b32 v30, v31, s60, v30
	v_and_or_b32 v31, v35, s60, v34
	global_store_dwordx4 v[32:33], v[28:31], off sc0 sc1
	ds_read_b32 v0, v19 offset:32
	ds_read_b32 v27, v19 offset:164
	ds_read_b32 v28, v19 offset:296
	ds_read_b32 v29, v19 offset:428
	ds_read_b32 v30, v19 offset:560
	ds_read_b32 v31, v19 offset:692
	ds_read_b32 v32, v19 offset:824
	ds_read_b32 v33, v19 offset:956
	s_waitcnt lgkmcnt(0)
	v_bfe_u32 v34, v0, 16, 1
	v_bfe_u32 v35, v27, 16, 1
	v_bfe_u32 v36, v28, 16, 1
	v_add3_u32 v0, v0, v34, s59
	v_bfe_u32 v38, v30, 16, 1
	v_add3_u32 v27, v27, v35, s59
	v_add3_u32 v28, v28, v36, s59
	v_lshrrev_b32_e32 v0, 16, v0
	v_add3_u32 v30, v30, v38, s59
	v_lshrrev_b32_e32 v34, 16, v28
	v_and_or_b32 v28, v27, s60, v0
	v_bfe_u32 v0, v31, 16, 1
	v_lshrrev_b32_e32 v30, 16, v30
	v_add3_u32 v0, v31, v0, s59
	v_and_or_b32 v30, v0, s60, v30
	v_bfe_u32 v0, v32, 16, 1
	v_add3_u32 v0, v32, v0, s59
	v_bfe_u32 v27, v33, 16, 1
	v_lshrrev_b32_e32 v0, 16, v0
	v_add3_u32 v27, v33, v27, s59
	v_bfe_u32 v37, v29, 16, 1
	v_and_or_b32 v31, v27, s60, v0
	v_or_b32_e32 v0, s4, v161
	v_add3_u32 v29, v29, v37, s59
	v_lshlrev_b32_e32 v0, 11, v0
	v_and_or_b32 v29, v29, s60, v34
	v_lshl_add_u64 v[32:33], v[16:17], 0, v[0:1]
	global_store_dwordx4 v[32:33], v[28:31], off sc0 sc1
	ds_read_b32 v0, v19 offset:64
	ds_read_b32 v27, v19 offset:196
	ds_read_b32 v29, v19 offset:328
	ds_read_b32 v30, v19 offset:460
	ds_read_b32 v31, v19 offset:592
	ds_read_b32 v32, v19 offset:724
	ds_read_b32 v33, v19 offset:856
	ds_read_b32 v34, v19 offset:988
	s_waitcnt lgkmcnt(0)
	v_bfe_u32 v28, v0, 16, 1
	v_add3_u32 v0, v0, v28, s59
	v_bfe_u32 v28, v27, 16, 1
	v_lshrrev_b32_e32 v0, 16, v0
	v_add3_u32 v27, v27, v28, s59
	v_and_or_b32 v28, v27, s60, v0
	v_bfe_u32 v0, v29, 16, 1
	v_add3_u32 v0, v29, v0, s59
	v_bfe_u32 v27, v30, 16, 1
	v_lshrrev_b32_e32 v0, 16, v0
	v_add3_u32 v27, v30, v27, s59
	v_and_or_b32 v29, v27, s60, v0
	v_bfe_u32 v0, v31, 16, 1
	v_add3_u32 v0, v31, v0, s59
	v_bfe_u32 v27, v32, 16, 1
	v_lshrrev_b32_e32 v0, 16, v0
	v_add3_u32 v27, v32, v27, s59
	v_and_or_b32 v30, v27, s60, v0
	v_bfe_u32 v0, v33, 16, 1
	v_add3_u32 v0, v33, v0, s59
	v_bfe_u32 v27, v34, 16, 1
	v_lshrrev_b32_e32 v0, 16, v0
	v_add3_u32 v27, v34, v27, s59
	v_and_or_b32 v31, v27, s60, v0
	v_or_b32_e32 v0, s4, v162
	v_lshlrev_b32_e32 v0, 11, v0
	v_lshl_add_u64 v[32:33], v[16:17], 0, v[0:1]
	global_store_dwordx4 v[32:33], v[28:31], off sc0 sc1
	ds_read_b32 v0, v19 offset:96
	ds_read_b32 v27, v19 offset:228
	ds_read_b32 v29, v19 offset:360
	ds_read_b32 v30, v19 offset:492
	ds_read_b32 v31, v19 offset:624
	ds_read_b32 v32, v19 offset:756
	ds_read_b32 v33, v19 offset:888
	ds_read_b32 v34, v19 offset:1020
	s_waitcnt lgkmcnt(0)
	v_bfe_u32 v28, v0, 16, 1
	v_add3_u32 v0, v0, v28, s59
	v_bfe_u32 v28, v27, 16, 1
	v_lshrrev_b32_e32 v0, 16, v0
	v_add3_u32 v27, v27, v28, s59
	v_and_or_b32 v28, v27, s60, v0
	v_bfe_u32 v0, v29, 16, 1
	v_add3_u32 v0, v29, v0, s59
	v_bfe_u32 v27, v30, 16, 1
	v_lshrrev_b32_e32 v0, 16, v0
	v_add3_u32 v27, v30, v27, s59
	v_and_or_b32 v29, v27, s60, v0
	v_bfe_u32 v0, v31, 16, 1
	v_add3_u32 v0, v31, v0, s59
	v_bfe_u32 v27, v32, 16, 1
	v_lshrrev_b32_e32 v0, 16, v0
	v_add3_u32 v27, v32, v27, s59
	v_and_or_b32 v30, v27, s60, v0
	v_bfe_u32 v0, v33, 16, 1
	v_add3_u32 v0, v33, v0, s59
	v_bfe_u32 v27, v34, 16, 1
	v_lshrrev_b32_e32 v0, 16, v0
	v_add3_u32 v27, v34, v27, s59
	v_and_or_b32 v31, v27, s60, v0
	v_or_b32_e32 v0, s4, v163
	v_lshlrev_b32_e32 v0, 11, v0
	v_lshl_add_u64 v[16:17], v[16:17], 0, v[0:1]
	global_store_dwordx4 v[16:17], v[28:31], off sc0 sc1
	s_waitcnt lgkmcnt(0)

; #define LAS __attribute__((address_space(3)))
; #define TR_TRY(CNT, NBLK, ...) if (r < (CNT)) { const int k0 = 64 * (r / (NBLK)), n0 = 32 * (r % (NBLK)); (void)k0; (void)n0; __VA_ARGS__; continue; } r -= (CNT);
; #define TR_TRY(CNT, NBLK, ...) if (r < (CNT)) { const int k0 = 64 * (r / (NBLK)), n0 = 32 * (r % (NBLK)); (void)k0; (void)n0; __VA_ARGS__; continue; } r -= (CNT);
; __device__ __forceinline__ void tr_item(const float* W, int N, int k0, int n0, bf16* WT, int Kd, int drow0, int dk0, LAS float* scr, int lane) {
;     {
;         float wv[32]; const int n = n0 + (lane & 31); const float* wp = W + (size_t)(k0 + (lane >> 5)) * N + n;
; #pragma unroll
;         for (int i = 0; i < 32; ++i) wv[i] = (n < N) ? wp[(size_t)(2 * i) * N] : 0.f;
; #pragma unroll
;         for (int i = 0; i < 32; ++i) scr[(2 * i + (lane >> 5)) * 33 + (lane & 31)] = wv[i];
;     }
; __global__ void __launch_bounds__(NTHREADS, 2) mega_fwd(Args a_unused) {
;     ...
;             TR_TRY(I_IN, DINP / 32, tr_item(ap->in[9], DIN, k0, n0, Win, D, n0, k0, scr, lane))
.LBB0_118:
	s_andn2_b64 vcc, exec, s[4:5]
	s_cbranch_vccnz .LBB0_184
	v_mov_b64_e32 v[16:17], s[38:39]
	global_load_dwordx2 v[16:17], v[16:17], off offset:72
	s_and_b32 s4, s97, 0x1fc0
	s_and_b32 s69, s7, 0x7e0
	s_add_i32 s10, s4, 0xffffef80
	v_or_b32_e32 v28, s69, v158
	v_or_b32_e32 v29, s10, v159
	v_lshlrev_b32_e32 v0, 2, v28
	v_mov_b32_e32 v27, 0
	v_cmp_gt_u32_e64 s[4:5], s73, v28
	s_waitcnt vmcnt(0) lgkmcnt(0)
	v_mad_u64_u32 v[16:17], s[12:13], v29, s72, v[16:17]
	v_lshl_add_u64 v[16:17], v[16:17], 0, v[0:1]
	v_mov_b32_e32 v0, 0
	s_and_saveexec_b64 s[12:13], s[4:5]
	s_cbranch_execz .LBB0_121
	global_load_dword v0, v[16:17], off
.LBB0_121:
	s_or_b64 exec, exec, s[12:13]
	s_and_saveexec_b64 s[12:13], s[4:5]
	s_cbranch_execz .LBB0_123
	v_add_co_u32_e32 v28, vcc, 0x3000, v16
	s_nop 1
	v_addc_co_u32_e32 v29, vcc, 0, v17, vcc
	global_load_dword v27, v[28:29], off offset:3520
.LBB0_123:
	s_or_b64 exec, exec, s[12:13]
	v_mov_b32_e32 v28, 0
	v_mov_b32_e32 v29, 0
	s_and_saveexec_b64 s[12:13], s[4:5]
	s_cbranch_execz .LBB0_125
	v_add_co_u32_e32 v30, vcc, 0x7000, v16
	s_nop 1
	v_addc_co_u32_e32 v31, vcc, 0, v17, vcc
	global_load_dword v29, v[30:31], off offset:2944
.LBB0_125:
	s_or_b64 exec, exec, s[12:13]
	s_and_saveexec_b64 s[12:13], s[4:5]
	s_cbranch_execz .LBB0_127
	v_add_co_u32_e32 v30, vcc, 0xb000, v16
	s_nop 1
	v_addc_co_u32_e32 v31, vcc, 0, v17, vcc
	global_load_dword v28, v[30:31], off offset:2368
.LBB0_127:
	s_or_b64 exec, exec, s[12:13]
	v_mov_b32_e32 v30, 0
	v_mov_b32_e32 v31, 0
	s_and_saveexec_b64 s[12:13], s[4:5]
	s_cbranch_execz .LBB0_129
	v_add_co_u32_e32 v32, vcc, 0xf000, v16
	s_nop 1
	v_addc_co_u32_e32 v33, vcc, 0, v17, vcc
	global_load_dword v31, v[32:33], off offset:1792
.LBB0_129:
	s_or_b64 exec, exec, s[12:13]
	s_and_saveexec_b64 s[12:13], s[4:5]
	s_cbranch_execz .LBB0_131
	v_add_co_u32_e32 v32, vcc, 0x13000, v16
	s_nop 1
	v_addc_co_u32_e32 v33, vcc, 0, v17, vcc
	global_load_dword v30, v[32:33], off offset:1216
.LBB0_131:
	s_or_b64 exec, exec, s[12:13]
	v_mov_b32_e32 v32, 0
	v_mov_b32_e32 v33, 0
	s_and_saveexec_b64 s[12:13], s[4:5]
	s_cbranch_execz .LBB0_133
	v_add_co_u32_e32 v34, vcc, 0x17000, v16
	s_nop 1
	v_addc_co_u32_e32 v35, vcc, 0, v17, vcc
	global_load_dword v33, v[34:35], off offset:640
.LBB0_133:
	s_or_b64 exec, exec, s[12:13]
	s_and_saveexec_b64 s[12:13], s[4:5]
	s_cbranch_execz .LBB0_135
	v_add_co_u32_e32 v34, vcc, 0x1b000, v16
	s_nop 1
	v_addc_co_u32_e32 v35, vcc, 0, v17, vcc
	global_load_dword v32, v[34:35], off offset:64
.LBB0_135:
	s_or_b64 exec, exec, s[12:13]
	v_mov_b32_e32 v34, 0
	v_mov_b32_e32 v35, 0
	s_and_saveexec_b64 s[12:13], s[4:5]
	s_cbranch_execz .LBB0_137
	v_add_co_u32_e32 v36, vcc, 0x1e000, v16
	s_nop 1
	v_addc_co_u32_e32 v37, vcc, 0, v17, vcc
	global_load_dword v35, v[36:37], off offset:3584
.LBB0_137:
	s_or_b64 exec, exec, s[12:13]
	s_and_saveexec_b64 s[12:13], s[4:5]
	s_cbranch_execz .LBB0_139
	v_add_co_u32_e32 v36, vcc, 0x22000, v16
	s_nop 1
	v_addc_co_u32_e32 v37, vcc, 0, v17, vcc
	global_load_dword v34, v[36:37], off offset:3008
.LBB0_139:
	s_or_b64 exec, exec, s[12:13]
	v_mov_b32_e32 v36, 0
	v_mov_b32_e32 v37, 0
	s_and_saveexec_b64 s[12:13], s[4:5]
	s_cbranch_execz .LBB0_141
	v_add_co_u32_e32 v38, vcc, 0x26000, v16
	s_nop 1
	v_addc_co_u32_e32 v39, vcc, 0, v17, vcc
	global_load_dword v37, v[38:39], off offset:2432
.LBB0_141:
	s_or_b64 exec, exec, s[12:13]
	s_and_saveexec_b64 s[12:13], s[4:5]
	s_cbranch_execz .LBB0_143
	v_add_co_u32_e32 v38, vcc, 0x2a000, v16
	s_nop 1
	v_addc_co_u32_e32 v39, vcc, 0, v17, vcc
	global_load_dword v36, v[38:39], off offset:1856
.LBB0_143:
	s_or_b64 exec, exec, s[12:13]
	v_mov_b32_e32 v38, 0
	v_mov_b32_e32 v39, 0
	s_and_saveexec_b64 s[12:13], s[4:5]
	s_cbranch_execz .LBB0_145
	v_add_co_u32_e32 v40, vcc, 0x2e000, v16
	s_nop 1
	v_addc_co_u32_e32 v41, vcc, 0, v17, vcc
	global_load_dword v39, v[40:41], off offset:1280
.LBB0_145:
	s_or_b64 exec, exec, s[12:13]
	s_and_saveexec_b64 s[12:13], s[4:5]
	s_cbranch_execz .LBB0_147
	v_add_co_u32_e32 v40, vcc, 0x32000, v16
	s_nop 1
	v_addc_co_u32_e32 v41, vcc, 0, v17, vcc
	global_load_dword v38, v[40:41], off offset:704
.LBB0_147:
	s_or_b64 exec, exec, s[12:13]
	v_mov_b32_e32 v40, 0
	v_mov_b32_e32 v41, 0
	s_and_saveexec_b64 s[12:13], s[4:5]
	s_cbranch_execz .LBB0_149
	v_add_co_u32_e32 v42, vcc, 0x36000, v16
	s_nop 1
	v_addc_co_u32_e32 v43, vcc, 0, v17, vcc
	global_load_dword v41, v[42:43], off offset:128
.LBB0_149:
	s_or_b64 exec, exec, s[12:13]
	s_and_saveexec_b64 s[12:13], s[4:5]
	s_cbranch_execz .LBB0_151
	v_add_co_u32_e32 v42, vcc, 0x39000, v16
	s_nop 1
	v_addc_co_u32_e32 v43, vcc, 0, v17, vcc
	global_load_dword v40, v[42:43], off offset:3648
.LBB0_151:
	s_or_b64 exec, exec, s[12:13]
	v_mov_b32_e32 v42, 0
	v_mov_b32_e32 v43, 0
	s_and_saveexec_b64 s[12:13], s[4:5]
	s_cbranch_execz .LBB0_153
	v_add_co_u32_e32 v44, vcc, 0x3d000, v16
	s_nop 1
	v_addc_co_u32_e32 v45, vcc, 0, v17, vcc
	global_load_dword v43, v[44:45], off offset:3072
.LBB0_153:
	s_or_b64 exec, exec, s[12:13]
	s_and_saveexec_b64 s[12:13], s[4:5]
	s_cbranch_execz .LBB0_155
	v_add_co_u32_e32 v44, vcc, 0x41000, v16
	s_nop 1
	v_addc_co_u32_e32 v45, vcc, 0, v17, vcc
	global_load_dword v42, v[44:45], off offset:2496
.LBB0_155:
	s_or_b64 exec, exec, s[12:13]
	v_mov_b32_e32 v44, 0
	v_mov_b32_e32 v45, 0
	s_and_saveexec_b64 s[12:13], s[4:5]
	s_cbranch_execz .LBB0_157
	v_add_co_u32_e32 v46, vcc, 0x45000, v16
	s_nop 1
	v_addc_co_u32_e32 v47, vcc, 0, v17, vcc
	global_load_dword v45, v[46:47], off offset:1920
.LBB0_157:
	s_or_b64 exec, exec, s[12:13]
	s_and_saveexec_b64 s[12:13], s[4:5]
	s_cbranch_execz .LBB0_159
	v_add_co_u32_e32 v46, vcc, 0x49000, v16
	s_nop 1
	v_addc_co_u32_e32 v47, vcc, 0, v17, vcc
	global_load_dword v44, v[46:47], off offset:1344
; __device__ __forceinline__ void tr_item(const float* W, int N, int k0, int n0, bf16* WT, int Kd, int drow0, int dk0, LAS float* scr, int lane) {
;     ...
;         float wv[32]; const int n = n0 + (lane & 31); const float* wp = W + (size_t)(k0 + (lane >> 5)) * N + n;
; #pragma unroll
;         for (int i = 0; i < 32; ++i) wv[i] = (n < N) ? wp[(size_t)(2 * i) * N] : 0.f;
.LBB0_159:
	s_or_b64 exec, exec, s[12:13]
	v_mov_b32_e32 v46, 0
	v_mov_b32_e32 v47, 0
	s_and_saveexec_b64 s[12:13], s[4:5]
	s_cbranch_execz .LBB0_161
	v_add_co_u32_e32 v48, vcc, 0x4d000, v16
	s_nop 1
	v_addc_co_u32_e32 v49, vcc, 0, v17, vcc
	global_load_dword v47, v[48:49], off offset:768
.LBB0_161:
	s_or_b64 exec, exec, s[12:13]
	s_and_saveexec_b64 s[12:13], s[4:5]
	s_cbranch_execz .LBB0_163
	v_add_co_u32_e32 v48, vcc, 0x51000, v16
	s_nop 1
	v_addc_co_u32_e32 v49, vcc, 0, v17, vcc
	global_load_dword v46, v[48:49], off offset:192
.LBB0_163:
	s_or_b64 exec, exec, s[12:13]
	v_mov_b32_e32 v48, 0
	v_mov_b32_e32 v49, 0
	s_and_saveexec_b64 s[12:13], s[4:5]
	s_cbranch_execz .LBB0_165
	v_add_co_u32_e32 v50, vcc, 0x54000, v16
	s_nop 1
	v_addc_co_u32_e32 v51, vcc, 0, v17, vcc
	global_load_dword v49, v[50:51], off offset:3712
.LBB0_165:
	s_or_b64 exec, exec, s[12:13]
	s_and_saveexec_b64 s[12:13], s[4:5]
	s_cbranch_execz .LBB0_167
	v_add_co_u32_e32 v50, vcc, 0x58000, v16
	s_nop 1
	v_addc_co_u32_e32 v51, vcc, 0, v17, vcc
	global_load_dword v48, v[50:51], off offset:3136
.LBB0_167:
	s_or_b64 exec, exec, s[12:13]
	v_mov_b32_e32 v50, 0
	v_mov_b32_e32 v51, 0
	s_and_saveexec_b64 s[12:13], s[4:5]
	s_cbranch_execz .LBB0_169
	v_add_co_u32_e32 v52, vcc, 0x5c000, v16
	s_nop 1
	v_addc_co_u32_e32 v53, vcc, 0, v17, vcc
	global_load_dword v51, v[52:53], off offset:2560
.LBB0_169:
	s_or_b64 exec, exec, s[12:13]
	s_and_saveexec_b64 s[12:13], s[4:5]
	s_cbranch_execz .LBB0_171
	v_add_co_u32_e32 v52, vcc, 0x60000, v16
	s_nop 1
	v_addc_co_u32_e32 v53, vcc, 0, v17, vcc
	global_load_dword v50, v[52:53], off offset:1984
.LBB0_171:
	s_or_b64 exec, exec, s[12:13]
	v_mov_b32_e32 v52, 0
	v_mov_b32_e32 v53, 0
	s_and_saveexec_b64 s[12:13], s[4:5]
	s_cbranch_execz .LBB0_173
	v_add_co_u32_e32 v54, vcc, 0x64000, v16
	s_nop 1
	v_addc_co_u32_e32 v55, vcc, 0, v17, vcc
	global_load_dword v53, v[54:55], off offset:1408
.LBB0_173:
	s_or_b64 exec, exec, s[12:13]
	s_and_saveexec_b64 s[12:13], s[4:5]
	s_cbranch_execz .LBB0_175
	v_add_co_u32_e32 v54, vcc, 0x68000, v16
	s_nop 1
	v_addc_co_u32_e32 v55, vcc, 0, v17, vcc
	global_load_dword v52, v[54:55], off offset:832
.LBB0_175:
	s_or_b64 exec, exec, s[12:13]
	v_mov_b32_e32 v54, 0
	v_mov_b32_e32 v55, 0
	s_and_saveexec_b64 s[12:13], s[4:5]
	s_cbranch_execz .LBB0_177
	v_add_co_u32_e32 v56, vcc, 0x6c000, v16
	s_nop 1
	v_addc_co_u32_e32 v57, vcc, 0, v17, vcc
	global_load_dword v55, v[56:57], off offset:256
.LBB0_177:
	s_or_b64 exec, exec, s[12:13]
	s_and_saveexec_b64 s[12:13], s[4:5]
	s_cbranch_execz .LBB0_179
	v_add_co_u32_e32 v56, vcc, 0x6f000, v16
	s_nop 1
	v_addc_co_u32_e32 v57, vcc, 0, v17, vcc
	global_load_dword v54, v[56:57], off offset:3776
.LBB0_179:
	s_or_b64 exec, exec, s[12:13]
	v_mov_b32_e32 v56, 0
	v_mov_b32_e32 v57, 0
	s_and_saveexec_b64 s[12:13], s[4:5]
	s_cbranch_execz .LBB0_181
	v_add_co_u32_e32 v58, vcc, 0x73000, v16
	s_nop 1
	v_addc_co_u32_e32 v59, vcc, 0, v17, vcc
	global_load_dword v57, v[58:59], off offset:3200
.LBB0_181:
	s_or_b64 exec, exec, s[12:13]
	s_and_saveexec_b64 s[12:13], s[4:5]
	s_cbranch_execz .LBB0_183
	v_add_co_u32_e32 v16, vcc, 0x77000, v16
	s_nop 1
	v_addc_co_u32_e32 v17, vcc, 0, v17, vcc
	global_load_dword v56, v[16:17], off offset:2624
; #define LAS __attribute__((address_space(3)))
; #define LDS_WAIT() asm volatile("s_waitcnt lgkmcnt(0)" ::: "memory")
; __device__ __forceinline__ unsigned pk2(float lo, float hi) { return f2bf(lo) | (f2bf(hi) << 16); }
; __device__ __forceinline__ void tr_item(const float* W, int N, int k0, int n0, bf16* WT, int Kd, int drow0, int dk0, LAS float* scr, int lane) {
;     ...
; #pragma unroll
;         for (int i = 0; i < 32; ++i) scr[(2 * i + (lane >> 5)) * 33 + (lane & 31)] = wv[i];
;     }
;     LDS_WAIT();
;     const int c = lane & 7;
; #pragma unroll
;     for (int j = 0; j < 4; ++j) { const int n = (lane >> 3) + 8 * j; const LAS float* s = scr + (8 * c) * 33 + n;
;         v4u o; o.x = pk2(s[0 * 33], s[1 * 33]); o.y = pk2(s[2 * 33], s[3 * 33]); o.z = pk2(s[4 * 33], s[5 * 33]); o.w = pk2(s[6 * 33], s[7 * 33]);
;         *(v4u*)(WT + (size_t)(drow0 + n) * Kd + dk0 + 8 * c) = o; }
;     LDS_WAIT();
.LBB0_183:
	s_or_b64 exec, exec, s[12:13]
	s_waitcnt vmcnt(0) lgkmcnt(0)
	ds_write2_b32 v18, v0, v27 offset1:66
	ds_write2_b32 v18, v29, v28 offset0:132 offset1:198
	ds_write2_b32 v20, v31, v30 offset0:8 offset1:74
	ds_write2_b32 v20, v33, v32 offset0:140 offset1:206
	ds_write2_b32 v21, v35, v34 offset0:16 offset1:82
	ds_write2_b32 v21, v37, v36 offset0:148 offset1:214
	ds_write2_b32 v22, v39, v38 offset0:24 offset1:90
	ds_write2_b32 v22, v41, v40 offset0:156 offset1:222
	ds_write2_b32 v23, v43, v42 offset0:32 offset1:98
	ds_write2_b32 v23, v45, v44 offset0:164 offset1:230
	ds_write2_b32 v24, v47, v46 offset0:40 offset1:106
	ds_write2_b32 v24, v49, v48 offset0:172 offset1:238
	ds_write2_b32 v25, v51, v50 offset0:48 offset1:114
	ds_write2_b32 v25, v53, v52 offset0:180 offset1:246
	ds_write2_b32 v26, v55, v54 offset0:56 offset1:122
	ds_write2_b32 v26, v57, v56 offset0:188 offset1:254
	s_waitcnt lgkmcnt(0)
	ds_read_b32 v0, v19
	ds_read_b32 v27, v19 offset:132
	ds_read_b32 v29, v19 offset:264
	ds_read_b32 v30, v19 offset:396
	ds_read_b32 v31, v19 offset:528
	ds_read_b32 v32, v19 offset:660
	ds_read_b32 v33, v19 offset:792
	ds_read_b32 v34, v19 offset:924
	s_waitcnt lgkmcnt(7)
	v_bfe_u32 v28, v0, 16, 1
	v_add3_u32 v0, v0, v28, s59
	s_waitcnt lgkmcnt(6)
	v_bfe_u32 v28, v27, 16, 1
	v_lshrrev_b32_e32 v0, 16, v0
	v_add3_u32 v27, v27, v28, s59
	v_and_or_b32 v28, v27, s60, v0
	s_waitcnt lgkmcnt(5)
	v_bfe_u32 v0, v29, 16, 1
	v_add3_u32 v0, v29, v0, s59
	s_waitcnt lgkmcnt(4)
	v_bfe_u32 v27, v30, 16, 1
	v_lshrrev_b32_e32 v0, 16, v0
	v_add3_u32 v27, v30, v27, s59
	v_and_or_b32 v29, v27, s60, v0
	s_waitcnt lgkmcnt(3)
	v_bfe_u32 v0, v31, 16, 1
	v_add3_u32 v0, v31, v0, s59
	s_waitcnt lgkmcnt(2)
	v_bfe_u32 v27, v32, 16, 1
	v_lshrrev_b32_e32 v0, 16, v0
	v_add3_u32 v27, v32, v27, s59
	v_and_or_b32 v30, v27, s60, v0
	s_waitcnt lgkmcnt(1)
	v_bfe_u32 v0, v33, 16, 1
	v_add3_u32 v0, v33, v0, s59
	s_waitcnt lgkmcnt(0)
	v_bfe_u32 v27, v34, 16, 1
	v_lshrrev_b32_e32 v0, 16, v0
	v_add3_u32 v27, v34, v27, s59
	v_and_or_b32 v31, v27, s60, v0
	v_or_b32_e32 v0, s69, v160
	v_lshl_add_u64 v[16:17], s[10:11], 1, v[10:11]
	v_lshlrev_b32_e32 v0, 11, v0
	v_lshl_add_u64 v[32:33], v[16:17], 0, v[0:1]
	global_store_dwordx4 v[32:33], v[28:31], off sc0 sc1
	ds_read_b32 v0, v19 offset:32
	ds_read_b32 v27, v19 offset:164
	ds_read_b32 v29, v19 offset:296
	ds_read_b32 v30, v19 offset:428
	ds_read_b32 v31, v19 offset:560
	ds_read_b32 v32, v19 offset:692
	ds_read_b32 v33, v19 offset:824
	ds_read_b32 v34, v19 offset:956
	s_waitcnt lgkmcnt(0)
	v_bfe_u32 v28, v0, 16, 1
	v_add3_u32 v0, v0, v28, s59
	v_bfe_u32 v28, v27, 16, 1
	v_lshrrev_b32_e32 v0, 16, v0
	v_add3_u32 v27, v27, v28, s59
	v_and_or_b32 v28, v27, s60, v0
	v_bfe_u32 v0, v29, 16, 1
	v_add3_u32 v0, v29, v0, s59
	v_bfe_u32 v27, v30, 16, 1
	v_lshrrev_b32_e32 v0, 16, v0
	v_add3_u32 v27, v30, v27, s59
	v_and_or_b32 v29, v27, s60, v0
	v_bfe_u32 v0, v31, 16, 1
	v_add3_u32 v0, v31, v0, s59
	v_bfe_u32 v27, v32, 16, 1
	v_lshrrev_b32_e32 v0, 16, v0
	v_add3_u32 v27, v32, v27, s59
	v_and_or_b32 v30, v27, s60, v0
	v_bfe_u32 v0, v33, 16, 1
	v_add3_u32 v0, v33, v0, s59
	v_bfe_u32 v27, v34, 16, 1
	v_lshrrev_b32_e32 v0, 16, v0
	v_add3_u32 v27, v34, v27, s59
	v_and_or_b32 v31, v27, s60, v0
	v_or_b32_e32 v0, s69, v161
	v_lshlrev_b32_e32 v0, 11, v0
	v_lshl_add_u64 v[32:33], v[16:17], 0, v[0:1]
	global_store_dwordx4 v[32:33], v[28:31], off sc0 sc1
	ds_read_b32 v0, v19 offset:64
	ds_read_b32 v27, v19 offset:196
	ds_read_b32 v29, v19 offset:328
	ds_read_b32 v30, v19 offset:460
	ds_read_b32 v31, v19 offset:592
	ds_read_b32 v32, v19 offset:724
	ds_read_b32 v33, v19 offset:856
	ds_read_b32 v34, v19 offset:988
	s_waitcnt lgkmcnt(0)
	v_bfe_u32 v28, v0, 16, 1
	v_add3_u32 v0, v0, v28, s59
	v_bfe_u32 v28, v27, 16, 1
	v_lshrrev_b32_e32 v0, 16, v0
	v_add3_u32 v27, v27, v28, s59
	v_and_or_b32 v28, v27, s60, v0
	v_bfe_u32 v0, v29, 16, 1
	v_add3_u32 v0, v29, v0, s59
	v_bfe_u32 v27, v30, 16, 1
	v_lshrrev_b32_e32 v0, 16, v0
	v_add3_u32 v27, v30, v27, s59
	v_and_or_b32 v29, v27, s60, v0
	v_bfe_u32 v0, v31, 16, 1
	v_add3_u32 v0, v31, v0, s59
	v_bfe_u32 v27, v32, 16, 1
	v_lshrrev_b32_e32 v0, 16, v0
	v_add3_u32 v27, v32, v27, s59
	v_and_or_b32 v30, v27, s60, v0
	v_bfe_u32 v0, v33, 16, 1
	v_add3_u32 v0, v33, v0, s59
	v_bfe_u32 v27, v34, 16, 1
	v_lshrrev_b32_e32 v0, 16, v0
	v_add3_u32 v27, v34, v27, s59
	v_and_or_b32 v31, v27, s60, v0
	v_or_b32_e32 v0, s69, v162
	v_lshlrev_b32_e32 v0, 11, v0
	v_lshl_add_u64 v[32:33], v[16:17], 0, v[0:1]
	global_store_dwordx4 v[32:33], v[28:31], off sc0 sc1
	ds_read_b32 v0, v19 offset:96
	ds_read_b32 v27, v19 offset:228
	ds_read_b32 v29, v19 offset:360
	ds_read_b32 v30, v19 offset:492
	ds_read_b32 v31, v19 offset:624
	ds_read_b32 v32, v19 offset:756
	ds_read_b32 v33, v19 offset:888
	ds_read_b32 v34, v19 offset:1020
	s_waitcnt lgkmcnt(0)
	v_bfe_u32 v28, v0, 16, 1
	v_add3_u32 v0, v0, v28, s59
	v_bfe_u32 v28, v27, 16, 1
	v_lshrrev_b32_e32 v0, 16, v0
	v_add3_u32 v27, v27, v28, s59
	v_and_or_b32 v28, v27, s60, v0
	v_bfe_u32 v0, v29, 16, 1
	v_add3_u32 v0, v29, v0, s59
	v_bfe_u32 v27, v30, 16, 1
	v_lshrrev_b32_e32 v0, 16, v0
	v_add3_u32 v27, v30, v27, s59
	v_and_or_b32 v29, v27, s60, v0
	v_bfe_u32 v0, v31, 16, 1
	v_add3_u32 v0, v31, v0, s59
	v_bfe_u32 v27, v32, 16, 1
	v_lshrrev_b32_e32 v0, 16, v0
	v_add3_u32 v27, v32, v27, s59
	v_and_or_b32 v30, v27, s60, v0
	v_bfe_u32 v0, v33, 16, 1
	v_add3_u32 v0, v33, v0, s59
	v_bfe_u32 v27, v34, 16, 1
	v_lshrrev_b32_e32 v0, 16, v0
	v_add3_u32 v27, v34, v27, s59
	v_and_or_b32 v31, v27, s60, v0
	v_or_b32_e32 v0, s69, v163
	v_lshlrev_b32_e32 v0, 11, v0
	v_lshl_add_u64 v[16:17], v[16:17], 0, v[0:1]
	global_store_dwordx4 v[16:17], v[28:31], off sc0 sc1
	s_waitcnt lgkmcnt(0)

; #define LAS __attribute__((address_space(3)))
; #define TR_TRY(CNT, NBLK, ...) if (r < (CNT)) { const int k0 = 64 * (r / (NBLK)), n0 = 32 * (r % (NBLK)); (void)k0; (void)n0; __VA_ARGS__; continue; } r -= (CNT);
; #define TR_TRY(CNT, NBLK, ...) if (r < (CNT)) { const int k0 = 64 * (r / (NBLK)), n0 = 32 * (r % (NBLK)); (void)k0; (void)n0; __VA_ARGS__; continue; } r -= (CNT);
; __device__ __forceinline__ void tr_item(const float* W, int N, int k0, int n0, bf16* WT, int Kd, int drow0, int dk0, LAS float* scr, int lane) {
;     {
;         float wv[32]; const int n = n0 + (lane & 31); const float* wp = W + (size_t)(k0 + (lane >> 5)) * N + n;
; #pragma unroll
;         for (int i = 0; i < 32; ++i) wv[i] = (n < N) ? wp[(size_t)(2 * i) * N] : 0.f;
; #pragma unroll
;         for (int i = 0; i < 32; ++i) scr[(2 * i + (lane >> 5)) * 33 + (lane & 31)] = wv[i];
;     }
; __global__ void __launch_bounds__(NTHREADS, 2) mega_fwd(Args a_unused) {
;     ...
;             TR_TRY(I_WD, D / 32, tr_item(ap->in[8], D, k0, n0, Wd1, FF, n0, k0, scr, lane))
.LBB0_185:
	s_andn2_b64 vcc, exec, s[4:5]
	s_cbranch_vccnz .LBB0_187
	v_mov_b64_e32 v[16:17], s[38:39]
	global_load_dwordx2 v[16:17], v[16:17], off offset:64
	s_add_i32 s5, s17, 0x80001820
	s_and_b32 s5, s5, 0x7fffffc0
	s_and_b32 s4, s7, 0x3e0
	v_or_b32_e32 v0, s5, v159
	v_or_b32_e32 v27, s4, v158
	v_lshlrev_b64 v[28:29], 12, v[0:1]
	v_lshlrev_b32_e32 v0, 2, v27
	s_lshl_b32 s10, s5, 1
	s_waitcnt vmcnt(0) lgkmcnt(0)
	v_lshl_add_u64 v[16:17], v[16:17], 0, v[28:29]
	v_lshl_add_u64 v[16:17], v[16:17], 0, v[0:1]
	v_add_co_u32_e32 v28, vcc, 0x2000, v16
	s_nop 1
	v_addc_co_u32_e32 v29, vcc, 0, v17, vcc
	v_add_co_u32_e32 v30, vcc, 0x4000, v16
	s_nop 1
	v_addc_co_u32_e32 v31, vcc, 0, v17, vcc
	v_add_co_u32_e32 v32, vcc, 0x6000, v16
	s_nop 1
	v_addc_co_u32_e32 v33, vcc, 0, v17, vcc
	v_add_co_u32_e32 v34, vcc, 0x8000, v16
	s_nop 1
	v_addc_co_u32_e32 v35, vcc, 0, v17, vcc
	v_add_co_u32_e32 v36, vcc, 0xa000, v16
	s_nop 1
	v_addc_co_u32_e32 v37, vcc, 0, v17, vcc
	v_add_co_u32_e32 v38, vcc, 0xc000, v16
	s_nop 1
	v_addc_co_u32_e32 v39, vcc, 0, v17, vcc
	v_add_co_u32_e32 v40, vcc, 0xe000, v16
	s_nop 1
	v_addc_co_u32_e32 v41, vcc, 0, v17, vcc
	v_add_co_u32_e32 v42, vcc, 0x10000, v16
	global_load_dword v0, v[16:17], off
	global_load_dword v27, v[28:29], off
	global_load_dword v44, v[30:31], off
	global_load_dword v45, v[32:33], off
	global_load_dword v46, v[34:35], off
	global_load_dword v47, v[36:37], off
	global_load_dword v48, v[38:39], off
	global_load_dword v49, v[40:41], off
	v_addc_co_u32_e32 v43, vcc, 0, v17, vcc
	v_add_co_u32_e32 v28, vcc, 0x12000, v16
	s_nop 1
	v_addc_co_u32_e32 v29, vcc, 0, v17, vcc
	v_add_co_u32_e32 v30, vcc, 0x14000, v16
	s_nop 1
	v_addc_co_u32_e32 v31, vcc, 0, v17, vcc
	v_add_co_u32_e32 v32, vcc, 0x16000, v16
	s_nop 1
	v_addc_co_u32_e32 v33, vcc, 0, v17, vcc
	v_add_co_u32_e32 v34, vcc, 0x18000, v16
	s_nop 1
	v_addc_co_u32_e32 v35, vcc, 0, v17, vcc
	v_add_co_u32_e32 v36, vcc, 0x1a000, v16
	s_nop 1
	v_addc_co_u32_e32 v37, vcc, 0, v17, vcc
	v_add_co_u32_e32 v38, vcc, 0x1c000, v16
	s_nop 1
	v_addc_co_u32_e32 v39, vcc, 0, v17, vcc
	v_add_co_u32_e32 v40, vcc, 0x1e000, v16
	s_nop 1
	v_addc_co_u32_e32 v41, vcc, 0, v17, vcc
	global_load_dword v50, v[42:43], off
	global_load_dword v51, v[28:29], off
	global_load_dword v52, v[30:31], off
	global_load_dword v53, v[32:33], off
	global_load_dword v54, v[34:35], off
	global_load_dword v55, v[36:37], off
	global_load_dword v56, v[38:39], off
	global_load_dword v57, v[40:41], off
	v_add_co_u32_e32 v28, vcc, 0x20000, v16
	s_nop 1
	v_addc_co_u32_e32 v29, vcc, 0, v17, vcc
	v_add_co_u32_e32 v30, vcc, 0x22000, v16
	s_nop 1
	v_addc_co_u32_e32 v31, vcc, 0, v17, vcc
	v_add_co_u32_e32 v32, vcc, 0x24000, v16
	s_nop 1
	v_addc_co_u32_e32 v33, vcc, 0, v17, vcc
	v_add_co_u32_e32 v34, vcc, 0x26000, v16
	s_nop 1
	v_addc_co_u32_e32 v35, vcc, 0, v17, vcc
	v_add_co_u32_e32 v36, vcc, 0x28000, v16
	s_nop 1
	v_addc_co_u32_e32 v37, vcc, 0, v17, vcc
	v_add_co_u32_e32 v38, vcc, 0x2a000, v16
	s_nop 1
	v_addc_co_u32_e32 v39, vcc, 0, v17, vcc
	v_add_co_u32_e32 v40, vcc, 0x2c000, v16
	s_nop 1
	v_addc_co_u32_e32 v41, vcc, 0, v17, vcc
	v_add_co_u32_e32 v42, vcc, 0x2e000, v16
	s_nop 1
	v_addc_co_u32_e32 v43, vcc, 0, v17, vcc
	global_load_dword v58, v[28:29], off
	global_load_dword v59, v[30:31], off
	global_load_dword v60, v[32:33], off
	global_load_dword v61, v[34:35], off
	global_load_dword v62, v[36:37], off
	global_load_dword v63, v[38:39], off
	global_load_dword v64, v[40:41], off
	s_nop 0
	global_load_dword v42, v[42:43], off
	v_add_co_u32_e32 v28, vcc, 0x30000, v16
	s_nop 1
	v_addc_co_u32_e32 v29, vcc, 0, v17, vcc
	v_add_co_u32_e32 v30, vcc, 0x32000, v16
	s_nop 1
	v_addc_co_u32_e32 v31, vcc, 0, v17, vcc
	v_add_co_u32_e32 v32, vcc, 0x34000, v16
	s_nop 1
	v_addc_co_u32_e32 v33, vcc, 0, v17, vcc
	v_add_co_u32_e32 v34, vcc, 0x36000, v16
	s_nop 1
	v_addc_co_u32_e32 v35, vcc, 0, v17, vcc
	v_add_co_u32_e32 v36, vcc, 0x38000, v16
	s_nop 1
	v_addc_co_u32_e32 v37, vcc, 0, v17, vcc
	v_add_co_u32_e32 v38, vcc, 0x3a000, v16
	s_nop 1
	v_addc_co_u32_e32 v39, vcc, 0, v17, vcc
	v_add_co_u32_e32 v40, vcc, 0x3c000, v16
	s_nop 1
	v_addc_co_u32_e32 v41, vcc, 0, v17, vcc
	v_add_co_u32_e32 v16, vcc, 0x3e000, v16
	s_nop 1
	v_addc_co_u32_e32 v17, vcc, 0, v17, vcc
	global_load_dword v28, v[28:29], off
	s_nop 0
	global_load_dword v29, v[30:31], off
	s_nop 0
	global_load_dword v30, v[32:33], off
	global_load_dword v31, v[34:35], off
	s_nop 0
	global_load_dword v32, v[36:37], off
	global_load_dword v33, v[38:39], off
	global_load_dword v34, v[40:41], off
	s_nop 0
	global_load_dword v16, v[16:17], off
	s_waitcnt vmcnt(0) lgkmcnt(0)
	ds_write2_b32 v18, v0, v27 offset1:66
	ds_write2_b32 v18, v44, v45 offset0:132 offset1:198
	ds_write2_b32 v20, v46, v47 offset0:8 offset1:74
	ds_write2_b32 v20, v48, v49 offset0:140 offset1:206
	ds_write2_b32 v21, v50, v51 offset0:16 offset1:82
	ds_write2_b32 v21, v52, v53 offset0:148 offset1:214
	ds_write2_b32 v22, v54, v55 offset0:24 offset1:90
	ds_write2_b32 v22, v56, v57 offset0:156 offset1:222
	ds_write2_b32 v23, v58, v59 offset0:32 offset1:98
	ds_write2_b32 v23, v60, v61 offset0:164 offset1:230
	ds_write2_b32 v24, v62, v63 offset0:40 offset1:106
	ds_write2_b32 v24, v64, v42 offset0:172 offset1:238
	ds_write2_b32 v25, v28, v29 offset0:48 offset1:114
	ds_write2_b32 v25, v30, v31 offset0:180 offset1:246
	ds_write2_b32 v26, v32, v33 offset0:56 offset1:122
	ds_write2_b32 v26, v34, v16 offset0:188 offset1:254
	s_waitcnt lgkmcnt(0)
; #define LAS __attribute__((address_space(3)))
; #define LDS_WAIT() asm volatile("s_waitcnt lgkmcnt(0)" ::: "memory")
; __device__ __forceinline__ unsigned pk2(float lo, float hi) { return f2bf(lo) | (f2bf(hi) << 16); }
; __device__ __forceinline__ void tr_item(const float* W, int N, int k0, int n0, bf16* WT, int Kd, int drow0, int dk0, LAS float* scr, int lane) {
;     ...
;     LDS_WAIT();
;     const int c = lane & 7;
; #pragma unroll
;     for (int j = 0; j < 4; ++j) { const int n = (lane >> 3) + 8 * j; const LAS float* s = scr + (8 * c) * 33 + n;
;         v4u o; o.x = pk2(s[0 * 33], s[1 * 33]); o.y = pk2(s[2 * 33], s[3 * 33]); o.z = pk2(s[4 * 33], s[5 * 33]); o.w = pk2(s[6 * 33], s[7 * 33]);
;         *(v4u*)(WT + (size_t)(drow0 + n) * Kd + dk0 + 8 * c) = o; }
;     LDS_WAIT();
	ds_read_b32 v0, v19
	ds_read_b32 v27, v19 offset:132
	ds_read_b32 v29, v19 offset:264
	ds_read_b32 v30, v19 offset:396
	ds_read_b32 v31, v19 offset:528
	ds_read_b32 v32, v19 offset:660
	ds_read_b32 v33, v19 offset:792
	ds_read_b32 v34, v19 offset:924
	s_waitcnt lgkmcnt(7)
	v_bfe_u32 v28, v0, 16, 1
	v_add3_u32 v0, v0, v28, s59
	s_waitcnt lgkmcnt(6)
	v_bfe_u32 v28, v27, 16, 1
	v_lshrrev_b32_e32 v0, 16, v0
	v_add3_u32 v27, v27, v28, s59
	v_and_or_b32 v28, v27, s60, v0
	s_waitcnt lgkmcnt(5)
	v_bfe_u32 v0, v29, 16, 1
	v_add3_u32 v0, v29, v0, s59
	s_waitcnt lgkmcnt(4)
	v_bfe_u32 v27, v30, 16, 1
	v_lshrrev_b32_e32 v0, 16, v0
	v_add3_u32 v27, v30, v27, s59
	v_and_or_b32 v29, v27, s60, v0
	s_waitcnt lgkmcnt(3)
	v_bfe_u32 v0, v31, 16, 1
	v_add3_u32 v0, v31, v0, s59
	s_waitcnt lgkmcnt(2)
	v_bfe_u32 v27, v32, 16, 1
	v_lshrrev_b32_e32 v0, 16, v0
	v_add3_u32 v27, v32, v27, s59
	v_and_or_b32 v30, v27, s60, v0
	s_waitcnt lgkmcnt(1)
	v_bfe_u32 v0, v33, 16, 1
	v_add3_u32 v0, v33, v0, s59
	s_waitcnt lgkmcnt(0)
	v_bfe_u32 v27, v34, 16, 1
	v_lshrrev_b32_e32 v0, 16, v0
	v_add3_u32 v27, v34, v27, s59
	v_and_or_b32 v31, v27, s60, v0
	v_or_b32_e32 v0, s4, v160
	v_mul_u32_u24_e32 v0, 0xb00, v0
	v_lshl_add_u64 v[16:17], v[12:13], 0, s[10:11]
	v_lshlrev_b32_e32 v0, 1, v0
	v_lshl_add_u64 v[32:33], v[16:17], 0, v[0:1]
	global_store_dwordx4 v[32:33], v[28:31], off sc0 sc1
	ds_read_b32 v0, v19 offset:32
	ds_read_b32 v27, v19 offset:164
	ds_read_b32 v29, v19 offset:296
	ds_read_b32 v30, v19 offset:428
	ds_read_b32 v31, v19 offset:560
	ds_read_b32 v32, v19 offset:692
	ds_read_b32 v33, v19 offset:824
	ds_read_b32 v34, v19 offset:956
	s_waitcnt lgkmcnt(0)
	v_bfe_u32 v28, v0, 16, 1
	v_add3_u32 v0, v0, v28, s59
	v_bfe_u32 v28, v27, 16, 1
	v_lshrrev_b32_e32 v0, 16, v0
	v_add3_u32 v27, v27, v28, s59
	v_and_or_b32 v28, v27, s60, v0
	v_bfe_u32 v0, v29, 16, 1
	v_add3_u32 v0, v29, v0, s59
	v_bfe_u32 v27, v30, 16, 1
	v_lshrrev_b32_e32 v0, 16, v0
	v_add3_u32 v27, v30, v27, s59
	v_and_or_b32 v29, v27, s60, v0
	v_bfe_u32 v0, v31, 16, 1
	v_add3_u32 v0, v31, v0, s59
	v_bfe_u32 v27, v32, 16, 1
	v_lshrrev_b32_e32 v0, 16, v0
	v_add3_u32 v27, v32, v27, s59
	v_and_or_b32 v30, v27, s60, v0
	v_bfe_u32 v0, v33, 16, 1
	v_add3_u32 v0, v33, v0, s59
	v_bfe_u32 v27, v34, 16, 1
	v_lshrrev_b32_e32 v0, 16, v0
	v_add3_u32 v27, v34, v27, s59
	v_and_or_b32 v31, v27, s60, v0
	v_or_b32_e32 v0, s4, v161
	v_mul_u32_u24_e32 v0, 0xb00, v0
	v_lshlrev_b32_e32 v0, 1, v0
	v_lshl_add_u64 v[32:33], v[16:17], 0, v[0:1]
	global_store_dwordx4 v[32:33], v[28:31], off sc0 sc1
	ds_read_b32 v0, v19 offset:64
	ds_read_b32 v27, v19 offset:196
	ds_read_b32 v29, v19 offset:328
	ds_read_b32 v30, v19 offset:460
	ds_read_b32 v31, v19 offset:592
	ds_read_b32 v32, v19 offset:724
	ds_read_b32 v33, v19 offset:856
	ds_read_b32 v34, v19 offset:988
	s_waitcnt lgkmcnt(0)
	v_bfe_u32 v28, v0, 16, 1
	v_add3_u32 v0, v0, v28, s59
	v_bfe_u32 v28, v27, 16, 1
	v_lshrrev_b32_e32 v0, 16, v0
	v_add3_u32 v27, v27, v28, s59
	v_and_or_b32 v28, v27, s60, v0
	v_bfe_u32 v0, v29, 16, 1
	v_add3_u32 v0, v29, v0, s59
	v_bfe_u32 v27, v30, 16, 1
	v_lshrrev_b32_e32 v0, 16, v0
	v_add3_u32 v27, v30, v27, s59
	v_and_or_b32 v29, v27, s60, v0
	v_bfe_u32 v0, v31, 16, 1
	v_add3_u32 v0, v31, v0, s59
	v_bfe_u32 v27, v32, 16, 1
	v_lshrrev_b32_e32 v0, 16, v0
	v_add3_u32 v27, v32, v27, s59
	v_and_or_b32 v30, v27, s60, v0
	v_bfe_u32 v0, v33, 16, 1
	v_add3_u32 v0, v33, v0, s59
	v_bfe_u32 v27, v34, 16, 1
	v_lshrrev_b32_e32 v0, 16, v0
	v_add3_u32 v27, v34, v27, s59
	v_and_or_b32 v31, v27, s60, v0
	v_or_b32_e32 v0, s4, v162
	v_mul_u32_u24_e32 v0, 0xb00, v0
	v_lshlrev_b32_e32 v0, 1, v0
	v_lshl_add_u64 v[32:33], v[16:17], 0, v[0:1]
	global_store_dwordx4 v[32:33], v[28:31], off sc0 sc1
	ds_read_b32 v0, v19 offset:96
	ds_read_b32 v27, v19 offset:228
	ds_read_b32 v29, v19 offset:360
	ds_read_b32 v30, v19 offset:492
	ds_read_b32 v31, v19 offset:624
	ds_read_b32 v32, v19 offset:756
	ds_read_b32 v33, v19 offset:888
	ds_read_b32 v34, v19 offset:1020
	s_waitcnt lgkmcnt(0)
	v_bfe_u32 v28, v0, 16, 1
	v_add3_u32 v0, v0, v28, s59
	v_bfe_u32 v28, v27, 16, 1
	v_lshrrev_b32_e32 v0, 16, v0
	v_add3_u32 v27, v27, v28, s59
	v_and_or_b32 v28, v27, s60, v0
	v_bfe_u32 v0, v29, 16, 1
	v_add3_u32 v0, v29, v0, s59
	v_bfe_u32 v27, v30, 16, 1
	v_lshrrev_b32_e32 v0, 16, v0
	v_add3_u32 v27, v30, v27, s59
	v_and_or_b32 v29, v27, s60, v0
	v_bfe_u32 v0, v31, 16, 1
	v_add3_u32 v0, v31, v0, s59
	v_bfe_u32 v27, v32, 16, 1
	v_lshrrev_b32_e32 v0, 16, v0
	v_add3_u32 v27, v32, v27, s59
	v_and_or_b32 v30, v27, s60, v0
	v_bfe_u32 v0, v33, 16, 1
	v_add3_u32 v0, v33, v0, s59
	v_bfe_u32 v27, v34, 16, 1
	v_lshrrev_b32_e32 v0, 16, v0
	v_add3_u32 v27, v34, v27, s59
	v_and_or_b32 v31, v27, s60, v0
	v_or_b32_e32 v0, s4, v163
	v_mul_u32_u24_e32 v0, 0xb00, v0
	v_lshlrev_b32_e32 v0, 1, v0
	v_lshl_add_u64 v[16:17], v[16:17], 0, v[0:1]
	global_store_dwordx4 v[16:17], v[28:31], off sc0 sc1
	s_waitcnt lgkmcnt(0)

; #define LAS __attribute__((address_space(3)))
; #define TR_TRY(CNT, NBLK, ...) if (r < (CNT)) { const int k0 = 64 * (r / (NBLK)), n0 = 32 * (r % (NBLK)); (void)k0; (void)n0; __VA_ARGS__; continue; } r -= (CNT);
; #define TR_TRY(CNT, NBLK, ...) if (r < (CNT)) { const int k0 = 64 * (r / (NBLK)), n0 = 32 * (r % (NBLK)); (void)k0; (void)n0; __VA_ARGS__; continue; } r -= (CNT);
; __device__ __forceinline__ void tr_item(const float* W, int N, int k0, int n0, bf16* WT, int Kd, int drow0, int dk0, LAS float* scr, int lane) {
;     {
;         float wv[32]; const int n = n0 + (lane & 31); const float* wp = W + (size_t)(k0 + (lane >> 5)) * N + n;
; #pragma unroll
;         for (int i = 0; i < 32; ++i) wv[i] = (n < N) ? wp[(size_t)(2 * i) * N] : 0.f;
; #pragma unroll
;         for (int i = 0; i < 32; ++i) scr[(2 * i + (lane >> 5)) * 33 + (lane & 31)] = wv[i];
;     }
; __global__ void __launch_bounds__(NTHREADS, 2) mega_fwd(Args a_unused) {
;     ...
;             TR_TRY(I_GU, FF / 32, tr_item(ap->in[7], FF, k0, n0, Wgu1, D, (n0 / 128) * 256 + 128 + (n0 % 128), k0, scr, lane))
.LBB0_188:
	s_andn2_b64 vcc, exec, s[4:5]
	s_cbranch_vccnz .LBB0_190
	v_mov_b64_e32 v[16:17], s[38:39]
	global_load_dwordx2 v[16:17], v[16:17], off offset:56
	s_add_i32 s4, s97, 0xfa80
	s_and_b32 s5, s4, 0xffff
	s_mul_i32 s5, s5, 0xba2f
	s_lshr_b32 s10, s5, 22
	s_lshr_b32 s5, s5, 16
	s_mulk_i32 s10, 0x58
	s_and_b32 s5, s5, 0xffc0
	s_sub_i32 s4, s4, s10
	v_or_b32_e32 v0, s5, v159
	s_and_b32 s4, s4, 0xffff
	v_mul_u32_u24_e32 v0, 0xb00, v0
	s_lshl_b32 s10, s4, 5
	v_lshlrev_b32_e32 v0, 2, v0
	v_or_b32_e32 v27, s10, v158
	s_lshl_b32 s4, s4, 6
	s_and_b32 s4, s4, 0x1f00
	s_and_b32 s10, s10, 0x60
	s_or_b32 s4, s10, s4
	s_bitset1_b32 s4, 7
	s_lshl_b32 s10, s5, 1
	s_waitcnt vmcnt(0) lgkmcnt(0)
	v_lshl_add_u64 v[16:17], v[16:17], 0, v[0:1]
	v_lshlrev_b32_e32 v0, 2, v27
	v_lshl_add_u64 v[16:17], v[16:17], 0, v[0:1]
	v_add_co_u32_e32 v28, vcc, s70, v16
	s_nop 1
	v_addc_co_u32_e32 v29, vcc, 0, v17, vcc
	v_add_co_u32_e32 v30, vcc, s71, v16
	s_nop 1
	v_addc_co_u32_e32 v31, vcc, 0, v17, vcc
	v_add_co_u32_e32 v32, vcc, s45, v16
	s_nop 1
	v_addc_co_u32_e32 v33, vcc, 0, v17, vcc
	v_add_co_u32_e32 v34, vcc, s47, v16
	s_nop 1
	v_addc_co_u32_e32 v35, vcc, 0, v17, vcc
	v_add_co_u32_e32 v36, vcc, s67, v16
	s_nop 1
	v_addc_co_u32_e32 v37, vcc, 0, v17, vcc
	v_add_co_u32_e32 v38, vcc, s68, v16
	s_nop 1
	v_addc_co_u32_e32 v39, vcc, 0, v17, vcc
	v_add_co_u32_e32 v40, vcc, s53, v16
	s_nop 1
	v_addc_co_u32_e32 v41, vcc, 0, v17, vcc
	v_add_co_u32_e32 v42, vcc, s56, v16
	global_load_dword v0, v[16:17], off
	global_load_dword v27, v[28:29], off offset:2048
	global_load_dword v56, v[30:31], off
	global_load_dword v57, v[32:33], off offset:2048
	global_load_dword v58, v[34:35], off
	global_load_dword v59, v[36:37], off offset:2048
	global_load_dword v60, v[38:39], off
	global_load_dword v61, v[40:41], off offset:2048
	v_addc_co_u32_e32 v43, vcc, 0, v17, vcc
	v_add_co_u32_e32 v44, vcc, s78, v16
	s_nop 1
	v_addc_co_u32_e32 v45, vcc, 0, v17, vcc
	v_add_co_u32_e32 v46, vcc, s79, v16
	s_nop 1
	v_addc_co_u32_e32 v47, vcc, 0, v17, vcc
	v_add_co_u32_e32 v48, vcc, s58, v16
	s_nop 1
	v_addc_co_u32_e32 v49, vcc, 0, v17, vcc
	v_add_co_u32_e32 v50, vcc, s80, v16
	s_nop 1
	v_addc_co_u32_e32 v51, vcc, 0, v17, vcc
	v_add_co_u32_e32 v52, vcc, s81, v16
	s_nop 1
	v_addc_co_u32_e32 v53, vcc, 0, v17, vcc
	v_add_co_u32_e32 v54, vcc, s74, v16
	s_nop 1
	v_addc_co_u32_e32 v55, vcc, 0, v17, vcc
	v_add_co_u32_e32 v28, vcc, s82, v16
	s_nop 1
	v_addc_co_u32_e32 v29, vcc, 0, v17, vcc
	global_load_dword v62, v[42:43], off
	s_nop 0
	global_load_dword v44, v[44:45], off offset:2048
	s_nop 0
	global_load_dword v45, v[46:47], off
	s_nop 0
	global_load_dword v46, v[48:49], off offset:2048
	global_load_dword v47, v[50:51], off
	s_nop 0
	global_load_dword v48, v[52:53], off offset:2048
	global_load_dword v49, v[54:55], off
	global_load_dword v50, v[28:29], off offset:2048
	v_add_co_u32_e32 v28, vcc, s75, v16
	s_nop 1
	v_addc_co_u32_e32 v29, vcc, 0, v17, vcc
	v_add_co_u32_e32 v30, vcc, s83, v16
	s_nop 1
	v_addc_co_u32_e32 v31, vcc, 0, v17, vcc
	v_add_co_u32_e32 v32, vcc, s84, v16
	s_nop 1
	v_addc_co_u32_e32 v33, vcc, 0, v17, vcc
	v_add_co_u32_e32 v34, vcc, s76, v16
	s_nop 1
	v_addc_co_u32_e32 v35, vcc, 0, v17, vcc
	v_add_co_u32_e32 v36, vcc, s85, v16
	s_nop 1
	v_addc_co_u32_e32 v37, vcc, 0, v17, vcc
	v_add_co_u32_e32 v38, vcc, s77, v16
	s_nop 1
	v_addc_co_u32_e32 v39, vcc, 0, v17, vcc
	v_add_co_u32_e32 v40, vcc, s86, v16
	s_nop 1
	v_addc_co_u32_e32 v41, vcc, 0, v17, vcc
	v_add_co_u32_e32 v42, vcc, s87, v16
	s_nop 1
	v_addc_co_u32_e32 v43, vcc, 0, v17, vcc
	global_load_dword v51, v[28:29], off
	global_load_dword v52, v[30:31], off offset:2048
	global_load_dword v53, v[32:33], off
	global_load_dword v54, v[34:35], off offset:2048
	global_load_dword v55, v[36:37], off
	global_load_dword v63, v[38:39], off offset:2048
	global_load_dword v64, v[40:41], off
	s_nop 0
	global_load_dword v42, v[42:43], off offset:2048
	v_add_co_u32_e32 v28, vcc, s88, v16
	s_nop 1
	v_addc_co_u32_e32 v29, vcc, 0, v17, vcc
	v_add_co_u32_e32 v30, vcc, s89, v16
	s_nop 1
	v_addc_co_u32_e32 v31, vcc, 0, v17, vcc
	v_add_co_u32_e32 v32, vcc, s90, v16
	s_nop 1
	v_addc_co_u32_e32 v33, vcc, 0, v17, vcc
	v_add_co_u32_e32 v34, vcc, s91, v16
	s_nop 1
	v_addc_co_u32_e32 v35, vcc, 0, v17, vcc
	v_add_co_u32_e32 v36, vcc, s92, v16
	s_nop 1
	v_addc_co_u32_e32 v37, vcc, 0, v17, vcc
	v_add_co_u32_e32 v38, vcc, s93, v16
	s_nop 1
	v_addc_co_u32_e32 v39, vcc, 0, v17, vcc
	v_add_co_u32_e32 v40, vcc, s94, v16
	s_nop 1
	v_addc_co_u32_e32 v41, vcc, 0, v17, vcc
	v_add_co_u32_e32 v16, vcc, s95, v16
	s_nop 1
	v_addc_co_u32_e32 v17, vcc, 0, v17, vcc
	global_load_dword v28, v[28:29], off
	s_nop 0
	global_load_dword v29, v[30:31], off offset:2048
	s_nop 0
	global_load_dword v30, v[32:33], off
	global_load_dword v31, v[34:35], off offset:2048
	s_nop 0
	global_load_dword v32, v[36:37], off
	global_load_dword v33, v[38:39], off offset:2048
	global_load_dword v34, v[40:41], off
	s_nop 0
	global_load_dword v16, v[16:17], off offset:2048
	s_waitcnt vmcnt(0) lgkmcnt(0)
; #define LAS __attribute__((address_space(3)))
; #define LDS_WAIT() asm volatile("s_waitcnt lgkmcnt(0)" ::: "memory")
; __device__ __forceinline__ unsigned pk2(float lo, float hi) { return f2bf(lo) | (f2bf(hi) << 16); }
; __device__ __forceinline__ void tr_item(const float* W, int N, int k0, int n0, bf16* WT, int Kd, int drow0, int dk0, LAS float* scr, int lane) {
;     ...
;     LDS_WAIT();
;     const int c = lane & 7;
; #pragma unroll
;     for (int j = 0; j < 4; ++j) { const int n = (lane >> 3) + 8 * j; const LAS float* s = scr + (8 * c) * 33 + n;
;         v4u o; o.x = pk2(s[0 * 33], s[1 * 33]); o.y = pk2(s[2 * 33], s[3 * 33]); o.z = pk2(s[4 * 33], s[5 * 33]); o.w = pk2(s[6 * 33], s[7 * 33]);
;         *(v4u*)(WT + (size_t)(drow0 + n) * Kd + dk0 + 8 * c) = o; }
;     LDS_WAIT();
	ds_write2_b32 v18, v0, v27 offset1:66
	ds_write2_b32 v18, v56, v57 offset0:132 offset1:198
	ds_write2_b32 v20, v58, v59 offset0:8 offset1:74
	ds_write2_b32 v20, v60, v61 offset0:140 offset1:206
	ds_write2_b32 v21, v62, v44 offset0:16 offset1:82
	ds_write2_b32 v21, v45, v46 offset0:148 offset1:214
	ds_write2_b32 v22, v47, v48 offset0:24 offset1:90
	ds_write2_b32 v22, v49, v50 offset0:156 offset1:222
	ds_write2_b32 v23, v51, v52 offset0:32 offset1:98
	ds_write2_b32 v23, v53, v54 offset0:164 offset1:230
	ds_write2_b32 v24, v55, v63 offset0:40 offset1:106
	ds_write2_b32 v24, v64, v42 offset0:172 offset1:238
	ds_write2_b32 v25, v28, v29 offset0:48 offset1:114
	ds_write2_b32 v25, v30, v31 offset0:180 offset1:246
	ds_write2_b32 v26, v32, v33 offset0:56 offset1:122
	ds_write2_b32 v26, v34, v16 offset0:188 offset1:254
	s_waitcnt lgkmcnt(0)
	ds_read_b32 v0, v19
	ds_read_b32 v27, v19 offset:132
	ds_read_b32 v29, v19 offset:264
	ds_read_b32 v30, v19 offset:396
	ds_read_b32 v31, v19 offset:528
	ds_read_b32 v32, v19 offset:660
	ds_read_b32 v33, v19 offset:792
	ds_read_b32 v34, v19 offset:924
	s_waitcnt lgkmcnt(7)
	v_bfe_u32 v28, v0, 16, 1
	v_add3_u32 v0, v0, v28, s59
	s_waitcnt lgkmcnt(6)
	v_bfe_u32 v28, v27, 16, 1
	v_lshrrev_b32_e32 v0, 16, v0
	v_add3_u32 v27, v27, v28, s59
	v_and_or_b32 v28, v27, s60, v0
	s_waitcnt lgkmcnt(5)
	v_bfe_u32 v0, v29, 16, 1
	v_add3_u32 v0, v29, v0, s59
	s_waitcnt lgkmcnt(4)
	v_bfe_u32 v27, v30, 16, 1
	v_lshrrev_b32_e32 v0, 16, v0
	v_add3_u32 v27, v30, v27, s59
	v_and_or_b32 v29, v27, s60, v0
	s_waitcnt lgkmcnt(3)
	v_bfe_u32 v0, v31, 16, 1
	v_add3_u32 v0, v31, v0, s59
	s_waitcnt lgkmcnt(2)
	v_bfe_u32 v27, v32, 16, 1
	v_lshrrev_b32_e32 v0, 16, v0
	v_add3_u32 v27, v32, v27, s59
	v_and_or_b32 v30, v27, s60, v0
	s_waitcnt lgkmcnt(1)
	v_bfe_u32 v0, v33, 16, 1
	v_add3_u32 v0, v33, v0, s59
	s_waitcnt lgkmcnt(0)
	v_bfe_u32 v27, v34, 16, 1
	v_lshrrev_b32_e32 v0, 16, v0
	v_add3_u32 v27, v34, v27, s59
	v_and_or_b32 v31, v27, s60, v0
	v_or_b32_e32 v0, s4, v160
	v_lshl_add_u64 v[16:17], v[14:15], 0, s[10:11]
	v_lshlrev_b32_e32 v0, 11, v0
	v_lshl_add_u64 v[32:33], v[16:17], 0, v[0:1]
	global_store_dwordx4 v[32:33], v[28:31], off sc0 sc1
	ds_read_b32 v0, v19 offset:32
	ds_read_b32 v27, v19 offset:164
	ds_read_b32 v29, v19 offset:296
	ds_read_b32 v30, v19 offset:428
	ds_read_b32 v31, v19 offset:560
	ds_read_b32 v32, v19 offset:692
	ds_read_b32 v33, v19 offset:824
	ds_read_b32 v34, v19 offset:956
	s_waitcnt lgkmcnt(0)
	v_bfe_u32 v28, v0, 16, 1
	v_add3_u32 v0, v0, v28, s59
	v_bfe_u32 v28, v27, 16, 1
	v_lshrrev_b32_e32 v0, 16, v0
	v_add3_u32 v27, v27, v28, s59
	v_and_or_b32 v28, v27, s60, v0
	v_bfe_u32 v0, v29, 16, 1
	v_add3_u32 v0, v29, v0, s59
	v_bfe_u32 v27, v30, 16, 1
	v_lshrrev_b32_e32 v0, 16, v0
	v_add3_u32 v27, v30, v27, s59
	v_and_or_b32 v29, v27, s60, v0
	v_bfe_u32 v0, v31, 16, 1
	v_add3_u32 v0, v31, v0, s59
	v_bfe_u32 v27, v32, 16, 1
	v_lshrrev_b32_e32 v0, 16, v0
	v_add3_u32 v27, v32, v27, s59
	v_and_or_b32 v30, v27, s60, v0
	v_bfe_u32 v0, v33, 16, 1
	v_add3_u32 v0, v33, v0, s59
	v_bfe_u32 v27, v34, 16, 1
	v_lshrrev_b32_e32 v0, 16, v0
	v_add3_u32 v27, v34, v27, s59
	v_and_or_b32 v31, v27, s60, v0
	v_or_b32_e32 v0, s4, v161
	v_lshlrev_b32_e32 v0, 11, v0
	v_lshl_add_u64 v[32:33], v[16:17], 0, v[0:1]
	global_store_dwordx4 v[32:33], v[28:31], off sc0 sc1
	ds_read_b32 v0, v19 offset:64
	ds_read_b32 v27, v19 offset:196
	ds_read_b32 v29, v19 offset:328
	ds_read_b32 v30, v19 offset:460
	ds_read_b32 v31, v19 offset:592
	ds_read_b32 v32, v19 offset:724
	ds_read_b32 v33, v19 offset:856
	ds_read_b32 v34, v19 offset:988
	s_waitcnt lgkmcnt(0)
	v_bfe_u32 v28, v0, 16, 1
	v_add3_u32 v0, v0, v28, s59
	v_bfe_u32 v28, v27, 16, 1
	v_lshrrev_b32_e32 v0, 16, v0
	v_add3_u32 v27, v27, v28, s59
	v_and_or_b32 v28, v27, s60, v0
	v_bfe_u32 v0, v29, 16, 1
	v_add3_u32 v0, v29, v0, s59
	v_bfe_u32 v27, v30, 16, 1
	v_lshrrev_b32_e32 v0, 16, v0
	v_add3_u32 v27, v30, v27, s59
	v_and_or_b32 v29, v27, s60, v0
	v_bfe_u32 v0, v31, 16, 1
	v_add3_u32 v0, v31, v0, s59
	v_bfe_u32 v27, v32, 16, 1
	v_lshrrev_b32_e32 v0, 16, v0
	v_add3_u32 v27, v32, v27, s59
	v_and_or_b32 v30, v27, s60, v0
	v_bfe_u32 v0, v33, 16, 1
	v_add3_u32 v0, v33, v0, s59
	v_bfe_u32 v27, v34, 16, 1
	v_lshrrev_b32_e32 v0, 16, v0
	v_add3_u32 v27, v34, v27, s59
	v_and_or_b32 v31, v27, s60, v0
	v_or_b32_e32 v0, s4, v162
	v_lshlrev_b32_e32 v0, 11, v0
	v_lshl_add_u64 v[32:33], v[16:17], 0, v[0:1]
	global_store_dwordx4 v[32:33], v[28:31], off sc0 sc1
	ds_read_b32 v0, v19 offset:96
	ds_read_b32 v27, v19 offset:228
	ds_read_b32 v29, v19 offset:360
	ds_read_b32 v30, v19 offset:492
	ds_read_b32 v31, v19 offset:624
	ds_read_b32 v32, v19 offset:756
	ds_read_b32 v33, v19 offset:888
	ds_read_b32 v34, v19 offset:1020
	s_waitcnt lgkmcnt(0)
	v_bfe_u32 v28, v0, 16, 1
	v_add3_u32 v0, v0, v28, s59
	v_bfe_u32 v28, v27, 16, 1
	v_lshrrev_b32_e32 v0, 16, v0
	v_add3_u32 v27, v27, v28, s59
	v_and_or_b32 v28, v27, s60, v0
	v_bfe_u32 v0, v29, 16, 1
	v_add3_u32 v0, v29, v0, s59
	v_bfe_u32 v27, v30, 16, 1
	v_lshrrev_b32_e32 v0, 16, v0
	v_add3_u32 v27, v30, v27, s59
	v_and_or_b32 v29, v27, s60, v0
	v_bfe_u32 v0, v31, 16, 1
	v_add3_u32 v0, v31, v0, s59
	v_bfe_u32 v27, v32, 16, 1
	v_lshrrev_b32_e32 v0, 16, v0
	v_add3_u32 v27, v32, v27, s59
	v_and_or_b32 v30, v27, s60, v0
	v_bfe_u32 v0, v33, 16, 1
	v_add3_u32 v0, v33, v0, s59
	v_bfe_u32 v27, v34, 16, 1
	v_lshrrev_b32_e32 v0, 16, v0
	v_add3_u32 v27, v34, v27, s59
	v_and_or_b32 v31, v27, s60, v0
	v_or_b32_e32 v0, s4, v163
	v_lshlrev_b32_e32 v0, 11, v0
	v_lshl_add_u64 v[16:17], v[16:17], 0, v[0:1]
	global_store_dwordx4 v[16:17], v[28:31], off sc0 sc1
	s_waitcnt lgkmcnt(0)

; #define LAS __attribute__((address_space(3)))
; #define TR_TRY(CNT, NBLK, ...) if (r < (CNT)) { const int k0 = 64 * (r / (NBLK)), n0 = 32 * (r % (NBLK)); (void)k0; (void)n0; __VA_ARGS__; continue; } r -= (CNT);
; #define TR_TRY(CNT, NBLK, ...) if (r < (CNT)) { const int k0 = 64 * (r / (NBLK)), n0 = 32 * (r % (NBLK)); (void)k0; (void)n0; __VA_ARGS__; continue; } r -= (CNT);
; __device__ __forceinline__ void tr_item(const float* W, int N, int k0, int n0, bf16* WT, int Kd, int drow0, int dk0, LAS float* scr, int lane) {
;     {
;         float wv[32]; const int n = n0 + (lane & 31); const float* wp = W + (size_t)(k0 + (lane >> 5)) * N + n;
; #pragma unroll
;         for (int i = 0; i < 32; ++i) wv[i] = (n < N) ? wp[(size_t)(2 * i) * N] : 0.f;
; #pragma unroll
;         for (int i = 0; i < 32; ++i) scr[(2 * i + (lane >> 5)) * 33 + (lane & 31)] = wv[i];
;     }
; __global__ void __launch_bounds__(NTHREADS, 2) mega_fwd(Args a_unused) {
;     ...
;             TR_TRY(I_GU, FF / 32, tr_item(ap->in[6], FF, k0, n0, Wgu1, D, (n0 / 128) * 256 + (n0 % 128), k0, scr, lane))
.LBB0_191:
	s_andn2_b64 vcc, exec, s[4:5]
	s_cbranch_vccnz .LBB0_100
	v_mov_b64_e32 v[16:17], s[38:39]
	global_load_dwordx2 v[16:17], v[16:17], off offset:48
	s_mul_hi_i32 s4, s97, 0x2e8ba2e9
	s_lshr_b32 s5, s4, 31
	s_ashr_i32 s10, s4, 4
	s_add_i32 s10, s10, s5
	s_mul_i32 s5, s10, 0xfffff500
	s_lshl_b32 s4, s10, 6
	s_add_i32 s5, s7, s5
	v_or_b32_e32 v0, s4, v159
	v_add_u32_e32 v28, s5, v158
	v_ashrrev_i32_e32 v29, 31, v28
	s_mulk_i32 s10, 0xffa8
	s_add_i32 s10, s97, s10
	s_waitcnt vmcnt(0) lgkmcnt(0)
	v_mad_i64_i32 v[16:17], s[12:13], v0, s96, v[16:17]
	v_lshl_add_u64 v[16:17], v[28:29], 2, v[16:17]
	v_add_co_u32_e32 v28, vcc, s70, v16
	s_bfe_i32 s12, s10, 0x80000
	s_nop 0
	v_addc_co_u32_e32 v29, vcc, 0, v17, vcc
	v_add_co_u32_e32 v30, vcc, s71, v16
	s_bfe_u32 s12, s12, 0x2000d
	s_nop 0
	v_addc_co_u32_e32 v31, vcc, 0, v17, vcc
	v_add_co_u32_e32 v32, vcc, s45, v16
	s_add_i32 s10, s10, s12
	s_nop 0
	v_addc_co_u32_e32 v33, vcc, 0, v17, vcc
	v_add_co_u32_e32 v34, vcc, s47, v16
	s_bfe_u32 s12, s5, 0x70018
	s_nop 0
	v_addc_co_u32_e32 v35, vcc, 0, v17, vcc
	v_add_co_u32_e32 v36, vcc, s67, v16
	s_bfe_i32 s10, s10, 0x80000
	s_nop 0
	v_addc_co_u32_e32 v37, vcc, 0, v17, vcc
	v_add_co_u32_e32 v38, vcc, s68, v16
	s_add_i32 s12, s5, s12
	s_nop 0
	v_addc_co_u32_e32 v39, vcc, 0, v17, vcc
	v_add_co_u32_e32 v40, vcc, s53, v16
	s_sext_i32_i16 s10, s10
	s_nop 0
	v_addc_co_u32_e32 v41, vcc, 0, v17, vcc
	v_add_co_u32_e32 v42, vcc, s56, v16
	s_and_b32 s12, s12, 0xff80
	s_nop 0
	v_addc_co_u32_e32 v43, vcc, 0, v17, vcc
	v_add_co_u32_e32 v44, vcc, s78, v16
	s_lshl_b32 s10, s10, 6
	s_nop 0
	v_addc_co_u32_e32 v45, vcc, 0, v17, vcc
	v_add_co_u32_e32 v46, vcc, s79, v16
	s_sub_i32 s5, s5, s12
	s_nop 0
	v_addc_co_u32_e32 v47, vcc, 0, v17, vcc
	v_add_co_u32_e32 v48, vcc, s58, v16
	s_and_b32 s10, s10, 0xffffff00
	s_nop 0
	v_addc_co_u32_e32 v49, vcc, 0, v17, vcc
	v_add_co_u32_e32 v50, vcc, s80, v16
	s_sext_i32_i16 s5, s5
	s_nop 0
	v_addc_co_u32_e32 v51, vcc, 0, v17, vcc
	v_add_co_u32_e32 v52, vcc, s81, v16
	s_add_i32 s10, s10, s5
	s_nop 0
	v_addc_co_u32_e32 v53, vcc, 0, v17, vcc
	v_add_co_u32_e32 v54, vcc, s74, v16
	s_ashr_i32 s5, s4, 31
	s_nop 0
	v_addc_co_u32_e32 v55, vcc, 0, v17, vcc
	v_add_co_u32_e32 v56, vcc, s82, v16
	s_nop 1
	v_addc_co_u32_e32 v57, vcc, 0, v17, vcc
	global_load_dword v0, v[16:17], off
	global_load_dword v27, v[28:29], off offset:2048
	global_load_dword v58, v[30:31], off
	global_load_dword v59, v[32:33], off offset:2048
	global_load_dword v60, v[34:35], off
	global_load_dword v61, v[36:37], off offset:2048
	global_load_dword v62, v[38:39], off
	global_load_dword v63, v[40:41], off offset:2048
	global_load_dword v64, v[42:43], off
	s_nop 0
	global_load_dword v44, v[44:45], off offset:2048
	s_nop 0
	global_load_dword v45, v[46:47], off
	s_nop 0
	global_load_dword v46, v[48:49], off offset:2048
	global_load_dword v47, v[50:51], off
	s_nop 0
	global_load_dword v48, v[52:53], off offset:2048
	global_load_dword v49, v[54:55], off
	global_load_dword v50, v[56:57], off offset:2048
	v_add_co_u32_e32 v28, vcc, s75, v16
	s_nop 1
	v_addc_co_u32_e32 v29, vcc, 0, v17, vcc
	v_add_co_u32_e32 v30, vcc, s83, v16
	s_nop 1
	v_addc_co_u32_e32 v31, vcc, 0, v17, vcc
	v_add_co_u32_e32 v32, vcc, s84, v16
	s_nop 1
	v_addc_co_u32_e32 v33, vcc, 0, v17, vcc
	v_add_co_u32_e32 v34, vcc, s76, v16
	s_nop 1
	v_addc_co_u32_e32 v35, vcc, 0, v17, vcc
	v_add_co_u32_e32 v36, vcc, s85, v16
	s_nop 1
	v_addc_co_u32_e32 v37, vcc, 0, v17, vcc
	v_add_co_u32_e32 v38, vcc, s77, v16
	s_nop 1
	v_addc_co_u32_e32 v39, vcc, 0, v17, vcc
	v_add_co_u32_e32 v40, vcc, s86, v16
	s_nop 1
	v_addc_co_u32_e32 v41, vcc, 0, v17, vcc
	v_add_co_u32_e32 v42, vcc, s87, v16
	s_nop 1
	v_addc_co_u32_e32 v43, vcc, 0, v17, vcc
	global_load_dword v51, v[28:29], off
	global_load_dword v52, v[30:31], off offset:2048
	global_load_dword v53, v[32:33], off
	global_load_dword v54, v[34:35], off offset:2048
	global_load_dword v55, v[36:37], off
	global_load_dword v56, v[38:39], off offset:2048
	global_load_dword v57, v[40:41], off
	s_nop 0
	global_load_dword v42, v[42:43], off offset:2048
	v_add_co_u32_e32 v28, vcc, s88, v16
	s_nop 1
	v_addc_co_u32_e32 v29, vcc, 0, v17, vcc
	v_add_co_u32_e32 v30, vcc, s89, v16
	s_nop 1
	v_addc_co_u32_e32 v31, vcc, 0, v17, vcc
	v_add_co_u32_e32 v32, vcc, s90, v16
	s_nop 1
	v_addc_co_u32_e32 v33, vcc, 0, v17, vcc
	v_add_co_u32_e32 v34, vcc, s91, v16
	s_nop 1
	v_addc_co_u32_e32 v35, vcc, 0, v17, vcc
	v_add_co_u32_e32 v36, vcc, s92, v16
	s_nop 1
	v_addc_co_u32_e32 v37, vcc, 0, v17, vcc
	v_add_co_u32_e32 v38, vcc, s93, v16
	s_nop 1
	v_addc_co_u32_e32 v39, vcc, 0, v17, vcc
	v_add_co_u32_e32 v40, vcc, s94, v16
	s_nop 1
	v_addc_co_u32_e32 v41, vcc, 0, v17, vcc
	v_add_co_u32_e32 v16, vcc, s95, v16
	s_nop 1
	v_addc_co_u32_e32 v17, vcc, 0, v17, vcc
	global_load_dword v28, v[28:29], off
	s_nop 0
	global_load_dword v29, v[30:31], off offset:2048
	s_nop 0
	global_load_dword v30, v[32:33], off
	global_load_dword v31, v[34:35], off offset:2048
	s_nop 0
	global_load_dword v32, v[36:37], off
	global_load_dword v33, v[38:39], off offset:2048
	global_load_dword v34, v[40:41], off
	s_nop 0
	global_load_dword v16, v[16:17], off offset:2048
	s_waitcnt vmcnt(0) lgkmcnt(0)
; #define LAS __attribute__((address_space(3)))
; #define LDS_WAIT() asm volatile("s_waitcnt lgkmcnt(0)" ::: "memory")
; __device__ __forceinline__ unsigned pk2(float lo, float hi) { return f2bf(lo) | (f2bf(hi) << 16); }
; __device__ __forceinline__ void tr_item(const float* W, int N, int k0, int n0, bf16* WT, int Kd, int drow0, int dk0, LAS float* scr, int lane) {
;     ...
;     LDS_WAIT();
;     const int c = lane & 7;
; #pragma unroll
;     for (int j = 0; j < 4; ++j) { const int n = (lane >> 3) + 8 * j; const LAS float* s = scr + (8 * c) * 33 + n;
;         v4u o; o.x = pk2(s[0 * 33], s[1 * 33]); o.y = pk2(s[2 * 33], s[3 * 33]); o.z = pk2(s[4 * 33], s[5 * 33]); o.w = pk2(s[6 * 33], s[7 * 33]);
;         *(v4u*)(WT + (size_t)(drow0 + n) * Kd + dk0 + 8 * c) = o; }
;     LDS_WAIT();
	ds_write2_b32 v18, v0, v27 offset1:66
	ds_write2_b32 v18, v58, v59 offset0:132 offset1:198
	ds_write2_b32 v20, v60, v61 offset0:8 offset1:74
	ds_write2_b32 v20, v62, v63 offset0:140 offset1:206
	ds_write2_b32 v21, v64, v44 offset0:16 offset1:82
	ds_write2_b32 v21, v45, v46 offset0:148 offset1:214
	ds_write2_b32 v22, v47, v48 offset0:24 offset1:90
	ds_write2_b32 v22, v49, v50 offset0:156 offset1:222
	ds_write2_b32 v23, v51, v52 offset0:32 offset1:98
	ds_write2_b32 v23, v53, v54 offset0:164 offset1:230
	ds_write2_b32 v24, v55, v56 offset0:40 offset1:106
	ds_write2_b32 v24, v57, v42 offset0:172 offset1:238
	ds_write2_b32 v25, v28, v29 offset0:48 offset1:114
	ds_write2_b32 v25, v30, v31 offset0:180 offset1:246
	ds_write2_b32 v26, v32, v33 offset0:56 offset1:122
	ds_write2_b32 v26, v34, v16 offset0:188 offset1:254
	s_waitcnt lgkmcnt(0)
	ds_read_b32 v0, v19
	ds_read_b32 v27, v19 offset:132
	ds_read_b32 v29, v19 offset:264
	ds_read_b32 v30, v19 offset:396
	ds_read_b32 v31, v19 offset:528
	ds_read_b32 v32, v19 offset:660
	ds_read_b32 v33, v19 offset:792
	ds_read_b32 v34, v19 offset:924
	s_waitcnt lgkmcnt(7)
	v_bfe_u32 v28, v0, 16, 1
	v_add3_u32 v0, v0, v28, s59
	s_waitcnt lgkmcnt(6)
	v_bfe_u32 v28, v27, 16, 1
	v_lshrrev_b32_e32 v0, 16, v0
	v_add3_u32 v27, v27, v28, s59
	v_and_or_b32 v28, v27, s60, v0
	s_waitcnt lgkmcnt(5)
	v_bfe_u32 v0, v29, 16, 1
	v_add3_u32 v0, v29, v0, s59
	s_waitcnt lgkmcnt(4)
	v_bfe_u32 v27, v30, 16, 1
	v_lshrrev_b32_e32 v0, 16, v0
	v_add3_u32 v27, v30, v27, s59
	v_and_or_b32 v29, v27, s60, v0
	s_waitcnt lgkmcnt(3)
	v_bfe_u32 v0, v31, 16, 1
	v_add3_u32 v0, v31, v0, s59
	s_waitcnt lgkmcnt(2)
	v_bfe_u32 v27, v32, 16, 1
	v_lshrrev_b32_e32 v0, 16, v0
	v_add3_u32 v27, v32, v27, s59
	v_and_or_b32 v30, v27, s60, v0
	s_waitcnt lgkmcnt(1)
	v_bfe_u32 v0, v33, 16, 1
	v_or_b32_e32 v32, s10, v160
	v_add3_u32 v0, v33, v0, s59
	s_waitcnt lgkmcnt(0)
	v_bfe_u32 v27, v34, 16, 1
	v_ashrrev_i32_e32 v33, 31, v32
	v_lshl_add_u64 v[16:17], s[4:5], 1, v[14:15]
	v_lshrrev_b32_e32 v0, 16, v0
	v_add3_u32 v27, v34, v27, s59
	v_lshlrev_b64 v[32:33], 11, v[32:33]
	v_and_or_b32 v31, v27, s60, v0
	v_lshl_add_u64 v[32:33], v[16:17], 0, v[32:33]
	global_store_dwordx4 v[32:33], v[28:31], off sc0 sc1
	ds_read_b32 v0, v19 offset:32
	ds_read_b32 v27, v19 offset:164
	ds_read_b32 v29, v19 offset:296
	ds_read_b32 v30, v19 offset:428
	ds_read_b32 v31, v19 offset:560
	ds_read_b32 v32, v19 offset:692
	ds_read_b32 v33, v19 offset:824
	ds_read_b32 v34, v19 offset:956
	s_waitcnt lgkmcnt(0)
	v_bfe_u32 v28, v0, 16, 1
	v_add3_u32 v0, v0, v28, s59
	v_bfe_u32 v28, v27, 16, 1
	v_lshrrev_b32_e32 v0, 16, v0
	v_add3_u32 v27, v27, v28, s59
	v_and_or_b32 v28, v27, s60, v0
	v_bfe_u32 v0, v29, 16, 1
	v_add3_u32 v0, v29, v0, s59
	v_bfe_u32 v27, v30, 16, 1
	v_lshrrev_b32_e32 v0, 16, v0
	v_add3_u32 v27, v30, v27, s59
	v_and_or_b32 v29, v27, s60, v0
	v_bfe_u32 v0, v31, 16, 1
	v_add3_u32 v0, v31, v0, s59
	v_bfe_u32 v27, v32, 16, 1
	v_lshrrev_b32_e32 v0, 16, v0
	v_add3_u32 v27, v32, v27, s59
	v_and_or_b32 v30, v27, s60, v0
	v_bfe_u32 v0, v33, 16, 1
	v_or_b32_e32 v32, s10, v161
	v_add3_u32 v0, v33, v0, s59
	v_bfe_u32 v27, v34, 16, 1
	v_ashrrev_i32_e32 v33, 31, v32
	v_lshrrev_b32_e32 v0, 16, v0
	v_add3_u32 v27, v34, v27, s59
	v_lshlrev_b64 v[32:33], 11, v[32:33]
	v_and_or_b32 v31, v27, s60, v0
	v_lshl_add_u64 v[32:33], v[16:17], 0, v[32:33]
	global_store_dwordx4 v[32:33], v[28:31], off sc0 sc1
	ds_read_b32 v0, v19 offset:64
	ds_read_b32 v27, v19 offset:196
	ds_read_b32 v29, v19 offset:328
	ds_read_b32 v30, v19 offset:460
	ds_read_b32 v31, v19 offset:592
	ds_read_b32 v32, v19 offset:724
	ds_read_b32 v33, v19 offset:856
	ds_read_b32 v34, v19 offset:988
	s_waitcnt lgkmcnt(0)
	v_bfe_u32 v28, v0, 16, 1
	v_add3_u32 v0, v0, v28, s59
	v_bfe_u32 v28, v27, 16, 1
	v_lshrrev_b32_e32 v0, 16, v0
	v_add3_u32 v27, v27, v28, s59
	v_and_or_b32 v28, v27, s60, v0
	v_bfe_u32 v0, v29, 16, 1
	v_add3_u32 v0, v29, v0, s59
	v_bfe_u32 v27, v30, 16, 1
	v_lshrrev_b32_e32 v0, 16, v0
	v_add3_u32 v27, v30, v27, s59
	v_and_or_b32 v29, v27, s60, v0
	v_bfe_u32 v0, v31, 16, 1
	v_add3_u32 v0, v31, v0, s59
	v_bfe_u32 v27, v32, 16, 1
	v_lshrrev_b32_e32 v0, 16, v0
	v_add3_u32 v27, v32, v27, s59
	v_and_or_b32 v30, v27, s60, v0
	v_bfe_u32 v0, v33, 16, 1
	v_or_b32_e32 v32, s10, v162
	v_add3_u32 v0, v33, v0, s59
	v_bfe_u32 v27, v34, 16, 1
	v_ashrrev_i32_e32 v33, 31, v32
	v_lshrrev_b32_e32 v0, 16, v0
	v_add3_u32 v27, v34, v27, s59
	v_lshlrev_b64 v[32:33], 11, v[32:33]
	v_and_or_b32 v31, v27, s60, v0
	v_lshl_add_u64 v[32:33], v[16:17], 0, v[32:33]
	global_store_dwordx4 v[32:33], v[28:31], off sc0 sc1
	ds_read_b32 v0, v19 offset:96
	ds_read_b32 v27, v19 offset:228
	ds_read_b32 v29, v19 offset:360
	ds_read_b32 v30, v19 offset:492
	ds_read_b32 v31, v19 offset:624
	ds_read_b32 v32, v19 offset:756
	ds_read_b32 v33, v19 offset:888
	ds_read_b32 v34, v19 offset:1020
	s_waitcnt lgkmcnt(0)
	v_bfe_u32 v28, v0, 16, 1
	v_add3_u32 v0, v0, v28, s59
	v_bfe_u32 v28, v27, 16, 1
	v_lshrrev_b32_e32 v0, 16, v0
	v_add3_u32 v27, v27, v28, s59
	v_and_or_b32 v28, v27, s60, v0
	v_bfe_u32 v0, v29, 16, 1
	v_add3_u32 v0, v29, v0, s59
	v_bfe_u32 v27, v30, 16, 1
	v_lshrrev_b32_e32 v0, 16, v0
	v_add3_u32 v27, v30, v27, s59
	v_and_or_b32 v29, v27, s60, v0
	v_bfe_u32 v0, v31, 16, 1
	v_add3_u32 v0, v31, v0, s59
	v_bfe_u32 v27, v32, 16, 1
	v_lshrrev_b32_e32 v0, 16, v0
	v_add3_u32 v27, v32, v27, s59
	v_and_or_b32 v30, v27, s60, v0
	v_bfe_u32 v0, v33, 16, 1
	v_or_b32_e32 v32, s10, v163
	v_add3_u32 v0, v33, v0, s59
	v_bfe_u32 v27, v34, 16, 1
	v_ashrrev_i32_e32 v33, 31, v32
	v_lshrrev_b32_e32 v0, 16, v0
	v_add3_u32 v27, v34, v27, s59
	v_lshlrev_b64 v[32:33], 11, v[32:33]
	v_and_or_b32 v31, v27, s60, v0
	v_lshl_add_u64 v[16:17], v[16:17], 0, v[32:33]
	global_store_dwordx4 v[16:17], v[28:31], off sc0 sc1
	s_waitcnt lgkmcnt(0)
	s_branch .LBB0_100

; __global__ void __launch_bounds__(NTHREADS, 2) mega_fwd(Args a_unused) {
;     ...
;         if (tid == 0) { unsigned sp_ = 0; unsigned* cw_ = (unsigned*)(ws + WS_CTL) + MODCNT_WORD;
;             while (__hip_atomic_load(cw_, __ATOMIC_RELAXED, __HIP_MEMORY_SCOPE_AGENT) < (unsigned)G) { __builtin_amdgcn_s_sleep(2); if (++sp_ > (1u << 22)) break; }
;             __builtin_amdgcn_fence(__ATOMIC_ACQUIRE, "agent"); asm volatile("s_waitcnt vmcnt(0)" ::: "memory"); }
.LBB0_200:
	global_load_dword v2, v[0:1], off sc1
	s_or_b64 s[8:9], s[8:9], exec
	s_waitcnt vmcnt(0) lgkmcnt(0)
	v_cmp_gt_u32_e32 vcc, s28, v2
	s_and_saveexec_b64 s[12:13], vcc
	s_cbranch_execz .LBB0_199
	s_sleep 2
	global_load_dword v2, v[0:1], off sc1
	s_mov_b64 s[16:17], -1
	s_waitcnt vmcnt(0) lgkmcnt(0)
	v_cmp_gt_u32_e32 vcc, s28, v2
	s_and_saveexec_b64 s[14:15], vcc
	s_cbranch_execz .LBB0_198
	s_sleep 2
	global_load_dword v2, v[0:1], off sc1
	s_mov_b64 s[18:19], -1
	s_waitcnt vmcnt(0) lgkmcnt(0)
	v_cmp_gt_u32_e32 vcc, s28, v2
	s_and_saveexec_b64 s[16:17], vcc
	s_cbranch_execz .LBB0_197
	s_sleep 2
	global_load_dword v2, v[0:1], off sc1
	s_mov_b64 s[20:21], -1
	s_waitcnt vmcnt(0) lgkmcnt(0)
	v_cmp_gt_u32_e32 vcc, s28, v2
	s_and_saveexec_b64 s[18:19], vcc
	s_cbranch_execz .LBB0_196
	s_sleep 2
	global_load_dword v2, v[0:1], off sc1
	s_waitcnt vmcnt(0) lgkmcnt(0)
	v_cmp_gt_u32_e32 vcc, s28, v2
	s_and_saveexec_b64 s[40:41], vcc
	s_cbranch_execz .LBB0_195
	s_add_i32 s7, s7, -5
	s_cmp_eq_u32 s7, 0
	s_cselect_b64 s[20:21], -1, 0
	s_orn2_b64 s[20:21], s[20:21], exec
	s_sleep 2
	s_branch .LBB0_195

; __device__ __forceinline__ unsigned pk2(float lo, float hi) { return f2bf(lo) | (f2bf(hi) << 16); }
; template <bool DO_LN, bool DO_U> __device__ __forceinline__ void row_pass(const float* xin, float* xout, const float* lng, const float* lnb, const float* mod, int sh_off, int sc_off, bf16* U, int gw, int NGW, int lane) {
;     f32x4 nx[4];
;     if (gw < M) {
; #pragma unroll
;         for (int j = 0; j < 4; ++j) nx[j] = ((const f32x4*)(xin + (size_t)gw * D) + lane)[64 * j];
;     }
;     for (int m = gw; m < M; m += NGW) {
;         const int b = m >> 13;
;         f32x4 v[4];
; #pragma unroll
;         for (int j = 0; j < 4; ++j) v[j] = nx[j];
;         if (!DO_LN && m + NGW < M) {
; #pragma unroll
;             for (int j = 0; j < 4; ++j) nx[j] = ((const f32x4*)(xin + (size_t)(m + NGW) * D) + lane)[64 * j];
;         } else if (m + NGW < M) {
; #pragma unroll
;             for (int j = 0; j < 4; ++j) nx[j] = ((const f32x4*)(xin + (size_t)(m + NGW) * D) + lane)[64 * j];
;         }
;         if (DO_LN) {
;             float s = 0.f;
; #pragma unroll
;             for (int j = 0; j < 4; ++j) s += (v[j].x + v[j].y) + (v[j].z + v[j].w);
;             const float mean = wave_sum(s) * (1.f / D); float s2 = 0.f;
; #pragma unroll
;             for (int j = 0; j < 4; ++j) { v[j] = v[j] - mean; s2 += (v[j].x * v[j].x + v[j].y * v[j].y) + (v[j].z * v[j].z + v[j].w * v[j].w); }
;             const float rstd = 1.f / sqrtf(wave_sum(s2) * (1.f / D) + LN_EPS);
;             f32x4* xo = (f32x4*)(xout + (size_t)m * D) + lane;
; #pragma unroll
;             for (int j = 0; j < 4; ++j) { const f32x4 gg = *((const f32x4*)lng + lane + 64 * j), bb = *((const f32x4*)lnb + lane + 64 * j); v[j] = v[j] * rstd * gg + bb; xo[64 * j] = v[j]; }
;         }
;         if (DO_U) {
;             const f32x4* shp = (const f32x4*)(mod + (size_t)b * NMOD + sh_off) + lane; const f32x4* scp = (const f32x4*)(mod + (size_t)b * NMOD + sc_off) + lane;
;             unsigned long long* o8 = (unsigned long long*)(U + (size_t)m * D) + lane;
; #pragma unroll
;             for (int j = 0; j < 4; ++j) { const f32x4 u = v[j] * (scp[64 * j] + 1.0f) + shp[64 * j];
;                 o8[64 * j] = (unsigned long long)pk2(u.x, u.y) | ((unsigned long long)pk2(u.z, u.w) << 32); }
;         }
.LBB0_207:
	s_or_b64 exec, exec, s[4:5]
	s_cmpk_gt_i32 s6, 0x3fff
	v_lshlrev_b32_e32 v150, 4, v141
	v_lshlrev_b32_e32 v148, 3, v141
	s_waitcnt lgkmcnt(0)
	s_barrier
	s_cbranch_scc1 .LBB0_212
	v_mov_b64_e32 v[0:1], s[38:39]
	global_load_dwordx2 v[12:13], v[0:1], off
	s_ashr_i32 s7, s6, 31
	s_lshl_b64 s[4:5], s[6:7], 12
	v_mov_b32_e32 v151, 0
	v_mov_b32_e32 v149, v151
	s_mov_b64 s[10:11], 0x1000
	s_movk_i32 s14, 0x7fff
	s_mov_b32 s15, 0xffff0000
	s_waitcnt vmcnt(0) lgkmcnt(0)
	v_lshl_add_u64 v[0:1], v[12:13], 0, s[4:5]
	v_lshl_add_u64 v[14:15], v[0:1], 0, v[150:151]
	global_load_dwordx4 v[28:31], v[14:15], off
	global_load_dwordx4 v[8:11], v[14:15], off offset:1024
	global_load_dwordx4 v[4:7], v[14:15], off offset:2048
	global_load_dwordx4 v[0:3], v[14:15], off offset:3072
	s_lshl_b64 s[4:5], s[6:7], 11
	s_add_u32 s4, s30, s4
	s_addc_u32 s5, s31, s5
	s_add_i32 s8, s6, s34
	s_ashr_i32 s9, s8, 31
	v_lshl_add_u64 v[14:15], s[4:5], 0, v[148:149]
	s_mov_b64 s[4:5], 0x3a00000
	s_lshl_b64 s[8:9], s[8:9], 12
	v_lshl_add_u64 v[32:33], v[14:15], 0, s[4:5]
	s_ashr_i32 s35, s34, 31
	v_or_b32_e32 v14, s8, v150
	v_mov_b32_e32 v15, s9
	s_lshl_b64 s[4:5], s[34:35], 11
	v_lshl_add_u64 v[34:35], v[12:13], 0, v[14:15]
	s_lshl_b64 s[8:9], s[34:35], 12
	s_movk_i32 s7, 0x1000
	s_branch .LBB0_210
.LBB0_209:
	s_ashr_i32 s6, s6, 13
	s_mul_hi_i32 s17, s6, 0x9000
	s_mul_i32 s6, s6, 0x9000
	s_add_u32 s18, s30, s6
	s_addc_u32 s19, s31, s17
	v_lshl_add_u64 v[44:45], s[18:19], 0, v[150:151]
	v_add_co_u32_e32 v46, vcc, s7, v44
	v_lshl_add_u64 v[34:35], v[34:35], 0, s[8:9]
	s_nop 0
	v_addc_co_u32_e32 v47, vcc, 0, v45, vcc
	global_load_dwordx4 v[36:39], v[46:47], off
	global_load_dwordx4 v[40:43], v[44:45], off
	v_lshl_add_u64 v[46:47], v[44:45], 0, s[10:11]
	s_mov_b32 s6, s16
	s_andn2_b64 vcc, exec, s[12:13]
	s_waitcnt vmcnt(0) lgkmcnt(0)
	v_pk_add_f32 v[38:39], v[38:39], 1.0 op_sel_hi:[1,0]
	v_pk_add_f32 v[36:37], v[36:37], 1.0 op_sel_hi:[1,0]
	v_pk_fma_f32 v[30:31], v[30:31], v[38:39], v[42:43]
	v_pk_fma_f32 v[28:29], v[28:29], v[36:37], v[40:41]
	v_bfe_u32 v38, v30, 16, 1
	v_bfe_u32 v36, v28, 16, 1
	v_bfe_u32 v37, v29, 16, 1
	v_bfe_u32 v39, v31, 16, 1
	v_add3_u32 v28, v28, v36, s14
	v_add3_u32 v30, v30, v38, s14
	v_add3_u32 v29, v29, v37, s14
	v_add3_u32 v31, v31, v39, s14
	v_lshrrev_b32_e32 v28, 16, v28
	v_lshrrev_b32_e32 v30, 16, v30
	v_and_or_b32 v28, v29, s15, v28
	v_and_or_b32 v29, v31, s15, v30
	global_store_dwordx2 v[32:33], v[28:29], off
	global_load_dwordx4 v[28:31], v[46:47], off offset:1024
	s_nop 0
	global_load_dwordx4 v[36:39], v[44:45], off offset:1024
	s_waitcnt vmcnt(0) lgkmcnt(0)
	v_pk_add_f32 v[30:31], v[30:31], 1.0 op_sel_hi:[1,0]
	v_pk_add_f32 v[28:29], v[28:29], 1.0 op_sel_hi:[1,0]
	v_pk_fma_f32 v[10:11], v[10:11], v[30:31], v[38:39]
	v_pk_fma_f32 v[8:9], v[8:9], v[28:29], v[36:37]
	v_bfe_u32 v30, v10, 16, 1
	v_bfe_u32 v28, v8, 16, 1
	v_bfe_u32 v29, v9, 16, 1
	v_bfe_u32 v31, v11, 16, 1
	v_add3_u32 v8, v8, v28, s14
	v_add3_u32 v10, v10, v30, s14
	v_add3_u32 v9, v9, v29, s14
	v_add3_u32 v11, v11, v31, s14
	v_lshrrev_b32_e32 v8, 16, v8
	v_lshrrev_b32_e32 v10, 16, v10
	v_and_or_b32 v8, v9, s15, v8
	v_and_or_b32 v9, v11, s15, v10
	global_store_dwordx2 v[32:33], v[8:9], off offset:512
	global_load_dwordx4 v[8:11], v[46:47], off offset:2048
	s_nop 0
	global_load_dwordx4 v[28:31], v[44:45], off offset:2048
	s_waitcnt vmcnt(0) lgkmcnt(0)
	v_pk_add_f32 v[10:11], v[10:11], 1.0 op_sel_hi:[1,0]
	v_pk_add_f32 v[8:9], v[8:9], 1.0 op_sel_hi:[1,0]
	v_pk_fma_f32 v[6:7], v[6:7], v[10:11], v[30:31]
	v_pk_fma_f32 v[4:5], v[4:5], v[8:9], v[28:29]
	v_bfe_u32 v10, v6, 16, 1
	v_bfe_u32 v8, v4, 16, 1
	v_bfe_u32 v9, v5, 16, 1
	v_bfe_u32 v11, v7, 16, 1
	v_add3_u32 v4, v4, v8, s14
	v_add3_u32 v6, v6, v10, s14
	v_add3_u32 v5, v5, v9, s14
	v_add3_u32 v7, v7, v11, s14
	v_lshrrev_b32_e32 v4, 16, v4
	v_lshrrev_b32_e32 v6, 16, v6
	v_and_or_b32 v4, v5, s15, v4
	v_and_or_b32 v5, v7, s15, v6
	global_store_dwordx2 v[32:33], v[4:5], off offset:1024
	global_load_dwordx4 v[36:39], v[46:47], off offset:3072
	global_load_dwordx4 v[40:43], v[44:45], off offset:3072
	v_mov_b32_e32 v28, v16
	v_mov_b32_e32 v29, v17
	v_mov_b32_e32 v30, v18
	v_mov_b32_e32 v31, v19
	v_mov_b32_e32 v8, v20
	v_mov_b32_e32 v9, v21
	v_mov_b32_e32 v10, v22
	v_mov_b32_e32 v11, v23
	v_mov_b32_e32 v4, v24
	v_mov_b32_e32 v5, v25
	v_mov_b32_e32 v6, v26
	v_mov_b32_e32 v7, v27
	s_waitcnt vmcnt(0) lgkmcnt(0)
	v_pk_add_f32 v[16:17], v[38:39], 1.0 op_sel_hi:[1,0]
	v_pk_add_f32 v[18:19], v[36:37], 1.0 op_sel_hi:[1,0]
	v_pk_fma_f32 v[16:17], v[2:3], v[16:17], v[42:43]
	v_pk_fma_f32 v[18:19], v[0:1], v[18:19], v[40:41]
	v_mov_b32_e32 v1, v13
	v_bfe_u32 v3, v18, 16, 1
	v_bfe_u32 v13, v16, 16, 1
	v_mov_b32_e32 v0, v12
	v_mov_b32_e32 v2, v14
	v_bfe_u32 v12, v19, 16, 1
	v_bfe_u32 v14, v17, 16, 1
	v_add3_u32 v3, v18, v3, s14
	v_add3_u32 v13, v16, v13, s14
	v_add3_u32 v12, v19, v12, s14
	v_add3_u32 v14, v17, v14, s14
	v_lshrrev_b32_e32 v3, 16, v3
	v_lshrrev_b32_e32 v13, 16, v13
	v_and_or_b32 v12, v12, s15, v3
	v_and_or_b32 v13, v14, s15, v13
	global_store_dwordx2 v[32:33], v[12:13], off offset:1536
	v_lshl_add_u64 v[32:33], v[32:33], 0, s[4:5]
	v_mov_b32_e32 v3, v15
	s_cbranch_vccz .LBB0_212
.LBB0_210:
	s_add_i32 s16, s6, s34
	s_cmpk_gt_i32 s16, 0x3fff
	s_cselect_b64 s[12:13], -1, 0
	s_and_b64 vcc, exec, s[12:13]
	s_waitcnt vmcnt(0) lgkmcnt(0)
	v_mov_b32_e32 v16, v28
	v_mov_b32_e32 v17, v29
	v_mov_b32_e32 v18, v30
	v_mov_b32_e32 v19, v31
	v_mov_b32_e32 v20, v8
	v_mov_b32_e32 v21, v9
	v_mov_b32_e32 v22, v10
	v_mov_b32_e32 v23, v11
	v_mov_b32_e32 v24, v4
	v_mov_b32_e32 v25, v5
	v_mov_b32_e32 v26, v6
	v_mov_b32_e32 v27, v7
	v_mov_b32_e32 v12, v0
	v_mov_b32_e32 v13, v1
	v_mov_b32_e32 v14, v2
	v_mov_b32_e32 v15, v3
	s_cbranch_vccnz .LBB0_209
	global_load_dwordx4 v[16:19], v[34:35], off
	global_load_dwordx4 v[20:23], v[34:35], off offset:1024
	global_load_dwordx4 v[24:27], v[34:35], off offset:2048
	global_load_dwordx4 v[12:15], v[34:35], off offset:3072
	s_branch .LBB0_209

; #define PG8_STAGE(bufoff, gbase, voff) do { _Pragma("unroll") for (int _i = 0; _i < 2; ++_i) \
;         __builtin_amdgcn_global_load_lds((const unsigned*)((const char*)(gbase) + (voff)[_i]), (PG8_LAS unsigned*)(lds + (bufoff) + ldsw + _i * 8192), 16, 0, 0); } while (0)
; #define PG8_WAIT_V(n) asm volatile("s_waitcnt vmcnt(" #n ")" ::: "memory")
; #define PG8_BAR __builtin_amdgcn_s_barrier()
; template <class Epi, class Sched, bool ALIGN_EPI = false, bool SP2 = false>
; __device__ __forceinline__ void gemm_phase(PG8_LAS unsigned char* lds, const Gemm g, const Sched& S, const Epi& E) {
;     int tid_o = threadIdx.x; asm volatile("" : "+v"(tid_o));
;     const int tid = tid_o, wid = __builtin_amdgcn_readfirstlane(tid >> 6), lane = tid & 63, wr = wid >> 2, wc = wid & 3, fr = lane & 15, fq = lane >> 4;
;     const int K = g.K, nt = K / BK;
;     unsigned voffA[2], voffB[2];
; #pragma unroll
;     for (int i = 0; i < 2; ++i) { int R, C; stage_rc(tid * 16 + i * 8192, R, C); const int Rb = Epi::PERM ? ((R & ~31) + perm32(R & 31)) : R;
;         voffA[i] = (unsigned)(R * K + C) * 2u; voffB[i] = (unsigned)(Rb * K + C) * 2u; }
;     const size_t kstep = (size_t)(BK * 2);
;     const size_t hstep = (size_t)HALF * K * 2;
;     const size_t tstep = 2 * hstep;
;     const unsigned ldsw = (unsigned)wid * 1024u;
;     const int aoff = lds_byte(wr * 64 + fr, fq * 8), boff = lds_byte(wc * 32 + fr, fq * 8);
;     ...
;     Unit cur, nxt; int ui = 0;
;     if (!S.next(0, cur)) return;
;     f32x4 acc[2][2][4][2];
; #pragma unroll
;     for (int a = 0; a < 2; ++a)
; #pragma unroll
;         for (int b = 0; b < 2; ++b)
; #pragma unroll
;             for (int m = 0; m < 4; ++m)
; #pragma unroll
;                 for (int n = 0; n < 2; ++n) acc[a][b][m][n] = (f32x4){0.f, 0.f, 0.f, 0.f};
;     bf16x8 At[4][2], B0[2][2], B1[2][2];
;     const char* cA = (const char*)g.A + (size_t)cur.pm * tstep; const char* cB = (const char*)g.Bt + (size_t)cur.pn * tstep;
;     S.a_ready(cur);
;     if constexpr (SP2) {
;         PG8_STAGE(PG8_SB(0, 0), cB, voffB); PG8_STAGE(PG8_SB(0, 1), cB + hstep, voffB); PG8_STAGE(PG8_SA(0, 0), cA, voffA); PG8_STAGE(PG8_SA(0, 1), cA + hstep, voffA);
;         if (wr == 1) PG8_BAR;
;         PG8_WAIT_V(2); PG8_BAR;
;         PG8_STAGE(PG8_SB(1, 0), cB + kstep, voffB); PG8_STAGE(PG8_SA(1, 0), cA + kstep, voffA); PG8_STAGE(PG8_SB(1, 1), cB + hstep + kstep, voffB);
.LBB0_277:
	s_or_b64 exec, exec, s[4:5]
	s_mov_b64 s[8:9], s[0:1]
	s_waitcnt lgkmcnt(0)
	s_barrier
	s_cmpk_lt_i32 s2, 0x580
	v_mov_b64_e32 v[0:1], s[8:9]
	global_load_dwordx2 v[0:1], v[0:1], off offset:200
	s_cselect_b64 s[6:7], -1, 0
	s_movk_i32 s4, 0x400
	v_mov_b32_e32 v12, v144
	v_writelane_b32 v250, s6, 0
	v_readfirstlane_b32 s20, v144
	s_cmpk_gt_i32 s2, 0x57f
	v_writelane_b32 v250, s7, 1
	s_waitcnt vmcnt(0) lgkmcnt(0)
	v_readfirstlane_b32 s11, v1
	v_readfirstlane_b32 s10, v0
	s_nop 0
	v_readfirstlane_b32 s7, v12
	s_cbranch_scc1 .LBB0_298
	v_lshlrev_b32_e32 v0, 4, v12
	v_add_u32_e32 v1, 0x2000, v0
	v_ashrrev_i32_e32 v2, 31, v1
	v_lshrrev_b32_e32 v2, 22, v2
	v_add_u32_e32 v2, v1, v2
	v_ashrrev_i32_e32 v2, 10, v2
	v_mul_i32_i24_e32 v3, 0x400, v2
	v_sub_u32_e32 v1, v1, v3
	v_lshrrev_b32_e32 v3, 4, v1
	v_bitop3_b32 v1, v3, v1, 32 bitop3:0x6c
	v_ashrrev_i32_e32 v3, 31, v1
	v_lshrrev_b32_e32 v3, 26, v3
	v_add_u32_e32 v3, v1, v3
	v_lshlrev_b32_e32 v5, 3, v2
	v_ashrrev_i32_e32 v4, 6, v3
	v_and_b32_e32 v5, -16, v5
	v_lshlrev_b32_e32 v2, 5, v2
	v_add_u32_e32 v5, v4, v5
	v_and_b32_e32 v13, 32, v2
	v_and_b32_e32 v2, 0xc0, v3
	v_and_b32_e32 v4, 3, v4
	s_mov_b32 s6, 0x7fffffe0
	v_lshrrev_b32_e32 v6, 2, v5
	v_lshlrev_b32_e32 v7, 1, v5
	v_sub_u32_e32 v1, v1, v2
	v_mov_b32_e32 v2, 1
	v_and_or_b32 v4, v5, s6, v4
	v_and_b32_e32 v6, 4, v6
	v_and_b32_e32 v7, 24, v7
	v_ashrrev_i16_sdwa v1, v2, sext(v1) dst_sel:DWORD dst_unused:UNUSED_PAD src0_sel:DWORD src1_sel:BYTE_0
	v_or3_b32 v4, v4, v6, v7
	v_bfe_i32 v14, v1, 0, 16
	v_mul_lo_u32 v4, v4, s4
	v_add_u32_e32 v1, v13, v14
	v_mul_lo_u32 v15, v5, s4
	v_add_lshl_u32 v128, v4, v1, 1
	v_add_lshl_u32 v130, v1, v15, 1
	v_bfe_i32 v1, v12, 27, 1
	v_lshrrev_b32_e32 v1, 22, v1
	v_add_u32_e32 v1, v0, v1
	v_and_b32_e32 v1, 0xfffffc00, v1
	v_sub_u32_e32 v0, v0, v1
	v_lshrrev_b32_e32 v1, 4, v0
	v_ashrrev_i32_e32 v4, 31, v12
	v_bitop3_b32 v0, v1, v0, 32 bitop3:0x6c
	v_lshrrev_b32_e32 v4, 26, v4
	v_ashrrev_i32_e32 v1, 31, v0
	v_add_u32_e32 v4, v12, v4
	s_add_u32 s21, s10, 0x3a00000
	v_lshrrev_b32_e32 v1, 26, v1
	v_ashrrev_i32_e32 v4, 6, v4
	s_addc_u32 s35, s11, 0
	v_add_u32_e32 v1, v0, v1
	v_lshlrev_b32_e32 v5, 3, v4
	s_add_u32 s48, s10, 0x100000
	v_ashrrev_i32_e32 v3, 6, v1
	v_and_b32_e32 v5, -16, v5
	s_addc_u32 s49, s11, 0
	v_add_u32_e32 v5, v3, v5
	v_and_b32_e32 v3, 3, v3
	s_ashr_i32 s51, s2, 31
	v_and_or_b32 v3, v5, s6, v3
	s_lshr_b32 s6, s51, 29
	s_add_i32 s6, s2, s6
	s_ashr_i32 s38, s7, 6
	s_ashr_i32 s5, s4, 31
	s_ashr_i32 s16, s6, 3
	s_and_b32 s6, s6, -8
	s_ashr_i32 s39, s7, 8
	s_lshl_b64 s[12:13], s[4:5], 8
	s_lshl_b64 s[14:15], s[4:5], 9
	s_lshl_b32 s50, s38, 10
	s_sub_i32 s6, s2, s6
	s_cmp_lt_i32 s6, 0
	s_movk_i32 s52, 0xb1
	s_cselect_b32 s17, s52, 0xb0
	s_mul_i32 s6, s6, s17
	s_add_i32 s6, s6, s16
	s_mul_hi_i32 s16, s6, 0x2e8ba2e9
	s_lshr_b32 s17, s16, 31
	s_ashr_i32 s16, s16, 5
	s_add_i32 s16, s16, s17
	s_lshl_b32 s17, s16, 3
	s_mulk_i32 s16, 0xb0
	s_sub_i32 s16, s6, s16
	s_sext_i32_i16 s6, s16
	s_bfe_u32 s6, s6, 0x3001c
	s_add_i32 s18, s16, s6
	s_sext_i32_i16 s30, s18
	s_and_b32 s18, s18, 0xfff8
	s_sub_i32 s16, s16, s18
	s_sext_i32_i16 s16, s16
	s_add_i32 s69, s17, s16
	s_ashr_i32 s16, s69, 31
	s_mul_i32 s16, s14, s16
	s_mul_hi_u32 s17, s14, s69
	s_add_i32 s18, s17, s16
	s_lshr_b64 s[16:17], s[4:5], 23
	s_lshr_b32 s6, s30, 3
	s_mul_i32 s17, s16, s69
	s_add_i32 s31, s18, s17
	s_bfe_i64 s[18:19], s[6:7], 0x100000
	s_ashr_i32 s17, s30, 3
	v_and_b32_e32 v1, 0xc0, v1
	s_mul_hi_u32 s18, s14, s17
	s_mul_i32 s19, s14, s19
	v_lshrrev_b32_e32 v6, 2, v5
	v_lshlrev_b32_e32 v7, 1, v5
	v_sub_u32_e32 v0, v0, v1
	s_add_i32 s18, s18, s19
	s_mul_i32 s16, s16, s17
	v_and_b32_e32 v6, 4, v6
	v_and_b32_e32 v7, 24, v7
	v_lshlrev_b32_e32 v4, 5, v4
	v_ashrrev_i16_sdwa v0, v2, sext(v0) dst_sel:DWORD dst_unused:UNUSED_PAD src0_sel:DWORD src1_sel:BYTE_0
	s_add_i32 s18, s18, s16
	s_mul_i32 s16, s14, s17
	v_or3_b32 v3, v3, v6, v7
	v_and_b32_e32 v16, 32, v4
	v_bfe_i32 v17, v0, 0, 16
	s_add_u32 s44, s48, s16
	v_mul_lo_u32 v3, v3, s4
	v_add_u32_e32 v0, v16, v17
	s_addc_u32 s45, s49, s18
	s_add_i32 s53, s50, 0
	v_add_lshl_u32 v132, v3, v0, 1
	s_add_i32 m0, s53, 0x10000
	s_mul_i32 s40, s14, s69
	global_load_lds_dwordx4 v132, s[44:45]
	s_add_i32 m0, s53, 0x12000
	s_add_u32 s16, s44, s12
	global_load_lds_dwordx4 v128, s[44:45]
	s_addc_u32 s17, s45, s13
	s_add_i32 m0, s53, 0x14000
	v_mul_lo_u32 v18, v5, s4
	global_load_lds_dwordx4 v132, s[16:17]
	s_add_i32 m0, s53, 0x16000
	s_add_u32 s46, s21, s40
	s_addc_u32 s47, s35, s31
	s_add_i32 s54, s53, 0x2000
	v_add_lshl_u32 v134, v0, v18, 1
	global_load_lds_dwordx4 v128, s[16:17]
	s_mov_b32 m0, s53
	s_add_u32 s18, s46, s12
	global_load_lds_dwordx4 v134, s[46:47]
	s_mov_b32 m0, s54
	s_addc_u32 s19, s47, s13
	s_add_i32 s55, s53, 0x4000
	global_load_lds_dwordx4 v130, s[46:47]
	s_mov_b32 m0, s55
	s_add_i32 s56, s53, 0x6000
	global_load_lds_dwordx4 v134, s[18:19]
	s_mov_b32 m0, s56
	v_mov_b32_e32 v133, 0
	global_load_lds_dwordx4 v130, s[18:19]
	v_mov_b32_e32 v129, v133
	v_mov_b32_e32 v135, v133
	v_mov_b32_e32 v131, v133
	s_cmp_eq_u32 s39, 1
	s_mov_b32 s57, 0
	v_lshl_add_u64 v[8:9], s[44:45], 0, v[132:133]
	v_lshl_add_u64 v[4:5], s[44:45], 0, v[128:129]
	v_lshl_add_u64 v[2:3], s[16:17], 0, v[132:133]
	v_lshl_add_u64 v[0:1], s[16:17], 0, v[128:129]
	v_lshl_add_u64 v[6:7], s[46:47], 0, v[134:135]
	s_cselect_b64 s[16:17], -1, 0
	s_cmp_lg_u32 s39, 1
	v_lshl_add_u64 v[10:11], s[46:47], 0, v[130:131]
	s_cbranch_scc1 .LBB0_280
	s_barrier

; __device__ __forceinline__ unsigned cvt_pk_bf16(float lo, float hi) { unsigned r; asm volatile("v_cvt_pk_bf16_f32 %0, %1, %2" : "=v"(r) : "v"(lo), "v"(hi)); return r; }
;     __device__ __forceinline__ void operator()(const f32x4 (&acc)[2][2][4][2], const Unit& u, int wr, int wc, int fr, int fq) const {
;         const int row0 = u.pm * BM + wr * 64 + fr, col0 = u.pn * 128 + wc * 32 + 8 * fq;
; #pragma unroll
;         for (int ai = 0; ai < 2; ++ai)
; #pragma unroll
;             for (int m = 0; m < 4; ++m) {
;                 bf16_t* rowp = O + (size_t)(row0 + ai * HALF + m * 16) * ldc + col0;
;                 float h[8];
; #pragma unroll
;                 for (int n = 0; n < 2; ++n)
; #pragma unroll
;                     for (int e = 0; e < 4; ++e) { const float g = acc[ai][0][m][n][e], up = acc[ai][1][m][n][e]; h[4 * n + e] = g * __builtin_amdgcn_rcpf(1.f + __expf(-g)) * up; }
;                 u32x4 w; w.x = cvt_pk_bf16(h[0], h[1]); w.y = cvt_pk_bf16(h[2], h[3]); w.z = cvt_pk_bf16(h[4], h[5]); w.w = cvt_pk_bf16(h[6], h[7]);
;                 *(u32x4*)rowp = w;
;             }
;     }
.LBB0_294:
	v_mul_f32_e32 v156, 0xbfb8aa3b, v124
	v_exp_f32_e32 v172, v156
	v_mul_f32_e32 v156, 0xbfb8aa3b, v125
	v_exp_f32_e32 v173, v156
	v_lshl_or_b32 v170, s70, 7, v151
	v_add_f32_e32 v172, 1.0, v172
	v_rcp_f32_e32 v174, v172
	v_add_f32_e32 v172, 1.0, v173
	v_rcp_f32_e32 v175, v172
	v_lshl_add_u32 v169, s69, 8, v147
	v_mul_f32_e32 v124, v124, v174
	v_mul_f32_e32 v120, v120, v124
	v_mul_f32_e32 v124, v125, v175
	v_mul_f32_e32 v125, 0xbfb8aa3b, v126
	v_exp_f32_e32 v125, v125
	v_mul_f32_e32 v174, 0xbfb8aa3b, v127
	v_exp_f32_e32 v174, v174
	v_mul_f32_e32 v121, v121, v124
	v_add_f32_e32 v124, 1.0, v125
	v_rcp_f32_e32 v124, v124
	v_add_f32_e32 v125, 1.0, v174
	v_mul_f32_e32 v174, 0xbfb8aa3b, v116
	v_rcp_f32_e32 v125, v125
	v_exp_f32_e32 v174, v174
	v_mul_f32_e32 v124, v126, v124
	v_mul_f32_e32 v122, v122, v124
	v_mul_f32_e32 v124, v127, v125
	v_add_f32_e32 v125, 1.0, v174
	v_rcp_f32_e32 v125, v125
	v_mul_f32_e32 v126, 0xbfb8aa3b, v117
	v_exp_f32_e32 v126, v126
	v_mul_f32_e32 v123, v123, v124
	v_mul_f32_e32 v116, v116, v125
	v_mul_f32_e32 v116, v112, v116
	v_add_f32_e32 v112, 1.0, v126
	v_mul_f32_e32 v124, 0xbfb8aa3b, v118
	v_rcp_f32_e32 v112, v112
	v_exp_f32_e32 v124, v124
	v_mul_f32_e32 v125, 0xbfb8aa3b, v119
	v_exp_f32_e32 v125, v125
	v_mul_f32_e32 v112, v117, v112
	v_add_f32_e32 v117, 1.0, v124
	v_rcp_f32_e32 v117, v117
	v_add_f32_e32 v124, 1.0, v125
	v_rcp_f32_e32 v124, v124
	v_mul_f32_e32 v125, v113, v112
	v_mul_f32_e32 v112, v118, v117
	v_ashrrev_i32_e32 v171, 31, v170
	v_mov_b64_e32 v[156:157], s[18:19]
	v_mul_f32_e32 v117, v114, v112
	v_mul_f32_e32 v112, v119, v124
	v_mad_i64_i32 v[172:173], s[44:45], v169, s66, v[156:157]
	v_mul_f32_e32 v124, v115, v112
	v_lshlrev_b64 v[112:113], 1, v[170:171]
	v_lshl_add_u64 v[118:119], v[172:173], 0, v[112:113]
	v_cvt_pk_bf16_f32 v114, v120, v121
	v_cvt_pk_bf16_f32 v115, v122, v123
	v_cvt_pk_bf16_f32 v116, v116, v125
	v_cvt_pk_bf16_f32 v117, v117, v124
	global_store_dwordx4 v[118:119], v[114:117], off sc0 sc1
	s_and_b64 vcc, exec, s[4:5]
	s_mov_b64 s[4:5], -1
	v_mul_f32_e32 v114, 0xbfb8aa3b, v108
	v_exp_f32_e32 v114, v114
	v_mul_f32_e32 v115, 0xbfb8aa3b, v109
	v_exp_f32_e32 v115, v115
	v_or_b32_e32 v116, 16, v169
	v_add_f32_e32 v114, 1.0, v114
	v_rcp_f32_e32 v117, v114
	v_add_f32_e32 v114, 1.0, v115
	v_rcp_f32_e32 v118, v114
	v_mad_i64_i32 v[114:115], s[44:45], v116, s66, v[156:157]
	v_mul_f32_e32 v108, v108, v117
	v_mul_f32_e32 v104, v104, v108
	v_mul_f32_e32 v108, v109, v118
	v_mul_f32_e32 v109, 0xbfb8aa3b, v110
	v_exp_f32_e32 v109, v109
	v_mul_f32_e32 v116, 0xbfb8aa3b, v111
	v_exp_f32_e32 v116, v116
	v_mul_f32_e32 v105, v105, v108
	v_add_f32_e32 v108, 1.0, v109
	v_rcp_f32_e32 v108, v108
	v_add_f32_e32 v109, 1.0, v116
	v_mul_f32_e32 v116, 0xbfb8aa3b, v100
	v_rcp_f32_e32 v109, v109
	v_exp_f32_e32 v116, v116
	v_mul_f32_e32 v108, v110, v108
	v_mul_f32_e32 v106, v106, v108
	v_mul_f32_e32 v108, v111, v109
	v_add_f32_e32 v109, 1.0, v116
	v_rcp_f32_e32 v109, v109
	v_mul_f32_e32 v110, 0xbfb8aa3b, v101
	v_exp_f32_e32 v110, v110
	v_mul_f32_e32 v107, v107, v108
	v_mul_f32_e32 v100, v100, v109
	v_mul_f32_e32 v108, v96, v100
	v_mul_f32_e32 v100, 0xbfb8aa3b, v102
	v_add_f32_e32 v96, 1.0, v110
	v_exp_f32_e32 v100, v100
	v_mul_f32_e32 v109, 0xbfb8aa3b, v103
	v_rcp_f32_e32 v96, v96
	v_exp_f32_e32 v109, v109
	v_add_f32_e32 v100, 1.0, v100
	v_rcp_f32_e32 v100, v100
	v_mul_f32_e32 v96, v101, v96
	v_add_f32_e32 v101, 1.0, v109
	v_rcp_f32_e32 v101, v101
	v_mul_f32_e32 v109, v97, v96
	v_mul_f32_e32 v96, v102, v100
	v_mul_f32_e32 v102, v98, v96
	v_mul_f32_e32 v96, v103, v101
	v_mul_f32_e32 v99, v99, v96
	v_lshl_add_u64 v[100:101], v[114:115], 0, v[112:113]
	v_cvt_pk_bf16_f32 v96, v104, v105
	v_cvt_pk_bf16_f32 v97, v106, v107
	v_cvt_pk_bf16_f32 v98, v108, v109
	v_cvt_pk_bf16_f32 v99, v102, v99
	global_store_dwordx4 v[100:101], v[96:99], off sc0 sc1
	s_nop 1
	v_mul_f32_e32 v96, 0xbfb8aa3b, v92
	v_exp_f32_e32 v96, v96
	v_mul_f32_e32 v97, 0xbfb8aa3b, v93
	v_exp_f32_e32 v97, v97
	v_or_b32_e32 v98, 32, v169
	v_add_f32_e32 v96, 1.0, v96
	v_rcp_f32_e32 v99, v96
	v_add_f32_e32 v96, 1.0, v97
	v_rcp_f32_e32 v100, v96
	v_mad_i64_i32 v[96:97], s[44:45], v98, s66, v[156:157]
	v_mul_f32_e32 v92, v92, v99
	v_mul_f32_e32 v88, v88, v92
	v_mul_f32_e32 v92, v93, v100
	v_mul_f32_e32 v93, 0xbfb8aa3b, v94
	v_exp_f32_e32 v93, v93
	v_mul_f32_e32 v98, 0xbfb8aa3b, v95
	v_exp_f32_e32 v98, v98
	v_mul_f32_e32 v89, v89, v92
	v_add_f32_e32 v92, 1.0, v93
	v_rcp_f32_e32 v92, v92
	v_add_f32_e32 v93, 1.0, v98
	v_mul_f32_e32 v98, 0xbfb8aa3b, v84
	v_rcp_f32_e32 v93, v93
	v_exp_f32_e32 v98, v98
	v_mul_f32_e32 v92, v94, v92
	v_mul_f32_e32 v90, v90, v92
	v_mul_f32_e32 v92, v95, v93
	v_add_f32_e32 v93, 1.0, v98
	v_rcp_f32_e32 v93, v93
	v_mul_f32_e32 v94, 0xbfb8aa3b, v85
	v_exp_f32_e32 v94, v94
	v_mul_f32_e32 v91, v91, v92
	v_mul_f32_e32 v84, v84, v93
	v_mul_f32_e32 v92, v80, v84
	v_mul_f32_e32 v84, 0xbfb8aa3b, v86
	v_add_f32_e32 v80, 1.0, v94
	v_exp_f32_e32 v84, v84
	v_mul_f32_e32 v93, 0xbfb8aa3b, v87
	v_rcp_f32_e32 v80, v80
	v_exp_f32_e32 v93, v93
	v_add_f32_e32 v84, 1.0, v84
	v_rcp_f32_e32 v84, v84
	v_mul_f32_e32 v80, v85, v80
	v_add_f32_e32 v85, 1.0, v93
	v_rcp_f32_e32 v85, v85
	v_mul_f32_e32 v93, v81, v80
	v_mul_f32_e32 v80, v86, v84
	v_mul_f32_e32 v86, v82, v80
	v_mul_f32_e32 v80, v87, v85
	v_mul_f32_e32 v83, v83, v80
	v_lshl_add_u64 v[84:85], v[96:97], 0, v[112:113]
	v_cvt_pk_bf16_f32 v80, v88, v89
	v_cvt_pk_bf16_f32 v81, v90, v91
	v_cvt_pk_bf16_f32 v82, v92, v93
	v_cvt_pk_bf16_f32 v83, v86, v83
	global_store_dwordx4 v[84:85], v[80:83], off sc0 sc1
	s_nop 1
	v_mul_f32_e32 v80, 0xbfb8aa3b, v76
	v_exp_f32_e32 v80, v80
	v_mul_f32_e32 v81, 0xbfb8aa3b, v77
; __device__ __forceinline__ unsigned cvt_pk_bf16(float lo, float hi) { unsigned r; asm volatile("v_cvt_pk_bf16_f32 %0, %1, %2" : "=v"(r) : "v"(lo), "v"(hi)); return r; }
;     __device__ __forceinline__ void operator()(const f32x4 (&acc)[2][2][4][2], const Unit& u, int wr, int wc, int fr, int fq) const {
;         const int row0 = u.pm * BM + wr * 64 + fr, col0 = u.pn * 128 + wc * 32 + 8 * fq;
; #pragma unroll
;         for (int ai = 0; ai < 2; ++ai)
; #pragma unroll
;             for (int m = 0; m < 4; ++m) {
;                 bf16_t* rowp = O + (size_t)(row0 + ai * HALF + m * 16) * ldc + col0;
;                 float h[8];
; #pragma unroll
;                 for (int n = 0; n < 2; ++n)
; #pragma unroll
;                     for (int e = 0; e < 4; ++e) { const float g = acc[ai][0][m][n][e], up = acc[ai][1][m][n][e]; h[4 * n + e] = g * __builtin_amdgcn_rcpf(1.f + __expf(-g)) * up; }
;                 u32x4 w; w.x = cvt_pk_bf16(h[0], h[1]); w.y = cvt_pk_bf16(h[2], h[3]); w.z = cvt_pk_bf16(h[4], h[5]); w.w = cvt_pk_bf16(h[6], h[7]);
;                 *(u32x4*)rowp = w;
;             }
;     }
	v_exp_f32_e32 v81, v81
	v_or_b32_e32 v82, 48, v169
	v_add_f32_e32 v80, 1.0, v80
	v_rcp_f32_e32 v83, v80
	v_add_f32_e32 v80, 1.0, v81
	v_rcp_f32_e32 v84, v80
	v_mad_i64_i32 v[80:81], s[44:45], v82, s66, v[156:157]
	v_mul_f32_e32 v76, v76, v83
	v_mul_f32_e32 v72, v72, v76
	v_mul_f32_e32 v76, v77, v84
	v_mul_f32_e32 v77, 0xbfb8aa3b, v78
	v_exp_f32_e32 v77, v77
	v_mul_f32_e32 v82, 0xbfb8aa3b, v79
	v_exp_f32_e32 v82, v82
	v_mul_f32_e32 v73, v73, v76
	v_add_f32_e32 v76, 1.0, v77
	v_rcp_f32_e32 v76, v76
	v_add_f32_e32 v77, 1.0, v82
	v_mul_f32_e32 v82, 0xbfb8aa3b, v68
	v_rcp_f32_e32 v77, v77
	v_exp_f32_e32 v82, v82
	v_mul_f32_e32 v76, v78, v76
	v_mul_f32_e32 v74, v74, v76
	v_mul_f32_e32 v76, v79, v77
	v_add_f32_e32 v77, 1.0, v82
	v_rcp_f32_e32 v77, v77
	v_mul_f32_e32 v78, 0xbfb8aa3b, v69
	v_exp_f32_e32 v78, v78
	v_mul_f32_e32 v75, v75, v76
	v_mul_f32_e32 v68, v68, v77
	v_mul_f32_e32 v76, v64, v68
	v_mul_f32_e32 v68, 0xbfb8aa3b, v70
	v_add_f32_e32 v64, 1.0, v78
	v_exp_f32_e32 v68, v68
	v_mul_f32_e32 v77, 0xbfb8aa3b, v71
	v_rcp_f32_e32 v64, v64
	v_exp_f32_e32 v77, v77
	v_add_f32_e32 v68, 1.0, v68
	v_rcp_f32_e32 v68, v68
	v_mul_f32_e32 v64, v69, v64
	v_add_f32_e32 v69, 1.0, v77
	v_rcp_f32_e32 v69, v69
	v_mul_f32_e32 v77, v65, v64
	v_mul_f32_e32 v64, v70, v68
	v_mul_f32_e32 v70, v66, v64
	v_mul_f32_e32 v64, v71, v69
	v_mul_f32_e32 v67, v67, v64
	v_lshl_add_u64 v[68:69], v[80:81], 0, v[112:113]
	v_cvt_pk_bf16_f32 v64, v72, v73
	v_cvt_pk_bf16_f32 v65, v74, v75
	v_cvt_pk_bf16_f32 v66, v76, v77
	v_cvt_pk_bf16_f32 v67, v70, v67
	global_store_dwordx4 v[68:69], v[64:67], off sc0 sc1
	s_nop 1
	v_mul_f32_e32 v64, 0xbfb8aa3b, v60
	v_exp_f32_e32 v64, v64
	v_mul_f32_e32 v65, 0xbfb8aa3b, v61
	v_exp_f32_e32 v65, v65
	v_add_u32_e32 v66, 0x80, v169
	v_add_f32_e32 v64, 1.0, v64
	v_rcp_f32_e32 v67, v64
	v_add_f32_e32 v64, 1.0, v65
	v_rcp_f32_e32 v68, v64
	v_mad_i64_i32 v[64:65], s[44:45], v66, s66, v[156:157]
	v_mul_f32_e32 v60, v60, v67
	v_mul_f32_e32 v56, v56, v60
	v_mul_f32_e32 v60, v61, v68
	v_mul_f32_e32 v61, 0xbfb8aa3b, v62
	v_exp_f32_e32 v61, v61
	v_mul_f32_e32 v66, 0xbfb8aa3b, v63
	v_exp_f32_e32 v66, v66
	v_mul_f32_e32 v57, v57, v60
	v_add_f32_e32 v60, 1.0, v61
	v_rcp_f32_e32 v60, v60
	v_add_f32_e32 v61, 1.0, v66
	v_mul_f32_e32 v66, 0xbfb8aa3b, v52
	v_rcp_f32_e32 v61, v61
	v_exp_f32_e32 v66, v66
	v_mul_f32_e32 v60, v62, v60
	v_mul_f32_e32 v58, v58, v60
	v_mul_f32_e32 v60, v63, v61
	v_add_f32_e32 v61, 1.0, v66
	v_rcp_f32_e32 v61, v61
	v_mul_f32_e32 v62, 0xbfb8aa3b, v53
	v_exp_f32_e32 v62, v62
	v_mul_f32_e32 v59, v59, v60
	v_mul_f32_e32 v52, v52, v61
	v_mul_f32_e32 v60, v48, v52
	v_mul_f32_e32 v52, 0xbfb8aa3b, v54
	v_add_f32_e32 v48, 1.0, v62
	v_exp_f32_e32 v52, v52
	v_mul_f32_e32 v61, 0xbfb8aa3b, v55
	v_rcp_f32_e32 v48, v48
	v_exp_f32_e32 v61, v61
	v_add_f32_e32 v52, 1.0, v52
	v_rcp_f32_e32 v52, v52
	v_mul_f32_e32 v48, v53, v48
	v_add_f32_e32 v53, 1.0, v61
	v_rcp_f32_e32 v53, v53
	v_mul_f32_e32 v61, v49, v48
	v_mul_f32_e32 v48, v54, v52
	v_mul_f32_e32 v54, v50, v48
	v_mul_f32_e32 v48, v55, v53
	v_mul_f32_e32 v51, v51, v48
	v_lshl_add_u64 v[52:53], v[64:65], 0, v[112:113]
	v_cvt_pk_bf16_f32 v48, v56, v57
	v_cvt_pk_bf16_f32 v49, v58, v59
	v_cvt_pk_bf16_f32 v50, v60, v61
	v_cvt_pk_bf16_f32 v51, v54, v51
	global_store_dwordx4 v[52:53], v[48:51], off sc0 sc1
	s_nop 1
	v_mul_f32_e32 v48, 0xbfb8aa3b, v44
	v_exp_f32_e32 v48, v48
	v_mul_f32_e32 v49, 0xbfb8aa3b, v45
	v_exp_f32_e32 v49, v49
	v_add_u32_e32 v50, 0x90, v169
	v_add_f32_e32 v48, 1.0, v48
	v_rcp_f32_e32 v51, v48
	v_add_f32_e32 v48, 1.0, v49
	v_rcp_f32_e32 v52, v48
	v_mad_i64_i32 v[48:49], s[44:45], v50, s66, v[156:157]
	v_mul_f32_e32 v44, v44, v51
	v_mul_f32_e32 v40, v40, v44
	v_mul_f32_e32 v44, v45, v52
	v_mul_f32_e32 v45, 0xbfb8aa3b, v46
	v_exp_f32_e32 v45, v45
	v_mul_f32_e32 v50, 0xbfb8aa3b, v47
	v_exp_f32_e32 v50, v50
	v_mul_f32_e32 v41, v41, v44
	v_add_f32_e32 v44, 1.0, v45
	v_rcp_f32_e32 v44, v44
	v_add_f32_e32 v45, 1.0, v50
	v_mul_f32_e32 v50, 0xbfb8aa3b, v36
	v_rcp_f32_e32 v45, v45
	v_exp_f32_e32 v50, v50
	v_mul_f32_e32 v44, v46, v44
	v_mul_f32_e32 v42, v42, v44
	v_mul_f32_e32 v44, v47, v45
	v_add_f32_e32 v45, 1.0, v50
	v_rcp_f32_e32 v45, v45
	v_mul_f32_e32 v46, 0xbfb8aa3b, v37
	v_exp_f32_e32 v46, v46
; __device__ __forceinline__ unsigned cvt_pk_bf16(float lo, float hi) { unsigned r; asm volatile("v_cvt_pk_bf16_f32 %0, %1, %2" : "=v"(r) : "v"(lo), "v"(hi)); return r; }
; #define PG8_BAR __builtin_amdgcn_s_barrier()
; template <class Epi, class Sched, bool ALIGN_EPI = false, bool SP2 = false>
; __device__ __forceinline__ void gemm_phase(PG8_LAS unsigned char* lds, const Gemm g, const Sched& S, const Epi& E) {
;     ...
;         if constexpr (ALIGN_EPI) { if (wr == 0) PG8_BAR; }
;         if constexpr (!Epi::AFTER_DRAIN) { E(acc, cur, wr, wc, fr, fq); S.done(cur); }
;         if (!has_next) break;
; #pragma unroll
;         for (int a = 0; a < 2; ++a)
; #pragma unroll
;             for (int b = 0; b < 2; ++b)
; #pragma unroll
;                 for (int m = 0; m < 4; ++m)
; #pragma unroll
;                     for (int n = 0; n < 2; ++n) acc[a][b][m][n] = (f32x4){0.f, 0.f, 0.f, 0.f};
;         cur = nxt; cA = nA; cB = nB; ++ui;
;         if constexpr (ALIGN_EPI) { if (wr == 1) PG8_BAR; }
;     __device__ __forceinline__ void operator()(const f32x4 (&acc)[2][2][4][2], const Unit& u, int wr, int wc, int fr, int fq) const {
;         const int row0 = u.pm * BM + wr * 64 + fr, col0 = u.pn * 128 + wc * 32 + 8 * fq;
; #pragma unroll
;         for (int ai = 0; ai < 2; ++ai)
; #pragma unroll
;             for (int m = 0; m < 4; ++m) {
;                 bf16_t* rowp = O + (size_t)(row0 + ai * HALF + m * 16) * ldc + col0;
;                 float h[8];
; #pragma unroll
;                 for (int n = 0; n < 2; ++n)
; #pragma unroll
;                     for (int e = 0; e < 4; ++e) { const float g = acc[ai][0][m][n][e], up = acc[ai][1][m][n][e]; h[4 * n + e] = g * __builtin_amdgcn_rcpf(1.f + __expf(-g)) * up; }
;                 u32x4 w; w.x = cvt_pk_bf16(h[0], h[1]); w.y = cvt_pk_bf16(h[2], h[3]); w.z = cvt_pk_bf16(h[4], h[5]); w.w = cvt_pk_bf16(h[6], h[7]);
;                 *(u32x4*)rowp = w;
;             }
;     }
	v_mul_f32_e32 v43, v43, v44
	v_mul_f32_e32 v36, v36, v45
	v_mul_f32_e32 v44, v32, v36
	v_mul_f32_e32 v36, 0xbfb8aa3b, v38
	v_add_f32_e32 v32, 1.0, v46
	v_exp_f32_e32 v36, v36
	v_mul_f32_e32 v45, 0xbfb8aa3b, v39
	v_rcp_f32_e32 v32, v32
	v_exp_f32_e32 v45, v45
	v_add_f32_e32 v36, 1.0, v36
	v_rcp_f32_e32 v36, v36
	v_mul_f32_e32 v32, v37, v32
	v_add_f32_e32 v37, 1.0, v45
	v_rcp_f32_e32 v37, v37
	v_mul_f32_e32 v45, v33, v32
	v_mul_f32_e32 v32, v38, v36
	v_mul_f32_e32 v38, v34, v32
	v_mul_f32_e32 v32, v39, v37
	v_mul_f32_e32 v35, v35, v32
	v_lshl_add_u64 v[36:37], v[48:49], 0, v[112:113]
	v_cvt_pk_bf16_f32 v32, v40, v41
	v_cvt_pk_bf16_f32 v33, v42, v43
	v_cvt_pk_bf16_f32 v34, v44, v45
	v_cvt_pk_bf16_f32 v35, v38, v35
	global_store_dwordx4 v[36:37], v[32:35], off sc0 sc1
	s_nop 1
	v_mul_f32_e32 v32, 0xbfb8aa3b, v28
	v_exp_f32_e32 v32, v32
	v_mul_f32_e32 v33, 0xbfb8aa3b, v29
	v_exp_f32_e32 v33, v33
	v_add_u32_e32 v34, 0xa0, v169
	v_add_f32_e32 v32, 1.0, v32
	v_rcp_f32_e32 v35, v32
	v_add_f32_e32 v32, 1.0, v33
	v_rcp_f32_e32 v36, v32
	v_mad_i64_i32 v[32:33], s[44:45], v34, s66, v[156:157]
	v_mul_f32_e32 v28, v28, v35
	v_mul_f32_e32 v24, v24, v28
	v_mul_f32_e32 v28, v29, v36
	v_mul_f32_e32 v29, 0xbfb8aa3b, v30
	v_exp_f32_e32 v29, v29
	v_mul_f32_e32 v34, 0xbfb8aa3b, v31
	v_exp_f32_e32 v34, v34
	v_mul_f32_e32 v25, v25, v28
	v_add_f32_e32 v28, 1.0, v29
	v_rcp_f32_e32 v28, v28
	v_add_f32_e32 v29, 1.0, v34
	v_mul_f32_e32 v34, 0xbfb8aa3b, v20
	v_rcp_f32_e32 v29, v29
	v_exp_f32_e32 v34, v34
	v_mul_f32_e32 v28, v30, v28
	v_mul_f32_e32 v26, v26, v28
	v_mul_f32_e32 v28, v31, v29
	v_add_f32_e32 v29, 1.0, v34
	v_rcp_f32_e32 v29, v29
	v_mul_f32_e32 v30, 0xbfb8aa3b, v21
	v_exp_f32_e32 v30, v30
	v_mul_f32_e32 v27, v27, v28
	v_mul_f32_e32 v20, v20, v29
	v_mul_f32_e32 v28, v16, v20
	v_mul_f32_e32 v20, 0xbfb8aa3b, v22
	v_add_f32_e32 v16, 1.0, v30
	v_exp_f32_e32 v20, v20
	v_mul_f32_e32 v29, 0xbfb8aa3b, v23
	v_rcp_f32_e32 v16, v16
	v_exp_f32_e32 v29, v29
	v_add_f32_e32 v20, 1.0, v20
	v_rcp_f32_e32 v20, v20
	v_mul_f32_e32 v16, v21, v16
	v_add_f32_e32 v21, 1.0, v29
	v_rcp_f32_e32 v21, v21
	v_mul_f32_e32 v29, v17, v16
	v_mul_f32_e32 v16, v22, v20
	v_mul_f32_e32 v22, v18, v16
	v_mul_f32_e32 v16, v23, v21
	v_mul_f32_e32 v19, v19, v16
	v_lshl_add_u64 v[20:21], v[32:33], 0, v[112:113]
	v_cvt_pk_bf16_f32 v16, v24, v25
	v_cvt_pk_bf16_f32 v17, v26, v27
	v_cvt_pk_bf16_f32 v18, v28, v29
	v_cvt_pk_bf16_f32 v19, v22, v19
	global_store_dwordx4 v[20:21], v[16:19], off sc0 sc1
	s_nop 1
	v_mul_f32_e32 v16, 0xbfb8aa3b, v12
	v_exp_f32_e32 v16, v16
	v_mul_f32_e32 v17, 0xbfb8aa3b, v13
	v_exp_f32_e32 v17, v17
	v_add_u32_e32 v18, 0xb0, v169
	v_add_f32_e32 v16, 1.0, v16
	v_rcp_f32_e32 v19, v16
	v_add_f32_e32 v16, 1.0, v17
	v_rcp_f32_e32 v20, v16
	v_mad_i64_i32 v[16:17], s[44:45], v18, s66, v[156:157]
	v_mul_f32_e32 v12, v12, v19
	v_mul_f32_e32 v8, v8, v12
	v_mul_f32_e32 v12, v13, v20
	v_mul_f32_e32 v13, 0xbfb8aa3b, v14
	v_exp_f32_e32 v13, v13
	v_mul_f32_e32 v18, 0xbfb8aa3b, v15
	v_exp_f32_e32 v18, v18
	v_mul_f32_e32 v9, v9, v12
	v_add_f32_e32 v12, 1.0, v13
	v_rcp_f32_e32 v12, v12
	v_add_f32_e32 v13, 1.0, v18
	v_mul_f32_e32 v18, 0xbfb8aa3b, v4
	v_rcp_f32_e32 v13, v13
	v_exp_f32_e32 v18, v18
	v_mul_f32_e32 v12, v14, v12
	v_mul_f32_e32 v10, v10, v12
	v_mul_f32_e32 v12, v15, v13
	v_add_f32_e32 v13, 1.0, v18
	v_rcp_f32_e32 v13, v13
	v_mul_f32_e32 v14, 0xbfb8aa3b, v5
	v_exp_f32_e32 v14, v14
	v_mul_f32_e32 v11, v11, v12
	v_mul_f32_e32 v4, v4, v13
	v_mul_f32_e32 v12, v0, v4
	v_mul_f32_e32 v4, 0xbfb8aa3b, v6
	v_add_f32_e32 v0, 1.0, v14
	v_exp_f32_e32 v4, v4
	v_mul_f32_e32 v13, 0xbfb8aa3b, v7
	v_rcp_f32_e32 v0, v0
	v_exp_f32_e32 v13, v13
	v_add_f32_e32 v4, 1.0, v4
	v_rcp_f32_e32 v4, v4
	v_mul_f32_e32 v0, v5, v0
	v_add_f32_e32 v5, 1.0, v13
	v_rcp_f32_e32 v5, v5
	v_mul_f32_e32 v13, v1, v0
	v_mul_f32_e32 v0, v6, v4
	v_mul_f32_e32 v6, v2, v0
	v_mul_f32_e32 v0, v7, v5
	v_mul_f32_e32 v3, v3, v0
	v_lshl_add_u64 v[4:5], v[16:17], 0, v[112:113]
	v_cvt_pk_bf16_f32 v0, v8, v9
	v_cvt_pk_bf16_f32 v1, v10, v11
	v_cvt_pk_bf16_f32 v2, v12, v13
	v_cvt_pk_bf16_f32 v3, v6, v3
	global_store_dwordx4 v[4:5], v[0:3], off sc0 sc1
	s_cbranch_vccnz .LBB0_282
	s_andn2_b64 vcc, exec, s[16:17]
	s_cbranch_vccnz .LBB0_281
	s_barrier
	s_branch .LBB0_281

; #define LAS __attribute__((address_space(3)))
; #define LDS_WAIT() asm volatile("s_waitcnt lgkmcnt(0)" ::: "memory")
; #define TR_TRY(CNT, NBLK, ...) if (r < (CNT)) { const int k0 = 64 * (r / (NBLK)), n0 = 32 * (r % (NBLK)); (void)k0; (void)n0; __VA_ARGS__; continue; } r -= (CNT);
; #define TR_TRY(CNT, NBLK, ...) if (r < (CNT)) { const int k0 = 64 * (r / (NBLK)), n0 = 32 * (r % (NBLK)); (void)k0; (void)n0; __VA_ARGS__; continue; } r -= (CNT);
; __device__ __forceinline__ void tr_item(const float* W, int N, int k0, int n0, bf16* WT, int Kd, int drow0, int dk0, LAS float* scr, int lane) {
;     {
;         float wv[32]; const int n = n0 + (lane & 31); const float* wp = W + (size_t)(k0 + (lane >> 5)) * N + n;
; #pragma unroll
;         for (int i = 0; i < 32; ++i) wv[i] = (n < N) ? wp[(size_t)(2 * i) * N] : 0.f;
; #pragma unroll
;         for (int i = 0; i < 32; ++i) scr[(2 * i + (lane >> 5)) * 33 + (lane & 31)] = wv[i];
;     }
;     LDS_WAIT();
; __global__ void __launch_bounds__(NTHREADS, 2) mega_fwd(Args a_unused) {
;     ...
;             for (int it = hb * 8 + wave; it < NIT2; it += nh * 8) {
;                 int r = it;
;     ...
;                 TR_TRY(I_GU, FF / 32, tr_item(ap->in[21], FF, k0, n0, Wgu2, D, (n0 / 128) * 256 + (n0 % 128), k0, scr, lane))
;                 TR_TRY(I_GU, FF / 32, tr_item(ap->in[22], FF, k0, n0, Wgu2, D, (n0 / 128) * 256 + 128 + (n0 % 128), k0, scr, lane))
;                 TR_TRY(I_WD, D / 32, tr_item(ap->in[23], D, k0, n0, Wd2, FF, n0, k0, scr, lane))
;                 TR_TRY(I_OUT, D / 32, tr_item(ap->in[20], D, k0, n0, Wout, D, n0, k0, scr, lane))
.LBB0_302:
	s_cmpk_gt_i32 s12, 0x57f
	s_mov_b64 s[6:7], -1
	s_cbranch_scc0 .LBB0_312
	s_cmpk_gt_u32 s12, 0xaff
	s_cbranch_scc0 .LBB0_309
	s_and_b32 s4, s11, 0x3e0
	v_or_b32_e32 v0, s4, v158
	s_cmpk_gt_u32 s12, 0x107f
	v_or_b32_e32 v22, s4, v160
	v_or_b32_e32 v21, s4, v161
	v_or_b32_e32 v20, s4, v162
	v_or_b32_e32 v19, s4, v163
	v_lshlrev_b32_e32 v8, 2, v0
	s_cbranch_scc0 .LBB0_306
	v_mov_b64_e32 v[24:25], s[8:9]
	global_load_dwordx2 v[24:25], v[24:25], off offset:160
	s_and_b32 s4, s14, 0x7fffffc0
	v_or_b32_e32 v0, s4, v159
	v_lshlrev_b64 v[26:27], 12, v[0:1]
	v_mov_b32_e32 v9, v1
	s_lshl_b32 s4, s4, 1
	s_mov_b64 s[6:7], 0
	s_waitcnt vmcnt(0) lgkmcnt(0)
	v_lshl_add_u64 v[24:25], v[24:25], 0, v[26:27]
	v_lshl_add_u64 v[24:25], v[24:25], 0, v[8:9]
	v_add_co_u32_e32 v26, vcc, 0x2000, v24
	s_nop 1
	v_addc_co_u32_e32 v27, vcc, 0, v25, vcc
	v_add_co_u32_e32 v28, vcc, 0x4000, v24
	s_nop 1
	v_addc_co_u32_e32 v29, vcc, 0, v25, vcc
	v_add_co_u32_e32 v30, vcc, 0x6000, v24
	s_nop 1
	v_addc_co_u32_e32 v31, vcc, 0, v25, vcc
	v_add_co_u32_e32 v32, vcc, 0x8000, v24
	s_nop 1
	v_addc_co_u32_e32 v33, vcc, 0, v25, vcc
	v_add_co_u32_e32 v34, vcc, 0xa000, v24
	s_nop 1
	v_addc_co_u32_e32 v35, vcc, 0, v25, vcc
	v_add_co_u32_e32 v36, vcc, 0xc000, v24
	s_nop 1
	v_addc_co_u32_e32 v37, vcc, 0, v25, vcc
	v_add_co_u32_e32 v38, vcc, 0xe000, v24
	s_nop 1
	v_addc_co_u32_e32 v39, vcc, 0, v25, vcc
	v_add_co_u32_e32 v40, vcc, 0x10000, v24
	global_load_dword v0, v[24:25], off
	global_load_dword v9, v[26:27], off
	global_load_dword v23, v[28:29], off
	global_load_dword v42, v[30:31], off
	global_load_dword v43, v[32:33], off
	global_load_dword v44, v[34:35], off
	global_load_dword v45, v[36:37], off
	global_load_dword v46, v[38:39], off
	v_addc_co_u32_e32 v41, vcc, 0, v25, vcc
	v_add_co_u32_e32 v26, vcc, 0x12000, v24
	s_nop 1
	v_addc_co_u32_e32 v27, vcc, 0, v25, vcc
	v_add_co_u32_e32 v28, vcc, 0x14000, v24
	s_nop 1
	v_addc_co_u32_e32 v29, vcc, 0, v25, vcc
	v_add_co_u32_e32 v30, vcc, 0x16000, v24
	s_nop 1
	v_addc_co_u32_e32 v31, vcc, 0, v25, vcc
	v_add_co_u32_e32 v32, vcc, 0x18000, v24
	s_nop 1
	v_addc_co_u32_e32 v33, vcc, 0, v25, vcc
	v_add_co_u32_e32 v34, vcc, 0x1a000, v24
	s_nop 1
	v_addc_co_u32_e32 v35, vcc, 0, v25, vcc
	v_add_co_u32_e32 v36, vcc, 0x1c000, v24
	s_nop 1
	v_addc_co_u32_e32 v37, vcc, 0, v25, vcc
	v_add_co_u32_e32 v38, vcc, 0x1e000, v24
	s_nop 1
	v_addc_co_u32_e32 v39, vcc, 0, v25, vcc
	global_load_dword v47, v[40:41], off
	global_load_dword v48, v[26:27], off
	global_load_dword v49, v[28:29], off
	global_load_dword v50, v[30:31], off
	global_load_dword v51, v[32:33], off
	global_load_dword v52, v[34:35], off
	global_load_dword v53, v[36:37], off
	global_load_dword v54, v[38:39], off
	v_add_co_u32_e32 v26, vcc, 0x20000, v24
	s_nop 1
	v_addc_co_u32_e32 v27, vcc, 0, v25, vcc
	v_add_co_u32_e32 v28, vcc, 0x22000, v24
	s_nop 1
	v_addc_co_u32_e32 v29, vcc, 0, v25, vcc
	v_add_co_u32_e32 v30, vcc, 0x24000, v24
	s_nop 1
	v_addc_co_u32_e32 v31, vcc, 0, v25, vcc
	v_add_co_u32_e32 v32, vcc, 0x26000, v24
	s_nop 1
	v_addc_co_u32_e32 v33, vcc, 0, v25, vcc
	v_add_co_u32_e32 v34, vcc, 0x28000, v24
	s_nop 1
	v_addc_co_u32_e32 v35, vcc, 0, v25, vcc
	v_add_co_u32_e32 v36, vcc, 0x2a000, v24
	s_nop 1
	v_addc_co_u32_e32 v37, vcc, 0, v25, vcc
	v_add_co_u32_e32 v38, vcc, 0x2c000, v24
	s_nop 1
	v_addc_co_u32_e32 v39, vcc, 0, v25, vcc
	v_add_co_u32_e32 v40, vcc, 0x2e000, v24
	s_nop 1
	v_addc_co_u32_e32 v41, vcc, 0, v25, vcc
	global_load_dword v55, v[26:27], off
	global_load_dword v56, v[28:29], off
	global_load_dword v57, v[30:31], off
	global_load_dword v58, v[32:33], off
	global_load_dword v59, v[34:35], off
	global_load_dword v60, v[36:37], off
	global_load_dword v61, v[38:39], off
	s_nop 0
	global_load_dword v40, v[40:41], off
	v_add_co_u32_e32 v26, vcc, 0x30000, v24
	s_nop 1
	v_addc_co_u32_e32 v27, vcc, 0, v25, vcc
	v_add_co_u32_e32 v28, vcc, 0x32000, v24
	s_nop 1
	v_addc_co_u32_e32 v29, vcc, 0, v25, vcc
	v_add_co_u32_e32 v30, vcc, 0x34000, v24
	s_nop 1
	v_addc_co_u32_e32 v31, vcc, 0, v25, vcc
	v_add_co_u32_e32 v32, vcc, 0x36000, v24
	s_nop 1
	v_addc_co_u32_e32 v33, vcc, 0, v25, vcc
	v_add_co_u32_e32 v34, vcc, 0x38000, v24
	s_nop 1
	v_addc_co_u32_e32 v35, vcc, 0, v25, vcc
	v_add_co_u32_e32 v36, vcc, 0x3a000, v24
	s_nop 1
	v_addc_co_u32_e32 v37, vcc, 0, v25, vcc
	v_add_co_u32_e32 v38, vcc, 0x3c000, v24
	s_nop 1
	v_addc_co_u32_e32 v39, vcc, 0, v25, vcc
	v_add_co_u32_e32 v24, vcc, 0x3e000, v24
	s_nop 1
	v_addc_co_u32_e32 v25, vcc, 0, v25, vcc
	global_load_dword v26, v[26:27], off
	s_nop 0
	global_load_dword v27, v[28:29], off
	s_nop 0
	global_load_dword v28, v[30:31], off
	global_load_dword v29, v[32:33], off
	s_nop 0
	global_load_dword v30, v[34:35], off
	global_load_dword v31, v[36:37], off
	global_load_dword v32, v[38:39], off
	s_nop 0
	global_load_dword v24, v[24:25], off
	s_waitcnt vmcnt(0) lgkmcnt(0)
	ds_write2_b32 v10, v0, v9 offset1:66
	ds_write2_b32 v10, v23, v42 offset0:132 offset1:198
	ds_write2_b32 v12, v43, v44 offset0:8 offset1:74
	ds_write2_b32 v12, v45, v46 offset0:140 offset1:206
	ds_write2_b32 v13, v47, v48 offset0:16 offset1:82
	ds_write2_b32 v13, v49, v50 offset0:148 offset1:214
	ds_write2_b32 v14, v51, v52 offset0:24 offset1:90
	ds_write2_b32 v14, v53, v54 offset0:156 offset1:222
	ds_write2_b32 v15, v55, v56 offset0:32 offset1:98
	ds_write2_b32 v15, v57, v58 offset0:164 offset1:230
	ds_write2_b32 v16, v59, v60 offset0:40 offset1:106
	ds_write2_b32 v16, v61, v40 offset0:172 offset1:238
	ds_write2_b32 v17, v26, v27 offset0:48 offset1:114
	ds_write2_b32 v17, v28, v29 offset0:180 offset1:246
	ds_write2_b32 v18, v30, v31 offset0:56 offset1:122
	ds_write2_b32 v18, v32, v24 offset0:188 offset1:254
	s_waitcnt lgkmcnt(0)
; #define LAS __attribute__((address_space(3)))
; #define LDS_WAIT() asm volatile("s_waitcnt lgkmcnt(0)" ::: "memory")
; __device__ __forceinline__ unsigned pk2(float lo, float hi) { return f2bf(lo) | (f2bf(hi) << 16); }
; __device__ __forceinline__ void tr_item(const float* W, int N, int k0, int n0, bf16* WT, int Kd, int drow0, int dk0, LAS float* scr, int lane) {
;     ...
;     const int c = lane & 7;
; #pragma unroll
;     for (int j = 0; j < 4; ++j) { const int n = (lane >> 3) + 8 * j; const LAS float* s = scr + (8 * c) * 33 + n;
;         v4u o; o.x = pk2(s[0 * 33], s[1 * 33]); o.y = pk2(s[2 * 33], s[3 * 33]); o.z = pk2(s[4 * 33], s[5 * 33]); o.w = pk2(s[6 * 33], s[7 * 33]);
;         *(v4u*)(WT + (size_t)(drow0 + n) * Kd + dk0 + 8 * c) = o; }
;     LDS_WAIT();
	ds_read_b32 v0, v11
	ds_read_b32 v9, v11 offset:132
	ds_read_b32 v23, v11 offset:264
	ds_read_b32 v25, v11 offset:396
	ds_read_b32 v26, v11 offset:528
	ds_read_b32 v27, v11 offset:660
	ds_read_b32 v30, v11 offset:792
	ds_read_b32 v31, v11 offset:924
	s_waitcnt lgkmcnt(7)
	v_bfe_u32 v24, v0, 16, 1
	v_add3_u32 v0, v0, v24, s21
	s_waitcnt lgkmcnt(6)
	v_bfe_u32 v24, v9, 16, 1
	v_lshrrev_b32_e32 v0, 16, v0
	v_add3_u32 v9, v9, v24, s21
	v_and_or_b32 v24, v9, s35, v0
	s_waitcnt lgkmcnt(5)
	v_bfe_u32 v0, v23, 16, 1
	v_add3_u32 v0, v23, v0, s21
	s_waitcnt lgkmcnt(4)
	v_bfe_u32 v9, v25, 16, 1
	v_lshrrev_b32_e32 v0, 16, v0
	v_add3_u32 v9, v25, v9, s21
	v_and_or_b32 v25, v9, s35, v0
	s_waitcnt lgkmcnt(3)
	v_bfe_u32 v0, v26, 16, 1
	v_add3_u32 v0, v26, v0, s21
	s_waitcnt lgkmcnt(2)
	v_bfe_u32 v9, v27, 16, 1
	v_lshrrev_b32_e32 v0, 16, v0
	v_add3_u32 v9, v27, v9, s21
	v_and_or_b32 v26, v9, s35, v0
	s_waitcnt lgkmcnt(1)
	v_bfe_u32 v0, v30, 16, 1
	v_add3_u32 v0, v30, v0, s21
	s_waitcnt lgkmcnt(0)
	v_bfe_u32 v9, v31, 16, 1
	v_lshrrev_b32_e32 v0, 16, v0
	v_add3_u32 v9, v31, v9, s21
	v_lshl_add_u64 v[28:29], v[2:3], 0, s[4:5]
	v_and_or_b32 v27, v9, s35, v0
	v_lshlrev_b32_e32 v0, 11, v22
	v_lshl_add_u64 v[30:31], v[28:29], 0, v[0:1]
	global_store_dwordx4 v[30:31], v[24:27], off sc0 sc1
	ds_read_b32 v0, v11 offset:32
	ds_read_b32 v9, v11 offset:164
	ds_read_b32 v23, v11 offset:296
	ds_read_b32 v25, v11 offset:428
	ds_read_b32 v26, v11 offset:560
	ds_read_b32 v27, v11 offset:692
	ds_read_b32 v30, v11 offset:824
	ds_read_b32 v31, v11 offset:956
	s_waitcnt lgkmcnt(0)
	v_bfe_u32 v24, v0, 16, 1
	v_add3_u32 v0, v0, v24, s21
	v_bfe_u32 v24, v9, 16, 1
	v_lshrrev_b32_e32 v0, 16, v0
	v_add3_u32 v9, v9, v24, s21
	v_and_or_b32 v24, v9, s35, v0
	v_bfe_u32 v0, v23, 16, 1
	v_add3_u32 v0, v23, v0, s21
	v_bfe_u32 v9, v25, 16, 1
	v_lshrrev_b32_e32 v0, 16, v0
	v_add3_u32 v9, v25, v9, s21
	v_and_or_b32 v25, v9, s35, v0
	v_bfe_u32 v0, v26, 16, 1
	v_add3_u32 v0, v26, v0, s21
	v_bfe_u32 v9, v27, 16, 1
	v_lshrrev_b32_e32 v0, 16, v0
	v_add3_u32 v9, v27, v9, s21
	v_and_or_b32 v26, v9, s35, v0
	v_bfe_u32 v0, v30, 16, 1
	v_add3_u32 v0, v30, v0, s21
	v_bfe_u32 v9, v31, 16, 1
	v_lshrrev_b32_e32 v0, 16, v0
	v_add3_u32 v9, v31, v9, s21
	v_and_or_b32 v27, v9, s35, v0
	v_lshlrev_b32_e32 v0, 11, v21
	v_lshl_add_u64 v[30:31], v[28:29], 0, v[0:1]
	global_store_dwordx4 v[30:31], v[24:27], off sc0 sc1
	ds_read_b32 v0, v11 offset:64
	ds_read_b32 v9, v11 offset:196
	ds_read_b32 v23, v11 offset:328
	ds_read_b32 v25, v11 offset:460
	ds_read_b32 v26, v11 offset:592
	ds_read_b32 v27, v11 offset:724
	ds_read_b32 v30, v11 offset:856
	ds_read_b32 v31, v11 offset:988
	s_waitcnt lgkmcnt(0)
	v_bfe_u32 v24, v0, 16, 1
	v_add3_u32 v0, v0, v24, s21
	v_bfe_u32 v24, v9, 16, 1
	v_lshrrev_b32_e32 v0, 16, v0
	v_add3_u32 v9, v9, v24, s21
	v_and_or_b32 v24, v9, s35, v0
	v_bfe_u32 v0, v23, 16, 1
	v_add3_u32 v0, v23, v0, s21
	v_bfe_u32 v9, v25, 16, 1
	v_lshrrev_b32_e32 v0, 16, v0
	v_add3_u32 v9, v25, v9, s21
	v_and_or_b32 v25, v9, s35, v0
	v_bfe_u32 v0, v26, 16, 1
	v_add3_u32 v0, v26, v0, s21
	v_bfe_u32 v9, v27, 16, 1
	v_lshrrev_b32_e32 v0, 16, v0
	v_add3_u32 v9, v27, v9, s21
	v_and_or_b32 v26, v9, s35, v0
	v_bfe_u32 v0, v30, 16, 1
	v_add3_u32 v0, v30, v0, s21
	v_bfe_u32 v9, v31, 16, 1
	v_lshrrev_b32_e32 v0, 16, v0
	v_add3_u32 v9, v31, v9, s21
	v_and_or_b32 v27, v9, s35, v0
	v_lshlrev_b32_e32 v0, 11, v20
	v_lshl_add_u64 v[30:31], v[28:29], 0, v[0:1]
	global_store_dwordx4 v[30:31], v[24:27], off sc0 sc1
	ds_read_b32 v0, v11 offset:96
	ds_read_b32 v9, v11 offset:228
	ds_read_b32 v23, v11 offset:360
	ds_read_b32 v25, v11 offset:492
	ds_read_b32 v26, v11 offset:624
	ds_read_b32 v27, v11 offset:756
	ds_read_b32 v30, v11 offset:888
	ds_read_b32 v31, v11 offset:1020
	s_waitcnt lgkmcnt(0)
	v_bfe_u32 v24, v0, 16, 1
	v_add3_u32 v0, v0, v24, s21
	v_bfe_u32 v24, v9, 16, 1
	v_lshrrev_b32_e32 v0, 16, v0
	v_add3_u32 v9, v9, v24, s21
	v_and_or_b32 v24, v9, s35, v0
	v_bfe_u32 v0, v23, 16, 1
	v_add3_u32 v0, v23, v0, s21
	v_bfe_u32 v9, v25, 16, 1
	v_lshrrev_b32_e32 v0, 16, v0
	v_add3_u32 v9, v25, v9, s21
	v_and_or_b32 v25, v9, s35, v0
	v_bfe_u32 v0, v26, 16, 1
	v_add3_u32 v0, v26, v0, s21
	v_bfe_u32 v9, v27, 16, 1
	v_lshrrev_b32_e32 v0, 16, v0
	v_add3_u32 v9, v27, v9, s21
	v_and_or_b32 v26, v9, s35, v0
	v_bfe_u32 v0, v30, 16, 1
	v_add3_u32 v0, v30, v0, s21
	v_bfe_u32 v9, v31, 16, 1
	v_lshrrev_b32_e32 v0, 16, v0
	v_add3_u32 v9, v31, v9, s21
	v_and_or_b32 v27, v9, s35, v0
	v_lshlrev_b32_e32 v0, 11, v19
	v_lshl_add_u64 v[28:29], v[28:29], 0, v[0:1]
	global_store_dwordx4 v[28:29], v[24:27], off sc0 sc1
	s_waitcnt lgkmcnt(0)
; #define LAS __attribute__((address_space(3)))
; #define LDS_WAIT() asm volatile("s_waitcnt lgkmcnt(0)" ::: "memory")
; #define TR_TRY(CNT, NBLK, ...) if (r < (CNT)) { const int k0 = 64 * (r / (NBLK)), n0 = 32 * (r % (NBLK)); (void)k0; (void)n0; __VA_ARGS__; continue; } r -= (CNT);
; #define TR_TRY(CNT, NBLK, ...) if (r < (CNT)) { const int k0 = 64 * (r / (NBLK)), n0 = 32 * (r % (NBLK)); (void)k0; (void)n0; __VA_ARGS__; continue; } r -= (CNT);
; __device__ __forceinline__ void tr_item(const float* W, int N, int k0, int n0, bf16* WT, int Kd, int drow0, int dk0, LAS float* scr, int lane) {
;     {
;         float wv[32]; const int n = n0 + (lane & 31); const float* wp = W + (size_t)(k0 + (lane >> 5)) * N + n;
; #pragma unroll
;         for (int i = 0; i < 32; ++i) wv[i] = (n < N) ? wp[(size_t)(2 * i) * N] : 0.f;
; #pragma unroll
;         for (int i = 0; i < 32; ++i) scr[(2 * i + (lane >> 5)) * 33 + (lane & 31)] = wv[i];
;     }
;     LDS_WAIT();
; __global__ void __launch_bounds__(NTHREADS, 2) mega_fwd(Args a_unused) {
;     ...
;                 TR_TRY(I_WD, D / 32, tr_item(ap->in[23], D, k0, n0, Wd2, FF, n0, k0, scr, lane))
.LBB0_306:
	s_andn2_b64 vcc, exec, s[6:7]
	s_cbranch_vccnz .LBB0_308
	v_mov_b64_e32 v[24:25], s[8:9]
	global_load_dwordx2 v[24:25], v[24:25], off offset:184
	s_add_i32 s4, s14, 0xb00
	s_and_b32 s4, s4, 0x7fffffc0
	v_or_b32_e32 v0, s4, v159
	v_lshlrev_b64 v[26:27], 12, v[0:1]
	v_mov_b32_e32 v9, v1
	s_lshl_b32 s4, s4, 1
	s_waitcnt vmcnt(0) lgkmcnt(0)
	v_lshl_add_u64 v[24:25], v[24:25], 0, v[26:27]
	v_lshl_add_u64 v[8:9], v[24:25], 0, v[8:9]
	v_add_co_u32_e32 v24, vcc, 0x2000, v8
	s_nop 1
	v_addc_co_u32_e32 v25, vcc, 0, v9, vcc
	v_add_co_u32_e32 v26, vcc, 0x4000, v8
	s_nop 1
	v_addc_co_u32_e32 v27, vcc, 0, v9, vcc
	v_add_co_u32_e32 v28, vcc, 0x6000, v8
	s_nop 1
	v_addc_co_u32_e32 v29, vcc, 0, v9, vcc
	v_add_co_u32_e32 v30, vcc, 0x8000, v8
	s_nop 1
	v_addc_co_u32_e32 v31, vcc, 0, v9, vcc
	v_add_co_u32_e32 v32, vcc, 0xa000, v8
	s_nop 1
	v_addc_co_u32_e32 v33, vcc, 0, v9, vcc
	v_add_co_u32_e32 v34, vcc, 0xc000, v8
	s_nop 1
	v_addc_co_u32_e32 v35, vcc, 0, v9, vcc
	v_add_co_u32_e32 v36, vcc, 0xe000, v8
	s_nop 1
	v_addc_co_u32_e32 v37, vcc, 0, v9, vcc
	v_add_co_u32_e32 v38, vcc, 0x10000, v8
	global_load_dword v0, v[8:9], off
	global_load_dword v23, v[24:25], off
	global_load_dword v40, v[26:27], off
	global_load_dword v41, v[28:29], off
	global_load_dword v42, v[30:31], off
	global_load_dword v43, v[32:33], off
	global_load_dword v44, v[34:35], off
	global_load_dword v45, v[36:37], off
	v_addc_co_u32_e32 v39, vcc, 0, v9, vcc
	v_add_co_u32_e32 v24, vcc, 0x12000, v8
	s_nop 1
	v_addc_co_u32_e32 v25, vcc, 0, v9, vcc
	v_add_co_u32_e32 v26, vcc, 0x14000, v8
	s_nop 1
	v_addc_co_u32_e32 v27, vcc, 0, v9, vcc
	v_add_co_u32_e32 v28, vcc, 0x16000, v8
	s_nop 1
	v_addc_co_u32_e32 v29, vcc, 0, v9, vcc
	v_add_co_u32_e32 v30, vcc, 0x18000, v8
	s_nop 1
	v_addc_co_u32_e32 v31, vcc, 0, v9, vcc
	v_add_co_u32_e32 v32, vcc, 0x1a000, v8
	s_nop 1
	v_addc_co_u32_e32 v33, vcc, 0, v9, vcc
	v_add_co_u32_e32 v34, vcc, 0x1c000, v8
	s_nop 1
	v_addc_co_u32_e32 v35, vcc, 0, v9, vcc
	v_add_co_u32_e32 v36, vcc, 0x1e000, v8
	s_nop 1
	v_addc_co_u32_e32 v37, vcc, 0, v9, vcc
	global_load_dword v46, v[38:39], off
	global_load_dword v47, v[24:25], off
	global_load_dword v48, v[26:27], off
	global_load_dword v49, v[28:29], off
	global_load_dword v50, v[30:31], off
	global_load_dword v51, v[32:33], off
	global_load_dword v52, v[34:35], off
	global_load_dword v53, v[36:37], off
	v_add_co_u32_e32 v24, vcc, 0x20000, v8
	s_nop 1
	v_addc_co_u32_e32 v25, vcc, 0, v9, vcc
	v_add_co_u32_e32 v26, vcc, 0x22000, v8
	s_nop 1
	v_addc_co_u32_e32 v27, vcc, 0, v9, vcc
	v_add_co_u32_e32 v28, vcc, 0x24000, v8
	s_nop 1
	v_addc_co_u32_e32 v29, vcc, 0, v9, vcc
	v_add_co_u32_e32 v30, vcc, 0x26000, v8
	s_nop 1
	v_addc_co_u32_e32 v31, vcc, 0, v9, vcc
	v_add_co_u32_e32 v32, vcc, 0x28000, v8
	s_nop 1
	v_addc_co_u32_e32 v33, vcc, 0, v9, vcc
	v_add_co_u32_e32 v34, vcc, 0x2a000, v8
	s_nop 1
	v_addc_co_u32_e32 v35, vcc, 0, v9, vcc
	v_add_co_u32_e32 v36, vcc, 0x2c000, v8
	s_nop 1
	v_addc_co_u32_e32 v37, vcc, 0, v9, vcc
	v_add_co_u32_e32 v38, vcc, 0x2e000, v8
	s_nop 1
	v_addc_co_u32_e32 v39, vcc, 0, v9, vcc
	global_load_dword v54, v[24:25], off
	global_load_dword v55, v[26:27], off
	global_load_dword v56, v[28:29], off
	global_load_dword v57, v[30:31], off
	global_load_dword v58, v[32:33], off
	global_load_dword v59, v[34:35], off
	global_load_dword v60, v[36:37], off
	s_nop 0
	global_load_dword v38, v[38:39], off
	v_add_co_u32_e32 v24, vcc, 0x30000, v8
	s_nop 1
	v_addc_co_u32_e32 v25, vcc, 0, v9, vcc
	v_add_co_u32_e32 v26, vcc, 0x32000, v8
	s_nop 1
	v_addc_co_u32_e32 v27, vcc, 0, v9, vcc
	v_add_co_u32_e32 v28, vcc, 0x34000, v8
	s_nop 1
	v_addc_co_u32_e32 v29, vcc, 0, v9, vcc
	v_add_co_u32_e32 v30, vcc, 0x36000, v8
	s_nop 1
	v_addc_co_u32_e32 v31, vcc, 0, v9, vcc
	v_add_co_u32_e32 v32, vcc, 0x38000, v8
	s_nop 1
	v_addc_co_u32_e32 v33, vcc, 0, v9, vcc
	v_add_co_u32_e32 v34, vcc, 0x3a000, v8
	s_nop 1
	v_addc_co_u32_e32 v35, vcc, 0, v9, vcc
	v_add_co_u32_e32 v36, vcc, 0x3c000, v8
	s_nop 1
	v_addc_co_u32_e32 v37, vcc, 0, v9, vcc
	v_add_co_u32_e32 v8, vcc, 0x3e000, v8
	s_nop 1
	v_addc_co_u32_e32 v9, vcc, 0, v9, vcc
	global_load_dword v24, v[24:25], off
	s_nop 0
	global_load_dword v25, v[26:27], off
	s_nop 0
	global_load_dword v26, v[28:29], off
	global_load_dword v27, v[30:31], off
	s_nop 0
	global_load_dword v28, v[32:33], off
	global_load_dword v29, v[34:35], off
	global_load_dword v30, v[36:37], off
	s_nop 0
	global_load_dword v8, v[8:9], off
	s_waitcnt vmcnt(0) lgkmcnt(0)
	ds_write2_b32 v10, v0, v23 offset1:66
	ds_write2_b32 v10, v40, v41 offset0:132 offset1:198
	ds_write2_b32 v12, v42, v43 offset0:8 offset1:74
	ds_write2_b32 v12, v44, v45 offset0:140 offset1:206
	ds_write2_b32 v13, v46, v47 offset0:16 offset1:82
	ds_write2_b32 v13, v48, v49 offset0:148 offset1:214
	ds_write2_b32 v14, v50, v51 offset0:24 offset1:90
	ds_write2_b32 v14, v52, v53 offset0:156 offset1:222
	ds_write2_b32 v15, v54, v55 offset0:32 offset1:98
	ds_write2_b32 v15, v56, v57 offset0:164 offset1:230
	ds_write2_b32 v16, v58, v59 offset0:40 offset1:106
	ds_write2_b32 v16, v60, v38 offset0:172 offset1:238
	ds_write2_b32 v17, v24, v25 offset0:48 offset1:114
	ds_write2_b32 v17, v26, v27 offset0:180 offset1:246
	ds_write2_b32 v18, v28, v29 offset0:56 offset1:122
	ds_write2_b32 v18, v30, v8 offset0:188 offset1:254
	s_waitcnt lgkmcnt(0)
; #define LAS __attribute__((address_space(3)))
; #define LDS_WAIT() asm volatile("s_waitcnt lgkmcnt(0)" ::: "memory")
; __device__ __forceinline__ unsigned pk2(float lo, float hi) { return f2bf(lo) | (f2bf(hi) << 16); }
; __device__ __forceinline__ void tr_item(const float* W, int N, int k0, int n0, bf16* WT, int Kd, int drow0, int dk0, LAS float* scr, int lane) {
;     ...
;     const int c = lane & 7;
; #pragma unroll
;     for (int j = 0; j < 4; ++j) { const int n = (lane >> 3) + 8 * j; const LAS float* s = scr + (8 * c) * 33 + n;
;         v4u o; o.x = pk2(s[0 * 33], s[1 * 33]); o.y = pk2(s[2 * 33], s[3 * 33]); o.z = pk2(s[4 * 33], s[5 * 33]); o.w = pk2(s[6 * 33], s[7 * 33]);
;         *(v4u*)(WT + (size_t)(drow0 + n) * Kd + dk0 + 8 * c) = o; }
;     LDS_WAIT();
	ds_read_b32 v0, v11
	ds_read_b32 v23, v11 offset:132
	ds_read_b32 v25, v11 offset:264
	ds_read_b32 v26, v11 offset:396
	ds_read_b32 v27, v11 offset:528
	ds_read_b32 v28, v11 offset:660
	ds_read_b32 v29, v11 offset:792
	ds_read_b32 v30, v11 offset:924
	s_waitcnt lgkmcnt(7)
	v_bfe_u32 v24, v0, 16, 1
	v_add3_u32 v0, v0, v24, s21
	s_waitcnt lgkmcnt(6)
	v_bfe_u32 v24, v23, 16, 1
	v_lshrrev_b32_e32 v0, 16, v0
	v_add3_u32 v23, v23, v24, s21
	v_and_or_b32 v24, v23, s35, v0
	s_waitcnt lgkmcnt(5)
	v_bfe_u32 v0, v25, 16, 1
	v_add3_u32 v0, v25, v0, s21
	s_waitcnt lgkmcnt(4)
	v_bfe_u32 v23, v26, 16, 1
	v_lshrrev_b32_e32 v0, 16, v0
	v_add3_u32 v23, v26, v23, s21
	v_and_or_b32 v25, v23, s35, v0
	s_waitcnt lgkmcnt(3)
	v_bfe_u32 v0, v27, 16, 1
	v_add3_u32 v0, v27, v0, s21
	s_waitcnt lgkmcnt(2)
	v_bfe_u32 v23, v28, 16, 1
	v_lshrrev_b32_e32 v0, 16, v0
	v_add3_u32 v23, v28, v23, s21
	v_and_or_b32 v26, v23, s35, v0
	s_waitcnt lgkmcnt(1)
	v_bfe_u32 v0, v29, 16, 1
	v_add3_u32 v0, v29, v0, s21
	s_waitcnt lgkmcnt(0)
	v_bfe_u32 v23, v30, 16, 1
	v_lshrrev_b32_e32 v0, 16, v0
	v_add3_u32 v23, v30, v23, s21
	v_and_or_b32 v27, v23, s35, v0
	v_mul_u32_u24_e32 v0, 0xb00, v22
	v_lshl_add_u64 v[8:9], v[4:5], 0, s[4:5]
	v_lshlrev_b32_e32 v0, 1, v0
	v_lshl_add_u64 v[22:23], v[8:9], 0, v[0:1]
	global_store_dwordx4 v[22:23], v[24:27], off sc0 sc1
	ds_read_b32 v0, v11 offset:32
	ds_read_b32 v22, v11 offset:164
	ds_read_b32 v23, v11 offset:296
	ds_read_b32 v24, v11 offset:428
	ds_read_b32 v25, v11 offset:560
	ds_read_b32 v26, v11 offset:692
	ds_read_b32 v27, v11 offset:824
	ds_read_b32 v28, v11 offset:956
	s_waitcnt lgkmcnt(0)
	v_bfe_u32 v29, v0, 16, 1
	v_add3_u32 v0, v0, v29, s21
	v_bfe_u32 v29, v22, 16, 1
	v_lshrrev_b32_e32 v0, 16, v0
	v_add3_u32 v22, v22, v29, s21
	v_and_or_b32 v22, v22, s35, v0
	v_bfe_u32 v0, v23, 16, 1
	v_add3_u32 v0, v23, v0, s21
	v_bfe_u32 v23, v24, 16, 1
	v_lshrrev_b32_e32 v0, 16, v0
	v_add3_u32 v23, v24, v23, s21
	v_and_or_b32 v23, v23, s35, v0
	v_bfe_u32 v0, v25, 16, 1
	v_add3_u32 v0, v25, v0, s21
	v_bfe_u32 v24, v26, 16, 1
	v_lshrrev_b32_e32 v0, 16, v0
	v_add3_u32 v24, v26, v24, s21
	v_and_or_b32 v24, v24, s35, v0
	v_bfe_u32 v0, v27, 16, 1
	v_add3_u32 v0, v27, v0, s21
	v_bfe_u32 v25, v28, 16, 1
	v_lshrrev_b32_e32 v0, 16, v0
	v_add3_u32 v25, v28, v25, s21
	v_and_or_b32 v25, v25, s35, v0
	v_mul_u32_u24_e32 v0, 0xb00, v21
	v_lshlrev_b32_e32 v0, 1, v0
	v_lshl_add_u64 v[26:27], v[8:9], 0, v[0:1]
	global_store_dwordx4 v[26:27], v[22:25], off sc0 sc1
	ds_read_b32 v0, v11 offset:64
	ds_read_b32 v21, v11 offset:196
	ds_read_b32 v23, v11 offset:328
	ds_read_b32 v24, v11 offset:460
	ds_read_b32 v25, v11 offset:592
	ds_read_b32 v26, v11 offset:724
	ds_read_b32 v27, v11 offset:856
	ds_read_b32 v28, v11 offset:988
	s_waitcnt lgkmcnt(0)
	v_bfe_u32 v22, v0, 16, 1
	v_add3_u32 v0, v0, v22, s21
	v_bfe_u32 v22, v21, 16, 1
	v_lshrrev_b32_e32 v0, 16, v0
	v_add3_u32 v21, v21, v22, s21
	v_and_or_b32 v22, v21, s35, v0
	v_bfe_u32 v0, v23, 16, 1
	v_add3_u32 v0, v23, v0, s21
	v_bfe_u32 v21, v24, 16, 1
	v_lshrrev_b32_e32 v0, 16, v0
	v_add3_u32 v21, v24, v21, s21
	v_and_or_b32 v23, v21, s35, v0
	v_bfe_u32 v0, v25, 16, 1
	v_add3_u32 v0, v25, v0, s21
	v_bfe_u32 v21, v26, 16, 1
	v_lshrrev_b32_e32 v0, 16, v0
	v_add3_u32 v21, v26, v21, s21
	v_and_or_b32 v24, v21, s35, v0
	v_bfe_u32 v0, v27, 16, 1
	v_add3_u32 v0, v27, v0, s21
	v_bfe_u32 v21, v28, 16, 1
	v_lshrrev_b32_e32 v0, 16, v0
	v_add3_u32 v21, v28, v21, s21
	v_and_or_b32 v25, v21, s35, v0
	v_mul_u32_u24_e32 v0, 0xb00, v20
	v_lshlrev_b32_e32 v0, 1, v0
	v_lshl_add_u64 v[20:21], v[8:9], 0, v[0:1]
	global_store_dwordx4 v[20:21], v[22:25], off sc0 sc1
	ds_read_b32 v0, v11 offset:96
	ds_read_b32 v20, v11 offset:228
	ds_read_b32 v21, v11 offset:360
	ds_read_b32 v22, v11 offset:492
	ds_read_b32 v23, v11 offset:624
	ds_read_b32 v24, v11 offset:756
	ds_read_b32 v25, v11 offset:888
	ds_read_b32 v26, v11 offset:1020
	s_waitcnt lgkmcnt(0)
	v_bfe_u32 v27, v0, 16, 1
	v_add3_u32 v0, v0, v27, s21
	v_bfe_u32 v27, v20, 16, 1
	v_lshrrev_b32_e32 v0, 16, v0
	v_add3_u32 v20, v20, v27, s21
	v_and_or_b32 v20, v20, s35, v0
	v_bfe_u32 v0, v21, 16, 1
	v_add3_u32 v0, v21, v0, s21
	v_bfe_u32 v21, v22, 16, 1
	v_lshrrev_b32_e32 v0, 16, v0
	v_add3_u32 v21, v22, v21, s21
	v_and_or_b32 v21, v21, s35, v0
	v_bfe_u32 v0, v23, 16, 1
	v_add3_u32 v0, v23, v0, s21
	v_bfe_u32 v22, v24, 16, 1
	v_lshrrev_b32_e32 v0, 16, v0
	v_add3_u32 v22, v24, v22, s21
	v_and_or_b32 v22, v22, s35, v0
	v_bfe_u32 v0, v25, 16, 1
	v_add3_u32 v0, v25, v0, s21
	v_bfe_u32 v23, v26, 16, 1
	v_lshrrev_b32_e32 v0, 16, v0
	v_add3_u32 v23, v26, v23, s21
	v_and_or_b32 v23, v23, s35, v0
	v_mul_u32_u24_e32 v0, 0xb00, v19
	v_lshlrev_b32_e32 v0, 1, v0
	v_lshl_add_u64 v[8:9], v[8:9], 0, v[0:1]
	global_store_dwordx4 v[8:9], v[20:23], off sc0 sc1
	s_waitcnt lgkmcnt(0)

; #define LAS __attribute__((address_space(3)))
; #define LDS_WAIT() asm volatile("s_waitcnt lgkmcnt(0)" ::: "memory")
; #define TR_TRY(CNT, NBLK, ...) if (r < (CNT)) { const int k0 = 64 * (r / (NBLK)), n0 = 32 * (r % (NBLK)); (void)k0; (void)n0; __VA_ARGS__; continue; } r -= (CNT);
; #define TR_TRY(CNT, NBLK, ...) if (r < (CNT)) { const int k0 = 64 * (r / (NBLK)), n0 = 32 * (r % (NBLK)); (void)k0; (void)n0; __VA_ARGS__; continue; } r -= (CNT);
; __device__ __forceinline__ void tr_item(const float* W, int N, int k0, int n0, bf16* WT, int Kd, int drow0, int dk0, LAS float* scr, int lane) {
;     {
;         float wv[32]; const int n = n0 + (lane & 31); const float* wp = W + (size_t)(k0 + (lane >> 5)) * N + n;
; #pragma unroll
;         for (int i = 0; i < 32; ++i) wv[i] = (n < N) ? wp[(size_t)(2 * i) * N] : 0.f;
; #pragma unroll
;         for (int i = 0; i < 32; ++i) scr[(2 * i + (lane >> 5)) * 33 + (lane & 31)] = wv[i];
;     }
;     LDS_WAIT();
; __global__ void __launch_bounds__(NTHREADS, 2) mega_fwd(Args a_unused) {
;     ...
;                 TR_TRY(I_GU, FF / 32, tr_item(ap->in[22], FF, k0, n0, Wgu2, D, (n0 / 128) * 256 + 128 + (n0 % 128), k0, scr, lane))
.LBB0_309:
	s_andn2_b64 vcc, exec, s[6:7]
	s_cbranch_vccnz .LBB0_311
	v_mov_b64_e32 v[8:9], s[8:9]
	global_load_dwordx2 v[8:9], v[8:9], off offset:176
	s_add_i32 s6, s12, 0xfa80
	s_and_b32 s4, s6, 0xffff
	s_mul_i32 s4, s4, 0xba2f
	s_lshr_b32 s7, s4, 22
	s_lshr_b32 s4, s4, 16
	s_mulk_i32 s7, 0x58
	s_and_b32 s4, s4, 0xffc0
	s_sub_i32 s6, s6, s7
	v_or_b32_e32 v0, s4, v159
	s_and_b32 s6, s6, 0xffff
	v_mul_u32_u24_e32 v0, 0xb00, v0
	s_lshl_b32 s7, s6, 5
	v_lshlrev_b32_e32 v0, 2, v0
	v_or_b32_e32 v19, s7, v158
	s_lshl_b32 s6, s6, 6
	s_and_b32 s6, s6, 0x1f00
	s_and_b32 s7, s7, 0x60
	s_or_b32 s6, s7, s6
	s_bitset1_b32 s6, 7
	s_lshl_b32 s4, s4, 1
	s_waitcnt vmcnt(0) lgkmcnt(0)
	v_lshl_add_u64 v[8:9], v[8:9], 0, v[0:1]
	v_lshlrev_b32_e32 v0, 2, v19
	v_lshl_add_u64 v[8:9], v[8:9], 0, v[0:1]
	v_add_co_u32_e32 v20, vcc, s38, v8
	s_nop 1
	v_addc_co_u32_e32 v21, vcc, 0, v9, vcc
	v_add_co_u32_e32 v22, vcc, s39, v8
	s_nop 1
	v_addc_co_u32_e32 v23, vcc, 0, v9, vcc
	v_add_co_u32_e32 v24, vcc, s16, v8
	s_nop 1
	v_addc_co_u32_e32 v25, vcc, 0, v9, vcc
	v_add_co_u32_e32 v26, vcc, s17, v8
	s_nop 1
	v_addc_co_u32_e32 v27, vcc, 0, v9, vcc
	v_add_co_u32_e32 v28, vcc, s40, v8
	s_nop 1
	v_addc_co_u32_e32 v29, vcc, 0, v9, vcc
	v_add_co_u32_e32 v30, vcc, s41, v8
	s_nop 1
	v_addc_co_u32_e32 v31, vcc, 0, v9, vcc
	v_add_co_u32_e32 v32, vcc, s18, v8
	s_nop 1
	v_addc_co_u32_e32 v33, vcc, 0, v9, vcc
	v_add_co_u32_e32 v34, vcc, s19, v8
	global_load_dword v0, v[8:9], off
	global_load_dword v19, v[20:21], off offset:2048
	global_load_dword v48, v[22:23], off
	global_load_dword v49, v[24:25], off offset:2048
	global_load_dword v50, v[26:27], off
	global_load_dword v51, v[28:29], off offset:2048
	global_load_dword v52, v[30:31], off
	global_load_dword v53, v[32:33], off offset:2048
	v_addc_co_u32_e32 v35, vcc, 0, v9, vcc
	v_add_co_u32_e32 v36, vcc, s42, v8
	s_nop 1
	v_addc_co_u32_e32 v37, vcc, 0, v9, vcc
	v_add_co_u32_e32 v38, vcc, s43, v8
	s_nop 1
	v_addc_co_u32_e32 v39, vcc, 0, v9, vcc
	v_add_co_u32_e32 v40, vcc, s20, v8
	s_nop 1
	v_addc_co_u32_e32 v41, vcc, 0, v9, vcc
	v_add_co_u32_e32 v42, vcc, s44, v8
	s_nop 1
	v_addc_co_u32_e32 v43, vcc, 0, v9, vcc
	v_add_co_u32_e32 v44, vcc, s45, v8
	s_nop 1
	v_addc_co_u32_e32 v45, vcc, 0, v9, vcc
	v_add_co_u32_e32 v46, vcc, s46, v8
	s_nop 1
	v_addc_co_u32_e32 v47, vcc, 0, v9, vcc
	v_add_co_u32_e32 v20, vcc, s47, v8
	s_nop 1
	v_addc_co_u32_e32 v21, vcc, 0, v9, vcc
	global_load_dword v54, v[34:35], off
	s_nop 0
	global_load_dword v36, v[36:37], off offset:2048
	s_nop 0
	global_load_dword v37, v[38:39], off
	s_nop 0
	global_load_dword v38, v[40:41], off offset:2048
	global_load_dword v39, v[42:43], off
	s_nop 0
	global_load_dword v40, v[44:45], off offset:2048
	global_load_dword v41, v[46:47], off
	global_load_dword v42, v[20:21], off offset:2048
	v_add_co_u32_e32 v20, vcc, s48, v8
	s_nop 1
	v_addc_co_u32_e32 v21, vcc, 0, v9, vcc
	v_add_co_u32_e32 v22, vcc, s49, v8
	s_nop 1
	v_addc_co_u32_e32 v23, vcc, 0, v9, vcc
	v_add_co_u32_e32 v24, vcc, s50, v8
	s_nop 1
	v_addc_co_u32_e32 v25, vcc, 0, v9, vcc
	v_add_co_u32_e32 v26, vcc, s51, v8
	s_nop 1
	v_addc_co_u32_e32 v27, vcc, 0, v9, vcc
	v_add_co_u32_e32 v28, vcc, s52, v8
	s_nop 1
	v_addc_co_u32_e32 v29, vcc, 0, v9, vcc
	v_add_co_u32_e32 v30, vcc, s53, v8
	s_nop 1
	v_addc_co_u32_e32 v31, vcc, 0, v9, vcc
	v_add_co_u32_e32 v32, vcc, s54, v8
	s_nop 1
	v_addc_co_u32_e32 v33, vcc, 0, v9, vcc
	v_add_co_u32_e32 v34, vcc, s55, v8
	s_nop 1
	v_addc_co_u32_e32 v35, vcc, 0, v9, vcc
	global_load_dword v43, v[20:21], off
	global_load_dword v44, v[22:23], off offset:2048
	global_load_dword v45, v[24:25], off
	global_load_dword v46, v[26:27], off offset:2048
	global_load_dword v47, v[28:29], off
	global_load_dword v55, v[30:31], off offset:2048
	global_load_dword v56, v[32:33], off
	s_nop 0
	global_load_dword v34, v[34:35], off offset:2048
	v_add_co_u32_e32 v20, vcc, s56, v8
	s_nop 1
	v_addc_co_u32_e32 v21, vcc, 0, v9, vcc
	v_add_co_u32_e32 v22, vcc, s57, v8
	s_nop 1
	v_addc_co_u32_e32 v23, vcc, 0, v9, vcc
	v_add_co_u32_e32 v24, vcc, s58, v8
	s_nop 1
	v_addc_co_u32_e32 v25, vcc, 0, v9, vcc
	v_add_co_u32_e32 v26, vcc, s59, v8
	s_nop 1
	v_addc_co_u32_e32 v27, vcc, 0, v9, vcc
	v_add_co_u32_e32 v28, vcc, s60, v8
	s_nop 1
	v_addc_co_u32_e32 v29, vcc, 0, v9, vcc
	v_add_co_u32_e32 v30, vcc, s61, v8
	s_nop 1
	v_addc_co_u32_e32 v31, vcc, 0, v9, vcc
	v_add_co_u32_e32 v32, vcc, s62, v8
	s_nop 1
	v_addc_co_u32_e32 v33, vcc, 0, v9, vcc
	v_add_co_u32_e32 v8, vcc, s63, v8
	s_nop 1
	v_addc_co_u32_e32 v9, vcc, 0, v9, vcc
	global_load_dword v20, v[20:21], off
	s_nop 0
	global_load_dword v21, v[22:23], off offset:2048
	s_nop 0
	global_load_dword v22, v[24:25], off
	global_load_dword v23, v[26:27], off offset:2048
	s_nop 0
	global_load_dword v24, v[28:29], off
	global_load_dword v25, v[30:31], off offset:2048
	global_load_dword v26, v[32:33], off
	s_nop 0
	global_load_dword v8, v[8:9], off offset:2048
	s_waitcnt vmcnt(0) lgkmcnt(0)
; #define LAS __attribute__((address_space(3)))
; #define LDS_WAIT() asm volatile("s_waitcnt lgkmcnt(0)" ::: "memory")
; __device__ __forceinline__ unsigned pk2(float lo, float hi) { return f2bf(lo) | (f2bf(hi) << 16); }
; __device__ __forceinline__ void tr_item(const float* W, int N, int k0, int n0, bf16* WT, int Kd, int drow0, int dk0, LAS float* scr, int lane) {
;     ...
;     const int c = lane & 7;
; #pragma unroll
;     for (int j = 0; j < 4; ++j) { const int n = (lane >> 3) + 8 * j; const LAS float* s = scr + (8 * c) * 33 + n;
;         v4u o; o.x = pk2(s[0 * 33], s[1 * 33]); o.y = pk2(s[2 * 33], s[3 * 33]); o.z = pk2(s[4 * 33], s[5 * 33]); o.w = pk2(s[6 * 33], s[7 * 33]);
;         *(v4u*)(WT + (size_t)(drow0 + n) * Kd + dk0 + 8 * c) = o; }
;     LDS_WAIT();
	ds_write2_b32 v10, v0, v19 offset1:66
	ds_write2_b32 v10, v48, v49 offset0:132 offset1:198
	ds_write2_b32 v12, v50, v51 offset0:8 offset1:74
	ds_write2_b32 v12, v52, v53 offset0:140 offset1:206
	ds_write2_b32 v13, v54, v36 offset0:16 offset1:82
	ds_write2_b32 v13, v37, v38 offset0:148 offset1:214
	ds_write2_b32 v14, v39, v40 offset0:24 offset1:90
	ds_write2_b32 v14, v41, v42 offset0:156 offset1:222
	ds_write2_b32 v15, v43, v44 offset0:32 offset1:98
	ds_write2_b32 v15, v45, v46 offset0:164 offset1:230
	ds_write2_b32 v16, v47, v55 offset0:40 offset1:106
	ds_write2_b32 v16, v56, v34 offset0:172 offset1:238
	ds_write2_b32 v17, v20, v21 offset0:48 offset1:114
	ds_write2_b32 v17, v22, v23 offset0:180 offset1:246
	ds_write2_b32 v18, v24, v25 offset0:56 offset1:122
	ds_write2_b32 v18, v26, v8 offset0:188 offset1:254
	s_waitcnt lgkmcnt(0)
	ds_read_b32 v0, v11
	ds_read_b32 v19, v11 offset:132
	ds_read_b32 v21, v11 offset:264
	ds_read_b32 v22, v11 offset:396
	ds_read_b32 v23, v11 offset:528
	ds_read_b32 v24, v11 offset:660
	ds_read_b32 v25, v11 offset:792
	ds_read_b32 v26, v11 offset:924
	s_waitcnt lgkmcnt(7)
	v_bfe_u32 v20, v0, 16, 1
	v_add3_u32 v0, v0, v20, s21
	s_waitcnt lgkmcnt(6)
	v_bfe_u32 v20, v19, 16, 1
	v_lshrrev_b32_e32 v0, 16, v0
	v_add3_u32 v19, v19, v20, s21
	v_and_or_b32 v20, v19, s35, v0
	s_waitcnt lgkmcnt(5)
	v_bfe_u32 v0, v21, 16, 1
	v_add3_u32 v0, v21, v0, s21
	s_waitcnt lgkmcnt(4)
	v_bfe_u32 v19, v22, 16, 1
	v_lshrrev_b32_e32 v0, 16, v0
	v_add3_u32 v19, v22, v19, s21
	v_and_or_b32 v21, v19, s35, v0
	s_waitcnt lgkmcnt(3)
	v_bfe_u32 v0, v23, 16, 1
	v_add3_u32 v0, v23, v0, s21
	s_waitcnt lgkmcnt(2)
	v_bfe_u32 v19, v24, 16, 1
	v_lshrrev_b32_e32 v0, 16, v0
	v_add3_u32 v19, v24, v19, s21
	v_and_or_b32 v22, v19, s35, v0
	s_waitcnt lgkmcnt(1)
	v_bfe_u32 v0, v25, 16, 1
	v_add3_u32 v0, v25, v0, s21
	s_waitcnt lgkmcnt(0)
	v_bfe_u32 v19, v26, 16, 1
	v_lshrrev_b32_e32 v0, 16, v0
	v_add3_u32 v19, v26, v19, s21
	v_and_or_b32 v23, v19, s35, v0
	v_or_b32_e32 v0, s6, v160
	v_lshl_add_u64 v[8:9], v[6:7], 0, s[4:5]
	v_lshlrev_b32_e32 v0, 11, v0
	v_lshl_add_u64 v[24:25], v[8:9], 0, v[0:1]
	global_store_dwordx4 v[24:25], v[20:23], off sc0 sc1
	ds_read_b32 v0, v11 offset:32
	ds_read_b32 v19, v11 offset:164
	ds_read_b32 v21, v11 offset:296
	ds_read_b32 v22, v11 offset:428
	ds_read_b32 v23, v11 offset:560
	ds_read_b32 v24, v11 offset:692
	ds_read_b32 v25, v11 offset:824
	ds_read_b32 v26, v11 offset:956
	s_waitcnt lgkmcnt(0)
	v_bfe_u32 v20, v0, 16, 1
	v_add3_u32 v0, v0, v20, s21
	v_bfe_u32 v20, v19, 16, 1
	v_lshrrev_b32_e32 v0, 16, v0
	v_add3_u32 v19, v19, v20, s21
	v_and_or_b32 v20, v19, s35, v0
	v_bfe_u32 v0, v21, 16, 1
	v_add3_u32 v0, v21, v0, s21
	v_bfe_u32 v19, v22, 16, 1
	v_lshrrev_b32_e32 v0, 16, v0
	v_add3_u32 v19, v22, v19, s21
	v_and_or_b32 v21, v19, s35, v0
	v_bfe_u32 v0, v23, 16, 1
	v_add3_u32 v0, v23, v0, s21
	v_bfe_u32 v19, v24, 16, 1
	v_lshrrev_b32_e32 v0, 16, v0
	v_add3_u32 v19, v24, v19, s21
	v_and_or_b32 v22, v19, s35, v0
	v_bfe_u32 v0, v25, 16, 1
	v_add3_u32 v0, v25, v0, s21
	v_bfe_u32 v19, v26, 16, 1
	v_lshrrev_b32_e32 v0, 16, v0
	v_add3_u32 v19, v26, v19, s21
	v_and_or_b32 v23, v19, s35, v0
	v_or_b32_e32 v0, s6, v161
	v_lshlrev_b32_e32 v0, 11, v0
	v_lshl_add_u64 v[24:25], v[8:9], 0, v[0:1]
	global_store_dwordx4 v[24:25], v[20:23], off sc0 sc1
	ds_read_b32 v0, v11 offset:64
	ds_read_b32 v19, v11 offset:196
	ds_read_b32 v21, v11 offset:328
	ds_read_b32 v22, v11 offset:460
	ds_read_b32 v23, v11 offset:592
	ds_read_b32 v24, v11 offset:724
	ds_read_b32 v25, v11 offset:856
	ds_read_b32 v26, v11 offset:988
	s_waitcnt lgkmcnt(0)
	v_bfe_u32 v20, v0, 16, 1
	v_add3_u32 v0, v0, v20, s21
	v_bfe_u32 v20, v19, 16, 1
	v_lshrrev_b32_e32 v0, 16, v0
	v_add3_u32 v19, v19, v20, s21
	v_and_or_b32 v20, v19, s35, v0
	v_bfe_u32 v0, v21, 16, 1
	v_add3_u32 v0, v21, v0, s21
	v_bfe_u32 v19, v22, 16, 1
	v_lshrrev_b32_e32 v0, 16, v0
	v_add3_u32 v19, v22, v19, s21
	v_and_or_b32 v21, v19, s35, v0
	v_bfe_u32 v0, v23, 16, 1
	v_add3_u32 v0, v23, v0, s21
	v_bfe_u32 v19, v24, 16, 1
	v_lshrrev_b32_e32 v0, 16, v0
	v_add3_u32 v19, v24, v19, s21
	v_and_or_b32 v22, v19, s35, v0
	v_bfe_u32 v0, v25, 16, 1
	v_add3_u32 v0, v25, v0, s21
	v_bfe_u32 v19, v26, 16, 1
	v_lshrrev_b32_e32 v0, 16, v0
	v_add3_u32 v19, v26, v19, s21
	v_and_or_b32 v23, v19, s35, v0
	v_or_b32_e32 v0, s6, v162
	v_lshlrev_b32_e32 v0, 11, v0
	v_lshl_add_u64 v[24:25], v[8:9], 0, v[0:1]
	global_store_dwordx4 v[24:25], v[20:23], off sc0 sc1
	ds_read_b32 v0, v11 offset:96
	ds_read_b32 v19, v11 offset:228
	ds_read_b32 v21, v11 offset:360
	ds_read_b32 v22, v11 offset:492
	ds_read_b32 v23, v11 offset:624
	ds_read_b32 v24, v11 offset:756
	ds_read_b32 v25, v11 offset:888
	ds_read_b32 v26, v11 offset:1020
	s_waitcnt lgkmcnt(0)
	v_bfe_u32 v20, v0, 16, 1
	v_add3_u32 v0, v0, v20, s21
	v_bfe_u32 v20, v19, 16, 1
	v_lshrrev_b32_e32 v0, 16, v0
	v_add3_u32 v19, v19, v20, s21
	v_and_or_b32 v20, v19, s35, v0
	v_bfe_u32 v0, v21, 16, 1
	v_add3_u32 v0, v21, v0, s21
	v_bfe_u32 v19, v22, 16, 1
	v_lshrrev_b32_e32 v0, 16, v0
	v_add3_u32 v19, v22, v19, s21
	v_and_or_b32 v21, v19, s35, v0
	v_bfe_u32 v0, v23, 16, 1
	v_add3_u32 v0, v23, v0, s21
	v_bfe_u32 v19, v24, 16, 1
	v_lshrrev_b32_e32 v0, 16, v0
	v_add3_u32 v19, v24, v19, s21
	v_and_or_b32 v22, v19, s35, v0
	v_bfe_u32 v0, v25, 16, 1
	v_add3_u32 v0, v25, v0, s21
	v_bfe_u32 v19, v26, 16, 1
	v_lshrrev_b32_e32 v0, 16, v0
	v_add3_u32 v19, v26, v19, s21
	v_and_or_b32 v23, v19, s35, v0
	v_or_b32_e32 v0, s6, v163
	v_lshlrev_b32_e32 v0, 11, v0
	v_lshl_add_u64 v[8:9], v[8:9], 0, v[0:1]
	global_store_dwordx4 v[8:9], v[20:23], off sc0 sc1
	s_waitcnt lgkmcnt(0)

; #define LAS __attribute__((address_space(3)))
; #define LDS_WAIT() asm volatile("s_waitcnt lgkmcnt(0)" ::: "memory")
; #define TR_TRY(CNT, NBLK, ...) if (r < (CNT)) { const int k0 = 64 * (r / (NBLK)), n0 = 32 * (r % (NBLK)); (void)k0; (void)n0; __VA_ARGS__; continue; } r -= (CNT);
; #define TR_TRY(CNT, NBLK, ...) if (r < (CNT)) { const int k0 = 64 * (r / (NBLK)), n0 = 32 * (r % (NBLK)); (void)k0; (void)n0; __VA_ARGS__; continue; } r -= (CNT);
; __device__ __forceinline__ void tr_item(const float* W, int N, int k0, int n0, bf16* WT, int Kd, int drow0, int dk0, LAS float* scr, int lane) {
;     {
;         float wv[32]; const int n = n0 + (lane & 31); const float* wp = W + (size_t)(k0 + (lane >> 5)) * N + n;
; #pragma unroll
;         for (int i = 0; i < 32; ++i) wv[i] = (n < N) ? wp[(size_t)(2 * i) * N] : 0.f;
; #pragma unroll
;         for (int i = 0; i < 32; ++i) scr[(2 * i + (lane >> 5)) * 33 + (lane & 31)] = wv[i];
;     }
;     LDS_WAIT();
; __global__ void __launch_bounds__(NTHREADS, 2) mega_fwd(Args a_unused) {
;     ...
;                 TR_TRY(I_GU, FF / 32, tr_item(ap->in[21], FF, k0, n0, Wgu2, D, (n0 / 128) * 256 + (n0 % 128), k0, scr, lane))
.LBB0_312:
	s_andn2_b64 vcc, exec, s[6:7]
	s_cbranch_vccnz .LBB0_301
	v_mov_b64_e32 v[8:9], s[8:9]
	global_load_dwordx2 v[8:9], v[8:9], off offset:168
	s_mul_hi_i32 s4, s12, 0x2e8ba2e9
	s_lshr_b32 s6, s4, 31
	s_ashr_i32 s7, s4, 4
	s_add_i32 s7, s7, s6
	s_mul_i32 s4, s7, 0xfffff500
	s_lshl_b32 s6, s7, 6
	s_add_i32 s4, s11, s4
	v_or_b32_e32 v0, s6, v159
	v_add_u32_e32 v20, s4, v158
	v_ashrrev_i32_e32 v21, 31, v20
	s_mulk_i32 s7, 0xffa8
	s_add_i32 s7, s12, s7
	s_bfe_i32 s65, s7, 0x80000
	s_bfe_u32 s65, s65, 0x2000d
	s_add_i32 s7, s7, s65
	s_bfe_u32 s65, s4, 0x70018
	s_bfe_i32 s7, s7, 0x80000
	s_add_i32 s65, s4, s65
	s_sext_i32_i16 s7, s7
	s_and_b32 s65, s65, 0xff80
	s_lshl_b32 s7, s7, 6
	s_sub_i32 s4, s4, s65
	s_and_b32 s7, s7, 0xffffff00
	s_sext_i32_i16 s4, s4
	s_add_i32 s4, s7, s4
	s_ashr_i32 s7, s6, 31
	s_waitcnt vmcnt(0) lgkmcnt(0)
	v_mad_i64_i32 v[8:9], s[66:67], v0, s64, v[8:9]
	v_lshl_add_u64 v[8:9], v[20:21], 2, v[8:9]
	v_add_co_u32_e32 v20, vcc, s38, v8
	s_nop 1
	v_addc_co_u32_e32 v21, vcc, 0, v9, vcc
	v_add_co_u32_e32 v22, vcc, s39, v8
	s_nop 1
	v_addc_co_u32_e32 v23, vcc, 0, v9, vcc
	v_add_co_u32_e32 v24, vcc, s16, v8
	s_nop 1
	v_addc_co_u32_e32 v25, vcc, 0, v9, vcc
	v_add_co_u32_e32 v26, vcc, s17, v8
	s_nop 1
	v_addc_co_u32_e32 v27, vcc, 0, v9, vcc
	v_add_co_u32_e32 v28, vcc, s40, v8
	s_nop 1
	v_addc_co_u32_e32 v29, vcc, 0, v9, vcc
	v_add_co_u32_e32 v30, vcc, s41, v8
	s_nop 1
	v_addc_co_u32_e32 v31, vcc, 0, v9, vcc
	v_add_co_u32_e32 v32, vcc, s18, v8
	s_nop 1
	v_addc_co_u32_e32 v33, vcc, 0, v9, vcc
	v_add_co_u32_e32 v34, vcc, s19, v8
	s_nop 1
	v_addc_co_u32_e32 v35, vcc, 0, v9, vcc
	v_add_co_u32_e32 v36, vcc, s42, v8
	s_nop 1
	v_addc_co_u32_e32 v37, vcc, 0, v9, vcc
	v_add_co_u32_e32 v38, vcc, s43, v8
	s_nop 1
	v_addc_co_u32_e32 v39, vcc, 0, v9, vcc
	v_add_co_u32_e32 v40, vcc, s20, v8
	s_nop 1
	v_addc_co_u32_e32 v41, vcc, 0, v9, vcc
	v_add_co_u32_e32 v42, vcc, s44, v8
	s_nop 1
	v_addc_co_u32_e32 v43, vcc, 0, v9, vcc
	v_add_co_u32_e32 v44, vcc, s45, v8
	s_nop 1
	v_addc_co_u32_e32 v45, vcc, 0, v9, vcc
	v_add_co_u32_e32 v46, vcc, s46, v8
	s_nop 1
	v_addc_co_u32_e32 v47, vcc, 0, v9, vcc
	v_add_co_u32_e32 v48, vcc, s47, v8
	s_nop 1
	v_addc_co_u32_e32 v49, vcc, 0, v9, vcc
	global_load_dword v0, v[8:9], off
	global_load_dword v19, v[20:21], off offset:2048
	global_load_dword v50, v[22:23], off
	global_load_dword v51, v[24:25], off offset:2048
	global_load_dword v52, v[26:27], off
	global_load_dword v53, v[28:29], off offset:2048
	global_load_dword v54, v[30:31], off
	global_load_dword v55, v[32:33], off offset:2048
	global_load_dword v56, v[34:35], off
	s_nop 0
	global_load_dword v36, v[36:37], off offset:2048
	s_nop 0
	global_load_dword v37, v[38:39], off
	s_nop 0
	global_load_dword v38, v[40:41], off offset:2048
	global_load_dword v39, v[42:43], off
	s_nop 0
	global_load_dword v40, v[44:45], off offset:2048
	global_load_dword v41, v[46:47], off
	global_load_dword v42, v[48:49], off offset:2048
	v_add_co_u32_e32 v20, vcc, s48, v8
	s_nop 1
	v_addc_co_u32_e32 v21, vcc, 0, v9, vcc
	v_add_co_u32_e32 v22, vcc, s49, v8
	s_nop 1
	v_addc_co_u32_e32 v23, vcc, 0, v9, vcc
	v_add_co_u32_e32 v24, vcc, s50, v8
	s_nop 1
	v_addc_co_u32_e32 v25, vcc, 0, v9, vcc
	v_add_co_u32_e32 v26, vcc, s51, v8
	s_nop 1
	v_addc_co_u32_e32 v27, vcc, 0, v9, vcc
	v_add_co_u32_e32 v28, vcc, s52, v8
	s_nop 1
	v_addc_co_u32_e32 v29, vcc, 0, v9, vcc
	v_add_co_u32_e32 v30, vcc, s53, v8
	s_nop 1
	v_addc_co_u32_e32 v31, vcc, 0, v9, vcc
	v_add_co_u32_e32 v32, vcc, s54, v8
	s_nop 1
	v_addc_co_u32_e32 v33, vcc, 0, v9, vcc
	v_add_co_u32_e32 v34, vcc, s55, v8
	s_nop 1
	v_addc_co_u32_e32 v35, vcc, 0, v9, vcc
	global_load_dword v43, v[20:21], off
	global_load_dword v44, v[22:23], off offset:2048
	global_load_dword v45, v[24:25], off
	global_load_dword v46, v[26:27], off offset:2048
	global_load_dword v47, v[28:29], off
	global_load_dword v48, v[30:31], off offset:2048
	global_load_dword v49, v[32:33], off
	s_nop 0
	global_load_dword v34, v[34:35], off offset:2048
	v_add_co_u32_e32 v20, vcc, s56, v8
	s_nop 1
	v_addc_co_u32_e32 v21, vcc, 0, v9, vcc
	v_add_co_u32_e32 v22, vcc, s57, v8
	s_nop 1
	v_addc_co_u32_e32 v23, vcc, 0, v9, vcc
	v_add_co_u32_e32 v24, vcc, s58, v8
	s_nop 1
	v_addc_co_u32_e32 v25, vcc, 0, v9, vcc
	v_add_co_u32_e32 v26, vcc, s59, v8
	s_nop 1
	v_addc_co_u32_e32 v27, vcc, 0, v9, vcc
	v_add_co_u32_e32 v28, vcc, s60, v8
	s_nop 1
	v_addc_co_u32_e32 v29, vcc, 0, v9, vcc
	v_add_co_u32_e32 v30, vcc, s61, v8
	s_nop 1
	v_addc_co_u32_e32 v31, vcc, 0, v9, vcc
	v_add_co_u32_e32 v32, vcc, s62, v8
	s_nop 1
	v_addc_co_u32_e32 v33, vcc, 0, v9, vcc
	v_add_co_u32_e32 v8, vcc, s63, v8
	s_nop 1
	v_addc_co_u32_e32 v9, vcc, 0, v9, vcc
	global_load_dword v20, v[20:21], off
	s_nop 0
	global_load_dword v21, v[22:23], off offset:2048
	s_nop 0
	global_load_dword v22, v[24:25], off
	global_load_dword v23, v[26:27], off offset:2048
	s_nop 0
	global_load_dword v24, v[28:29], off
	global_load_dword v25, v[30:31], off offset:2048
	global_load_dword v26, v[32:33], off
	s_nop 0
	global_load_dword v8, v[8:9], off offset:2048
	s_waitcnt vmcnt(0) lgkmcnt(0)
; #define LAS __attribute__((address_space(3)))
; #define LDS_WAIT() asm volatile("s_waitcnt lgkmcnt(0)" ::: "memory")
; __device__ __forceinline__ unsigned pk2(float lo, float hi) { return f2bf(lo) | (f2bf(hi) << 16); }
; __device__ __forceinline__ void tr_item(const float* W, int N, int k0, int n0, bf16* WT, int Kd, int drow0, int dk0, LAS float* scr, int lane) {
;     ...
;     const int c = lane & 7;
; #pragma unroll
;     for (int j = 0; j < 4; ++j) { const int n = (lane >> 3) + 8 * j; const LAS float* s = scr + (8 * c) * 33 + n;
;         v4u o; o.x = pk2(s[0 * 33], s[1 * 33]); o.y = pk2(s[2 * 33], s[3 * 33]); o.z = pk2(s[4 * 33], s[5 * 33]); o.w = pk2(s[6 * 33], s[7 * 33]);
;         *(v4u*)(WT + (size_t)(drow0 + n) * Kd + dk0 + 8 * c) = o; }
;     LDS_WAIT();
; __global__ void __launch_bounds__(NTHREADS, 2) mega_fwd(Args a_unused) {
;     ...
;             for (int it = hb * 8 + wave; it < NIT2; it += nh * 8) {
	ds_write2_b32 v10, v0, v19 offset1:66
	ds_write2_b32 v10, v50, v51 offset0:132 offset1:198
	ds_write2_b32 v12, v52, v53 offset0:8 offset1:74
	ds_write2_b32 v12, v54, v55 offset0:140 offset1:206
	ds_write2_b32 v13, v56, v36 offset0:16 offset1:82
	ds_write2_b32 v13, v37, v38 offset0:148 offset1:214
	ds_write2_b32 v14, v39, v40 offset0:24 offset1:90
	ds_write2_b32 v14, v41, v42 offset0:156 offset1:222
	ds_write2_b32 v15, v43, v44 offset0:32 offset1:98
	ds_write2_b32 v15, v45, v46 offset0:164 offset1:230
	ds_write2_b32 v16, v47, v48 offset0:40 offset1:106
	ds_write2_b32 v16, v49, v34 offset0:172 offset1:238
	ds_write2_b32 v17, v20, v21 offset0:48 offset1:114
	ds_write2_b32 v17, v22, v23 offset0:180 offset1:246
	ds_write2_b32 v18, v24, v25 offset0:56 offset1:122
	ds_write2_b32 v18, v26, v8 offset0:188 offset1:254
	s_waitcnt lgkmcnt(0)
	ds_read_b32 v0, v11
	ds_read_b32 v19, v11 offset:132
	ds_read_b32 v21, v11 offset:264
	ds_read_b32 v22, v11 offset:396
	ds_read_b32 v23, v11 offset:528
	ds_read_b32 v24, v11 offset:660
	ds_read_b32 v25, v11 offset:792
	ds_read_b32 v26, v11 offset:924
	s_waitcnt lgkmcnt(7)
	v_bfe_u32 v20, v0, 16, 1
	v_add3_u32 v0, v0, v20, s21
	s_waitcnt lgkmcnt(6)
	v_bfe_u32 v20, v19, 16, 1
	v_lshrrev_b32_e32 v0, 16, v0
	v_add3_u32 v19, v19, v20, s21
	v_and_or_b32 v20, v19, s35, v0
	s_waitcnt lgkmcnt(5)
	v_bfe_u32 v0, v21, 16, 1
	v_add3_u32 v0, v21, v0, s21
	s_waitcnt lgkmcnt(4)
	v_bfe_u32 v19, v22, 16, 1
	v_lshrrev_b32_e32 v0, 16, v0
	v_add3_u32 v19, v22, v19, s21
	v_and_or_b32 v21, v19, s35, v0
	s_waitcnt lgkmcnt(3)
	v_bfe_u32 v0, v23, 16, 1
	v_add3_u32 v0, v23, v0, s21
	s_waitcnt lgkmcnt(2)
	v_bfe_u32 v19, v24, 16, 1
	v_lshrrev_b32_e32 v0, 16, v0
	v_add3_u32 v19, v24, v19, s21
	v_and_or_b32 v22, v19, s35, v0
	s_waitcnt lgkmcnt(1)
	v_bfe_u32 v0, v25, 16, 1
	v_or_b32_e32 v24, s4, v160
	v_add3_u32 v0, v25, v0, s21
	s_waitcnt lgkmcnt(0)
	v_bfe_u32 v19, v26, 16, 1
	v_ashrrev_i32_e32 v25, 31, v24
	v_lshl_add_u64 v[8:9], s[6:7], 1, v[6:7]
	v_lshrrev_b32_e32 v0, 16, v0
	v_add3_u32 v19, v26, v19, s21
	v_lshlrev_b64 v[24:25], 11, v[24:25]
	v_and_or_b32 v23, v19, s35, v0
	v_lshl_add_u64 v[24:25], v[8:9], 0, v[24:25]
	global_store_dwordx4 v[24:25], v[20:23], off sc0 sc1
	ds_read_b32 v0, v11 offset:32
	ds_read_b32 v19, v11 offset:164
	ds_read_b32 v21, v11 offset:296
	ds_read_b32 v22, v11 offset:428
	ds_read_b32 v23, v11 offset:560
	ds_read_b32 v24, v11 offset:692
	ds_read_b32 v25, v11 offset:824
	ds_read_b32 v26, v11 offset:956
	s_waitcnt lgkmcnt(0)
	v_bfe_u32 v20, v0, 16, 1
	v_add3_u32 v0, v0, v20, s21
	v_bfe_u32 v20, v19, 16, 1
	v_lshrrev_b32_e32 v0, 16, v0
	v_add3_u32 v19, v19, v20, s21
	v_and_or_b32 v20, v19, s35, v0
	v_bfe_u32 v0, v21, 16, 1
	v_add3_u32 v0, v21, v0, s21
	v_bfe_u32 v19, v22, 16, 1
	v_lshrrev_b32_e32 v0, 16, v0
	v_add3_u32 v19, v22, v19, s21
	v_and_or_b32 v21, v19, s35, v0
	v_bfe_u32 v0, v23, 16, 1
	v_add3_u32 v0, v23, v0, s21
	v_bfe_u32 v19, v24, 16, 1
	v_lshrrev_b32_e32 v0, 16, v0
	v_add3_u32 v19, v24, v19, s21
	v_and_or_b32 v22, v19, s35, v0
	v_bfe_u32 v0, v25, 16, 1
	v_or_b32_e32 v24, s4, v161
	v_add3_u32 v0, v25, v0, s21
	v_bfe_u32 v19, v26, 16, 1
	v_ashrrev_i32_e32 v25, 31, v24
	v_lshrrev_b32_e32 v0, 16, v0
	v_add3_u32 v19, v26, v19, s21
	v_lshlrev_b64 v[24:25], 11, v[24:25]
	v_and_or_b32 v23, v19, s35, v0
	v_lshl_add_u64 v[24:25], v[8:9], 0, v[24:25]
	global_store_dwordx4 v[24:25], v[20:23], off sc0 sc1
	ds_read_b32 v0, v11 offset:64
	ds_read_b32 v19, v11 offset:196
	ds_read_b32 v21, v11 offset:328
	ds_read_b32 v22, v11 offset:460
	ds_read_b32 v23, v11 offset:592
	ds_read_b32 v24, v11 offset:724
	ds_read_b32 v25, v11 offset:856
	ds_read_b32 v26, v11 offset:988
	s_waitcnt lgkmcnt(0)
	v_bfe_u32 v20, v0, 16, 1
	v_add3_u32 v0, v0, v20, s21
	v_bfe_u32 v20, v19, 16, 1
	v_lshrrev_b32_e32 v0, 16, v0
	v_add3_u32 v19, v19, v20, s21
	v_and_or_b32 v20, v19, s35, v0
	v_bfe_u32 v0, v21, 16, 1
	v_add3_u32 v0, v21, v0, s21
	v_bfe_u32 v19, v22, 16, 1
	v_lshrrev_b32_e32 v0, 16, v0
	v_add3_u32 v19, v22, v19, s21
	v_and_or_b32 v21, v19, s35, v0
	v_bfe_u32 v0, v23, 16, 1
	v_add3_u32 v0, v23, v0, s21
	v_bfe_u32 v19, v24, 16, 1
	v_lshrrev_b32_e32 v0, 16, v0
	v_add3_u32 v19, v24, v19, s21
	v_and_or_b32 v22, v19, s35, v0
	v_bfe_u32 v0, v25, 16, 1
	v_or_b32_e32 v24, s4, v162
	v_add3_u32 v0, v25, v0, s21
	v_bfe_u32 v19, v26, 16, 1
	v_ashrrev_i32_e32 v25, 31, v24
	v_lshrrev_b32_e32 v0, 16, v0
	v_add3_u32 v19, v26, v19, s21
	v_lshlrev_b64 v[24:25], 11, v[24:25]
	v_and_or_b32 v23, v19, s35, v0
	v_lshl_add_u64 v[24:25], v[8:9], 0, v[24:25]
	global_store_dwordx4 v[24:25], v[20:23], off sc0 sc1
	ds_read_b32 v0, v11 offset:96
	ds_read_b32 v19, v11 offset:228
	ds_read_b32 v21, v11 offset:360
	ds_read_b32 v22, v11 offset:492
	ds_read_b32 v23, v11 offset:624
	ds_read_b32 v24, v11 offset:756
	ds_read_b32 v25, v11 offset:888
	ds_read_b32 v26, v11 offset:1020
	s_waitcnt lgkmcnt(0)
	v_bfe_u32 v20, v0, 16, 1
	v_add3_u32 v0, v0, v20, s21
	v_bfe_u32 v20, v19, 16, 1
	v_lshrrev_b32_e32 v0, 16, v0
	v_add3_u32 v19, v19, v20, s21
	v_and_or_b32 v20, v19, s35, v0
	v_bfe_u32 v0, v21, 16, 1
	v_add3_u32 v0, v21, v0, s21
	v_bfe_u32 v19, v22, 16, 1
	v_lshrrev_b32_e32 v0, 16, v0
	v_add3_u32 v19, v22, v19, s21
	v_and_or_b32 v21, v19, s35, v0
	v_bfe_u32 v0, v23, 16, 1
	v_add3_u32 v0, v23, v0, s21
	v_bfe_u32 v19, v24, 16, 1
	v_lshrrev_b32_e32 v0, 16, v0
	v_add3_u32 v19, v24, v19, s21
	v_and_or_b32 v22, v19, s35, v0
	v_bfe_u32 v0, v25, 16, 1
	v_or_b32_e32 v24, s4, v163
	v_add3_u32 v0, v25, v0, s21
	v_bfe_u32 v19, v26, 16, 1
	v_ashrrev_i32_e32 v25, 31, v24
	v_lshrrev_b32_e32 v0, 16, v0
	v_add3_u32 v19, v26, v19, s21
	v_lshlrev_b64 v[24:25], 11, v[24:25]
	v_and_or_b32 v23, v19, s35, v0
	v_lshl_add_u64 v[8:9], v[8:9], 0, v[24:25]
	global_store_dwordx4 v[8:9], v[20:23], off sc0 sc1
	s_waitcnt lgkmcnt(0)
	s_branch .LBB0_301

; template <class Epi, class Sched, bool ALIGN_EPI = false, bool SP2 = false>
; __device__ __forceinline__ void gemm_phase(PG8_LAS unsigned char* lds, const Gemm g, const Sched& S, const Epi& E) {
;     int tid_o = threadIdx.x; asm volatile("" : "+v"(tid_o));
;     const int tid = tid_o, wid = __builtin_amdgcn_readfirstlane(tid >> 6), lane = tid & 63, wr = wid >> 2, wc = wid & 3, fr = lane & 15, fq = lane >> 4;
;     const int K = g.K, nt = K / BK;
;     unsigned voffA[2], voffB[2];
; #pragma unroll
;     for (int i = 0; i < 2; ++i) { int R, C; stage_rc(tid * 16 + i * 8192, R, C); const int Rb = Epi::PERM ? ((R & ~31) + perm32(R & 31)) : R;
;         voffA[i] = (unsigned)(R * K + C) * 2u; voffB[i] = (unsigned)(Rb * K + C) * 2u; }
;     const size_t kstep = (size_t)(BK * 2);
;     const size_t hstep = (size_t)HALF * K * 2;
;     const size_t tstep = 2 * hstep;
;     const unsigned ldsw = (unsigned)wid * 1024u;
;     const int aoff = lds_byte(wr * 64 + fr, fq * 8), boff = lds_byte(wc * 32 + fr, fq * 8);
;     ...
;     Unit cur, nxt; int ui = 0;
;     if (!S.next(0, cur)) return;
; __global__ void __launch_bounds__(NTHREADS, 2) mega_fwd(Args a_unused) {
;     ...
;     { int Kq = FF; asm volatile("" : "+s"(Kq)); pg8::Gemm g{HFF, Wd1, M, D, Kq}; pg8::StaticOrder S; S.init(M, D, G, bx); pg8::EpiResidLn<true> E{XIN, XOUT, mod + 2 * D, 0.5f, ap->in[4] + 0 * D, ap->in[5] + 0 * D, mod + 3 * D, mod + 4 * D, U, {(unsigned*)(ws + WS_XCH), (unsigned*)(ws + WS_CTL) + (16384 * 0 + 16384) / 4, (unsigned*)(ws + WS_CTL) + 15360 / 4, 4, LN_EPS, 0x700u}};
;       pg8::gemm_phase<pg8::EpiResidLn<true>, pg8::StaticOrder, false, true>(lds, g, S, E); }
.LBB0_366:
	s_or_b64 exec, exec, s[4:5]
	s_mov_b64 s[4:5], s[0:1]
	s_waitcnt lgkmcnt(0)
	s_barrier
	s_movk_i32 s6, 0xb00
	v_mov_b64_e32 v[4:5], s[4:5]
	global_load_dwordx2 v[0:1], v[4:5], off offset:200
	v_mov_b32_e32 v149, v144
	s_andn2_b64 vcc, exec, s[36:37]
	s_waitcnt vmcnt(0) lgkmcnt(0)
	v_readfirstlane_b32 s13, v1
	v_readfirstlane_b32 s12, v0
	global_load_dwordx2 v[152:153], v[4:5], off offset:192
	global_load_dwordx2 v[138:139], v[4:5], off
	global_load_dwordx4 v[0:3], v[4:5], off offset:32
	v_cndmask_b32_e64 v4, 0, 1, s[36:37]
	v_cmp_ne_u32_e64 s[4:5], 1, v4
	v_readfirstlane_b32 s35, v149
	s_cbranch_vccnz .LBB0_432
	s_ashr_i32 s20, s2, 31
	s_lshr_b32 s7, s20, 29
	s_add_i32 s7, s2, s7
	s_and_b32 s8, s7, -8
	s_sub_i32 s11, s2, s8
	s_cmp_gt_i32 s11, -1
	s_cbranch_scc0 .LBB0_369
	s_lshl_b32 s10, s11, 5
	s_cbranch_execz .LBB0_370
	s_branch .LBB0_371

; #define PG8_LAS __attribute__((address_space(3)))
;     __device__ __forceinline__ void fused(f32x4 (&acc)[2][2][4][2], const Unit& u, int wr, int wc, int fr, int fq, PG8_LAS unsigned char* lds, int wid, int lane) const {
;         typedef float f32x2v __attribute__((ext_vector_type(2))); typedef unsigned u32x2v __attribute__((ext_vector_type(2)));
;         const PG8_LAS f32x2v* S = (const PG8_LAS f32x2v*)(lds + 8192);
;         const int col0 = u.pn * BM + wc * 32 + 4 * fq; const int b = (u.pm * BM) >> 13; const size_t mo = (size_t)b * 9216;
; #pragma unroll
;         for (int bj = 0; bj < 2; ++bj)
; #pragma unroll
;             for (int n = 0; n < 2; ++n) { const f32x4 gv = (*(const f32x4*)(gate + mo + col0 + bj * HALF + n * 16) + 1.0f) * coef;
; #pragma unroll
;                 for (int ai = 0; ai < 2; ++ai)
; #pragma unroll
;                     for (int m = 0; m < 4; ++m) acc[ai][bj][m][n] = acc[ai][bj][m][n] * gv; }
; #pragma unroll
;         for (int ai = 0; ai < 2; ++ai)
; #pragma unroll
;             for (int m = 0; m < 4; ++m) { const size_t off = (size_t)(u.pm * BM + ai * HALF + wr * 64 + m * 16 + fr) * 1024 + col0;
; #pragma unroll
;                 for (int bj = 0; bj < 2; ++bj)
; #pragma unroll
;                     for (int n = 0; n < 2; ++n) { const f32x4 xv = *(const f32x4*)(xin + off + bj * HALF + n * 16); acc[ai][bj][m][n] = xv * ALPHA_ + acc[ai][bj][m][n]; }
;                 asm volatile("" : "+v"(acc[ai][0][m][0]), "+v"(acc[ai][0][m][1]), "+v"(acc[ai][1][m][0]), "+v"(acc[ai][1][m][1]));
;                 if (m & 1) asm volatile("" ::: "memory"); }
.LBB0_392:
	s_lshl_b32 s6, s21, 5
	s_lshl_b32 s7, s14, 8
	s_or_b32 s6, s7, s6
	v_lshrrev_b32_e32 v4, 2, v149
	v_and_or_b32 v154, v4, 12, s6
	s_ashr_i32 s6, s50, 5
	s_mul_hi_i32 s7, s6, 0x2400
	s_mulk_i32 s6, 0x2400
	s_lshl_b64 s[16:17], s[6:7], 2
	v_ashrrev_i32_e32 v155, 31, v154
	s_add_u32 s6, s12, s16
	s_addc_u32 s7, s13, s17
	v_lshlrev_b64 v[136:137], 2, v[154:155]
	v_lshl_add_u64 v[156:157], s[6:7], 0, v[136:137]
	s_mov_b64 s[6:7], 0x2000
	s_lshl_b32 s20, s50, 8
	v_lshl_add_u64 v[164:165], v[156:157], 0, s[6:7]
	s_add_i32 s6, s20, s60
	v_or_b32_e32 v172, s6, v151
	s_movk_i32 s8, 0x2000
	v_ashrrev_i32_e32 v173, 31, v172
	v_add_co_u32_e32 v4, vcc, s8, v156
	v_lshlrev_b64 v[168:169], 12, v[172:173]
	s_nop 0
	v_addc_co_u32_e32 v5, vcc, 0, v157, vcc
	s_waitcnt vmcnt(0) lgkmcnt(0)
	v_lshl_add_u64 v[168:169], v[138:139], 0, v[168:169]
	s_barrier
	global_load_dwordx4 v[4:7], v[4:5], off
	s_nop 0
	global_load_dwordx4 v[156:159], v[164:165], off offset:64
	global_load_dwordx4 v[160:163], v[164:165], off offset:512
	s_nop 0
	global_load_dwordx4 v[164:167], v[164:165], off offset:576
	v_lshl_add_u64 v[168:169], v[168:169], 0, v[136:137]
	global_load_dwordx4 v[174:177], v[168:169], off
	global_load_dwordx4 v[182:185], v[168:169], off offset:64
	global_load_dwordx4 v[186:189], v[168:169], off offset:512
	global_load_dwordx4 v[190:193], v[168:169], off offset:576
	v_or_b32_e32 v168, 16, v172
	v_ashrrev_i32_e32 v169, 31, v168
	v_lshlrev_b64 v[168:169], 12, v[168:169]
	v_lshl_add_u64 v[168:169], v[138:139], 0, v[168:169]
	s_mov_b32 s6, 0x3f9837f0
	v_lshl_add_u64 v[194:195], v[168:169], 0, v[136:137]
	s_waitcnt vmcnt(0) lgkmcnt(0)
	v_pk_add_f32 v[168:169], v[158:159], 1.0 op_sel_hi:[1,0]
	v_pk_add_f32 v[6:7], v[6:7], 1.0 op_sel_hi:[1,0]
	v_pk_add_f32 v[4:5], v[4:5], 1.0 op_sel_hi:[1,0]
	v_pk_add_f32 v[170:171], v[156:157], 1.0 op_sel_hi:[1,0]
	v_pk_add_f32 v[196:197], v[162:163], 1.0 op_sel_hi:[1,0]
	v_pk_add_f32 v[198:199], v[160:161], 1.0 op_sel_hi:[1,0]
	v_pk_add_f32 v[200:201], v[166:167], 1.0 op_sel_hi:[1,0]
	v_pk_add_f32 v[202:203], v[164:165], 1.0 op_sel_hi:[1,0]
	v_pk_mul_f32 v[156:157], v[6:7], 0.5 op_sel_hi:[1,0]
	v_pk_mul_f32 v[158:159], v[4:5], 0.5 op_sel_hi:[1,0]
	v_pk_mul_f32 v[160:161], v[168:169], 0.5 op_sel_hi:[1,0]
	v_pk_mul_f32 v[162:163], v[170:171], 0.5 op_sel_hi:[1,0]
	v_pk_mul_f32 v[164:165], v[196:197], 0.5 op_sel_hi:[1,0]
	v_pk_mul_f32 v[166:167], v[198:199], 0.5 op_sel_hi:[1,0]
	v_pk_mul_f32 v[168:169], v[200:201], 0.5 op_sel_hi:[1,0]
	v_pk_mul_f32 v[170:171], v[202:203], 0.5 op_sel_hi:[1,0]
	v_pk_mul_f32 v[4:5], v[176:177], s[6:7] op_sel_hi:[1,0]
	v_pk_mul_f32 v[6:7], v[174:175], s[6:7] op_sel_hi:[1,0]
	v_pk_mul_f32 v[174:175], v[184:185], s[6:7] op_sel_hi:[1,0]
	v_pk_mul_f32 v[176:177], v[182:183], s[6:7] op_sel_hi:[1,0]
	v_pk_mul_f32 v[182:183], v[188:189], s[6:7] op_sel_hi:[1,0]
	v_pk_mul_f32 v[184:185], v[186:187], s[6:7] op_sel_hi:[1,0]
	v_pk_mul_f32 v[186:187], v[192:193], s[6:7] op_sel_hi:[1,0]
	v_pk_mul_f32 v[188:189], v[190:191], s[6:7] op_sel_hi:[1,0]
	v_pk_fma_f32 v[94:95], v[94:95], v[156:157], v[4:5]
	v_pk_fma_f32 v[92:93], v[92:93], v[158:159], v[6:7]
	v_pk_fma_f32 v[62:63], v[62:63], v[160:161], v[174:175]
	v_pk_fma_f32 v[60:61], v[60:61], v[162:163], v[176:177]
	v_pk_fma_f32 v[30:31], v[30:31], v[164:165], v[182:183]
	v_pk_fma_f32 v[28:29], v[28:29], v[166:167], v[184:185]
	v_pk_fma_f32 v[6:7], v[134:135], v[168:169], v[186:187]
	v_pk_fma_f32 v[4:5], v[132:133], v[170:171], v[188:189]
	v_or_b32_e32 v190, 32, v172
	global_load_dwordx4 v[132:135], v[194:195], off
	global_load_dwordx4 v[174:177], v[194:195], off offset:64
	global_load_dwordx4 v[182:185], v[194:195], off offset:512
	global_load_dwordx4 v[186:189], v[194:195], off offset:576
	v_ashrrev_i32_e32 v191, 31, v190
	v_lshlrev_b64 v[190:191], 12, v[190:191]
	v_lshl_add_u64 v[190:191], v[138:139], 0, v[190:191]
	v_lshl_add_u64 v[190:191], v[190:191], 0, v[136:137]
	v_mov_b32_e32 v194, v92
	v_mov_b32_e32 v195, v95
	v_mov_b32_e32 v196, v61
	v_mov_b32_e32 v197, v62
	v_add_f32_e32 v199, v30, v31
	v_mov_b32_e32 v198, v5
	v_mov_b32_e32 v200, v7
	s_waitcnt vmcnt(0) lgkmcnt(0)
	v_pk_mul_f32 v[134:135], v[134:135], s[6:7] op_sel_hi:[1,0]
	v_pk_mul_f32 v[132:133], v[132:133], s[6:7] op_sel_hi:[1,0]
	v_pk_mul_f32 v[176:177], v[176:177], s[6:7] op_sel_hi:[1,0]
	v_pk_mul_f32 v[174:175], v[174:175], s[6:7] op_sel_hi:[1,0]
	v_pk_mul_f32 v[184:185], v[184:185], s[6:7] op_sel_hi:[1,0]
	v_pk_mul_f32 v[182:183], v[182:183], s[6:7] op_sel_hi:[1,0]
	v_pk_mul_f32 v[188:189], v[188:189], s[6:7] op_sel_hi:[1,0]
	v_pk_mul_f32 v[186:187], v[186:187], s[6:7] op_sel_hi:[1,0]
	v_pk_fma_f32 v[102:103], v[102:103], v[156:157], v[134:135]
	v_pk_fma_f32 v[100:101], v[100:101], v[158:159], v[132:133]
	v_pk_fma_f32 v[70:71], v[70:71], v[160:161], v[176:177]
	v_pk_fma_f32 v[68:69], v[68:69], v[162:163], v[174:175]
	v_pk_fma_f32 v[38:39], v[38:39], v[164:165], v[184:185]
	v_pk_fma_f32 v[36:37], v[36:37], v[166:167], v[182:183]
	v_pk_fma_f32 v[10:11], v[10:11], v[168:169], v[188:189]
	v_pk_fma_f32 v[8:9], v[8:9], v[170:171], v[186:187]
	s_nop 0
	global_load_dwordx4 v[132:135], v[190:191], off
	global_load_dwordx4 v[174:177], v[190:191], off offset:64
	global_load_dwordx4 v[182:185], v[190:191], off offset:512
	global_load_dwordx4 v[186:189], v[190:191], off offset:576
	v_or_b32_e32 v190, 48, v172
	v_ashrrev_i32_e32 v191, 31, v190
	v_lshlrev_b64 v[190:191], 12, v[190:191]
	v_lshl_add_u64 v[190:191], v[138:139], 0, v[190:191]
	v_lshl_add_u64 v[190:191], v[190:191], 0, v[136:137]
	s_waitcnt vmcnt(0) lgkmcnt(0)
; #define PG8_LAS __attribute__((address_space(3)))
;     __device__ __forceinline__ bool run(const f32x4 (&v)[2][2][4][2], const Unit& u, int wr, int wc, int fr, int fq, PG8_LAS unsigned char* lds, int wid, int lane) const {
;     ...
;                 float s = 0.f;
; #pragma unroll
;                 for (int bj = 0; bj < 2; ++bj)
; #pragma unroll
;                     for (int n = 0; n < 2; ++n) { const f32x4 x = v[ai][bj][m][n]; s += (x[0] + x[1]) + (x[2] + x[3]); }
;                 s += __shfl_xor(s, 16); s += __shfl_xor(s, 32);
;     __device__ __forceinline__ void fused(f32x4 (&acc)[2][2][4][2], const Unit& u, int wr, int wc, int fr, int fq, PG8_LAS unsigned char* lds, int wid, int lane) const {
;         typedef float f32x2v __attribute__((ext_vector_type(2))); typedef unsigned u32x2v __attribute__((ext_vector_type(2)));
;         const PG8_LAS f32x2v* S = (const PG8_LAS f32x2v*)(lds + 8192);
;         const int col0 = u.pn * BM + wc * 32 + 4 * fq; const int b = (u.pm * BM) >> 13; const size_t mo = (size_t)b * 9216;
; #pragma unroll
;         for (int bj = 0; bj < 2; ++bj)
; #pragma unroll
;             for (int n = 0; n < 2; ++n) { const f32x4 gv = (*(const f32x4*)(gate + mo + col0 + bj * HALF + n * 16) + 1.0f) * coef;
; #pragma unroll
;                 for (int ai = 0; ai < 2; ++ai)
; #pragma unroll
;                     for (int m = 0; m < 4; ++m) acc[ai][bj][m][n] = acc[ai][bj][m][n] * gv; }
; #pragma unroll
;         for (int ai = 0; ai < 2; ++ai)
; #pragma unroll
;             for (int m = 0; m < 4; ++m) { const size_t off = (size_t)(u.pm * BM + ai * HALF + wr * 64 + m * 16 + fr) * 1024 + col0;
; #pragma unroll
;                 for (int bj = 0; bj < 2; ++bj)
; #pragma unroll
;                     for (int n = 0; n < 2; ++n) { const f32x4 xv = *(const f32x4*)(xin + off + bj * HALF + n * 16); acc[ai][bj][m][n] = xv * ALPHA_ + acc[ai][bj][m][n]; }
;                 asm volatile("" : "+v"(acc[ai][0][m][0]), "+v"(acc[ai][0][m][1]), "+v"(acc[ai][1][m][0]), "+v"(acc[ai][1][m][1]));
;                 if (m & 1) asm volatile("" ::: "memory"); }
	v_pk_mul_f32 v[134:135], v[134:135], s[6:7] op_sel_hi:[1,0]
	v_pk_mul_f32 v[132:133], v[132:133], s[6:7] op_sel_hi:[1,0]
	v_pk_mul_f32 v[176:177], v[176:177], s[6:7] op_sel_hi:[1,0]
	v_pk_mul_f32 v[174:175], v[174:175], s[6:7] op_sel_hi:[1,0]
	v_pk_mul_f32 v[184:185], v[184:185], s[6:7] op_sel_hi:[1,0]
	v_pk_mul_f32 v[182:183], v[182:183], s[6:7] op_sel_hi:[1,0]
	v_pk_mul_f32 v[188:189], v[188:189], s[6:7] op_sel_hi:[1,0]
	v_pk_mul_f32 v[186:187], v[186:187], s[6:7] op_sel_hi:[1,0]
	v_pk_fma_f32 v[110:111], v[110:111], v[156:157], v[134:135]
	v_pk_fma_f32 v[108:109], v[108:109], v[158:159], v[132:133]
	v_pk_fma_f32 v[74:75], v[74:75], v[160:161], v[176:177]
	v_pk_fma_f32 v[72:73], v[72:73], v[162:163], v[174:175]
	v_pk_fma_f32 v[42:43], v[42:43], v[164:165], v[184:185]
	v_pk_fma_f32 v[40:41], v[40:41], v[166:167], v[182:183]
	v_pk_fma_f32 v[14:15], v[14:15], v[168:169], v[188:189]
	v_pk_fma_f32 v[12:13], v[12:13], v[170:171], v[186:187]
	s_nop 0
	global_load_dwordx4 v[132:135], v[190:191], off
	global_load_dwordx4 v[174:177], v[190:191], off offset:64
	global_load_dwordx4 v[182:185], v[190:191], off offset:512
	global_load_dwordx4 v[186:189], v[190:191], off offset:576
	v_add_u32_e32 v190, 0x80, v172
	v_ashrrev_i32_e32 v191, 31, v190
	v_lshlrev_b64 v[190:191], 12, v[190:191]
	v_lshl_add_u64 v[190:191], v[138:139], 0, v[190:191]
	v_lshl_add_u64 v[190:191], v[190:191], 0, v[136:137]
	s_waitcnt vmcnt(0) lgkmcnt(0)
	v_pk_mul_f32 v[134:135], v[134:135], s[6:7] op_sel_hi:[1,0]
	v_pk_mul_f32 v[132:133], v[132:133], s[6:7] op_sel_hi:[1,0]
	v_pk_mul_f32 v[176:177], v[176:177], s[6:7] op_sel_hi:[1,0]
	v_pk_mul_f32 v[174:175], v[174:175], s[6:7] op_sel_hi:[1,0]
	v_pk_mul_f32 v[184:185], v[184:185], s[6:7] op_sel_hi:[1,0]
	v_pk_mul_f32 v[182:183], v[182:183], s[6:7] op_sel_hi:[1,0]
	v_pk_mul_f32 v[188:189], v[188:189], s[6:7] op_sel_hi:[1,0]
	v_pk_mul_f32 v[186:187], v[186:187], s[6:7] op_sel_hi:[1,0]
	v_pk_fma_f32 v[114:115], v[114:115], v[156:157], v[134:135]
	v_pk_fma_f32 v[112:113], v[112:113], v[158:159], v[132:133]
	v_pk_fma_f32 v[82:83], v[82:83], v[160:161], v[176:177]
	v_pk_fma_f32 v[80:81], v[80:81], v[162:163], v[174:175]
	v_pk_fma_f32 v[50:51], v[50:51], v[164:165], v[184:185]
	v_pk_fma_f32 v[48:49], v[48:49], v[166:167], v[182:183]
	v_pk_fma_f32 v[18:19], v[18:19], v[168:169], v[188:189]
	v_pk_fma_f32 v[16:17], v[16:17], v[170:171], v[186:187]
	s_nop 0
	global_load_dwordx4 v[132:135], v[190:191], off
	global_load_dwordx4 v[174:177], v[190:191], off offset:64
	global_load_dwordx4 v[182:185], v[190:191], off offset:512
	global_load_dwordx4 v[186:189], v[190:191], off offset:576
	v_add_u32_e32 v190, 0x90, v172
	v_ashrrev_i32_e32 v191, 31, v190
	v_lshlrev_b64 v[190:191], 12, v[190:191]
	v_lshl_add_u64 v[190:191], v[138:139], 0, v[190:191]
	v_lshl_add_u64 v[190:191], v[190:191], 0, v[136:137]
	s_waitcnt vmcnt(0) lgkmcnt(0)
	v_pk_mul_f32 v[134:135], v[134:135], s[6:7] op_sel_hi:[1,0]
	v_pk_mul_f32 v[132:133], v[132:133], s[6:7] op_sel_hi:[1,0]
	v_pk_mul_f32 v[176:177], v[176:177], s[6:7] op_sel_hi:[1,0]
	v_pk_mul_f32 v[174:175], v[174:175], s[6:7] op_sel_hi:[1,0]
	v_pk_mul_f32 v[184:185], v[184:185], s[6:7] op_sel_hi:[1,0]
	v_pk_mul_f32 v[182:183], v[182:183], s[6:7] op_sel_hi:[1,0]
	v_pk_mul_f32 v[188:189], v[188:189], s[6:7] op_sel_hi:[1,0]
	v_pk_mul_f32 v[186:187], v[186:187], s[6:7] op_sel_hi:[1,0]
	v_pk_fma_f32 v[118:119], v[118:119], v[156:157], v[134:135]
	v_pk_fma_f32 v[116:117], v[116:117], v[158:159], v[132:133]
	v_pk_fma_f32 v[86:87], v[86:87], v[160:161], v[176:177]
	v_pk_fma_f32 v[84:85], v[84:85], v[162:163], v[174:175]
	v_pk_fma_f32 v[54:55], v[54:55], v[164:165], v[184:185]
	v_pk_fma_f32 v[52:53], v[52:53], v[166:167], v[182:183]
	v_pk_fma_f32 v[22:23], v[22:23], v[168:169], v[188:189]
	v_pk_fma_f32 v[20:21], v[20:21], v[170:171], v[186:187]
	s_nop 0
	global_load_dwordx4 v[132:135], v[190:191], off
	global_load_dwordx4 v[174:177], v[190:191], off offset:64
	global_load_dwordx4 v[182:185], v[190:191], off offset:512
	global_load_dwordx4 v[186:189], v[190:191], off offset:576
	v_add_u32_e32 v190, 0xa0, v172
	v_ashrrev_i32_e32 v191, 31, v190
	v_lshlrev_b64 v[190:191], 12, v[190:191]
	v_lshl_add_u64 v[190:191], v[138:139], 0, v[190:191]
	v_lshl_add_u64 v[190:191], v[190:191], 0, v[136:137]
	s_waitcnt vmcnt(0) lgkmcnt(0)
	v_pk_mul_f32 v[134:135], v[134:135], s[6:7] op_sel_hi:[1,0]
	v_pk_mul_f32 v[132:133], v[132:133], s[6:7] op_sel_hi:[1,0]
	v_pk_mul_f32 v[176:177], v[176:177], s[6:7] op_sel_hi:[1,0]
	v_pk_mul_f32 v[174:175], v[174:175], s[6:7] op_sel_hi:[1,0]
	v_pk_mul_f32 v[184:185], v[184:185], s[6:7] op_sel_hi:[1,0]
	v_pk_mul_f32 v[182:183], v[182:183], s[6:7] op_sel_hi:[1,0]
	v_pk_mul_f32 v[188:189], v[188:189], s[6:7] op_sel_hi:[1,0]
	v_pk_mul_f32 v[186:187], v[186:187], s[6:7] op_sel_hi:[1,0]
	v_pk_fma_f32 v[122:123], v[122:123], v[156:157], v[134:135]
	v_pk_fma_f32 v[120:121], v[120:121], v[158:159], v[132:133]
	v_pk_fma_f32 v[90:91], v[90:91], v[160:161], v[176:177]
	v_pk_fma_f32 v[88:89], v[88:89], v[162:163], v[174:175]
	v_pk_fma_f32 v[58:59], v[58:59], v[164:165], v[184:185]
	v_pk_fma_f32 v[56:57], v[56:57], v[166:167], v[182:183]
	v_pk_fma_f32 v[26:27], v[26:27], v[168:169], v[188:189]
	v_pk_fma_f32 v[24:25], v[24:25], v[170:171], v[186:187]
	v_mbcnt_hi_u32_b32 v133, -1, v145
	global_load_dwordx4 v[174:177], v[190:191], off
	global_load_dwordx4 v[182:185], v[190:191], off offset:64
	global_load_dwordx4 v[186:189], v[190:191], off offset:512
	s_nop 0
	global_load_dwordx4 v[190:193], v[190:191], off offset:576
	v_and_b32_e32 v134, 64, v133
	v_add_u32_e32 v181, 64, v134
	v_add_u32_e32 v134, 0xb0, v172
	v_ashrrev_i32_e32 v135, 31, v134
	v_lshlrev_b64 v[134:135], 12, v[134:135]
	v_lshl_add_u64 v[134:135], v[138:139], 0, v[134:135]
	v_lshl_add_u64 v[134:135], v[134:135], 0, v[136:137]
	v_mov_b32_e32 v138, v93
	v_mov_b32_e32 v139, v94
	v_pk_add_f32 v[138:139], v[138:139], v[194:195]
	v_xor_b32_e32 v132, 16, v133
	v_add_f32_e32 v194, v138, v139
	v_add_f32_e32 v201, 0, v194
	v_cmp_lt_i32_e32 vcc, v132, v181
	s_waitcnt vmcnt(0) lgkmcnt(0)
;     __device__ __forceinline__ bool run(const f32x4 (&v)[2][2][4][2], const Unit& u, int wr, int wc, int fr, int fq, PG8_LAS unsigned char* lds, int wid, int lane) const {
;     ...
;                 float s = 0.f;
; #pragma unroll
;                 for (int bj = 0; bj < 2; ++bj)
; #pragma unroll
;                     for (int n = 0; n < 2; ++n) { const f32x4 x = v[ai][bj][m][n]; s += (x[0] + x[1]) + (x[2] + x[3]); }
;                 s += __shfl_xor(s, 16); s += __shfl_xor(s, 32);
;                 const float mw = s * (1.0f / 64.0f); float q = 0.f;
; #pragma unroll
;                 for (int bj = 0; bj < 2; ++bj)
; #pragma unroll
;                     for (int n = 0; n < 2; ++n) { const f32x4 d = v[ai][bj][m][n] - mw; q += (d[0] * d[0] + d[1] * d[1]) + (d[2] * d[2] + d[3] * d[3]); }
;                 q += __shfl_xor(q, 16); q += __shfl_xor(q, 32);
;                 if (fq == 0) P[(ai * HALF + wr * 64 + m * 16 + fr) * 4 + wc] = (f32x2v){mw, q};
;     __device__ __forceinline__ void fused(f32x4 (&acc)[2][2][4][2], const Unit& u, int wr, int wc, int fr, int fq, PG8_LAS unsigned char* lds, int wid, int lane) const {
;     ...
;                     for (int n = 0; n < 2; ++n) { const f32x4 xv = *(const f32x4*)(xin + off + bj * HALF + n * 16); acc[ai][bj][m][n] = xv * ALPHA_ + acc[ai][bj][m][n]; }
	v_pk_mul_f32 v[172:173], v[176:177], s[6:7] op_sel_hi:[1,0]
	v_pk_mul_f32 v[174:175], v[174:175], s[6:7] op_sel_hi:[1,0]
	v_pk_mul_f32 v[176:177], v[184:185], s[6:7] op_sel_hi:[1,0]
	v_pk_mul_f32 v[182:183], v[182:183], s[6:7] op_sel_hi:[1,0]
	v_pk_mul_f32 v[184:185], v[188:189], s[6:7] op_sel_hi:[1,0]
	v_pk_mul_f32 v[186:187], v[186:187], s[6:7] op_sel_hi:[1,0]
	v_pk_mul_f32 v[188:189], v[192:193], s[6:7] op_sel_hi:[1,0]
	v_pk_mul_f32 v[190:191], v[190:191], s[6:7] op_sel_hi:[1,0]
	v_pk_fma_f32 v[130:131], v[130:131], v[156:157], v[172:173]
	v_pk_fma_f32 v[128:129], v[128:129], v[158:159], v[174:175]
	v_pk_fma_f32 v[98:99], v[98:99], v[160:161], v[176:177]
	v_pk_fma_f32 v[96:97], v[96:97], v[162:163], v[182:183]
	v_pk_fma_f32 v[66:67], v[66:67], v[164:165], v[184:185]
	v_pk_fma_f32 v[64:65], v[64:65], v[166:167], v[186:187]
	v_pk_fma_f32 v[34:35], v[34:35], v[168:169], v[188:189]
	v_pk_fma_f32 v[32:33], v[32:33], v[170:171], v[190:191]
	v_mov_b32_e32 v176, v60
	global_load_dwordx4 v[172:175], v[134:135], off
	global_load_dwordx4 v[182:185], v[134:135], off offset:64
	global_load_dwordx4 v[186:189], v[134:135], off offset:512
	global_load_dwordx4 v[190:193], v[134:135], off offset:576
	v_mov_b32_e32 v177, v63
	v_pk_add_f32 v[176:177], v[196:197], v[176:177]
	v_add_f32_e32 v135, v28, v29
	v_pk_add_f32 v[138:139], v[176:177], v[176:177] op_sel_hi:[0,1]
	v_mov_b32_e32 v134, v4
	v_mov_b32_e32 v138, v6
	v_pk_add_f32 v[134:135], v[134:135], v[198:199]
	v_pk_add_f32 v[138:139], v[138:139], v[200:201]
	v_cndmask_b32_e32 v132, v133, v132, vcc
	v_pk_add_f32 v[134:135], v[134:135], v[138:139]
	v_lshlrev_b32_e32 v132, 2, v132
	v_add_f32_e32 v134, v134, v135
	ds_bpermute_b32 v135, v132, v134
	v_xor_b32_e32 v138, 32, v133
	v_cmp_lt_i32_e32 vcc, v138, v181
	s_waitcnt lgkmcnt(0)
	v_add_f32_e32 v134, v134, v135
	v_cndmask_b32_e32 v133, v133, v138, vcc
	v_lshlrev_b32_e32 v133, 2, v133
	ds_bpermute_b32 v135, v133, v134
	s_waitcnt lgkmcnt(0)
	v_add_f32_e32 v135, v134, v135
	v_fmamk_f32 v138, v135, 0xbc800000, v95
	v_fmamk_f32 v176, v135, 0xbc800000, v93
	v_fmamk_f32 v181, v135, 0xbc800000, v63
	v_fmamk_f32 v195, v135, 0xbc800000, v61
	v_fmamk_f32 v134, v135, 0xbc800000, v94
	v_fmamk_f32 v139, v135, 0xbc800000, v92
	v_fmamk_f32 v177, v135, 0xbc800000, v62
	v_fmamk_f32 v194, v135, 0xbc800000, v60
	v_fmamk_f32 v197, v135, 0xbc800000, v31
	v_fmamk_f32 v199, v135, 0xbc800000, v29
	v_mul_f32_e32 v176, v176, v176
	v_mul_f32_e32 v138, v138, v138
	v_mul_f32_e32 v195, v195, v195
	v_mul_f32_e32 v181, v181, v181
	v_fmamk_f32 v196, v135, 0xbc800000, v30
	v_fmamk_f32 v198, v135, 0xbc800000, v28
	v_fmamk_f32 v201, v135, 0xbc800000, v7
	v_fmamk_f32 v203, v135, 0xbc800000, v5
	v_mul_f32_e32 v199, v199, v199
	v_mul_f32_e32 v197, v197, v197
	v_fmac_f32_e32 v176, v139, v139
	v_fmac_f32_e32 v138, v134, v134
	v_fmac_f32_e32 v195, v194, v194
	v_fmac_f32_e32 v181, v177, v177
	v_fmamk_f32 v200, v135, 0xbc800000, v6
	v_fmamk_f32 v202, v135, 0xbc800000, v4
	v_mul_f32_e32 v203, v203, v203
	v_mul_f32_e32 v201, v201, v201
	v_fmac_f32_e32 v199, v198, v198
	v_fmac_f32_e32 v197, v196, v196
	v_add_f32_e32 v134, v176, v138
	v_add_f32_e32 v138, v195, v181
	v_fmac_f32_e32 v203, v202, v202
	v_fmac_f32_e32 v201, v200, v200
	v_add_f32_e32 v139, v199, v197
	v_add_f32_e32 v134, v134, v138
	v_add_f32_e32 v176, v203, v201
	v_add_f32_e32 v134, v139, v134
	v_add_f32_e32 v138, v176, v134
	ds_bpermute_b32 v139, v132, v138
	v_and_b32_e32 v134, 63, v149
	v_cmp_gt_u32_e32 vcc, 16, v134
	s_waitcnt lgkmcnt(0)
	v_add_f32_e32 v138, v138, v139
	ds_bpermute_b32 v139, v133, v138
	s_waitcnt vmcnt(0)
	v_pk_mul_f32 v[174:175], v[174:175], s[6:7] op_sel_hi:[1,0]
	v_pk_mul_f32 v[172:173], v[172:173], s[6:7] op_sel_hi:[1,0]
	v_pk_mul_f32 v[176:177], v[184:185], s[6:7] op_sel_hi:[1,0]
	v_pk_mul_f32 v[182:183], v[182:183], s[6:7] op_sel_hi:[1,0]
	v_pk_mul_f32 v[184:185], v[188:189], s[6:7] op_sel_hi:[1,0]
	v_pk_mul_f32 v[186:187], v[186:187], s[6:7] op_sel_hi:[1,0]
	v_pk_mul_f32 v[188:189], v[192:193], s[6:7] op_sel_hi:[1,0]
	v_pk_mul_f32 v[190:191], v[190:191], s[6:7] op_sel_hi:[1,0]
	v_pk_fma_f32 v[126:127], v[126:127], v[156:157], v[174:175]
	v_pk_fma_f32 v[124:125], v[124:125], v[158:159], v[172:173]
	v_pk_fma_f32 v[106:107], v[106:107], v[160:161], v[176:177]
	v_pk_fma_f32 v[104:105], v[104:105], v[162:163], v[182:183]
	v_pk_fma_f32 v[78:79], v[78:79], v[164:165], v[184:185]
	v_pk_fma_f32 v[76:77], v[76:77], v[166:167], v[186:187]
	v_pk_fma_f32 v[46:47], v[46:47], v[168:169], v[188:189]
	v_pk_fma_f32 v[44:45], v[44:45], v[170:171], v[190:191]
	s_lshl_b32 s6, s21, 3
	s_add_i32 s8, s6, 0
	s_and_saveexec_b64 s[6:7], vcc
	s_cbranch_execz .LBB0_394
	s_lshl_b32 s9, s51, 11
	s_add_i32 s9, s8, s9
	v_mul_f32_e32 v156, 0x3c800000, v135
	v_lshl_add_u32 v135, v151, 5, s9
	s_waitcnt lgkmcnt(0)
	v_add_f32_e32 v157, v138, v139
	ds_write_b64 v135, v[156:157]

;     __device__ __forceinline__ bool run(const f32x4 (&v)[2][2][4][2], const Unit& u, int wr, int wc, int fr, int fq, PG8_LAS unsigned char* lds, int wid, int lane) const {
;     ...
;         const int row = wid * 32 + (lane & 31);
;         if (lane < 32) {
;             const f32x2v a = P[row * 4 + 0], b = P[row * 4 + 1], c = P[row * 4 + 2], d = P[row * 4 + 3];
;             const float mt = (a.x + b.x + c.x + d.x) * 0.25f;
;             const float da = a.x - mt, db = b.x - mt, dc = c.x - mt, dd = d.x - mt;
;             const float m2 = (a.y + b.y) + (c.y + d.y) + 64.0f * ((da * da + db * db) + (dc * dc + dd * dd));
;             unsigned long long* slot = (unsigned long long*)xbuf + ((size_t)(u.pm * BM + row) * 4 + u.pn);
;             __hip_atomic_store(slot, ((unsigned long long)__float_as_uint(m2) << 32) | __float_as_uint(mt), __ATOMIC_RELAXED, __HIP_MEMORY_SCOPE_AGENT);
;         }
;         asm volatile("s_waitcnt vmcnt(0)" ::: "memory");
;         if (lane == 0) __hip_atomic_fetch_add(cnt + 64 * u.pm, 1u, __ATOMIC_RELAXED, __HIP_MEMORY_SCOPE_AGENT);
.LBB0_408:
	s_or_b64 exec, exec, s[6:7]
	v_and_b32_e32 v132, 31, v149
	s_waitcnt lgkmcnt(0)
	s_barrier
	v_lshl_or_b32 v149, s15, 5, v132
	s_add_u32 s18, s12, 0x3780000
	v_add_u32_e32 v132, s20, v149
	s_addc_u32 s19, s13, 0
	v_cmp_gt_u32_e64 s[6:7], 32, v134
	s_waitcnt lgkmcnt(0)
	v_ashrrev_i32_e32 v133, 31, v132
	s_and_saveexec_b64 s[8:9], s[6:7]
	s_cbranch_execz .LBB0_410
	v_lshl_add_u32 v135, v149, 5, 0
	ds_read_b128 v[156:159], v135
	ds_read_b128 v[160:163], v135 offset:16
	s_ashr_i32 s15, s14, 31
	s_waitcnt lgkmcnt(1)
	v_add_f32_e32 v135, v156, v158
	s_waitcnt lgkmcnt(0)
	v_add_f32_e32 v135, v135, v160
	v_add_f32_e32 v135, v135, v162
	v_fmamk_f32 v139, v135, 0xbe800000, v156
	v_fmac_f32_e32 v158, 0xbe800000, v135
	v_fmamk_f32 v151, v135, 0xbe800000, v160
	v_fmac_f32_e32 v162, 0xbe800000, v135
	v_mul_f32_e32 v165, v139, v139
	v_mul_f32_e32 v167, v158, v158
	v_mul_f32_e32 v169, v151, v151
	v_mul_f32_e32 v171, v162, v162
	v_mov_b32_e32 v164, v157
	v_mov_b32_e32 v166, v159
	v_mov_b32_e32 v168, v161
	v_mov_b32_e32 v170, v163
	v_pk_add_f32 v[156:157], v[164:165], v[166:167]
	v_pk_add_f32 v[158:159], v[168:169], v[170:171]
	v_mul_f32_e32 v138, 0x3e800000, v135
	v_pk_add_f32 v[156:157], v[156:157], v[158:159]
	s_nop 0
	v_fmamk_f32 v139, v157, 0x42800000, v156
	v_lshlrev_b64 v[156:157], 5, v[132:133]
	v_lshl_add_u64 v[156:157], s[18:19], 0, v[156:157]
	v_lshl_add_u64 v[156:157], s[14:15], 3, v[156:157]
	global_store_dwordx2 v[156:157], v[138:139], off sc1
.LBB0_410:
	s_or_b64 exec, exec, s[8:9]
	s_waitcnt vmcnt(0)
	s_add_u32 s21, s12, 0xd4000
	s_addc_u32 s36, s13, 0
	v_cmp_ne_u32_e64 s[10:11], 0, v134
	v_cmp_eq_u32_e64 s[8:9], 0, v134
	s_and_saveexec_b64 s[14:15], s[8:9]
	s_cbranch_execz .LBB0_412
	s_lshl_b32 s38, s50, 6
	s_ashr_i32 s39, s38, 31
	s_lshl_b64 s[38:39], s[38:39], 2
	s_add_u32 s38, s21, s38
	s_addc_u32 s39, s36, s39
	v_mov_b32_e32 v138, 1
	v_mov_b64_e32 v[134:135], s[38:39]
	global_atomic_add v[134:135], v138, off

;     __device__ __forceinline__ bool run(const f32x4 (&v)[2][2][4][2], const Unit& u, int wr, int wc, int fr, int fq, PG8_LAS unsigned char* lds, int wid, int lane) const {
;     ...
;             for (;;) {
;     ...
;                 break;
;     ...
;                 if ((unsigned)__builtin_amdgcn_readfirstlane(__hip_atomic_load(cnt + 64 * u.pm, __ATOMIC_RELAXED, __HIP_MEMORY_SCOPE_AGENT)) >= want) break;
;                 if (__builtin_amdgcn_s_memrealtime() - t0 > 2000000ull) {
;                     if (lane == 0) { unsigned expect = 0u; __hip_atomic_compare_exchange_strong(tmo + 1, &expect, code | (unsigned)(u.pm & 0xff), __ATOMIC_RELAXED, __ATOMIC_RELAXED, __HIP_MEMORY_SCOPE_AGENT);
;                                      __hip_atomic_store(tmo, 1u, __ATOMIC_RELAXED, __HIP_MEMORY_SCOPE_AGENT); }
;                     dead = true; break; }
;                 __builtin_amdgcn_s_sleep(2);
;             }
.LBB0_416:
	global_load_dword v151, v[134:135], off sc1
	s_mov_b64 s[36:37], -1
	s_mov_b64 s[38:39], -1
	s_waitcnt vmcnt(0) lgkmcnt(0)
	v_readfirstlane_b32 s21, v151
	s_cmp_gt_u32 s21, 31
	s_cbranch_scc1 .LBB0_415
	s_memrealtime s[36:37]
	s_waitcnt lgkmcnt(0)
	s_sub_u32 s36, s36, s14
	s_subb_u32 s37, s37, s15
	v_cmp_lt_u64_e32 vcc, s[36:37], v[138:139]
	s_cbranch_vccz .LBB0_414
	s_mov_b64 s[38:39], 0
	s_sleep 2
	s_branch .LBB0_414

;     __device__ __forceinline__ bool run(const f32x4 (&v)[2][2][4][2], const Unit& u, int wr, int wc, int fr, int fq, PG8_LAS unsigned char* lds, int wid, int lane) const {
;     ...
;                 if (__builtin_amdgcn_s_memrealtime() - t0 > 2000000ull) {
;                     if (lane == 0) { unsigned expect = 0u; __hip_atomic_compare_exchange_strong(tmo + 1, &expect, code | (unsigned)(u.pm & 0xff), __ATOMIC_RELAXED, __ATOMIC_RELAXED, __HIP_MEMORY_SCOPE_AGENT);
;                                      __hip_atomic_store(tmo, 1u, __ATOMIC_RELAXED, __HIP_MEMORY_SCOPE_AGENT); }
;                     dead = true; break; }
.LBB0_422:
	s_or_saveexec_b64 s[14:15], s[10:11]
	s_mov_b64 s[10:11], 0
	s_xor_b64 exec, exec, s[14:15]
	s_cbranch_execz .LBB0_424
	s_and_b32 s21, s50, 0xff
	v_mov_b32_e32 v134, s12
	s_or_b32 s21, s21, 0x700
	v_add_co_u32_e32 v134, vcc, 0xd3000, v134
	v_mov_b32_e32 v135, s13
	s_nop 0
	v_addc_co_u32_e32 v135, vcc, 0, v135, vcc
	v_mov_b32_e32 v138, s21
	v_mov_b32_e32 v139, 0
	global_atomic_cmpswap v[134:135], v[138:139], off offset:3076
	s_mov_b64 s[10:11], exec
	v_mov_b32_e32 v138, 1
	global_store_dword v[134:135], v138, off offset:3072 sc1

;     __device__ __forceinline__ bool run(const f32x4 (&v)[2][2][4][2], const Unit& u, int wr, int wc, int fr, int fq, PG8_LAS unsigned char* lds, int wid, int lane) const {
;     ...
;         const bool bad = flag[0] != 0u;
;         if (lane < 32) {
;             const unsigned long long* slot = (const unsigned long long*)xbuf + (size_t)(u.pm * BM + row) * 4; float mt[4], m2[4]; float ms = 0.f;
; #pragma unroll
;             for (int t = 0; t < 4; ++t) { if (t < ntn) { const unsigned long long w = __hip_atomic_load(slot + t, __ATOMIC_RELAXED, __HIP_MEMORY_SCOPE_AGENT); mt[t] = __uint_as_float((unsigned)w); m2[t] = __uint_as_float((unsigned)(w >> 32)); } else { mt[t] = 0.f; m2[t] = 0.f; } ms += mt[t]; }
;             const float mean = ms / (float)ntn; float q = 0.f;
; #pragma unroll
;             for (int t = 0; t < 4; ++t) if (t < ntn) { const float dm = mt[t] - mean; q += m2[t] + 256.0f * dm * dm; }
;             S[row] = (f32x2v){mean, 1.0f / sqrtf(q / (256.0f * (float)ntn) + eps)};
;     __device__ __forceinline__ void fused(f32x4 (&acc)[2][2][4][2], const Unit& u, int wr, int wc, int fr, int fq, PG8_LAS unsigned char* lds, int wid, int lane) const {
;     ...
; #pragma unroll
;         for (int bj = 0; bj < 2; ++bj)
; #pragma unroll
;             for (int n = 0; n < 2; ++n) {
;                 const int col = col0 + bj * HALF + n * 16;
;                 const f32x4 lg = *(const f32x4*)(lng + col), lb = *(const f32x4*)(lnb + col);
;                 f32x4 sc1 = (f32x4){1.f, 1.f, 1.f, 1.f}, sh = (f32x4){0.f, 0.f, 0.f, 0.f};
;                 if (DO_U) { sc1 = *(const f32x4*)(msc + mo + col) + 1.0f; sh = *(const f32x4*)(msh + mo + col); }
; #pragma unroll
;                 for (int ai = 0; ai < 2; ++ai)
; #pragma unroll
;                     for (int m = 0; m < 4; ++m) { const int r = ai * HALF + wr * 64 + m * 16 + fr; const f32x2v sr = S[r]; const size_t off = (size_t)(u.pm * BM + r) * 1024 + col;
;                         f32x4 y = (acc[ai][bj][m][n] - sr.x) * sr.y * lg + lb; if (bad) y = (f32x4){qnan, qnan, qnan, qnan};
;                         *(f32x4*)(out + off) = y;
;                         if (DO_U) { const f32x4 uu = y * sc1 + sh; u32x2v w; w.x = cvt_pk_bf16(uu[0], uu[1]); w.y = cvt_pk_bf16(uu[2], uu[3]); *(u32x2v*)(U + off) = w; } }
.LBB0_429:
	s_waitcnt vmcnt(0) lgkmcnt(0)
	s_barrier
	v_mov_b32_e32 v134, 0
	ds_read_b32 v151, v134 offset:10240
	s_and_saveexec_b64 s[8:9], s[6:7]
	s_cbranch_execz .LBB0_431
	v_lshlrev_b64 v[132:133], 5, v[132:133]
	v_lshl_add_u64 v[132:133], s[18:19], 0, v[132:133]
	global_load_dwordx2 v[134:135], v[132:133], off sc1
	global_load_dwordx2 v[138:139], v[132:133], off offset:8 sc1
	global_load_dwordx2 v[156:157], v[132:133], off offset:16 sc1
	s_nop 0
	global_load_dwordx2 v[132:133], v[132:133], off offset:24 sc1
	v_mov_b32_e32 v158, 0x3727c5ac
	s_mov_b32 s6, 0xf800000
	s_waitcnt vmcnt(0) lgkmcnt(0)
	v_add_f32_e32 v159, 0, v134
	v_add_f32_e32 v159, v159, v138
	v_add_f32_e32 v159, v159, v156
	v_add_f32_e32 v159, v159, v132
	v_fmamk_f32 v134, v159, 0xbe800000, v134
	v_fmamk_f32 v138, v159, 0xbe800000, v138
	v_fmamk_f32 v132, v159, 0xbe800000, v132
	v_mul_f32_e32 v160, 0x43800000, v134
	v_fmamk_f32 v156, v159, 0xbe800000, v156
	v_mul_f32_e32 v161, 0x43800000, v138
	v_mul_f32_e32 v163, 0x43800000, v132
	v_fmac_f32_e32 v135, v134, v160
	v_mul_f32_e32 v162, 0x43800000, v156
	v_fmac_f32_e32 v139, v138, v161
	v_fmac_f32_e32 v133, v132, v163
	v_add_f32_e32 v132, 0, v135
	v_fmac_f32_e32 v157, v156, v162
	v_add_f32_e32 v132, v139, v132
	v_add_f32_e32 v132, v157, v132
	v_add_f32_e32 v132, v133, v132
	v_fmac_f32_e32 v158, 0x3a800000, v132
	v_mul_f32_e32 v132, 0x4f800000, v158
	v_cmp_gt_f32_e32 vcc, s6, v158
	v_mov_b32_e32 v134, 0x260
	s_nop 0
	v_cndmask_b32_e32 v132, v158, v132, vcc
	v_sqrt_f32_e32 v133, v132
	s_nop 0
	v_add_u32_e32 v135, -1, v133
	v_add_u32_e32 v138, 1, v133
	v_fma_f32 v139, -v135, v133, v132
	v_fma_f32 v156, -v138, v133, v132
	v_cmp_ge_f32_e64 s[6:7], 0, v139
	s_nop 1
	v_cndmask_b32_e64 v133, v133, v135, s[6:7]
	v_cmp_lt_f32_e64 s[6:7], 0, v156
	s_nop 1
	v_cndmask_b32_e64 v133, v133, v138, s[6:7]
	v_mul_f32_e32 v135, 0x37800000, v133
	v_cndmask_b32_e32 v133, v133, v135, vcc
	v_cmp_class_f32_e32 vcc, v132, v134
	s_nop 1
	v_cndmask_b32_e32 v133, v133, v132, vcc
	v_div_scale_f32 v134, s[6:7], v133, v133, 1.0
	v_rcp_f32_e32 v135, v134
	v_div_scale_f32 v138, vcc, 1.0, v133, 1.0
	v_mul_f32_e32 v132, 0x3e800000, v159
	v_fma_f32 v139, -v134, v135, 1.0
	v_fmac_f32_e32 v135, v139, v135
	v_mul_f32_e32 v139, v138, v135
	v_fma_f32 v156, -v134, v139, v138
	v_fmac_f32_e32 v139, v156, v135
	v_fma_f32 v134, -v134, v139, v138
	v_div_fmas_f32 v134, v134, v135, v139
	v_div_fixup_f32 v133, v134, v133, 1.0
	v_lshl_add_u32 v134, v149, 3, 0
	ds_write_b64 v134, v[132:133] offset:8192
.LBB0_431:
	s_or_b64 exec, exec, s[8:9]
	s_add_u32 s6, s12, 0x3a00000
	s_addc_u32 s7, s13, 0
	s_add_u32 s8, s12, s16
	s_addc_u32 s9, s13, s17
	v_lshl_add_u64 v[174:175], s[8:9], 0, v[136:137]
	s_movk_i32 s8, 0x4000
	v_lshl_add_u64 v[156:157], v[0:1], 0, v[136:137]
	v_lshl_add_u64 v[158:159], v[2:3], 0, v[136:137]
	v_add_co_u32_e32 v136, vcc, s8, v174
	s_waitcnt lgkmcnt(0)
	s_barrier
	s_nop 0
	v_addc_co_u32_e32 v137, vcc, 0, v175, vcc
	s_movk_i32 s8, 0x3000
	global_load_dwordx4 v[132:135], v[156:157], off
	global_load_dwordx4 v[0:3], v[158:159], off
	global_load_dwordx4 v[160:163], v[136:137], off
	v_add_co_u32_e32 v136, vcc, s8, v174
	v_lshl_add_u32 v149, v147, 3, 0
	s_nop 0
	v_addc_co_u32_e32 v137, vcc, 0, v175, vcc
	global_load_dwordx4 v[136:139], v[136:137], off
	ds_read_b64 v[164:165], v149 offset:8192
	v_add_u32_e32 v176, s20, v147
	v_ashrrev_i32_e32 v177, 31, v176
	v_lshlrev_b64 v[170:171], 10, v[176:177]
	v_mov_b32_e32 v147, 0x7fc00000
	s_waitcnt lgkmcnt(0)
	v_sub_f32_e32 v93, v93, v164
	v_sub_f32_e32 v92, v92, v164
	v_sub_f32_e32 v95, v95, v164
	v_sub_f32_e32 v94, v94, v164
	v_pk_mul_f32 v[92:93], v[164:165], v[92:93] op_sel:[1,0]
	v_lshl_add_u64 v[182:183], v[170:171], 0, v[154:155]
	v_pk_mul_f32 v[94:95], v[164:165], v[94:95] op_sel:[1,0]
	v_cmp_eq_u32_e32 vcc, 0, v151
	v_lshl_add_u64 v[166:167], v[182:183], 2, v[152:153]
	v_lshl_add_u64 v[188:189], v[182:183], 1, s[6:7]
	v_add_u32_e32 v168, 16, v176
	v_ashrrev_i32_e32 v169, 31, v168
	v_lshlrev_b64 v[168:169], 10, v[168:169]
	v_lshl_add_u64 v[164:165], v[168:169], 0, v[154:155]
	v_add_u32_e32 v172, 32, v176
	v_ashrrev_i32_e32 v173, 31, v172
	v_add_u32_e32 v186, 48, v176
	v_ashrrev_i32_e32 v187, 31, v186
	s_mov_b64 s[8:9], 0x4000
	s_waitcnt vmcnt(0)
	v_pk_fma_f32 v[92:93], v[132:133], v[92:93], v[0:1]
	v_pk_fma_f32 v[94:95], v[134:135], v[94:95], v[2:3]
	v_cndmask_b32_e32 v183, v147, v93, vcc
	v_cndmask_b32_e32 v182, v147, v92, vcc
	v_pk_add_f32 v[92:93], v[160:161], 1.0 op_sel_hi:[1,0]
	v_cndmask_b32_e32 v185, v147, v95, vcc
	v_cndmask_b32_e32 v184, v147, v94, vcc
	v_pk_add_f32 v[94:95], v[162:163], 1.0 op_sel_hi:[1,0]
	v_pk_fma_f32 v[162:163], v[92:93], v[182:183], v[136:137]
	global_store_dwordx4 v[166:167], v[182:185], off sc0 sc1
	v_pk_fma_f32 v[160:161], v[94:95], v[184:185], v[138:139]
	v_cvt_pk_bf16_f32 v162, v162, v163
	s_nop 0
	v_cvt_pk_bf16_f32 v163, v160, v161
	global_store_dwordx2 v[188:189], v[162:163], off
	ds_read_b64 v[160:161], v149 offset:8320
	v_lshl_add_u64 v[162:163], v[164:165], 2, v[152:153]
	v_lshl_add_u64 v[164:165], v[164:165], 1, s[6:7]
	s_waitcnt lgkmcnt(0)
; __device__ __forceinline__ unsigned cvt_pk_bf16(float lo, float hi) { unsigned r; asm volatile("v_cvt_pk_bf16_f32 %0, %1, %2" : "=v"(r) : "v"(lo), "v"(hi)); return r; }
;     __device__ __forceinline__ void fused(f32x4 (&acc)[2][2][4][2], const Unit& u, int wr, int wc, int fr, int fq, PG8_LAS unsigned char* lds, int wid, int lane) const {
;     ...
; #pragma unroll
;         for (int bj = 0; bj < 2; ++bj)
; #pragma unroll
;             for (int n = 0; n < 2; ++n) {
;                 const int col = col0 + bj * HALF + n * 16;
;                 const f32x4 lg = *(const f32x4*)(lng + col), lb = *(const f32x4*)(lnb + col);
;                 f32x4 sc1 = (f32x4){1.f, 1.f, 1.f, 1.f}, sh = (f32x4){0.f, 0.f, 0.f, 0.f};
;                 if (DO_U) { sc1 = *(const f32x4*)(msc + mo + col) + 1.0f; sh = *(const f32x4*)(msh + mo + col); }
; #pragma unroll
;                 for (int ai = 0; ai < 2; ++ai)
; #pragma unroll
;                     for (int m = 0; m < 4; ++m) { const int r = ai * HALF + wr * 64 + m * 16 + fr; const f32x2v sr = S[r]; const size_t off = (size_t)(u.pm * BM + r) * 1024 + col;
;                         f32x4 y = (acc[ai][bj][m][n] - sr.x) * sr.y * lg + lb; if (bad) y = (f32x4){qnan, qnan, qnan, qnan};
;                         *(f32x4*)(out + off) = y;
;                         if (DO_U) { const f32x4 uu = y * sc1 + sh; u32x2v w; w.x = cvt_pk_bf16(uu[0], uu[1]); w.y = cvt_pk_bf16(uu[2], uu[3]); *(u32x2v*)(U + off) = w; } }
	v_sub_f32_e32 v103, v103, v160
	v_sub_f32_e32 v102, v102, v160
	v_sub_f32_e32 v101, v101, v160
	v_sub_f32_e32 v100, v100, v160
	v_pk_mul_f32 v[100:101], v[160:161], v[100:101] op_sel:[1,0]
	v_pk_mul_f32 v[102:103], v[160:161], v[102:103] op_sel:[1,0]
	v_pk_fma_f32 v[100:101], v[132:133], v[100:101], v[0:1]
	v_pk_fma_f32 v[102:103], v[134:135], v[102:103], v[2:3]
	v_cndmask_b32_e32 v101, v147, v101, vcc
	v_cndmask_b32_e32 v103, v147, v103, vcc
	v_cndmask_b32_e32 v102, v147, v102, vcc
	v_cndmask_b32_e32 v100, v147, v100, vcc
	global_store_dwordx4 v[162:163], v[100:103], off sc0 sc1
	s_nop 1
	v_pk_fma_f32 v[100:101], v[92:93], v[100:101], v[136:137]
	v_pk_fma_f32 v[102:103], v[94:95], v[102:103], v[138:139]
	v_cvt_pk_bf16_f32 v100, v100, v101
	s_nop 0
	v_cvt_pk_bf16_f32 v101, v102, v103
	global_store_dwordx2 v[164:165], v[100:101], off
	ds_read_b64 v[100:101], v149 offset:8448
	v_lshlrev_b64 v[164:165], 10, v[172:173]
	v_lshl_add_u64 v[102:103], v[164:165], 0, v[154:155]
	v_lshl_add_u64 v[160:161], v[102:103], 2, v[152:153]
	v_lshl_add_u64 v[172:173], v[102:103], 1, s[6:7]
	s_waitcnt lgkmcnt(0)
	v_sub_f32_e32 v103, v111, v100
	v_sub_f32_e32 v102, v110, v100
	v_sub_f32_e32 v109, v109, v100
	v_sub_f32_e32 v108, v108, v100
	v_pk_mul_f32 v[108:109], v[100:101], v[108:109] op_sel:[1,0]
	v_pk_mul_f32 v[100:101], v[100:101], v[102:103] op_sel:[1,0]
	v_pk_fma_f32 v[108:109], v[132:133], v[108:109], v[0:1]
	v_pk_fma_f32 v[100:101], v[134:135], v[100:101], v[2:3]
	v_lshlrev_b64 v[110:111], 10, v[186:187]
	v_cndmask_b32_e32 v103, v147, v101, vcc
	v_cndmask_b32_e32 v102, v147, v100, vcc
	v_cndmask_b32_e32 v101, v147, v109, vcc
	v_cndmask_b32_e32 v100, v147, v108, vcc
	global_store_dwordx4 v[160:161], v[100:103], off sc0 sc1
	v_lshl_add_u64 v[182:183], v[110:111], 0, v[154:155]
	s_nop 0
	v_pk_fma_f32 v[100:101], v[92:93], v[100:101], v[136:137]
	v_pk_fma_f32 v[102:103], v[94:95], v[102:103], v[138:139]
	v_cvt_pk_bf16_f32 v100, v100, v101
	s_nop 0
	v_cvt_pk_bf16_f32 v101, v102, v103
	global_store_dwordx2 v[172:173], v[100:101], off
	ds_read_b64 v[100:101], v149 offset:8576
	v_lshl_add_u64 v[172:173], v[174:175], 0, s[8:9]
	s_mov_b64 s[8:9], 0x3000
	s_waitcnt lgkmcnt(0)
	v_sub_f32_e32 v103, v115, v100
	v_sub_f32_e32 v102, v114, v100
	v_sub_f32_e32 v109, v113, v100
	v_sub_f32_e32 v108, v112, v100
	v_pk_mul_f32 v[108:109], v[100:101], v[108:109] op_sel:[1,0]
	v_pk_mul_f32 v[100:101], v[100:101], v[102:103] op_sel:[1,0]
	v_pk_fma_f32 v[108:109], v[132:133], v[108:109], v[0:1]
	v_pk_fma_f32 v[100:101], v[134:135], v[100:101], v[2:3]
	s_nop 0
	v_cndmask_b32_e32 v103, v147, v101, vcc
	v_cndmask_b32_e32 v102, v147, v100, vcc
	v_cndmask_b32_e32 v101, v147, v109, vcc
	v_cndmask_b32_e32 v100, v147, v108, vcc
	v_lshl_add_u64 v[108:109], v[182:183], 2, v[152:153]
	global_store_dwordx4 v[108:109], v[100:103], off sc0 sc1
	s_nop 1
	v_pk_fma_f32 v[102:103], v[94:95], v[102:103], v[138:139]
	v_pk_fma_f32 v[100:101], v[92:93], v[100:101], v[136:137]
	s_nop 0
	v_cvt_pk_bf16_f32 v100, v100, v101
	v_cvt_pk_bf16_f32 v101, v102, v103
	v_lshl_add_u64 v[102:103], v[182:183], 1, s[6:7]
	global_store_dwordx2 v[102:103], v[100:101], off
	ds_read_b64 v[100:101], v149 offset:9216
	v_add_u32_e32 v102, 0x80, v176
	v_ashrrev_i32_e32 v103, 31, v102
	v_lshlrev_b64 v[114:115], 10, v[102:103]
	v_lshl_add_u64 v[182:183], v[114:115], 0, v[154:155]
	s_waitcnt lgkmcnt(0)
	v_sub_f32_e32 v103, v119, v100
	v_sub_f32_e32 v102, v118, v100
	v_sub_f32_e32 v113, v117, v100
	v_sub_f32_e32 v112, v116, v100
	v_pk_mul_f32 v[112:113], v[100:101], v[112:113] op_sel:[1,0]
	v_pk_mul_f32 v[100:101], v[100:101], v[102:103] op_sel:[1,0]
	v_pk_fma_f32 v[112:113], v[132:133], v[112:113], v[0:1]
	v_pk_fma_f32 v[100:101], v[134:135], v[100:101], v[2:3]
	s_nop 0
	v_cndmask_b32_e32 v103, v147, v101, vcc
	v_cndmask_b32_e32 v102, v147, v100, vcc
	v_cndmask_b32_e32 v101, v147, v113, vcc
	v_cndmask_b32_e32 v100, v147, v112, vcc
	v_lshl_add_u64 v[112:113], v[182:183], 2, v[152:153]
	global_store_dwordx4 v[112:113], v[100:103], off sc0 sc1
	s_nop 1
	v_pk_fma_f32 v[102:103], v[94:95], v[102:103], v[138:139]
	v_pk_fma_f32 v[100:101], v[92:93], v[100:101], v[136:137]
	s_nop 0
	v_cvt_pk_bf16_f32 v100, v100, v101
	v_cvt_pk_bf16_f32 v101, v102, v103
	v_lshl_add_u64 v[102:103], v[182:183], 1, s[6:7]
	global_store_dwordx2 v[102:103], v[100:101], off
	ds_read_b64 v[100:101], v149 offset:9344
	v_add_u32_e32 v102, 0x90, v176
	v_ashrrev_i32_e32 v103, 31, v102
	v_lshlrev_b64 v[118:119], 10, v[102:103]
	v_lshl_add_u64 v[182:183], v[118:119], 0, v[154:155]
	s_waitcnt lgkmcnt(0)
	v_sub_f32_e32 v103, v123, v100
	v_sub_f32_e32 v102, v122, v100
	v_sub_f32_e32 v117, v121, v100
	v_sub_f32_e32 v116, v120, v100
	v_pk_mul_f32 v[116:117], v[100:101], v[116:117] op_sel:[1,0]
	v_pk_mul_f32 v[100:101], v[100:101], v[102:103] op_sel:[1,0]
	v_pk_fma_f32 v[116:117], v[132:133], v[116:117], v[0:1]
	v_pk_fma_f32 v[100:101], v[134:135], v[100:101], v[2:3]
	s_nop 0
	v_cndmask_b32_e32 v103, v147, v101, vcc
	v_cndmask_b32_e32 v102, v147, v100, vcc
	v_cndmask_b32_e32 v101, v147, v117, vcc
	v_cndmask_b32_e32 v100, v147, v116, vcc
	v_lshl_add_u64 v[116:117], v[182:183], 2, v[152:153]
	global_store_dwordx4 v[116:117], v[100:103], off sc0 sc1
	s_nop 1
	v_pk_fma_f32 v[102:103], v[94:95], v[102:103], v[138:139]
	v_pk_fma_f32 v[100:101], v[92:93], v[100:101], v[136:137]
	s_nop 0
	v_cvt_pk_bf16_f32 v100, v100, v101
	v_cvt_pk_bf16_f32 v101, v102, v103
	v_lshl_add_u64 v[102:103], v[182:183], 1, s[6:7]
	global_store_dwordx2 v[102:103], v[100:101], off
	ds_read_b64 v[100:101], v149 offset:9472
	v_add_u32_e32 v102, 0xa0, v176
	v_ashrrev_i32_e32 v103, 31, v102
	v_lshlrev_b64 v[122:123], 10, v[102:103]
	v_lshl_add_u64 v[182:183], v[122:123], 0, v[154:155]
	s_waitcnt lgkmcnt(0)
; __device__ __forceinline__ unsigned cvt_pk_bf16(float lo, float hi) { unsigned r; asm volatile("v_cvt_pk_bf16_f32 %0, %1, %2" : "=v"(r) : "v"(lo), "v"(hi)); return r; }
;     __device__ __forceinline__ void fused(f32x4 (&acc)[2][2][4][2], const Unit& u, int wr, int wc, int fr, int fq, PG8_LAS unsigned char* lds, int wid, int lane) const {
;     ...
; #pragma unroll
;         for (int bj = 0; bj < 2; ++bj)
; #pragma unroll
;             for (int n = 0; n < 2; ++n) {
;                 const int col = col0 + bj * HALF + n * 16;
;                 const f32x4 lg = *(const f32x4*)(lng + col), lb = *(const f32x4*)(lnb + col);
;                 f32x4 sc1 = (f32x4){1.f, 1.f, 1.f, 1.f}, sh = (f32x4){0.f, 0.f, 0.f, 0.f};
;                 if (DO_U) { sc1 = *(const f32x4*)(msc + mo + col) + 1.0f; sh = *(const f32x4*)(msh + mo + col); }
; #pragma unroll
;                 for (int ai = 0; ai < 2; ++ai)
; #pragma unroll
;                     for (int m = 0; m < 4; ++m) { const int r = ai * HALF + wr * 64 + m * 16 + fr; const f32x2v sr = S[r]; const size_t off = (size_t)(u.pm * BM + r) * 1024 + col;
;                         f32x4 y = (acc[ai][bj][m][n] - sr.x) * sr.y * lg + lb; if (bad) y = (f32x4){qnan, qnan, qnan, qnan};
;                         *(f32x4*)(out + off) = y;
;                         if (DO_U) { const f32x4 uu = y * sc1 + sh; u32x2v w; w.x = cvt_pk_bf16(uu[0], uu[1]); w.y = cvt_pk_bf16(uu[2], uu[3]); *(u32x2v*)(U + off) = w; } }
	v_sub_f32_e32 v103, v131, v100
	v_sub_f32_e32 v102, v130, v100
	v_sub_f32_e32 v121, v129, v100
	v_sub_f32_e32 v120, v128, v100
	v_pk_mul_f32 v[120:121], v[100:101], v[120:121] op_sel:[1,0]
	v_pk_mul_f32 v[100:101], v[100:101], v[102:103] op_sel:[1,0]
	v_pk_fma_f32 v[120:121], v[132:133], v[120:121], v[0:1]
	v_pk_fma_f32 v[100:101], v[134:135], v[100:101], v[2:3]
	v_or_b32_e32 v130, 16, v154
	v_cndmask_b32_e32 v103, v147, v101, vcc
	v_cndmask_b32_e32 v102, v147, v100, vcc
	v_cndmask_b32_e32 v101, v147, v121, vcc
	v_cndmask_b32_e32 v100, v147, v120, vcc
	v_lshl_add_u64 v[120:121], v[182:183], 2, v[152:153]
	global_store_dwordx4 v[120:121], v[100:103], off sc0 sc1
	v_ashrrev_i32_e32 v131, 31, v130
	s_nop 0
	v_pk_fma_f32 v[102:103], v[94:95], v[102:103], v[138:139]
	v_pk_fma_f32 v[100:101], v[92:93], v[100:101], v[136:137]
	s_nop 0
	v_cvt_pk_bf16_f32 v100, v100, v101
	v_cvt_pk_bf16_f32 v101, v102, v103
	v_lshl_add_u64 v[102:103], v[182:183], 1, s[6:7]
	global_store_dwordx2 v[102:103], v[100:101], off
	ds_read_b64 v[100:101], v149 offset:9600
	v_add_u32_e32 v102, 0xb0, v176
	v_ashrrev_i32_e32 v103, 31, v102
	v_lshlrev_b64 v[128:129], 10, v[102:103]
	v_lshl_add_u64 v[102:103], v[128:129], 0, v[154:155]
	s_waitcnt lgkmcnt(0)
	v_sub_f32_e32 v127, v127, v100
	v_sub_f32_e32 v126, v126, v100
	v_sub_f32_e32 v125, v125, v100
	v_sub_f32_e32 v124, v124, v100
	v_pk_mul_f32 v[124:125], v[100:101], v[124:125] op_sel:[1,0]
	v_pk_mul_f32 v[100:101], v[100:101], v[126:127] op_sel:[1,0]
	v_pk_fma_f32 v[0:1], v[132:133], v[124:125], v[0:1]
	v_pk_fma_f32 v[2:3], v[134:135], v[100:101], v[2:3]
	v_cndmask_b32_e32 v1, v147, v1, vcc
	v_cndmask_b32_e32 v3, v147, v3, vcc
	v_cndmask_b32_e32 v2, v147, v2, vcc
	v_cndmask_b32_e32 v0, v147, v0, vcc
	v_lshl_add_u64 v[124:125], v[102:103], 2, v[152:153]
	global_store_dwordx4 v[124:125], v[0:3], off sc0 sc1
	v_lshl_add_u64 v[126:127], v[174:175], 0, s[8:9]
	s_nop 0
	v_pk_fma_f32 v[2:3], v[94:95], v[2:3], v[138:139]
	v_pk_fma_f32 v[0:1], v[92:93], v[0:1], v[136:137]
	v_lshl_add_u64 v[138:139], v[170:171], 0, v[130:131]
	v_cvt_pk_bf16_f32 v0, v0, v1
	v_cvt_pk_bf16_f32 v1, v2, v3
	v_lshl_add_u64 v[2:3], v[102:103], 1, s[6:7]
	global_store_dwordx2 v[2:3], v[0:1], off
	global_load_dwordx4 v[132:135], v[172:173], off offset:64
	global_load_dwordx4 v[92:95], v[156:157], off offset:64
	global_load_dwordx4 v[100:103], v[158:159], off offset:64
	ds_read_b64 v[136:137], v149 offset:8192
	global_load_dwordx4 v[0:3], v[126:127], off offset:64
	s_waitcnt lgkmcnt(0)
	v_sub_f32_e32 v63, v63, v136
	v_sub_f32_e32 v62, v62, v136
	v_sub_f32_e32 v61, v61, v136
	v_sub_f32_e32 v60, v60, v136
	v_pk_mul_f32 v[152:153], v[136:137], v[60:61] op_sel:[1,0]
	v_pk_mul_f32 v[136:137], v[136:137], v[62:63] op_sel:[1,0]
	s_waitcnt vmcnt(0)
	v_pk_add_f32 v[60:61], v[132:133], 1.0 op_sel_hi:[1,0]
	v_pk_add_f32 v[62:63], v[134:135], 1.0 op_sel_hi:[1,0]
	v_pk_fma_f32 v[132:133], v[94:95], v[136:137], v[102:103]
	v_pk_fma_f32 v[136:137], v[92:93], v[152:153], v[100:101]
	v_cndmask_b32_e32 v135, v147, v133, vcc
	v_cndmask_b32_e32 v134, v147, v132, vcc
	v_cndmask_b32_e32 v133, v147, v137, vcc
	v_cndmask_b32_e32 v132, v147, v136, vcc
	global_store_dwordx4 v[166:167], v[132:135], off offset:64 sc0 sc1
	s_nop 1
	v_pk_fma_f32 v[134:135], v[62:63], v[134:135], v[2:3]
	v_pk_fma_f32 v[132:133], v[60:61], v[132:133], v[0:1]
	s_nop 0
	v_cvt_pk_bf16_f32 v132, v132, v133
	v_cvt_pk_bf16_f32 v133, v134, v135
	v_lshl_add_u64 v[134:135], v[138:139], 1, s[6:7]
	global_store_dwordx2 v[134:135], v[132:133], off
	ds_read_b64 v[132:133], v149 offset:8320
	v_lshl_add_u64 v[134:135], v[168:169], 0, v[130:131]
	s_waitcnt lgkmcnt(0)
	v_sub_f32_e32 v71, v71, v132
	v_sub_f32_e32 v70, v70, v132
	v_sub_f32_e32 v69, v69, v132
	v_sub_f32_e32 v68, v68, v132
	v_pk_mul_f32 v[68:69], v[132:133], v[68:69] op_sel:[1,0]
	v_pk_mul_f32 v[70:71], v[132:133], v[70:71] op_sel:[1,0]
	v_pk_fma_f32 v[68:69], v[92:93], v[68:69], v[100:101]
	v_pk_fma_f32 v[70:71], v[94:95], v[70:71], v[102:103]
	v_cndmask_b32_e32 v69, v147, v69, vcc
	v_cndmask_b32_e32 v71, v147, v71, vcc
	v_cndmask_b32_e32 v70, v147, v70, vcc
	v_cndmask_b32_e32 v68, v147, v68, vcc
	global_store_dwordx4 v[162:163], v[68:71], off offset:64 sc0 sc1
	v_lshl_add_u64 v[132:133], v[164:165], 0, v[130:131]
	s_nop 0
	v_pk_fma_f32 v[70:71], v[62:63], v[70:71], v[2:3]
	v_pk_fma_f32 v[68:69], v[60:61], v[68:69], v[0:1]
	s_nop 0
	v_cvt_pk_bf16_f32 v68, v68, v69
	v_cvt_pk_bf16_f32 v69, v70, v71
	v_lshl_add_u64 v[70:71], v[134:135], 1, s[6:7]
	global_store_dwordx2 v[70:71], v[68:69], off
	ds_read_b64 v[68:69], v149 offset:8448
	s_waitcnt lgkmcnt(0)
	v_sub_f32_e32 v71, v75, v68
	v_sub_f32_e32 v70, v74, v68
	v_sub_f32_e32 v73, v73, v68
	v_sub_f32_e32 v72, v72, v68
	v_pk_mul_f32 v[72:73], v[68:69], v[72:73] op_sel:[1,0]
	v_pk_mul_f32 v[68:69], v[68:69], v[70:71] op_sel:[1,0]
	v_pk_fma_f32 v[72:73], v[92:93], v[72:73], v[100:101]
	v_pk_fma_f32 v[68:69], v[94:95], v[68:69], v[102:103]
	s_nop 0
	v_cndmask_b32_e32 v71, v147, v69, vcc
	v_cndmask_b32_e32 v70, v147, v68, vcc
	v_cndmask_b32_e32 v69, v147, v73, vcc
	v_cndmask_b32_e32 v68, v147, v72, vcc
	global_store_dwordx4 v[160:161], v[68:71], off offset:64 sc0 sc1
	v_lshl_add_u64 v[72:73], v[110:111], 0, v[130:131]
	s_nop 0
	v_pk_fma_f32 v[70:71], v[62:63], v[70:71], v[2:3]
	v_pk_fma_f32 v[68:69], v[60:61], v[68:69], v[0:1]
	s_nop 0
	v_cvt_pk_bf16_f32 v68, v68, v69
	v_cvt_pk_bf16_f32 v69, v70, v71
	v_lshl_add_u64 v[70:71], v[132:133], 1, s[6:7]
	global_store_dwordx2 v[70:71], v[68:69], off
	ds_read_b64 v[68:69], v149 offset:8576
	s_waitcnt lgkmcnt(0)
; __device__ __forceinline__ unsigned cvt_pk_bf16(float lo, float hi) { unsigned r; asm volatile("v_cvt_pk_bf16_f32 %0, %1, %2" : "=v"(r) : "v"(lo), "v"(hi)); return r; }
;     __device__ __forceinline__ void fused(f32x4 (&acc)[2][2][4][2], const Unit& u, int wr, int wc, int fr, int fq, PG8_LAS unsigned char* lds, int wid, int lane) const {
;     ...
; #pragma unroll
;         for (int bj = 0; bj < 2; ++bj)
; #pragma unroll
;             for (int n = 0; n < 2; ++n) {
;                 const int col = col0 + bj * HALF + n * 16;
;                 const f32x4 lg = *(const f32x4*)(lng + col), lb = *(const f32x4*)(lnb + col);
;                 f32x4 sc1 = (f32x4){1.f, 1.f, 1.f, 1.f}, sh = (f32x4){0.f, 0.f, 0.f, 0.f};
;                 if (DO_U) { sc1 = *(const f32x4*)(msc + mo + col) + 1.0f; sh = *(const f32x4*)(msh + mo + col); }
; #pragma unroll
;                 for (int ai = 0; ai < 2; ++ai)
; #pragma unroll
;                     for (int m = 0; m < 4; ++m) { const int r = ai * HALF + wr * 64 + m * 16 + fr; const f32x2v sr = S[r]; const size_t off = (size_t)(u.pm * BM + r) * 1024 + col;
;                         f32x4 y = (acc[ai][bj][m][n] - sr.x) * sr.y * lg + lb; if (bad) y = (f32x4){qnan, qnan, qnan, qnan};
;                         *(f32x4*)(out + off) = y;
;                         if (DO_U) { const f32x4 uu = y * sc1 + sh; u32x2v w; w.x = cvt_pk_bf16(uu[0], uu[1]); w.y = cvt_pk_bf16(uu[2], uu[3]); *(u32x2v*)(U + off) = w; } }
	v_sub_f32_e32 v71, v83, v68
	v_sub_f32_e32 v70, v82, v68
	v_sub_f32_e32 v75, v81, v68
	v_sub_f32_e32 v74, v80, v68
	v_pk_mul_f32 v[74:75], v[68:69], v[74:75] op_sel:[1,0]
	v_pk_mul_f32 v[68:69], v[68:69], v[70:71] op_sel:[1,0]
	v_pk_fma_f32 v[74:75], v[92:93], v[74:75], v[100:101]
	v_pk_fma_f32 v[68:69], v[94:95], v[68:69], v[102:103]
	s_nop 0
	v_cndmask_b32_e32 v71, v147, v69, vcc
	v_cndmask_b32_e32 v70, v147, v68, vcc
	v_cndmask_b32_e32 v69, v147, v75, vcc
	v_cndmask_b32_e32 v68, v147, v74, vcc
	global_store_dwordx4 v[108:109], v[68:71], off offset:64 sc0 sc1
	s_nop 1
	v_pk_fma_f32 v[70:71], v[62:63], v[70:71], v[2:3]
	v_pk_fma_f32 v[68:69], v[60:61], v[68:69], v[0:1]
	s_nop 0
	v_cvt_pk_bf16_f32 v68, v68, v69
	v_cvt_pk_bf16_f32 v69, v70, v71
	v_lshl_add_u64 v[70:71], v[72:73], 1, s[6:7]
	global_store_dwordx2 v[70:71], v[68:69], off
	ds_read_b64 v[68:69], v149 offset:9216
	v_lshl_add_u64 v[72:73], v[114:115], 0, v[130:131]
	s_waitcnt lgkmcnt(0)
	v_sub_f32_e32 v71, v87, v68
	v_sub_f32_e32 v70, v86, v68
	v_sub_f32_e32 v75, v85, v68
	v_sub_f32_e32 v74, v84, v68
	v_pk_mul_f32 v[74:75], v[68:69], v[74:75] op_sel:[1,0]
	v_pk_mul_f32 v[68:69], v[68:69], v[70:71] op_sel:[1,0]
	v_pk_fma_f32 v[74:75], v[92:93], v[74:75], v[100:101]
	v_pk_fma_f32 v[68:69], v[94:95], v[68:69], v[102:103]
	s_nop 0
	v_cndmask_b32_e32 v71, v147, v69, vcc
	v_cndmask_b32_e32 v70, v147, v68, vcc
	v_cndmask_b32_e32 v69, v147, v75, vcc
	v_cndmask_b32_e32 v68, v147, v74, vcc
	global_store_dwordx4 v[112:113], v[68:71], off offset:64 sc0 sc1
	s_nop 1
	v_pk_fma_f32 v[70:71], v[62:63], v[70:71], v[2:3]
	v_pk_fma_f32 v[68:69], v[60:61], v[68:69], v[0:1]
	s_nop 0
	v_cvt_pk_bf16_f32 v68, v68, v69
	v_cvt_pk_bf16_f32 v69, v70, v71
	v_lshl_add_u64 v[70:71], v[72:73], 1, s[6:7]
	global_store_dwordx2 v[70:71], v[68:69], off
	ds_read_b64 v[68:69], v149 offset:9344
	v_lshl_add_u64 v[72:73], v[118:119], 0, v[130:131]
	s_waitcnt lgkmcnt(0)
	v_sub_f32_e32 v71, v91, v68
	v_sub_f32_e32 v70, v90, v68
	v_sub_f32_e32 v75, v89, v68
	v_sub_f32_e32 v74, v88, v68
	v_pk_mul_f32 v[74:75], v[68:69], v[74:75] op_sel:[1,0]
	v_pk_mul_f32 v[68:69], v[68:69], v[70:71] op_sel:[1,0]
	v_pk_fma_f32 v[74:75], v[92:93], v[74:75], v[100:101]
	v_pk_fma_f32 v[68:69], v[94:95], v[68:69], v[102:103]
	s_nop 0
	v_cndmask_b32_e32 v71, v147, v69, vcc
	v_cndmask_b32_e32 v70, v147, v68, vcc
	v_cndmask_b32_e32 v69, v147, v75, vcc
	v_cndmask_b32_e32 v68, v147, v74, vcc
	global_store_dwordx4 v[116:117], v[68:71], off offset:64 sc0 sc1
	s_nop 1
	v_pk_fma_f32 v[70:71], v[62:63], v[70:71], v[2:3]
	v_pk_fma_f32 v[68:69], v[60:61], v[68:69], v[0:1]
	s_nop 0
	v_cvt_pk_bf16_f32 v68, v68, v69
	v_cvt_pk_bf16_f32 v69, v70, v71
	v_lshl_add_u64 v[70:71], v[72:73], 1, s[6:7]
	global_store_dwordx2 v[70:71], v[68:69], off
	ds_read_b64 v[68:69], v149 offset:9472
	v_lshl_add_u64 v[72:73], v[122:123], 0, v[130:131]
	s_waitcnt lgkmcnt(0)
	v_sub_f32_e32 v71, v99, v68
	v_sub_f32_e32 v70, v98, v68
	v_sub_f32_e32 v75, v97, v68
	v_sub_f32_e32 v74, v96, v68
	v_pk_mul_f32 v[74:75], v[68:69], v[74:75] op_sel:[1,0]
	v_pk_mul_f32 v[68:69], v[68:69], v[70:71] op_sel:[1,0]
	v_pk_fma_f32 v[74:75], v[92:93], v[74:75], v[100:101]
	v_pk_fma_f32 v[68:69], v[94:95], v[68:69], v[102:103]
	s_nop 0
	v_cndmask_b32_e32 v71, v147, v69, vcc
	v_cndmask_b32_e32 v70, v147, v68, vcc
	v_cndmask_b32_e32 v69, v147, v75, vcc
	v_cndmask_b32_e32 v68, v147, v74, vcc
	global_store_dwordx4 v[120:121], v[68:71], off offset:64 sc0 sc1
	s_nop 1
	v_pk_fma_f32 v[70:71], v[62:63], v[70:71], v[2:3]
	v_pk_fma_f32 v[68:69], v[60:61], v[68:69], v[0:1]
	s_nop 0
	v_cvt_pk_bf16_f32 v68, v68, v69
	v_cvt_pk_bf16_f32 v69, v70, v71
	v_lshl_add_u64 v[70:71], v[72:73], 1, s[6:7]
	global_store_dwordx2 v[70:71], v[68:69], off
	ds_read_b64 v[68:69], v149 offset:9600
	v_lshl_add_u64 v[72:73], v[128:129], 0, v[130:131]
	s_waitcnt lgkmcnt(0)
	v_sub_f32_e32 v71, v107, v68
	v_sub_f32_e32 v70, v106, v68
	v_sub_f32_e32 v75, v105, v68
	v_sub_f32_e32 v74, v104, v68
	v_pk_mul_f32 v[74:75], v[68:69], v[74:75] op_sel:[1,0]
	v_pk_mul_f32 v[68:69], v[68:69], v[70:71] op_sel:[1,0]
	v_pk_fma_f32 v[74:75], v[92:93], v[74:75], v[100:101]
	v_pk_fma_f32 v[68:69], v[94:95], v[68:69], v[102:103]
	s_nop 0
	v_cndmask_b32_e32 v71, v147, v69, vcc
	v_cndmask_b32_e32 v70, v147, v68, vcc
	v_cndmask_b32_e32 v69, v147, v75, vcc
	v_cndmask_b32_e32 v68, v147, v74, vcc
	v_pk_fma_f32 v[2:3], v[62:63], v[70:71], v[2:3]
	v_pk_fma_f32 v[0:1], v[60:61], v[68:69], v[0:1]
	global_store_dwordx4 v[124:125], v[68:71], off offset:64 sc0 sc1
	v_cvt_pk_bf16_f32 v0, v0, v1
	v_cvt_pk_bf16_f32 v1, v2, v3
	v_lshl_add_u64 v[2:3], v[72:73], 1, s[6:7]
	global_store_dwordx2 v[2:3], v[0:1], off
	global_load_dwordx4 v[80:83], v[172:173], off offset:512
	global_load_dwordx4 v[60:63], v[156:157], off offset:512
	global_load_dwordx4 v[68:71], v[158:159], off offset:512
	s_nop 0
	global_load_dwordx4 v[0:3], v[126:127], off offset:512
	ds_read_b64 v[84:85], v149 offset:8192
	v_or_b32_e32 v74, 0x80, v154
	v_ashrrev_i32_e32 v75, 31, v74
	v_lshl_add_u64 v[86:87], v[170:171], 0, v[74:75]
	s_waitcnt lgkmcnt(0)
	v_sub_f32_e32 v89, v31, v84
	v_sub_f32_e32 v88, v30, v84
	v_sub_f32_e32 v29, v29, v84
	v_sub_f32_e32 v28, v28, v84
	v_pk_mul_f32 v[28:29], v[84:85], v[28:29] op_sel:[1,0]
	s_waitcnt vmcnt(0)
; __device__ __forceinline__ unsigned cvt_pk_bf16(float lo, float hi) { unsigned r; asm volatile("v_cvt_pk_bf16_f32 %0, %1, %2" : "=v"(r) : "v"(lo), "v"(hi)); return r; }
;     __device__ __forceinline__ void fused(f32x4 (&acc)[2][2][4][2], const Unit& u, int wr, int wc, int fr, int fq, PG8_LAS unsigned char* lds, int wid, int lane) const {
;     ...
; #pragma unroll
;         for (int bj = 0; bj < 2; ++bj)
; #pragma unroll
;             for (int n = 0; n < 2; ++n) {
;                 const int col = col0 + bj * HALF + n * 16;
;                 const f32x4 lg = *(const f32x4*)(lng + col), lb = *(const f32x4*)(lnb + col);
;                 f32x4 sc1 = (f32x4){1.f, 1.f, 1.f, 1.f}, sh = (f32x4){0.f, 0.f, 0.f, 0.f};
;                 if (DO_U) { sc1 = *(const f32x4*)(msc + mo + col) + 1.0f; sh = *(const f32x4*)(msh + mo + col); }
; #pragma unroll
;                 for (int ai = 0; ai < 2; ++ai)
; #pragma unroll
;                     for (int m = 0; m < 4; ++m) { const int r = ai * HALF + wr * 64 + m * 16 + fr; const f32x2v sr = S[r]; const size_t off = (size_t)(u.pm * BM + r) * 1024 + col;
;                         f32x4 y = (acc[ai][bj][m][n] - sr.x) * sr.y * lg + lb; if (bad) y = (f32x4){qnan, qnan, qnan, qnan};
;                         *(f32x4*)(out + off) = y;
;                         if (DO_U) { const f32x4 uu = y * sc1 + sh; u32x2v w; w.x = cvt_pk_bf16(uu[0], uu[1]); w.y = cvt_pk_bf16(uu[2], uu[3]); *(u32x2v*)(U + off) = w; } }
	v_pk_add_f32 v[30:31], v[80:81], 1.0 op_sel_hi:[1,0]
	v_pk_mul_f32 v[80:81], v[84:85], v[88:89] op_sel:[1,0]
	v_pk_fma_f32 v[28:29], v[60:61], v[28:29], v[68:69]
	v_pk_fma_f32 v[80:81], v[62:63], v[80:81], v[70:71]
	v_pk_add_f32 v[72:73], v[82:83], 1.0 op_sel_hi:[1,0]
	v_cndmask_b32_e32 v83, v147, v81, vcc
	v_cndmask_b32_e32 v82, v147, v80, vcc
	v_cndmask_b32_e32 v81, v147, v29, vcc
	v_cndmask_b32_e32 v80, v147, v28, vcc
	global_store_dwordx4 v[166:167], v[80:83], off offset:512 sc0 sc1
	v_pk_fma_f32 v[28:29], v[72:73], v[82:83], v[2:3]
	s_nop 0
	v_pk_fma_f32 v[80:81], v[30:31], v[80:81], v[0:1]
	s_nop 0
	v_cvt_pk_bf16_f32 v80, v80, v81
	v_cvt_pk_bf16_f32 v81, v28, v29
	v_lshl_add_u64 v[28:29], v[86:87], 1, s[6:7]
	global_store_dwordx2 v[28:29], v[80:81], off
	ds_read_b64 v[28:29], v149 offset:8320
	v_lshl_add_u64 v[80:81], v[168:169], 0, v[74:75]
	s_waitcnt lgkmcnt(0)
	v_sub_f32_e32 v39, v39, v28
	v_sub_f32_e32 v38, v38, v28
	v_sub_f32_e32 v37, v37, v28
	v_sub_f32_e32 v36, v36, v28
	v_pk_mul_f32 v[36:37], v[28:29], v[36:37] op_sel:[1,0]
	v_pk_mul_f32 v[28:29], v[28:29], v[38:39] op_sel:[1,0]
	v_pk_fma_f32 v[36:37], v[60:61], v[36:37], v[68:69]
	v_pk_fma_f32 v[28:29], v[62:63], v[28:29], v[70:71]
	v_cndmask_b32_e32 v37, v147, v37, vcc
	v_cndmask_b32_e32 v39, v147, v29, vcc
	v_cndmask_b32_e32 v38, v147, v28, vcc
	v_cndmask_b32_e32 v36, v147, v36, vcc
	global_store_dwordx4 v[162:163], v[36:39], off offset:512 sc0 sc1
	v_pk_fma_f32 v[28:29], v[72:73], v[38:39], v[2:3]
	s_nop 0
	v_pk_fma_f32 v[36:37], v[30:31], v[36:37], v[0:1]
	s_nop 0
	v_cvt_pk_bf16_f32 v36, v36, v37
	v_cvt_pk_bf16_f32 v37, v28, v29
	v_lshl_add_u64 v[28:29], v[80:81], 1, s[6:7]
	global_store_dwordx2 v[28:29], v[36:37], off
	ds_read_b64 v[28:29], v149 offset:8448
	v_lshl_add_u64 v[80:81], v[164:165], 0, v[74:75]
	s_waitcnt lgkmcnt(0)
	v_sub_f32_e32 v37, v43, v28
	v_sub_f32_e32 v36, v42, v28
	v_sub_f32_e32 v39, v41, v28
	v_sub_f32_e32 v38, v40, v28
	v_pk_mul_f32 v[38:39], v[28:29], v[38:39] op_sel:[1,0]
	v_pk_mul_f32 v[28:29], v[28:29], v[36:37] op_sel:[1,0]
	v_pk_fma_f32 v[36:37], v[60:61], v[38:39], v[68:69]
	v_pk_fma_f32 v[28:29], v[62:63], v[28:29], v[70:71]
	v_cndmask_b32_e32 v37, v147, v37, vcc
	v_cndmask_b32_e32 v39, v147, v29, vcc
	v_cndmask_b32_e32 v38, v147, v28, vcc
	v_cndmask_b32_e32 v36, v147, v36, vcc
	global_store_dwordx4 v[160:161], v[36:39], off offset:512 sc0 sc1
	v_pk_fma_f32 v[28:29], v[72:73], v[38:39], v[2:3]
	v_lshl_add_u64 v[40:41], v[110:111], 0, v[74:75]
	v_pk_fma_f32 v[36:37], v[30:31], v[36:37], v[0:1]
	s_nop 0
	v_cvt_pk_bf16_f32 v36, v36, v37
	v_cvt_pk_bf16_f32 v37, v28, v29
	v_lshl_add_u64 v[28:29], v[80:81], 1, s[6:7]
	global_store_dwordx2 v[28:29], v[36:37], off
	ds_read_b64 v[28:29], v149 offset:8576
	s_waitcnt lgkmcnt(0)
	v_sub_f32_e32 v37, v51, v28
	v_sub_f32_e32 v36, v50, v28
	v_sub_f32_e32 v39, v49, v28
	v_sub_f32_e32 v38, v48, v28
	v_pk_mul_f32 v[38:39], v[28:29], v[38:39] op_sel:[1,0]
	v_pk_mul_f32 v[28:29], v[28:29], v[36:37] op_sel:[1,0]
	v_pk_fma_f32 v[36:37], v[60:61], v[38:39], v[68:69]
	v_pk_fma_f32 v[28:29], v[62:63], v[28:29], v[70:71]
	v_cndmask_b32_e32 v37, v147, v37, vcc
	v_cndmask_b32_e32 v39, v147, v29, vcc
	v_cndmask_b32_e32 v38, v147, v28, vcc
	v_cndmask_b32_e32 v36, v147, v36, vcc
	global_store_dwordx4 v[108:109], v[36:39], off offset:512 sc0 sc1
	v_pk_fma_f32 v[28:29], v[72:73], v[38:39], v[2:3]
	v_or_b32_e32 v48, 0x90, v154
	v_pk_fma_f32 v[36:37], v[30:31], v[36:37], v[0:1]
	v_ashrrev_i32_e32 v49, 31, v48
	v_cvt_pk_bf16_f32 v36, v36, v37
	v_cvt_pk_bf16_f32 v37, v28, v29
	v_lshl_add_u64 v[28:29], v[40:41], 1, s[6:7]
	global_store_dwordx2 v[28:29], v[36:37], off
	ds_read_b64 v[28:29], v149 offset:9216
	v_lshl_add_u64 v[40:41], v[114:115], 0, v[74:75]
	s_waitcnt lgkmcnt(0)
	v_sub_f32_e32 v37, v55, v28
	v_sub_f32_e32 v36, v54, v28
	v_sub_f32_e32 v39, v53, v28
	v_sub_f32_e32 v38, v52, v28
	v_pk_mul_f32 v[38:39], v[28:29], v[38:39] op_sel:[1,0]
	v_pk_mul_f32 v[28:29], v[28:29], v[36:37] op_sel:[1,0]
	v_pk_fma_f32 v[36:37], v[60:61], v[38:39], v[68:69]
	v_pk_fma_f32 v[28:29], v[62:63], v[28:29], v[70:71]
	v_cndmask_b32_e32 v37, v147, v37, vcc
	v_cndmask_b32_e32 v39, v147, v29, vcc
	v_cndmask_b32_e32 v38, v147, v28, vcc
	v_cndmask_b32_e32 v36, v147, v36, vcc
	global_store_dwordx4 v[112:113], v[36:39], off offset:512 sc0 sc1
	v_pk_fma_f32 v[28:29], v[72:73], v[38:39], v[2:3]
	v_lshl_add_u64 v[52:53], v[170:171], 0, v[48:49]
	v_pk_fma_f32 v[36:37], v[30:31], v[36:37], v[0:1]
	s_nop 0
	v_cvt_pk_bf16_f32 v36, v36, v37
	v_cvt_pk_bf16_f32 v37, v28, v29
	v_lshl_add_u64 v[28:29], v[40:41], 1, s[6:7]
	global_store_dwordx2 v[28:29], v[36:37], off
	ds_read_b64 v[28:29], v149 offset:9344
	v_lshl_add_u64 v[40:41], v[118:119], 0, v[74:75]
	s_waitcnt lgkmcnt(0)
	v_sub_f32_e32 v37, v59, v28
	v_sub_f32_e32 v36, v58, v28
	v_sub_f32_e32 v39, v57, v28
	v_sub_f32_e32 v38, v56, v28
	v_pk_mul_f32 v[38:39], v[28:29], v[38:39] op_sel:[1,0]
	v_pk_mul_f32 v[28:29], v[28:29], v[36:37] op_sel:[1,0]
	v_pk_fma_f32 v[36:37], v[60:61], v[38:39], v[68:69]
	v_pk_fma_f32 v[28:29], v[62:63], v[28:29], v[70:71]
	v_cndmask_b32_e32 v37, v147, v37, vcc
	v_cndmask_b32_e32 v39, v147, v29, vcc
	v_cndmask_b32_e32 v38, v147, v28, vcc
	v_cndmask_b32_e32 v36, v147, v36, vcc
	global_store_dwordx4 v[116:117], v[36:39], off offset:512 sc0 sc1
	v_pk_fma_f32 v[28:29], v[72:73], v[38:39], v[2:3]
	s_nop 0
	v_pk_fma_f32 v[36:37], v[30:31], v[36:37], v[0:1]
	s_nop 0
	v_cvt_pk_bf16_f32 v36, v36, v37
	v_cvt_pk_bf16_f32 v37, v28, v29
	v_lshl_add_u64 v[28:29], v[40:41], 1, s[6:7]
	global_store_dwordx2 v[28:29], v[36:37], off
	ds_read_b64 v[28:29], v149 offset:9472
	v_lshl_add_u64 v[40:41], v[122:123], 0, v[74:75]
	s_waitcnt lgkmcnt(0)
; __device__ __forceinline__ unsigned cvt_pk_bf16(float lo, float hi) { unsigned r; asm volatile("v_cvt_pk_bf16_f32 %0, %1, %2" : "=v"(r) : "v"(lo), "v"(hi)); return r; }
;     __device__ __forceinline__ void fused(f32x4 (&acc)[2][2][4][2], const Unit& u, int wr, int wc, int fr, int fq, PG8_LAS unsigned char* lds, int wid, int lane) const {
;     ...
; #pragma unroll
;         for (int bj = 0; bj < 2; ++bj)
; #pragma unroll
;             for (int n = 0; n < 2; ++n) {
;                 const int col = col0 + bj * HALF + n * 16;
;                 const f32x4 lg = *(const f32x4*)(lng + col), lb = *(const f32x4*)(lnb + col);
;                 f32x4 sc1 = (f32x4){1.f, 1.f, 1.f, 1.f}, sh = (f32x4){0.f, 0.f, 0.f, 0.f};
;                 if (DO_U) { sc1 = *(const f32x4*)(msc + mo + col) + 1.0f; sh = *(const f32x4*)(msh + mo + col); }
; #pragma unroll
;                 for (int ai = 0; ai < 2; ++ai)
; #pragma unroll
;                     for (int m = 0; m < 4; ++m) { const int r = ai * HALF + wr * 64 + m * 16 + fr; const f32x2v sr = S[r]; const size_t off = (size_t)(u.pm * BM + r) * 1024 + col;
;                         f32x4 y = (acc[ai][bj][m][n] - sr.x) * sr.y * lg + lb; if (bad) y = (f32x4){qnan, qnan, qnan, qnan};
;                         *(f32x4*)(out + off) = y;
;                         if (DO_U) { const f32x4 uu = y * sc1 + sh; u32x2v w; w.x = cvt_pk_bf16(uu[0], uu[1]); w.y = cvt_pk_bf16(uu[2], uu[3]); *(u32x2v*)(U + off) = w; } }
	v_sub_f32_e32 v37, v67, v28
	v_sub_f32_e32 v36, v66, v28
	v_sub_f32_e32 v39, v65, v28
	v_sub_f32_e32 v38, v64, v28
	v_pk_mul_f32 v[38:39], v[28:29], v[38:39] op_sel:[1,0]
	v_pk_mul_f32 v[28:29], v[28:29], v[36:37] op_sel:[1,0]
	v_pk_fma_f32 v[36:37], v[60:61], v[38:39], v[68:69]
	v_pk_fma_f32 v[28:29], v[62:63], v[28:29], v[70:71]
	v_cndmask_b32_e32 v37, v147, v37, vcc
	v_cndmask_b32_e32 v39, v147, v29, vcc
	v_cndmask_b32_e32 v38, v147, v28, vcc
	v_cndmask_b32_e32 v36, v147, v36, vcc
	global_store_dwordx4 v[120:121], v[36:39], off offset:512 sc0 sc1
	v_pk_fma_f32 v[28:29], v[72:73], v[38:39], v[2:3]
	s_nop 0
	v_pk_fma_f32 v[36:37], v[30:31], v[36:37], v[0:1]
	s_nop 0
	v_cvt_pk_bf16_f32 v36, v36, v37
	v_cvt_pk_bf16_f32 v37, v28, v29
	v_lshl_add_u64 v[28:29], v[40:41], 1, s[6:7]
	global_store_dwordx2 v[28:29], v[36:37], off
	ds_read_b64 v[28:29], v149 offset:9600
	v_lshl_add_u64 v[40:41], v[128:129], 0, v[74:75]
	s_waitcnt lgkmcnt(0)
	v_sub_f32_e32 v37, v79, v28
	v_sub_f32_e32 v36, v78, v28
	v_sub_f32_e32 v39, v77, v28
	v_sub_f32_e32 v38, v76, v28
	v_pk_mul_f32 v[38:39], v[28:29], v[38:39] op_sel:[1,0]
	v_pk_mul_f32 v[28:29], v[28:29], v[36:37] op_sel:[1,0]
	v_pk_fma_f32 v[36:37], v[60:61], v[38:39], v[68:69]
	v_pk_fma_f32 v[28:29], v[62:63], v[28:29], v[70:71]
	v_cndmask_b32_e32 v37, v147, v37, vcc
	v_cndmask_b32_e32 v39, v147, v29, vcc
	v_cndmask_b32_e32 v38, v147, v28, vcc
	v_cndmask_b32_e32 v36, v147, v36, vcc
	v_pk_fma_f32 v[2:3], v[72:73], v[38:39], v[2:3]
	v_pk_fma_f32 v[0:1], v[30:31], v[36:37], v[0:1]
	global_store_dwordx4 v[124:125], v[36:39], off offset:512 sc0 sc1
	v_cvt_pk_bf16_f32 v0, v0, v1
	v_cvt_pk_bf16_f32 v1, v2, v3
	v_lshl_add_u64 v[2:3], v[40:41], 1, s[6:7]
	global_store_dwordx2 v[2:3], v[0:1], off
	global_load_dwordx4 v[40:43], v[172:173], off offset:576
	global_load_dwordx4 v[28:31], v[156:157], off offset:576
	global_load_dwordx4 v[36:39], v[158:159], off offset:576
	s_nop 0
	global_load_dwordx4 v[0:3], v[126:127], off offset:576
	ds_read_b64 v[50:51], v149 offset:8192
	s_waitcnt lgkmcnt(0)
	v_sub_f32_e32 v7, v7, v50
	v_sub_f32_e32 v6, v6, v50
	v_sub_f32_e32 v5, v5, v50
	v_sub_f32_e32 v4, v4, v50
	v_pk_mul_f32 v[4:5], v[50:51], v[4:5] op_sel:[1,0]
	v_pk_mul_f32 v[6:7], v[50:51], v[6:7] op_sel:[1,0]
	v_lshl_add_u64 v[50:51], v[168:169], 0, v[48:49]
	s_waitcnt vmcnt(0)
	v_pk_add_f32 v[42:43], v[42:43], 1.0 op_sel_hi:[1,0]
	v_pk_add_f32 v[40:41], v[40:41], 1.0 op_sel_hi:[1,0]
	v_pk_fma_f32 v[6:7], v[30:31], v[6:7], v[38:39]
	v_pk_fma_f32 v[4:5], v[28:29], v[4:5], v[36:37]
	v_cndmask_b32_e32 v7, v147, v7, vcc
	v_cndmask_b32_e32 v6, v147, v6, vcc
	v_cndmask_b32_e32 v5, v147, v5, vcc
	v_cndmask_b32_e32 v4, v147, v4, vcc
	global_store_dwordx4 v[166:167], v[4:7], off offset:576 sc0 sc1
	s_nop 1
	v_pk_fma_f32 v[6:7], v[42:43], v[6:7], v[2:3]
	v_pk_fma_f32 v[4:5], v[40:41], v[4:5], v[0:1]
	s_nop 0
	v_cvt_pk_bf16_f32 v4, v4, v5
	v_cvt_pk_bf16_f32 v5, v6, v7
	v_lshl_add_u64 v[6:7], v[52:53], 1, s[6:7]
	global_store_dwordx2 v[6:7], v[4:5], off
	ds_read_b64 v[4:5], v149 offset:8320
	s_waitcnt lgkmcnt(0)
	v_sub_f32_e32 v7, v11, v4
	v_sub_f32_e32 v6, v10, v4
	v_sub_f32_e32 v9, v9, v4
	v_sub_f32_e32 v8, v8, v4
	v_pk_mul_f32 v[8:9], v[4:5], v[8:9] op_sel:[1,0]
	v_pk_mul_f32 v[4:5], v[4:5], v[6:7] op_sel:[1,0]
	v_pk_fma_f32 v[8:9], v[28:29], v[8:9], v[36:37]
	v_pk_fma_f32 v[4:5], v[30:31], v[4:5], v[38:39]
	s_nop 0
	v_cndmask_b32_e32 v7, v147, v5, vcc
	v_cndmask_b32_e32 v6, v147, v4, vcc
	v_cndmask_b32_e32 v5, v147, v9, vcc
	v_cndmask_b32_e32 v4, v147, v8, vcc
	global_store_dwordx4 v[162:163], v[4:7], off offset:576 sc0 sc1
	v_lshl_add_u64 v[8:9], v[164:165], 0, v[48:49]
	s_nop 0
	v_pk_fma_f32 v[6:7], v[42:43], v[6:7], v[2:3]
	v_pk_fma_f32 v[4:5], v[40:41], v[4:5], v[0:1]
	s_nop 0
	v_cvt_pk_bf16_f32 v4, v4, v5
	v_cvt_pk_bf16_f32 v5, v6, v7
	v_lshl_add_u64 v[6:7], v[50:51], 1, s[6:7]
	global_store_dwordx2 v[6:7], v[4:5], off
	ds_read_b64 v[4:5], v149 offset:8448
	s_waitcnt lgkmcnt(0)
	v_sub_f32_e32 v7, v15, v4
	v_sub_f32_e32 v6, v14, v4
	v_sub_f32_e32 v11, v13, v4
	v_sub_f32_e32 v10, v12, v4
	v_pk_mul_f32 v[10:11], v[4:5], v[10:11] op_sel:[1,0]
	v_pk_mul_f32 v[4:5], v[4:5], v[6:7] op_sel:[1,0]
	v_pk_fma_f32 v[10:11], v[28:29], v[10:11], v[36:37]
	v_pk_fma_f32 v[4:5], v[30:31], v[4:5], v[38:39]
	s_nop 0
	v_cndmask_b32_e32 v7, v147, v5, vcc
	v_cndmask_b32_e32 v6, v147, v4, vcc
	v_cndmask_b32_e32 v5, v147, v11, vcc
	v_cndmask_b32_e32 v4, v147, v10, vcc
	global_store_dwordx4 v[160:161], v[4:7], off offset:576 sc0 sc1
	s_nop 1
	v_pk_fma_f32 v[6:7], v[42:43], v[6:7], v[2:3]
	v_pk_fma_f32 v[4:5], v[40:41], v[4:5], v[0:1]
	s_nop 0
	v_cvt_pk_bf16_f32 v4, v4, v5
	v_cvt_pk_bf16_f32 v5, v6, v7
	v_lshl_add_u64 v[6:7], v[8:9], 1, s[6:7]
	global_store_dwordx2 v[6:7], v[4:5], off
	ds_read_b64 v[4:5], v149 offset:8576
	v_lshl_add_u64 v[8:9], v[110:111], 0, v[48:49]
	s_waitcnt lgkmcnt(0)
; __device__ __forceinline__ unsigned cvt_pk_bf16(float lo, float hi) { unsigned r; asm volatile("v_cvt_pk_bf16_f32 %0, %1, %2" : "=v"(r) : "v"(lo), "v"(hi)); return r; }
;     __device__ __forceinline__ void fused(f32x4 (&acc)[2][2][4][2], const Unit& u, int wr, int wc, int fr, int fq, PG8_LAS unsigned char* lds, int wid, int lane) const {
;     ...
; #pragma unroll
;         for (int bj = 0; bj < 2; ++bj)
; #pragma unroll
;             for (int n = 0; n < 2; ++n) {
;                 const int col = col0 + bj * HALF + n * 16;
;                 const f32x4 lg = *(const f32x4*)(lng + col), lb = *(const f32x4*)(lnb + col);
;                 f32x4 sc1 = (f32x4){1.f, 1.f, 1.f, 1.f}, sh = (f32x4){0.f, 0.f, 0.f, 0.f};
;                 if (DO_U) { sc1 = *(const f32x4*)(msc + mo + col) + 1.0f; sh = *(const f32x4*)(msh + mo + col); }
; #pragma unroll
;                 for (int ai = 0; ai < 2; ++ai)
; #pragma unroll
;                     for (int m = 0; m < 4; ++m) { const int r = ai * HALF + wr * 64 + m * 16 + fr; const f32x2v sr = S[r]; const size_t off = (size_t)(u.pm * BM + r) * 1024 + col;
;                         f32x4 y = (acc[ai][bj][m][n] - sr.x) * sr.y * lg + lb; if (bad) y = (f32x4){qnan, qnan, qnan, qnan};
;                         *(f32x4*)(out + off) = y;
;                         if (DO_U) { const f32x4 uu = y * sc1 + sh; u32x2v w; w.x = cvt_pk_bf16(uu[0], uu[1]); w.y = cvt_pk_bf16(uu[2], uu[3]); *(u32x2v*)(U + off) = w; } }
	v_sub_f32_e32 v7, v19, v4
	v_sub_f32_e32 v6, v18, v4
	v_sub_f32_e32 v11, v17, v4
	v_sub_f32_e32 v10, v16, v4
	v_pk_mul_f32 v[10:11], v[4:5], v[10:11] op_sel:[1,0]
	v_pk_mul_f32 v[4:5], v[4:5], v[6:7] op_sel:[1,0]
	v_pk_fma_f32 v[10:11], v[28:29], v[10:11], v[36:37]
	v_pk_fma_f32 v[4:5], v[30:31], v[4:5], v[38:39]
	s_nop 0
	v_cndmask_b32_e32 v7, v147, v5, vcc
	v_cndmask_b32_e32 v6, v147, v4, vcc
	v_cndmask_b32_e32 v5, v147, v11, vcc
	v_cndmask_b32_e32 v4, v147, v10, vcc
	global_store_dwordx4 v[108:109], v[4:7], off offset:576 sc0 sc1
	s_nop 1
	v_pk_fma_f32 v[6:7], v[42:43], v[6:7], v[2:3]
	v_pk_fma_f32 v[4:5], v[40:41], v[4:5], v[0:1]
	s_nop 0
	v_cvt_pk_bf16_f32 v4, v4, v5
	v_cvt_pk_bf16_f32 v5, v6, v7
	v_lshl_add_u64 v[6:7], v[8:9], 1, s[6:7]
	global_store_dwordx2 v[6:7], v[4:5], off
	ds_read_b64 v[4:5], v149 offset:9216
	v_lshl_add_u64 v[8:9], v[114:115], 0, v[48:49]
	s_waitcnt lgkmcnt(0)
	v_sub_f32_e32 v7, v23, v4
	v_sub_f32_e32 v6, v22, v4
	v_sub_f32_e32 v11, v21, v4
	v_sub_f32_e32 v10, v20, v4
	v_pk_mul_f32 v[10:11], v[4:5], v[10:11] op_sel:[1,0]
	v_pk_mul_f32 v[4:5], v[4:5], v[6:7] op_sel:[1,0]
	v_pk_fma_f32 v[10:11], v[28:29], v[10:11], v[36:37]
	v_pk_fma_f32 v[4:5], v[30:31], v[4:5], v[38:39]
	s_nop 0
	v_cndmask_b32_e32 v7, v147, v5, vcc
	v_cndmask_b32_e32 v6, v147, v4, vcc
	v_cndmask_b32_e32 v5, v147, v11, vcc
	v_cndmask_b32_e32 v4, v147, v10, vcc
	global_store_dwordx4 v[112:113], v[4:7], off offset:576 sc0 sc1
	s_nop 1
	v_pk_fma_f32 v[6:7], v[42:43], v[6:7], v[2:3]
	v_pk_fma_f32 v[4:5], v[40:41], v[4:5], v[0:1]
	s_nop 0
	v_cvt_pk_bf16_f32 v4, v4, v5
	v_cvt_pk_bf16_f32 v5, v6, v7
	v_lshl_add_u64 v[6:7], v[8:9], 1, s[6:7]
	global_store_dwordx2 v[6:7], v[4:5], off
	ds_read_b64 v[4:5], v149 offset:9344
	v_lshl_add_u64 v[8:9], v[118:119], 0, v[48:49]
	s_waitcnt lgkmcnt(0)
	v_sub_f32_e32 v7, v27, v4
	v_sub_f32_e32 v6, v26, v4
	v_sub_f32_e32 v11, v25, v4
	v_sub_f32_e32 v10, v24, v4
	v_pk_mul_f32 v[10:11], v[4:5], v[10:11] op_sel:[1,0]
	v_pk_mul_f32 v[4:5], v[4:5], v[6:7] op_sel:[1,0]
	v_pk_fma_f32 v[10:11], v[28:29], v[10:11], v[36:37]
	v_pk_fma_f32 v[4:5], v[30:31], v[4:5], v[38:39]
	s_nop 0
	v_cndmask_b32_e32 v7, v147, v5, vcc
	v_cndmask_b32_e32 v6, v147, v4, vcc
	v_cndmask_b32_e32 v5, v147, v11, vcc
	v_cndmask_b32_e32 v4, v147, v10, vcc
	global_store_dwordx4 v[116:117], v[4:7], off offset:576 sc0 sc1
	s_nop 1
	v_pk_fma_f32 v[6:7], v[42:43], v[6:7], v[2:3]
	v_pk_fma_f32 v[4:5], v[40:41], v[4:5], v[0:1]
	s_nop 0
	v_cvt_pk_bf16_f32 v4, v4, v5
	v_cvt_pk_bf16_f32 v5, v6, v7
	v_lshl_add_u64 v[6:7], v[8:9], 1, s[6:7]
	global_store_dwordx2 v[6:7], v[4:5], off
	ds_read_b64 v[4:5], v149 offset:9472
	v_lshl_add_u64 v[8:9], v[122:123], 0, v[48:49]
	s_waitcnt lgkmcnt(0)
	v_sub_f32_e32 v7, v35, v4
	v_sub_f32_e32 v6, v34, v4
	v_sub_f32_e32 v11, v33, v4
	v_sub_f32_e32 v10, v32, v4
	v_pk_mul_f32 v[10:11], v[4:5], v[10:11] op_sel:[1,0]
	v_pk_mul_f32 v[4:5], v[4:5], v[6:7] op_sel:[1,0]
	v_pk_fma_f32 v[10:11], v[28:29], v[10:11], v[36:37]
	v_pk_fma_f32 v[4:5], v[30:31], v[4:5], v[38:39]
	s_nop 0
	v_cndmask_b32_e32 v7, v147, v5, vcc
	v_cndmask_b32_e32 v6, v147, v4, vcc
	v_cndmask_b32_e32 v5, v147, v11, vcc
	v_cndmask_b32_e32 v4, v147, v10, vcc
	global_store_dwordx4 v[120:121], v[4:7], off offset:576 sc0 sc1
	s_nop 1
	v_pk_fma_f32 v[6:7], v[42:43], v[6:7], v[2:3]
	v_pk_fma_f32 v[4:5], v[40:41], v[4:5], v[0:1]
	s_nop 0
	v_cvt_pk_bf16_f32 v4, v4, v5
	v_cvt_pk_bf16_f32 v5, v6, v7
	v_lshl_add_u64 v[6:7], v[8:9], 1, s[6:7]
	global_store_dwordx2 v[6:7], v[4:5], off
	ds_read_b64 v[4:5], v149 offset:9600
	v_lshl_add_u64 v[8:9], v[128:129], 0, v[48:49]
	s_waitcnt lgkmcnt(0)
	v_sub_f32_e32 v7, v47, v4
	v_sub_f32_e32 v6, v46, v4
	v_sub_f32_e32 v11, v45, v4
	v_sub_f32_e32 v10, v44, v4
	v_pk_mul_f32 v[10:11], v[4:5], v[10:11] op_sel:[1,0]
	v_pk_mul_f32 v[4:5], v[4:5], v[6:7] op_sel:[1,0]
	v_pk_fma_f32 v[10:11], v[28:29], v[10:11], v[36:37]
	v_pk_fma_f32 v[4:5], v[30:31], v[4:5], v[38:39]
	s_nop 0
	v_cndmask_b32_e32 v7, v147, v5, vcc
	v_cndmask_b32_e32 v6, v147, v4, vcc
	v_cndmask_b32_e32 v5, v147, v11, vcc
	v_cndmask_b32_e32 v4, v147, v10, vcc
	v_pk_fma_f32 v[2:3], v[42:43], v[6:7], v[2:3]
	v_pk_fma_f32 v[0:1], v[40:41], v[4:5], v[0:1]
	global_store_dwordx4 v[124:125], v[4:7], off offset:576 sc0 sc1
	v_cvt_pk_bf16_f32 v0, v0, v1
	v_cvt_pk_bf16_f32 v1, v2, v3
	v_lshl_add_u64 v[2:3], v[8:9], 1, s[6:7]
	global_store_dwordx2 v[2:3], v[0:1], off

;     __host__ __device__ bool next(int i, Unit& u) const {
;         const long L = (long)i * G + c; if (L >= nwg) return false;
;         int wgid = (int)L; { const int q = nwg / NXCD, r = nwg % NXCD, xcd = wgid % NXCD, off = wgid / NXCD; wgid = (xcd < r ? xcd * (q + 1) : r * (q + 1) + (xcd - r) * q) + off; }
;         const int nig = WGM * nN, gid = wgid / nig, fm = gid * WGM, gsz = (nM - fm) < WGM ? (nM - fm) : WGM;
;         u.pm = fm + ((wgid % nig) % gsz); u.pn = (wgid % nig) / gsz; return true;
.LBB0_484:
	s_or_b64 exec, exec, s[6:7]
	s_mov_b64 s[6:7], s[0:1]
	s_waitcnt lgkmcnt(0)
	s_barrier
	v_mov_b32_e32 v12, v144
	s_waitcnt vmcnt(0)
	v_mov_b64_e32 v[0:1], s[6:7]
	global_load_dwordx2 v[0:1], v[0:1], off offset:200
	s_movk_i32 s6, 0x400
	s_cmpk_gt_i32 s2, 0x1ff
	s_waitcnt vmcnt(0) lgkmcnt(0)
	v_readfirstlane_b32 s9, v1
	v_readfirstlane_b32 s8, v0
	s_nop 0
	v_readfirstlane_b32 s38, v12
	s_cbranch_scc1 .LBB0_514
	s_ashr_i32 s20, s2, 31
	s_lshr_b32 s7, s20, 29
	s_add_i32 s7, s2, s7
	s_and_b32 s10, s7, -8
	s_sub_i32 s12, s2, s10
	s_cmp_gt_i32 s12, -1
	s_cbranch_scc0 .LBB0_487
	s_lshl_b32 s14, s12, 6
	s_cbranch_execz .LBB0_488
	s_branch .LBB0_489

;     __device__ __forceinline__ void operator()(const f32x4 (&acc)[2][2][4][2], const Unit& u, int wr, int wc, int fr, int fq) const {
;         const int row0 = u.pm * BM + wr * 64 + fr; int colt = u.pn * BM; bf16_t* base = O;
;         float sc = 1.f; if (split_cols) { const int t = colt / split_cols; base += (size_t)t * split_stride; colt -= t * split_cols; if (t == 0) sc = scale0; }
;         const int col0 = colt + wc * 32 + 8 * fq, bcol0 = u.pn * BM + wc * 32 + 8 * fq;
;         f32x4 bv[2][2];
; #pragma unroll
;         for (int bj = 0; bj < 2; ++bj)
; #pragma unroll
;             for (int n = 0; n < 2; ++n) bv[bj][n] = bias ? *(const f32x4*)(bias + bcol0 + bj * HALF + 4 * n) : (f32x4){0.f, 0.f, 0.f, 0.f};
; #pragma unroll
;         for (int ai = 0; ai < 2; ++ai)
; #pragma unroll
;             for (int m = 0; m < 4; ++m) { bf16_t* rowp = base + (size_t)(row0 + ai * HALF + m * 16) * ldc + col0;
; #pragma unroll
;                 for (int bj = 0; bj < 2; ++bj) { f32x4 v0 = acc[ai][bj][m][0] + bv[bj][0], v1 = acc[ai][bj][m][1] + bv[bj][1];
;                     if (ACT == 1) { f32x2 a = gelu_pk((f32x2){v0[0], v0[1]}), b = gelu_pk((f32x2){v0[2], v0[3]}), c = gelu_pk((f32x2){v1[0], v1[1]}), d = gelu_pk((f32x2){v1[2], v1[3]});
;                         v0 = (f32x4){a.x, a.y, b.x, b.y}; v1 = (f32x4){c.x, c.y, d.x, d.y}; }
;                     v0 = v0 * sc; v1 = v1 * sc; u32x4 w; w.x = cvt_pk_bf16(v0[0], v0[1]); w.y = cvt_pk_bf16(v0[2], v0[3]); w.z = cvt_pk_bf16(v1[0], v1[1]); w.w = cvt_pk_bf16(v1[2], v1[3]);
;                     *(u32x4*)(rowp + bj * HALF) = w; } }
; template <class Epi, class Sched, bool ALIGN_EPI = false, bool SP2 = false>
; __device__ __forceinline__ void gemm_phase(PG8_LAS unsigned char* lds, const Gemm g, const Sched& S, const Epi& E) {
;     ...
;         if constexpr (ALIGN_EPI) { if (wr == 0) PG8_BAR; }
;         if constexpr (!Epi::AFTER_DRAIN) { E(acc, cur, wr, wc, fr, fq); S.done(cur); }
;         if (!has_next) break;
; #pragma unroll
;         for (int a = 0; a < 2; ++a)
; #pragma unroll
;             for (int b = 0; b < 2; ++b)
; #pragma unroll
;                 for (int m = 0; m < 4; ++m)
; #pragma unroll
;                     for (int n = 0; n < 2; ++n) acc[a][b][m][n] = (f32x4){0.f, 0.f, 0.f, 0.f};
;         cur = nxt; cA = nA; cB = nB; ++ui;
;         if constexpr (ALIGN_EPI) { if (wr == 1) PG8_BAR; }
.LBB0_510:
	v_lshl_add_u32 v24, s73, 8, v147
	v_lshl_or_b32 v16, s76, 8, v151
	v_ashrrev_i32_e32 v17, 31, v16
	v_ashrrev_i32_e32 v25, 31, v24
	v_lshl_add_u64 v[26:27], v[16:17], 1, s[16:17]
	v_lshlrev_b64 v[16:17], 12, v[24:25]
	v_lshl_add_u64 v[168:169], v[26:27], 0, v[16:17]
	v_cvt_pk_bf16_f32 v16, v124, v125
	v_cvt_pk_bf16_f32 v17, v126, v127
	v_cvt_pk_bf16_f32 v18, v120, v121
	v_cvt_pk_bf16_f32 v19, v122, v123
	global_store_dwordx4 v[168:169], v[16:19], off sc0 sc1
	s_nop 1
	v_cvt_pk_bf16_f32 v16, v158, v159
	v_cvt_pk_bf16_f32 v17, v156, v157
	v_cvt_pk_bf16_f32 v18, v162, v163
	v_cvt_pk_bf16_f32 v19, v160, v161
	global_store_dwordx4 v[168:169], v[16:19], off offset:256 sc0 sc1
	s_nop 1
	v_or_b32_e32 v16, 16, v24
	v_ashrrev_i32_e32 v17, 31, v16
	v_lshlrev_b64 v[16:17], 12, v[16:17]
	v_lshl_add_u64 v[120:121], v[26:27], 0, v[16:17]
	v_cvt_pk_bf16_f32 v16, v102, v103
	v_cvt_pk_bf16_f32 v17, v100, v101
	v_cvt_pk_bf16_f32 v18, v110, v111
	v_cvt_pk_bf16_f32 v19, v108, v109
	global_store_dwordx4 v[120:121], v[16:19], off sc0 sc1
	s_nop 1
	v_cvt_pk_bf16_f32 v16, v114, v115
	v_cvt_pk_bf16_f32 v17, v112, v113
	v_cvt_pk_bf16_f32 v18, v118, v119
	v_cvt_pk_bf16_f32 v19, v116, v117
	global_store_dwordx4 v[120:121], v[16:19], off offset:256 sc0 sc1
	s_nop 1
	v_or_b32_e32 v16, 32, v24
	v_ashrrev_i32_e32 v17, 31, v16
	v_lshlrev_b64 v[16:17], 12, v[16:17]
	v_lshl_add_u64 v[100:101], v[26:27], 0, v[16:17]
	v_cvt_pk_bf16_f32 v16, v86, v87
	v_cvt_pk_bf16_f32 v17, v84, v85
	v_cvt_pk_bf16_f32 v18, v94, v95
	v_cvt_pk_bf16_f32 v19, v92, v93
	global_store_dwordx4 v[100:101], v[16:19], off sc0 sc1
	s_nop 1
	v_cvt_pk_bf16_f32 v16, v98, v99
	v_cvt_pk_bf16_f32 v17, v96, v97
	v_cvt_pk_bf16_f32 v18, v106, v107
	v_cvt_pk_bf16_f32 v19, v104, v105
	global_store_dwordx4 v[100:101], v[16:19], off offset:256 sc0 sc1
	s_nop 1
	v_or_b32_e32 v16, 48, v24
	v_ashrrev_i32_e32 v17, 31, v16
	v_lshlrev_b64 v[16:17], 12, v[16:17]
	v_lshl_add_u64 v[24:25], v[26:27], 0, v[16:17]
	v_cvt_pk_bf16_f32 v16, v74, v75
	v_cvt_pk_bf16_f32 v17, v72, v73
	v_cvt_pk_bf16_f32 v18, v78, v79
	v_cvt_pk_bf16_f32 v19, v76, v77
	global_store_dwordx4 v[24:25], v[16:19], off sc0 sc1
	v_add_co_u32_e32 v26, vcc, s70, v168
	s_nop 0
	v_cvt_pk_bf16_f32 v16, v68, v69
	v_cvt_pk_bf16_f32 v17, v70, v71
	v_cvt_pk_bf16_f32 v18, v64, v65
	v_cvt_pk_bf16_f32 v19, v66, v67
	global_store_dwordx4 v[24:25], v[16:19], off offset:256 sc0 sc1
	v_addc_co_u32_e32 v27, vcc, 0, v169, vcc
	s_nop 0
	v_cvt_pk_bf16_f32 v16, v60, v61
	v_cvt_pk_bf16_f32 v17, v62, v63
	v_lshl_add_u64 v[24:25], v[168:169], 0, s[40:41]
	v_cvt_pk_bf16_f32 v18, v56, v57
	v_cvt_pk_bf16_f32 v19, v58, v59
	global_store_dwordx4 v[26:27], v[16:19], off sc0 sc1
	v_add_co_u32_e32 v26, vcc, s71, v168
	s_nop 0
	v_cvt_pk_bf16_f32 v16, v82, v83
	v_cvt_pk_bf16_f32 v17, v80, v81
	v_cvt_pk_bf16_f32 v18, v90, v91
	v_cvt_pk_bf16_f32 v19, v88, v89
	global_store_dwordx4 v[24:25], v[16:19], off offset:256 sc0 sc1
	v_addc_co_u32_e32 v27, vcc, 0, v169, vcc
	s_nop 0
	v_cvt_pk_bf16_f32 v16, v38, v39
	v_cvt_pk_bf16_f32 v17, v36, v37
	v_lshl_add_u64 v[24:25], v[168:169], 0, s[42:43]
	v_cvt_pk_bf16_f32 v18, v46, v47
	v_cvt_pk_bf16_f32 v19, v44, v45
	global_store_dwordx4 v[26:27], v[16:19], off sc0 sc1
	s_nop 1
	v_cvt_pk_bf16_f32 v16, v50, v51
	v_cvt_pk_bf16_f32 v17, v48, v49
	v_cvt_pk_bf16_f32 v18, v54, v55
	v_cvt_pk_bf16_f32 v19, v52, v53
	global_store_dwordx4 v[24:25], v[16:19], off offset:256 sc0 sc1
	v_lshl_add_u64 v[24:25], v[168:169], 0, s[44:45]
	s_nop 0
	v_cvt_pk_bf16_f32 v16, v22, v23
	v_cvt_pk_bf16_f32 v17, v20, v21
	v_add_co_u32_e32 v20, vcc, s72, v168
	v_cvt_pk_bf16_f32 v18, v30, v31
	v_cvt_pk_bf16_f32 v19, v28, v29
	s_nop 1
	v_addc_co_u32_e32 v21, vcc, 0, v169, vcc
	global_store_dwordx4 v[20:21], v[16:19], off sc0 sc1
	v_lshl_add_u64 v[20:21], v[168:169], 0, s[46:47]
	s_nop 0
	v_cvt_pk_bf16_f32 v16, v34, v35
	v_cvt_pk_bf16_f32 v17, v32, v33
	v_cvt_pk_bf16_f32 v18, v42, v43
	v_cvt_pk_bf16_f32 v19, v40, v41
	global_store_dwordx4 v[24:25], v[16:19], off offset:256 sc0 sc1
	s_nop 1
	v_cvt_pk_bf16_f32 v16, v10, v11
	v_cvt_pk_bf16_f32 v17, v8, v9
	v_add_co_u32_e32 v8, vcc, 0xb0000, v168
	v_cvt_pk_bf16_f32 v18, v14, v15
	v_cvt_pk_bf16_f32 v19, v12, v13
	s_nop 1
	v_addc_co_u32_e32 v9, vcc, 0, v169, vcc
	s_and_b64 vcc, exec, s[6:7]
	s_mov_b64 s[6:7], -1
	global_store_dwordx4 v[8:9], v[16:19], off sc0 sc1
	v_cvt_pk_bf16_f32 v4, v4, v5
	v_cvt_pk_bf16_f32 v5, v6, v7
	v_cvt_pk_bf16_f32 v6, v0, v1
	v_cvt_pk_bf16_f32 v7, v2, v3
	global_store_dwordx4 v[20:21], v[4:7], off offset:256 sc0 sc1
	s_cbranch_vccnz .LBB0_493
	s_andn2_b64 vcc, exec, s[14:15]
	s_cbranch_vccnz .LBB0_492
	s_barrier
	s_branch .LBB0_492

; #define LAS __attribute__((address_space(3)))
; __global__ void __launch_bounds__(NTHREADS, 2) mega_fwd(Args a_unused) {
;     ...
;     for (int rp_ = 0; rp_ < REP_EW; ++rp_) {
;     {
;         LAS v4u* rb = (LAS v4u*)(lds + wave * 4096); LAS unsigned short* hb = (LAS unsigned short*)rb;
;         float gq[6], gk[4];
; #pragma unroll
;         for (int j = 0; j < 3; ++j) { gq[2 * j] = ap->in[16][2 * lane + 128 * j]; gq[2 * j + 1] = ap->in[16][2 * lane + 128 * j + 1]; }
; #pragma unroll
;         for (int j = 0; j < 2; ++j) { gk[2 * j] = ap->in[17][2 * lane + 128 * j]; gk[2 * j + 1] = ap->in[17][2 * lane + 128 * j + 1]; }
;         v4u hv[4];
;         if (gw < M) {
; #pragma unroll
;             for (int j = 0; j < 4; ++j) hv[j] = ((const v4u*)(H + (size_t)gw * DINP))[lane + 64 * j];
;         }
.LBB0_566:
	s_or_b64 exec, exec, s[6:7]
	s_mov_b64 s[6:7], s[0:1]
	s_waitcnt lgkmcnt(0)
	s_barrier
	v_readfirstlane_b32 s8, v144
	v_mov_b64_e32 v[0:1], s[6:7]
	global_load_dwordx2 v[0:1], v[0:1], off offset:200
	s_lshr_b32 s8, s8, 6
	s_add_i32 s18, s8, s3
	v_lshrrev_b32_e32 v160, 3, v144
	v_and_b32_e32 v168, 15, v144
	s_cmpk_lt_i32 s18, 0x4000
	v_lshlrev_b32_e32 v128, 1, v141
	s_waitcnt vmcnt(0) lgkmcnt(0)
	v_readfirstlane_b32 s37, v1
	v_readfirstlane_b32 s36, v0
	s_cbranch_scc0 .LBB0_583
	v_mov_b64_e32 v[0:1], s[6:7]
	global_load_dwordx4 v[0:3], v[0:1], off offset:128
	s_lshl_b32 s12, s8, 12
	s_add_i32 s20, s12, 0
	s_add_u32 s40, s36, 0x3900000
	s_addc_u32 s41, s37, 0
	s_add_u32 s21, s36, 0x40000
	s_addc_u32 s59, s37, 0
	v_and_b32_e32 v4, 16, v144
	s_add_u32 s42, s36, 0xaa00000
	v_cmp_gt_u32_e64 s[8:9], 16, v143
	v_cmp_eq_u32_e32 vcc, 0, v4
	s_addc_u32 s43, s37, 0
	s_ashr_i32 s19, s18, 31
	s_and_b64 s[44:45], vcc, s[8:9]
	s_lshl_b64 s[12:13], s[18:19], 12
	v_mov_b32_e32 v149, 0
	s_add_u32 s12, s36, s12
	v_mov_b32_e32 v151, v149
	s_addc_u32 s13, s37, s13
	s_mov_b64 s[10:11], 0x5a00000
	s_mov_b32 s14, 0x5a00000
	v_lshl_add_u64 v[4:5], s[12:13], 0, v[150:151]
	v_lshl_add_u64 v[6:7], v[4:5], 0, s[10:11]
	v_add_co_u32_e32 v4, vcc, s14, v4
	global_load_dwordx4 v[8:11], v[6:7], off offset:1024
	global_load_dwordx4 v[12:15], v[6:7], off offset:2048
	v_addc_co_u32_e32 v5, vcc, 0, v5, vcc
	v_cmp_eq_u32_e64 s[6:7], 0, v143
	v_and_b32_e32 v78, 1, v160
	s_movk_i32 s16, 0x60
	v_cndmask_b32_e64 v24, -16, 16, s[6:7]
	v_mov_b32_e32 v129, v149
	s_lshl_b64 s[50:51], s[18:19], 6
	v_mov_b32_e32 v143, v149
	s_add_i32 s56, s18, s34
	s_mul_hi_i32 s35, s18, 0x300
	s_lshl_b64 s[54:55], s[18:19], 10
	s_ashr_i32 s57, s56, 31
	v_add_u32_e32 v76, s20, v150
	s_mul_i32 s38, s18, 0x300
	v_mov_b32_e32 v51, s35
	s_ashr_i32 s35, s34, 31
	s_lshl_b64 s[48:49], s[18:19], 9
	s_lshl_b64 s[56:57], s[56:57], 12
	s_mov_b32 s39, 0
	v_add_u32_e32 v77, v76, v24
	v_cmp_gt_u32_e64 s[10:11], 16, v141
	v_cmp_gt_u32_e64 s[12:13], 24, v141
	v_cmp_gt_u32_e64 s[14:15], 32, v141
	v_or_b32_e32 v50, s38, v142
	s_mul_hi_i32 s47, s34, 0x300
	s_mul_i32 s46, s34, 0x300
	v_or_b32_e32 v52, s48, v142
	v_mov_b32_e32 v53, s49
	s_lshl_b64 s[48:49], s[34:35], 9
	v_or_b32_e32 v60, s56, v150
	v_mov_b32_e32 v61, s57
	s_lshl_b64 s[56:57], s[34:35], 12
	s_mov_b32 s58, 0x3e38aa3b
	s_movk_i32 s64, 0x7fff
	s_mov_b32 s65, 0xbfb8aa3b
	s_mov_b32 s66, 0x42ce8ed0
	s_mov_b32 s67, 0xc2b17218
	v_mbcnt_hi_u32_b32 v84, -1, v145
	v_mov_b32_e32 v85, 0x3727c5ac
	s_mov_b32 s68, 0xf800000
	v_mov_b32_e32 v86, 0x260
	s_mov_b32 s69, 0xc200000
	s_mov_b32 s70, 0xce00000
	v_mov_b32_e32 v88, 0x7f800000
	s_waitcnt vmcnt(0) lgkmcnt(0)
	v_lshl_add_u64 v[0:1], v[0:1], 0, v[148:149]
	v_lshl_add_u64 v[2:3], v[2:3], 0, v[148:149]
	global_load_dwordx2 v[40:41], v[0:1], off
	global_load_dwordx2 v[42:43], v[0:1], off offset:512
	global_load_dwordx2 v[44:45], v[0:1], off offset:1024
	global_load_dwordx2 v[46:47], v[2:3], off
	global_load_dwordx2 v[48:49], v[2:3], off offset:512
	global_load_dwordx4 v[16:19], v[4:5], off
	global_load_dwordx4 v[20:23], v[6:7], off offset:3072
	v_xor_b32_e32 v0, 16, v141
	v_lshl_add_u32 v79, v0, 1, s20
	v_lshrrev_b32_e32 v0, 4, v141
	v_lshl_or_b32 v3, v78, 7, v146
	v_add_u32_e32 v2, s20, v24
	v_lshl_or_b32 v4, v0, 8, v3
	v_add_u32_e32 v80, s20, v4
	v_add_u32_e32 v81, v2, v4
	v_or_b32_e32 v4, 64, v141
	v_cmp_gt_u32_e64 s[16:17], s16, v4
	v_lshrrev_b32_e32 v4, 4, v4
	v_lshl_or_b32 v3, v4, 8, v3
	v_add_u32_e32 v82, s20, v3
	v_add_u32_e32 v83, v2, v3
	v_lshlrev_b32_e32 v2, 21, v4
	v_lshl_add_u64 v[4:5], s[50:51], 0, v[128:129]
	s_mov_b64 s[50:51], 0x3800000
	v_mov_b32_e32 v3, 0x60
	v_lshl_add_u64 v[54:55], v[4:5], 0, s[50:51]
	v_mad_i64_i32 v[4:5], s[52:53], s18, v3, v[142:143]
	s_mov_b64 s[52:53], 0x3600000
	v_mul_i32_i24_e32 v1, -14, v141
	v_lshlrev_b32_e32 v0, 21, v0
	v_lshl_add_u64 v[56:57], v[4:5], 0, s[52:53]
	v_or_b32_e32 v4, s54, v150
	v_mov_b32_e32 v5, s55
	s_mov_b64 s[54:55], 0x9a00000
	s_lshl_b64 s[50:51], s[34:35], 6
	s_mul_hi_i32 s53, s34, 0x60
	s_mul_i32 s52, s34, 0x60
	v_lshl_add_u64 v[58:59], v[4:5], 0, s[54:55]
	s_lshl_b64 s[54:55], s[34:35], 10
	s_mov_b32 s35, 0xffff0000
	v_lshlrev_b32_e32 v62, 1, v0
	v_lshlrev_b32_e32 v64, 1, v2
	v_add_u32_e32 v87, v76, v1
	s_branch .LBB0_569

; __global__ void __launch_bounds__(NTHREADS, 2) mega_fwd(Args a_unused) {
;     ...
;         for (int m = gw; m < M; m += NGW) {
;             const int b = m >> 13, t = m & 8191;
;             f32x4 c8[4];
; #pragma unroll
;             for (int j = 0; j < 4; ++j) c8[j] = *(const f32x4*)(CS8 + t * 16 + 4 * j);
;             const float c16 = CS16[t * 32 + (lane & 15)], s16 = CS16[t * 32 + 16 + (lane & 15)];
; #pragma unroll
;             for (int j = 0; j < 4; ++j) rb[lane + 64 * j] = hv[j];
;             if (m + NGW < M) {
; #pragma unroll
;                 for (int j = 0; j < 4; ++j) hv[j] = ((const v4u*)(H + (size_t)(m + NGW) * DINP))[lane + 64 * j];
;             }
.LBB0_569:
	s_and_b32 s19, s18, 0x1fff
	s_lshl_b32 s38, s19, 6
	s_add_u32 s60, s21, s38
	s_addc_u32 s61, s59, 0
	v_mov_b64_e32 v[0:1], s[60:61]
	global_load_dwordx4 v[36:39], v[0:1], off
	global_load_dwordx4 v[28:31], v[0:1], off offset:16
	global_load_dwordx4 v[32:35], v[0:1], off offset:32
	global_load_dwordx4 v[24:27], v[0:1], off offset:48
	v_lshlrev_b32_e32 v0, 2, v168
	v_lshl_or_b32 v148, s19, 7, v0
	v_lshl_add_u64 v[0:1], s[40:41], 0, v[148:149]
	global_load_dword v89, v[0:1], off
	global_load_dword v90, v[0:1], off offset:64
	s_add_i32 s71, s18, s34
	s_cmpk_gt_i32 s71, 0x3fff
	s_cselect_b64 s[60:61], -1, 0
	s_and_b64 vcc, exec, s[60:61]
	s_waitcnt vmcnt(0) lgkmcnt(0)
	ds_write_b128 v76, v[16:19]
	ds_write_b128 v76, v[8:11] offset:1024
	ds_write_b128 v76, v[12:15] offset:2048
	ds_write_b128 v76, v[20:23] offset:3072
	s_cbranch_vccnz .LBB0_571
	v_lshl_add_u64 v[0:1], s[36:37], 0, v[60:61]
	v_add_co_u32_e32 v0, vcc, 0x5a00000, v0
	s_nop 1
	v_addc_co_u32_e32 v1, vcc, 0, v1, vcc
	global_load_dwordx4 v[16:19], v[0:1], off
	global_load_dwordx4 v[8:11], v[0:1], off offset:1024
	global_load_dwordx4 v[12:15], v[0:1], off offset:2048
	global_load_dwordx4 v[20:23], v[0:1], off offset:3072

; __device__ __forceinline__ unsigned pk2(float lo, float hi) { return f2bf(lo) | (f2bf(hi) << 16); }
; __global__ void __launch_bounds__(NTHREADS, 2) mega_fwd(Args a_unused) {
;     ...
;                 const int base = 8 * lane, d0 = 8 * (lane & 7); float v[8];
; #pragma unroll
;                 for (int e = 0; e < 8; ++e) v[e] = bf2f(hb[base + e]);
;                 if (d0 < 16) {
; #pragma unroll
;                     for (int e = 0; e < 8; ++e) { const float c_ = c8[e >> 2][e & 3], s_ = c8[2 + (e >> 2)][e & 3]; const float pr = bf2f(hb[base + e + (d0 == 0 ? 8 : -8)]); v[e] = (d0 == 0) ? v[e] * c_ - pr * s_ : v[e] * c_ + pr * s_; }
;                 }
;                 v4u o; o.x = pk2(v[0] * QS_NSA, v[1] * QS_NSA); o.y = pk2(v[2] * QS_NSA, v[3] * QS_NSA); o.z = pk2(v[4] * QS_NSA, v[5] * QS_NSA); o.w = pk2(v[6] * QS_NSA, v[7] * QS_NSA);
;                 *(v4u*)(QN + (size_t)m * 512 + base) = o;
;             }
; #pragma unroll
;             for (int it = 0; it < 2; ++it) {
;                 const int ch = lane + 64 * it;
;                 if (ch < 96) {
;                     const int seg = ch >> 4, w = ch & 15, g = w >> 3, d0 = 8 * (w & 7), base = 512 + 128 * seg + 64 * g + d0; float v[8];
; #pragma unroll
;                     for (int e = 0; e < 8; ++e) v[e] = bf2f(hb[base + e]);
;                     if ((seg & 1) == 0 && d0 < 16) {
; #pragma unroll
;                         for (int e = 0; e < 8; ++e) { const float c_ = c8[e >> 2][e & 3], s_ = c8[2 + (e >> 2)][e & 3]; const float pr = bf2f(hb[base + e + (d0 == 0 ? 8 : -8)]); v[e] = (d0 == 0) ? v[e] * c_ - pr * s_ : v[e] * c_ + pr * s_; }
;                     }
;                     v4u o; o.x = pk2(v[0], v[1]); o.y = pk2(v[2], v[3]); o.z = pk2(v[4], v[5]); o.w = pk2(v[6], v[7]);
;                     *(v4u*)(KV6 + (size_t)seg * KV6_SEG + ((size_t)(b * 2 + g) * T + t) * 64 + d0) = o;
;                 }
;             }
.LBB0_573:
	s_or_b64 exec, exec, s[62:63]
	v_pk_mul_f32 v[2:3], v[70:71], s[58:59] op_sel_hi:[1,0]
	v_pk_mul_f32 v[6:7], v[66:67], s[58:59] op_sel_hi:[1,0]
	v_pk_mul_f32 v[0:1], v[0:1], s[58:59] op_sel_hi:[1,0]
	v_pk_mul_f32 v[4:5], v[68:69], s[58:59] op_sel_hi:[1,0]
	v_bfe_u32 v63, v7, 16, 1
	v_bfe_u32 v65, v6, 16, 1
	v_bfe_u32 v66, v3, 16, 1
	v_bfe_u32 v67, v2, 16, 1
	v_add3_u32 v67, v2, v67, s64
	v_add3_u32 v66, v3, v66, s64
	v_add3_u32 v2, v6, v65, s64
	v_add3_u32 v3, v7, v63, s64
	v_bfe_u32 v6, v0, 16, 1
	v_bfe_u32 v7, v1, 16, 1
	v_bfe_u32 v63, v4, 16, 1
	v_bfe_u32 v65, v5, 16, 1
	v_add3_u32 v5, v5, v65, s64
	v_add3_u32 v4, v4, v63, s64
	v_add3_u32 v1, v1, v7, s64
	v_add3_u32 v0, v0, v6, s64
	v_lshrrev_b32_e32 v0, 16, v0
	v_lshrrev_b32_e32 v1, 16, v1
	v_lshrrev_b32_e32 v4, 16, v4
	v_lshrrev_b32_e32 v5, 16, v5
	v_and_or_b32 v3, v3, s35, v5
	v_and_or_b32 v2, v2, s35, v4
	v_and_or_b32 v1, v66, s35, v1
	v_and_or_b32 v0, v67, s35, v0
	v_lshl_add_u64 v[4:5], s[36:37], 0, v[58:59]
	global_store_dwordx4 v[4:5], v[0:3], off sc0 sc1
	ds_read_b128 v[2:5], v80 offset:1024
	s_waitcnt lgkmcnt(0)
	v_lshlrev_b32_e32 v75, 16, v3
	v_lshlrev_b32_e32 v0, 16, v2
	v_and_b32_e32 v74, 0xffff0000, v2
	v_lshlrev_b32_e32 v73, 16, v4
	v_and_b32_e32 v72, 0xffff0000, v3
	v_lshlrev_b32_e32 v69, 16, v5
	v_and_b32_e32 v68, 0xffff0000, v4
	v_and_b32_e32 v70, 0xffff0000, v5
	s_and_saveexec_b64 s[62:63], s[44:45]
	s_cbranch_execz .LBB0_575
	ds_read_b128 v[2:5], v81 offset:1024
	v_mov_b32_e32 v6, v37
	v_mov_b32_e32 v7, v38
	s_waitcnt lgkmcnt(0)
	v_lshlrev_b32_e32 v1, 16, v2
	v_mul_f32_e32 v1, v32, v1
	v_and_b32_e32 v66, 0xffff0000, v2
	v_cndmask_b32_e64 v2, v1, -v1, s[6:7]
	v_lshlrev_b32_e32 v67, 16, v3
	v_fmac_f32_e32 v2, v36, v0
	v_mov_b32_e32 v0, v33
	v_mov_b32_e32 v1, v34
	v_pk_mul_f32 v[0:1], v[0:1], v[66:67]
	v_and_b32_e32 v71, 0xffff0000, v5
	v_pk_fma_f32 v[66:67], v[6:7], v[74:75], v[0:1] neg_lo:[0,0,1] neg_hi:[0,0,1]
	v_pk_fma_f32 v[0:1], v[6:7], v[74:75], v[0:1]
	v_and_b32_e32 v6, 0xffff0000, v3
	v_cndmask_b32_e64 v74, v0, v66, s[6:7]
	v_cndmask_b32_e64 v75, v1, v67, s[6:7]
	v_lshlrev_b32_e32 v7, 16, v4
	v_pk_mov_b32 v[66:67], v[34:35], v[24:25] op_sel:[1,0]
	v_pk_mov_b32 v[0:1], v[38:39], v[28:29] op_sel:[1,0]
	v_pk_mul_f32 v[6:7], v[66:67], v[6:7]
	s_nop 0
	v_pk_fma_f32 v[66:67], v[0:1], v[72:73], v[6:7] neg_lo:[0,0,1] neg_hi:[0,0,1]
	v_pk_fma_f32 v[0:1], v[0:1], v[72:73], v[6:7]
	v_lshlrev_b32_e32 v7, 16, v5
	v_cndmask_b32_e64 v72, v0, v66, s[6:7]
	v_cndmask_b32_e64 v73, v1, v67, s[6:7]
	v_and_b32_e32 v6, 0xffff0000, v4
	v_mov_b32_e32 v66, v25
	v_mov_b32_e32 v67, v26
	v_mov_b32_e32 v0, v29
	v_mov_b32_e32 v1, v30
	v_pk_mul_f32 v[6:7], v[66:67], v[6:7]
	s_nop 0
	v_pk_fma_f32 v[66:67], v[0:1], v[68:69], v[6:7] neg_lo:[0,0,1] neg_hi:[0,0,1]
	v_pk_fma_f32 v[0:1], v[0:1], v[68:69], v[6:7]
	s_nop 0
	v_cndmask_b32_e64 v68, v0, v66, s[6:7]
	v_cndmask_b32_e64 v69, v1, v67, s[6:7]
	v_mov_b32_e32 v0, v31
	v_mov_b32_e32 v1, v27
	v_pk_mul_f32 v[0:1], v[0:1], v[70:71]
	s_nop 0
	v_sub_f32_e32 v3, v0, v1
	v_add_f32_e32 v0, v0, v1
	v_cndmask_b32_e64 v70, v0, v3, s[6:7]
	s_waitcnt vmcnt(0)
	v_mov_b64_e32 v[0:1], v[2:3]
	v_mov_b64_e32 v[2:3], v[4:5]
	v_mov_b64_e32 v[4:5], v[6:7]
	v_mov_b64_e32 v[6:7], v[8:9]
.LBB0_575:
	s_or_b64 exec, exec, s[62:63]
	s_ashr_i32 s18, s18, 12
	v_and_or_b32 v2, s18, -2, v78
	v_ashrrev_i32_e32 v3, 31, v2
	v_bfe_u32 v1, v0, 16, 1
	v_lshlrev_b64 v[2:3], 20, v[2:3]
	v_add3_u32 v0, v0, v1, s64
	v_bfe_u32 v1, v74, 16, 1
	v_lshl_add_u64 v[2:3], s[42:43], 0, v[2:3]
	s_lshl_b32 s38, s19, 7
	v_lshrrev_b32_e32 v0, 16, v0
	v_add3_u32 v1, v74, v1, s64
	v_lshl_add_u64 v[2:3], v[2:3], 0, s[38:39]
	v_mov_b32_e32 v147, v149
	v_and_or_b32 v0, v1, s35, v0
	v_bfe_u32 v1, v75, 16, 1
	v_lshl_add_u64 v[66:67], v[2:3], 0, v[146:147]
	v_add3_u32 v1, v75, v1, s64
	v_bfe_u32 v2, v72, 16, 1
	v_lshrrev_b32_e32 v1, 16, v1
	v_add3_u32 v2, v72, v2, s64
	v_and_or_b32 v1, v2, s35, v1
	v_bfe_u32 v2, v73, 16, 1
	v_add3_u32 v2, v73, v2, s64
	v_bfe_u32 v3, v68, 16, 1
	v_lshrrev_b32_e32 v2, 16, v2
	v_add3_u32 v3, v68, v3, s64
	v_and_or_b32 v2, v3, s35, v2
	v_bfe_u32 v3, v69, 16, 1
	v_add3_u32 v3, v69, v3, s64
	v_bfe_u32 v4, v70, 16, 1
	v_lshrrev_b32_e32 v3, 16, v3
	v_add3_u32 v4, v70, v4, s64
	v_mov_b32_e32 v63, v149
	v_and_or_b32 v3, v4, s35, v3
	v_lshl_add_u64 v[4:5], v[66:67], 0, v[62:63]
	global_store_dwordx4 v[4:5], v[0:3], off sc0 sc1
	s_and_saveexec_b64 s[18:19], s[16:17]
	s_cbranch_execz .LBB0_579
	ds_read_b128 v[2:5], v82 offset:1024
	s_waitcnt lgkmcnt(0)
	v_lshlrev_b32_e32 v0, 16, v2
	v_lshlrev_b32_e32 v75, 16, v3
	v_and_b32_e32 v74, 0xffff0000, v2
	v_lshlrev_b32_e32 v73, 16, v4
	v_and_b32_e32 v72, 0xffff0000, v3
	v_lshlrev_b32_e32 v69, 16, v5
	v_and_b32_e32 v68, 0xffff0000, v4
	v_and_b32_e32 v70, 0xffff0000, v5
	s_and_saveexec_b64 s[62:63], s[44:45]
	s_cbranch_execz .LBB0_578
	ds_read_b128 v[2:5], v83 offset:1024
	v_mov_b32_e32 v6, v37
	v_mov_b32_e32 v7, v38
	s_waitcnt lgkmcnt(0)
	v_lshlrev_b32_e32 v1, 16, v2
	v_mul_f32_e32 v1, v32, v1
	v_and_b32_e32 v92, 0xffff0000, v2
	v_cndmask_b32_e64 v2, v1, -v1, s[6:7]
	v_lshlrev_b32_e32 v93, 16, v3
	v_fmac_f32_e32 v2, v36, v0
	v_mov_b32_e32 v0, v33
	v_mov_b32_e32 v1, v34
	v_pk_mul_f32 v[0:1], v[0:1], v[92:93]
	v_and_b32_e32 v71, 0xffff0000, v5
	v_pk_fma_f32 v[32:33], v[6:7], v[74:75], v[0:1] neg_lo:[0,0,1] neg_hi:[0,0,1]
	v_pk_fma_f32 v[0:1], v[6:7], v[74:75], v[0:1]
	v_and_b32_e32 v6, 0xffff0000, v3
	v_cndmask_b32_e64 v74, v0, v32, s[6:7]
	v_cndmask_b32_e64 v75, v1, v33, s[6:7]
	v_lshlrev_b32_e32 v7, 16, v4
	v_pk_mov_b32 v[32:33], v[34:35], v[24:25] op_sel:[1,0]
	v_pk_mov_b32 v[0:1], v[38:39], v[28:29] op_sel:[1,0]
	v_pk_mul_f32 v[6:7], v[32:33], v[6:7]
	v_mov_b32_e32 v24, v25
	v_pk_fma_f32 v[32:33], v[0:1], v[72:73], v[6:7] neg_lo:[0,0,1] neg_hi:[0,0,1]
	v_pk_fma_f32 v[0:1], v[0:1], v[72:73], v[6:7]
	v_lshlrev_b32_e32 v7, 16, v5
	v_and_b32_e32 v6, 0xffff0000, v4
	v_mov_b32_e32 v25, v26
	v_cndmask_b32_e64 v72, v0, v32, s[6:7]
	v_cndmask_b32_e64 v73, v1, v33, s[6:7]
	v_mov_b32_e32 v0, v29
	v_mov_b32_e32 v1, v30
	v_pk_mul_f32 v[6:7], v[24:25], v[6:7]
	v_mov_b32_e32 v26, v31
	v_pk_fma_f32 v[24:25], v[0:1], v[68:69], v[6:7] neg_lo:[0,0,1] neg_hi:[0,0,1]
	v_pk_fma_f32 v[0:1], v[0:1], v[68:69], v[6:7]
	s_nop 0
	v_cndmask_b32_e64 v68, v0, v24, s[6:7]
	v_cndmask_b32_e64 v69, v1, v25, s[6:7]
	v_pk_mul_f32 v[0:1], v[26:27], v[70:71]
	s_nop 0
	v_sub_f32_e32 v3, v0, v1
	v_add_f32_e32 v0, v0, v1
	v_cndmask_b32_e64 v70, v0, v3, s[6:7]
	s_waitcnt vmcnt(0)
	v_mov_b64_e32 v[0:1], v[2:3]
	v_mov_b64_e32 v[2:3], v[4:5]
	v_mov_b64_e32 v[4:5], v[6:7]
	v_mov_b64_e32 v[6:7], v[8:9]
; __device__ __forceinline__ unsigned pk2(float lo, float hi) { return f2bf(lo) | (f2bf(hi) << 16); }
; __global__ void __launch_bounds__(NTHREADS, 2) mega_fwd(Args a_unused) {
;     ...
;                     const int seg = ch >> 4, w = ch & 15, g = w >> 3, d0 = 8 * (w & 7), base = 512 + 128 * seg + 64 * g + d0; float v[8];
; #pragma unroll
;                     for (int e = 0; e < 8; ++e) v[e] = bf2f(hb[base + e]);
;                     if ((seg & 1) == 0 && d0 < 16) {
; #pragma unroll
;                         for (int e = 0; e < 8; ++e) { const float c_ = c8[e >> 2][e & 3], s_ = c8[2 + (e >> 2)][e & 3]; const float pr = bf2f(hb[base + e + (d0 == 0 ? 8 : -8)]); v[e] = (d0 == 0) ? v[e] * c_ - pr * s_ : v[e] * c_ + pr * s_; }
;                     }
;                     v4u o; o.x = pk2(v[0], v[1]); o.y = pk2(v[2], v[3]); o.z = pk2(v[4], v[5]); o.w = pk2(v[6], v[7]);
;                     *(v4u*)(KV6 + (size_t)seg * KV6_SEG + ((size_t)(b * 2 + g) * T + t) * 64 + d0) = o;
;                 }
;             }
;             if (lane < 24) GATES[(size_t)m * 24 + lane] = 1.f / (1.f + expf(-bf2f(hb[1280 + lane])));
.LBB0_578:
	s_or_b64 exec, exec, s[62:63]
	v_bfe_u32 v1, v0, 16, 1
	v_add3_u32 v0, v0, v1, s64
	v_bfe_u32 v1, v74, 16, 1
	v_lshrrev_b32_e32 v0, 16, v0
	v_add3_u32 v1, v74, v1, s64
	v_and_or_b32 v0, v1, s35, v0
	v_bfe_u32 v1, v75, 16, 1
	v_add3_u32 v1, v75, v1, s64
	v_bfe_u32 v2, v72, 16, 1
	v_lshrrev_b32_e32 v1, 16, v1
	v_add3_u32 v2, v72, v2, s64
	v_and_or_b32 v1, v2, s35, v1
	v_bfe_u32 v2, v73, 16, 1
	v_add3_u32 v2, v73, v2, s64
	v_bfe_u32 v3, v68, 16, 1
	v_lshrrev_b32_e32 v2, 16, v2
	v_add3_u32 v3, v68, v3, s64
	v_and_or_b32 v2, v3, s35, v2
	v_bfe_u32 v3, v69, 16, 1
	v_add3_u32 v3, v69, v3, s64
	v_bfe_u32 v4, v70, 16, 1
	v_lshrrev_b32_e32 v3, 16, v3
	v_add3_u32 v4, v70, v4, s64
	v_mov_b32_e32 v65, v149
	v_and_or_b32 v3, v4, s35, v3
	v_lshl_add_u64 v[4:5], v[66:67], 0, v[64:65]
	global_store_dwordx4 v[4:5], v[0:3], off sc0 sc1
.LBB0_579:
	s_or_b64 exec, exec, s[18:19]
	s_and_saveexec_b64 s[18:19], s[12:13]
	s_cbranch_execz .LBB0_581
	ds_read_u16 v0, v87 offset:2560
	s_waitcnt lgkmcnt(0)
	v_lshlrev_b32_e32 v0, 16, v0
	v_mul_f32_e32 v1, 0xbfb8aa3b, v0
	v_fma_f32 v2, v0, s65, -v1
	v_rndne_f32_e32 v3, v1
	v_fmac_f32_e32 v2, 0xb2a5705f, v0
	v_sub_f32_e32 v1, v1, v3
	v_add_f32_e32 v1, v1, v2
	v_cvt_i32_f32_e32 v3, v3
	v_exp_f32_e32 v1, v1
	v_cmp_nlt_f32_e32 vcc, s66, v0
	v_ldexp_f32 v1, v1, v3
	s_nop 0
	v_cndmask_b32_e32 v1, 0, v1, vcc
	v_cmp_ngt_f32_e32 vcc, s67, v0
	s_nop 1
	v_cndmask_b32_e32 v0, v88, v1, vcc
	v_add_f32_e32 v0, 1.0, v0
	v_div_scale_f32 v1, s[62:63], v0, v0, 1.0
	v_rcp_f32_e32 v2, v1
	v_div_scale_f32 v3, vcc, 1.0, v0, 1.0
	v_fma_f32 v4, -v1, v2, 1.0
	v_fmac_f32_e32 v2, v4, v2
	v_mul_f32_e32 v4, v3, v2
	v_fma_f32 v5, -v1, v4, v3
	v_fmac_f32_e32 v4, v5, v2
	v_fma_f32 v1, -v1, v4, v3
	v_div_fmas_f32 v1, v1, v2, v4
	v_div_fixup_f32 v2, v1, v0, 1.0
	v_lshl_add_u64 v[0:1], s[36:37], 0, v[56:57]
	global_store_dword v[0:1], v2, off
; __device__ __forceinline__ unsigned f2bf(float f) { unsigned u = __builtin_bit_cast(unsigned, f); return (u + 0x7fffu + ((u >> 16) & 1u)) >> 16; }
; __device__ __forceinline__ unsigned pk2(float lo, float hi) { return f2bf(lo) | (f2bf(hi) << 16); }
; __global__ void __launch_bounds__(NTHREADS, 2) mega_fwd(Args a_unused) {
;     ...
;             {
;                 float xv[6]; float ss = 0.f;
; #pragma unroll
;                 for (int j = 0; j < 3; ++j) { xv[2 * j] = bf2f(hb[1304 + 2 * lane + 128 * j]); xv[2 * j + 1] = bf2f(hb[1304 + 2 * lane + 128 * j + 1]); ss += xv[2 * j] * xv[2 * j] + xv[2 * j + 1] * xv[2 * j + 1]; }
;                 const float r = 1.f / sqrtf(wave_sum(ss) * (1.f / 384.f) + LN_EPS);
; #pragma unroll
;                 for (int j = 0; j < 3; ++j) { const int i = 2 * lane + 128 * j; *(unsigned*)(CQN + (size_t)m * 384 + i) = pk2(xv[2 * j] * r * gq[2 * j], xv[2 * j + 1] * r * gq[2 * j + 1]); }
;             }
;             {
;                 float xv[4]; float ss = 0.f;
; #pragma unroll
;                 for (int j = 0; j < 2; ++j) { xv[2 * j] = bf2f(hb[1688 + 2 * lane + 128 * j]); xv[2 * j + 1] = bf2f(hb[1688 + 2 * lane + 128 * j + 1]); ss += xv[2 * j] * xv[2 * j] + xv[2 * j + 1] * xv[2 * j + 1]; }
;                 const float r = 1.f / sqrtf(wave_sum(ss) * (1.f / 256.f) + LN_EPS);
; #pragma unroll
;                 for (int j = 0; j < 2; ++j) { const int i = 2 * lane + 128 * j; *(unsigned*)(CKVN + (size_t)m * 256 + i) = pk2(xv[2 * j] * r * gk[2 * j], xv[2 * j + 1] * r * gk[2 * j + 1]); }
;             }
;             if (lane < 32) {
;                 const float xs = bf2f(hb[1944 + lane]), pr = bf2f(hb[1944 + (lane ^ 16)]); const float c_ = c16, s_ = s16;
;                 const float r = (lane < 16) ? xs * c_ - pr * s_ : xs * c_ + pr * s_;
;                 KR[(size_t)m * 32 + lane] = (bf16)f2bf(r);
;             }
.LBB0_581:
	s_or_b64 exec, exec, s[18:19]
	v_add_u32_e32 v4, s20, v142
	v_add_u32_e32 v2, 48, v4
	ds_read2st64_b32 v[0:1], v2 offset0:10 offset1:11
	ds_read2st64_b32 v[2:3], v2 offset0:12 offset1:13
	v_xor_b32_e32 v26, 1, v84
	ds_read_b32 v4, v4 offset:3632
	s_waitcnt lgkmcnt(0)
	v_lshlrev_b32_e32 v5, 16, v0
	v_lshlrev_b32_e32 v6, 16, v1
	v_and_b32_e32 v0, 0xffff0000, v0
	v_and_b32_e32 v7, 0xffff0000, v1
	v_mul_f32_e32 v1, v5, v5
	v_mul_f32_e32 v24, v6, v6
	v_fmac_f32_e32 v1, v0, v0
	v_fmac_f32_e32 v24, v7, v7
	v_add_f32_e32 v1, v1, v24
	v_lshlrev_b32_e32 v24, 16, v2
	v_and_b32_e32 v2, 0xffff0000, v2
	v_mul_f32_e32 v25, v24, v24
	v_fmac_f32_e32 v25, v2, v2
	v_add_f32_e32 v1, v1, v25
	v_and_b32_e32 v25, 64, v84
	v_add_u32_e32 v25, 64, v25
	v_cmp_lt_i32_e32 vcc, v26, v25
	s_nop 1
	v_cndmask_b32_e32 v26, v84, v26, vcc
	v_lshlrev_b32_e32 v26, 2, v26
	ds_bpermute_b32 v27, v26, v1
	s_waitcnt lgkmcnt(0)
	v_add_f32_e32 v1, v1, v27
	v_xor_b32_e32 v27, 2, v84
	v_cmp_lt_i32_e32 vcc, v27, v25
	s_nop 1
	v_cndmask_b32_e32 v27, v84, v27, vcc
	v_lshlrev_b32_e32 v27, 2, v27
	ds_bpermute_b32 v28, v27, v1
	s_waitcnt lgkmcnt(0)
	v_add_f32_e32 v1, v1, v28
	v_xor_b32_e32 v28, 4, v84
	v_cmp_lt_i32_e32 vcc, v28, v25
	s_nop 1
	v_cndmask_b32_e32 v28, v84, v28, vcc
	v_lshlrev_b32_e32 v28, 2, v28
	ds_bpermute_b32 v29, v28, v1
	s_waitcnt lgkmcnt(0)
	v_add_f32_e32 v1, v1, v29
	v_xor_b32_e32 v29, 8, v84
	v_cmp_lt_i32_e32 vcc, v29, v25
	s_nop 1
	v_cndmask_b32_e32 v29, v84, v29, vcc
	v_lshlrev_b32_e32 v29, 2, v29
	ds_bpermute_b32 v30, v29, v1
	s_waitcnt lgkmcnt(0)
	v_add_f32_e32 v1, v1, v30
	v_xor_b32_e32 v30, 16, v84
	v_cmp_lt_i32_e32 vcc, v30, v25
	s_nop 1
	v_cndmask_b32_e32 v30, v84, v30, vcc
	v_lshlrev_b32_e32 v30, 2, v30
	ds_bpermute_b32 v31, v30, v1
	s_waitcnt lgkmcnt(0)
	v_add_f32_e32 v1, v1, v31
	v_xor_b32_e32 v31, 32, v84
	v_cmp_lt_i32_e32 vcc, v31, v25
	s_nop 1
	v_cndmask_b32_e32 v25, v84, v31, vcc
	v_lshlrev_b32_e32 v25, 2, v25
	ds_bpermute_b32 v31, v25, v1
	s_waitcnt lgkmcnt(0)
	v_add_f32_e32 v1, v1, v31
	v_fmamk_f32 v1, v1, 0x3b2aaaab, v85
	v_mul_f32_e32 v31, 0x4f800000, v1
	v_cmp_gt_f32_e32 vcc, s68, v1
	s_nop 1
	v_cndmask_b32_e32 v1, v1, v31, vcc
	v_sqrt_f32_e32 v31, v1
	s_nop 0
	v_add_u32_e32 v32, -1, v31
	v_fma_f32 v33, -v32, v31, v1
	v_cmp_ge_f32_e64 s[18:19], 0, v33
	v_add_u32_e32 v33, 1, v31
	s_nop 0
	v_cndmask_b32_e64 v32, v31, v32, s[18:19]
	v_fma_f32 v31, -v33, v31, v1
	v_cmp_lt_f32_e64 s[18:19], 0, v31
	s_nop 1
	v_cndmask_b32_e64 v31, v32, v33, s[18:19]
	v_mul_f32_e32 v32, 0x37800000, v31
	v_cndmask_b32_e32 v31, v31, v32, vcc
	v_cmp_class_f32_e32 vcc, v1, v86
	s_nop 1
	v_cndmask_b32_e32 v1, v31, v1, vcc
	v_div_scale_f32 v31, s[18:19], v1, v1, 1.0
	v_rcp_f32_e32 v32, v31
	s_nop 0
	v_fma_f32 v33, -v31, v32, 1.0
	v_fmac_f32_e32 v32, v33, v32
	v_div_scale_f32 v33, vcc, 1.0, v1, 1.0
	v_mul_f32_e32 v34, v33, v32
	v_fma_f32 v35, -v31, v34, v33
	v_fmac_f32_e32 v34, v35, v32
	v_fma_f32 v31, -v31, v34, v33
	v_div_fmas_f32 v31, v31, v32, v34
	v_div_fixup_f32 v31, v31, v1, 1.0
	v_mul_f32_e32 v1, v31, v5
	v_mul_f32_e32 v1, v1, v40
	v_bfe_u32 v5, v1, 16, 1
	v_add3_u32 v1, v1, v5, s64
	v_lshlrev_b32_e32 v5, 16, v3
	v_lshlrev_b32_e32 v33, 16, v4
	v_and_b32_e32 v3, 0xffff0000, v3
	v_mul_f32_e32 v32, v5, v5
	v_and_b32_e32 v4, 0xffff0000, v4
	v_mul_f32_e32 v34, v33, v33
	v_fmac_f32_e32 v32, v3, v3
	v_fmac_f32_e32 v34, v4, v4
	v_add_f32_e32 v32, v32, v34
	ds_bpermute_b32 v26, v26, v32
	v_mul_f32_e32 v0, v31, v0
	v_mul_f32_e32 v0, v0, v41
	v_mul_f32_e32 v6, v31, v6
	v_bfe_u32 v34, v0, 16, 1
	s_waitcnt lgkmcnt(0)
	v_add_f32_e32 v26, v32, v26
	ds_bpermute_b32 v27, v27, v26
	v_mul_f32_e32 v6, v6, v42
	v_mul_f32_e32 v7, v31, v7
	v_lshrrev_b32_e32 v1, 16, v1
	v_add3_u32 v0, v0, v34, s64
	s_waitcnt lgkmcnt(0)
	v_add_f32_e32 v26, v26, v27
	ds_bpermute_b32 v27, v28, v26
	v_mul_f32_e32 v7, v7, v43
	v_bfe_u32 v28, v6, 16, 1
	v_and_or_b32 v34, v0, s35, v1
	v_lshl_add_u64 v[0:1], s[36:37], 0, v[50:51]
	s_waitcnt lgkmcnt(0)
	v_add_f32_e32 v26, v26, v27
	ds_bpermute_b32 v27, v29, v26
	v_add3_u32 v6, v6, v28, s64
	v_bfe_u32 v28, v7, 16, 1
	v_add_co_u32_e32 v0, vcc, s69, v0
	s_waitcnt lgkmcnt(0)
	v_add_f32_e32 v26, v26, v27
	ds_bpermute_b32 v27, v30, v26
	v_lshrrev_b32_e32 v6, 16, v6
	v_add3_u32 v7, v7, v28, s64
	v_addc_co_u32_e32 v1, vcc, 0, v1, vcc
	v_and_or_b32 v6, v7, s35, v6
	s_waitcnt lgkmcnt(0)
	v_add_f32_e32 v7, v26, v27
	global_store_dword v[0:1], v6, off offset:256
	v_mul_f32_e32 v6, v31, v24
	ds_bpermute_b32 v24, v25, v7
	v_mul_f32_e32 v6, v6, v44
	v_mul_f32_e32 v2, v31, v2
	v_mul_f32_e32 v2, v2, v45
	v_bfe_u32 v25, v6, 16, 1
	s_waitcnt lgkmcnt(0)
	v_add_f32_e32 v7, v7, v24
	v_fmamk_f32 v7, v7, 0x3b800000, v85
	v_mul_f32_e32 v24, 0x4f800000, v7
	v_cmp_gt_f32_e32 vcc, s68, v7
	v_add3_u32 v6, v6, v25, s64
	v_bfe_u32 v25, v2, 16, 1
	v_cndmask_b32_e32 v7, v7, v24, vcc
	v_sqrt_f32_e32 v24, v7
	v_lshrrev_b32_e32 v6, 16, v6
	v_add3_u32 v2, v2, v25, s64
	v_and_or_b32 v2, v2, s35, v6
	v_add_u32_e32 v26, -1, v24
	v_fma_f32 v27, -v26, v24, v7
	v_cmp_ge_f32_e64 s[18:19], 0, v27
	v_add_u32_e32 v27, 1, v24
	global_store_dword v[0:1], v34, off
	v_cndmask_b32_e64 v26, v24, v26, s[18:19]
	v_fma_f32 v24, -v27, v24, v7
	v_cmp_lt_f32_e64 s[18:19], 0, v24
	global_store_dword v[0:1], v2, off offset:512
	s_nop 0
	v_cndmask_b32_e64 v24, v26, v27, s[18:19]
	v_mul_f32_e32 v26, 0x37800000, v24
	v_cndmask_b32_e32 v24, v24, v26, vcc
	v_cmp_class_f32_e32 vcc, v7, v86
	s_nop 1
	v_cndmask_b32_e32 v7, v24, v7, vcc
	v_div_scale_f32 v24, s[18:19], v7, v7, 1.0
	v_rcp_f32_e32 v26, v24
	s_nop 0
	v_fma_f32 v0, -v24, v26, 1.0
	v_fmac_f32_e32 v26, v0, v26
	v_div_scale_f32 v0, vcc, 1.0, v7, 1.0
	v_mul_f32_e32 v1, v0, v26
	v_fma_f32 v2, -v24, v1, v0
	v_fmac_f32_e32 v1, v2, v26
	v_fma_f32 v0, -v24, v1, v0
	v_div_fmas_f32 v0, v0, v26, v1
	v_div_fixup_f32 v2, v0, v7, 1.0
	v_mul_f32_e32 v0, v2, v5
	v_mul_f32_e32 v0, v0, v46
	v_mul_f32_e32 v1, v2, v3
	v_mul_f32_e32 v1, v1, v47
	v_bfe_u32 v3, v0, 16, 1
	v_add3_u32 v0, v0, v3, s64
	v_bfe_u32 v3, v1, 16, 1
	v_lshrrev_b32_e32 v0, 16, v0
	v_add3_u32 v1, v1, v3, s64
	v_and_or_b32 v3, v1, s35, v0
	v_lshl_add_u64 v[0:1], s[36:37], 0, v[52:53]
	v_add_co_u32_e32 v0, vcc, s70, v0
	s_nop 1
	v_addc_co_u32_e32 v1, vcc, 0, v1, vcc
	global_store_dword v[0:1], v3, off
	v_mul_f32_e32 v3, v2, v33
	v_mul_f32_e32 v3, v3, v48
	v_mul_f32_e32 v2, v2, v4
	v_mul_f32_e32 v2, v2, v49
	v_bfe_u32 v4, v3, 16, 1
	v_add3_u32 v3, v3, v4, s64
	v_bfe_u32 v4, v2, 16, 1
	v_lshrrev_b32_e32 v3, 16, v3
	v_add3_u32 v2, v2, v4, s64
	v_and_or_b32 v2, v2, s35, v3
	global_store_dword v[0:1], v2, off offset:256
	s_and_saveexec_b64 s[18:19], s[14:15]
	s_cbranch_execz .LBB0_568
	ds_read_u16 v0, v87 offset:3888
	ds_read_u16 v1, v79 offset:3888
	s_waitcnt lgkmcnt(0)
	v_lshlrev_b32_e32 v0, 16, v0
	v_lshlrev_b32_e32 v1, 16, v1
	v_mul_f32_e32 v1, v90, v1
	v_cndmask_b32_e64 v1, v1, -v1, s[10:11]
	v_fmac_f32_e32 v1, v89, v0
	v_bfe_u32 v0, v1, 16, 1
	v_add3_u32 v2, v1, v0, s64
	v_lshl_add_u64 v[0:1], s[36:37], 0, v[54:55]
	global_store_short_d16_hi v[0:1], v2, off
	s_branch .LBB0_568

;     __host__ __device__ bool next(int i, Unit& u) const {
;         const long L = (long)i * G + c; if (L >= nwg) return false;
;         int wgid = (int)L; { const int q = nwg / NXCD, r = nwg % NXCD, xcd = wgid % NXCD, off = wgid / NXCD; wgid = (xcd < r ? xcd * (q + 1) : r * (q + 1) + (xcd - r) * q) + off; }
;         const int nig = WGM * nN, gid = wgid / nig, fm = gid * WGM, gsz = (nM - fm) < WGM ? (nM - fm) : WGM;
;         u.pm = fm + ((wgid % nig) % gsz); u.pn = (wgid % nig) / gsz; return true;
; template <class Epi, class Sched, bool ALIGN_EPI = false, bool SP2 = false>
; __device__ __forceinline__ void gemm_phase(PG8_LAS unsigned char* lds, const Gemm g, const Sched& S, const Epi& E) {
;     ...
;     const int tid = tid_o, wid = __builtin_amdgcn_readfirstlane(tid >> 6), lane = tid & 63, wr = wid >> 2, wc = wid & 3, fr = lane & 15, fq = lane >> 4;
;     const int K = g.K, nt = K / BK;
;     unsigned voffA[2], voffB[2];
; #pragma unroll
;     for (int i = 0; i < 2; ++i) { int R, C; stage_rc(tid * 16 + i * 8192, R, C); const int Rb = Epi::PERM ? ((R & ~31) + perm32(R & 31)) : R;
;         voffA[i] = (unsigned)(R * K + C) * 2u; voffB[i] = (unsigned)(Rb * K + C) * 2u; }
;     const size_t kstep = (size_t)(BK * 2);
;     const size_t hstep = (size_t)HALF * K * 2;
;     const size_t tstep = 2 * hstep;
;     const unsigned ldsw = (unsigned)wid * 1024u;
;     const int aoff = lds_byte(wr * 64 + fr, fq * 8), boff = lds_byte(wc * 32 + fr, fq * 8);
;     ...
;     Unit cur, nxt; int ui = 0;
;     if (!S.next(0, cur)) return;
;     f32x4 acc[2][2][4][2];
; #pragma unroll
;     for (int a = 0; a < 2; ++a)
; #pragma unroll
;         for (int b = 0; b < 2; ++b)
; #pragma unroll
;             for (int m = 0; m < 4; ++m)
; #pragma unroll
;                 for (int n = 0; n < 2; ++n) acc[a][b][m][n] = (f32x4){0.f, 0.f, 0.f, 0.f};
;     bf16x8 At[4][2], B0[2][2], B1[2][2];
;     const char* cA = (const char*)g.A + (size_t)cur.pm * tstep; const char* cB = (const char*)g.Bt + (size_t)cur.pn * tstep;
;     S.a_ready(cur);
;     if constexpr (SP2) {
;         PG8_STAGE(PG8_SB(0, 0), cB, voffB); PG8_STAGE(PG8_SB(0, 1), cB + hstep, voffB); PG8_STAGE(PG8_SA(0, 0), cA, voffA); PG8_STAGE(PG8_SA(0, 1), cA + hstep, voffA);
.LBB0_636:
	s_or_b64 exec, exec, s[6:7]
	s_mov_b64 s[6:7], s[0:1]
	s_waitcnt lgkmcnt(0)
	s_barrier
	s_waitcnt vmcnt(0)
	v_mov_b32_e32 v12, v144
	v_mov_b64_e32 v[0:1], s[6:7]
	global_load_dwordx2 v[0:1], v[0:1], off offset:200
	s_movk_i32 s6, 0x180
	s_cmpk_lt_i32 s2, 0xc0
	s_cselect_b64 s[12:13], -1, 0
	s_cmpk_gt_i32 s2, 0xbf
	s_waitcnt vmcnt(0) lgkmcnt(0)
	v_readfirstlane_b32 s11, v1
	v_readfirstlane_b32 s10, v0
	s_nop 0
	v_readfirstlane_b32 s9, v12
	s_cbranch_scc1 .LBB0_661
	v_lshlrev_b32_e32 v2, 4, v12
	v_add_u32_e32 v0, 0x2000, v2
	v_ashrrev_i32_e32 v1, 31, v0
	v_lshrrev_b32_e32 v1, 22, v1
	v_add_u32_e32 v1, v0, v1
	v_ashrrev_i32_e32 v1, 10, v1
	v_mul_i32_i24_e32 v3, 0x400, v1
	v_sub_u32_e32 v0, v0, v3
	v_lshrrev_b32_e32 v3, 4, v0
	v_bitop3_b32 v3, v3, v0, 32 bitop3:0x6c
	v_ashrrev_i32_e32 v0, 31, v3
	v_lshrrev_b32_e32 v0, 26, v0
	v_add_u32_e32 v4, v3, v0
	v_lshlrev_b32_e32 v5, 3, v1
	v_ashrrev_i32_e32 v0, 6, v4
	v_and_b32_e32 v5, 0x7ffffff0, v5
	v_add_u32_e32 v5, v0, v5
	v_lshlrev_b32_e32 v0, 5, v1
	v_and_b32_e32 v0, 32, v0
	v_mad_u64_u32 v[0:1], s[18:19], v5, s6, v[0:1]
	v_and_b32_e32 v1, 0xc0, v4
	v_sub_u32_e32 v1, v3, v1
	v_mov_b32_e32 v3, 1
	v_ashrrev_i16_sdwa v1, v3, sext(v1) dst_sel:DWORD dst_unused:UNUSED_PAD src0_sel:DWORD src1_sel:BYTE_0
	v_bfe_i32 v1, v1, 0, 16
	v_add_lshl_u32 v130, v0, v1, 1
	v_bfe_i32 v0, v12, 27, 1
	v_lshrrev_b32_e32 v0, 22, v0
	v_add_u32_e32 v0, v2, v0
	v_and_b32_e32 v0, 0xfffffc00, v0
	v_sub_u32_e32 v0, v2, v0
	v_lshrrev_b32_e32 v1, 4, v0
	v_bitop3_b32 v2, v1, v0, 32 bitop3:0x6c
	v_ashrrev_i32_e32 v1, 31, v12
	v_lshrrev_b32_e32 v1, 26, v1
	v_ashrrev_i32_e32 v0, 31, v2
	v_add_u32_e32 v1, v12, v1
	s_add_u32 s35, s10, 0xc200000
	v_lshrrev_b32_e32 v0, 26, v0
	v_ashrrev_i32_e32 v1, 6, v1
	s_addc_u32 s45, s11, 0
	v_add_u32_e32 v4, v2, v0
	v_lshlrev_b32_e32 v5, 3, v1
	s_add_u32 s52, s10, 0x2900000
	v_ashrrev_i32_e32 v0, 6, v4
	v_and_b32_e32 v5, 0x7ffffff0, v5
	s_addc_u32 s53, s11, 0
	v_add_u32_e32 v5, v0, v5
	v_lshlrev_b32_e32 v0, 5, v1
	s_ashr_i32 s55, s2, 31
	v_and_b32_e32 v0, 32, v0
	s_lshr_b32 s8, s55, 29
	v_mad_u64_u32 v[0:1], s[18:19], v5, s6, v[0:1]
	s_add_i32 s8, s2, s8
	s_ashr_i32 s40, s9, 6
	s_ashr_i32 s7, s6, 31
	s_ashr_i32 s18, s8, 3
	s_and_b32 s8, s8, -8
	s_ashr_i32 s41, s9, 8
	s_lshl_b64 s[14:15], s[6:7], 8
	s_lshl_b64 s[16:17], s[6:7], 9
	s_lshl_b32 s54, s40, 10
	s_sub_i32 s8, s2, s8
	s_cmp_lt_i32 s8, 0
	s_cselect_b32 s19, 25, 24
	s_mul_i32 s8, s8, s19
	s_add_i32 s8, s8, s18
	s_mul_hi_i32 s18, s8, 0x2aaaaaab
	s_lshr_b32 s19, s18, 31
	s_ashr_i32 s18, s18, 2
	s_add_i32 s18, s18, s19
	s_lshl_b32 s19, s18, 3
	s_mul_i32 s18, s18, 24
	s_sub_i32 s18, s8, s18
	s_bfe_i32 s8, s18, 0x80000
	s_bfe_u32 s8, s8, 0x3000c
	s_add_i32 s20, s18, s8
	s_bfe_i32 s8, s20, 0x80000
	s_and_b32 s20, s20, 0xf8
	s_sub_i32 s18, s18, s20
	s_sext_i32_i8 s18, s18
	s_add_i32 s20, s19, s18
	s_ashr_i32 s18, s20, 31
	s_mul_i32 s18, s16, s18
	s_mul_hi_u32 s19, s16, s20
	s_sext_i32_i16 s21, s8
	s_add_i32 s36, s19, s18
	s_lshr_b64 s[18:19], s[6:7], 23
	s_lshr_b32 s8, s21, 3
	s_mul_i32 s19, s18, s20
	s_add_i32 s38, s36, s19
	s_bfe_i64 s[36:37], s[8:9], 0x100000
	s_ashr_i32 s19, s21, 3
	s_mul_hi_u32 s21, s16, s19
	s_mul_i32 s36, s16, s37
	v_and_b32_e32 v1, 0xc0, v4
	s_add_i32 s21, s21, s36
	s_mul_i32 s18, s18, s19
	v_sub_u32_e32 v1, v2, v1
	s_add_i32 s21, s21, s18
	s_mul_i32 s18, s16, s19
	v_ashrrev_i16_sdwa v1, v3, sext(v1) dst_sel:DWORD dst_unused:UNUSED_PAD src0_sel:DWORD src1_sel:BYTE_0
	s_add_u32 s48, s52, s18
	v_bfe_i32 v1, v1, 0, 16
	s_addc_u32 s49, s53, s21
	s_add_i32 s56, s54, 0
	v_add_lshl_u32 v132, v0, v1, 1
	s_add_i32 m0, s56, 0x10000
	s_mul_i32 s39, s16, s20
	global_load_lds_dwordx4 v132, s[48:49]
	s_add_i32 m0, s56, 0x12000
	s_add_u32 s18, s48, s14
	global_load_lds_dwordx4 v130, s[48:49]
	s_addc_u32 s19, s49, s15
	s_add_i32 m0, s56, 0x14000
	v_mov_b32_e32 v135, 0
	global_load_lds_dwordx4 v132, s[18:19]
	s_add_i32 m0, s56, 0x16000
	s_add_u32 s50, s35, s39
	s_addc_u32 s51, s45, s38
	s_add_i32 s57, s56, 0x2000
	global_load_lds_dwordx4 v130, s[18:19]
	s_mov_b32 m0, s56
	s_add_u32 s36, s50, s14
	global_load_lds_dwordx4 v132, s[50:51]
	s_mov_b32 m0, s57
	s_addc_u32 s37, s51, s15
	s_add_i32 s58, s56, 0x4000
	global_load_lds_dwordx4 v130, s[50:51]
	s_mov_b32 m0, s58
	s_add_i32 s59, s56, 0x6000
	global_load_lds_dwordx4 v132, s[36:37]
	s_mov_b32 m0, s59
	v_mov_b32_e32 v133, v135
	global_load_lds_dwordx4 v130, s[36:37]
	v_mov_b32_e32 v131, v135
	s_cmp_eq_u32 s41, 1
	s_mov_b32 s60, 0
	v_lshl_add_u64 v[10:11], s[48:49], 0, v[132:133]
	v_lshl_add_u64 v[8:9], s[48:49], 0, v[130:131]
	v_lshl_add_u64 v[2:3], s[18:19], 0, v[132:133]
	v_lshl_add_u64 v[0:1], s[18:19], 0, v[130:131]
	v_lshl_add_u64 v[4:5], s[50:51], 0, v[132:133]
	s_cselect_b64 s[18:19], -1, 0
	s_cmp_lg_u32 s41, 1
	v_lshl_add_u64 v[6:7], s[50:51], 0, v[130:131]
	s_cbranch_scc1 .LBB0_639
	s_barrier

; __device__ __forceinline__ unsigned cvt_pk_bf16(float lo, float hi) { unsigned r; asm volatile("v_cvt_pk_bf16_f32 %0, %1, %2" : "=v"(r) : "v"(lo), "v"(hi)); return r; }
;     __device__ __forceinline__ void operator()(const f32x4 (&acc)[2][2][4][2], const Unit& u, int wr, int wc, int fr, int fq) const {
;     ...
;         } else {
; #pragma unroll
;             for (int ai = 0; ai < 2; ++ai)
; #pragma unroll
;                 for (int m = 0; m < 4; ++m) {
;                     const int row = row0 + ai * HALF + m * 16; const int pos = row & 8191;
;                     const f32x4 cs = *(const f32x4*)(cst + (size_t)pos * 32 + 4 * fq), sn = *(const f32x4*)(cst + (size_t)pos * 32 + 16 + 4 * fq);
; #pragma unroll
;                     for (int bj = 0; bj < 2; ++bj) {
;                         const f32x4 x1 = acc[ai][bj][m][0], x2 = acc[ai][bj][m][1];
;                         const f32x4 o1 = (x1 * cs - x2 * sn) * QS_MLA, o2 = (x2 * cs + x1 * sn) * QS_MLA;
;                         bf16_t* p = O + (size_t)row * 768 + col0 + bj * HALF;
;                         *(unsigned long long*)(p) = (unsigned long long)cvt_pk_bf16(o1[0], o1[1]) | ((unsigned long long)cvt_pk_bf16(o1[2], o1[3]) << 32);
;                         *(unsigned long long*)(p + 16) = (unsigned long long)cvt_pk_bf16(o2[0], o2[1]) | ((unsigned long long)cvt_pk_bf16(o2[2], o2[3]) << 32);
;                     }
;                 }
.LBB0_655:
	s_and_b64 vcc, exec, s[6:7]
	s_mov_b64 s[6:7], -1
	global_store_dwordx2 v[152:153], v[154:155], off offset:288
	s_cbranch_vccnz .LBB0_641
	s_branch .LBB0_658
.LBB0_656:
	v_lshlrev_b32_e32 v152, 7, v167
	v_and_b32_e32 v152, 0xfe780, v152
	v_mov_b32_e32 v153, v135
	v_lshl_add_u64 v[152:153], v[136:137], 0, v[152:153]
	global_load_dwordx4 v[170:173], v[152:153], off offset:64
	global_load_dwordx4 v[174:177], v[152:153], off
	v_mov_b64_e32 v[152:153], s[36:37]
	v_lshlrev_b64 v[154:155], 1, v[134:135]
	v_mad_i64_i32 v[184:185], s[20:21], v167, s69, v[152:153]
	v_lshlrev_b32_e32 v169, 7, v166
	v_lshl_add_u64 v[184:185], v[184:185], 0, v[154:155]
	v_mov_b32_e32 v183, v135
	v_and_b32_e32 v182, 0xfef80, v169
	v_lshl_add_u64 v[182:183], v[136:137], 0, v[182:183]
	v_lshlrev_b32_e32 v169, 7, v165
	s_waitcnt vmcnt(0) lgkmcnt(0)
	v_pk_mul_f32 v[186:187], v[122:123], v[172:173]
	v_pk_mul_f32 v[188:189], v[120:121], v[170:171]
	v_pk_mul_f32 v[190:191], v[126:127], v[172:173]
	v_pk_mul_f32 v[192:193], v[124:125], v[170:171]
	v_pk_mul_f32 v[194:195], v[114:115], v[172:173]
	v_pk_mul_f32 v[196:197], v[112:113], v[170:171]
	v_pk_mul_f32 v[172:173], v[118:119], v[172:173]
	v_pk_mul_f32 v[170:171], v[116:117], v[170:171]
	v_pk_fma_f32 v[186:187], v[126:127], v[176:177], v[186:187] neg_lo:[0,0,1] neg_hi:[0,0,1]
	v_pk_fma_f32 v[188:189], v[124:125], v[174:175], v[188:189] neg_lo:[0,0,1] neg_hi:[0,0,1]
	v_pk_fma_f32 v[190:191], v[122:123], v[176:177], v[190:191]
	v_pk_fma_f32 v[192:193], v[120:121], v[174:175], v[192:193]
	v_pk_fma_f32 v[194:195], v[118:119], v[176:177], v[194:195] neg_lo:[0,0,1] neg_hi:[0,0,1]
	v_pk_fma_f32 v[196:197], v[116:117], v[174:175], v[196:197] neg_lo:[0,0,1] neg_hi:[0,0,1]
	v_pk_fma_f32 v[172:173], v[114:115], v[176:177], v[172:173]
	v_pk_fma_f32 v[170:171], v[112:113], v[174:175], v[170:171]
	v_pk_mul_f32 v[174:175], v[186:187], s[44:45] op_sel_hi:[1,0]
	v_pk_mul_f32 v[176:177], v[188:189], s[44:45] op_sel_hi:[1,0]
	v_pk_mul_f32 v[186:187], v[190:191], s[44:45] op_sel_hi:[1,0]
	v_pk_mul_f32 v[188:189], v[192:193], s[44:45] op_sel_hi:[1,0]
	v_pk_mul_f32 v[170:171], v[170:171], s[44:45] op_sel_hi:[1,0]
	v_cvt_pk_bf16_f32 v176, v176, v177
	v_cvt_pk_bf16_f32 v177, v174, v175
	global_store_dwordx2 v[184:185], v[176:177], off
	v_cvt_pk_bf16_f32 v174, v188, v189
	v_cvt_pk_bf16_f32 v175, v186, v187
	v_pk_mul_f32 v[190:191], v[194:195], s[44:45] op_sel_hi:[1,0]
	v_pk_mul_f32 v[192:193], v[196:197], s[44:45] op_sel_hi:[1,0]
	v_pk_mul_f32 v[172:173], v[172:173], s[44:45] op_sel_hi:[1,0]
	global_store_dwordx2 v[184:185], v[174:175], off offset:32
	v_cvt_pk_bf16_f32 v174, v192, v193
	v_cvt_pk_bf16_f32 v175, v190, v191
	global_store_dwordx2 v[184:185], v[174:175], off offset:256
	v_cvt_pk_bf16_f32 v170, v170, v171
	v_cvt_pk_bf16_f32 v171, v172, v173
	global_store_dwordx2 v[184:185], v[170:171], off offset:288
	global_load_dwordx4 v[170:173], v[182:183], off offset:64
	s_nop 0
	global_load_dwordx4 v[174:177], v[182:183], off
	v_mad_i64_i32 v[184:185], s[20:21], v166, s69, v[152:153]
	v_lshl_add_u64 v[184:185], v[184:185], 0, v[154:155]
	v_mov_b32_e32 v183, v135
	v_and_b32_e32 v182, 0xff780, v169
	v_lshl_add_u64 v[182:183], v[136:137], 0, v[182:183]
	v_lshlrev_b32_e32 v169, 7, v164
	s_waitcnt vmcnt(0) lgkmcnt(0)
	v_pk_mul_f32 v[186:187], v[106:107], v[172:173]
	v_pk_mul_f32 v[188:189], v[104:105], v[170:171]
	v_pk_mul_f32 v[190:191], v[110:111], v[172:173]
	v_pk_mul_f32 v[192:193], v[108:109], v[170:171]
	v_pk_mul_f32 v[194:195], v[98:99], v[172:173]
	v_pk_mul_f32 v[196:197], v[96:97], v[170:171]
	v_pk_mul_f32 v[172:173], v[102:103], v[172:173]
	v_pk_mul_f32 v[170:171], v[100:101], v[170:171]
	v_pk_fma_f32 v[186:187], v[110:111], v[176:177], v[186:187] neg_lo:[0,0,1] neg_hi:[0,0,1]
	v_pk_fma_f32 v[188:189], v[108:109], v[174:175], v[188:189] neg_lo:[0,0,1] neg_hi:[0,0,1]
	v_pk_fma_f32 v[190:191], v[106:107], v[176:177], v[190:191]
	v_pk_fma_f32 v[192:193], v[104:105], v[174:175], v[192:193]
	v_pk_fma_f32 v[194:195], v[102:103], v[176:177], v[194:195] neg_lo:[0,0,1] neg_hi:[0,0,1]
	v_pk_fma_f32 v[196:197], v[100:101], v[174:175], v[196:197] neg_lo:[0,0,1] neg_hi:[0,0,1]
	v_pk_fma_f32 v[172:173], v[98:99], v[176:177], v[172:173]
	v_pk_fma_f32 v[170:171], v[96:97], v[174:175], v[170:171]
	v_pk_mul_f32 v[174:175], v[186:187], s[44:45] op_sel_hi:[1,0]
	v_pk_mul_f32 v[176:177], v[188:189], s[44:45] op_sel_hi:[1,0]
	v_pk_mul_f32 v[186:187], v[190:191], s[44:45] op_sel_hi:[1,0]
	v_pk_mul_f32 v[188:189], v[192:193], s[44:45] op_sel_hi:[1,0]
	v_pk_mul_f32 v[170:171], v[170:171], s[44:45] op_sel_hi:[1,0]
	v_cvt_pk_bf16_f32 v176, v176, v177
	v_cvt_pk_bf16_f32 v177, v174, v175
	global_store_dwordx2 v[184:185], v[176:177], off
	v_cvt_pk_bf16_f32 v174, v188, v189
	v_cvt_pk_bf16_f32 v175, v186, v187
	v_pk_mul_f32 v[190:191], v[194:195], s[44:45] op_sel_hi:[1,0]
	v_pk_mul_f32 v[192:193], v[196:197], s[44:45] op_sel_hi:[1,0]
	v_pk_mul_f32 v[172:173], v[172:173], s[44:45] op_sel_hi:[1,0]
	global_store_dwordx2 v[184:185], v[174:175], off offset:32
	v_cvt_pk_bf16_f32 v174, v192, v193
	v_cvt_pk_bf16_f32 v175, v190, v191
	global_store_dwordx2 v[184:185], v[174:175], off offset:256
	v_cvt_pk_bf16_f32 v170, v170, v171
	v_cvt_pk_bf16_f32 v171, v172, v173
	global_store_dwordx2 v[184:185], v[170:171], off offset:288
	global_load_dwordx4 v[170:173], v[182:183], off offset:64
	s_nop 0
	global_load_dwordx4 v[174:177], v[182:183], off
	v_mad_i64_i32 v[184:185], s[20:21], v165, s69, v[152:153]
	v_lshl_add_u64 v[184:185], v[184:185], 0, v[154:155]
	v_mov_b32_e32 v183, v135
	v_and_b32_e32 v182, 0xfff80, v169
	v_lshl_add_u64 v[182:183], v[136:137], 0, v[182:183]
	v_lshlrev_b32_e32 v169, 7, v163
	s_waitcnt vmcnt(0) lgkmcnt(0)
; __device__ __forceinline__ unsigned cvt_pk_bf16(float lo, float hi) { unsigned r; asm volatile("v_cvt_pk_bf16_f32 %0, %1, %2" : "=v"(r) : "v"(lo), "v"(hi)); return r; }
;     __device__ __forceinline__ void operator()(const f32x4 (&acc)[2][2][4][2], const Unit& u, int wr, int wc, int fr, int fq) const {
;     ...
;                     const int row = row0 + ai * HALF + m * 16; const int pos = row & 8191;
;                     const f32x4 cs = *(const f32x4*)(cst + (size_t)pos * 32 + 4 * fq), sn = *(const f32x4*)(cst + (size_t)pos * 32 + 16 + 4 * fq);
; #pragma unroll
;                     for (int bj = 0; bj < 2; ++bj) {
;                         const f32x4 x1 = acc[ai][bj][m][0], x2 = acc[ai][bj][m][1];
;                         const f32x4 o1 = (x1 * cs - x2 * sn) * QS_MLA, o2 = (x2 * cs + x1 * sn) * QS_MLA;
;                         bf16_t* p = O + (size_t)row * 768 + col0 + bj * HALF;
;                         *(unsigned long long*)(p) = (unsigned long long)cvt_pk_bf16(o1[0], o1[1]) | ((unsigned long long)cvt_pk_bf16(o1[2], o1[3]) << 32);
;                         *(unsigned long long*)(p + 16) = (unsigned long long)cvt_pk_bf16(o2[0], o2[1]) | ((unsigned long long)cvt_pk_bf16(o2[2], o2[3]) << 32);
;                     }
;                 }
	v_pk_mul_f32 v[186:187], v[90:91], v[172:173]
	v_pk_mul_f32 v[188:189], v[88:89], v[170:171]
	v_pk_mul_f32 v[190:191], v[94:95], v[172:173]
	v_pk_mul_f32 v[192:193], v[92:93], v[170:171]
	v_pk_mul_f32 v[194:195], v[82:83], v[172:173]
	v_pk_mul_f32 v[196:197], v[80:81], v[170:171]
	v_pk_mul_f32 v[172:173], v[86:87], v[172:173]
	v_pk_mul_f32 v[170:171], v[84:85], v[170:171]
	v_pk_fma_f32 v[186:187], v[94:95], v[176:177], v[186:187] neg_lo:[0,0,1] neg_hi:[0,0,1]
	v_pk_fma_f32 v[188:189], v[92:93], v[174:175], v[188:189] neg_lo:[0,0,1] neg_hi:[0,0,1]
	v_pk_fma_f32 v[190:191], v[90:91], v[176:177], v[190:191]
	v_pk_fma_f32 v[192:193], v[88:89], v[174:175], v[192:193]
	v_pk_fma_f32 v[194:195], v[86:87], v[176:177], v[194:195] neg_lo:[0,0,1] neg_hi:[0,0,1]
	v_pk_fma_f32 v[196:197], v[84:85], v[174:175], v[196:197] neg_lo:[0,0,1] neg_hi:[0,0,1]
	v_pk_fma_f32 v[172:173], v[82:83], v[176:177], v[172:173]
	v_pk_fma_f32 v[170:171], v[80:81], v[174:175], v[170:171]
	v_pk_mul_f32 v[174:175], v[186:187], s[44:45] op_sel_hi:[1,0]
	v_pk_mul_f32 v[176:177], v[188:189], s[44:45] op_sel_hi:[1,0]
	v_pk_mul_f32 v[186:187], v[190:191], s[44:45] op_sel_hi:[1,0]
	v_pk_mul_f32 v[188:189], v[192:193], s[44:45] op_sel_hi:[1,0]
	v_pk_mul_f32 v[170:171], v[170:171], s[44:45] op_sel_hi:[1,0]
	v_cvt_pk_bf16_f32 v176, v176, v177
	v_cvt_pk_bf16_f32 v177, v174, v175
	global_store_dwordx2 v[184:185], v[176:177], off
	v_cvt_pk_bf16_f32 v174, v188, v189
	v_cvt_pk_bf16_f32 v175, v186, v187
	v_pk_mul_f32 v[190:191], v[194:195], s[44:45] op_sel_hi:[1,0]
	v_pk_mul_f32 v[192:193], v[196:197], s[44:45] op_sel_hi:[1,0]
	v_pk_mul_f32 v[172:173], v[172:173], s[44:45] op_sel_hi:[1,0]
	global_store_dwordx2 v[184:185], v[174:175], off offset:32
	v_cvt_pk_bf16_f32 v174, v192, v193
	v_cvt_pk_bf16_f32 v175, v190, v191
	global_store_dwordx2 v[184:185], v[174:175], off offset:256
	v_cvt_pk_bf16_f32 v170, v170, v171
	v_cvt_pk_bf16_f32 v171, v172, v173
	global_store_dwordx2 v[184:185], v[170:171], off offset:288
	global_load_dwordx4 v[170:173], v[182:183], off offset:64
	s_nop 0
	global_load_dwordx4 v[174:177], v[182:183], off
	v_mad_i64_i32 v[184:185], s[20:21], v164, s69, v[152:153]
	v_lshl_add_u64 v[184:185], v[184:185], 0, v[154:155]
	v_mov_b32_e32 v183, v135
	v_and_b32_e32 v182, 0xfe780, v169
	v_lshl_add_u64 v[182:183], v[136:137], 0, v[182:183]
	v_lshlrev_b32_e32 v169, 7, v162
	s_waitcnt vmcnt(0) lgkmcnt(0)
	v_pk_mul_f32 v[186:187], v[74:75], v[172:173]
	v_pk_mul_f32 v[188:189], v[72:73], v[170:171]
	v_pk_mul_f32 v[190:191], v[78:79], v[172:173]
	v_pk_mul_f32 v[192:193], v[76:77], v[170:171]
	v_pk_mul_f32 v[194:195], v[66:67], v[172:173]
	v_pk_mul_f32 v[196:197], v[64:65], v[170:171]
	v_pk_mul_f32 v[172:173], v[70:71], v[172:173]
	v_pk_mul_f32 v[170:171], v[68:69], v[170:171]
	v_pk_fma_f32 v[186:187], v[78:79], v[176:177], v[186:187] neg_lo:[0,0,1] neg_hi:[0,0,1]
	v_pk_fma_f32 v[188:189], v[76:77], v[174:175], v[188:189] neg_lo:[0,0,1] neg_hi:[0,0,1]
	v_pk_fma_f32 v[190:191], v[74:75], v[176:177], v[190:191]
	v_pk_fma_f32 v[192:193], v[72:73], v[174:175], v[192:193]
	v_pk_fma_f32 v[194:195], v[70:71], v[176:177], v[194:195] neg_lo:[0,0,1] neg_hi:[0,0,1]
	v_pk_fma_f32 v[196:197], v[68:69], v[174:175], v[196:197] neg_lo:[0,0,1] neg_hi:[0,0,1]
	v_pk_fma_f32 v[172:173], v[66:67], v[176:177], v[172:173]
	v_pk_fma_f32 v[170:171], v[64:65], v[174:175], v[170:171]
	v_pk_mul_f32 v[174:175], v[186:187], s[44:45] op_sel_hi:[1,0]
	v_pk_mul_f32 v[176:177], v[188:189], s[44:45] op_sel_hi:[1,0]
	v_pk_mul_f32 v[186:187], v[190:191], s[44:45] op_sel_hi:[1,0]
	v_pk_mul_f32 v[188:189], v[192:193], s[44:45] op_sel_hi:[1,0]
	v_pk_mul_f32 v[170:171], v[170:171], s[44:45] op_sel_hi:[1,0]
	v_cvt_pk_bf16_f32 v176, v176, v177
	v_cvt_pk_bf16_f32 v177, v174, v175
	global_store_dwordx2 v[184:185], v[176:177], off
	v_cvt_pk_bf16_f32 v174, v188, v189
	v_cvt_pk_bf16_f32 v175, v186, v187
	v_pk_mul_f32 v[190:191], v[194:195], s[44:45] op_sel_hi:[1,0]
	v_pk_mul_f32 v[192:193], v[196:197], s[44:45] op_sel_hi:[1,0]
	v_pk_mul_f32 v[172:173], v[172:173], s[44:45] op_sel_hi:[1,0]
	global_store_dwordx2 v[184:185], v[174:175], off offset:32
	v_cvt_pk_bf16_f32 v174, v192, v193
	v_cvt_pk_bf16_f32 v175, v190, v191
	global_store_dwordx2 v[184:185], v[174:175], off offset:256
	v_cvt_pk_bf16_f32 v170, v170, v171
	v_cvt_pk_bf16_f32 v171, v172, v173
	global_store_dwordx2 v[184:185], v[170:171], off offset:288
	global_load_dwordx4 v[170:173], v[182:183], off offset:64
	s_nop 0
	global_load_dwordx4 v[174:177], v[182:183], off
	v_mad_i64_i32 v[184:185], s[20:21], v163, s69, v[152:153]
	v_lshl_add_u64 v[184:185], v[184:185], 0, v[154:155]
	v_mov_b32_e32 v183, v135
	v_and_b32_e32 v182, 0xfef80, v169
	v_lshl_add_u64 v[182:183], v[136:137], 0, v[182:183]
	v_lshlrev_b32_e32 v169, 7, v161
	s_waitcnt vmcnt(0) lgkmcnt(0)
; __device__ __forceinline__ unsigned cvt_pk_bf16(float lo, float hi) { unsigned r; asm volatile("v_cvt_pk_bf16_f32 %0, %1, %2" : "=v"(r) : "v"(lo), "v"(hi)); return r; }
;     __device__ __forceinline__ void operator()(const f32x4 (&acc)[2][2][4][2], const Unit& u, int wr, int wc, int fr, int fq) const {
;     ...
;                     const int row = row0 + ai * HALF + m * 16; const int pos = row & 8191;
;                     const f32x4 cs = *(const f32x4*)(cst + (size_t)pos * 32 + 4 * fq), sn = *(const f32x4*)(cst + (size_t)pos * 32 + 16 + 4 * fq);
; #pragma unroll
;                     for (int bj = 0; bj < 2; ++bj) {
;                         const f32x4 x1 = acc[ai][bj][m][0], x2 = acc[ai][bj][m][1];
;                         const f32x4 o1 = (x1 * cs - x2 * sn) * QS_MLA, o2 = (x2 * cs + x1 * sn) * QS_MLA;
;                         bf16_t* p = O + (size_t)row * 768 + col0 + bj * HALF;
;                         *(unsigned long long*)(p) = (unsigned long long)cvt_pk_bf16(o1[0], o1[1]) | ((unsigned long long)cvt_pk_bf16(o1[2], o1[3]) << 32);
;                         *(unsigned long long*)(p + 16) = (unsigned long long)cvt_pk_bf16(o2[0], o2[1]) | ((unsigned long long)cvt_pk_bf16(o2[2], o2[3]) << 32);
;                     }
;                 }
	v_pk_mul_f32 v[186:187], v[58:59], v[172:173]
	v_pk_mul_f32 v[188:189], v[56:57], v[170:171]
	v_pk_mul_f32 v[190:191], v[62:63], v[172:173]
	v_pk_mul_f32 v[192:193], v[60:61], v[170:171]
	v_pk_mul_f32 v[194:195], v[50:51], v[172:173]
	v_pk_mul_f32 v[196:197], v[48:49], v[170:171]
	v_pk_mul_f32 v[172:173], v[54:55], v[172:173]
	v_pk_mul_f32 v[170:171], v[52:53], v[170:171]
	v_pk_fma_f32 v[186:187], v[62:63], v[176:177], v[186:187] neg_lo:[0,0,1] neg_hi:[0,0,1]
	v_pk_fma_f32 v[188:189], v[60:61], v[174:175], v[188:189] neg_lo:[0,0,1] neg_hi:[0,0,1]
	v_pk_fma_f32 v[190:191], v[58:59], v[176:177], v[190:191]
	v_pk_fma_f32 v[192:193], v[56:57], v[174:175], v[192:193]
	v_pk_fma_f32 v[194:195], v[54:55], v[176:177], v[194:195] neg_lo:[0,0,1] neg_hi:[0,0,1]
	v_pk_fma_f32 v[196:197], v[52:53], v[174:175], v[196:197] neg_lo:[0,0,1] neg_hi:[0,0,1]
	v_pk_fma_f32 v[172:173], v[50:51], v[176:177], v[172:173]
	v_pk_fma_f32 v[170:171], v[48:49], v[174:175], v[170:171]
	v_pk_mul_f32 v[174:175], v[186:187], s[44:45] op_sel_hi:[1,0]
	v_pk_mul_f32 v[176:177], v[188:189], s[44:45] op_sel_hi:[1,0]
	v_pk_mul_f32 v[186:187], v[190:191], s[44:45] op_sel_hi:[1,0]
	v_pk_mul_f32 v[188:189], v[192:193], s[44:45] op_sel_hi:[1,0]
	v_pk_mul_f32 v[170:171], v[170:171], s[44:45] op_sel_hi:[1,0]
	v_cvt_pk_bf16_f32 v176, v176, v177
	v_cvt_pk_bf16_f32 v177, v174, v175
	global_store_dwordx2 v[184:185], v[176:177], off
	v_cvt_pk_bf16_f32 v174, v188, v189
	v_cvt_pk_bf16_f32 v175, v186, v187
	v_pk_mul_f32 v[190:191], v[194:195], s[44:45] op_sel_hi:[1,0]
	v_pk_mul_f32 v[192:193], v[196:197], s[44:45] op_sel_hi:[1,0]
	v_pk_mul_f32 v[172:173], v[172:173], s[44:45] op_sel_hi:[1,0]
	global_store_dwordx2 v[184:185], v[174:175], off offset:32
	v_cvt_pk_bf16_f32 v174, v192, v193
	v_cvt_pk_bf16_f32 v175, v190, v191
	global_store_dwordx2 v[184:185], v[174:175], off offset:256
	v_cvt_pk_bf16_f32 v170, v170, v171
	v_cvt_pk_bf16_f32 v171, v172, v173
	global_store_dwordx2 v[184:185], v[170:171], off offset:288
	global_load_dwordx4 v[170:173], v[182:183], off offset:64
	s_nop 0
	global_load_dwordx4 v[174:177], v[182:183], off
	v_mad_i64_i32 v[184:185], s[20:21], v162, s69, v[152:153]
	v_lshl_add_u64 v[184:185], v[184:185], 0, v[154:155]
	v_mov_b32_e32 v183, v135
	v_and_b32_e32 v182, 0xff780, v169
	v_lshl_add_u64 v[182:183], v[136:137], 0, v[182:183]
	v_lshlrev_b32_e32 v169, 7, v159
	s_waitcnt vmcnt(0) lgkmcnt(0)
	v_pk_mul_f32 v[186:187], v[42:43], v[172:173]
	v_pk_mul_f32 v[188:189], v[40:41], v[170:171]
	v_pk_mul_f32 v[190:191], v[46:47], v[172:173]
	v_pk_mul_f32 v[192:193], v[44:45], v[170:171]
	v_pk_mul_f32 v[194:195], v[34:35], v[172:173]
	v_pk_mul_f32 v[196:197], v[32:33], v[170:171]
	v_pk_mul_f32 v[172:173], v[38:39], v[172:173]
	v_pk_mul_f32 v[170:171], v[36:37], v[170:171]
	v_pk_fma_f32 v[186:187], v[46:47], v[176:177], v[186:187] neg_lo:[0,0,1] neg_hi:[0,0,1]
	v_pk_fma_f32 v[188:189], v[44:45], v[174:175], v[188:189] neg_lo:[0,0,1] neg_hi:[0,0,1]
	v_pk_fma_f32 v[190:191], v[42:43], v[176:177], v[190:191]
	v_pk_fma_f32 v[192:193], v[40:41], v[174:175], v[192:193]
	v_pk_fma_f32 v[194:195], v[38:39], v[176:177], v[194:195] neg_lo:[0,0,1] neg_hi:[0,0,1]
	v_pk_fma_f32 v[196:197], v[36:37], v[174:175], v[196:197] neg_lo:[0,0,1] neg_hi:[0,0,1]
	v_pk_fma_f32 v[172:173], v[34:35], v[176:177], v[172:173]
	v_pk_fma_f32 v[170:171], v[32:33], v[174:175], v[170:171]
	v_pk_mul_f32 v[174:175], v[186:187], s[44:45] op_sel_hi:[1,0]
	v_pk_mul_f32 v[176:177], v[188:189], s[44:45] op_sel_hi:[1,0]
	v_pk_mul_f32 v[186:187], v[190:191], s[44:45] op_sel_hi:[1,0]
	v_pk_mul_f32 v[188:189], v[192:193], s[44:45] op_sel_hi:[1,0]
	v_pk_mul_f32 v[170:171], v[170:171], s[44:45] op_sel_hi:[1,0]
	v_cvt_pk_bf16_f32 v176, v176, v177
	v_cvt_pk_bf16_f32 v177, v174, v175
	global_store_dwordx2 v[184:185], v[176:177], off
	v_cvt_pk_bf16_f32 v174, v188, v189
	v_cvt_pk_bf16_f32 v175, v186, v187
	v_pk_mul_f32 v[190:191], v[194:195], s[44:45] op_sel_hi:[1,0]
	v_pk_mul_f32 v[192:193], v[196:197], s[44:45] op_sel_hi:[1,0]
	v_pk_mul_f32 v[172:173], v[172:173], s[44:45] op_sel_hi:[1,0]
	global_store_dwordx2 v[184:185], v[174:175], off offset:32
	v_cvt_pk_bf16_f32 v174, v192, v193
	v_cvt_pk_bf16_f32 v175, v190, v191
	global_store_dwordx2 v[184:185], v[174:175], off offset:256
	v_cvt_pk_bf16_f32 v170, v170, v171
	v_cvt_pk_bf16_f32 v171, v172, v173
	global_store_dwordx2 v[184:185], v[170:171], off offset:288
	global_load_dwordx4 v[170:173], v[182:183], off offset:64
	s_nop 0
	global_load_dwordx4 v[174:177], v[182:183], off
	v_mad_i64_i32 v[184:185], s[20:21], v161, s69, v[152:153]
	v_lshl_add_u64 v[184:185], v[184:185], 0, v[154:155]
	v_mov_b32_e32 v183, v135
	v_and_b32_e32 v182, 0xfff80, v169
	v_lshl_add_u64 v[182:183], v[136:137], 0, v[182:183]
	v_mad_i64_i32 v[152:153], s[20:21], v159, s69, v[152:153]
	v_lshl_add_u64 v[152:153], v[152:153], 0, v[154:155]
	s_waitcnt vmcnt(0) lgkmcnt(0)
; __device__ __forceinline__ unsigned cvt_pk_bf16(float lo, float hi) { unsigned r; asm volatile("v_cvt_pk_bf16_f32 %0, %1, %2" : "=v"(r) : "v"(lo), "v"(hi)); return r; }
;     __device__ __forceinline__ void operator()(const f32x4 (&acc)[2][2][4][2], const Unit& u, int wr, int wc, int fr, int fq) const {
;     ...
;         if (u.pn < 2) {
; #pragma unroll
;             for (int ai = 0; ai < 2; ++ai)
; #pragma unroll
;                 for (int m = 0; m < 4; ++m)
; #pragma unroll
;                     for (int bj = 0; bj < 2; ++bj)
; #pragma unroll
;                         for (int n = 0; n < 2; ++n) { const f32x4 v = acc[ai][bj][m][n] * QS_MLA; unsigned lo = cvt_pk_bf16(v[0], v[1]), hi = cvt_pk_bf16(v[2], v[3]);
;                             unsigned long long w = (unsigned long long)lo | ((unsigned long long)hi << 32);
;                             *(unsigned long long*)(O + (size_t)(row0 + ai * HALF + m * 16) * 768 + col0 + bj * HALF + n * 16) = w; }
;         } else {
; #pragma unroll
;             for (int ai = 0; ai < 2; ++ai)
; #pragma unroll
;                 for (int m = 0; m < 4; ++m) {
;                     const int row = row0 + ai * HALF + m * 16; const int pos = row & 8191;
;                     const f32x4 cs = *(const f32x4*)(cst + (size_t)pos * 32 + 4 * fq), sn = *(const f32x4*)(cst + (size_t)pos * 32 + 16 + 4 * fq);
; #pragma unroll
;                     for (int bj = 0; bj < 2; ++bj) {
;                         const f32x4 x1 = acc[ai][bj][m][0], x2 = acc[ai][bj][m][1];
;                         const f32x4 o1 = (x1 * cs - x2 * sn) * QS_MLA, o2 = (x2 * cs + x1 * sn) * QS_MLA;
;                         bf16_t* p = O + (size_t)row * 768 + col0 + bj * HALF;
;                         *(unsigned long long*)(p) = (unsigned long long)cvt_pk_bf16(o1[0], o1[1]) | ((unsigned long long)cvt_pk_bf16(o1[2], o1[3]) << 32);
;                         *(unsigned long long*)(p + 16) = (unsigned long long)cvt_pk_bf16(o2[0], o2[1]) | ((unsigned long long)cvt_pk_bf16(o2[2], o2[3]) << 32);
;                     }
;                 }
	v_pk_mul_f32 v[186:187], v[26:27], v[172:173]
	v_pk_mul_f32 v[188:189], v[24:25], v[170:171]
	v_pk_mul_f32 v[190:191], v[30:31], v[172:173]
	v_pk_mul_f32 v[192:193], v[28:29], v[170:171]
	v_pk_mul_f32 v[194:195], v[18:19], v[172:173]
	v_pk_mul_f32 v[196:197], v[16:17], v[170:171]
	v_pk_mul_f32 v[172:173], v[22:23], v[172:173]
	v_pk_mul_f32 v[170:171], v[20:21], v[170:171]
	v_pk_fma_f32 v[186:187], v[30:31], v[176:177], v[186:187] neg_lo:[0,0,1] neg_hi:[0,0,1]
	v_pk_fma_f32 v[188:189], v[28:29], v[174:175], v[188:189] neg_lo:[0,0,1] neg_hi:[0,0,1]
	v_pk_fma_f32 v[190:191], v[26:27], v[176:177], v[190:191]
	v_pk_fma_f32 v[192:193], v[24:25], v[174:175], v[192:193]
	v_pk_fma_f32 v[194:195], v[22:23], v[176:177], v[194:195] neg_lo:[0,0,1] neg_hi:[0,0,1]
	v_pk_fma_f32 v[196:197], v[20:21], v[174:175], v[196:197] neg_lo:[0,0,1] neg_hi:[0,0,1]
	v_pk_fma_f32 v[172:173], v[18:19], v[176:177], v[172:173]
	v_pk_fma_f32 v[170:171], v[16:17], v[174:175], v[170:171]
	v_pk_mul_f32 v[174:175], v[186:187], s[44:45] op_sel_hi:[1,0]
	v_pk_mul_f32 v[176:177], v[188:189], s[44:45] op_sel_hi:[1,0]
	v_pk_mul_f32 v[186:187], v[190:191], s[44:45] op_sel_hi:[1,0]
	v_pk_mul_f32 v[188:189], v[192:193], s[44:45] op_sel_hi:[1,0]
	v_pk_mul_f32 v[170:171], v[170:171], s[44:45] op_sel_hi:[1,0]
	v_cvt_pk_bf16_f32 v176, v176, v177
	v_cvt_pk_bf16_f32 v177, v174, v175
	global_store_dwordx2 v[184:185], v[176:177], off
	v_cvt_pk_bf16_f32 v174, v188, v189
	v_cvt_pk_bf16_f32 v175, v186, v187
	v_pk_mul_f32 v[190:191], v[194:195], s[44:45] op_sel_hi:[1,0]
	v_pk_mul_f32 v[192:193], v[196:197], s[44:45] op_sel_hi:[1,0]
	v_pk_mul_f32 v[172:173], v[172:173], s[44:45] op_sel_hi:[1,0]
	global_store_dwordx2 v[184:185], v[174:175], off offset:32
	v_cvt_pk_bf16_f32 v174, v192, v193
	v_cvt_pk_bf16_f32 v175, v190, v191
	global_store_dwordx2 v[184:185], v[174:175], off offset:256
	v_cvt_pk_bf16_f32 v170, v170, v171
	v_cvt_pk_bf16_f32 v171, v172, v173
	global_store_dwordx2 v[184:185], v[170:171], off offset:288
	global_load_dwordx4 v[170:173], v[182:183], off offset:64
	s_nop 0
	global_load_dwordx4 v[174:177], v[182:183], off
	s_waitcnt vmcnt(0) lgkmcnt(0)
	v_pk_mul_f32 v[154:155], v[10:11], v[172:173]
	v_pk_mul_f32 v[182:183], v[8:9], v[170:171]
	v_pk_mul_f32 v[184:185], v[14:15], v[172:173]
	v_pk_mul_f32 v[186:187], v[12:13], v[170:171]
	v_pk_mul_f32 v[190:191], v[0:1], v[170:171]
	v_pk_mul_f32 v[170:171], v[4:5], v[170:171]
	v_pk_fma_f32 v[154:155], v[14:15], v[176:177], v[154:155] neg_lo:[0,0,1] neg_hi:[0,0,1]
	v_pk_fma_f32 v[182:183], v[12:13], v[174:175], v[182:183] neg_lo:[0,0,1] neg_hi:[0,0,1]
	v_pk_mul_f32 v[188:189], v[2:3], v[172:173]
	v_pk_mul_f32 v[172:173], v[6:7], v[172:173]
	v_pk_fma_f32 v[184:185], v[10:11], v[176:177], v[184:185]
	v_pk_fma_f32 v[186:187], v[8:9], v[174:175], v[186:187]
	v_pk_fma_f32 v[190:191], v[4:5], v[174:175], v[190:191] neg_lo:[0,0,1] neg_hi:[0,0,1]
	v_pk_fma_f32 v[170:171], v[0:1], v[174:175], v[170:171]
	v_pk_mul_f32 v[154:155], v[154:155], s[44:45] op_sel_hi:[1,0]
	v_pk_mul_f32 v[174:175], v[182:183], s[44:45] op_sel_hi:[1,0]
	v_pk_fma_f32 v[188:189], v[6:7], v[176:177], v[188:189] neg_lo:[0,0,1] neg_hi:[0,0,1]
	v_pk_fma_f32 v[172:173], v[2:3], v[176:177], v[172:173]
	v_pk_mul_f32 v[176:177], v[184:185], s[44:45] op_sel_hi:[1,0]
	v_pk_mul_f32 v[182:183], v[186:187], s[44:45] op_sel_hi:[1,0]
	v_cvt_pk_bf16_f32 v174, v174, v175
	v_cvt_pk_bf16_f32 v175, v154, v155
	global_store_dwordx2 v[152:153], v[174:175], off
	v_cvt_pk_bf16_f32 v154, v182, v183
	v_cvt_pk_bf16_f32 v155, v176, v177
	v_pk_mul_f32 v[184:185], v[188:189], s[44:45] op_sel_hi:[1,0]
	v_pk_mul_f32 v[186:187], v[190:191], s[44:45] op_sel_hi:[1,0]
	global_store_dwordx2 v[152:153], v[154:155], off offset:32
	v_cvt_pk_bf16_f32 v154, v186, v187
	v_cvt_pk_bf16_f32 v155, v184, v185
	v_pk_mul_f32 v[172:173], v[172:173], s[44:45] op_sel_hi:[1,0]
	v_pk_mul_f32 v[170:171], v[170:171], s[44:45] op_sel_hi:[1,0]
	global_store_dwordx2 v[152:153], v[154:155], off offset:256
	v_cvt_pk_bf16_f32 v154, v170, v171
	v_cvt_pk_bf16_f32 v155, v172, v173
	s_cbranch_execnz .LBB0_655
.LBB0_657:
	v_pk_mul_f32 v[124:125], v[124:125], s[44:45] op_sel_hi:[1,0]
	v_ashrrev_i32_e32 v153, 31, v134
	v_mov_b32_e32 v152, v134
	v_pk_mul_f32 v[126:127], v[126:127], s[44:45] op_sel_hi:[1,0]
	v_cvt_pk_bf16_f32 v154, v124, v125
	v_mov_b64_e32 v[124:125], s[36:37]
	v_cvt_pk_bf16_f32 v155, v126, v127
	v_mad_i64_i32 v[170:171], s[20:21], v167, s69, v[124:125]
	v_lshlrev_b64 v[126:127], 1, v[152:153]
	v_lshl_add_u64 v[152:153], v[170:171], 0, v[126:127]
	v_pk_mul_f32 v[120:121], v[120:121], s[44:45] op_sel_hi:[1,0]
	v_pk_mul_f32 v[116:117], v[116:117], s[44:45] op_sel_hi:[1,0]
	v_pk_mul_f32 v[112:113], v[112:113], s[44:45] op_sel_hi:[1,0]
	v_pk_mul_f32 v[110:111], v[110:111], s[44:45] op_sel_hi:[1,0]
	v_pk_mul_f32 v[108:109], v[108:109], s[44:45] op_sel_hi:[1,0]
	global_store_dwordx2 v[152:153], v[154:155], off
	v_pk_mul_f32 v[122:123], v[122:123], s[44:45] op_sel_hi:[1,0]
	v_cvt_pk_bf16_f32 v120, v120, v121
	v_pk_mul_f32 v[118:119], v[118:119], s[44:45] op_sel_hi:[1,0]
	v_cvt_pk_bf16_f32 v121, v122, v123
	global_store_dwordx2 v[152:153], v[120:121], off offset:32
	v_cvt_pk_bf16_f32 v116, v116, v117
	v_cvt_pk_bf16_f32 v117, v118, v119
	global_store_dwordx2 v[152:153], v[116:117], off offset:256
	v_pk_mul_f32 v[114:115], v[114:115], s[44:45] op_sel_hi:[1,0]
	v_cvt_pk_bf16_f32 v112, v112, v113
	v_pk_mul_f32 v[104:105], v[104:105], s[44:45] op_sel_hi:[1,0]
	v_cvt_pk_bf16_f32 v113, v114, v115
	global_store_dwordx2 v[152:153], v[112:113], off offset:288
	v_cvt_pk_bf16_f32 v108, v108, v109
	v_cvt_pk_bf16_f32 v109, v110, v111
; __device__ __forceinline__ unsigned cvt_pk_bf16(float lo, float hi) { unsigned r; asm volatile("v_cvt_pk_bf16_f32 %0, %1, %2" : "=v"(r) : "v"(lo), "v"(hi)); return r; }
;     __device__ __forceinline__ void operator()(const f32x4 (&acc)[2][2][4][2], const Unit& u, int wr, int wc, int fr, int fq) const {
;     ...
;         if (u.pn < 2) {
; #pragma unroll
;             for (int ai = 0; ai < 2; ++ai)
; #pragma unroll
;                 for (int m = 0; m < 4; ++m)
; #pragma unroll
;                     for (int bj = 0; bj < 2; ++bj)
; #pragma unroll
;                         for (int n = 0; n < 2; ++n) { const f32x4 v = acc[ai][bj][m][n] * QS_MLA; unsigned lo = cvt_pk_bf16(v[0], v[1]), hi = cvt_pk_bf16(v[2], v[3]);
;                             unsigned long long w = (unsigned long long)lo | ((unsigned long long)hi << 32);
;                             *(unsigned long long*)(O + (size_t)(row0 + ai * HALF + m * 16) * 768 + col0 + bj * HALF + n * 16) = w; }
	v_mad_i64_i32 v[110:111], s[20:21], v166, s69, v[124:125]
	v_lshl_add_u64 v[110:111], v[110:111], 0, v[126:127]
	v_pk_mul_f32 v[100:101], v[100:101], s[44:45] op_sel_hi:[1,0]
	v_pk_mul_f32 v[96:97], v[96:97], s[44:45] op_sel_hi:[1,0]
	v_pk_mul_f32 v[94:95], v[94:95], s[44:45] op_sel_hi:[1,0]
	v_pk_mul_f32 v[92:93], v[92:93], s[44:45] op_sel_hi:[1,0]
	global_store_dwordx2 v[110:111], v[108:109], off
	v_pk_mul_f32 v[106:107], v[106:107], s[44:45] op_sel_hi:[1,0]
	v_cvt_pk_bf16_f32 v104, v104, v105
	v_pk_mul_f32 v[102:103], v[102:103], s[44:45] op_sel_hi:[1,0]
	v_cvt_pk_bf16_f32 v105, v106, v107
	global_store_dwordx2 v[110:111], v[104:105], off offset:32
	v_cvt_pk_bf16_f32 v100, v100, v101
	v_cvt_pk_bf16_f32 v101, v102, v103
	global_store_dwordx2 v[110:111], v[100:101], off offset:256
	v_pk_mul_f32 v[98:99], v[98:99], s[44:45] op_sel_hi:[1,0]
	v_cvt_pk_bf16_f32 v96, v96, v97
	v_pk_mul_f32 v[88:89], v[88:89], s[44:45] op_sel_hi:[1,0]
	v_cvt_pk_bf16_f32 v97, v98, v99
	global_store_dwordx2 v[110:111], v[96:97], off offset:288
	v_cvt_pk_bf16_f32 v92, v92, v93
	v_cvt_pk_bf16_f32 v93, v94, v95
	v_mad_i64_i32 v[94:95], s[20:21], v165, s69, v[124:125]
	v_lshl_add_u64 v[94:95], v[94:95], 0, v[126:127]
	v_pk_mul_f32 v[84:85], v[84:85], s[44:45] op_sel_hi:[1,0]
	v_pk_mul_f32 v[80:81], v[80:81], s[44:45] op_sel_hi:[1,0]
	v_pk_mul_f32 v[78:79], v[78:79], s[44:45] op_sel_hi:[1,0]
	v_pk_mul_f32 v[76:77], v[76:77], s[44:45] op_sel_hi:[1,0]
	global_store_dwordx2 v[94:95], v[92:93], off
	v_pk_mul_f32 v[90:91], v[90:91], s[44:45] op_sel_hi:[1,0]
	v_cvt_pk_bf16_f32 v88, v88, v89
	v_pk_mul_f32 v[86:87], v[86:87], s[44:45] op_sel_hi:[1,0]
	v_cvt_pk_bf16_f32 v89, v90, v91
	global_store_dwordx2 v[94:95], v[88:89], off offset:32
	v_cvt_pk_bf16_f32 v84, v84, v85
	v_cvt_pk_bf16_f32 v85, v86, v87
	global_store_dwordx2 v[94:95], v[84:85], off offset:256
	v_pk_mul_f32 v[82:83], v[82:83], s[44:45] op_sel_hi:[1,0]
	v_cvt_pk_bf16_f32 v80, v80, v81
	v_pk_mul_f32 v[72:73], v[72:73], s[44:45] op_sel_hi:[1,0]
	v_cvt_pk_bf16_f32 v81, v82, v83
	global_store_dwordx2 v[94:95], v[80:81], off offset:288
	v_cvt_pk_bf16_f32 v76, v76, v77
	v_cvt_pk_bf16_f32 v77, v78, v79
	v_mad_i64_i32 v[78:79], s[20:21], v164, s69, v[124:125]
	v_lshl_add_u64 v[78:79], v[78:79], 0, v[126:127]
	v_pk_mul_f32 v[68:69], v[68:69], s[44:45] op_sel_hi:[1,0]
	v_pk_mul_f32 v[64:65], v[64:65], s[44:45] op_sel_hi:[1,0]
	v_pk_mul_f32 v[62:63], v[62:63], s[44:45] op_sel_hi:[1,0]
	v_pk_mul_f32 v[60:61], v[60:61], s[44:45] op_sel_hi:[1,0]
	global_store_dwordx2 v[78:79], v[76:77], off
	v_pk_mul_f32 v[74:75], v[74:75], s[44:45] op_sel_hi:[1,0]
	v_cvt_pk_bf16_f32 v72, v72, v73
	v_pk_mul_f32 v[70:71], v[70:71], s[44:45] op_sel_hi:[1,0]
	v_cvt_pk_bf16_f32 v73, v74, v75
	global_store_dwordx2 v[78:79], v[72:73], off offset:32
	v_cvt_pk_bf16_f32 v68, v68, v69
	v_cvt_pk_bf16_f32 v69, v70, v71
	global_store_dwordx2 v[78:79], v[68:69], off offset:256
	v_pk_mul_f32 v[66:67], v[66:67], s[44:45] op_sel_hi:[1,0]
	v_cvt_pk_bf16_f32 v64, v64, v65
	v_pk_mul_f32 v[56:57], v[56:57], s[44:45] op_sel_hi:[1,0]
	v_cvt_pk_bf16_f32 v65, v66, v67
	global_store_dwordx2 v[78:79], v[64:65], off offset:288
	v_cvt_pk_bf16_f32 v60, v60, v61
	v_cvt_pk_bf16_f32 v61, v62, v63
	v_mad_i64_i32 v[62:63], s[20:21], v163, s69, v[124:125]
	v_lshl_add_u64 v[62:63], v[62:63], 0, v[126:127]
	v_pk_mul_f32 v[52:53], v[52:53], s[44:45] op_sel_hi:[1,0]
	v_pk_mul_f32 v[48:49], v[48:49], s[44:45] op_sel_hi:[1,0]
	v_pk_mul_f32 v[46:47], v[46:47], s[44:45] op_sel_hi:[1,0]
	v_pk_mul_f32 v[44:45], v[44:45], s[44:45] op_sel_hi:[1,0]
	global_store_dwordx2 v[62:63], v[60:61], off
; __device__ __forceinline__ unsigned cvt_pk_bf16(float lo, float hi) { unsigned r; asm volatile("v_cvt_pk_bf16_f32 %0, %1, %2" : "=v"(r) : "v"(lo), "v"(hi)); return r; }
;     __device__ __forceinline__ void operator()(const f32x4 (&acc)[2][2][4][2], const Unit& u, int wr, int wc, int fr, int fq) const {
;     ...
;         if (u.pn < 2) {
; #pragma unroll
;             for (int ai = 0; ai < 2; ++ai)
; #pragma unroll
;                 for (int m = 0; m < 4; ++m)
; #pragma unroll
;                     for (int bj = 0; bj < 2; ++bj)
; #pragma unroll
;                         for (int n = 0; n < 2; ++n) { const f32x4 v = acc[ai][bj][m][n] * QS_MLA; unsigned lo = cvt_pk_bf16(v[0], v[1]), hi = cvt_pk_bf16(v[2], v[3]);
;                             unsigned long long w = (unsigned long long)lo | ((unsigned long long)hi << 32);
;                             *(unsigned long long*)(O + (size_t)(row0 + ai * HALF + m * 16) * 768 + col0 + bj * HALF + n * 16) = w; }
	v_pk_mul_f32 v[58:59], v[58:59], s[44:45] op_sel_hi:[1,0]
	v_cvt_pk_bf16_f32 v56, v56, v57
	v_pk_mul_f32 v[54:55], v[54:55], s[44:45] op_sel_hi:[1,0]
	v_cvt_pk_bf16_f32 v57, v58, v59
	global_store_dwordx2 v[62:63], v[56:57], off offset:32
	v_cvt_pk_bf16_f32 v52, v52, v53
	v_cvt_pk_bf16_f32 v53, v54, v55
	global_store_dwordx2 v[62:63], v[52:53], off offset:256
	v_pk_mul_f32 v[50:51], v[50:51], s[44:45] op_sel_hi:[1,0]
	v_cvt_pk_bf16_f32 v48, v48, v49
	v_pk_mul_f32 v[40:41], v[40:41], s[44:45] op_sel_hi:[1,0]
	v_cvt_pk_bf16_f32 v49, v50, v51
	global_store_dwordx2 v[62:63], v[48:49], off offset:288
	v_cvt_pk_bf16_f32 v44, v44, v45
	v_cvt_pk_bf16_f32 v45, v46, v47
	v_mad_i64_i32 v[46:47], s[20:21], v162, s69, v[124:125]
	v_lshl_add_u64 v[46:47], v[46:47], 0, v[126:127]
	v_pk_mul_f32 v[36:37], v[36:37], s[44:45] op_sel_hi:[1,0]
	v_pk_mul_f32 v[32:33], v[32:33], s[44:45] op_sel_hi:[1,0]
	v_pk_mul_f32 v[30:31], v[30:31], s[44:45] op_sel_hi:[1,0]
	v_pk_mul_f32 v[28:29], v[28:29], s[44:45] op_sel_hi:[1,0]
	global_store_dwordx2 v[46:47], v[44:45], off
	v_pk_mul_f32 v[42:43], v[42:43], s[44:45] op_sel_hi:[1,0]
	v_cvt_pk_bf16_f32 v40, v40, v41
	v_pk_mul_f32 v[38:39], v[38:39], s[44:45] op_sel_hi:[1,0]
	v_cvt_pk_bf16_f32 v41, v42, v43
	global_store_dwordx2 v[46:47], v[40:41], off offset:32
	v_cvt_pk_bf16_f32 v36, v36, v37
	v_cvt_pk_bf16_f32 v37, v38, v39
	global_store_dwordx2 v[46:47], v[36:37], off offset:256
	v_pk_mul_f32 v[34:35], v[34:35], s[44:45] op_sel_hi:[1,0]
	v_cvt_pk_bf16_f32 v32, v32, v33
	v_pk_mul_f32 v[24:25], v[24:25], s[44:45] op_sel_hi:[1,0]
	v_cvt_pk_bf16_f32 v33, v34, v35
	global_store_dwordx2 v[46:47], v[32:33], off offset:288
	v_cvt_pk_bf16_f32 v28, v28, v29
	v_cvt_pk_bf16_f32 v29, v30, v31
	v_mad_i64_i32 v[30:31], s[20:21], v161, s69, v[124:125]
	v_lshl_add_u64 v[30:31], v[30:31], 0, v[126:127]
	v_pk_mul_f32 v[20:21], v[20:21], s[44:45] op_sel_hi:[1,0]
	v_pk_mul_f32 v[16:17], v[16:17], s[44:45] op_sel_hi:[1,0]
	v_pk_mul_f32 v[14:15], v[14:15], s[44:45] op_sel_hi:[1,0]
	v_pk_mul_f32 v[12:13], v[12:13], s[44:45] op_sel_hi:[1,0]
	global_store_dwordx2 v[30:31], v[28:29], off
	v_pk_mul_f32 v[26:27], v[26:27], s[44:45] op_sel_hi:[1,0]
	v_cvt_pk_bf16_f32 v24, v24, v25
	v_pk_mul_f32 v[22:23], v[22:23], s[44:45] op_sel_hi:[1,0]
	v_cvt_pk_bf16_f32 v25, v26, v27
	global_store_dwordx2 v[30:31], v[24:25], off offset:32
	v_cvt_pk_bf16_f32 v20, v20, v21
	v_cvt_pk_bf16_f32 v21, v22, v23
	global_store_dwordx2 v[30:31], v[20:21], off offset:256
	v_pk_mul_f32 v[18:19], v[18:19], s[44:45] op_sel_hi:[1,0]
	v_cvt_pk_bf16_f32 v16, v16, v17
	v_pk_mul_f32 v[8:9], v[8:9], s[44:45] op_sel_hi:[1,0]
	v_cvt_pk_bf16_f32 v17, v18, v19
	global_store_dwordx2 v[30:31], v[16:17], off offset:288
	v_cvt_pk_bf16_f32 v12, v12, v13
	v_cvt_pk_bf16_f32 v13, v14, v15
	v_mad_i64_i32 v[14:15], s[20:21], v159, s69, v[124:125]
	v_lshl_add_u64 v[152:153], v[14:15], 0, v[126:127]
	v_pk_mul_f32 v[4:5], v[4:5], s[44:45] op_sel_hi:[1,0]
	global_store_dwordx2 v[152:153], v[12:13], off
	v_pk_mul_f32 v[10:11], v[10:11], s[44:45] op_sel_hi:[1,0]
	v_cvt_pk_bf16_f32 v8, v8, v9
	v_pk_mul_f32 v[6:7], v[6:7], s[44:45] op_sel_hi:[1,0]
	v_cvt_pk_bf16_f32 v9, v10, v11
	global_store_dwordx2 v[152:153], v[8:9], off offset:32
	v_cvt_pk_bf16_f32 v4, v4, v5
	v_cvt_pk_bf16_f32 v5, v6, v7
	global_store_dwordx2 v[152:153], v[4:5], off offset:256
	v_pk_mul_f32 v[2:3], v[2:3], s[44:45] op_sel_hi:[1,0]
	v_pk_mul_f32 v[0:1], v[0:1], s[44:45] op_sel_hi:[1,0]
	s_nop 0
	v_cvt_pk_bf16_f32 v154, v0, v1
	v_cvt_pk_bf16_f32 v155, v2, v3
	s_and_b64 vcc, exec, s[6:7]
	s_mov_b64 s[6:7], -1
	global_store_dwordx2 v[152:153], v[154:155], off offset:288
	s_cbranch_vccnz .LBB0_641

;     __device__ __forceinline__ void operator()(const f32x4 (&acc)[2][2][4][2], const Unit& u, int wr, int wc, int fr, int fq) const {
;         const int row0 = u.pm * BM + wr * 64 + fr, col0 = u.pn * BM + wc * 32 + 4 * fq;
; #pragma unroll
;         for (int ai = 0; ai < 2; ++ai)
; #pragma unroll
;             for (int m = 0; m < 4; ++m)
; #pragma unroll
;                 for (int bj = 0; bj < 2; ++bj)
; #pragma unroll
;                     for (int n = 0; n < 2; ++n) *(f32x4*)(out + (size_t)(row0 + ai * HALF + m * 16) * ldc + col0 + bj * HALF + n * 16) = acc[ai][bj][m][n];
;     }
.LBB0_686:
	v_lshl_add_u32 v148, s83, 8, v129
	v_lshl_or_b32 v150, s86, 8, v139
	v_ashrrev_i32_e32 v149, 31, v148
	v_ashrrev_i32_e32 v151, 31, v150
	v_lshlrev_b64 v[152:153], 11, v[148:149]
	v_lshl_add_u64 v[152:153], s[36:37], 0, v[152:153]
	v_lshlrev_b64 v[150:151], 2, v[150:151]
	v_lshl_add_u64 v[152:153], v[152:153], 0, v[150:151]
	global_store_dwordx4 v[152:153], v[124:127], off sc0 sc1
	global_store_dwordx4 v[152:153], v[120:123], off offset:64 sc0 sc1
	global_store_dwordx4 v[152:153], v[116:119], off offset:512 sc0 sc1
	global_store_dwordx4 v[152:153], v[112:115], off offset:576 sc0 sc1
	s_nop 1
	v_or_b32_e32 v112, 16, v148
	v_ashrrev_i32_e32 v113, 31, v112
	v_lshlrev_b64 v[112:113], 11, v[112:113]
	v_lshl_add_u64 v[112:113], s[36:37], 0, v[112:113]
	v_lshl_add_u64 v[112:113], v[112:113], 0, v[150:151]
	global_store_dwordx4 v[112:113], v[108:111], off sc0 sc1
	global_store_dwordx4 v[112:113], v[104:107], off offset:64 sc0 sc1
	global_store_dwordx4 v[112:113], v[100:103], off offset:512 sc0 sc1
	global_store_dwordx4 v[112:113], v[96:99], off offset:576 sc0 sc1
	s_nop 1
	v_or_b32_e32 v96, 32, v148
	v_ashrrev_i32_e32 v97, 31, v96
	v_lshlrev_b64 v[96:97], 11, v[96:97]
	v_lshl_add_u64 v[96:97], s[36:37], 0, v[96:97]
	v_lshl_add_u64 v[96:97], v[96:97], 0, v[150:151]
	global_store_dwordx4 v[96:97], v[92:95], off sc0 sc1
	global_store_dwordx4 v[96:97], v[88:91], off offset:64 sc0 sc1
	global_store_dwordx4 v[96:97], v[84:87], off offset:512 sc0 sc1
	global_store_dwordx4 v[96:97], v[80:83], off offset:576 sc0 sc1
	s_nop 1
	v_or_b32_e32 v80, 48, v148
	v_ashrrev_i32_e32 v81, 31, v80
	v_lshlrev_b64 v[80:81], 11, v[80:81]
	v_lshl_add_u64 v[80:81], s[36:37], 0, v[80:81]
	v_lshl_add_u64 v[80:81], v[80:81], 0, v[150:151]
	global_store_dwordx4 v[80:81], v[76:79], off sc0 sc1
	global_store_dwordx4 v[80:81], v[72:75], off offset:64 sc0 sc1
	global_store_dwordx4 v[80:81], v[68:71], off offset:512 sc0 sc1
	global_store_dwordx4 v[80:81], v[64:67], off offset:576 sc0 sc1
	s_nop 1
	v_add_co_u32_e32 v66, vcc, s79, v152
	v_lshl_add_u64 v[64:65], v[152:153], 0, s[44:45]
	s_nop 0
	v_addc_co_u32_e32 v67, vcc, 0, v153, vcc
	global_store_dwordx4 v[66:67], v[60:63], off sc0 sc1
	global_store_dwordx4 v[64:65], v[56:59], off offset:64 sc0 sc1
	global_store_dwordx4 v[64:65], v[52:55], off offset:512 sc0 sc1
	global_store_dwordx4 v[64:65], v[48:51], off offset:576 sc0 sc1
	s_nop 1
	v_add_co_u32_e32 v50, vcc, s80, v152
	v_lshl_add_u64 v[48:49], v[152:153], 0, s[46:47]
	s_nop 0
	v_addc_co_u32_e32 v51, vcc, 0, v153, vcc
	global_store_dwordx4 v[50:51], v[44:47], off sc0 sc1
	global_store_dwordx4 v[48:49], v[40:43], off offset:64 sc0 sc1
	global_store_dwordx4 v[48:49], v[36:39], off offset:512 sc0 sc1
	global_store_dwordx4 v[48:49], v[32:35], off offset:576 sc0 sc1
	s_nop 1
	v_add_co_u32_e32 v34, vcc, s81, v152
	v_lshl_add_u64 v[32:33], v[152:153], 0, s[48:49]
	s_nop 0
	v_addc_co_u32_e32 v35, vcc, 0, v153, vcc
	global_store_dwordx4 v[34:35], v[28:31], off sc0 sc1
	global_store_dwordx4 v[32:33], v[24:27], off offset:64 sc0 sc1
	global_store_dwordx4 v[32:33], v[20:23], off offset:512 sc0 sc1
	global_store_dwordx4 v[32:33], v[16:19], off offset:576 sc0 sc1
	s_nop 1
	v_add_co_u32_e32 v18, vcc, s82, v152
	v_lshl_add_u64 v[16:17], v[152:153], 0, s[50:51]
	s_nop 0
	v_addc_co_u32_e32 v19, vcc, 0, v153, vcc
	s_and_b64 vcc, exec, s[6:7]
	s_mov_b64 s[6:7], -1
	global_store_dwordx4 v[18:19], v[12:15], off sc0 sc1
	global_store_dwordx4 v[16:17], v[8:11], off offset:64 sc0 sc1
	global_store_dwordx4 v[16:17], v[4:7], off offset:512 sc0 sc1
	global_store_dwordx4 v[16:17], v[0:3], off offset:576 sc0 sc1
	s_cbranch_vccnz .LBB0_670
	s_andn2_b64 vcc, exec, s[18:19]
	s_cbranch_vccnz .LBB0_669
	s_barrier
	s_branch .LBB0_669

;     __device__ __forceinline__ void operator()(const f32x4 (&acc)[2][2][4][2], const Unit& u, int wr, int wc, int fr, int fq) const {
;         const int row0 = u.pm * BM + wr * 64 + fr, col0 = u.pn * BM + wc * 32 + 4 * fq;
; #pragma unroll
;         for (int ai = 0; ai < 2; ++ai)
; #pragma unroll
;             for (int m = 0; m < 4; ++m)
; #pragma unroll
;                 for (int bj = 0; bj < 2; ++bj)
; #pragma unroll
;                     for (int n = 0; n < 2; ++n) *(f32x4*)(out + (size_t)(row0 + ai * HALF + m * 16) * ldc + col0 + bj * HALF + n * 16) = acc[ai][bj][m][n];
;     }
.LBB0_715:
	v_lshl_add_u32 v148, s79, 8, v129
	v_lshl_or_b32 v150, s82, 8, v139
	v_ashrrev_i32_e32 v149, 31, v148
	v_ashrrev_i32_e32 v151, 31, v150
	v_lshlrev_b64 v[152:153], 11, v[148:149]
	v_lshl_add_u64 v[152:153], s[36:37], 0, v[152:153]
	v_lshlrev_b64 v[150:151], 2, v[150:151]
	v_lshl_add_u64 v[152:153], v[152:153], 0, v[150:151]
	global_store_dwordx4 v[152:153], v[124:127], off sc0 sc1
	global_store_dwordx4 v[152:153], v[120:123], off offset:64 sc0 sc1
	global_store_dwordx4 v[152:153], v[116:119], off offset:512 sc0 sc1
	global_store_dwordx4 v[152:153], v[112:115], off offset:576 sc0 sc1
	s_nop 1
	v_or_b32_e32 v112, 16, v148
	v_ashrrev_i32_e32 v113, 31, v112
	v_lshlrev_b64 v[112:113], 11, v[112:113]
	v_lshl_add_u64 v[112:113], s[36:37], 0, v[112:113]
	v_lshl_add_u64 v[112:113], v[112:113], 0, v[150:151]
	global_store_dwordx4 v[112:113], v[108:111], off sc0 sc1
	global_store_dwordx4 v[112:113], v[104:107], off offset:64 sc0 sc1
	global_store_dwordx4 v[112:113], v[100:103], off offset:512 sc0 sc1
	global_store_dwordx4 v[112:113], v[96:99], off offset:576 sc0 sc1
	s_nop 1
	v_or_b32_e32 v96, 32, v148
	v_ashrrev_i32_e32 v97, 31, v96
	v_lshlrev_b64 v[96:97], 11, v[96:97]
	v_lshl_add_u64 v[96:97], s[36:37], 0, v[96:97]
	v_lshl_add_u64 v[96:97], v[96:97], 0, v[150:151]
	global_store_dwordx4 v[96:97], v[92:95], off sc0 sc1
	global_store_dwordx4 v[96:97], v[88:91], off offset:64 sc0 sc1
	global_store_dwordx4 v[96:97], v[84:87], off offset:512 sc0 sc1
	global_store_dwordx4 v[96:97], v[80:83], off offset:576 sc0 sc1
	s_nop 1
	v_or_b32_e32 v80, 48, v148
	v_ashrrev_i32_e32 v81, 31, v80
	v_lshlrev_b64 v[80:81], 11, v[80:81]
	v_lshl_add_u64 v[80:81], s[36:37], 0, v[80:81]
	v_lshl_add_u64 v[80:81], v[80:81], 0, v[150:151]
	global_store_dwordx4 v[80:81], v[76:79], off sc0 sc1
	global_store_dwordx4 v[80:81], v[72:75], off offset:64 sc0 sc1
	global_store_dwordx4 v[80:81], v[68:71], off offset:512 sc0 sc1
	global_store_dwordx4 v[80:81], v[64:67], off offset:576 sc0 sc1
	s_nop 1
	v_add_co_u32_e32 v66, vcc, s75, v152
	v_lshl_add_u64 v[64:65], v[152:153], 0, s[42:43]
	s_nop 0
	v_addc_co_u32_e32 v67, vcc, 0, v153, vcc
	global_store_dwordx4 v[66:67], v[60:63], off sc0 sc1
	global_store_dwordx4 v[64:65], v[56:59], off offset:64 sc0 sc1
	global_store_dwordx4 v[64:65], v[52:55], off offset:512 sc0 sc1
	global_store_dwordx4 v[64:65], v[48:51], off offset:576 sc0 sc1
	s_nop 1
	v_add_co_u32_e32 v50, vcc, s76, v152
	v_lshl_add_u64 v[48:49], v[152:153], 0, s[44:45]
	s_nop 0
	v_addc_co_u32_e32 v51, vcc, 0, v153, vcc
	global_store_dwordx4 v[50:51], v[44:47], off sc0 sc1
	global_store_dwordx4 v[48:49], v[40:43], off offset:64 sc0 sc1
	global_store_dwordx4 v[48:49], v[36:39], off offset:512 sc0 sc1
	global_store_dwordx4 v[48:49], v[32:35], off offset:576 sc0 sc1
	s_nop 1
	v_add_co_u32_e32 v34, vcc, s77, v152
	v_lshl_add_u64 v[32:33], v[152:153], 0, s[46:47]
	s_nop 0
	v_addc_co_u32_e32 v35, vcc, 0, v153, vcc
	global_store_dwordx4 v[34:35], v[28:31], off sc0 sc1
	global_store_dwordx4 v[32:33], v[24:27], off offset:64 sc0 sc1
	global_store_dwordx4 v[32:33], v[20:23], off offset:512 sc0 sc1
	global_store_dwordx4 v[32:33], v[16:19], off offset:576 sc0 sc1
	s_nop 1
	v_add_co_u32_e32 v18, vcc, s78, v152
	v_lshl_add_u64 v[16:17], v[152:153], 0, s[48:49]
	s_nop 0
	v_addc_co_u32_e32 v19, vcc, 0, v153, vcc
	s_and_b64 vcc, exec, s[6:7]
	s_mov_b64 s[6:7], -1
	global_store_dwordx4 v[18:19], v[12:15], off sc0 sc1
	global_store_dwordx4 v[16:17], v[8:11], off offset:64 sc0 sc1
	global_store_dwordx4 v[16:17], v[4:7], off offset:512 sc0 sc1
	global_store_dwordx4 v[16:17], v[0:3], off offset:576 sc0 sc1
	s_cbranch_vccnz .LBB0_699
	s_andn2_b64 vcc, exec, s[18:19]
	s_cbranch_vccnz .LBB0_698
	s_barrier
	s_branch .LBB0_698

; __device__ __forceinline__ unsigned cvt_pk_bf16(float lo, float hi) { unsigned r; asm volatile("v_cvt_pk_bf16_f32 %0, %1, %2" : "=v"(r) : "v"(lo), "v"(hi)); return r; }
;     __device__ __forceinline__ void operator()(const f32x4 (&acc)[2][2][4][2], const Unit& u, int wr, int wc, int fr, int fq) const {
;         const int row0 = u.pm * BM + wr * 64 + fr; int colt = u.pn * BM; bf16_t* base = O;
;         float sc = 1.f; if (split_cols) { const int t = colt / split_cols; base += (size_t)t * split_stride; colt -= t * split_cols; if (t == 0) sc = scale0; }
;         const int col0 = colt + wc * 32 + 8 * fq, bcol0 = u.pn * BM + wc * 32 + 8 * fq;
;         f32x4 bv[2][2];
; #pragma unroll
;         for (int bj = 0; bj < 2; ++bj)
; #pragma unroll
;             for (int n = 0; n < 2; ++n) bv[bj][n] = bias ? *(const f32x4*)(bias + bcol0 + bj * HALF + 4 * n) : (f32x4){0.f, 0.f, 0.f, 0.f};
; #pragma unroll
;         for (int ai = 0; ai < 2; ++ai)
; #pragma unroll
;             for (int m = 0; m < 4; ++m) { bf16_t* rowp = base + (size_t)(row0 + ai * HALF + m * 16) * ldc + col0;
; #pragma unroll
;                 for (int bj = 0; bj < 2; ++bj) { f32x4 v0 = acc[ai][bj][m][0] + bv[bj][0], v1 = acc[ai][bj][m][1] + bv[bj][1];
;                     if (ACT == 1) { f32x2 a = gelu_pk((f32x2){v0[0], v0[1]}), b = gelu_pk((f32x2){v0[2], v0[3]}), c = gelu_pk((f32x2){v1[0], v1[1]}), d = gelu_pk((f32x2){v1[2], v1[3]});
;                         v0 = (f32x4){a.x, a.y, b.x, b.y}; v1 = (f32x4){c.x, c.y, d.x, d.y}; }
;                     v0 = v0 * sc; v1 = v1 * sc; u32x4 w; w.x = cvt_pk_bf16(v0[0], v0[1]); w.y = cvt_pk_bf16(v0[2], v0[3]); w.z = cvt_pk_bf16(v1[0], v1[1]); w.w = cvt_pk_bf16(v1[2], v1[3]);
;                     *(u32x4*)(rowp + bj * HALF) = w; } }
.LBB0_745:
	v_lshl_add_u32 v24, s74, 8, v129
	v_lshl_or_b32 v16, s77, 8, v143
	v_ashrrev_i32_e32 v17, 31, v16
	v_ashrrev_i32_e32 v25, 31, v24
	v_lshl_add_u64 v[26:27], v[16:17], 1, s[10:11]
	v_lshlrev_b64 v[16:17], 11, v[24:25]
	v_lshl_add_u64 v[164:165], v[26:27], 0, v[16:17]
	v_cvt_pk_bf16_f32 v16, v124, v125
	v_cvt_pk_bf16_f32 v17, v126, v127
	v_cvt_pk_bf16_f32 v18, v120, v121
	v_cvt_pk_bf16_f32 v19, v122, v123
	global_store_dwordx4 v[164:165], v[16:19], off sc0 sc1
	s_nop 1
	v_cvt_pk_bf16_f32 v16, v154, v155
	v_cvt_pk_bf16_f32 v17, v152, v153
	v_cvt_pk_bf16_f32 v18, v158, v159
	v_cvt_pk_bf16_f32 v19, v156, v157
	global_store_dwordx4 v[164:165], v[16:19], off offset:256 sc0 sc1
	s_nop 1
	v_or_b32_e32 v16, 16, v24
	v_ashrrev_i32_e32 v17, 31, v16
	v_lshlrev_b64 v[16:17], 11, v[16:17]
	v_lshl_add_u64 v[120:121], v[26:27], 0, v[16:17]
	v_cvt_pk_bf16_f32 v16, v102, v103
	v_cvt_pk_bf16_f32 v17, v100, v101
	v_cvt_pk_bf16_f32 v18, v110, v111
	v_cvt_pk_bf16_f32 v19, v108, v109
	global_store_dwordx4 v[120:121], v[16:19], off sc0 sc1
	s_nop 1
	v_cvt_pk_bf16_f32 v16, v114, v115
	v_cvt_pk_bf16_f32 v17, v112, v113
	v_cvt_pk_bf16_f32 v18, v118, v119
	v_cvt_pk_bf16_f32 v19, v116, v117
	global_store_dwordx4 v[120:121], v[16:19], off offset:256 sc0 sc1
	s_nop 1
	v_or_b32_e32 v16, 32, v24
	v_ashrrev_i32_e32 v17, 31, v16
	v_lshlrev_b64 v[16:17], 11, v[16:17]
	v_lshl_add_u64 v[100:101], v[26:27], 0, v[16:17]
	v_cvt_pk_bf16_f32 v16, v86, v87
	v_cvt_pk_bf16_f32 v17, v84, v85
	v_cvt_pk_bf16_f32 v18, v94, v95
	v_cvt_pk_bf16_f32 v19, v92, v93
	global_store_dwordx4 v[100:101], v[16:19], off sc0 sc1
	s_nop 1
	v_cvt_pk_bf16_f32 v16, v98, v99
	v_cvt_pk_bf16_f32 v17, v96, v97
	v_cvt_pk_bf16_f32 v18, v106, v107
	v_cvt_pk_bf16_f32 v19, v104, v105
	global_store_dwordx4 v[100:101], v[16:19], off offset:256 sc0 sc1
	s_nop 1
	v_or_b32_e32 v16, 48, v24
	v_ashrrev_i32_e32 v17, 31, v16
	v_lshlrev_b64 v[16:17], 11, v[16:17]
	v_lshl_add_u64 v[24:25], v[26:27], 0, v[16:17]
	v_cvt_pk_bf16_f32 v16, v74, v75
	v_cvt_pk_bf16_f32 v17, v72, v73
	v_cvt_pk_bf16_f32 v18, v78, v79
	v_cvt_pk_bf16_f32 v19, v76, v77
	global_store_dwordx4 v[24:25], v[16:19], off sc0 sc1
	v_add_co_u32_e32 v26, vcc, s71, v164
	s_nop 0
	v_cvt_pk_bf16_f32 v16, v68, v69
	v_cvt_pk_bf16_f32 v17, v70, v71
	v_cvt_pk_bf16_f32 v18, v64, v65
	v_cvt_pk_bf16_f32 v19, v66, v67
	global_store_dwordx4 v[24:25], v[16:19], off offset:256 sc0 sc1
	v_addc_co_u32_e32 v27, vcc, 0, v165, vcc
	s_nop 0
	v_cvt_pk_bf16_f32 v16, v60, v61
	v_cvt_pk_bf16_f32 v17, v62, v63
	v_lshl_add_u64 v[24:25], v[164:165], 0, s[40:41]
	v_cvt_pk_bf16_f32 v18, v56, v57
	v_cvt_pk_bf16_f32 v19, v58, v59
	global_store_dwordx4 v[26:27], v[16:19], off sc0 sc1
	v_add_co_u32_e32 v26, vcc, s72, v164
	s_nop 0
	v_cvt_pk_bf16_f32 v16, v82, v83
	v_cvt_pk_bf16_f32 v17, v80, v81
	v_cvt_pk_bf16_f32 v18, v90, v91
	v_cvt_pk_bf16_f32 v19, v88, v89
	global_store_dwordx4 v[24:25], v[16:19], off offset:256 sc0 sc1
	v_addc_co_u32_e32 v27, vcc, 0, v165, vcc
	s_nop 0
	v_cvt_pk_bf16_f32 v16, v38, v39
	v_cvt_pk_bf16_f32 v17, v36, v37
	v_lshl_add_u64 v[24:25], v[164:165], 0, s[42:43]
	v_cvt_pk_bf16_f32 v18, v46, v47
	v_cvt_pk_bf16_f32 v19, v44, v45
	global_store_dwordx4 v[26:27], v[16:19], off sc0 sc1
	s_nop 1
	v_cvt_pk_bf16_f32 v16, v50, v51
	v_cvt_pk_bf16_f32 v17, v48, v49
	v_cvt_pk_bf16_f32 v18, v54, v55
	v_cvt_pk_bf16_f32 v19, v52, v53
	global_store_dwordx4 v[24:25], v[16:19], off offset:256 sc0 sc1
	v_lshl_add_u64 v[24:25], v[164:165], 0, s[44:45]
	s_nop 0
	v_cvt_pk_bf16_f32 v16, v22, v23
	v_cvt_pk_bf16_f32 v17, v20, v21
	v_add_co_u32_e32 v20, vcc, s73, v164
	v_cvt_pk_bf16_f32 v18, v30, v31
	v_cvt_pk_bf16_f32 v19, v28, v29
	s_nop 1
	v_addc_co_u32_e32 v21, vcc, 0, v165, vcc
	global_store_dwordx4 v[20:21], v[16:19], off sc0 sc1
	v_lshl_add_u64 v[20:21], v[164:165], 0, s[46:47]
	s_nop 0
	v_cvt_pk_bf16_f32 v16, v34, v35
	v_cvt_pk_bf16_f32 v17, v32, v33
	v_cvt_pk_bf16_f32 v18, v42, v43
	v_cvt_pk_bf16_f32 v19, v40, v41
	global_store_dwordx4 v[24:25], v[16:19], off offset:256 sc0 sc1
	s_nop 1
	v_cvt_pk_bf16_f32 v16, v10, v11
	v_cvt_pk_bf16_f32 v17, v8, v9
	v_add_co_u32_e32 v8, vcc, 0x58000, v164
	v_cvt_pk_bf16_f32 v18, v14, v15
	v_cvt_pk_bf16_f32 v19, v12, v13
	s_nop 1
	v_addc_co_u32_e32 v9, vcc, 0, v165, vcc
	s_and_b64 vcc, exec, s[6:7]
	s_mov_b64 s[6:7], -1
	global_store_dwordx4 v[8:9], v[16:19], off sc0 sc1
	v_cvt_pk_bf16_f32 v4, v4, v5
	v_cvt_pk_bf16_f32 v5, v6, v7
	v_cvt_pk_bf16_f32 v6, v0, v1
	v_cvt_pk_bf16_f32 v7, v2, v3
	global_store_dwordx4 v[20:21], v[4:7], off offset:256 sc0 sc1
	s_cbranch_vccnz .LBB0_728
	s_andn2_b64 vcc, exec, s[16:17]
	s_cbranch_vccnz .LBB0_727
	s_barrier
	s_branch .LBB0_727

; #define LAS __attribute__((address_space(3)))
; __global__ void __launch_bounds__(NTHREADS, 2) mega_fwd(Args a_unused) {
;     ...
;     PH_BEGIN
;     for (int rp_ = 0; rp_ < REP_EW; ++rp_) {
;     {
;         LAS float* hbuf = (LAS float*)(lds + 131072 + wave * 1024);
;         LAS float* w2s = (LAS float*)lds;
;         for (int i = tid; i < 2 * 4096; i += NTHREADS) { const int kv = i >> 12, q4 = i & 4095; *(LAS f32x4*)(w2s + kv * 16384 + 4 * q4) = *(const f32x4*)(ap->in[kv ? 15 : 12] + 4 * q4); }
;         __syncthreads();
;         for (int idx = gw; idx < 2 * 4 * 512; idx += NGW) {
;             const int kv = idx >> 11, bg = (idx >> 9) & 3, n = idx & 511;
;             bf16* dst = (kv ? VCMP : KCMP) + ((size_t)bg * 512 + n) * 64;
;             if (n == 511) { dst[lane] = 0; continue; }
;             const float* Y = kv ? YV : YK; const float* pb = posb + kv * 256; const LAS float* w2 = w2s + kv * 16384;
.LBB0_801:
	s_or_b64 exec, exec, s[6:7]
	s_mov_b64 s[8:9], s[0:1]
	s_waitcnt lgkmcnt(0)
	s_barrier
	v_readfirstlane_b32 s12, v144
	v_mov_b64_e32 v[0:1], s[8:9]
	global_load_dwordx2 v[4:5], v[0:1], off offset:200
	s_mov_b64 s[10:11], 0
	s_movk_i32 s13, 0x1000
	v_mov_b32_e32 v2, 0x78
	v_mov_b32_e32 v3, 0x60
	v_mov_b32_e32 v1, 0
	s_movk_i32 s14, 0x1dff
	s_waitcnt vmcnt(0) lgkmcnt(0)
	v_readfirstlane_b32 s7, v5
	v_readfirstlane_b32 s6, v4
	v_mov_b32_e32 v4, v144
.LBB0_802:
	v_cmp_gt_u32_e32 vcc, s13, v4
	v_and_b32_e32 v5, 0x4000, v180
	v_add_u32_e32 v10, 0x200, v4
	v_cndmask_b32_e32 v0, v2, v3, vcc
	v_lshl_add_u64 v[6:7], s[8:9], 0, v[0:1]
	global_load_dwordx2 v[6:7], v[6:7], off
	v_lshlrev_b32_e32 v0, 2, v180
	v_and_b32_e32 v0, 0xfff0, v0
	v_cmp_lt_u32_e32 vcc, s14, v4
	v_lshlrev_b32_e32 v5, 2, v5
	v_add_u32_e32 v180, 0x800, v180
	s_or_b64 s[10:11], vcc, s[10:11]
	v_mov_b32_e32 v4, v10
	s_waitcnt vmcnt(0) lgkmcnt(0)
	v_lshl_add_u64 v[6:7], v[6:7], 0, v[0:1]
	global_load_dwordx4 v[6:9], v[6:7], off
	v_add3_u32 v0, 0, v5, v0
	s_waitcnt vmcnt(0) lgkmcnt(0)
	ds_write_b128 v0, v[6:9]
	s_andn2_b64 exec, exec, s[10:11]
	s_cbranch_execnz .LBB0_802
	s_or_b64 exec, exec, s[10:11]
	s_lshr_b32 s8, s12, 6
	s_add_i32 s3, s8, s3
	s_cmpk_gt_i32 s3, 0xfff
	s_waitcnt lgkmcnt(0)
	s_barrier
	s_cbranch_scc1 .LBB0_812
	s_lshl_b32 s14, s8, 10
	s_add_i32 s8, s14, 0
	v_mov_b32_e32 v129, 0
	s_add_i32 s8, s8, 0x20000
	v_mov_b32_e32 v143, v129
	v_add_u32_e32 v4, s8, v142
	v_lshl_add_u64 v[0:1], s[6:7], 0, v[142:143]
	s_mov_b64 s[8:9], 0x20000
	v_lshl_add_u64 v[0:1], v[0:1], 0, s[8:9]
	s_mov_b32 s15, 0x2d00000
	s_mov_b32 s16, 0x2e00000
	s_mov_b32 s17, 0x3fb8aa3b
	s_mov_b32 s18, 0xc2ce8ed0
	s_mov_b32 s19, 0x42b17218
	s_movk_i32 s20, 0x7fff
	v_mov_b32_e32 v5, 0x7f800000
	s_branch .LBB0_806

; #define LAS __attribute__((address_space(3)))
; __global__ void __launch_bounds__(NTHREADS, 2) mega_fwd(Args a_unused) {
;     ...
;             const float* Y = kv ? YV : YK; const float* pb = posb + kv * 256; const LAS float* w2 = w2s + kv * 16384;
; #pragma unroll
;             for (int i = 0; i < 4; ++i) { const int j = lane + 64 * i; const float p = Y[((size_t)bg * 512 + n) * 512 + j] + Y[((size_t)bg * 512 + n + 1) * 512 + 256 + j] + pb[j];
;                 const float y = 0.7978845608028654f * (p + 0.044715f * p * p * p); const float th = 1.f - 2.f / (expf(2.f * y) + 1.f); hbuf[j] = 0.5f * p * (1.f + th); }
.LBB0_808:
	s_ashr_i32 s12, s3, 11
	s_and_b64 s[10:11], s[10:11], exec
	s_cselect_b32 s10, s16, 0x3200000
	s_add_u32 s13, s6, s10
	s_addc_u32 s35, s7, 0
	s_lshl_b32 s10, s12, 8
	s_ashr_i32 s11, s10, 31
	s_lshl_b32 s21, s21, 11
	s_add_u32 s36, s13, s21
	s_addc_u32 s37, s35, 0
	v_lshl_add_u64 v[2:3], s[36:37], 0, v[142:143]
	v_lshl_add_u64 v[6:7], s[10:11], 2, v[0:1]
	global_load_dword v8, v[2:3], off
	global_load_dword v9, v[2:3], off offset:3072
	global_load_dword v10, v[6:7], off
	s_waitcnt vmcnt(0) lgkmcnt(0)
	v_add_f32_e32 v8, v8, v9
	v_add_f32_e32 v8, v8, v10
	v_mul_f32_e32 v9, 0x3d372713, v8
	v_mul_f32_e32 v9, v8, v9
	v_fma_f32 v9, v8, v9, v8
	v_mul_f32_e32 v9, 0x3f4c422a, v9
	v_add_f32_e32 v9, v9, v9
	v_mul_f32_e32 v10, 0x3fb8aa3b, v9
	v_fma_f32 v11, v9, s17, -v10
	v_rndne_f32_e32 v12, v10
	v_fmac_f32_e32 v11, 0x32a5705f, v9
	v_sub_f32_e32 v10, v10, v12
	v_add_f32_e32 v10, v10, v11
	v_cvt_i32_f32_e32 v12, v12
	v_exp_f32_e32 v10, v10
	v_cmp_ngt_f32_e32 vcc, s18, v9
	v_mul_f32_e32 v8, 0.5, v8
	v_ldexp_f32 v10, v10, v12
	v_cndmask_b32_e32 v10, 0, v10, vcc
	v_cmp_nlt_f32_e32 vcc, s19, v9
	s_nop 1
	v_cndmask_b32_e32 v9, v5, v10, vcc
	v_add_f32_e32 v9, 1.0, v9
	v_div_scale_f32 v10, s[10:11], v9, v9, 2.0
	v_rcp_f32_e32 v11, v10
	v_div_scale_f32 v12, vcc, 2.0, v9, 2.0
	v_fma_f32 v13, -v10, v11, 1.0
	v_fmac_f32_e32 v11, v13, v11
	v_mul_f32_e32 v13, v12, v11
	v_fma_f32 v14, -v10, v13, v12
	v_fmac_f32_e32 v13, v14, v11
	v_fma_f32 v10, -v10, v13, v12
	v_div_fmas_f32 v10, v10, v11, v13
	v_div_fixup_f32 v9, v10, v9, 2.0
	v_sub_f32_e32 v9, 1.0, v9
	v_add_f32_e32 v9, 1.0, v9
	v_mul_f32_e32 v8, v8, v9
	ds_write_b32 v4, v8
	global_load_dword v8, v[2:3], off offset:256
	global_load_dword v9, v[2:3], off offset:3328
	global_load_dword v10, v[6:7], off offset:256
	s_waitcnt vmcnt(0) lgkmcnt(0)
	v_add_f32_e32 v8, v8, v9
	v_add_f32_e32 v8, v8, v10
	v_mul_f32_e32 v9, 0x3d372713, v8
	v_mul_f32_e32 v9, v8, v9
	v_fma_f32 v9, v8, v9, v8
	v_mul_f32_e32 v9, 0x3f4c422a, v9
	v_add_f32_e32 v9, v9, v9
	v_mul_f32_e32 v10, 0x3fb8aa3b, v9
	v_fma_f32 v11, v9, s17, -v10
	v_rndne_f32_e32 v12, v10
	v_fmac_f32_e32 v11, 0x32a5705f, v9
	v_sub_f32_e32 v10, v10, v12
	v_add_f32_e32 v10, v10, v11
	v_cvt_i32_f32_e32 v12, v12
	v_exp_f32_e32 v10, v10
	v_cmp_ngt_f32_e32 vcc, s18, v9
	v_mul_f32_e32 v8, 0.5, v8
	v_ldexp_f32 v10, v10, v12
	v_cndmask_b32_e32 v10, 0, v10, vcc
	v_cmp_nlt_f32_e32 vcc, s19, v9
	s_nop 1
	v_cndmask_b32_e32 v9, v5, v10, vcc
	v_add_f32_e32 v9, 1.0, v9
	v_div_scale_f32 v10, s[10:11], v9, v9, 2.0
	v_rcp_f32_e32 v11, v10
	v_div_scale_f32 v12, vcc, 2.0, v9, 2.0
	v_fma_f32 v13, -v10, v11, 1.0
	v_fmac_f32_e32 v11, v13, v11
	v_mul_f32_e32 v13, v12, v11
	v_fma_f32 v14, -v10, v13, v12
	v_fmac_f32_e32 v13, v14, v11
	v_fma_f32 v10, -v10, v13, v12
	v_div_fmas_f32 v10, v10, v11, v13
	v_div_fixup_f32 v9, v10, v9, 2.0
	v_sub_f32_e32 v9, 1.0, v9
	v_add_f32_e32 v9, 1.0, v9
	v_mul_f32_e32 v8, v8, v9
	ds_write_b32 v4, v8 offset:256
	global_load_dword v8, v[2:3], off offset:512
	global_load_dword v9, v[2:3], off offset:3584
	global_load_dword v10, v[6:7], off offset:512
	s_waitcnt vmcnt(0) lgkmcnt(0)
	v_add_f32_e32 v8, v8, v9
	v_add_f32_e32 v8, v8, v10
	v_mul_f32_e32 v9, 0x3d372713, v8
	v_mul_f32_e32 v9, v8, v9
	v_fma_f32 v9, v8, v9, v8
	v_mul_f32_e32 v9, 0x3f4c422a, v9
	v_add_f32_e32 v9, v9, v9
	v_mul_f32_e32 v10, 0x3fb8aa3b, v9
	v_fma_f32 v11, v9, s17, -v10
	v_rndne_f32_e32 v12, v10
	v_fmac_f32_e32 v11, 0x32a5705f, v9
	v_sub_f32_e32 v10, v10, v12
	v_add_f32_e32 v10, v10, v11
	v_cvt_i32_f32_e32 v12, v12
	v_exp_f32_e32 v10, v10
	v_cmp_ngt_f32_e32 vcc, s18, v9
	v_mul_f32_e32 v8, 0.5, v8
	v_ldexp_f32 v10, v10, v12
	v_cndmask_b32_e32 v10, 0, v10, vcc
	v_cmp_nlt_f32_e32 vcc, s19, v9
	s_nop 1
	v_cndmask_b32_e32 v9, v5, v10, vcc
	v_add_f32_e32 v9, 1.0, v9
	v_div_scale_f32 v10, s[10:11], v9, v9, 2.0
	v_rcp_f32_e32 v11, v10
	v_div_scale_f32 v12, vcc, 2.0, v9, 2.0
	v_fma_f32 v13, -v10, v11, 1.0
	v_fmac_f32_e32 v11, v13, v11
	v_mul_f32_e32 v13, v12, v11
	v_fma_f32 v14, -v10, v13, v12
	v_fmac_f32_e32 v13, v14, v11
	v_fma_f32 v10, -v10, v13, v12
	v_div_fmas_f32 v10, v10, v11, v13
	v_div_fixup_f32 v9, v10, v9, 2.0
	v_sub_f32_e32 v9, 1.0, v9
	v_add_f32_e32 v9, 1.0, v9
	v_mul_f32_e32 v8, v8, v9
	ds_write_b32 v4, v8 offset:512
	global_load_dword v8, v[2:3], off offset:768
	global_load_dword v9, v[2:3], off offset:3840
	global_load_dword v10, v[6:7], off offset:768
	s_waitcnt vmcnt(0) lgkmcnt(0)
	v_add_f32_e32 v2, v8, v9
	v_add_f32_e32 v3, v2, v10
	v_mul_f32_e32 v2, 0x3d372713, v3
	v_mul_f32_e32 v2, v3, v2
	v_fma_f32 v2, v3, v2, v3
	v_mul_f32_e32 v2, 0x3f4c422a, v2
	v_add_f32_e32 v6, v2, v2
	v_mul_f32_e32 v2, 0x3fb8aa3b, v6
	v_fma_f32 v7, v6, s17, -v2
	v_rndne_f32_e32 v8, v2
	v_fmac_f32_e32 v7, 0x32a5705f, v6
	v_sub_f32_e32 v2, v2, v8
	v_add_f32_e32 v2, v2, v7
	v_cvt_i32_f32_e32 v8, v8
	v_exp_f32_e32 v7, v2
	v_cmp_ngt_f32_e32 vcc, s18, v6
	v_mul_f32_e32 v3, 0.5, v3
	v_mov_b32_e32 v2, 0
	v_ldexp_f32 v7, v7, v8
	v_cndmask_b32_e32 v7, 0, v7, vcc
	v_cmp_nlt_f32_e32 vcc, s19, v6
	s_nop 1
	v_cndmask_b32_e32 v6, v5, v7, vcc
	v_add_f32_e32 v6, 1.0, v6
	v_div_scale_f32 v7, s[10:11], v6, v6, 2.0
	v_rcp_f32_e32 v8, v7
	v_div_scale_f32 v9, vcc, 2.0, v6, 2.0
	s_mov_b32 s10, -2
	v_fma_f32 v10, -v7, v8, 1.0
	v_fmac_f32_e32 v8, v10, v8
	v_mul_f32_e32 v10, v9, v8
	v_fma_f32 v11, -v7, v10, v9
	v_fmac_f32_e32 v10, v11, v8
	v_fma_f32 v7, -v7, v10, v9
	v_div_fmas_f32 v7, v7, v8, v10
	v_div_fixup_f32 v6, v7, v6, 2.0
	v_sub_f32_e32 v6, 1.0, v6
	v_add_f32_e32 v6, 1.0, v6
	v_mul_f32_e32 v3, v3, v6
	ds_write_b32 v4, v3 offset:768
	s_waitcnt lgkmcnt(0)
	v_lshl_or_b32 v6, s12, 16, v142
	s_mov_b32 s11, s14
	v_mov_b32_e32 v3, v2
; #define LDS_WAIT() asm volatile("s_waitcnt lgkmcnt(0)" ::: "memory")
; __device__ __forceinline__ unsigned f2bf(float f) { unsigned u = __builtin_bit_cast(unsigned, f); return (u + 0x7fffu + ((u >> 16) & 1u)) >> 16; }
; __global__ void __launch_bounds__(NTHREADS, 2) mega_fwd(Args a_unused) {
;     ...
;             if (n == 511) { dst[lane] = 0; continue; }
;     ...
;             LDS_WAIT();
;             float acc0 = 0.f, acc1 = 0.f;
; #pragma unroll 8
;             for (int j = 0; j < 256; j += 2) { acc0 += hbuf[j] * w2[j * 64 + lane]; acc1 += hbuf[j + 1] * w2[(j + 1) * 64 + lane]; }
;             dst[lane] = (bf16)f2bf(acc0 + acc1);
;             LDS_WAIT(); asm volatile("" ::: "memory");
.LBB0_809:
	s_add_i32 s12, s11, 0
	v_add_u32_e32 v7, 0, v6
	s_add_i32 s13, s12, 0x20000
	ds_read2st64_b32 v[24:25], v7 offset1:1
	ds_read2st64_b32 v[26:27], v7 offset0:2 offset1:3
	ds_read2st64_b32 v[28:29], v7 offset0:4 offset1:5
	ds_read2st64_b32 v[30:31], v7 offset0:6 offset1:7
	ds_read2st64_b32 v[32:33], v7 offset0:8 offset1:9
	ds_read2st64_b32 v[34:35], v7 offset0:10 offset1:11
	ds_read2st64_b32 v[36:37], v7 offset0:12 offset1:13
	ds_read2st64_b32 v[38:39], v7 offset0:14 offset1:15
	v_mov_b32_e32 v7, s13
	ds_read_b128 v[8:11], v7
	s_add_i32 s21, s12, 0x20010
	s_add_i32 s35, s12, 0x20020
	s_add_i32 s12, s12, 0x20030
	v_mov_b32_e32 v12, s21
	v_mov_b32_e32 v16, s35
	v_mov_b32_e32 v20, s12
	ds_read_b128 v[12:15], v12
	ds_read_b128 v[16:19], v16
	ds_read_b128 v[20:23], v20
	s_waitcnt lgkmcnt(3)
	v_pk_fma_f32 v[2:3], v[8:9], v[24:25], v[2:3]
	s_add_i32 s10, s10, 16
	v_pk_fma_f32 v[2:3], v[10:11], v[26:27], v[2:3]
	s_add_i32 s11, s11, 64
	s_waitcnt lgkmcnt(2)
	v_pk_fma_f32 v[2:3], v[12:13], v[28:29], v[2:3]
	v_add_u32_e32 v6, 0x1000, v6
	v_pk_fma_f32 v[2:3], v[14:15], v[30:31], v[2:3]
	s_cmpk_gt_u32 s10, 0xfd
	s_waitcnt lgkmcnt(1)
	v_pk_fma_f32 v[2:3], v[16:17], v[32:33], v[2:3]
	s_nop 0
	v_pk_fma_f32 v[2:3], v[18:19], v[34:35], v[2:3]
	s_waitcnt lgkmcnt(0)
	v_pk_fma_f32 v[2:3], v[20:21], v[36:37], v[2:3]
	s_nop 0
	v_pk_fma_f32 v[2:3], v[22:23], v[38:39], v[2:3]
	s_cbranch_scc0 .LBB0_809
	v_pk_add_f32 v[2:3], v[2:3], v[2:3] op_sel:[1,0] op_sel_hi:[0,1]
	v_bfe_u32 v3, v2, 16, 1
	v_add3_u32 v6, v2, v3, s20
	v_lshl_add_u64 v[2:3], s[8:9], 0, v[128:129]
	global_store_short_d16_hi v[2:3], v6, off
	s_waitcnt lgkmcnt(0)
	s_branch .LBB0_805
.LBB0_811:
	v_lshl_add_u64 v[2:3], s[8:9], 0, v[128:129]
	global_store_short v[2:3], v129, off
	s_branch .LBB0_805

; #define LAS __attribute__((address_space(3)))
; __device__ __forceinline__ void nsa_item(LAS unsigned char* lds, const NsaPtrs& P, int b, int g, int qb, int tid) {
;     const int wave = tid >> 6, lane = tid & 63, fr = lane & 15, fq = lane >> 4, hh = fr >> 2;
;     const int t0 = 64 * qb; const size_t bg = (size_t)(b * 2 + g);
;     int tpos[2], tok[2];
; #pragma unroll
;     for (int i = 0; i < 2; ++i) { tok[i] = 8 * wave + 4 * i + (fr & 3); tpos[i] = t0 + tok[i]; }
;     const int wave_tmin = t0 + 8 * wave, wave_tmax = t0 + 8 * wave + 7;
;     LAS float* imp = (LAS float*)(lds + OFF_IMP);
;     LAS v4u* ocl = (LAS v4u*)(lds + OFF_OC);
;     for (int idx = tid; idx < 64 * ISTR; idx += NTHREADS) imp[idx] = 0.f;
; __global__ void __launch_bounds__(NTHREADS, 2) mega_fwd(Args a_unused) {
;     ...
;     PH_BEGIN
;     {
;     ...
;         for (int pi0 = bx; pi0 < 256; pi0 += G) {
;             const int pi = (G == 256) ? ((pi0 & 7) * 32 + (pi0 >> 3)) : pi0;
;     ...
; #pragma nounroll
;             for (int rep = 0; rep < 2 * REP_MLA; ++rep) {
;                 unsigned char* w2 = ws; asm volatile("" : "+s"(w2));
;                 const att::MlaPtrs MP{(const bf16*)(w2 + WS_QMLA), (const bf16*)(w2 + WS_KVMLA), (const bf16*)(w2 + WS_KR), (bf16*)(w2 + WS_U)};
;                 const int bh = pi >> 4, s = pi & 15; att::mla_item(lds, MP, bh >> 3, bh & 7, (rep & 1) ? s : 31 - s, tid);
;             }
;     ...
; #pragma nounroll
;             for (int rep = 0; rep < 2 * REP_NSA; ++rep) {
;                 unsigned char* w2 = ws; asm volatile("" : "+s"(w2));
;                 const att::NsaPtrs NP{(const bf16*)(w2 + WS_QN), (const bf16*)(w2 + WS_KV6), (const bf16*)(w2 + WS_KCMP), (const bf16*)(w2 + WS_VCMP), (const float*)(w2 + WS_GATES), (bf16*)(w2 + WS_U)};
;                 const int bg = pi >> 6, s = pi & 63; att::nsa_item(lds, NP, bg >> 1, bg & 1, (rep & 1) ? s : 127 - s, tid);
.LBB0_864:
	s_or_b64 exec, exec, s[6:7]
	s_mov_b64 s[6:7], s[0:1]
	s_waitcnt lgkmcnt(0)
	s_barrier
	s_and_b64 vcc, exec, s[4:5]
	v_mov_b64_e32 v[0:1], s[6:7]
	global_load_dwordx2 v[0:1], v[0:1], off offset:200
	s_waitcnt vmcnt(0) lgkmcnt(0)
	v_readfirstlane_b32 s17, v1
	v_readfirstlane_b32 s16, v0
	s_cbranch_vccnz .LBB0_1222
	v_lshlrev_b32_e32 v5, 4, v144
	s_add_i32 s3, 0, 0x1a800
	v_add_u32_e32 v173, s3, v5
	s_add_i32 s3, 0, 0x1c800
	v_add_u32_e32 v174, s3, v5
	s_add_i32 s3, 0, 0x1e800
	v_bfe_u32 v1, v144, 4, 2
	v_and_b32_e32 v170, 0x78, v160
	v_add_u32_e32 v175, s3, v5
	s_add_i32 s3, 0, 0x20800
	v_lshlrev_b32_e32 v0, 3, v1
	v_lshlrev_b32_e32 v2, 2, v1
	v_lshrrev_b32_e32 v1, 2, v144
	v_and_or_b32 v171, v144, 3, v170
	v_bfe_u32 v3, v144, 2, 2
	v_add_u32_e32 v176, s3, v5
	s_movk_i32 s3, 0x210
	v_mov_b32_e32 v147, 0
	v_or_b32_e32 v172, 4, v171
	v_mul_u32_u24_e32 v4, 3, v3
	v_and_b32_e32 v6, 12, v1
	v_mad_u32_u24 v1, v171, s3, 0
	v_and_b32_e32 v169, 0x1e0, v140
	s_mov_b32 s19, 0
	v_lshlrev_b32_e32 v177, 4, v171
	v_lshlrev_b32_e32 v180, 4, v172
	v_lshlrev_b32_e32 v181, 6, v3
	v_add_u32_e32 v179, 0x12400, v179
	v_add_u32_e32 v182, 0x12400, v1
	s_movk_i32 s74, 0x600
	v_lshlrev_b32_e32 v148, 1, v0
	v_mov_b32_e32 v149, v147
	s_mov_b64 s[34:35], 0x20000
	s_movk_i32 s75, 0x1000
	s_movk_i32 s76, 0xa0
	s_mov_b32 s77, 0xefa18f08
	s_mov_b32 s78, 0xf149f2ca
	s_movk_i32 s79, 0x50
	s_mov_b64 s[36:37], 0x3000
	s_mov_b32 s80, 0x41000000
	s_mov_b64 s[38:39], 0x2000
	s_mov_b64 s[40:41], 0x40000
	s_mov_b64 s[42:43], 0x3a00000
	v_lshlrev_b32_e32 v150, 1, v2
	s_movk_i32 s81, 0x7fff
	s_mov_b32 s82, 0xffff0000
	s_movk_i32 s83, 0x1eff
	s_mov_b64 s[44:45], 0x4000
	s_movk_i32 s84, 0x60
	v_lshlrev_b32_e32 v152, 2, v4
	v_lshlrev_b32_e32 v154, 1, v6
	v_mov_b32_e32 v183, 0xf149f2ca
	v_mov_b32_e32 v184, 0xa00
	v_mbcnt_hi_u32_b32 v185, -1, v145
	v_mov_b32_e32 v186, 0x80
	v_mov_b32_e32 v187, 0x100
	v_mov_b32_e32 v188, 0x200
	v_mov_b32_e32 v189, 0x400
	v_mov_b32_e32 v190, 0x800
	v_mov_b32_e32 v191, 0x1000
	v_mov_b32_e32 v192, 0x2000
	v_mov_b32_e32 v193, 0x4000
	v_mov_b32_e32 v194, 0xffff8000
	s_mov_b32 s85, s2
	s_branch .LBB0_867

; __device__ __forceinline__ unsigned pk2(float lo, float hi) { return f2bf(lo) | (f2bf(hi) << 16); }
; template <int DQK> __device__ __forceinline__ void causal_pass_pipe(LAS unsigned char* lds, const bf16* K0, int p0, const bf16* K1, int p1, const bf16* V, int pv, int thi,
;         const bf16x8 (&qf)[2][DQK / 32], const int (&tpos)[2], int wave_tmin, int wave_tmax, f32x4 (&o)[2][4], int tid) {
;     ...
; #pragma unroll
;     for (int i = 0; i < 2; ++i) {
;         const float lt = rows_sum(l[i]);
;         const float iv = lt > 0.f ? 1.0f / lt : 0.f;
; #pragma unroll
;         for (int dt = 0; dt < 4; ++dt) o[i][dt] = o[i][dt] * iv;
;     }
; __device__ __forceinline__ void mla_item(LAS unsigned char* lds, const MlaPtrs& P, int b, int h, int qb, int tid) {
;     ...
; #pragma unroll
;     for (int i = 0; i < 2; ++i) {
;         bf16* orow = P.OCAT + ((size_t)b * T + tpos[i]) * 1024 + 512 + h * 64 + 4 * fq;
; #pragma unroll
;         for (int dt = 0; dt < 4; ++dt) { const f32x4 r = o[i][dt];
;             *(unsigned long long*)(orow + 16 * dt) = (unsigned long long)pk2(r[0], r[1]) | ((unsigned long long)pk2(r[2], r[3]) << 32); }
;     }
.LBB0_868:
	v_mov_b32_e32 v0, v165
	s_nop 1
	v_permlane16_swap_b32_e32 v165, v0
	v_add_f32_e32 v1, v165, v0
	v_mov_b32_e32 v0, v164
	s_nop 1
	v_permlane16_swap_b32_e32 v164, v0
	v_add_f32_e32 v0, v164, v0
	v_mov_b32_e32 v3, v1
	v_mov_b32_e32 v2, v0
	s_nop 0
	v_permlane32_swap_b32_e32 v1, v3
	v_permlane32_swap_b32_e32 v0, v2
	v_pk_add_f32 v[0:1], v[0:1], v[2:3]
	v_lshlrev_b32_e32 v146, 11, v158
	v_div_scale_f32 v2, s[6:7], v1, v1, 1.0
	v_rcp_f32_e32 v3, v2
	v_mov_b32_e32 v151, v147
	s_mov_b64 s[10:11], 0
	v_fma_f32 v4, -v2, v3, 1.0
	v_fmac_f32_e32 v3, v4, v3
	v_div_scale_f32 v4, vcc, 1.0, v1, 1.0
	v_mul_f32_e32 v5, v4, v3
	v_fma_f32 v6, -v2, v5, v4
	v_fmac_f32_e32 v5, v6, v3
	v_fma_f32 v2, -v2, v5, v4
	v_div_fmas_f32 v2, v2, v3, v5
	v_div_fixup_f32 v2, v2, v1, 1.0
	v_cmp_lt_f32_e32 vcc, 0, v1
	v_div_scale_f32 v1, s[6:7], v0, v0, 1.0
	s_nop 0
	v_cndmask_b32_e32 v2, 0, v2, vcc
	v_pk_mul_f32 v[6:7], v[96:97], v[2:3] op_sel_hi:[1,0]
	v_pk_mul_f32 v[4:5], v[98:99], v[2:3] op_sel_hi:[1,0]
	s_waitcnt vmcnt(0) lgkmcnt(0)
	v_bfe_u32 v34, v6, 16, 1
	v_add3_u32 v6, v6, v34, s81
	v_bfe_u32 v34, v7, 16, 1
	v_lshrrev_b32_e32 v6, 16, v6
	v_add3_u32 v7, v7, v34, s81
	s_add_u32 s6, s56, s50
	v_and_or_b32 v6, v7, s82, v6
	v_bfe_u32 v7, v4, 16, 1
	s_addc_u32 s7, s57, s51
	v_add3_u32 v4, v4, v7, s81
	v_bfe_u32 v7, v5, 16, 1
	v_pk_mul_f32 v[10:11], v[88:89], v[2:3] op_sel_hi:[1,0]
	s_add_u32 s6, s6, 0x3a00000
	v_lshrrev_b32_e32 v4, 16, v4
	v_add3_u32 v5, v5, v7, s81
	s_addc_u32 s7, s7, 0
	v_and_or_b32 v7, v5, s82, v4
	v_bfe_u32 v4, v10, 16, 1
	v_lshl_add_u64 v[32:33], s[6:7], 0, v[146:147]
	v_add3_u32 v4, v10, v4, s81
	v_bfe_u32 v5, v11, 16, 1
	v_pk_mul_f32 v[8:9], v[90:91], v[2:3] op_sel_hi:[1,0]
	v_lshl_add_u64 v[32:33], v[32:33], 0, s[18:19]
	v_lshrrev_b32_e32 v4, 16, v4
	v_add3_u32 v5, v11, v5, s81
	v_lshl_add_u64 v[32:33], v[32:33], 0, v[150:151]
	v_and_or_b32 v4, v5, s82, v4
	v_bfe_u32 v5, v8, 16, 1
	global_store_dwordx2 v[32:33], v[6:7], off offset:1024
	v_add3_u32 v5, v8, v5, s81
	v_bfe_u32 v6, v9, 16, 1
	v_lshrrev_b32_e32 v5, 16, v5
	v_add3_u32 v6, v9, v6, s81
	v_rcp_f32_e32 v18, v1
	v_pk_mul_f32 v[14:15], v[92:93], v[2:3] op_sel_hi:[1,0]
	v_and_or_b32 v5, v6, s82, v5
	global_store_dwordx2 v[32:33], v[4:5], off offset:1056
	v_bfe_u32 v4, v14, 16, 1
	v_add3_u32 v4, v14, v4, s81
	v_bfe_u32 v5, v15, 16, 1
	v_pk_mul_f32 v[12:13], v[94:95], v[2:3] op_sel_hi:[1,0]
	v_lshrrev_b32_e32 v4, 16, v4
	v_add3_u32 v5, v15, v5, s81
	v_fma_f32 v19, -v1, v18, 1.0
	v_and_or_b32 v4, v5, s82, v4
	v_bfe_u32 v5, v12, 16, 1
	v_fmac_f32_e32 v18, v19, v18
	v_div_scale_f32 v19, vcc, 1.0, v0, 1.0
	v_add3_u32 v5, v12, v5, s81
	v_bfe_u32 v6, v13, 16, 1
	v_mul_f32_e32 v20, v19, v18
	v_lshrrev_b32_e32 v5, 16, v5
	v_add3_u32 v6, v13, v6, s81
	v_pk_mul_f32 v[16:17], v[50:51], v[2:3] op_sel_hi:[1,0]
	v_pk_mul_f32 v[2:3], v[48:49], v[2:3] op_sel_hi:[1,0]
	v_fma_f32 v21, -v1, v20, v19
	v_and_or_b32 v5, v6, s82, v5
	v_fmac_f32_e32 v20, v21, v18
	global_store_dwordx2 v[32:33], v[4:5], off offset:1088
	v_bfe_u32 v4, v2, 16, 1
	v_fma_f32 v1, -v1, v20, v19
	v_add3_u32 v2, v2, v4, s81
	v_bfe_u32 v4, v3, 16, 1
	v_div_fmas_f32 v1, v1, v18, v20
	v_lshrrev_b32_e32 v2, 16, v2
	v_add3_u32 v3, v3, v4, s81
	v_div_fixup_f32 v1, v1, v0, 1.0
	v_cmp_lt_f32_e32 vcc, 0, v0
	v_and_or_b32 v2, v3, s82, v2
	v_bfe_u32 v3, v16, 16, 1
	v_cndmask_b32_e32 v0, 0, v1, vcc
	v_add3_u32 v3, v16, v3, s81
	v_bfe_u32 v4, v17, 16, 1
	v_pk_mul_f32 v[20:21], v[84:85], v[0:1] op_sel_hi:[1,0]
	v_lshrrev_b32_e32 v3, 16, v3
	v_add3_u32 v4, v17, v4, s81
	v_and_or_b32 v3, v4, s82, v3
	v_bfe_u32 v4, v20, 16, 1
	v_add3_u32 v4, v20, v4, s81
	v_bfe_u32 v5, v21, 16, 1
	v_pk_mul_f32 v[18:19], v[86:87], v[0:1] op_sel_hi:[1,0]
	v_lshrrev_b32_e32 v4, 16, v4
	v_add3_u32 v5, v21, v5, s81
	v_lshlrev_b32_e32 v146, 11, v156
	v_and_or_b32 v4, v5, s82, v4
	v_bfe_u32 v5, v18, 16, 1
	global_store_dwordx2 v[32:33], v[2:3], off offset:1120
	v_lshl_add_u64 v[2:3], s[6:7], 0, v[146:147]
	v_add3_u32 v5, v18, v5, s81
	v_bfe_u32 v6, v19, 16, 1
	v_lshl_add_u64 v[2:3], v[2:3], 0, s[18:19]
	v_lshrrev_b32_e32 v5, 16, v5
	v_add3_u32 v6, v19, v6, s81
	v_pk_mul_f32 v[24:25], v[76:77], v[0:1] op_sel_hi:[1,0]
	v_lshl_add_u64 v[2:3], v[2:3], 0, v[150:151]
	v_and_or_b32 v5, v6, s82, v5
	global_store_dwordx2 v[2:3], v[4:5], off offset:1024
	v_bfe_u32 v4, v24, 16, 1
	v_add3_u32 v4, v24, v4, s81
	v_bfe_u32 v5, v25, 16, 1
	v_pk_mul_f32 v[22:23], v[78:79], v[0:1] op_sel_hi:[1,0]
	v_lshrrev_b32_e32 v4, 16, v4
	v_add3_u32 v5, v25, v5, s81
	v_and_or_b32 v4, v5, s82, v4
	v_bfe_u32 v5, v22, 16, 1
	v_add3_u32 v5, v22, v5, s81
	v_bfe_u32 v6, v23, 16, 1
	v_lshrrev_b32_e32 v5, 16, v5
	v_add3_u32 v6, v23, v6, s81
	v_pk_mul_f32 v[28:29], v[80:81], v[0:1] op_sel_hi:[1,0]
	v_and_or_b32 v5, v6, s82, v5
	global_store_dwordx2 v[2:3], v[4:5], off offset:1056
	v_bfe_u32 v4, v28, 16, 1
	v_add3_u32 v4, v28, v4, s81
	v_bfe_u32 v5, v29, 16, 1
	v_pk_mul_f32 v[26:27], v[82:83], v[0:1] op_sel_hi:[1,0]
	v_lshrrev_b32_e32 v4, 16, v4
	v_add3_u32 v5, v29, v5, s81
	v_and_or_b32 v4, v5, s82, v4
	v_bfe_u32 v5, v26, 16, 1
	v_add3_u32 v5, v26, v5, s81
	v_bfe_u32 v6, v27, 16, 1
	v_lshrrev_b32_e32 v5, 16, v5
	v_add3_u32 v6, v27, v6, s81
	v_pk_mul_f32 v[30:31], v[58:59], v[0:1] op_sel_hi:[1,0]
	v_pk_mul_f32 v[0:1], v[56:57], v[0:1] op_sel_hi:[1,0]
	v_and_or_b32 v5, v6, s82, v5
	global_store_dwordx2 v[2:3], v[4:5], off offset:1088
	v_bfe_u32 v4, v0, 16, 1
	v_add3_u32 v0, v0, v4, s81
	v_bfe_u32 v4, v1, 16, 1
	v_lshrrev_b32_e32 v0, 16, v0
	v_add3_u32 v1, v1, v4, s81
	v_and_or_b32 v0, v1, s82, v0
	v_bfe_u32 v1, v30, 16, 1
	v_add3_u32 v1, v30, v1, s81
	v_bfe_u32 v4, v31, 16, 1
	v_lshrrev_b32_e32 v1, 16, v1
	v_add3_u32 v4, v31, v4, s81
	v_and_or_b32 v1, v4, s82, v1
	s_and_b64 vcc, exec, s[58:59]
	global_store_dwordx2 v[2:3], v[0:1], off offset:1120
	s_cbranch_vccnz .LBB0_981
; #define LAS __attribute__((address_space(3)))
; template <int DQK> __device__ __forceinline__ void stage_load(Stage<DQK>& s, const bf16* K0, int p0, const bf16* K1, int p1, const bf16* V, int pv, int tile, bool withV, int tid) {
;     { const int key = tid >> 3, c = tid & 7; s.k0 = *(const v4u*)(K0 + (size_t)(64 * tile + key) * p0 + 8 * c); }
;     if (DQK == 96) { if (tid < 256) { const int key = tid >> 2, c = tid & 3; s.k1 = *(const v4u*)(K1 + (size_t)(64 * tile + key) * p1 + 8 * c); } }
;     if (withV) { const int key = tid >> 3, c = tid & 7; s.v = *(const v4u*)(V + (size_t)(64 * tile + key) * pv + 8 * c); }
; }
; __device__ __forceinline__ void mla_item(LAS unsigned char* lds, const MlaPtrs& P, int b, int h, int qb, int tid) {
;     const int wave = tid >> 6, lane = tid & 63, fr = lane & 15, fq = lane >> 4;
;     const int t0 = 256 * qb;
;     int tpos[2], tok[2]; bf16x8 qf[2][3];
; #pragma unroll
;     for (int i = 0; i < 2; ++i) {
;         tok[i] = 0; tpos[i] = t0 + 32 * wave + 16 * i + fr;
;         const bf16* qrow = P.QMLA + ((size_t)b * T + tpos[i]) * 768;
;         qf[i][0] = *(const bf16x8*)(qrow + h * 64 + 8 * fq); qf[i][1] = *(const bf16x8*)(qrow + h * 64 + 32 + 8 * fq); qf[i][2] = *(const bf16x8*)(qrow + 512 + h * 32 + 8 * fq);
;     }
;     const int wave_tmin = t0 + 32 * wave, wave_tmax = t0 + 32 * wave + 31;
;     f32x4 o[2][4]; float mf[2], li[2];
;     const bf16* kv = P.KVMLA + (size_t)b * T * 1024;
;     causal_pass_pipe<96>(lds, kv + h * 64, 1024, P.KR + (size_t)b * T * 32, 32, kv + 512 + h * 64, 1024, 4 * qb + 3, qf, tpos, wave_tmin, wave_tmax, o, tid);
.LBB0_869:
	s_mov_b64 s[56:57], s[16:17]
	s_add_u32 s6, s56, 0x5a00000
	s_addc_u32 s7, s57, 0
	s_and_b64 s[8:9], s[10:11], exec
	s_cselect_b32 s20, s88, s87
	v_lshl_add_u32 v151, s20, 8, v169
	v_or_b32_e32 v158, v151, v168
	v_mov_b32_e32 v159, v147
	v_or_b32_e32 v156, 16, v158
	v_mov_b32_e32 v157, v147
	v_lshl_add_u64 v[0:1], s[46:47], 0, v[158:159]
	v_mov_b64_e32 v[8:9], s[6:7]
	v_lshl_add_u64 v[12:13], s[46:47], 0, v[156:157]
	v_mad_u64_u32 v[10:11], s[6:7], v0, s74, v[8:9]
	v_mad_u64_u32 v[16:17], s[6:7], v12, s74, v[8:9]
	s_add_u32 s6, s56, s50
	s_addc_u32 s7, s57, s51
	s_add_u32 s6, s6, s18
	s_addc_u32 s7, s7, 0
	s_add_u32 s14, s6, 0x7200000
	s_addc_u32 s15, s7, 0
	v_mad_i32_i24 v11, v1, s74, v11
	v_mad_i32_i24 v17, v13, s74, v17
	s_add_u32 s8, s56, s52
	v_lshl_add_u64 v[0:1], v[10:11], 0, s[18:19]
	v_lshl_add_u64 v[10:11], v[10:11], 0, s[54:55]
	v_lshl_add_u64 v[8:9], v[16:17], 0, s[18:19]
	v_lshl_add_u64 v[16:17], v[16:17], 0, s[54:55]
	s_addc_u32 s9, s57, s53
	v_lshl_add_u64 v[4:5], v[0:1], 0, v[148:149]
	v_lshl_add_u64 v[10:11], v[10:11], 0, v[148:149]
	v_lshl_add_u64 v[18:19], v[8:9], 0, v[148:149]
	v_lshl_add_u64 v[20:21], v[16:17], 0, v[148:149]
	s_add_u32 s12, s8, 0x3800000
	v_mov_b32_e32 v50, v144
	global_load_dwordx4 v[0:3], v[4:5], off
	s_nop 0
	global_load_dwordx4 v[4:7], v[4:5], off offset:64
	s_nop 0
	global_load_dwordx4 v[8:11], v[10:11], off offset:1024
	s_nop 0
	global_load_dwordx4 v[12:15], v[18:19], off
	s_nop 0
	global_load_dwordx4 v[16:19], v[18:19], off offset:64
	s_nop 0
	global_load_dwordx4 v[20:23], v[20:21], off offset:1024
	s_addc_u32 s13, s9, 0
	s_add_u32 s8, s6, 0x7200400
	v_ashrrev_i32_e32 v48, 3, v50
	v_ashrrev_i32_e32 v49, 31, v48
	v_lshlrev_b32_e32 v28, 3, v50
	s_addc_u32 s9, s7, 0
	v_lshlrev_b64 v[36:37], 11, v[48:49]
	v_and_b32_e32 v24, 56, v28
	v_lshlrev_b32_e32 v146, 1, v24
	v_lshl_add_u64 v[160:161], s[14:15], 0, v[36:37]
	v_lshl_add_u64 v[24:25], v[160:161], 0, v[146:147]
	global_load_dwordx4 v[24:27], v[24:25], off
	s_movk_i32 s6, 0x100
	v_ashrrev_i32_e32 v76, 2, v50
	v_and_b32_e32 v28, 24, v28
	v_cmp_gt_i32_e64 s[6:7], s6, v50
	v_ashrrev_i32_e32 v77, 31, v76
	v_lshlrev_b32_e32 v42, 1, v28
	s_and_saveexec_b64 s[58:59], s[6:7]
	s_cbranch_execz .LBB0_871
	v_lshlrev_b64 v[28:29], 6, v[76:77]
	v_lshl_add_u64 v[28:29], s[12:13], 0, v[28:29]
	v_mov_b32_e32 v43, v147
	v_lshl_add_u64 v[28:29], v[28:29], 0, v[42:43]
	global_load_dwordx4 v[28:31], v[28:29], off
.LBB0_871:
	s_or_b64 exec, exec, s[58:59]
	v_lshl_add_u64 v[44:45], v[36:37], 0, s[34:35]
	v_lshl_add_u64 v[162:163], s[8:9], 0, v[36:37]
	v_lshl_add_u64 v[36:37], s[14:15], 0, v[44:45]
	v_lshl_add_u64 v[32:33], v[162:163], 0, v[146:147]
	v_lshl_add_u64 v[36:37], v[36:37], 0, v[146:147]
	global_load_dwordx4 v[32:35], v[32:33], off
	s_nop 0
	global_load_dwordx4 v[36:39], v[36:37], off
	s_and_saveexec_b64 s[14:15], s[6:7]
	s_cbranch_execz .LBB0_873
	v_lshlrev_b64 v[40:41], 6, v[76:77]
	v_lshl_add_u64 v[40:41], s[12:13], 0, v[40:41]
	v_mov_b32_e32 v43, v147
	v_lshl_add_u64 v[40:41], v[40:41], 0, v[42:43]
	v_add_co_u32_e32 v40, vcc, 0x1000, v40
	s_nop 1
	v_addc_co_u32_e32 v41, vcc, 0, v41, vcc
	global_load_dwordx4 v[40:43], v[40:41], off
; #define LAS __attribute__((address_space(3)))
; template <int DQK> __device__ __forceinline__ void x1_tile(LAS unsigned char* lds, const bf16x8 (&qf)[2][DQK / 32], const float (&m)[2], f32x4 (&s)[2][4], int fr, int fq) {
;     constexpr int NKS = DQK / 32;
; #pragma unroll
;     for (int q = 0; q < 2; ++q) { const float c = (m[q] > -1e29f) ? -m[q] : 0.f;
; #pragma unroll
;         for (int ss = 0; ss < 4; ++ss) s[q][ss] = (f32x4){c, c, c, c}; }
; #pragma unroll
;     for (int ss = 0; ss < 4; ++ss)
; #pragma unroll
;         for (int ks = 0; ks < NKS; ++ks) {
;             const bf16x8 kf = *(const LAS bf16x8*)(lds + k_off<DQK>(16 * ss + fr, 4 * ks + fq));
; #pragma unroll
;             for (int q = 0; q < 2; ++q) s[q][ss] = __builtin_amdgcn_mfma_f32_16x16x32_bf16(kf, qf[q][ks], s[q][ss], 0, 0, 0);
;         }
; }
; template <bool FULL> __device__ __forceinline__ void x2_tile(int kbase, const int (&tpos)[2], float (&m)[2], float (&l)[2], f32x4 (&o)[2][4], f32x4 (&s)[2][4], int fq) {
; #pragma unroll
;     for (int q = 0; q < 2; ++q) {
;         f32x4 (&sq)[4] = s[q];
;         const float mo = m[q]; const float meff = (mo > -1e29f) ? mo : 0.f;
;         bool slow = true;
;         if (FULL) {
;             int ia = __builtin_bit_cast(int, sq[0][0]);
;     ...
;             ia = IMX3(ia, sq[0][1], sq[0][2]); ia = IMX3(ia, sq[0][3], sq[1][0]); ia = IMX3(ia, sq[1][1], sq[1][2]); ia = IMX3(ia, sq[1][3], sq[2][0]);
;             int ib = __builtin_bit_cast(int, sq[2][1]);
; template <int DQK> __device__ __forceinline__ void causal_pass_pipe(LAS unsigned char* lds, const bf16* K0, int p0, const bf16* K1, int p1, const bf16* V, int pv, int thi,
;         const bf16x8 (&qf)[2][DQK / 32], const int (&tpos)[2], int wave_tmin, int wave_tmax, f32x4 (&o)[2][4], int tid) {
;     ...
;     Stage<DQK> st;
;     {
;         Stage<DQK> st1;
;         stage_load<DQK>(st, K0, p0, K1, p1, V, pv, 0, true, tid);
;         if (thi >= 1) stage_load<DQK>(st1, K0, p0, K1, p1, V, pv, 1, true, tid);
;         stage_store<DQK>(st, lds, true, tid);
;         if (thi >= 1) stage_store<DQK>(st1, lds + SLOT, true, tid);
;     }
;     ATT_BAR();
;     f32x4 sa[2][4], sb[2][4]; bool ca = true, cb = false;
;     x1_tile<DQK>(lds, qf, m, sa, fr, fq);
;     if (63 <= wave_tmin) x2_tile<true>(0, tpos, m, l, o, sa, fq); else x2_tile<false>(0, tpos, m, l, o, sa, fq);
.LBB0_873:
	s_or_b64 exec, exec, s[14:15]
	v_lshl_add_u64 v[44:45], s[8:9], 0, v[44:45]
	v_lshl_add_u64 v[44:45], v[44:45], 0, v[146:147]
	global_load_dwordx4 v[44:47], v[44:45], off
	v_lshrrev_b32_e32 v51, 3, v50
	v_and_b32_e32 v49, 7, v50
	v_bitop3_b32 v51, v51, v49, 15 bitop3:0x6c
	v_lshlrev_b32_e32 v155, 4, v51
	v_lshlrev_b32_e32 v153, 8, v48
	v_add_u32_e32 v51, 0, v155
	v_add_u32_e32 v51, v51, v153
	v_and_b32_e32 v78, 3, v50
	v_lshlrev_b32_e32 v157, 8, v76
	v_and_b32_e32 v79, 15, v76
	s_waitcnt vmcnt(0) lgkmcnt(0)
	ds_write_b128 v51, v[24:27]
	s_and_saveexec_b64 s[8:9], s[6:7]
	v_bitop3_b32 v52, v78, v79, 8 bitop3:0x36
	v_lshlrev_b32_e32 v52, 4, v52
	v_add3_u32 v52, 0, v52, v157
	ds_write_b128 v52, v[28:31]
	s_or_b64 exec, exec, s[8:9]
	v_lshlrev_b32_e32 v146, 4, v49
	v_mul_lo_u32 v159, v48, s76
	v_add_u32_e32 v48, 0, v146
	v_add_u32_e32 v48, v48, v159
	ds_write_b128 v48, v[32:35] offset:16384
	ds_write_b128 v51, v[36:39] offset:26624
	s_and_saveexec_b64 s[8:9], s[6:7]
	v_bitop3_b32 v36, v78, v79, 8 bitop3:0x36
	v_lshlrev_b32_e32 v36, 4, v36
	v_add3_u32 v36, 0, v36, v157
	ds_write_b128 v36, v[40:43] offset:26624
	s_or_b64 exec, exec, s[8:9]
	v_lshrrev_b32_e32 v36, 4, v50
	v_and_b32_e32 v80, 15, v50
	v_lshlrev_b32_e32 v195, 8, v80
	v_bitop3_b32 v36, v36, v80, 3 bitop3:0x6c
	ds_write_b128 v48, v[44:47] offset:43008
	v_add_u32_e32 v56, 0, v195
	v_lshlrev_b32_e32 v196, 4, v36
	s_waitcnt lgkmcnt(0)
	s_barrier
	v_add_u32_e32 v64, v56, v196
	ds_read_b128 v[36:39], v64
	ds_read_b128 v[44:47], v64 offset:4096
	v_bfe_u32 v81, v50, 4, 2
	v_bitop3_b32 v48, v81, v80, 4 bitop3:0x36
	v_lshlrev_b32_e32 v197, 4, v48
	v_add_u32_e32 v68, v56, v197
	s_waitcnt lgkmcnt(1)
	v_mfma_f32_16x16x32_bf16 v[40:43], v[36:39], v[0:3], 0
	ds_read_b128 v[48:51], v68
	ds_read_b128 v[52:55], v68 offset:4096
	v_cmp_gt_u32_e32 vcc, 63, v151
	v_lshlrev_b32_e32 v199, 2, v81
	v_mfma_f32_16x16x32_bf16 v[36:39], v[36:39], v[12:15], 0
	s_waitcnt lgkmcnt(1)
	v_mfma_f32_16x16x32_bf16 v[40:43], v[48:51], v[4:7], v[40:43]
	v_mfma_f32_16x16x32_bf16 v[48:51], v[48:51], v[16:19], v[36:39]
	s_nop 4
	v_bitop3_b32 v36, v81, v80, 8 bitop3:0x36
	v_lshlrev_b32_e32 v198, 4, v36
	v_add_u32_e32 v72, v56, v198
	ds_read_b128 v[56:59], v72
	ds_read_b128 v[60:63], v72 offset:4096
	s_waitcnt lgkmcnt(1)
	v_mfma_f32_16x16x32_bf16 v[36:39], v[56:59], v[8:11], v[40:43]
	v_mfma_f32_16x16x32_bf16 v[40:43], v[56:59], v[20:23], v[48:51]
	v_mfma_f32_16x16x32_bf16 v[48:51], v[44:47], v[0:3], 0
	v_mfma_f32_16x16x32_bf16 v[44:47], v[44:47], v[12:15], 0
	v_mfma_f32_16x16x32_bf16 v[48:51], v[52:55], v[4:7], v[48:51]
	v_mfma_f32_16x16x32_bf16 v[52:55], v[52:55], v[16:19], v[44:47]
	s_waitcnt lgkmcnt(0)
	v_mfma_f32_16x16x32_bf16 v[44:47], v[60:63], v[8:11], v[48:51]
	s_nop 4
	ds_read_b128 v[48:51], v64 offset:8192
	ds_read_b128 v[56:59], v64 offset:12288
	ds_read_b128 v[64:67], v68 offset:8192
	ds_read_b128 v[68:71], v68 offset:12288
	v_mfma_f32_16x16x32_bf16 v[52:55], v[60:63], v[20:23], v[52:55]
	s_waitcnt lgkmcnt(3)
	v_mfma_f32_16x16x32_bf16 v[60:63], v[48:51], v[0:3], 0
	v_mfma_f32_16x16x32_bf16 v[48:51], v[48:51], v[12:15], 0
	s_waitcnt lgkmcnt(1)
	v_mfma_f32_16x16x32_bf16 v[60:63], v[64:67], v[4:7], v[60:63]
	v_mfma_f32_16x16x32_bf16 v[48:51], v[64:67], v[16:19], v[48:51]
	ds_read_b128 v[64:67], v72 offset:8192
	ds_read_b128 v[72:75], v72 offset:12288
	s_waitcnt lgkmcnt(1)
	v_mfma_f32_16x16x32_bf16 v[60:63], v[64:67], v[8:11], v[60:63]
	v_mfma_f32_16x16x32_bf16 v[64:67], v[64:67], v[20:23], v[48:51]
	v_mfma_f32_16x16x32_bf16 v[48:51], v[56:59], v[0:3], 0
	v_mfma_f32_16x16x32_bf16 v[56:59], v[56:59], v[12:15], 0
	v_mfma_f32_16x16x32_bf16 v[48:51], v[68:71], v[4:7], v[48:51]
	v_mfma_f32_16x16x32_bf16 v[82:85], v[68:71], v[16:19], v[56:59]
	s_waitcnt lgkmcnt(0)
	v_mfma_f32_16x16x32_bf16 v[68:71], v[72:75], v[8:11], v[48:51]
	v_mfma_f32_16x16x32_bf16 v[72:75], v[72:75], v[20:23], v[82:85]
	s_and_saveexec_b64 s[8:9], vcc
	s_xor_b64 s[14:15], exec, s[8:9]
	s_cbranch_execz .LBB0_883
	v_cmp_lt_u32_e32 vcc, v199, v158
	v_or_b32_e32 v49, 2, v199
	v_or_b32_e32 v56, 17, v199
	v_cndmask_b32_e32 v37, v183, v37, vcc
	v_cmp_le_u32_e32 vcc, v49, v158
	v_or_b32_e32 v49, 3, v199
	v_or_b32_e32 v57, 18, v199
	v_cndmask_b32_e32 v38, v183, v38, vcc
	v_cmp_le_u32_e32 vcc, v49, v158
	v_or_b32_e32 v49, 16, v199
	v_or_b32_e32 v58, 19, v199
	v_cndmask_b32_e32 v39, v183, v39, vcc
	v_cmp_le_u32_e32 vcc, v49, v158
	v_or_b32_e32 v59, 32, v199
	v_cmp_gt_u32_e64 s[8:9], v199, v158
	v_cndmask_b32_e32 v44, v183, v44, vcc
	v_cmp_le_u32_e32 vcc, v56, v158
	v_or_b32_e32 v81, 33, v199
	v_cndmask_b32_e64 v36, v36, v183, s[8:9]
	v_cndmask_b32_e32 v45, v183, v45, vcc
	v_cmp_le_u32_e32 vcc, v57, v158
	v_or_b32_e32 v82, 34, v199
	v_max3_f32 v48, v36, s78, v37
	v_cndmask_b32_e32 v46, v183, v46, vcc
	v_cmp_le_u32_e32 vcc, v58, v158
	v_or_b32_e32 v83, 35, v199
	v_max3_f32 v48, v48, v38, v39
	v_cndmask_b32_e32 v47, v183, v47, vcc
	v_cmp_le_u32_e32 vcc, v59, v158
	v_or_b32_e32 v84, 48, v199
	v_max3_f32 v48, v48, v44, v45
	v_cndmask_b32_e32 v60, v183, v60, vcc
	v_cmp_le_u32_e32 vcc, v81, v158
	v_or_b32_e32 v85, 49, v199
	v_max3_f32 v48, v48, v46, v47
	v_cndmask_b32_e32 v61, v183, v61, vcc
	v_cmp_le_u32_e32 vcc, v82, v158
	v_or_b32_e32 v86, 50, v199
	v_max3_f32 v48, v48, v60, v61
	v_cndmask_b32_e32 v62, v183, v62, vcc
	v_cmp_le_u32_e32 vcc, v83, v158
	v_or_b32_e32 v87, 51, v199
	s_nop 0
	v_cndmask_b32_e32 v63, v183, v63, vcc
	v_cmp_le_u32_e32 vcc, v84, v158
	v_max3_f32 v48, v48, v62, v63
	s_nop 0
	v_cndmask_b32_e32 v68, v183, v68, vcc
	v_cmp_le_u32_e32 vcc, v85, v158
	s_nop 1
	v_cndmask_b32_e32 v69, v183, v69, vcc
	v_cmp_le_u32_e32 vcc, v86, v158
	v_max3_f32 v48, v48, v68, v69
	s_nop 0
	v_cndmask_b32_e32 v70, v183, v70, vcc
	v_cmp_le_u32_e32 vcc, v87, v158
	s_nop 1
	v_cndmask_b32_e32 v71, v183, v71, vcc
	v_max3_f32 v48, v48, v70, v71
	v_mov_b32_e32 v49, v48
	s_nop 1
	v_permlane16_swap_b32_e32 v48, v49
	v_max_f32_e32 v49, v49, v49
	v_max_f32_e32 v48, v48, v48
	v_max_f32_e32 v48, v48, v49
	v_mov_b32_e32 v49, v48
	s_nop 1
	v_permlane32_swap_b32_e32 v48, v49
	v_max_f32_e32 v49, v49, v49
	v_max_f32_e32 v48, v48, v48
	v_max_f32_e32 v48, v48, v49
	v_cmp_lt_f32_e32 vcc, s77, v48
	s_cbranch_vccz .LBB0_880
	v_add_f32_e32 v49, 0, v48
	v_cndmask_b32_e32 v200, v183, v49, vcc
	v_sub_f32_e32 v49, 0xf149f2ca, v200
	v_exp_f32_e32 v49, v49
	v_cndmask_b32_e32 v88, 0, v48, vcc
	v_sub_f32_e32 v36, v36, v88
	v_sub_f32_e32 v37, v37, v88
	v_mul_f32_e32 v48, 0, v49
	v_cndmask_b32_e32 v48, 0, v48, vcc
	v_mov_b32_e32 v49, v48
	v_mov_b32_e32 v50, v48
	v_mov_b32_e32 v51, v48
	v_sub_f32_e32 v38, v38, v88
	v_sub_f32_e32 v39, v39, v88
	v_sub_f32_e32 v44, v44, v88
	v_sub_f32_e32 v45, v45, v88
	v_sub_f32_e32 v46, v46, v88
	v_sub_f32_e32 v47, v47, v88
	v_sub_f32_e32 v60, v60, v88
	v_sub_f32_e32 v61, v61, v88
	v_sub_f32_e32 v62, v62, v88
	v_sub_f32_e32 v63, v63, v88
	v_sub_f32_e32 v68, v68, v88
	v_sub_f32_e32 v69, v69, v88
	v_sub_f32_e32 v70, v70, v88
	v_sub_f32_e32 v71, v71, v88
	v_mov_b32_e32 v165, v48
	s_branch .LBB0_881

; template <int DQK> __device__ __forceinline__ void stage_load(Stage<DQK>& s, const bf16* K0, int p0, const bf16* K1, int p1, const bf16* V, int pv, int tile, bool withV, int tid) {
;     { const int key = tid >> 3, c = tid & 7; s.k0 = *(const v4u*)(K0 + (size_t)(64 * tile + key) * p0 + 8 * c); }
;     if (DQK == 96) { if (tid < 256) { const int key = tid >> 2, c = tid & 3; s.k1 = *(const v4u*)(K1 + (size_t)(64 * tile + key) * p1 + 8 * c); } }
;     if (withV) { const int key = tid >> 3, c = tid & 7; s.v = *(const v4u*)(V + (size_t)(64 * tile + key) * pv + 8 * c); }
; }
.LBB0_894:
	s_add_i32 s92, s96, 2
	s_cmp_gt_u32 s92, s89
	s_cselect_b64 s[62:63], -1, 0
	s_cmp_le_u32 s92, s89
	s_cselect_b64 s[64:65], -1, 0
	s_and_b64 vcc, exec, s[62:63]
	s_cbranch_vccnz .LBB0_898
	s_waitcnt vmcnt(0) lgkmcnt(0)
	v_lshl_add_u64 v[24:25], v[160:161], 0, v[146:147]
	v_add_co_u32_e32 v24, vcc, 0x40000, v24
	s_nop 1
	v_addc_co_u32_e32 v25, vcc, 0, v25, vcc
	global_load_dwordx4 v[24:27], v[24:25], off
	s_and_saveexec_b64 s[8:9], s[6:7]
	s_cbranch_execz .LBB0_897
	v_add_co_u32_e32 v28, vcc, 0xfffff000, v166
	s_nop 1
	v_addc_co_u32_e32 v29, vcc, -1, v167, vcc
	global_load_dwordx4 v[28:31], v[28:29], off
.LBB0_897:
	s_or_b64 exec, exec, s[8:9]
	v_lshl_add_u64 v[32:33], v[162:163], 0, v[146:147]
	v_add_co_u32_e32 v32, vcc, 0x40000, v32
	s_nop 1
	v_addc_co_u32_e32 v33, vcc, 0, v33, vcc
	global_load_dwordx4 v[32:35], v[32:33], off

; template <int DQK> __device__ __forceinline__ void causal_pass_pipe(LAS unsigned char* lds, const bf16* K0, int p0, const bf16* K1, int p1, const bf16* V, int pv, int thi,
;         const bf16x8 (&qf)[2][DQK / 32], const int (&tpos)[2], int wave_tmin, int wave_tmax, f32x4 (&o)[2][4], int tid) {
;     ...
;     for (int t = 0; t <= thi; t += 2) {
;         PIPE_STEP(sa, sb, ca, cb, t);
;         if (t + 1 <= thi) PIPE_STEP(sb, sa, cb, ca, t + 1);
.LBB0_935:
	s_waitcnt lgkmcnt(0)
	s_barrier
	s_andn2_b64 vcc, exec, s[66:67]
	s_cbranch_vccnz .LBB0_945
	s_cmp_le_u32 s96, s49
	s_cselect_b64 s[14:15], -1, 0
	s_cmp_gt_u32 s96, s49
	s_cbranch_scc1 .LBB0_940
	s_waitcnt vmcnt(0) lgkmcnt(0)
	v_lshl_add_u64 v[24:25], v[160:161], 0, v[146:147]
	v_add_co_u32_e32 v24, vcc, 0x60000, v24
	s_nop 1
	v_addc_co_u32_e32 v25, vcc, 0, v25, vcc
	global_load_dwordx4 v[24:27], v[24:25], off
	s_and_saveexec_b64 s[10:11], s[6:7]
	s_cbranch_execz .LBB0_939
	global_load_dwordx4 v[28:31], v[166:167], off
.LBB0_939:
	s_or_b64 exec, exec, s[10:11]
	v_lshl_add_u64 v[32:33], v[162:163], 0, v[146:147]
	v_add_co_u32_e32 v32, vcc, 0x60000, v32
	s_nop 1
	v_addc_co_u32_e32 v33, vcc, 0, v33, vcc
	global_load_dwordx4 v[32:35], v[32:33], off

; __device__ __forceinline__ unsigned cvtpk(float lo, float hi) { f32x2_t v = {lo, hi}; bf16x2_t b = __builtin_convertvector(v, bf16x2_t); return __builtin_bit_cast(unsigned, b); }
; __device__ __forceinline__ f32x4 unpk_lo(const v4u& w) { return (f32x4){__uint_as_float(w.x << 16), __uint_as_float(w.x & 0xffff0000u), __uint_as_float(w.y << 16), __uint_as_float(w.y & 0xffff0000u)}; }
; __device__ __forceinline__ f32x4 unpk_hi(const v4u& w) { return (f32x4){__uint_as_float(w.z << 16), __uint_as_float(w.z & 0xffff0000u), __uint_as_float(w.w << 16), __uint_as_float(w.w & 0xffff0000u)}; }
; template <int DQK, int MODE> __device__ __forceinline__ void attn_pass(LAS unsigned char* lds, const bf16* K0, int p0, const bf16* K1, int p1, const bf16* V, int pv, int tlo, int thi, ...
;     ...
; #pragma unroll
;     for (int i = 0; i < 2; ++i) {
;         const float lt = rows_sum(l[i]);
;         const float iv = lt > 0.f ? 1.0f / lt : 0.f;
;         mfin[i] = m[i]; linv[i] = iv;
; #pragma unroll
;         for (int dt = 0; dt < 4; ++dt) o[i][dt] = o[i][dt] * iv;
;     }
; __device__ __forceinline__ void nsa_item(LAS unsigned char* lds, const NsaPtrs& P, int b, int g, int qb, int tid) {
;     ...
; #pragma unroll
;     for (int i = 0; i < 2; ++i) {
;         const float gw = P.GATES[((size_t)b * T + tpos[i]) * 24 + g * 12 + hh * 3 + 2];
;         bf16* orow = P.OCAT + ((size_t)b * T + tpos[i]) * 1024 + (g * 4 + hh) * 64 + 4 * fq;
; #pragma unroll
;         for (int dt = 0; dt < 4; ++dt) { const v4u w = ocl[(i * 2 + (dt >> 1)) * NTHREADS + tid]; const f32x4 r = ((dt & 1) ? unpk_hi(w) : unpk_lo(w)) + o[i][dt] * gw;
;             *(unsigned long long*)(orow + 16 * dt) = (unsigned long long)cvtpk(r[0], r[1]) | ((unsigned long long)cvtpk(r[2], r[3]) << 32); }
;     }
.LBB0_982:
	s_add_u32 s6, s56, s18
	s_addc_u32 s7, s57, 0
	v_mov_b32_e32 v153, v147
	v_lshl_add_u64 v[36:37], s[6:7], 0, v[152:153]
	v_lshl_add_u64 v[32:33], v[36:37], 0, v[124:125]
	global_load_dword v38, v[32:33], off offset:8
	v_lshl_add_u64 v[36:37], v[36:37], 0, v[122:123]
	global_load_dword v36, v[36:37], off offset:8
	v_mov_b32_e32 v39, v105
	v_mov_b32_e32 v44, v104
	v_mov_b32_e32 v113, v147
	v_permlane16_swap_b32_e32 v105, v39
	v_permlane16_swap_b32_e32 v104, v44
	v_mov_b32_e32 v155, v147
	v_lshl_add_u64 v[42:43], s[54:55], 0, v[112:113]
	v_add_f32_e32 v45, v105, v39
	v_add_f32_e32 v44, v104, v44
	ds_read_b128 v[32:35], v173
	v_lshl_add_u64 v[42:43], v[42:43], 0, v[154:155]
	v_mov_b32_e32 v47, v45
	v_mov_b32_e32 v46, v44
	v_lshlrev_b64 v[40:41], 11, v[120:121]
	s_waitcnt lgkmcnt(0)
	v_lshlrev_b64 v[34:35], 11, v[118:119]
	v_lshl_add_u64 v[42:43], v[42:43], 0, s[42:43]
	v_permlane32_swap_b32_e32 v45, v47
	v_permlane32_swap_b32_e32 v44, v46
	v_lshl_add_u64 v[40:41], v[42:43], 0, v[40:41]
	v_lshl_add_u64 v[34:35], v[42:43], 0, v[34:35]
	v_pk_add_f32 v[42:43], v[44:45], v[46:47]
	v_lshlrev_b32_e32 v44, 16, v32
	v_div_scale_f32 v37, s[6:7], v43, v43, 1.0
	v_rcp_f32_e32 v46, v37
	v_div_scale_f32 v47, s[6:7], v42, v42, 1.0
	s_waitcnt vmcnt(0)
	v_rcp_f32_e32 v48, v47
	v_fma_f32 v50, -v37, v46, 1.0
	v_div_scale_f32 v39, vcc, 1.0, v43, 1.0
	v_fmac_f32_e32 v46, v50, v46
	v_fma_f32 v51, -v47, v48, 1.0
	v_mul_f32_e32 v50, v39, v46
	v_fmac_f32_e32 v48, v51, v48
	v_fma_f32 v51, -v37, v50, v39
	v_fmac_f32_e32 v50, v51, v46
	v_fma_f32 v37, -v37, v50, v39
	v_div_fmas_f32 v37, v37, v46, v50
	v_div_fixup_f32 v37, v37, v43, 1.0
	v_cmp_lt_f32_e32 vcc, 0, v43
	v_and_b32_e32 v45, 0xffff0000, v32
	v_lshlrev_b32_e32 v32, 16, v33
	v_cndmask_b32_e32 v46, 0, v37, vcc
	v_and_b32_e32 v33, 0xffff0000, v33
	v_pk_mul_f32 v[28:29], v[28:29], v[46:47] op_sel_hi:[1,0]
	v_pk_mul_f32 v[30:31], v[30:31], v[46:47] op_sel_hi:[1,0]
	v_pk_mul_f32 v[24:25], v[24:25], v[46:47] op_sel_hi:[1,0]
	v_pk_mul_f32 v[26:27], v[26:27], v[46:47] op_sel_hi:[1,0]
	v_pk_mul_f32 v[20:21], v[20:21], v[46:47] op_sel_hi:[1,0]
	v_pk_mul_f32 v[22:23], v[22:23], v[46:47] op_sel_hi:[1,0]
	v_div_scale_f32 v49, s[6:7], 1.0, v42, 1.0
	s_mov_b64 vcc, s[6:7]
	v_pk_mul_f32 v[16:17], v[16:17], v[46:47] op_sel_hi:[1,0]
	v_pk_mul_f32 v[18:19], v[18:19], v[46:47] op_sel_hi:[1,0]
	s_mov_b64 s[6:7], 0
	v_pk_fma_f32 v[30:31], v[38:39], v[30:31], v[32:33] op_sel_hi:[0,1,1]
	v_pk_fma_f32 v[28:29], v[38:39], v[28:29], v[44:45] op_sel_hi:[0,1,1]
	v_cvt_pk_bf16_f32 v28, v28, v29
	v_cvt_pk_bf16_f32 v29, v30, v31
	global_store_dwordx2 v[40:41], v[28:29], off
	ds_read_b128 v[28:31], v173
	v_mul_f32_e32 v32, v49, v48
	v_fma_f32 v33, -v47, v32, v49
	v_fmac_f32_e32 v32, v33, v48
	s_waitcnt lgkmcnt(0)
	v_lshlrev_b32_e32 v28, 16, v30
	v_and_b32_e32 v29, 0xffff0000, v30
	v_lshlrev_b32_e32 v30, 16, v31
	v_and_b32_e32 v31, 0xffff0000, v31
	v_pk_fma_f32 v[26:27], v[38:39], v[26:27], v[30:31] op_sel_hi:[0,1,1]
	v_pk_fma_f32 v[24:25], v[38:39], v[24:25], v[28:29] op_sel_hi:[0,1,1]
	v_cvt_pk_bf16_f32 v24, v24, v25
	v_cvt_pk_bf16_f32 v25, v26, v27
	global_store_dwordx2 v[40:41], v[24:25], off offset:32
	ds_read_b128 v[24:27], v173 offset:8192
	v_fma_f32 v28, -v47, v32, v49
	s_waitcnt lgkmcnt(0)
	v_lshlrev_b32_e32 v26, 16, v24
	v_and_b32_e32 v27, 0xffff0000, v24
	v_lshlrev_b32_e32 v24, 16, v25
	v_and_b32_e32 v25, 0xffff0000, v25
	v_pk_fma_f32 v[22:23], v[38:39], v[22:23], v[24:25] op_sel_hi:[0,1,1]
	v_pk_fma_f32 v[20:21], v[38:39], v[20:21], v[26:27] op_sel_hi:[0,1,1]
	v_cvt_pk_bf16_f32 v20, v20, v21
	v_cvt_pk_bf16_f32 v21, v22, v23
	global_store_dwordx2 v[40:41], v[20:21], off offset:64
	ds_read_b128 v[20:23], v173 offset:8192
	s_waitcnt lgkmcnt(0)
	v_div_fmas_f32 v20, v28, v48, v32
	v_div_fixup_f32 v24, v20, v42, 1.0
	v_cmp_lt_f32_e32 vcc, 0, v42
	v_lshlrev_b32_e32 v20, 16, v22
	v_and_b32_e32 v21, 0xffff0000, v22
	v_lshlrev_b32_e32 v22, 16, v23
	v_and_b32_e32 v23, 0xffff0000, v23
	v_pk_fma_f32 v[18:19], v[38:39], v[18:19], v[22:23] op_sel_hi:[0,1,1]
	v_pk_fma_f32 v[16:17], v[38:39], v[16:17], v[20:21] op_sel_hi:[0,1,1]
	v_cvt_pk_bf16_f32 v16, v16, v17
	v_cvt_pk_bf16_f32 v17, v18, v19
	global_store_dwordx2 v[40:41], v[16:17], off offset:96
	ds_read_b128 v[16:19], v173 offset:16384
	s_waitcnt lgkmcnt(0)
	v_cndmask_b32_e32 v18, 0, v24, vcc
	s_and_b64 vcc, exec, s[52:53]
	v_pk_mul_f32 v[12:13], v[12:13], v[18:19] op_sel_hi:[1,0]
	v_pk_mul_f32 v[14:15], v[14:15], v[18:19] op_sel_hi:[1,0]
	v_lshlrev_b32_e32 v20, 16, v16
	v_and_b32_e32 v21, 0xffff0000, v16
	v_lshlrev_b32_e32 v16, 16, v17
	v_and_b32_e32 v17, 0xffff0000, v17
	v_pk_fma_f32 v[14:15], v[14:15], v[36:37], v[16:17] op_sel_hi:[1,0,1]
	v_pk_fma_f32 v[12:13], v[12:13], v[36:37], v[20:21] op_sel_hi:[1,0,1]
	v_pk_mul_f32 v[8:9], v[8:9], v[18:19] op_sel_hi:[1,0]
	v_cvt_pk_bf16_f32 v12, v12, v13
	v_cvt_pk_bf16_f32 v13, v14, v15
	global_store_dwordx2 v[34:35], v[12:13], off
	ds_read_b128 v[12:15], v173 offset:16384
	v_pk_mul_f32 v[10:11], v[10:11], v[18:19] op_sel_hi:[1,0]
	v_pk_mul_f32 v[4:5], v[4:5], v[18:19] op_sel_hi:[1,0]
	v_pk_mul_f32 v[6:7], v[6:7], v[18:19] op_sel_hi:[1,0]
	v_pk_mul_f32 v[0:1], v[0:1], v[18:19] op_sel_hi:[1,0]
	s_waitcnt lgkmcnt(0)
	v_lshlrev_b32_e32 v12, 16, v14
	v_and_b32_e32 v13, 0xffff0000, v14
	v_lshlrev_b32_e32 v14, 16, v15
	v_and_b32_e32 v15, 0xffff0000, v15
	v_pk_fma_f32 v[10:11], v[10:11], v[36:37], v[14:15] op_sel_hi:[1,0,1]
	v_pk_fma_f32 v[8:9], v[8:9], v[36:37], v[12:13] op_sel_hi:[1,0,1]
	v_pk_mul_f32 v[2:3], v[2:3], v[18:19] op_sel_hi:[1,0]
	v_cvt_pk_bf16_f32 v8, v8, v9
	v_cvt_pk_bf16_f32 v9, v10, v11
	global_store_dwordx2 v[34:35], v[8:9], off offset:32
	ds_read_b128 v[8:11], v173 offset:24576
	s_waitcnt lgkmcnt(0)
	v_lshlrev_b32_e32 v10, 16, v8
	v_and_b32_e32 v11, 0xffff0000, v8
	v_lshlrev_b32_e32 v8, 16, v9
	v_and_b32_e32 v9, 0xffff0000, v9
	v_pk_fma_f32 v[6:7], v[6:7], v[36:37], v[8:9] op_sel_hi:[1,0,1]
	v_pk_fma_f32 v[4:5], v[4:5], v[36:37], v[10:11] op_sel_hi:[1,0,1]
	s_nop 0
	v_cvt_pk_bf16_f32 v4, v4, v5
	v_cvt_pk_bf16_f32 v5, v6, v7
	global_store_dwordx2 v[34:35], v[4:5], off offset:64
	ds_read_b128 v[4:7], v173 offset:24576
	s_waitcnt lgkmcnt(0)
	v_lshlrev_b32_e32 v4, 16, v6
	v_and_b32_e32 v5, 0xffff0000, v6
	v_lshlrev_b32_e32 v6, 16, v7
	v_and_b32_e32 v7, 0xffff0000, v7
	v_pk_fma_f32 v[2:3], v[2:3], v[36:37], v[6:7] op_sel_hi:[1,0,1]
	v_pk_fma_f32 v[0:1], v[0:1], v[36:37], v[4:5] op_sel_hi:[1,0,1]
	s_nop 0
	v_cvt_pk_bf16_f32 v0, v0, v1
	v_cvt_pk_bf16_f32 v1, v2, v3
	global_store_dwordx2 v[34:35], v[0:1], off offset:96
	s_cbranch_vccnz .LBB0_866

; #define LAS __attribute__((address_space(3)))
; template <int DQK, int MODE> __device__ __forceinline__ void attn_pass(LAS unsigned char* lds, const bf16* K0, int p0, const bf16* K1, int p1, const bf16* V, int pv, int tlo, int thi, ...
;     ...
;     Stage<DQK> st;
;     {
;         Stage<DQK> st1;
;         stage_load<DQK>(st, K0, p0, K1, p1, V, pv, tlo, true, tid);
;         if (tlo < thi) stage_load<DQK>(st1, K0, p0, K1, p1, V, pv, tlo + 1, true, tid);
;         stage_store<DQK>(st, lds, true, tid);
;         if (tlo < thi) stage_store<DQK>(st1, lds + KL<DQK>::SLOT, true, tid);
;     }
; __device__ __forceinline__ void nsa_load_q(const bf16* QN, int b, int g, int tid, int t0, bf16x8 (&qf)[2][2]) {
;     asm volatile("" : "+v"(tid)); asm volatile("" : "+s"(QN));
;     const int wave = tid >> 6, fr = tid & 15, fq = (tid & 63) >> 4, hh = fr >> 2;
; #pragma unroll
;     for (int i = 0; i < 2; ++i) {
;         const size_t mrow = (size_t)b * T + t0 + 8 * wave + 4 * i + (fr & 3);
;         const bf16* qrow = QN + mrow * 512 + (g * 4 + hh) * 64;
; #pragma unroll
;         for (int ks = 0; ks < 2; ++ks) qf[i][ks] = *(const bf16x8*)(qrow + 32 * ks + 8 * fq);
;     }
; }
; __device__ __forceinline__ void nsa_item(LAS unsigned char* lds, const NsaPtrs& P, int b, int g, int qb, int tid) {
;     const int wave = tid >> 6, lane = tid & 63, fr = lane & 15, fq = lane >> 4, hh = fr >> 2;
;     const int t0 = 64 * qb; const size_t bg = (size_t)(b * 2 + g);
;     int tpos[2], tok[2];
; #pragma unroll
;     for (int i = 0; i < 2; ++i) { tok[i] = 8 * wave + 4 * i + (fr & 3); tpos[i] = t0 + tok[i]; }
;     const int wave_tmin = t0 + 8 * wave, wave_tmax = t0 + 8 * wave + 7;
;     LAS float* imp = (LAS float*)(lds + OFF_IMP);
;     LAS v4u* ocl = (LAS v4u*)(lds + OFF_OC);
;     for (int idx = tid; idx < 64 * ISTR; idx += NTHREADS) imp[idx] = 0.f;
;     bf16x8 qf[2][2]; f32x4 o[2][4]; float mf[2], li[2];
;     const bf16* Kc = P.KCMP + bg * 512 * 64; const bf16* Vc = P.VCMP + bg * 512 * 64;
;     const int thi_c = ((t0 + 63 - 31) >> 4) >> 6;
;     nsa_load_q(P.QN, b, g, tid, t0, qf);
;     attn_pass<64, CMP>(lds, Kc, 64, nullptr, 0, Vc, 64, 0, thi_c, qf, tpos, tok, wave_tmin, wave_tmax, o, mf, li, tid, fr, fq);
.LBB0_984:
	v_add_u32_e32 v1, 0x200, v1
	v_cmp_lt_u32_e32 vcc, s83, v1
	ds_write_b32 v0, v147
	s_or_b64 s[8:9], vcc, s[8:9]
	v_add_u32_e32 v0, 0x800, v0
	s_andn2_b64 exec, exec, s[8:9]
	s_cbranch_execnz .LBB0_984
	s_or_b64 exec, exec, s[8:9]
	s_and_b64 s[6:7], s[6:7], exec
	s_cselect_b32 s72, s69, s68
	s_lshl_b32 s73, s72, 6
	s_add_u32 s58, s54, 0x9a00000
	s_addc_u32 s59, s55, 0
	s_add_u32 s6, s54, s48
	s_addc_u32 s7, s55, s49
	s_add_u32 s14, s6, 0x2d00000
	s_addc_u32 s15, s7, 0
	v_mov_b32_e32 v4, v144
	s_add_u32 s6, s6, 0x2d80000
	s_addc_u32 s7, s7, 0
	v_ashrrev_i32_e32 v0, 3, v4
	s_or_b32 s86, s46, s73
	v_and_b32_e32 v0, -8, v0
	v_ashrrev_i32_e32 v1, 31, v0
	v_and_or_b32 v2, v4, 3, s86
	v_mov_b32_e32 v3, s47
	v_lshl_add_u64 v[0:1], v[2:3], 0, v[0:1]
	v_lshlrev_b32_e32 v2, 4, v4
	v_and_b32_e32 v2, 0xc0, v2
	v_or_b32_e32 v2, s70, v2
	s_mov_b64 s[8:9], s[58:59]
	v_lshlrev_b32_e32 v146, 1, v2
	v_lshlrev_b64 v[0:1], 10, v[0:1]
	v_lshl_add_u64 v[2:3], s[8:9], 0, v[146:147]
	v_and_b32_e32 v146, 48, v4
	v_lshl_add_u64 v[2:3], v[2:3], 0, v[146:147]
	v_lshl_add_u64 v[8:9], v[2:3], 0, v[0:1]
	v_add_co_u32_e32 v12, vcc, s75, v8
	v_mov_b32_e32 v28, v144
	s_nop 0
	v_addc_co_u32_e32 v13, vcc, 0, v9, vcc
	global_load_dwordx4 v[0:3], v[8:9], off
	global_load_dwordx4 v[4:7], v[8:9], off offset:64
	s_nop 0
	global_load_dwordx4 v[8:11], v[12:13], off
	s_nop 0
	global_load_dwordx4 v[12:15], v[12:13], off offset:64
	s_mov_b64 s[8:9], s[14:15]
	v_ashrrev_i32_e32 v26, 3, v28
	v_ashrrev_i32_e32 v27, 31, v26
	v_lshlrev_b32_e32 v18, 3, v28
	v_lshlrev_b64 v[24:25], 7, v[26:27]
	v_and_b32_e32 v18, 56, v18
	v_lshlrev_b32_e32 v146, 1, v18
	v_lshl_add_u64 v[16:17], s[8:9], 0, v[24:25]
	v_lshl_add_u64 v[16:17], v[16:17], 0, v[146:147]
	global_load_dwordx4 v[48:51], v[16:17], off
	v_lshl_add_u64 v[16:17], s[6:7], 0, v[24:25]
	v_lshl_add_u64 v[16:17], v[16:17], 0, v[146:147]
	global_load_dwordx4 v[52:55], v[16:17], off
	s_cmp_gt_u32 s72, 15
	s_cselect_b64 s[10:11], -1, 0
	s_cmp_lt_u32 s72, 16
	v_readfirstlane_b32 s18, v28
	s_cbranch_scc1 .LBB0_987
	v_lshl_add_u64 v[16:17], v[24:25], 0, s[38:39]
	v_lshl_add_u64 v[18:19], s[6:7], 0, v[16:17]
	v_lshl_add_u64 v[16:17], s[8:9], 0, v[16:17]
	v_lshl_add_u64 v[18:19], v[18:19], 0, v[146:147]
	v_lshl_add_u64 v[16:17], v[16:17], 0, v[146:147]
	global_load_dwordx4 v[20:23], v[16:17], off
	s_nop 0
	global_load_dwordx4 v[16:19], v[18:19], off

; #define LAS __attribute__((address_space(3)))
; template <int DQK> __device__ __forceinline__ void stage_load(Stage<DQK>& s, const bf16* K0, int p0, const bf16* K1, int p1, const bf16* V, int pv, int tile, bool withV, int tid) {
;     { const int key = tid >> 3, c = tid & 7; s.k0 = *(const v4u*)(K0 + (size_t)(64 * tile + key) * p0 + 8 * c); }
;     if (DQK == 96) { if (tid < 256) { const int key = tid >> 2, c = tid & 3; s.k1 = *(const v4u*)(K1 + (size_t)(64 * tile + key) * p1 + 8 * c); } }
;     if (withV) { const int key = tid >> 3, c = tid & 7; s.v = *(const v4u*)(V + (size_t)(64 * tile + key) * pv + 8 * c); }
; }
; template <int DQK, int MODE> __device__ __forceinline__ void attn_pass(LAS unsigned char* lds, const bf16* K0, int p0, const bf16* K1, int p1, const bf16* V, int pv, int tlo, int thi, ...
;     ...
;     for (int t = tlo; t <= thi; ++t) {
;         LAS unsigned char* buf = lds + slot * KL<DQK>::SLOT;
;         const int slot2 = (slot == 0) ? 2 : slot - 1;
;         if (t + 2 <= thi) stage_load<DQK>(st, K0, p0, K1, p1, V, pv, t + 2, true, tid);
.LBB0_993:
	s_cmp_le_u32 s20, s64
	s_cselect_b64 s[56:57], -1, 0
	s_cmp_gt_u32 s20, s64
	s_cbranch_scc1 .LBB0_995
	s_waitcnt vmcnt(0) lgkmcnt(0)
	global_load_dwordx4 v[48:51], v[106:107], off
	global_load_dwordx4 v[52:55], v[108:109], off

; __device__ __forceinline__ v4u pack8(const f32x4& a, const f32x4& b) { return (v4u){cvtpk(a[0], a[1]), cvtpk(a[2], a[3]), cvtpk(b[0], b[1]), cvtpk(b[2], b[3])}; }
; template <int DQK, int MODE> __device__ __forceinline__ void attn_pass(LAS unsigned char* lds, const bf16* K0, int p0, const bf16* K1, int p1, const bf16* V, int pv, int tlo, int thi, ...
;     ...
; #pragma unroll
;     for (int i = 0; i < 2; ++i) {
;         const float lt = rows_sum(l[i]);
;         const float iv = lt > 0.f ? 1.0f / lt : 0.f;
;         mfin[i] = m[i]; linv[i] = iv;
; #pragma unroll
;         for (int dt = 0; dt < 4; ++dt) o[i][dt] = o[i][dt] * iv;
;     }
; __device__ __forceinline__ void nsa_item(LAS unsigned char* lds, const NsaPtrs& P, int b, int g, int qb, int tid) {
;     ...
; #pragma unroll
;     for (int i = 0; i < 2; ++i) { const float gc = P.GATES[((size_t)b * T + tpos[i]) * 24 + g * 12 + hh * 3 + 0];
;         ocl[(i * 2 + 0) * NTHREADS + tid] = pack8(o[i][0] * gc, o[i][1] * gc); ocl[(i * 2 + 1) * NTHREADS + tid] = pack8(o[i][2] * gc, o[i][3] * gc); }
;     ...
;     int tid_i = tid; asm volatile("" : "+v"(tid_i)); const int fr_i = tid_i & 15, fq_i = (tid_i & 63) >> 4; asm volatile("" : "+s"(Kc));
;     v4u kpre = *(const v4u*)(Kc + (size_t)(tid_i >> 3) * 64 + 8 * (tid_i & 7));
.LBB0_1018:
	s_add_u32 s56, s54, 0x3600000
	s_addc_u32 s57, s55, 0
	v_mov_b32_e32 v115, v147
	v_lshl_add_u64 v[120:121], s[46:47], 0, v[114:115]
	s_waitcnt vmcnt(0) lgkmcnt(0)
	v_mov_b64_e32 v[48:49], s[56:57]
	v_mad_u64_u32 v[50:51], s[6:7], v120, s84, v[48:49]
	v_mad_i32_i24 v51, v121, s84, v51
	s_lshl_b32 s18, s71, 2
	v_lshl_add_u64 v[50:51], v[50:51], 0, s[18:19]
	v_mov_b32_e32 v153, v147
	v_lshl_add_u64 v[128:129], v[50:51], 0, v[152:153]
	global_load_dword v50, v[128:129], off
	v_mov_b32_e32 v51, v104
	v_mov_b32_e32 v52, v105
	s_nop 0
	v_permlane16_swap_b32_e32 v104, v51
	v_permlane16_swap_b32_e32 v105, v52
	v_add_f32_e32 v53, v104, v51
	v_add_f32_e32 v52, v105, v52
	v_mov_b32_e32 v55, v53
	v_mov_b32_e32 v54, v52
	s_nop 0
	v_permlane32_swap_b32_e32 v53, v55
	v_permlane32_swap_b32_e32 v52, v54
	v_pk_add_f32 v[52:53], v[52:53], v[54:55]
	v_mov_b32_e32 v117, v147
	v_div_scale_f32 v51, s[6:7], v53, v53, 1.0
	v_lshl_add_u64 v[118:119], s[46:47], 0, v[116:117]
	v_rcp_f32_e32 v54, v51
	v_mad_u64_u32 v[48:49], s[6:7], v118, s84, v[48:49]
	v_mad_i32_i24 v49, v119, s84, v49
	v_lshl_add_u64 v[48:49], v[48:49], 0, s[18:19]
	v_lshl_add_u64 v[126:127], v[48:49], 0, v[152:153]
	v_fma_f32 v48, -v51, v54, 1.0
	v_div_scale_f32 v55, vcc, 1.0, v53, 1.0
	v_fmac_f32_e32 v54, v48, v54
	v_mul_f32_e32 v48, v55, v54
	v_fma_f32 v49, -v51, v48, v55
	v_fmac_f32_e32 v48, v49, v54
	v_fma_f32 v49, -v51, v48, v55
	v_div_fmas_f32 v48, v49, v54, v48
	v_div_fixup_f32 v48, v48, v53, 1.0
	v_cmp_lt_f32_e32 vcc, 0, v53
	v_mad_u64_u32 v[124:125], s[6:7], v120, s84, 0
	s_nop 0
	v_cndmask_b32_e32 v64, 0, v48, vcc
	v_pk_mul_f32 v[44:45], v[44:45], v[64:65] op_sel_hi:[1,0]
	v_pk_mul_f32 v[46:47], v[46:47], v[64:65] op_sel_hi:[1,0]
	v_pk_mul_f32 v[40:41], v[40:41], v[64:65] op_sel_hi:[1,0]
	v_pk_mul_f32 v[42:43], v[42:43], v[64:65] op_sel_hi:[1,0]
	v_pk_mul_f32 v[36:37], v[36:37], v[64:65] op_sel_hi:[1,0]
	v_pk_mul_f32 v[38:39], v[38:39], v[64:65] op_sel_hi:[1,0]
	v_pk_mul_f32 v[32:33], v[32:33], v[64:65] op_sel_hi:[1,0]
	v_pk_mul_f32 v[34:35], v[34:35], v[64:65] op_sel_hi:[1,0]
	v_mad_u64_u32 v[122:123], s[6:7], v118, s84, 0
	v_mad_i32_i24 v125, v121, s84, v125
	v_mad_i32_i24 v123, v119, s84, v123
	s_mov_b32 s10, 0
	s_mov_b32 s11, 0
	s_waitcnt vmcnt(0) lgkmcnt(0)
	v_pk_mul_f32 v[46:47], v[50:51], v[46:47] op_sel_hi:[0,1]
	v_pk_mul_f32 v[44:45], v[50:51], v[44:45] op_sel_hi:[0,1]
	v_pk_mul_f32 v[42:43], v[50:51], v[42:43] op_sel_hi:[0,1]
	v_pk_mul_f32 v[40:41], v[50:51], v[40:41] op_sel_hi:[0,1]
	v_pk_mul_f32 v[38:39], v[50:51], v[38:39] op_sel_hi:[0,1]
	v_pk_mul_f32 v[36:37], v[50:51], v[36:37] op_sel_hi:[0,1]
	v_pk_mul_f32 v[48:49], v[50:51], v[34:35] op_sel_hi:[0,1]
	v_pk_mul_f32 v[50:51], v[50:51], v[32:33] op_sel_hi:[0,1]
	v_cvt_pk_bf16_f32 v32, v44, v45
	v_cvt_pk_bf16_f32 v33, v46, v47
	v_cvt_pk_bf16_f32 v34, v40, v41
	v_cvt_pk_bf16_f32 v35, v42, v43
	v_cvt_pk_bf16_f32 v36, v36, v37
	v_cvt_pk_bf16_f32 v37, v38, v39
	v_cvt_pk_bf16_f32 v38, v50, v51
	v_cvt_pk_bf16_f32 v39, v48, v49
	ds_write_b128 v173, v[32:35]
	ds_write_b128 v174, v[36:39]
	global_load_dword v32, v[126:127], off
	v_div_scale_f32 v33, s[6:7], v52, v52, 1.0
	v_rcp_f32_e32 v34, v33
	v_div_scale_f32 v35, vcc, 1.0, v52, 1.0
	v_mov_b32_e32 v36, v144
	v_fma_f32 v37, -v33, v34, 1.0
	v_fmac_f32_e32 v34, v37, v34
	v_mul_f32_e32 v37, v35, v34
	v_fma_f32 v38, -v33, v37, v35
	v_fmac_f32_e32 v37, v38, v34
	v_fma_f32 v33, -v33, v37, v35
	v_div_fmas_f32 v33, v33, v34, v37
	v_div_fixup_f32 v33, v33, v52, 1.0
	v_cmp_lt_f32_e32 vcc, 0, v52
	s_nop 1
	v_cndmask_b32_e32 v66, 0, v33, vcc
	v_pk_mul_f32 v[28:29], v[28:29], v[66:67] op_sel_hi:[1,0]
	v_pk_mul_f32 v[30:31], v[30:31], v[66:67] op_sel_hi:[1,0]
	v_pk_mul_f32 v[24:25], v[24:25], v[66:67] op_sel_hi:[1,0]
	v_pk_mul_f32 v[26:27], v[26:27], v[66:67] op_sel_hi:[1,0]
	v_pk_mul_f32 v[20:21], v[20:21], v[66:67] op_sel_hi:[1,0]
	v_pk_mul_f32 v[22:23], v[22:23], v[66:67] op_sel_hi:[1,0]
	v_pk_mul_f32 v[16:17], v[16:17], v[66:67] op_sel_hi:[1,0]
	v_pk_mul_f32 v[18:19], v[18:19], v[66:67] op_sel_hi:[1,0]
	s_waitcnt vmcnt(0) lgkmcnt(0)
	v_pk_mul_f32 v[30:31], v[32:33], v[30:31] op_sel_hi:[0,1]
	v_pk_mul_f32 v[28:29], v[32:33], v[28:29] op_sel_hi:[0,1]
	v_pk_mul_f32 v[26:27], v[32:33], v[26:27] op_sel_hi:[0,1]
	v_pk_mul_f32 v[24:25], v[32:33], v[24:25] op_sel_hi:[0,1]
	v_pk_mul_f32 v[20:21], v[32:33], v[20:21] op_sel_hi:[0,1]
	v_pk_mul_f32 v[22:23], v[32:33], v[22:23] op_sel_hi:[0,1]
	v_pk_mul_f32 v[34:35], v[32:33], v[18:19] op_sel_hi:[0,1]
	v_pk_mul_f32 v[32:33], v[32:33], v[16:17] op_sel_hi:[0,1]
	v_cvt_pk_bf16_f32 v16, v28, v29
	v_cvt_pk_bf16_f32 v17, v30, v31
	v_cvt_pk_bf16_f32 v18, v24, v25
	v_cvt_pk_bf16_f32 v19, v26, v27
	v_cvt_pk_bf16_f32 v20, v20, v21
	v_cvt_pk_bf16_f32 v21, v22, v23
	v_cvt_pk_bf16_f32 v22, v32, v33
	v_cvt_pk_bf16_f32 v23, v34, v35
	ds_write_b128 v175, v[16:19]
	ds_write_b128 v176, v[20:23]
	s_nop 0
	v_ashrrev_i32_e32 v20, 3, v36
	v_ashrrev_i32_e32 v21, 31, v20
	v_lshlrev_b32_e32 v18, 4, v36
	v_lshlrev_b64 v[22:23], 7, v[20:21]
	v_lshl_add_u64 v[16:17], s[14:15], 0, v[22:23]
	v_and_b32_e32 v146, 0x70, v18
	v_lshl_add_u64 v[16:17], v[16:17], 0, v[146:147]
	global_load_dwordx4 v[16:19], v[16:17], off
	v_lshlrev_b32_e32 v26, 7, v20
	v_lshrrev_b32_e32 v20, 1, v20
	v_xor_b32_e32 v20, v20, v36
	v_lshlrev_b32_e32 v20, 4, v20
	v_and_b32_e32 v20, 0x70, v20
	v_lshrrev_b32_e32 v24, 4, v36
	v_bfe_u32 v25, v36, 4, 2
	v_add_u32_e32 v27, 0, v20
	v_bfe_u32 v20, v36, 1, 3
	v_bitop3_b32 v24, v24, v20, 3 bitop3:0x6c
	v_bitop3_b32 v20, v25, v20, 4 bitop3:0x36
	v_lshlrev_b32_e32 v29, 4, v20
	v_and_b32_e32 v20, 7, v36
	v_and_b32_e32 v21, 15, v36
	v_lshl_or_b32 v22, v20, 4, v22
	v_lshl_add_u32 v28, v21, 7, 0
	v_lshlrev_b32_e32 v24, 4, v24
	v_cmp_gt_u32_e32 vcc, 4, v21
	v_lshl_add_u64 v[20:21], s[14:15], 0, v[22:23]
	v_lshlrev_b32_e32 v65, 6, v25
	v_lshl_add_u64 v[68:69], v[20:21], 0, s[38:39]
	v_lshl_add_u32 v67, v25, 2, v182
	v_add_u32_e32 v70, v27, v26
	v_add_u32_e32 v71, v28, v24
	v_add_u32_e32 v72, v28, v29
	s_branch .LBB0_1020

; #define LAS __attribute__((address_space(3)))
; template <int DQK> __device__ __forceinline__ void qk_tile(LAS unsigned char* lds, const bf16x8 (&qf)[DQK / 32], f32x4 (&s)[4], int fr, int fq) {
;     constexpr int NKS = DQK / 32;
; #pragma unroll
;     for (int ss = 0; ss < 4; ++ss) {
;         s[ss] = (f32x4){0.f, 0.f, 0.f, 0.f};
; #pragma unroll
;         for (int ks = 0; ks < NKS; ++ks) {
;             const bf16x8 kf = *(const LAS bf16x8*)(lds + k_off<DQK>(16 * ss + fr, 4 * ks + fq));
;             s[ss] = __builtin_amdgcn_mfma_f32_16x16x32_bf16(kf, qf[ks], s[ss], 0, 0, 0);
;         }
;     }
; }
; __device__ __forceinline__ void nsa_item(LAS unsigned char* lds, const NsaPtrs& P, int b, int g, int qb, int tid) {
;     ...
;     for (int t = 0; t <= thi_c; ++t) {
;         __syncthreads();
;         { const int key = tid_i >> 3, c = tid_i & 7; *(LAS v4u*)(lds + k_off<64>(key, c)) = kpre; }
;         __syncthreads();
;         if (t < thi_c) kpre = *(const v4u*)(Kc + (size_t)(64 * (t + 1) + (tid_i >> 3)) * 64 + 8 * (tid_i & 7));
;         if (16 * (64 * t) + 31 > wave_tmax) continue;
; #pragma unroll
;         for (int i = 0; i < 2; ++i) {
;             f32x4 s[4];
;             qk_tile<64>(lds, qf[i], s, fr_i, fq_i);
; #pragma unroll
;             for (int ss = 0; ss < 4; ++ss) {
;                 float a = 0.f, b3 = 0.f;
; #pragma unroll
;                 for (int e = 0; e < 4; ++e) { const int n = 64 * t + 16 * ss + 4 * fq_i + e; const float p = (16 * n + 31 <= tpos[i]) ? __builtin_amdgcn_exp2f(s[ss][e] - mf[i]) * li[i] : 0.f; a += p; if (e == 3) b3 = p; }
;                 a += __shfl_xor(a, 4); a += __shfl_xor(a, 8); b3 += __shfl_xor(b3, 4); b3 += __shfl_xor(b3, 8);
;                 if (fr_i < 4) { const int jp = 16 * t + 4 * ss + fq_i;
;                     __hip_atomic_fetch_add(imp + tok[i] * ISTR + jp, a, __ATOMIC_RELAXED, __HIP_MEMORY_SCOPE_WORKGROUP);
;                     __hip_atomic_fetch_add(imp + tok[i] * ISTR + jp + 1, b3, __ATOMIC_RELAXED, __HIP_MEMORY_SCOPE_WORKGROUP); }
.LBB0_1020:
	s_cmp_ge_u32 s11, s64
	s_waitcnt lgkmcnt(0)
	s_barrier
	s_waitcnt vmcnt(0)
	ds_write_b128 v70, v[16:19]
	s_waitcnt lgkmcnt(0)
	s_barrier
	s_cbranch_scc1 .LBB0_1022
	global_load_dwordx4 v[16:19], v[68:69], off
.LBB0_1022:
	s_add_i32 s6, s10, 31
	v_cmp_le_u32_e64 s[6:7], s6, v136
	s_and_saveexec_b64 s[8:9], s[6:7]
	s_cbranch_execz .LBB0_1019
	ds_read_b128 v[44:47], v71
	ds_read_b128 v[40:43], v71 offset:2048
	ds_read_b128 v[48:51], v72
	ds_read_b128 v[32:35], v72 offset:2048
	v_and_b32_e32 v57, 64, v185
	s_waitcnt lgkmcnt(0)
	v_mfma_f32_16x16x32_bf16 v[20:23], v[44:47], v[0:3], 0
	v_xor_b32_e32 v56, 4, v185
	v_add_u32_e32 v74, 64, v57
	v_add_u32_e32 v79, s10, v65
	v_cmp_lt_i32_e64 s[6:7], v56, v74
	v_mfma_f32_16x16x32_bf16 v[52:55], v[48:51], v[4:7], v[20:23]
	v_add_u32_e32 v75, 31, v79
	v_add_u32_e32 v76, 47, v79
	s_nop 0
	v_cndmask_b32_e64 v20, v185, v56, s[6:7]
	v_cmp_le_u32_e64 s[6:7], v75, v114
	s_nop 2
	v_sub_f32_e32 v52, v52, v111
	v_exp_f32_e32 v52, v52
	v_sub_f32_e32 v53, v53, v111
	v_exp_f32_e32 v53, v53
	v_sub_f32_e32 v54, v54, v111
	v_exp_f32_e32 v54, v54
	v_fma_f32 v52, v64, v52, 0
	v_mfma_f32_16x16x32_bf16 v[24:27], v[40:43], v[0:3], 0
	v_cndmask_b32_e64 v52, 0, v52, s[6:7]
	v_mul_f32_e32 v53, v64, v53
	v_cmp_le_u32_e64 s[6:7], v76, v114
	ds_read_b128 v[36:39], v71 offset:4096
	ds_read_b128 v[28:31], v72 offset:4096
	v_cndmask_b32_e64 v53, 0, v53, s[6:7]
	v_add_f32_e32 v52, v53, v52
	v_mul_f32_e32 v53, v64, v54
	v_sub_f32_e32 v54, v55, v111
	v_exp_f32_e32 v54, v54
	v_mfma_f32_16x16x32_bf16 v[60:63], v[32:35], v[4:7], v[24:27]
	v_add_u32_e32 v77, 63, v79
	v_cmp_le_u32_e64 s[6:7], v77, v114
	v_add_u32_e32 v78, 0x4f, v79
	ds_read_b128 v[24:27], v71 offset:6144
	v_cndmask_b32_e64 v53, 0, v53, s[6:7]
	v_add_f32_e32 v52, v53, v52
	v_mul_f32_e32 v53, v64, v54
	v_cmp_le_u32_e64 s[6:7], v78, v114
	v_lshlrev_b32_e32 v73, 2, v20
	ds_read_b128 v[20:23], v72 offset:6144
	v_cndmask_b32_e64 v82, 0, v53, s[6:7]
	v_add_f32_e32 v81, v82, v52
	v_xor_b32_e32 v80, 8, v185
	s_nop 0
	v_mov_b32_dpp v83, v81 row_ror:12 row_mask:0xf bank_mask:0xf
	v_mov_b32_dpp v84, v82 row_ror:12 row_mask:0xf bank_mask:0xf
	v_cmp_lt_i32_e64 s[6:7], v80, v74
	s_waitcnt lgkmcnt(0)
	v_mfma_f32_16x16x32_bf16 v[56:59], v[36:39], v[0:3], 0
	v_add_f32_e32 v82, v82, v84
	v_cndmask_b32_e64 v52, v185, v80, s[6:7]
	v_lshlrev_b32_e32 v74, 2, v52
	v_mfma_f32_16x16x32_bf16 v[52:55], v[24:27], v[0:3], 0
	v_add_f32_e32 v80, v81, v83
	s_nop 1
	v_mov_b32_dpp v81, v80 row_ror:8 row_mask:0xf bank_mask:0xf
	v_mov_b32_dpp v83, v82 row_ror:8 row_mask:0xf bank_mask:0xf
	v_mfma_f32_16x16x32_bf16 v[56:59], v[28:31], v[4:7], v[56:59]
	v_mfma_f32_16x16x32_bf16 v[52:55], v[20:23], v[4:7], v[52:55]
	s_and_saveexec_b64 s[6:7], vcc
	s_cbranch_execz .LBB0_1025
	s_waitcnt lgkmcnt(0)
	v_add_f32_e32 v80, v80, v81
	v_add_f32_e32 v81, v82, v83
	ds_add_f32 v67, v80
	ds_add_f32 v67, v81 offset:4
.LBB0_1025:
	s_or_b64 exec, exec, s[6:7]
	v_sub_f32_e32 v60, v60, v111
	v_exp_f32_e32 v80, v60
	v_sub_f32_e32 v61, v61, v111
	s_waitcnt lgkmcnt(0)
	v_exp_f32_e32 v81, v61
	v_add_u32_e32 v60, 0x11f, v79
	v_sub_f32_e32 v62, v62, v111
	v_fma_f32 v61, v64, v80, 0
	v_cmp_le_u32_e64 s[6:7], v60, v114
	v_exp_f32_e32 v82, v62
	v_mul_f32_e32 v81, v64, v81
	v_cndmask_b32_e64 v80, 0, v61, s[6:7]
	v_add_u32_e32 v61, 0x12f, v79
	v_cmp_le_u32_e64 s[6:7], v61, v114
	v_sub_f32_e32 v63, v63, v111
	s_nop 0
	v_cndmask_b32_e64 v62, 0, v81, s[6:7]
	v_add_f32_e32 v80, v62, v80
	v_add_u32_e32 v62, 0x13f, v79
	v_mul_f32_e32 v81, v64, v82
	v_exp_f32_e32 v82, v63
	v_cmp_le_u32_e64 s[6:7], v62, v114
	s_nop 1
	v_cndmask_b32_e64 v63, 0, v81, s[6:7]
	v_add_f32_e32 v80, v63, v80
	v_add_u32_e32 v63, 0x14f, v79
	v_mul_f32_e32 v81, v64, v82
	v_cmp_le_u32_e64 s[6:7], v63, v114
	s_nop 1
	v_cndmask_b32_e64 v82, 0, v81, s[6:7]
	v_add_f32_e32 v80, v82, v80
	s_nop 1
	v_mov_b32_dpp v81, v80 row_ror:12 row_mask:0xf bank_mask:0xf
	v_mov_b32_dpp v83, v82 row_ror:12 row_mask:0xf bank_mask:0xf
	s_waitcnt lgkmcnt(0)
	v_add_f32_e32 v80, v80, v81
	v_add_f32_e32 v82, v82, v83
	s_nop 0
	v_mov_b32_dpp v81, v80 row_ror:8 row_mask:0xf bank_mask:0xf
	v_mov_b32_dpp v83, v82 row_ror:8 row_mask:0xf bank_mask:0xf
	s_and_saveexec_b64 s[6:7], vcc
	s_cbranch_execz .LBB0_1027
	s_waitcnt lgkmcnt(0)
	v_add_f32_e32 v80, v80, v81
	v_add_f32_e32 v81, v82, v83
	ds_add_f32 v67, v80 offset:16
	ds_add_f32 v67, v81 offset:20
.LBB0_1027:
	s_or_b64 exec, exec, s[6:7]
	v_sub_f32_e32 v56, v56, v111
	v_exp_f32_e32 v80, v56
	v_sub_f32_e32 v57, v57, v111
	s_waitcnt lgkmcnt(0)
	v_exp_f32_e32 v81, v57
	v_add_u32_e32 v56, 0x21f, v79
	v_sub_f32_e32 v58, v58, v111
	v_fma_f32 v57, v64, v80, 0
	v_cmp_le_u32_e64 s[6:7], v56, v114
	v_exp_f32_e32 v82, v58
	v_mul_f32_e32 v81, v64, v81
	v_cndmask_b32_e64 v80, 0, v57, s[6:7]
	v_add_u32_e32 v57, 0x22f, v79
	v_cmp_le_u32_e64 s[6:7], v57, v114
	v_sub_f32_e32 v59, v59, v111
	s_nop 0
	v_cndmask_b32_e64 v58, 0, v81, s[6:7]
	v_add_f32_e32 v80, v58, v80
	v_add_u32_e32 v58, 0x23f, v79
	v_mul_f32_e32 v81, v64, v82
	v_exp_f32_e32 v82, v59
	v_cmp_le_u32_e64 s[6:7], v58, v114
	s_nop 1
	v_cndmask_b32_e64 v59, 0, v81, s[6:7]
	v_add_f32_e32 v80, v59, v80
	v_add_u32_e32 v59, 0x24f, v79
	v_mul_f32_e32 v81, v64, v82
	v_cmp_le_u32_e64 s[6:7], v59, v114
	s_nop 1
	v_cndmask_b32_e64 v82, 0, v81, s[6:7]
	v_add_f32_e32 v80, v82, v80
	s_nop 1
	v_mov_b32_dpp v81, v80 row_ror:12 row_mask:0xf bank_mask:0xf
	v_mov_b32_dpp v83, v82 row_ror:12 row_mask:0xf bank_mask:0xf
	s_waitcnt lgkmcnt(0)
	v_add_f32_e32 v80, v80, v81
	v_add_f32_e32 v82, v82, v83
	s_nop 0
	v_mov_b32_dpp v81, v80 row_ror:8 row_mask:0xf bank_mask:0xf
	v_mov_b32_dpp v83, v82 row_ror:8 row_mask:0xf bank_mask:0xf
	s_and_saveexec_b64 s[6:7], vcc
	s_cbranch_execz .LBB0_1029
	s_waitcnt lgkmcnt(0)
	v_add_f32_e32 v80, v80, v81
	v_add_f32_e32 v81, v82, v83
	ds_add_f32 v67, v80 offset:32
	ds_add_f32 v67, v81 offset:36
; #define LAS __attribute__((address_space(3)))
; template <int DQK> __device__ __forceinline__ void qk_tile(LAS unsigned char* lds, const bf16x8 (&qf)[DQK / 32], f32x4 (&s)[4], int fr, int fq) {
;     constexpr int NKS = DQK / 32;
; #pragma unroll
;     for (int ss = 0; ss < 4; ++ss) {
;         s[ss] = (f32x4){0.f, 0.f, 0.f, 0.f};
; #pragma unroll
;         for (int ks = 0; ks < NKS; ++ks) {
;             const bf16x8 kf = *(const LAS bf16x8*)(lds + k_off<DQK>(16 * ss + fr, 4 * ks + fq));
;             s[ss] = __builtin_amdgcn_mfma_f32_16x16x32_bf16(kf, qf[ks], s[ss], 0, 0, 0);
;         }
; __device__ __forceinline__ void nsa_item(LAS unsigned char* lds, const NsaPtrs& P, int b, int g, int qb, int tid) {
;     ...
;         for (int i = 0; i < 2; ++i) {
;             f32x4 s[4];
;             qk_tile<64>(lds, qf[i], s, fr_i, fq_i);
; #pragma unroll
;             for (int ss = 0; ss < 4; ++ss) {
;                 float a = 0.f, b3 = 0.f;
; #pragma unroll
;                 for (int e = 0; e < 4; ++e) { const int n = 64 * t + 16 * ss + 4 * fq_i + e; const float p = (16 * n + 31 <= tpos[i]) ? __builtin_amdgcn_exp2f(s[ss][e] - mf[i]) * li[i] : 0.f; a += p; if (e == 3) b3 = p; }
;                 a += __shfl_xor(a, 4); a += __shfl_xor(a, 8); b3 += __shfl_xor(b3, 4); b3 += __shfl_xor(b3, 8);
;                 if (fr_i < 4) { const int jp = 16 * t + 4 * ss + fq_i;
;                     __hip_atomic_fetch_add(imp + tok[i] * ISTR + jp, a, __ATOMIC_RELAXED, __HIP_MEMORY_SCOPE_WORKGROUP);
;                     __hip_atomic_fetch_add(imp + tok[i] * ISTR + jp + 1, b3, __ATOMIC_RELAXED, __HIP_MEMORY_SCOPE_WORKGROUP); }
.LBB0_1029:
	s_or_b64 exec, exec, s[6:7]
	v_sub_f32_e32 v52, v52, v111
	v_exp_f32_e32 v80, v52
	v_sub_f32_e32 v53, v53, v111
	s_waitcnt lgkmcnt(0)
	v_exp_f32_e32 v81, v53
	v_add_u32_e32 v52, 0x31f, v79
	v_sub_f32_e32 v54, v54, v111
	v_fma_f32 v53, v64, v80, 0
	v_cmp_le_u32_e64 s[6:7], v52, v114
	v_exp_f32_e32 v82, v54
	v_mul_f32_e32 v81, v64, v81
	v_cndmask_b32_e64 v80, 0, v53, s[6:7]
	v_add_u32_e32 v53, 0x32f, v79
	v_cmp_le_u32_e64 s[6:7], v53, v114
	v_sub_f32_e32 v55, v55, v111
	s_nop 0
	v_cndmask_b32_e64 v54, 0, v81, s[6:7]
	v_add_f32_e32 v80, v54, v80
	v_add_u32_e32 v54, 0x33f, v79
	v_mul_f32_e32 v81, v64, v82
	v_exp_f32_e32 v82, v55
	v_cmp_le_u32_e64 s[6:7], v54, v114
	s_nop 1
	v_cndmask_b32_e64 v55, 0, v81, s[6:7]
	v_add_f32_e32 v80, v55, v80
	v_add_u32_e32 v55, 0x34f, v79
	v_mul_f32_e32 v79, v64, v82
	v_cmp_le_u32_e64 s[6:7], v55, v114
	s_nop 1
	v_cndmask_b32_e64 v81, 0, v79, s[6:7]
	v_add_f32_e32 v79, v81, v80
	s_nop 1
	v_mov_b32_dpp v80, v79 row_ror:12 row_mask:0xf bank_mask:0xf
	v_mov_b32_dpp v82, v81 row_ror:12 row_mask:0xf bank_mask:0xf
	s_waitcnt lgkmcnt(0)
	v_add_f32_e32 v79, v79, v80
	v_add_f32_e32 v81, v81, v82
	s_nop 0
	v_mov_b32_dpp v80, v79 row_ror:8 row_mask:0xf bank_mask:0xf
	v_mov_b32_dpp v82, v81 row_ror:8 row_mask:0xf bank_mask:0xf
	s_and_saveexec_b64 s[6:7], vcc
	s_cbranch_execz .LBB0_1031
	s_waitcnt lgkmcnt(0)
	v_add_f32_e32 v79, v79, v80
	v_add_f32_e32 v80, v81, v82
	ds_add_f32 v67, v79 offset:48
	ds_add_f32 v67, v80 offset:52
.LBB0_1031:
	s_or_b64 exec, exec, s[6:7]
	v_mfma_f32_16x16x32_bf16 v[44:47], v[44:47], v[8:11], 0
	v_cmp_le_u32_e64 s[6:7], v75, v116
	v_mfma_f32_16x16x32_bf16 v[44:47], v[48:51], v[12:15], v[44:47]
	v_mfma_f32_16x16x32_bf16 v[40:43], v[40:43], v[8:11], 0
	v_mfma_f32_16x16x32_bf16 v[32:35], v[32:35], v[12:15], v[40:43]
	s_nop 5
	v_sub_f32_e32 v44, v44, v110
	v_sub_f32_e32 v45, v45, v110
	v_exp_f32_e32 v44, v44
	v_exp_f32_e32 v45, v45
	v_sub_f32_e32 v46, v46, v110
	v_exp_f32_e32 v46, v46
	v_sub_f32_e32 v42, v47, v110
	v_mfma_f32_16x16x32_bf16 v[36:39], v[36:39], v[8:11], 0
	v_exp_f32_e32 v42, v42
	v_fma_f32 v44, v66, v44, 0
	v_mul_f32_e32 v45, v66, v45
	v_cndmask_b32_e64 v44, 0, v44, s[6:7]
	v_cmp_le_u32_e64 s[6:7], v76, v116
	v_mul_f32_e32 v41, v66, v46
	v_mfma_f32_16x16x32_bf16 v[28:31], v[28:31], v[12:15], v[36:39]
	v_cndmask_b32_e64 v40, 0, v45, s[6:7]
	v_cmp_le_u32_e64 s[6:7], v77, v116
	v_add_f32_e32 v40, v40, v44
	v_mul_f32_e32 v37, v66, v42
	v_cndmask_b32_e64 v36, 0, v41, s[6:7]
	v_cmp_le_u32_e64 s[6:7], v78, v116
	v_add_f32_e32 v36, v36, v40
	s_nop 0
	v_cndmask_b32_e64 v40, 0, v37, s[6:7]
	v_add_f32_e32 v41, v40, v36
	s_nop 1
	v_mov_b32_dpp v42, v41 row_ror:12 row_mask:0xf bank_mask:0xf
	v_mov_b32_dpp v43, v40 row_ror:12 row_mask:0xf bank_mask:0xf
	v_mfma_f32_16x16x32_bf16 v[36:39], v[24:27], v[8:11], 0
	s_waitcnt lgkmcnt(0)
	v_add_f32_e32 v24, v41, v42
	v_add_f32_e32 v26, v40, v43
	s_nop 0
	v_mov_b32_dpp v25, v24 row_ror:8 row_mask:0xf bank_mask:0xf
	v_mov_b32_dpp v27, v26 row_ror:8 row_mask:0xf bank_mask:0xf
	v_mfma_f32_16x16x32_bf16 v[20:23], v[20:23], v[12:15], v[36:39]
	s_and_saveexec_b64 s[6:7], vcc
	s_cbranch_execz .LBB0_1033
	s_waitcnt lgkmcnt(0)
	v_add_f32_e32 v24, v24, v25
	v_add_f32_e32 v25, v26, v27
	ds_add_f32 v67, v24 offset:2112
	ds_add_f32 v67, v25 offset:2116
; __device__ __forceinline__ void nsa_item(LAS unsigned char* lds, const NsaPtrs& P, int b, int g, int qb, int tid) {
;     ...
;             for (int ss = 0; ss < 4; ++ss) {
;                 float a = 0.f, b3 = 0.f;
; #pragma unroll
;                 for (int e = 0; e < 4; ++e) { const int n = 64 * t + 16 * ss + 4 * fq_i + e; const float p = (16 * n + 31 <= tpos[i]) ? __builtin_amdgcn_exp2f(s[ss][e] - mf[i]) * li[i] : 0.f; a += p; if (e == 3) b3 = p; }
;                 a += __shfl_xor(a, 4); a += __shfl_xor(a, 8); b3 += __shfl_xor(b3, 4); b3 += __shfl_xor(b3, 8);
;                 if (fr_i < 4) { const int jp = 16 * t + 4 * ss + fq_i;
;                     __hip_atomic_fetch_add(imp + tok[i] * ISTR + jp, a, __ATOMIC_RELAXED, __HIP_MEMORY_SCOPE_WORKGROUP);
;                     __hip_atomic_fetch_add(imp + tok[i] * ISTR + jp + 1, b3, __ATOMIC_RELAXED, __HIP_MEMORY_SCOPE_WORKGROUP); }
.LBB0_1033:
	s_or_b64 exec, exec, s[6:7]
	v_sub_f32_e32 v24, v32, v110
	v_exp_f32_e32 v24, v24
	s_waitcnt lgkmcnt(0)
	v_sub_f32_e32 v25, v33, v110
	v_exp_f32_e32 v25, v25
	v_sub_f32_e32 v26, v34, v110
	v_exp_f32_e32 v26, v26
	v_fma_f32 v24, v66, v24, 0
	v_cmp_le_u32_e64 s[6:7], v60, v116
	v_mul_f32_e32 v25, v66, v25
	s_nop 0
	v_cndmask_b32_e64 v24, 0, v24, s[6:7]
	v_cmp_le_u32_e64 s[6:7], v61, v116
	s_nop 1
	v_cndmask_b32_e64 v25, 0, v25, s[6:7]
	v_add_f32_e32 v24, v25, v24
	v_mul_f32_e32 v25, v66, v26
	v_sub_f32_e32 v26, v35, v110
	v_exp_f32_e32 v26, v26
	v_cmp_le_u32_e64 s[6:7], v62, v116
	s_nop 1
	v_cndmask_b32_e64 v25, 0, v25, s[6:7]
	v_add_f32_e32 v24, v25, v24
	v_mul_f32_e32 v25, v66, v26
	v_cmp_le_u32_e64 s[6:7], v63, v116
	s_nop 1
	v_cndmask_b32_e64 v26, 0, v25, s[6:7]
	v_add_f32_e32 v24, v26, v24
	s_nop 1
	v_mov_b32_dpp v25, v24 row_ror:12 row_mask:0xf bank_mask:0xf
	v_mov_b32_dpp v27, v26 row_ror:12 row_mask:0xf bank_mask:0xf
	s_waitcnt lgkmcnt(0)
	v_add_f32_e32 v24, v24, v25
	v_add_f32_e32 v26, v26, v27
	s_nop 0
	v_mov_b32_dpp v25, v24 row_ror:8 row_mask:0xf bank_mask:0xf
	v_mov_b32_dpp v27, v26 row_ror:8 row_mask:0xf bank_mask:0xf
	s_and_saveexec_b64 s[6:7], vcc
	s_cbranch_execz .LBB0_1035
	s_waitcnt lgkmcnt(0)
	v_add_f32_e32 v24, v24, v25
	v_add_f32_e32 v25, v26, v27
	ds_add_f32 v67, v24 offset:2128
	ds_add_f32 v67, v25 offset:2132
.LBB0_1035:
	s_or_b64 exec, exec, s[6:7]
	v_sub_f32_e32 v24, v28, v110
	v_exp_f32_e32 v24, v24
	s_waitcnt lgkmcnt(0)
	v_sub_f32_e32 v25, v29, v110
	v_exp_f32_e32 v25, v25
	v_sub_f32_e32 v26, v30, v110
	v_exp_f32_e32 v26, v26
	v_fma_f32 v24, v66, v24, 0
	v_cmp_le_u32_e64 s[6:7], v56, v116
	v_mul_f32_e32 v25, v66, v25
	s_nop 0
	v_cndmask_b32_e64 v24, 0, v24, s[6:7]
	v_cmp_le_u32_e64 s[6:7], v57, v116
	s_nop 1
	v_cndmask_b32_e64 v25, 0, v25, s[6:7]
	v_add_f32_e32 v24, v25, v24
	v_mul_f32_e32 v25, v66, v26
	v_sub_f32_e32 v26, v31, v110
	v_exp_f32_e32 v26, v26
	v_cmp_le_u32_e64 s[6:7], v58, v116
	s_nop 1
	v_cndmask_b32_e64 v25, 0, v25, s[6:7]
	v_add_f32_e32 v24, v25, v24
	v_mul_f32_e32 v25, v66, v26
	v_cmp_le_u32_e64 s[6:7], v59, v116
	s_nop 1
	v_cndmask_b32_e64 v26, 0, v25, s[6:7]
	v_add_f32_e32 v24, v26, v24
	s_nop 1
	v_mov_b32_dpp v25, v24 row_ror:12 row_mask:0xf bank_mask:0xf
	v_mov_b32_dpp v27, v26 row_ror:12 row_mask:0xf bank_mask:0xf
	s_waitcnt lgkmcnt(0)
	v_add_f32_e32 v24, v24, v25
	v_add_f32_e32 v26, v26, v27
	s_nop 0
	v_mov_b32_dpp v25, v24 row_ror:8 row_mask:0xf bank_mask:0xf
	v_mov_b32_dpp v27, v26 row_ror:8 row_mask:0xf bank_mask:0xf
	s_and_saveexec_b64 s[6:7], vcc
	s_cbranch_execz .LBB0_1037
	s_waitcnt lgkmcnt(0)
	v_add_f32_e32 v24, v24, v25
	v_add_f32_e32 v25, v26, v27
	ds_add_f32 v67, v24 offset:2144
	ds_add_f32 v67, v25 offset:2148
.LBB0_1037:
	s_or_b64 exec, exec, s[6:7]
	v_sub_f32_e32 v20, v20, v110
	v_exp_f32_e32 v20, v20
	v_sub_f32_e32 v21, v21, v110
	v_exp_f32_e32 v21, v21
	v_sub_f32_e32 v22, v22, v110
	v_exp_f32_e32 v22, v22
	v_fma_f32 v20, v66, v20, 0
	v_cmp_le_u32_e64 s[6:7], v52, v116
	v_mul_f32_e32 v21, v66, v21
	s_nop 0
	v_cndmask_b32_e64 v20, 0, v20, s[6:7]
	v_cmp_le_u32_e64 s[6:7], v53, v116
	s_nop 1
	v_cndmask_b32_e64 v21, 0, v21, s[6:7]
	v_add_f32_e32 v20, v21, v20
	v_mul_f32_e32 v21, v66, v22
	v_sub_f32_e32 v22, v23, v110
	v_exp_f32_e32 v22, v22
	v_cmp_le_u32_e64 s[6:7], v54, v116
	s_nop 1
	v_cndmask_b32_e64 v21, 0, v21, s[6:7]
	v_add_f32_e32 v20, v21, v20
	v_mul_f32_e32 v21, v66, v22
	v_cmp_le_u32_e64 s[6:7], v55, v116
	s_nop 1
	v_cndmask_b32_e64 v22, 0, v21, s[6:7]
	v_add_f32_e32 v20, v22, v20
	s_nop 1
	v_mov_b32_dpp v21, v20 row_ror:12 row_mask:0xf bank_mask:0xf
	v_mov_b32_dpp v23, v22 row_ror:12 row_mask:0xf bank_mask:0xf
	s_waitcnt lgkmcnt(0)
	v_add_f32_e32 v20, v20, v21
	v_add_f32_e32 v22, v22, v23
	s_nop 0
	v_mov_b32_dpp v21, v20 row_ror:8 row_mask:0xf bank_mask:0xf
	v_mov_b32_dpp v23, v22 row_ror:8 row_mask:0xf bank_mask:0xf
	s_and_b64 exec, exec, vcc
	s_cbranch_execz .LBB0_1019
	s_waitcnt lgkmcnt(0)
	v_add_f32_e32 v20, v20, v21
	v_add_f32_e32 v21, v22, v23
	ds_add_f32 v67, v20 offset:2160
	ds_add_f32 v67, v21 offset:2164
	s_branch .LBB0_1019

; #define LAS __attribute__((address_space(3)))
; __device__ __forceinline__ void sel_pass(LAS unsigned char* lds, const bf16* K0, const bf16* V, int thi, const bf16x8 (&qf)[2][2], const int (&tpos)[2], const int (&tok)[2], int wave_tmin, int wave_tmax,
;         f32x4 (&o)[2][4], float (&mfin)[2], float (&linv)[2], int tid, int fr, int fq) {
;     ...
;     Stage<64> st[2];
;     stage_load<64>(st[0], K0, 64, nullptr, 0, V, 64, 0, true, tid);
;     if (thi >= 1) stage_load<64>(st[1], K0, 64, nullptr, 0, V, 64, 1, true, tid);
;     stage_store<64, SEL_V>(st[0], lds, true, tid);
;     if (thi >= 1) stage_store<64, SEL_V>(st[1], lds + SEL_SLOT, true, tid);
; __device__ __forceinline__ void nsa_item(LAS unsigned char* lds, const NsaPtrs& P, int b, int g, int qb, int tid) {
;     ...
;         unsigned bits = 0u;
; #pragma unroll
;         for (int jj = 0; jj < 16; ++jj) { const int j = part * 16 + jj; if (j <= qb && cnt[jj] < 16) bits |= (1u << jj); }
;         ((LAS unsigned short*)(lds + OFF_SEL))[tk * 8 + part] = (unsigned short)bits;
;     }
;     ...
;     __syncthreads();
;     ...
;     nsa_load_q(P.QN, b, g, tid, t0, qf);
;     ...
;     sel_pass(lds, P.KV6 + 2 * KV6_SEG + bg * T * 64, P.KV6 + 3 * KV6_SEG + bg * T * 64, qb, qf, tpos, tok, wave_tmin, wave_tmax, o, mf, li, tid, fr, fq);
;     ...
;     sel_pass(lds, P.KV6 + 2 * KV6_SEG + bg * T * 64, P.KV6 + 3 * KV6_SEG + bg * T * 64, qb, qf, tpos, tok, wave_tmin, wave_tmax, o, mf, li, tid, fr, fq);
.LBB0_1078:
	v_cmp_ge_u32_e32 vcc, s72, v33
	v_cmp_gt_u32_e64 s[6:7], 16, v31
	s_and_b64 s[6:7], vcc, s[6:7]
	v_cmp_gt_u32_e32 vcc, s72, v33
	v_cndmask_b32_e64 v0, 0, 1, s[6:7]
	v_cmp_gt_u32_e64 s[6:7], 16, v29
	s_and_b64 s[6:7], vcc, s[6:7]
	v_cmp_gt_u32_e32 vcc, 16, v27
	v_cndmask_b32_e64 v2, 0, 2, s[6:7]
	v_cmp_ge_u32_e64 s[6:7], s72, v34
	s_and_b64 s[6:7], s[6:7], vcc
	v_or_b32_e32 v0, v2, v0
	v_cndmask_b32_e64 v2, 0, 4, s[6:7]
	v_cmp_gt_u32_e32 vcc, 16, v25
	v_cmp_ge_u32_e64 s[6:7], s72, v35
	s_and_b64 s[6:7], s[6:7], vcc
	v_cmp_gt_u32_e32 vcc, 16, v23
	v_cndmask_b32_e64 v4, 0, 8, s[6:7]
	v_cmp_ge_u32_e64 s[6:7], s72, v36
	s_and_b64 s[6:7], s[6:7], vcc
	v_bitop3_b16 v0, v0, v4, v2 bitop3:0xfe
	v_cndmask_b32_e64 v2, 0, 16, s[6:7]
	v_cmp_gt_u32_e32 vcc, 16, v21
	v_cmp_ge_u32_e64 s[6:7], s72, v37
	s_and_b64 s[6:7], s[6:7], vcc
	v_cmp_gt_u32_e32 vcc, 16, v19
	v_cndmask_b32_e64 v4, 0, 32, s[6:7]
	v_cmp_ge_u32_e64 s[6:7], s72, v38
	s_and_b64 s[6:7], s[6:7], vcc
	v_bitop3_b16 v0, v0, v4, v2 bitop3:0xfe
	v_cndmask_b32_e64 v2, 0, 64, s[6:7]
	v_cmp_gt_u32_e32 vcc, 16, v17
	v_cmp_ge_u32_e64 s[6:7], s72, v39
	s_and_b64 vcc, s[6:7], vcc
	v_cndmask_b32_e32 v4, 0, v186, vcc
	v_cmp_gt_u32_e32 vcc, 16, v15
	v_cmp_ge_u32_e64 s[6:7], s72, v40
	s_and_b64 vcc, s[6:7], vcc
	v_bitop3_b16 v0, v0, v4, v2 bitop3:0xfe
	v_cndmask_b32_e32 v2, 0, v187, vcc
	v_cmp_gt_u32_e32 vcc, 16, v13
	v_cmp_ge_u32_e64 s[6:7], s72, v41
	s_and_b64 vcc, s[6:7], vcc
	v_cndmask_b32_e32 v4, 0, v188, vcc
	v_cmp_gt_u32_e32 vcc, 16, v11
	v_cmp_ge_u32_e64 s[6:7], s72, v42
	s_and_b64 vcc, s[6:7], vcc
	v_bitop3_b16 v0, v0, v4, v2 bitop3:0xfe
	v_cndmask_b32_e32 v2, 0, v189, vcc
	v_cmp_gt_u32_e32 vcc, 16, v9
	v_cmp_ge_u32_e64 s[6:7], s72, v44
	s_and_b64 vcc, s[6:7], vcc
	v_cndmask_b32_e32 v4, 0, v190, vcc
	v_cmp_gt_u32_e32 vcc, 16, v7
	v_cmp_ge_u32_e64 s[6:7], s72, v45
	s_and_b64 vcc, s[6:7], vcc
	v_bitop3_b16 v0, v0, v4, v2 bitop3:0xfe
	v_cndmask_b32_e32 v2, 0, v191, vcc
	v_cmp_gt_u32_e32 vcc, 16, v5
	v_cmp_ge_u32_e64 s[6:7], s72, v46
	s_and_b64 vcc, s[6:7], vcc
	v_cndmask_b32_e32 v4, 0, v192, vcc
	v_cmp_gt_u32_e32 vcc, 16, v3
	v_cmp_ge_u32_e64 s[6:7], s72, v47
	s_and_b64 vcc, s[6:7], vcc
	v_bitop3_b16 v0, v0, v4, v2 bitop3:0xfe
	v_cndmask_b32_e32 v2, 0, v193, vcc
	v_cmp_gt_u32_e32 vcc, 16, v1
	v_cmp_ge_u32_e64 s[6:7], s72, v48
	s_and_b64 vcc, s[6:7], vcc
	v_cndmask_b32_e32 v1, 0, v194, vcc
	v_bitop3_b16 v0, v0, v1, v2 bitop3:0xfe
	v_lshl_add_u32 v1, v32, 1, 0
	v_add_u32_e32 v1, 0x12000, v1
	v_mov_b32_e32 v4, v144
	ds_write_b16 v1, v0
	s_waitcnt lgkmcnt(0)
	s_barrier
	v_mov_b32_e32 v3, s47
	v_ashrrev_i32_e32 v0, 3, v4
	v_and_b32_e32 v0, -8, v0
	v_ashrrev_i32_e32 v1, 31, v0
	v_and_or_b32 v2, v4, 3, s86
	v_lshl_add_u64 v[0:1], v[2:3], 0, v[0:1]
	v_lshlrev_b32_e32 v2, 4, v4
	v_and_b32_e32 v2, 0xc0, v2
	v_or_b32_e32 v2, s70, v2
	s_mov_b64 s[6:7], s[58:59]
	v_lshlrev_b32_e32 v146, 1, v2
	v_lshlrev_b64 v[0:1], 10, v[0:1]
	v_lshl_add_u64 v[2:3], s[6:7], 0, v[146:147]
	v_and_b32_e32 v146, 48, v4
	v_lshl_add_u64 v[2:3], v[2:3], 0, v[146:147]
	v_lshl_add_u64 v[0:1], v[2:3], 0, v[0:1]
	global_load_dwordx4 v[12:15], v[0:1], off
	global_load_dwordx4 v[16:19], v[0:1], off offset:64
	v_add_co_u32_e32 v0, vcc, s75, v0
	s_add_u32 s10, s54, s50
	s_nop 0
	v_addc_co_u32_e32 v1, vcc, 0, v1, vcc
	s_addc_u32 s11, s55, s51
	v_mov_b32_e32 v4, v144
	global_load_dwordx4 v[20:23], v[0:1], off
	global_load_dwordx4 v[24:27], v[0:1], off offset:64
	s_add_u32 s6, s10, 0xb200000
	s_addc_u32 s7, s11, 0
	v_ashrrev_i32_e32 v0, 3, v4
	v_ashrrev_i32_e32 v1, 31, v0
	s_add_u32 s10, s10, 0xb600000
	v_lshlrev_b64 v[2:3], 7, v[0:1]
	v_lshlrev_b32_e32 v1, 3, v4
	s_addc_u32 s11, s11, 0
	v_and_b32_e32 v1, 56, v1
	v_lshlrev_b32_e32 v146, 1, v1
	v_lshl_add_u64 v[130:131], s[6:7], 0, v[2:3]
	v_lshl_add_u64 v[6:7], v[130:131], 0, v[146:147]
	v_lshl_add_u64 v[132:133], s[10:11], 0, v[2:3]
	global_load_dwordx4 v[32:35], v[6:7], off
	v_lshl_add_u64 v[6:7], v[132:133], 0, v[146:147]
	global_load_dwordx4 v[36:39], v[6:7], off
	s_and_b64 vcc, exec, s[8:9]
	s_cbranch_vccz .LBB0_1080
	v_lshl_add_u64 v[2:3], v[2:3], 0, s[38:39]
	v_lshl_add_u64 v[6:7], s[10:11], 0, v[2:3]
	v_lshl_add_u64 v[2:3], s[6:7], 0, v[2:3]
	v_lshl_add_u64 v[2:3], v[2:3], 0, v[146:147]
	v_lshl_add_u64 v[6:7], v[6:7], 0, v[146:147]
	global_load_dwordx4 v[44:47], v[2:3], off
	global_load_dwordx4 v[48:51], v[6:7], off

; template <int DQK> __device__ __forceinline__ void stage_load(Stage<DQK>& s, const bf16* K0, int p0, const bf16* K1, int p1, const bf16* V, int pv, int tile, bool withV, int tid) {
;     { const int key = tid >> 3, c = tid & 7; s.k0 = *(const v4u*)(K0 + (size_t)(64 * tile + key) * p0 + 8 * c); }
;     if (DQK == 96) { if (tid < 256) { const int key = tid >> 2, c = tid & 3; s.k1 = *(const v4u*)(K1 + (size_t)(64 * tile + key) * p1 + 8 * c); } }
;     if (withV) { const int key = tid >> 3, c = tid & 7; s.v = *(const v4u*)(V + (size_t)(64 * tile + key) * pv + 8 * c); }
; }
; __device__ __forceinline__ void sel_pass(LAS unsigned char* lds, const bf16* K0, const bf16* V, int thi, const bf16x8 (&qf)[2][2], const int (&tpos)[2], const int (&tok)[2], int wave_tmin, int wave_tmax,
;         f32x4 (&o)[2][4], float (&mfin)[2], float (&linv)[2], int tid, int fr, int fq) {
;     ...
;     for (int g = 0; 2 * g <= thi; ++g) {
;         const int par = g & 1;
; #pragma unroll
;         for (int u = 0; u < 2; ++u) if (2 * g + 2 + u <= thi) stage_load<64>(st[u], K0, 64, nullptr, 0, V, 64, 2 * g + 2 + u, true, tid);
.LBB0_1083:
	s_add_i32 s91, s94, 2
	s_cmp_le_u32 s91, s72
	s_cselect_b64 s[60:61], -1, 0
	s_cmp_gt_u32 s91, s72
	v_lshl_add_u64 v[66:67], v[130:131], 0, v[146:147]
	v_lshl_add_u64 v[64:65], v[132:133], 0, v[146:147]
	s_cbranch_scc1 .LBB0_1085
	s_waitcnt vmcnt(0) lgkmcnt(0)
	v_add_co_u32_e32 v32, vcc, 0x4000, v66
	s_nop 1
	v_addc_co_u32_e32 v33, vcc, 0, v67, vcc
	v_add_co_u32_e32 v36, vcc, 0x4000, v64
	global_load_dwordx4 v[32:35], v[32:33], off
	s_nop 0
	v_addc_co_u32_e32 v37, vcc, 0, v65, vcc
	global_load_dwordx4 v[36:39], v[36:37], off
.LBB0_1085:
	s_add_i32 s6, s94, 3
	s_cmp_le_u32 s6, s72
	s_cselect_b64 s[62:63], -1, 0
	s_cmp_gt_u32 s6, s72
	s_cbranch_scc1 .LBB0_1087
	s_waitcnt vmcnt(0) lgkmcnt(0)
	v_add_co_u32_e32 v44, vcc, 0x6000, v66
	s_nop 1
	v_addc_co_u32_e32 v45, vcc, 0, v67, vcc
	v_add_co_u32_e32 v48, vcc, 0x6000, v64
	global_load_dwordx4 v[44:47], v[44:45], off
	s_nop 0
	v_addc_co_u32_e32 v49, vcc, 0, v65, vcc
	global_load_dwordx4 v[48:51], v[48:49], off

; template <int MODE> __device__ __forceinline__ bool key_ok(int kpos, int tpos, bool rowsel) {
;     if (MODE == CAUSAL) return kpos <= tpos;
;     if (MODE == WINDOW) return kpos <= tpos && kpos + 512 > tpos;
;     if (MODE == CMP) return 16 * kpos + 31 <= tpos;
;     return rowsel && kpos <= tpos;
; }
; template <int DQK, int MODE, bool FULL, int I0, int NQ> __device__ __forceinline__ void tile_x(LAS unsigned char* lds, const bf16x8 (&qf)[2][DQK / 32], int kbase, const int (&tpos)[2], const bool (&rowsel)[2],
;         float (&m)[2], float (&l)[2], f32x4 (&o)[2][4], f32x4 (&s)[2][4], int fr, int fq) {
;     ...
;             } else {
;                 mx = NEG;
; #pragma unroll
;                 for (int ss = 0; ss < 4; ++ss)
; #pragma unroll
;                     for (int i = 0; i < 4; ++i) { const bool ok = key_ok<MODE>(kbase + 16 * ss + 4 * fq + i, tpos[I0 + q], rowsel[I0 + q]); const float v = ok ? sq[ss][i] : NEG; sq[ss][i] = v; mx = fmaxf(mx, v); }
.Lsel_maskA:
	v_add_u32_e32 v196, s97, v142
	v_sub_u32_e32 v198, v116, v196
	s_nop 4
	v_cmp_le_i32_e64 s[100:101], 0, v198
	v_cmp_le_i32_e64 s[20:21], 1, v198
	v_cmp_le_i32_e64 s[64:65], 2, v198
	v_cndmask_b32_e64 v212, v183, v212, s[100:101]
	v_cmp_le_i32_e64 s[100:101], 3, v198
	v_cndmask_b32_e64 v213, v183, v213, s[20:21]
	v_cmp_le_i32_e64 s[20:21], 16, v198
	v_cndmask_b32_e64 v214, v183, v214, s[64:65]
	v_cmp_le_i32_e64 s[64:65], 17, v198
	v_cndmask_b32_e64 v215, v183, v215, s[100:101]
	v_cmp_le_i32_e64 s[100:101], 18, v198
	v_cndmask_b32_e64 v216, v183, v216, s[20:21]
	v_cmp_le_i32_e64 s[20:21], 19, v198
	v_cndmask_b32_e64 v217, v183, v217, s[64:65]
	v_cmp_le_i32_e64 s[64:65], 32, v198
	v_cndmask_b32_e64 v218, v183, v218, s[100:101]
	v_cmp_le_i32_e64 s[100:101], 33, v198
	v_cndmask_b32_e64 v219, v183, v219, s[20:21]
	v_cmp_le_i32_e64 s[20:21], 34, v198
	v_cndmask_b32_e64 v220, v183, v220, s[64:65]
	v_cmp_le_i32_e64 s[64:65], 35, v198
	v_cndmask_b32_e64 v221, v183, v221, s[100:101]
	v_cmp_le_i32_e64 s[100:101], 48, v198
	v_cndmask_b32_e64 v222, v183, v222, s[20:21]
	v_cmp_le_i32_e64 s[20:21], 49, v198
	v_cndmask_b32_e64 v223, v183, v223, s[64:65]
	v_cmp_le_i32_e64 s[64:65], 50, v198
	v_cndmask_b32_e64 v224, v183, v224, s[100:101]
	v_cmp_le_i32_e64 s[100:101], 51, v198
	s_nop 1
	v_cndmask_b32_e64 v225, v183, v225, s[20:21]
	v_cndmask_b32_e64 v226, v183, v226, s[64:65]
	v_cndmask_b32_e64 v227, v183, v227, s[100:101]
	s_branch .Lsel_slowA

; template <int MODE> __device__ __forceinline__ bool key_ok(int kpos, int tpos, bool rowsel) {
;     if (MODE == CAUSAL) return kpos <= tpos;
;     if (MODE == WINDOW) return kpos <= tpos && kpos + 512 > tpos;
;     if (MODE == CMP) return 16 * kpos + 31 <= tpos;
;     return rowsel && kpos <= tpos;
; }
; template <int DQK, int MODE, bool FULL, int I0, int NQ> __device__ __forceinline__ void tile_x(LAS unsigned char* lds, const bf16x8 (&qf)[2][DQK / 32], int kbase, const int (&tpos)[2], const bool (&rowsel)[2],
;         float (&m)[2], float (&l)[2], f32x4 (&o)[2][4], f32x4 (&s)[2][4], int fr, int fq) {
;     ...
;             } else {
;                 mx = NEG;
; #pragma unroll
;                 for (int ss = 0; ss < 4; ++ss)
; #pragma unroll
;                     for (int i = 0; i < 4; ++i) { const bool ok = key_ok<MODE>(kbase + 16 * ss + 4 * fq + i, tpos[I0 + q], rowsel[I0 + q]); const float v = ok ? sq[ss][i] : NEG; sq[ss][i] = v; mx = fmaxf(mx, v); }
.Lsel_maskB:
	v_add_u32_e32 v196, s97, v142
	v_sub_u32_e32 v198, v114, v196
	s_nop 4
	v_cmp_le_i32_e64 s[100:101], 0, v198
	v_cmp_le_i32_e64 s[20:21], 1, v198
	v_cmp_le_i32_e64 s[64:65], 2, v198
	v_cndmask_b32_e64 v212, v183, v212, s[100:101]
	v_cmp_le_i32_e64 s[100:101], 3, v198
	v_cndmask_b32_e64 v213, v183, v213, s[20:21]
	v_cmp_le_i32_e64 s[20:21], 16, v198
	v_cndmask_b32_e64 v214, v183, v214, s[64:65]
	v_cmp_le_i32_e64 s[64:65], 17, v198
	v_cndmask_b32_e64 v215, v183, v215, s[100:101]
	v_cmp_le_i32_e64 s[100:101], 18, v198
	v_cndmask_b32_e64 v216, v183, v216, s[20:21]
	v_cmp_le_i32_e64 s[20:21], 19, v198
	v_cndmask_b32_e64 v217, v183, v217, s[64:65]
	v_cmp_le_i32_e64 s[64:65], 32, v198
	v_cndmask_b32_e64 v218, v183, v218, s[100:101]
	v_cmp_le_i32_e64 s[100:101], 33, v198
	v_cndmask_b32_e64 v219, v183, v219, s[20:21]
	v_cmp_le_i32_e64 s[20:21], 34, v198
	v_cndmask_b32_e64 v220, v183, v220, s[64:65]
	v_cmp_le_i32_e64 s[64:65], 35, v198
	v_cndmask_b32_e64 v221, v183, v221, s[100:101]
	v_cmp_le_i32_e64 s[100:101], 48, v198
	v_cndmask_b32_e64 v222, v183, v222, s[20:21]
	v_cmp_le_i32_e64 s[20:21], 49, v198
	v_cndmask_b32_e64 v223, v183, v223, s[64:65]
	v_cmp_le_i32_e64 s[64:65], 50, v198
	v_cndmask_b32_e64 v224, v183, v224, s[100:101]
	v_cmp_le_i32_e64 s[100:101], 51, v198
	s_nop 1
	v_cndmask_b32_e64 v225, v183, v225, s[20:21]
	v_cndmask_b32_e64 v226, v183, v226, s[64:65]
	v_cndmask_b32_e64 v227, v183, v227, s[100:101]
	s_branch .Lsel_slowB

; __device__ __forceinline__ v4u pack8(const f32x4& a, const f32x4& b) { return (v4u){cvtpk(a[0], a[1]), cvtpk(a[2], a[3]), cvtpk(b[0], b[1]), cvtpk(b[2], b[3])}; }
; __device__ __forceinline__ f32x4 unpk_lo(const v4u& w) { return (f32x4){__uint_as_float(w.x << 16), __uint_as_float(w.x & 0xffff0000u), __uint_as_float(w.y << 16), __uint_as_float(w.y & 0xffff0000u)}; }
; __device__ __forceinline__ f32x4 unpk_hi(const v4u& w) { return (f32x4){__uint_as_float(w.z << 16), __uint_as_float(w.z & 0xffff0000u), __uint_as_float(w.w << 16), __uint_as_float(w.w & 0xffff0000u)}; }
; __device__ __forceinline__ void sel_pass(LAS unsigned char* lds, const bf16* K0, const bf16* V, int thi, const bf16x8 (&qf)[2][2], const int (&tpos)[2], const int (&tok)[2], int wave_tmin, int wave_tmax,
;         f32x4 (&o)[2][4], float (&mfin)[2], float (&linv)[2], int tid, int fr, int fq) {
;     ...
; #pragma unroll
;     for (int i = 0; i < 2; ++i) {
;         const float lt = rows_sum(l[i]);
;         const float iv = lt > 0.f ? 1.0f / lt : 0.f;
;         mfin[i] = m[i]; linv[i] = iv;
; #pragma unroll
;         for (int dt = 0; dt < 4; ++dt) o[i][dt] = o[i][dt] * iv;
;     }
; __device__ __forceinline__ void nsa_item(LAS unsigned char* lds, const NsaPtrs& P, int b, int g, int qb, int tid) {
;     ...
; #pragma unroll
;     for (int i = 0; i < 2; ++i) { const float gs = P.GATES[((size_t)b * T + tpos[i]) * 24 + g * 12 + hh * 3 + 1];
; #pragma unroll
;         for (int h = 0; h < 2; ++h) { const v4u w = ocl[(i * 2 + h) * NTHREADS + tid]; ocl[(i * 2 + h) * NTHREADS + tid] = pack8(unpk_lo(w) + o[i][2 * h] * gs, unpk_hi(w) + o[i][2 * h + 1] * gs); } }
;     ...
;     nsa_load_q(P.QN, b, g, tid, t0, qf);
;     ...
;     attn_pass<64, WINDOW>(lds, P.KV6 + 4 * KV6_SEG + bg * T * 64, 64, nullptr, 0, P.KV6 + 5 * KV6_SEG + bg * T * 64, 64, (qb >= 8 ? qb - 8 : 0), qb, qf, tpos, tok, wave_tmin, wave_tmax, o, mf, li, tid, fr, fq);
;     ...
;     attn_pass<64, WINDOW>(lds, P.KV6 + 4 * KV6_SEG + bg * T * 64, 64, nullptr, 0, P.KV6 + 5 * KV6_SEG + bg * T * 64, 64, (qb >= 8 ? qb - 8 : 0), qb, qf, tpos, tok, wave_tmin, wave_tmax, o, mf, li, tid, fr, fq);
.LBB0_1189:
	global_load_dword v20, v[128:129], off offset:4
	v_mov_b32_e32 v21, v134
	v_mov_b32_e32 v22, v135
	s_nop 0
	v_permlane16_swap_b32_e32 v134, v21
	v_permlane16_swap_b32_e32 v135, v22
	v_add_f32_e32 v23, v134, v21
	v_add_f32_e32 v22, v135, v22
	v_mov_b32_e32 v25, v23
	v_mov_b32_e32 v24, v22
	s_nop 0
	v_permlane32_swap_b32_e32 v23, v25
	v_permlane32_swap_b32_e32 v22, v24
	v_pk_add_f32 v[22:23], v[22:23], v[24:25]
	ds_read_b128 v[12:15], v173
	ds_read_b128 v[16:19], v173 offset:8192
	v_div_scale_f32 v21, s[6:7], v23, v23, 1.0
	s_waitcnt vmcnt(0) lgkmcnt(0)
	v_rcp_f32_e32 v36, v21
	v_div_scale_f32 v37, vcc, 1.0, v23, 1.0
	v_lshlrev_b32_e32 v24, 16, v12
	v_fma_f32 v38, -v21, v36, 1.0
	v_fmac_f32_e32 v36, v38, v36
	v_mul_f32_e32 v38, v37, v36
	v_fma_f32 v39, -v21, v38, v37
	v_fmac_f32_e32 v38, v39, v36
	v_fma_f32 v21, -v21, v38, v37
	v_div_fmas_f32 v21, v21, v36, v38
	v_div_fixup_f32 v21, v21, v23, 1.0
	v_cmp_lt_f32_e32 vcc, 0, v23
	v_and_b32_e32 v25, 0xffff0000, v12
	v_lshlrev_b32_e32 v12, 16, v13
	v_cndmask_b32_e32 v36, 0, v21, vcc
	v_and_b32_e32 v13, 0xffff0000, v13
	v_lshlrev_b32_e32 v26, 16, v14
	v_and_b32_e32 v27, 0xffff0000, v14
	v_lshlrev_b32_e32 v14, 16, v15
	v_and_b32_e32 v15, 0xffff0000, v15
	v_pk_mul_f32 v[38:39], v[60:61], v[36:37] op_sel_hi:[1,0]
	v_pk_mul_f32 v[44:45], v[62:63], v[36:37] op_sel_hi:[1,0]
	v_pk_mul_f32 v[46:47], v[56:57], v[36:37] op_sel_hi:[1,0]
	v_pk_mul_f32 v[48:49], v[58:59], v[36:37] op_sel_hi:[1,0]
	v_lshlrev_b32_e32 v32, 16, v16
	v_and_b32_e32 v33, 0xffff0000, v16
	v_lshlrev_b32_e32 v16, 16, v17
	v_and_b32_e32 v17, 0xffff0000, v17
	v_lshlrev_b32_e32 v34, 16, v18
	v_and_b32_e32 v35, 0xffff0000, v18
	v_lshlrev_b32_e32 v18, 16, v19
	v_and_b32_e32 v19, 0xffff0000, v19
	v_pk_mul_f32 v[50:51], v[52:53], v[36:37] op_sel_hi:[1,0]
	v_pk_mul_f32 v[52:53], v[54:55], v[36:37] op_sel_hi:[1,0]
	v_pk_mul_f32 v[40:41], v[40:41], v[36:37] op_sel_hi:[1,0]
	v_pk_mul_f32 v[36:37], v[42:43], v[36:37] op_sel_hi:[1,0]
	s_add_u32 s6, s54, s50
	s_addc_u32 s11, s55, s51
	s_add_u32 s8, s6, 0xba00000
	s_addc_u32 s9, s11, 0
	s_add_u32 s10, s6, 0xbe00000
	v_mov_b32_e32 v23, s47
	s_addc_u32 s11, s11, 0
	v_pk_fma_f32 v[42:43], v[20:21], v[44:45], v[12:13] op_sel_hi:[0,1,1]
	v_pk_fma_f32 v[12:13], v[20:21], v[38:39], v[24:25] op_sel_hi:[0,1,1]
	v_pk_fma_f32 v[24:25], v[20:21], v[48:49], v[14:15] op_sel_hi:[0,1,1]
	v_pk_fma_f32 v[14:15], v[20:21], v[46:47], v[26:27] op_sel_hi:[0,1,1]
	v_pk_fma_f32 v[26:27], v[20:21], v[52:53], v[16:17] op_sel_hi:[0,1,1]
	v_pk_fma_f32 v[16:17], v[20:21], v[50:51], v[32:33] op_sel_hi:[0,1,1]
	v_pk_fma_f32 v[32:33], v[20:21], v[36:37], v[18:19] op_sel_hi:[0,1,1]
	v_pk_fma_f32 v[18:19], v[20:21], v[40:41], v[34:35] op_sel_hi:[0,1,1]
	v_cvt_pk_bf16_f32 v12, v12, v13
	v_cvt_pk_bf16_f32 v13, v42, v43
	v_cvt_pk_bf16_f32 v14, v14, v15
	v_cvt_pk_bf16_f32 v15, v24, v25
	v_cvt_pk_bf16_f32 v16, v16, v17
	v_cvt_pk_bf16_f32 v17, v26, v27
	v_cvt_pk_bf16_f32 v18, v18, v19
	v_cvt_pk_bf16_f32 v19, v32, v33
	ds_write_b128 v173, v[12:15]
	ds_write_b128 v173, v[16:19] offset:8192
	global_load_dword v24, v[126:127], off offset:4
	v_div_scale_f32 v38, s[6:7], v22, v22, 1.0
	v_rcp_f32_e32 v39, v38
	v_div_scale_f32 v40, vcc, 1.0, v22, 1.0
	ds_read_b128 v[14:17], v173 offset:16384
	ds_read_b128 v[18:21], v173 offset:24576
	v_fma_f32 v41, -v38, v39, 1.0
	v_fmac_f32_e32 v39, v41, v39
	v_mul_f32_e32 v41, v40, v39
	v_fma_f32 v42, -v38, v41, v40
	v_fmac_f32_e32 v41, v42, v39
	v_fma_f32 v38, -v38, v41, v40
	v_div_fmas_f32 v38, v38, v39, v41
	v_div_fixup_f32 v38, v38, v22, 1.0
	v_cmp_lt_f32_e32 vcc, 0, v22
	v_sub_u32_e64 v25, s72, 8 clamp
	s_waitcnt lgkmcnt(0)
	v_lshlrev_b32_e32 v26, 16, v14
	v_cndmask_b32_e32 v22, 0, v38, vcc
	v_and_b32_e32 v27, 0xffff0000, v14
	v_lshlrev_b32_e32 v14, 16, v15
	v_and_b32_e32 v15, 0xffff0000, v15
	v_lshlrev_b32_e32 v32, 16, v16
	v_and_b32_e32 v33, 0xffff0000, v16
	v_lshlrev_b32_e32 v16, 16, v17
	v_and_b32_e32 v17, 0xffff0000, v17
	v_pk_mul_f32 v[28:29], v[28:29], v[22:23] op_sel_hi:[1,0]
	v_pk_mul_f32 v[30:31], v[30:31], v[22:23] op_sel_hi:[1,0]
	v_pk_mul_f32 v[8:9], v[8:9], v[22:23] op_sel_hi:[1,0]
	v_pk_mul_f32 v[10:11], v[10:11], v[22:23] op_sel_hi:[1,0]
	v_lshlrev_b32_e32 v34, 16, v18
	v_and_b32_e32 v35, 0xffff0000, v18
	v_lshlrev_b32_e32 v18, 16, v19
	v_and_b32_e32 v19, 0xffff0000, v19
	v_lshlrev_b32_e32 v36, 16, v20
	v_and_b32_e32 v37, 0xffff0000, v20
	v_lshlrev_b32_e32 v20, 16, v21
	v_and_b32_e32 v21, 0xffff0000, v21
	v_pk_mul_f32 v[4:5], v[4:5], v[22:23] op_sel_hi:[1,0]
	v_pk_mul_f32 v[6:7], v[6:7], v[22:23] op_sel_hi:[1,0]
	v_pk_mul_f32 v[0:1], v[0:1], v[22:23] op_sel_hi:[1,0]
	v_pk_mul_f32 v[2:3], v[2:3], v[22:23] op_sel_hi:[1,0]
	v_mov_b32_e32 v13, v144
	v_mov_b32_e32 v12, v144
	v_cmp_gt_u32_e64 s[6:7], s72, v25
	s_waitcnt vmcnt(0)
	v_pk_fma_f32 v[14:15], v[24:25], v[30:31], v[14:15] op_sel_hi:[0,1,1]
	v_pk_fma_f32 v[26:27], v[24:25], v[28:29], v[26:27] op_sel_hi:[0,1,1]
	v_pk_fma_f32 v[10:11], v[24:25], v[10:11], v[16:17] op_sel_hi:[0,1,1]
	v_pk_fma_f32 v[8:9], v[24:25], v[8:9], v[32:33] op_sel_hi:[0,1,1]
	v_pk_fma_f32 v[6:7], v[24:25], v[6:7], v[18:19] op_sel_hi:[0,1,1]
	v_pk_fma_f32 v[4:5], v[24:25], v[4:5], v[34:35] op_sel_hi:[0,1,1]
	v_pk_fma_f32 v[16:17], v[24:25], v[2:3], v[20:21] op_sel_hi:[0,1,1]
	v_pk_fma_f32 v[18:19], v[24:25], v[0:1], v[36:37] op_sel_hi:[0,1,1]
	v_cvt_pk_bf16_f32 v0, v26, v27
	v_cvt_pk_bf16_f32 v1, v14, v15
	v_cvt_pk_bf16_f32 v2, v8, v9
	v_cvt_pk_bf16_f32 v3, v10, v11
	v_cvt_pk_bf16_f32 v4, v4, v5
	v_cvt_pk_bf16_f32 v5, v6, v7
	v_cvt_pk_bf16_f32 v6, v18, v19
	v_cvt_pk_bf16_f32 v7, v16, v17
	ds_write_b128 v173, v[0:3] offset:16384
	ds_write_b128 v173, v[4:7] offset:24576
	s_nop 0
	v_lshlrev_b32_e32 v1, 4, v13
	v_ashrrev_i32_e32 v0, 3, v13
	v_and_b32_e32 v2, 0xc0, v1
	v_and_b32_e32 v0, -8, v0
	v_or_b32_e32 v2, s70, v2
	v_and_or_b32 v22, v13, 3, s86
	v_ashrrev_i32_e32 v1, 31, v0
	v_lshlrev_b32_e32 v146, 1, v2
	v_lshl_add_u64 v[0:1], v[22:23], 0, v[0:1]
	v_lshl_add_u64 v[2:3], s[58:59], 0, v[146:147]
	v_and_b32_e32 v146, 48, v13
	v_lshlrev_b64 v[0:1], 10, v[0:1]
	v_lshl_add_u64 v[2:3], v[2:3], 0, v[146:147]
	v_lshl_add_u64 v[0:1], v[2:3], 0, v[0:1]
	global_load_dwordx4 v[32:35], v[0:1], off
	global_load_dwordx4 v[36:39], v[0:1], off offset:64
	v_add_co_u32_e32 v0, vcc, s75, v0
	s_nop 1
	v_addc_co_u32_e32 v1, vcc, 0, v1, vcc
	global_load_dwordx4 v[40:43], v[0:1], off
	global_load_dwordx4 v[44:47], v[0:1], off offset:64
	v_cmp_le_u32_e32 vcc, s72, v25
	v_ashrrev_i32_e32 v8, 3, v12
	v_lshlrev_b32_e32 v1, 3, v12
	v_lshl_add_u32 v0, v25, 6, v8
	v_and_b32_e32 v4, 56, v1
	v_ashrrev_i32_e32 v1, 31, v0
	v_lshlrev_b64 v[2:3], 7, v[0:1]
	v_lshl_add_u64 v[0:1], s[8:9], 0, v[2:3]
	v_lshlrev_b32_e32 v146, 1, v4
	v_lshl_add_u64 v[0:1], v[0:1], 0, v[146:147]
	global_load_dwordx4 v[48:51], v[0:1], off
	v_lshl_add_u64 v[0:1], s[10:11], 0, v[2:3]
	v_lshl_add_u64 v[0:1], v[0:1], 0, v[146:147]
	global_load_dwordx4 v[52:55], v[0:1], off
	v_readfirstlane_b32 s20, v12
	s_cbranch_vccnz .LBB0_1191
; template <int DQK> __device__ __forceinline__ void stage_load(Stage<DQK>& s, const bf16* K0, int p0, const bf16* K1, int p1, const bf16* V, int pv, int tile, bool withV, int tid) {
;     { const int key = tid >> 3, c = tid & 7; s.k0 = *(const v4u*)(K0 + (size_t)(64 * tile + key) * p0 + 8 * c); }
;     if (DQK == 96) { if (tid < 256) { const int key = tid >> 2, c = tid & 3; s.k1 = *(const v4u*)(K1 + (size_t)(64 * tile + key) * p1 + 8 * c); } }
;     if (withV) { const int key = tid >> 3, c = tid & 7; s.v = *(const v4u*)(V + (size_t)(64 * tile + key) * pv + 8 * c); }
; }
; template <int DQK, int MODE> __device__ __forceinline__ void attn_pass(LAS unsigned char* lds, const bf16* K0, int p0, const bf16* K1, int p1, const bf16* V, int pv, int tlo, int thi, ...
;     ...
;         stage_load<DQK>(st, K0, p0, K1, p1, V, pv, tlo, true, tid);
;         if (tlo < thi) stage_load<DQK>(st1, K0, p0, K1, p1, V, pv, tlo + 1, true, tid);
	v_lshl_add_u64 v[0:1], v[2:3], 0, s[38:39]
	v_lshl_add_u64 v[2:3], s[10:11], 0, v[0:1]
	v_lshl_add_u64 v[0:1], s[8:9], 0, v[0:1]
	v_lshl_add_u64 v[2:3], v[2:3], 0, v[146:147]
	v_lshl_add_u64 v[0:1], v[0:1], 0, v[146:147]
	global_load_dwordx4 v[4:7], v[0:1], off
	s_nop 0
	global_load_dwordx4 v[0:3], v[2:3], off

; #define LAS __attribute__((address_space(3)))
; template <int DQK> __device__ __forceinline__ void stage_load(Stage<DQK>& s, const bf16* K0, int p0, const bf16* K1, int p1, const bf16* V, int pv, int tile, bool withV, int tid) {
;     { const int key = tid >> 3, c = tid & 7; s.k0 = *(const v4u*)(K0 + (size_t)(64 * tile + key) * p0 + 8 * c); }
;     if (DQK == 96) { if (tid < 256) { const int key = tid >> 2, c = tid & 3; s.k1 = *(const v4u*)(K1 + (size_t)(64 * tile + key) * p1 + 8 * c); } }
;     if (withV) { const int key = tid >> 3, c = tid & 7; s.v = *(const v4u*)(V + (size_t)(64 * tile + key) * pv + 8 * c); }
; }
; template <int DQK, int MODE> __device__ __forceinline__ void attn_pass(LAS unsigned char* lds, const bf16* K0, int p0, const bf16* K1, int p1, const bf16* V, int pv, int tlo, int thi, ...
;     ...
;     for (int t = tlo; t <= thi; ++t) {
;         LAS unsigned char* buf = lds + slot * KL<DQK>::SLOT;
;         const int slot2 = (slot == 0) ? 2 : slot - 1;
;         if (t + 2 <= thi) stage_load<DQK>(st, K0, p0, K1, p1, V, pv, t + 2, true, tid);
.LBB0_1197:
	s_add_i32 s6, s21, 3
	s_cmp_le_u32 s6, s72
	s_cselect_b64 s[14:15], -1, 0
	s_cmp_gt_u32 s6, s72
	s_cbranch_scc1 .LBB0_1199
	s_waitcnt vmcnt(0) lgkmcnt(0)
	global_load_dwordx4 v[48:51], v[106:107], off
	global_load_dwordx4 v[52:55], v[108:109], off

; __global__ void __launch_bounds__(NTHREADS, 2) mega_fwd(Args a_unused) {
;     ...
;     PH_BEGIN
;     ...
;     { int Kq = D; asm volatile("" : "+s"(Kq)); pg8::Gemm g{U, Wout, M, D, Kq}; pg8::StaticOrder S; S.init(M, D, G, bx); pg8::EpiResidLn<true> E{XOUT, XOUT, mod + 5 * D, 1.0f, ap->in[4] + 1 * D, ap->in[5] + 1 * D, mod + 6 * D, mod + 7 * D, U2, {(unsigned*)(ws + WS_XCH), (unsigned*)(ws + WS_CTL) + (16384 * 1 + 16384) / 4, (unsigned*)(ws + WS_CTL) + 15360 / 4, 4, LN_EPS, 0x740u}};
;       pg8::gemm_phase<pg8::EpiResidLn<true>, pg8::StaticOrder, false, true>(lds, g, S, E); }
.LBB0_1274:
	s_or_b64 exec, exec, s[6:7]
	s_mov_b64 s[6:7], s[0:1]
	s_waitcnt lgkmcnt(0)
	s_barrier
	v_mov_b32_e32 v177, v144
	v_mov_b64_e32 v[4:5], s[6:7]
	global_load_dwordx2 v[0:1], v[4:5], off offset:200
	s_movk_i32 s6, 0x400
	s_and_b64 vcc, exec, s[4:5]
	s_waitcnt vmcnt(0) lgkmcnt(0)
	v_readfirstlane_b32 s13, v1
	v_readfirstlane_b32 s12, v0
	global_load_dwordx2 v[138:139], v[4:5], off offset:192
	global_load_dwordx4 v[0:3], v[4:5], off offset:32
	s_nop 0
	v_readfirstlane_b32 s3, v177
	s_cbranch_vccnz .LBB0_1340
	s_ashr_i32 s20, s2, 31
	s_lshr_b32 s7, s20, 29
	s_add_i32 s7, s2, s7
	s_and_b32 s8, s7, -8
	s_sub_i32 s11, s2, s8
	s_cmp_gt_i32 s11, -1
	s_cbranch_scc0 .LBB0_1277
	s_lshl_b32 s10, s11, 5
	s_cbranch_execz .LBB0_1278
	s_branch .LBB0_1279

;     __device__ __forceinline__ void fused(f32x4 (&acc)[2][2][4][2], const Unit& u, int wr, int wc, int fr, int fq, PG8_LAS unsigned char* lds, int wid, int lane) const {
;     ...
;         const int col0 = u.pn * BM + wc * 32 + 4 * fq; const int b = (u.pm * BM) >> 13; const size_t mo = (size_t)b * 9216;
; #pragma unroll
;         for (int bj = 0; bj < 2; ++bj)
; #pragma unroll
;             for (int n = 0; n < 2; ++n) { const f32x4 gv = (*(const f32x4*)(gate + mo + col0 + bj * HALF + n * 16) + 1.0f) * coef;
; #pragma unroll
;                 for (int ai = 0; ai < 2; ++ai)
; #pragma unroll
;                     for (int m = 0; m < 4; ++m) acc[ai][bj][m][n] = acc[ai][bj][m][n] * gv; }
; #pragma unroll
;         for (int ai = 0; ai < 2; ++ai)
; #pragma unroll
;             for (int m = 0; m < 4; ++m) { const size_t off = (size_t)(u.pm * BM + ai * HALF + wr * 64 + m * 16 + fr) * 1024 + col0;
; #pragma unroll
;                 for (int bj = 0; bj < 2; ++bj)
; #pragma unroll
;                     for (int n = 0; n < 2; ++n) { const f32x4 xv = *(const f32x4*)(xin + off + bj * HALF + n * 16); acc[ai][bj][m][n] = xv * ALPHA_ + acc[ai][bj][m][n]; }
;                 asm volatile("" : "+v"(acc[ai][0][m][0]), "+v"(acc[ai][0][m][1]), "+v"(acc[ai][1][m][0]), "+v"(acc[ai][1][m][1]));
;                 if (m & 1) asm volatile("" ::: "memory"); }
.LBB0_1300:
	s_lshl_b32 s6, s21, 5
	s_lshl_b32 s7, s14, 8
	s_or_b32 s6, s7, s6
	v_lshrrev_b32_e32 v4, 2, v177
	v_and_or_b32 v140, v4, 12, s6
	s_ashr_i32 s6, s46, 5
	s_mul_hi_i32 s7, s6, 0x2400
	s_mulk_i32 s6, 0x2400
	s_lshl_b64 s[16:17], s[6:7], 2
	v_ashrrev_i32_e32 v141, 31, v140
	s_add_u32 s6, s12, s16
	s_addc_u32 s7, s13, s17
	v_lshlrev_b64 v[136:137], 2, v[140:141]
	v_lshl_add_u64 v[4:5], s[6:7], 0, v[136:137]
	s_mov_b64 s[6:7], 0x5000
	v_lshl_add_u64 v[142:143], v[4:5], 0, s[6:7]
	s_movk_i32 s6, 0x5000
	s_lshl_b32 s20, s46, 8
	v_add_co_u32_e32 v146, vcc, s6, v4
	s_add_i32 s6, s20, s57
	v_or_b32_e32 v158, s6, v178
	v_ashrrev_i32_e32 v159, 31, v158
	s_barrier
	v_addc_co_u32_e32 v147, vcc, 0, v5, vcc
	global_load_dwordx4 v[4:7], v[142:143], off offset:64
	global_load_dwordx4 v[148:151], v[142:143], off offset:512
	global_load_dwordx4 v[152:155], v[146:147], off
	global_load_dwordx4 v[180:183], v[142:143], off offset:576
	v_lshlrev_b64 v[142:143], 12, v[158:159]
	s_waitcnt vmcnt(0) lgkmcnt(0)
	v_lshl_add_u64 v[142:143], v[138:139], 0, v[142:143]
	v_lshl_add_u64 v[142:143], v[142:143], 0, v[136:137]
	global_load_dwordx4 v[184:187], v[142:143], off
	global_load_dwordx4 v[188:191], v[142:143], off offset:64
	global_load_dwordx4 v[192:195], v[142:143], off offset:512
	global_load_dwordx4 v[196:199], v[142:143], off offset:576
	v_or_b32_e32 v146, 16, v158
	v_ashrrev_i32_e32 v147, 31, v146
	s_mov_b32 s6, 0x3f9837f0
	v_lshlrev_b64 v[146:147], 12, v[146:147]
	v_lshl_add_u64 v[146:147], v[138:139], 0, v[146:147]
	v_lshl_add_u64 v[146:147], v[146:147], 0, v[136:137]
	v_pk_add_f32 v[164:165], v[6:7], 1.0 op_sel_hi:[1,0]
	v_pk_add_f32 v[166:167], v[4:5], 1.0 op_sel_hi:[1,0]
	v_pk_add_f32 v[160:161], v[154:155], 1.0 op_sel_hi:[1,0]
	v_pk_add_f32 v[162:163], v[152:153], 1.0 op_sel_hi:[1,0]
	v_pk_add_f32 v[168:169], v[150:151], 1.0 op_sel_hi:[1,0]
	v_pk_add_f32 v[170:171], v[148:149], 1.0 op_sel_hi:[1,0]
	v_pk_add_f32 v[172:173], v[182:183], 1.0 op_sel_hi:[1,0]
	v_pk_add_f32 v[174:175], v[180:181], 1.0 op_sel_hi:[1,0]
	s_waitcnt vmcnt(0) lgkmcnt(0)
	v_pk_mul_f32 v[4:5], v[186:187], s[6:7] op_sel_hi:[1,0]
	v_pk_mul_f32 v[6:7], v[184:185], s[6:7] op_sel_hi:[1,0]
	v_pk_mul_f32 v[148:149], v[190:191], s[6:7] op_sel_hi:[1,0]
	v_pk_mul_f32 v[150:151], v[188:189], s[6:7] op_sel_hi:[1,0]
	v_pk_mul_f32 v[152:153], v[194:195], s[6:7] op_sel_hi:[1,0]
	v_pk_mul_f32 v[154:155], v[192:193], s[6:7] op_sel_hi:[1,0]
	v_pk_mul_f32 v[156:157], v[198:199], s[6:7] op_sel_hi:[1,0]
	v_pk_mul_f32 v[180:181], v[196:197], s[6:7] op_sel_hi:[1,0]
	v_pk_fma_f32 v[94:95], v[94:95], v[160:161], v[4:5]
	v_pk_fma_f32 v[92:93], v[92:93], v[162:163], v[6:7]
	v_pk_fma_f32 v[66:67], v[66:67], v[164:165], v[148:149]
	v_pk_fma_f32 v[64:65], v[64:65], v[166:167], v[150:151]
	v_pk_fma_f32 v[34:35], v[34:35], v[168:169], v[152:153]
	v_pk_fma_f32 v[32:33], v[32:33], v[170:171], v[154:155]
	v_pk_fma_f32 v[6:7], v[134:135], v[172:173], v[156:157]
	v_pk_fma_f32 v[4:5], v[132:133], v[174:175], v[180:181]
	v_or_b32_e32 v148, 32, v158
	global_load_dwordx4 v[132:135], v[146:147], off
	global_load_dwordx4 v[150:153], v[146:147], off offset:64
	global_load_dwordx4 v[154:157], v[146:147], off offset:512
	global_load_dwordx4 v[180:183], v[146:147], off offset:576
	v_ashrrev_i32_e32 v149, 31, v148
	v_lshlrev_b64 v[148:149], 12, v[148:149]
	v_lshl_add_u64 v[148:149], v[138:139], 0, v[148:149]
	v_lshl_add_u64 v[148:149], v[148:149], 0, v[136:137]
	v_mov_b32_e32 v196, v65
	v_mov_b32_e32 v197, v66
	v_mov_b32_e32 v198, v64
	v_mov_b32_e32 v199, v67
	v_add_f32_e32 v201, v32, v33
	v_add_f32_e32 v203, v34, v35
	v_mov_b32_e32 v200, v4
	v_mov_b32_e32 v202, v5
	v_mov_b32_e32 v204, v7
	s_waitcnt vmcnt(0) lgkmcnt(0)
	v_pk_mul_f32 v[134:135], v[134:135], s[6:7] op_sel_hi:[1,0]
	v_pk_mul_f32 v[132:133], v[132:133], s[6:7] op_sel_hi:[1,0]
	v_pk_mul_f32 v[152:153], v[152:153], s[6:7] op_sel_hi:[1,0]
	v_pk_mul_f32 v[150:151], v[150:151], s[6:7] op_sel_hi:[1,0]
	v_pk_mul_f32 v[156:157], v[156:157], s[6:7] op_sel_hi:[1,0]
	v_pk_mul_f32 v[154:155], v[154:155], s[6:7] op_sel_hi:[1,0]
	v_pk_mul_f32 v[182:183], v[182:183], s[6:7] op_sel_hi:[1,0]
	v_pk_mul_f32 v[180:181], v[180:181], s[6:7] op_sel_hi:[1,0]
	v_pk_fma_f32 v[102:103], v[102:103], v[160:161], v[134:135]
	v_pk_fma_f32 v[100:101], v[100:101], v[162:163], v[132:133]
	v_pk_fma_f32 v[70:71], v[70:71], v[164:165], v[152:153]
	v_pk_fma_f32 v[68:69], v[68:69], v[166:167], v[150:151]
	v_pk_fma_f32 v[38:39], v[38:39], v[168:169], v[156:157]
	v_pk_fma_f32 v[36:37], v[36:37], v[170:171], v[154:155]
	v_pk_fma_f32 v[10:11], v[10:11], v[172:173], v[182:183]
	v_pk_fma_f32 v[8:9], v[8:9], v[174:175], v[180:181]
	v_or_b32_e32 v150, 48, v158
	global_load_dwordx4 v[132:135], v[148:149], off
	global_load_dwordx4 v[152:155], v[148:149], off offset:64
	global_load_dwordx4 v[180:183], v[148:149], off offset:512
	global_load_dwordx4 v[184:187], v[148:149], off offset:576
	v_ashrrev_i32_e32 v151, 31, v150
	v_lshlrev_b64 v[150:151], 12, v[150:151]
	v_lshl_add_u64 v[150:151], v[138:139], 0, v[150:151]
	v_lshl_add_u64 v[150:151], v[150:151], 0, v[136:137]
	s_waitcnt vmcnt(0) lgkmcnt(0)
;     __device__ __forceinline__ void fused(f32x4 (&acc)[2][2][4][2], const Unit& u, int wr, int wc, int fr, int fq, PG8_LAS unsigned char* lds, int wid, int lane) const {
;     ...
;         for (int ai = 0; ai < 2; ++ai)
; #pragma unroll
;             for (int m = 0; m < 4; ++m) { const size_t off = (size_t)(u.pm * BM + ai * HALF + wr * 64 + m * 16 + fr) * 1024 + col0;
; #pragma unroll
;                 for (int bj = 0; bj < 2; ++bj)
; #pragma unroll
;                     for (int n = 0; n < 2; ++n) { const f32x4 xv = *(const f32x4*)(xin + off + bj * HALF + n * 16); acc[ai][bj][m][n] = xv * ALPHA_ + acc[ai][bj][m][n]; }
;                 asm volatile("" : "+v"(acc[ai][0][m][0]), "+v"(acc[ai][0][m][1]), "+v"(acc[ai][1][m][0]), "+v"(acc[ai][1][m][1]));
;                 if (m & 1) asm volatile("" ::: "memory"); }
	v_pk_mul_f32 v[134:135], v[134:135], s[6:7] op_sel_hi:[1,0]
	v_pk_mul_f32 v[132:133], v[132:133], s[6:7] op_sel_hi:[1,0]
	v_pk_mul_f32 v[154:155], v[154:155], s[6:7] op_sel_hi:[1,0]
	v_pk_mul_f32 v[152:153], v[152:153], s[6:7] op_sel_hi:[1,0]
	v_pk_mul_f32 v[156:157], v[182:183], s[6:7] op_sel_hi:[1,0]
	v_pk_mul_f32 v[180:181], v[180:181], s[6:7] op_sel_hi:[1,0]
	v_pk_mul_f32 v[182:183], v[186:187], s[6:7] op_sel_hi:[1,0]
	v_pk_mul_f32 v[184:185], v[184:185], s[6:7] op_sel_hi:[1,0]
	v_pk_fma_f32 v[106:107], v[106:107], v[160:161], v[134:135]
	v_pk_fma_f32 v[104:105], v[104:105], v[162:163], v[132:133]
	v_pk_fma_f32 v[74:75], v[74:75], v[164:165], v[154:155]
	v_pk_fma_f32 v[72:73], v[72:73], v[166:167], v[152:153]
	v_pk_fma_f32 v[42:43], v[42:43], v[168:169], v[156:157]
	v_pk_fma_f32 v[40:41], v[40:41], v[170:171], v[180:181]
	v_pk_fma_f32 v[14:15], v[14:15], v[172:173], v[182:183]
	v_pk_fma_f32 v[12:13], v[12:13], v[174:175], v[184:185]
	v_add_u32_e32 v152, 0x80, v158
	global_load_dwordx4 v[132:135], v[150:151], off
	global_load_dwordx4 v[154:157], v[150:151], off offset:64
	global_load_dwordx4 v[180:183], v[150:151], off offset:512
	global_load_dwordx4 v[184:187], v[150:151], off offset:576
	v_ashrrev_i32_e32 v153, 31, v152
	v_lshlrev_b64 v[152:153], 12, v[152:153]
	v_lshl_add_u64 v[152:153], v[138:139], 0, v[152:153]
	v_lshl_add_u64 v[152:153], v[152:153], 0, v[136:137]
	s_waitcnt vmcnt(0) lgkmcnt(0)
	v_pk_mul_f32 v[134:135], v[134:135], s[6:7] op_sel_hi:[1,0]
	v_pk_mul_f32 v[132:133], v[132:133], s[6:7] op_sel_hi:[1,0]
	v_pk_mul_f32 v[156:157], v[156:157], s[6:7] op_sel_hi:[1,0]
	v_pk_mul_f32 v[154:155], v[154:155], s[6:7] op_sel_hi:[1,0]
	v_pk_mul_f32 v[182:183], v[182:183], s[6:7] op_sel_hi:[1,0]
	v_pk_mul_f32 v[180:181], v[180:181], s[6:7] op_sel_hi:[1,0]
	v_pk_mul_f32 v[186:187], v[186:187], s[6:7] op_sel_hi:[1,0]
	v_pk_mul_f32 v[184:185], v[184:185], s[6:7] op_sel_hi:[1,0]
	v_pk_fma_f32 v[114:115], v[114:115], v[160:161], v[134:135]
	v_pk_fma_f32 v[112:113], v[112:113], v[162:163], v[132:133]
	v_pk_fma_f32 v[82:83], v[82:83], v[164:165], v[156:157]
	v_pk_fma_f32 v[80:81], v[80:81], v[166:167], v[154:155]
	v_pk_fma_f32 v[50:51], v[50:51], v[168:169], v[182:183]
	v_pk_fma_f32 v[48:49], v[48:49], v[170:171], v[180:181]
	v_pk_fma_f32 v[18:19], v[18:19], v[172:173], v[186:187]
	v_pk_fma_f32 v[16:17], v[16:17], v[174:175], v[184:185]
	v_add_u32_e32 v154, 0x90, v158
	global_load_dwordx4 v[132:135], v[152:153], off
	global_load_dwordx4 v[180:183], v[152:153], off offset:64
	global_load_dwordx4 v[184:187], v[152:153], off offset:512
	global_load_dwordx4 v[188:191], v[152:153], off offset:576
	v_ashrrev_i32_e32 v155, 31, v154
	v_lshlrev_b64 v[154:155], 12, v[154:155]
	v_lshl_add_u64 v[154:155], v[138:139], 0, v[154:155]
	v_lshl_add_u64 v[154:155], v[154:155], 0, v[136:137]
	s_waitcnt vmcnt(0) lgkmcnt(0)
	v_pk_mul_f32 v[134:135], v[134:135], s[6:7] op_sel_hi:[1,0]
	v_pk_mul_f32 v[132:133], v[132:133], s[6:7] op_sel_hi:[1,0]
	v_pk_mul_f32 v[156:157], v[182:183], s[6:7] op_sel_hi:[1,0]
	v_pk_mul_f32 v[180:181], v[180:181], s[6:7] op_sel_hi:[1,0]
	v_pk_mul_f32 v[182:183], v[186:187], s[6:7] op_sel_hi:[1,0]
	v_pk_mul_f32 v[184:185], v[184:185], s[6:7] op_sel_hi:[1,0]
	v_pk_mul_f32 v[186:187], v[190:191], s[6:7] op_sel_hi:[1,0]
	v_pk_mul_f32 v[188:189], v[188:189], s[6:7] op_sel_hi:[1,0]
	v_pk_fma_f32 v[118:119], v[118:119], v[160:161], v[134:135]
	v_pk_fma_f32 v[116:117], v[116:117], v[162:163], v[132:133]
	v_pk_fma_f32 v[86:87], v[86:87], v[164:165], v[156:157]
	v_pk_fma_f32 v[84:85], v[84:85], v[166:167], v[180:181]
	v_pk_fma_f32 v[54:55], v[54:55], v[168:169], v[182:183]
	v_pk_fma_f32 v[52:53], v[52:53], v[170:171], v[184:185]
	v_pk_fma_f32 v[22:23], v[22:23], v[172:173], v[186:187]
	v_pk_fma_f32 v[20:21], v[20:21], v[174:175], v[188:189]
	v_add_u32_e32 v156, 0xa0, v158
	global_load_dwordx4 v[132:135], v[154:155], off
	global_load_dwordx4 v[180:183], v[154:155], off offset:64
	global_load_dwordx4 v[184:187], v[154:155], off offset:512
	global_load_dwordx4 v[188:191], v[154:155], off offset:576
	v_ashrrev_i32_e32 v157, 31, v156
	v_lshlrev_b64 v[156:157], 12, v[156:157]
	v_lshl_add_u64 v[156:157], v[138:139], 0, v[156:157]
	v_lshl_add_u64 v[156:157], v[156:157], 0, v[136:137]
	s_waitcnt vmcnt(0) lgkmcnt(0)
;     __device__ __forceinline__ bool run(const f32x4 (&v)[2][2][4][2], const Unit& u, int wr, int wc, int fr, int fq, PG8_LAS unsigned char* lds, int wid, int lane) const {
;     ...
;                 float s = 0.f;
; #pragma unroll
;                 for (int bj = 0; bj < 2; ++bj)
; #pragma unroll
;                     for (int n = 0; n < 2; ++n) { const f32x4 x = v[ai][bj][m][n]; s += (x[0] + x[1]) + (x[2] + x[3]); }
;                 s += __shfl_xor(s, 16); s += __shfl_xor(s, 32);
;                 const float mw = s * (1.0f / 64.0f); float q = 0.f;
; #pragma unroll
;                 for (int bj = 0; bj < 2; ++bj)
; #pragma unroll
;                     for (int n = 0; n < 2; ++n) { const f32x4 d = v[ai][bj][m][n] - mw; q += (d[0] * d[0] + d[1] * d[1]) + (d[2] * d[2] + d[3] * d[3]); }
;                 q += __shfl_xor(q, 16); q += __shfl_xor(q, 32);
;                 if (fq == 0) P[(ai * HALF + wr * 64 + m * 16 + fr) * 4 + wc] = (f32x2v){mw, q};
;     __device__ __forceinline__ void fused(f32x4 (&acc)[2][2][4][2], const Unit& u, int wr, int wc, int fr, int fq, PG8_LAS unsigned char* lds, int wid, int lane) const {
;     ...
;         for (int ai = 0; ai < 2; ++ai)
; #pragma unroll
;             for (int m = 0; m < 4; ++m) { const size_t off = (size_t)(u.pm * BM + ai * HALF + wr * 64 + m * 16 + fr) * 1024 + col0;
; #pragma unroll
;                 for (int bj = 0; bj < 2; ++bj)
; #pragma unroll
;                     for (int n = 0; n < 2; ++n) { const f32x4 xv = *(const f32x4*)(xin + off + bj * HALF + n * 16); acc[ai][bj][m][n] = xv * ALPHA_ + acc[ai][bj][m][n]; }
;                 asm volatile("" : "+v"(acc[ai][0][m][0]), "+v"(acc[ai][0][m][1]), "+v"(acc[ai][1][m][0]), "+v"(acc[ai][1][m][1]));
;                 if (m & 1) asm volatile("" ::: "memory"); }
	v_pk_mul_f32 v[134:135], v[134:135], s[6:7] op_sel_hi:[1,0]
	v_pk_mul_f32 v[132:133], v[132:133], s[6:7] op_sel_hi:[1,0]
	v_pk_mul_f32 v[182:183], v[182:183], s[6:7] op_sel_hi:[1,0]
	v_pk_mul_f32 v[180:181], v[180:181], s[6:7] op_sel_hi:[1,0]
	v_pk_mul_f32 v[186:187], v[186:187], s[6:7] op_sel_hi:[1,0]
	v_pk_mul_f32 v[184:185], v[184:185], s[6:7] op_sel_hi:[1,0]
	v_pk_mul_f32 v[190:191], v[190:191], s[6:7] op_sel_hi:[1,0]
	v_pk_mul_f32 v[188:189], v[188:189], s[6:7] op_sel_hi:[1,0]
	v_pk_fma_f32 v[122:123], v[122:123], v[160:161], v[134:135]
	v_pk_fma_f32 v[120:121], v[120:121], v[162:163], v[132:133]
	v_pk_fma_f32 v[90:91], v[90:91], v[164:165], v[182:183]
	v_pk_fma_f32 v[88:89], v[88:89], v[166:167], v[180:181]
	v_pk_fma_f32 v[58:59], v[58:59], v[168:169], v[186:187]
	v_pk_fma_f32 v[56:57], v[56:57], v[170:171], v[184:185]
	v_pk_fma_f32 v[26:27], v[26:27], v[172:173], v[190:191]
	v_pk_fma_f32 v[24:25], v[24:25], v[174:175], v[188:189]
	v_mbcnt_hi_u32_b32 v133, -1, v145
	global_load_dwordx4 v[180:183], v[156:157], off
	global_load_dwordx4 v[184:187], v[156:157], off offset:64
	global_load_dwordx4 v[188:191], v[156:157], off offset:512
	global_load_dwordx4 v[192:195], v[156:157], off offset:576
	v_and_b32_e32 v134, 64, v133
	v_add_u32_e32 v179, 64, v134
	v_add_u32_e32 v134, 0xb0, v158
	v_ashrrev_i32_e32 v135, 31, v134
	v_lshlrev_b64 v[134:135], 12, v[134:135]
	v_lshl_add_u64 v[134:135], v[138:139], 0, v[134:135]
	v_lshl_add_u64 v[158:159], v[134:135], 0, v[136:137]
	v_mov_b32_e32 v134, v93
	v_mov_b32_e32 v135, v94
	v_mov_b32_e32 v138, v92
	v_mov_b32_e32 v139, v95
	v_pk_add_f32 v[134:135], v[134:135], v[138:139]
	v_pk_add_f32 v[138:139], v[196:197], v[198:199]
	v_add_f32_e32 v198, v134, v135
	v_pk_add_f32 v[134:135], v[138:139], v[138:139] op_sel_hi:[0,1]
	v_xor_b32_e32 v132, 16, v133
	v_add_f32_e32 v205, 0, v198
	v_mov_b32_e32 v134, v6
	v_cmp_lt_i32_e32 vcc, v132, v179
	v_pk_add_f32 v[196:197], v[200:201], v[202:203]
	v_pk_add_f32 v[134:135], v[134:135], v[204:205]
	v_cndmask_b32_e32 v132, v133, v132, vcc
	v_pk_add_f32 v[134:135], v[196:197], v[134:135]
	v_lshlrev_b32_e32 v132, 2, v132
	v_add_f32_e32 v134, v134, v135
	ds_bpermute_b32 v135, v132, v134
	v_xor_b32_e32 v138, 32, v133
	v_cmp_lt_i32_e32 vcc, v138, v179
	s_waitcnt lgkmcnt(0)
	v_add_f32_e32 v134, v134, v135
	v_cndmask_b32_e32 v133, v133, v138, vcc
	v_lshlrev_b32_e32 v133, 2, v133
	ds_bpermute_b32 v135, v133, v134
	s_waitcnt lgkmcnt(0)
	v_add_f32_e32 v135, v134, v135
	v_fmamk_f32 v138, v135, 0xbc800000, v95
	v_fmamk_f32 v179, v135, 0xbc800000, v93
	v_fmamk_f32 v197, v135, 0xbc800000, v67
	v_fmamk_f32 v199, v135, 0xbc800000, v65
	v_fmamk_f32 v134, v135, 0xbc800000, v94
	v_fmamk_f32 v139, v135, 0xbc800000, v92
	v_fmamk_f32 v196, v135, 0xbc800000, v66
	v_fmamk_f32 v198, v135, 0xbc800000, v64
	v_fmamk_f32 v201, v135, 0xbc800000, v35
	v_fmamk_f32 v203, v135, 0xbc800000, v33
	v_mul_f32_e32 v179, v179, v179
	v_mul_f32_e32 v138, v138, v138
	v_mul_f32_e32 v199, v199, v199
	v_mul_f32_e32 v197, v197, v197
	v_fmamk_f32 v200, v135, 0xbc800000, v34
	v_fmamk_f32 v202, v135, 0xbc800000, v32
	v_fmamk_f32 v205, v135, 0xbc800000, v7
	v_fmamk_f32 v207, v135, 0xbc800000, v5
	v_mul_f32_e32 v203, v203, v203
	v_mul_f32_e32 v201, v201, v201
	v_fmac_f32_e32 v179, v139, v139
	v_fmac_f32_e32 v138, v134, v134
	v_fmac_f32_e32 v199, v198, v198
	v_fmac_f32_e32 v197, v196, v196
	v_fmamk_f32 v204, v135, 0xbc800000, v6
	v_fmamk_f32 v206, v135, 0xbc800000, v4
	v_mul_f32_e32 v207, v207, v207
	v_mul_f32_e32 v205, v205, v205
	v_fmac_f32_e32 v203, v202, v202
	v_fmac_f32_e32 v201, v200, v200
	v_add_f32_e32 v134, v179, v138
	v_add_f32_e32 v138, v199, v197
	v_fmac_f32_e32 v207, v206, v206
	v_fmac_f32_e32 v205, v204, v204
	v_add_f32_e32 v139, v203, v201
	v_add_f32_e32 v134, v134, v138
	v_add_f32_e32 v179, v207, v205
	s_waitcnt vmcnt(0)
	v_pk_mul_f32 v[182:183], v[182:183], s[6:7] op_sel_hi:[1,0]
	v_pk_mul_f32 v[180:181], v[180:181], s[6:7] op_sel_hi:[1,0]
	v_pk_mul_f32 v[186:187], v[186:187], s[6:7] op_sel_hi:[1,0]
	v_pk_mul_f32 v[184:185], v[184:185], s[6:7] op_sel_hi:[1,0]
	v_pk_mul_f32 v[190:191], v[190:191], s[6:7] op_sel_hi:[1,0]
	v_pk_mul_f32 v[188:189], v[188:189], s[6:7] op_sel_hi:[1,0]
	v_pk_mul_f32 v[194:195], v[194:195], s[6:7] op_sel_hi:[1,0]
	v_pk_mul_f32 v[192:193], v[192:193], s[6:7] op_sel_hi:[1,0]
	v_pk_fma_f32 v[126:127], v[126:127], v[160:161], v[182:183]
	v_pk_fma_f32 v[124:125], v[124:125], v[162:163], v[180:181]
	v_pk_fma_f32 v[98:99], v[98:99], v[164:165], v[186:187]
	v_pk_fma_f32 v[96:97], v[96:97], v[166:167], v[184:185]
	v_pk_fma_f32 v[62:63], v[62:63], v[168:169], v[190:191]
	v_pk_fma_f32 v[60:61], v[60:61], v[170:171], v[188:189]
	v_pk_fma_f32 v[30:31], v[30:31], v[172:173], v[194:195]
	v_pk_fma_f32 v[28:29], v[28:29], v[174:175], v[192:193]
	v_add_f32_e32 v134, v139, v134
	global_load_dwordx4 v[180:183], v[158:159], off
	global_load_dwordx4 v[184:187], v[158:159], off offset:64
	global_load_dwordx4 v[188:191], v[158:159], off offset:512
	global_load_dwordx4 v[192:195], v[158:159], off offset:576
	v_add_f32_e32 v138, v179, v134
	ds_bpermute_b32 v139, v132, v138
	v_and_b32_e32 v134, 63, v177
	v_cmp_gt_u32_e32 vcc, 16, v134
	s_waitcnt lgkmcnt(0)
	v_add_f32_e32 v138, v138, v139
	ds_bpermute_b32 v139, v133, v138
	s_waitcnt vmcnt(0)
	v_pk_mul_f32 v[182:183], v[182:183], s[6:7] op_sel_hi:[1,0]
	v_pk_mul_f32 v[180:181], v[180:181], s[6:7] op_sel_hi:[1,0]
	v_pk_mul_f32 v[186:187], v[186:187], s[6:7] op_sel_hi:[1,0]
	v_pk_mul_f32 v[184:185], v[184:185], s[6:7] op_sel_hi:[1,0]
	v_pk_mul_f32 v[190:191], v[190:191], s[6:7] op_sel_hi:[1,0]
	v_pk_mul_f32 v[188:189], v[188:189], s[6:7] op_sel_hi:[1,0]
	v_pk_mul_f32 v[194:195], v[194:195], s[6:7] op_sel_hi:[1,0]
	v_pk_mul_f32 v[192:193], v[192:193], s[6:7] op_sel_hi:[1,0]
	v_pk_fma_f32 v[130:131], v[130:131], v[160:161], v[182:183]
	v_pk_fma_f32 v[128:129], v[128:129], v[162:163], v[180:181]
	v_pk_fma_f32 v[110:111], v[110:111], v[164:165], v[186:187]
	v_pk_fma_f32 v[108:109], v[108:109], v[166:167], v[184:185]
	v_pk_fma_f32 v[78:79], v[78:79], v[168:169], v[190:191]
	v_pk_fma_f32 v[76:77], v[76:77], v[170:171], v[188:189]
	v_pk_fma_f32 v[46:47], v[46:47], v[172:173], v[194:195]
	v_pk_fma_f32 v[44:45], v[44:45], v[174:175], v[192:193]
	s_lshl_b32 s6, s21, 3
	s_add_i32 s8, s6, 0
	s_and_saveexec_b64 s[6:7], vcc
	s_cbranch_execz .LBB0_1302
	s_lshl_b32 s9, s47, 11
	s_add_i32 s9, s8, s9
	v_mul_f32_e32 v160, 0x3c800000, v135
	v_lshl_add_u32 v135, v178, 5, s9
	s_waitcnt lgkmcnt(0)
	v_add_f32_e32 v161, v138, v139
	ds_write_b64 v135, v[160:161]

;     __device__ __forceinline__ bool run(const f32x4 (&v)[2][2][4][2], const Unit& u, int wr, int wc, int fr, int fq, PG8_LAS unsigned char* lds, int wid, int lane) const {
;     ...
;         asm volatile("s_waitcnt lgkmcnt(0)" ::: "memory"); __builtin_amdgcn_s_barrier(); asm volatile("" ::: "memory");
;     ...
;         if (blockIdx.x >= 64) { const long long t0_ = clock64(); while (clock64() - t0_ < 60000) __builtin_amdgcn_s_sleep(8); }
;     ...
;         const int row = wid * 32 + (lane & 31);
;         if (lane < 32) {
;             const f32x2v a = P[row * 4 + 0], b = P[row * 4 + 1], c = P[row * 4 + 2], d = P[row * 4 + 3];
;             const float mt = (a.x + b.x + c.x + d.x) * 0.25f;
;             const float da = a.x - mt, db = b.x - mt, dc = c.x - mt, dd = d.x - mt;
;             const float m2 = (a.y + b.y) + (c.y + d.y) + 64.0f * ((da * da + db * db) + (dc * dc + dd * dd));
;             unsigned long long* slot = (unsigned long long*)xbuf + ((size_t)(u.pm * BM + row) * 4 + u.pn);
;             __hip_atomic_store(slot, ((unsigned long long)__float_as_uint(m2) << 32) | __float_as_uint(mt), __ATOMIC_RELAXED, __HIP_MEMORY_SCOPE_AGENT);
;         }
;         asm volatile("s_waitcnt vmcnt(0)" ::: "memory");
;         if (lane == 0) __hip_atomic_fetch_add(cnt + 64 * u.pm, 1u, __ATOMIC_RELAXED, __HIP_MEMORY_SCOPE_AGENT);
.LBB0_1316:
	s_or_b64 exec, exec, s[6:7]
	v_and_b32_e32 v132, 31, v177
	s_waitcnt lgkmcnt(0)
	s_barrier
	v_lshl_or_b32 v160, s15, 5, v132
	s_add_u32 s18, s12, 0x3780000
	v_add_u32_e32 v132, s20, v160
	s_addc_u32 s19, s13, 0
	v_cmp_gt_u32_e64 s[6:7], 32, v134
	s_waitcnt lgkmcnt(0)
	v_ashrrev_i32_e32 v133, 31, v132
	s_and_saveexec_b64 s[8:9], s[6:7]
	s_cbranch_execz .LBB0_1318
	v_lshl_add_u32 v135, v160, 5, 0
	ds_read_b128 v[162:165], v135
	ds_read_b128 v[166:169], v135 offset:16
	s_ashr_i32 s15, s14, 31
	s_waitcnt lgkmcnt(1)
	v_add_f32_e32 v135, v162, v164
	s_waitcnt lgkmcnt(0)
	v_add_f32_e32 v135, v135, v166
	v_add_f32_e32 v135, v135, v168
	v_fmamk_f32 v139, v135, 0xbe800000, v162
	v_fmac_f32_e32 v164, 0xbe800000, v135
	v_fmamk_f32 v161, v135, 0xbe800000, v166
	v_fmac_f32_e32 v168, 0xbe800000, v135
	v_mul_f32_e32 v171, v139, v139
	v_mul_f32_e32 v173, v164, v164
	v_mul_f32_e32 v175, v161, v161
	v_mul_f32_e32 v179, v168, v168
	v_mov_b32_e32 v170, v163
	v_mov_b32_e32 v172, v165
	v_mov_b32_e32 v174, v167
	v_mov_b32_e32 v178, v169
	v_pk_add_f32 v[162:163], v[170:171], v[172:173]
	v_pk_add_f32 v[164:165], v[174:175], v[178:179]
	v_mul_f32_e32 v138, 0x3e800000, v135
	v_pk_add_f32 v[162:163], v[162:163], v[164:165]
	s_nop 0
	v_fmamk_f32 v139, v163, 0x42800000, v162
	v_lshlrev_b64 v[162:163], 5, v[132:133]
	v_lshl_add_u64 v[162:163], s[18:19], 0, v[162:163]
	v_lshl_add_u64 v[162:163], s[14:15], 3, v[162:163]
	global_store_dwordx2 v[162:163], v[138:139], off sc1
.LBB0_1318:
	s_or_b64 exec, exec, s[8:9]
	s_waitcnt vmcnt(0)
	s_add_u32 s21, s12, 0xd8000
	s_addc_u32 s30, s13, 0
	v_cmp_ne_u32_e64 s[10:11], 0, v134
	v_cmp_eq_u32_e64 s[8:9], 0, v134
	s_and_saveexec_b64 s[14:15], s[8:9]
	s_cbranch_execz .LBB0_1320
	s_lshl_b32 s34, s46, 6
	s_ashr_i32 s35, s34, 31
	s_lshl_b64 s[34:35], s[34:35], 2
	s_add_u32 s34, s21, s34
	s_addc_u32 s35, s30, s35
	v_mov_b32_e32 v138, 1
	v_mov_b64_e32 v[134:135], s[34:35]
	global_atomic_add v[134:135], v138, off

;     __device__ __forceinline__ bool run(const f32x4 (&v)[2][2][4][2], const Unit& u, int wr, int wc, int fr, int fq, PG8_LAS unsigned char* lds, int wid, int lane) const {
;     ...
;         if (wid == 0) {
;             bool dead = false; const unsigned long long t0 = __builtin_amdgcn_s_memrealtime(); const unsigned want = 8u * (unsigned)ntn;
;             for (;;) {
;     ...
;                 break;
;     ...
;                 if ((unsigned)__builtin_amdgcn_readfirstlane(__hip_atomic_load(cnt + 64 * u.pm, __ATOMIC_RELAXED, __HIP_MEMORY_SCOPE_AGENT)) >= want) break;
;                 if (__builtin_amdgcn_s_memrealtime() - t0 > 2000000ull) {
;                     if (lane == 0) { unsigned expect = 0u; __hip_atomic_compare_exchange_strong(tmo + 1, &expect, code | (unsigned)(u.pm & 0xff), __ATOMIC_RELAXED, __ATOMIC_RELAXED, __HIP_MEMORY_SCOPE_AGENT);
;                                      __hip_atomic_store(tmo, 1u, __ATOMIC_RELAXED, __HIP_MEMORY_SCOPE_AGENT); }
;                     dead = true; break; }
;                 __builtin_amdgcn_s_sleep(2);
;             }
.LBB0_1324:
	global_load_dword v161, v[134:135], off sc1
	s_mov_b64 s[30:31], -1
	s_mov_b64 s[34:35], -1
	s_waitcnt vmcnt(0) lgkmcnt(0)
	v_readfirstlane_b32 s3, v161
	s_cmp_gt_u32 s3, 31
	s_cbranch_scc1 .LBB0_1323
	s_memrealtime s[30:31]
	s_waitcnt lgkmcnt(0)
	s_sub_u32 s30, s30, s14
	s_subb_u32 s31, s31, s15
	v_cmp_lt_u64_e32 vcc, s[30:31], v[138:139]
	s_cbranch_vccz .LBB0_1322
	s_mov_b64 s[34:35], 0
	s_sleep 2
	s_branch .LBB0_1322

;     __device__ __forceinline__ bool run(const f32x4 (&v)[2][2][4][2], const Unit& u, int wr, int wc, int fr, int fq, PG8_LAS unsigned char* lds, int wid, int lane) const {
;     ...
;                 if (__builtin_amdgcn_s_memrealtime() - t0 > 2000000ull) {
;                     if (lane == 0) { unsigned expect = 0u; __hip_atomic_compare_exchange_strong(tmo + 1, &expect, code | (unsigned)(u.pm & 0xff), __ATOMIC_RELAXED, __ATOMIC_RELAXED, __HIP_MEMORY_SCOPE_AGENT);
;                                      __hip_atomic_store(tmo, 1u, __ATOMIC_RELAXED, __HIP_MEMORY_SCOPE_AGENT); }
;                     dead = true; break; }
.LBB0_1330:
	s_or_saveexec_b64 s[14:15], s[10:11]
	s_mov_b64 s[10:11], 0
	s_xor_b64 exec, exec, s[14:15]
	s_cbranch_execz .LBB0_1332
	s_and_b32 s3, s46, 0xbf
	v_mov_b32_e32 v134, s12
	s_or_b32 s3, s3, 0x740
	v_add_co_u32_e32 v134, vcc, 0xd3000, v134
	v_mov_b32_e32 v135, s13
	s_nop 0
	v_addc_co_u32_e32 v135, vcc, 0, v135, vcc
	v_mov_b32_e32 v138, s3
	v_mov_b32_e32 v139, 0
	global_atomic_cmpswap v[134:135], v[138:139], off offset:3076
	s_mov_b64 s[10:11], exec
	v_mov_b32_e32 v138, 1
	global_store_dword v[134:135], v138, off offset:3072 sc1

;     __device__ __forceinline__ bool run(const f32x4 (&v)[2][2][4][2], const Unit& u, int wr, int wc, int fr, int fq, PG8_LAS unsigned char* lds, int wid, int lane) const {
;     ...
;         asm volatile("s_waitcnt vmcnt(0) lgkmcnt(0)" ::: "memory"); __builtin_amdgcn_s_barrier(); asm volatile("" ::: "memory");
;         const bool bad = flag[0] != 0u;
;         if (lane < 32) {
;             const unsigned long long* slot = (const unsigned long long*)xbuf + (size_t)(u.pm * BM + row) * 4; float mt[4], m2[4]; float ms = 0.f;
; #pragma unroll
;             for (int t = 0; t < 4; ++t) { if (t < ntn) { const unsigned long long w = __hip_atomic_load(slot + t, __ATOMIC_RELAXED, __HIP_MEMORY_SCOPE_AGENT); mt[t] = __uint_as_float((unsigned)w); m2[t] = __uint_as_float((unsigned)(w >> 32)); } else { mt[t] = 0.f; m2[t] = 0.f; } ms += mt[t]; }
;             const float mean = ms / (float)ntn; float q = 0.f;
; #pragma unroll
;             for (int t = 0; t < 4; ++t) if (t < ntn) { const float dm = mt[t] - mean; q += m2[t] + 256.0f * dm * dm; }
;             S[row] = (f32x2v){mean, 1.0f / sqrtf(q / (256.0f * (float)ntn) + eps)};
;         }
;         asm volatile("s_waitcnt lgkmcnt(0)" ::: "memory"); __builtin_amdgcn_s_barrier(); asm volatile("" ::: "memory");
;     __device__ __forceinline__ void fused(f32x4 (&acc)[2][2][4][2], const Unit& u, int wr, int wc, int fr, int fq, PG8_LAS unsigned char* lds, int wid, int lane) const {
;     ...
;         const float qnan = __builtin_nanf("");
; #pragma unroll
;         for (int bj = 0; bj < 2; ++bj)
; #pragma unroll
;             for (int n = 0; n < 2; ++n) {
;                 const int col = col0 + bj * HALF + n * 16;
;                 const f32x4 lg = *(const f32x4*)(lng + col), lb = *(const f32x4*)(lnb + col);
;                 f32x4 sc1 = (f32x4){1.f, 1.f, 1.f, 1.f}, sh = (f32x4){0.f, 0.f, 0.f, 0.f};
;                 if (DO_U) { sc1 = *(const f32x4*)(msc + mo + col) + 1.0f; sh = *(const f32x4*)(msh + mo + col); }
; #pragma unroll
;                 for (int ai = 0; ai < 2; ++ai)
; #pragma unroll
;                     for (int m = 0; m < 4; ++m) { const int r = ai * HALF + wr * 64 + m * 16 + fr; const f32x2v sr = S[r]; const size_t off = (size_t)(u.pm * BM + r) * 1024 + col;
;                         f32x4 y = (acc[ai][bj][m][n] - sr.x) * sr.y * lg + lb; if (bad) y = (f32x4){qnan, qnan, qnan, qnan};
.LBB0_1337:
	s_waitcnt vmcnt(0) lgkmcnt(0)
	s_barrier
	v_mov_b32_e32 v134, 0
	ds_read_b32 v164, v134 offset:10240
	s_and_saveexec_b64 s[8:9], s[6:7]
	s_cbranch_execz .LBB0_1339
	v_lshlrev_b64 v[132:133], 5, v[132:133]
	v_lshl_add_u64 v[132:133], s[18:19], 0, v[132:133]
	global_load_dwordx2 v[134:135], v[132:133], off sc1
	global_load_dwordx2 v[138:139], v[132:133], off offset:8 sc1
	global_load_dwordx2 v[162:163], v[132:133], off offset:16 sc1
	s_nop 0
	global_load_dwordx2 v[132:133], v[132:133], off offset:24 sc1
	v_mov_b32_e32 v161, 0x3727c5ac
	s_mov_b32 s3, 0xf800000
	s_waitcnt vmcnt(0) lgkmcnt(0)
	v_add_f32_e32 v165, 0, v134
	v_add_f32_e32 v165, v165, v138
	v_add_f32_e32 v165, v165, v162
	v_add_f32_e32 v165, v165, v132
	v_fmamk_f32 v134, v165, 0xbe800000, v134
	v_fmamk_f32 v138, v165, 0xbe800000, v138
	v_fmamk_f32 v132, v165, 0xbe800000, v132
	v_mul_f32_e32 v166, 0x43800000, v134
	v_fmamk_f32 v162, v165, 0xbe800000, v162
	v_mul_f32_e32 v167, 0x43800000, v138
	v_mul_f32_e32 v169, 0x43800000, v132
	v_fmac_f32_e32 v135, v134, v166
	v_mul_f32_e32 v168, 0x43800000, v162
	v_fmac_f32_e32 v139, v138, v167
	v_fmac_f32_e32 v133, v132, v169
	v_add_f32_e32 v132, 0, v135
	v_fmac_f32_e32 v163, v162, v168
	v_add_f32_e32 v132, v139, v132
	v_add_f32_e32 v132, v163, v132
	v_add_f32_e32 v132, v133, v132
	v_fmac_f32_e32 v161, 0x3a800000, v132
	v_mul_f32_e32 v132, 0x4f800000, v161
	v_cmp_gt_f32_e32 vcc, s3, v161
	v_mov_b32_e32 v134, 0x260
	s_nop 0
	v_cndmask_b32_e32 v132, v161, v132, vcc
	v_sqrt_f32_e32 v133, v132
	s_nop 0
	v_add_u32_e32 v135, -1, v133
	v_add_u32_e32 v138, 1, v133
	v_fma_f32 v139, -v135, v133, v132
	v_fma_f32 v161, -v138, v133, v132
	v_cmp_ge_f32_e64 s[6:7], 0, v139
	s_nop 1
	v_cndmask_b32_e64 v133, v133, v135, s[6:7]
	v_cmp_lt_f32_e64 s[6:7], 0, v161
	s_nop 1
	v_cndmask_b32_e64 v133, v133, v138, s[6:7]
	v_mul_f32_e32 v135, 0x37800000, v133
	v_cndmask_b32_e32 v133, v133, v135, vcc
	v_cmp_class_f32_e32 vcc, v132, v134
	s_nop 1
	v_cndmask_b32_e32 v133, v133, v132, vcc
	v_div_scale_f32 v134, s[6:7], v133, v133, 1.0
	v_rcp_f32_e32 v135, v134
	v_div_scale_f32 v138, vcc, 1.0, v133, 1.0
	v_mul_f32_e32 v132, 0x3e800000, v165
	v_fma_f32 v139, -v134, v135, 1.0
	v_fmac_f32_e32 v135, v139, v135
	v_mul_f32_e32 v139, v138, v135
	v_fma_f32 v161, -v134, v139, v138
	v_fmac_f32_e32 v139, v161, v135
	v_fma_f32 v134, -v134, v139, v138
	v_div_fmas_f32 v134, v134, v135, v139
	v_div_fixup_f32 v133, v134, v133, 1.0
	v_lshl_add_u32 v134, v160, 3, 0
	ds_write_b64 v134, v[132:133] offset:8192
.LBB0_1339:
	s_or_b64 exec, exec, s[8:9]
	s_mov_b64 s[6:7], 0x1000
	v_lshl_add_u64 v[162:163], v[0:1], 0, s[6:7]
	v_lshl_add_u64 v[160:161], v[2:3], 0, s[6:7]
	s_add_u32 s6, s12, 0xd600000
	s_addc_u32 s7, s13, 0
	s_add_u32 s8, s12, s16
	s_addc_u32 s9, s13, s17
	v_lshl_add_u64 v[172:173], s[8:9], 0, v[136:137]
	s_movk_i32 s3, 0x7000
	v_lshl_add_u64 v[0:1], v[162:163], 0, v[136:137]
	v_lshl_add_u64 v[132:133], v[160:161], 0, v[136:137]
	v_add_co_u32_e32 v136, vcc, s3, v172
	s_waitcnt lgkmcnt(0)
	s_barrier
	s_nop 0
	v_addc_co_u32_e32 v137, vcc, 0, v173, vcc
	s_movk_i32 s3, 0x6000
	global_load_dwordx4 v[0:3], v[0:1], off
	v_lshl_add_u32 v177, v176, 3, 0
	global_load_dwordx4 v[132:135], v[132:133], off
	ds_read_b64 v[166:167], v177 offset:8192
	global_load_dwordx4 v[178:181], v[136:137], off
	v_add_co_u32_e32 v136, vcc, s3, v172
	v_add_u32_e32 v174, s20, v176
	s_nop 0
	v_addc_co_u32_e32 v137, vcc, 0, v173, vcc
	global_load_dwordx4 v[136:139], v[136:137], off
	s_waitcnt lgkmcnt(0)
	v_sub_f32_e32 v95, v95, v166
	v_sub_f32_e32 v94, v94, v166
	v_sub_f32_e32 v93, v93, v166
	v_sub_f32_e32 v92, v92, v166
	v_ashrrev_i32_e32 v175, 31, v174
	v_pk_mul_f32 v[92:93], v[166:167], v[92:93] op_sel:[1,0]
	v_pk_mul_f32 v[94:95], v[166:167], v[94:95] op_sel:[1,0]
	v_mov_b32_e32 v176, 0x7fc00000
	v_lshlrev_b64 v[168:169], 10, v[174:175]
	v_cmp_eq_u32_e32 vcc, 0, v164
	v_lshl_add_u64 v[186:187], v[168:169], 0, v[140:141]
	v_lshl_add_u64 v[186:187], v[186:187], 1, s[6:7]
	v_add_u32_e32 v170, 16, v174
	v_ashrrev_i32_e32 v171, 31, v170
	v_add_u32_e32 v182, 32, v174
	v_ashrrev_i32_e32 v183, 31, v182
	v_add_u32_e32 v184, 48, v174
	v_ashrrev_i32_e32 v185, 31, v184
	s_mov_b64 s[8:9], 0x7000
	s_waitcnt vmcnt(0)
	v_pk_fma_f32 v[94:95], v[2:3], v[94:95], v[134:135]
	v_pk_fma_f32 v[92:93], v[0:1], v[92:93], v[132:133]
	v_cndmask_b32_e32 v167, v176, v95, vcc
	v_cndmask_b32_e32 v166, v176, v94, vcc
	v_cndmask_b32_e32 v165, v176, v93, vcc
	v_cndmask_b32_e32 v164, v176, v92, vcc
	v_pk_add_f32 v[92:93], v[178:179], 1.0 op_sel_hi:[1,0]
	global_store_dwordx4 v[142:143], v[164:167], off sc0 sc1
	v_pk_add_f32 v[94:95], v[180:181], 1.0 op_sel_hi:[1,0]
	s_nop 0
	v_pk_fma_f32 v[164:165], v[92:93], v[164:165], v[136:137]
	v_pk_fma_f32 v[166:167], v[94:95], v[166:167], v[138:139]
	v_cvt_pk_bf16_f32 v164, v164, v165
	s_nop 0
	v_cvt_pk_bf16_f32 v165, v166, v167
	global_store_dwordx2 v[186:187], v[164:165], off
	ds_read_b64 v[164:165], v177 offset:8320
	v_lshlrev_b64 v[166:167], 10, v[170:171]
	v_lshl_add_u64 v[170:171], v[166:167], 0, v[140:141]
	v_lshl_add_u64 v[170:171], v[170:171], 1, s[6:7]
	s_waitcnt lgkmcnt(0)
; __device__ __forceinline__ unsigned cvt_pk_bf16(float lo, float hi) { unsigned r; asm volatile("v_cvt_pk_bf16_f32 %0, %1, %2" : "=v"(r) : "v"(lo), "v"(hi)); return r; }
;     __device__ __forceinline__ void fused(f32x4 (&acc)[2][2][4][2], const Unit& u, int wr, int wc, int fr, int fq, PG8_LAS unsigned char* lds, int wid, int lane) const {
;     ...
;         for (int bj = 0; bj < 2; ++bj)
; #pragma unroll
;             for (int n = 0; n < 2; ++n) {
;                 const int col = col0 + bj * HALF + n * 16;
;                 const f32x4 lg = *(const f32x4*)(lng + col), lb = *(const f32x4*)(lnb + col);
;                 f32x4 sc1 = (f32x4){1.f, 1.f, 1.f, 1.f}, sh = (f32x4){0.f, 0.f, 0.f, 0.f};
;                 if (DO_U) { sc1 = *(const f32x4*)(msc + mo + col) + 1.0f; sh = *(const f32x4*)(msh + mo + col); }
; #pragma unroll
;                 for (int ai = 0; ai < 2; ++ai)
; #pragma unroll
;                     for (int m = 0; m < 4; ++m) { const int r = ai * HALF + wr * 64 + m * 16 + fr; const f32x2v sr = S[r]; const size_t off = (size_t)(u.pm * BM + r) * 1024 + col;
;                         f32x4 y = (acc[ai][bj][m][n] - sr.x) * sr.y * lg + lb; if (bad) y = (f32x4){qnan, qnan, qnan, qnan};
;                         *(f32x4*)(out + off) = y;
;                         if (DO_U) { const f32x4 uu = y * sc1 + sh; u32x2v w; w.x = cvt_pk_bf16(uu[0], uu[1]); w.y = cvt_pk_bf16(uu[2], uu[3]); *(u32x2v*)(U + off) = w; } }
	v_sub_f32_e32 v103, v103, v164
	v_sub_f32_e32 v102, v102, v164
	v_sub_f32_e32 v101, v101, v164
	v_sub_f32_e32 v100, v100, v164
	v_pk_mul_f32 v[100:101], v[164:165], v[100:101] op_sel:[1,0]
	v_pk_mul_f32 v[102:103], v[164:165], v[102:103] op_sel:[1,0]
	v_pk_fma_f32 v[100:101], v[0:1], v[100:101], v[132:133]
	v_pk_fma_f32 v[102:103], v[2:3], v[102:103], v[134:135]
	v_cndmask_b32_e32 v101, v176, v101, vcc
	v_cndmask_b32_e32 v103, v176, v103, vcc
	v_cndmask_b32_e32 v102, v176, v102, vcc
	v_cndmask_b32_e32 v100, v176, v100, vcc
	global_store_dwordx4 v[146:147], v[100:103], off sc0 sc1
	v_lshlrev_b64 v[164:165], 10, v[182:183]
	s_nop 0
	v_pk_fma_f32 v[100:101], v[92:93], v[100:101], v[136:137]
	v_pk_fma_f32 v[102:103], v[94:95], v[102:103], v[138:139]
	v_cvt_pk_bf16_f32 v100, v100, v101
	s_nop 0
	v_cvt_pk_bf16_f32 v101, v102, v103
	global_store_dwordx2 v[170:171], v[100:101], off
	ds_read_b64 v[100:101], v177 offset:8448
	v_lshl_add_u64 v[102:103], v[164:165], 0, v[140:141]
	v_lshl_add_u64 v[170:171], v[102:103], 1, s[6:7]
	s_waitcnt lgkmcnt(0)
	v_sub_f32_e32 v103, v107, v100
	v_sub_f32_e32 v102, v106, v100
	v_sub_f32_e32 v105, v105, v100
	v_sub_f32_e32 v104, v104, v100
	v_pk_mul_f32 v[104:105], v[100:101], v[104:105] op_sel:[1,0]
	v_pk_mul_f32 v[100:101], v[100:101], v[102:103] op_sel:[1,0]
	v_pk_fma_f32 v[104:105], v[0:1], v[104:105], v[132:133]
	v_pk_fma_f32 v[100:101], v[2:3], v[100:101], v[134:135]
	s_nop 0
	v_cndmask_b32_e32 v103, v176, v101, vcc
	v_cndmask_b32_e32 v102, v176, v100, vcc
	v_cndmask_b32_e32 v101, v176, v105, vcc
	v_cndmask_b32_e32 v100, v176, v104, vcc
	global_store_dwordx4 v[148:149], v[100:103], off sc0 sc1
	v_lshlrev_b64 v[104:105], 10, v[184:185]
	v_lshl_add_u64 v[106:107], v[104:105], 0, v[140:141]
	v_pk_fma_f32 v[100:101], v[92:93], v[100:101], v[136:137]
	v_pk_fma_f32 v[102:103], v[94:95], v[102:103], v[138:139]
	v_cvt_pk_bf16_f32 v100, v100, v101
	s_nop 0
	v_cvt_pk_bf16_f32 v101, v102, v103
	global_store_dwordx2 v[170:171], v[100:101], off
	ds_read_b64 v[100:101], v177 offset:8576
	v_lshl_add_u64 v[170:171], v[172:173], 0, s[8:9]
	s_mov_b64 s[8:9], 0x6000
	s_waitcnt lgkmcnt(0)
	v_sub_f32_e32 v103, v115, v100
	v_sub_f32_e32 v102, v114, v100
	v_sub_f32_e32 v113, v113, v100
	v_sub_f32_e32 v112, v112, v100
	v_pk_mul_f32 v[112:113], v[100:101], v[112:113] op_sel:[1,0]
	v_pk_mul_f32 v[100:101], v[100:101], v[102:103] op_sel:[1,0]
	v_pk_fma_f32 v[112:113], v[0:1], v[112:113], v[132:133]
	v_pk_fma_f32 v[100:101], v[2:3], v[100:101], v[134:135]
	s_nop 0
	v_cndmask_b32_e32 v103, v176, v101, vcc
	v_cndmask_b32_e32 v102, v176, v100, vcc
	v_cndmask_b32_e32 v101, v176, v113, vcc
	v_cndmask_b32_e32 v100, v176, v112, vcc
	global_store_dwordx4 v[150:151], v[100:103], off sc0 sc1
	s_nop 1
	v_pk_fma_f32 v[102:103], v[94:95], v[102:103], v[138:139]
	v_pk_fma_f32 v[100:101], v[92:93], v[100:101], v[136:137]
	s_nop 0
	v_cvt_pk_bf16_f32 v100, v100, v101
	v_cvt_pk_bf16_f32 v101, v102, v103
	v_lshl_add_u64 v[102:103], v[106:107], 1, s[6:7]
	global_store_dwordx2 v[102:103], v[100:101], off
	ds_read_b64 v[100:101], v177 offset:9216
	v_add_u32_e32 v102, 0x80, v174
	v_ashrrev_i32_e32 v103, 31, v102
	v_lshlrev_b64 v[106:107], 10, v[102:103]
	v_lshl_add_u64 v[112:113], v[106:107], 0, v[140:141]
	s_waitcnt lgkmcnt(0)
	v_sub_f32_e32 v103, v119, v100
	v_sub_f32_e32 v102, v118, v100
	v_sub_f32_e32 v115, v117, v100
	v_sub_f32_e32 v114, v116, v100
	v_pk_mul_f32 v[114:115], v[100:101], v[114:115] op_sel:[1,0]
	v_pk_mul_f32 v[100:101], v[100:101], v[102:103] op_sel:[1,0]
	v_pk_fma_f32 v[114:115], v[0:1], v[114:115], v[132:133]
	v_pk_fma_f32 v[100:101], v[2:3], v[100:101], v[134:135]
	s_nop 0
	v_cndmask_b32_e32 v103, v176, v101, vcc
	v_cndmask_b32_e32 v102, v176, v100, vcc
	v_cndmask_b32_e32 v101, v176, v115, vcc
	v_cndmask_b32_e32 v100, v176, v114, vcc
	global_store_dwordx4 v[152:153], v[100:103], off sc0 sc1
	s_nop 1
	v_pk_fma_f32 v[102:103], v[94:95], v[102:103], v[138:139]
	v_pk_fma_f32 v[100:101], v[92:93], v[100:101], v[136:137]
	s_nop 0
	v_cvt_pk_bf16_f32 v100, v100, v101
	v_cvt_pk_bf16_f32 v101, v102, v103
	v_lshl_add_u64 v[102:103], v[112:113], 1, s[6:7]
	global_store_dwordx2 v[102:103], v[100:101], off
	ds_read_b64 v[100:101], v177 offset:9344
	v_add_u32_e32 v102, 0x90, v174
	v_ashrrev_i32_e32 v103, 31, v102
	v_lshlrev_b64 v[112:113], 10, v[102:103]
	v_lshl_add_u64 v[114:115], v[112:113], 0, v[140:141]
	s_waitcnt lgkmcnt(0)
	v_sub_f32_e32 v103, v123, v100
	v_sub_f32_e32 v102, v122, v100
	v_sub_f32_e32 v117, v121, v100
	v_sub_f32_e32 v116, v120, v100
	v_pk_mul_f32 v[116:117], v[100:101], v[116:117] op_sel:[1,0]
	v_pk_mul_f32 v[100:101], v[100:101], v[102:103] op_sel:[1,0]
	v_pk_fma_f32 v[116:117], v[0:1], v[116:117], v[132:133]
	v_pk_fma_f32 v[100:101], v[2:3], v[100:101], v[134:135]
	s_nop 0
	v_cndmask_b32_e32 v103, v176, v101, vcc
	v_cndmask_b32_e32 v102, v176, v100, vcc
	v_cndmask_b32_e32 v101, v176, v117, vcc
	v_cndmask_b32_e32 v100, v176, v116, vcc
	global_store_dwordx4 v[154:155], v[100:103], off sc0 sc1
	s_nop 1
	v_pk_fma_f32 v[102:103], v[94:95], v[102:103], v[138:139]
	v_pk_fma_f32 v[100:101], v[92:93], v[100:101], v[136:137]
	s_nop 0
	v_cvt_pk_bf16_f32 v100, v100, v101
	v_cvt_pk_bf16_f32 v101, v102, v103
	v_lshl_add_u64 v[102:103], v[114:115], 1, s[6:7]
	global_store_dwordx2 v[102:103], v[100:101], off
	ds_read_b64 v[100:101], v177 offset:9472
	v_add_u32_e32 v102, 0xa0, v174
	v_ashrrev_i32_e32 v103, 31, v102
	v_lshlrev_b64 v[114:115], 10, v[102:103]
	v_lshl_add_u64 v[116:117], v[114:115], 0, v[140:141]
	s_waitcnt lgkmcnt(0)
; __device__ __forceinline__ unsigned cvt_pk_bf16(float lo, float hi) { unsigned r; asm volatile("v_cvt_pk_bf16_f32 %0, %1, %2" : "=v"(r) : "v"(lo), "v"(hi)); return r; }
;     __device__ __forceinline__ void fused(f32x4 (&acc)[2][2][4][2], const Unit& u, int wr, int wc, int fr, int fq, PG8_LAS unsigned char* lds, int wid, int lane) const {
;     ...
;         for (int bj = 0; bj < 2; ++bj)
; #pragma unroll
;             for (int n = 0; n < 2; ++n) {
;                 const int col = col0 + bj * HALF + n * 16;
;                 const f32x4 lg = *(const f32x4*)(lng + col), lb = *(const f32x4*)(lnb + col);
;                 f32x4 sc1 = (f32x4){1.f, 1.f, 1.f, 1.f}, sh = (f32x4){0.f, 0.f, 0.f, 0.f};
;                 if (DO_U) { sc1 = *(const f32x4*)(msc + mo + col) + 1.0f; sh = *(const f32x4*)(msh + mo + col); }
; #pragma unroll
;                 for (int ai = 0; ai < 2; ++ai)
; #pragma unroll
;                     for (int m = 0; m < 4; ++m) { const int r = ai * HALF + wr * 64 + m * 16 + fr; const f32x2v sr = S[r]; const size_t off = (size_t)(u.pm * BM + r) * 1024 + col;
;                         f32x4 y = (acc[ai][bj][m][n] - sr.x) * sr.y * lg + lb; if (bad) y = (f32x4){qnan, qnan, qnan, qnan};
;                         *(f32x4*)(out + off) = y;
;                         if (DO_U) { const f32x4 uu = y * sc1 + sh; u32x2v w; w.x = cvt_pk_bf16(uu[0], uu[1]); w.y = cvt_pk_bf16(uu[2], uu[3]); *(u32x2v*)(U + off) = w; } }
	v_sub_f32_e32 v103, v127, v100
	v_sub_f32_e32 v102, v126, v100
	v_sub_f32_e32 v119, v125, v100
	v_sub_f32_e32 v118, v124, v100
	v_pk_mul_f32 v[118:119], v[100:101], v[118:119] op_sel:[1,0]
	v_pk_mul_f32 v[100:101], v[100:101], v[102:103] op_sel:[1,0]
	v_pk_fma_f32 v[118:119], v[0:1], v[118:119], v[132:133]
	v_pk_fma_f32 v[100:101], v[2:3], v[100:101], v[134:135]
	s_nop 0
	v_cndmask_b32_e32 v103, v176, v101, vcc
	v_cndmask_b32_e32 v102, v176, v100, vcc
	v_cndmask_b32_e32 v101, v176, v119, vcc
	v_cndmask_b32_e32 v100, v176, v118, vcc
	global_store_dwordx4 v[156:157], v[100:103], off sc0 sc1
	s_nop 1
	v_pk_fma_f32 v[102:103], v[94:95], v[102:103], v[138:139]
	v_pk_fma_f32 v[100:101], v[92:93], v[100:101], v[136:137]
	s_nop 0
	v_cvt_pk_bf16_f32 v100, v100, v101
	v_cvt_pk_bf16_f32 v101, v102, v103
	v_lshl_add_u64 v[102:103], v[116:117], 1, s[6:7]
	global_store_dwordx2 v[102:103], v[100:101], off
	ds_read_b64 v[100:101], v177 offset:9600
	v_add_u32_e32 v102, 0xb0, v174
	v_ashrrev_i32_e32 v103, 31, v102
	v_lshlrev_b64 v[116:117], 10, v[102:103]
	v_lshl_add_u64 v[102:103], v[116:117], 0, v[140:141]
	s_waitcnt lgkmcnt(0)
	v_sub_f32_e32 v119, v131, v100
	v_sub_f32_e32 v118, v130, v100
	v_sub_f32_e32 v121, v129, v100
	v_sub_f32_e32 v120, v128, v100
	v_pk_mul_f32 v[120:121], v[100:101], v[120:121] op_sel:[1,0]
	v_pk_mul_f32 v[100:101], v[100:101], v[118:119] op_sel:[1,0]
	v_pk_fma_f32 v[0:1], v[0:1], v[120:121], v[132:133]
	v_pk_fma_f32 v[2:3], v[2:3], v[100:101], v[134:135]
	v_cndmask_b32_e32 v1, v176, v1, vcc
	v_cndmask_b32_e32 v3, v176, v3, vcc
	v_cndmask_b32_e32 v2, v176, v2, vcc
	v_cndmask_b32_e32 v0, v176, v0, vcc
	global_store_dwordx4 v[158:159], v[0:3], off sc0 sc1
	v_or_b32_e32 v120, 16, v140
	v_ashrrev_i32_e32 v121, 31, v120
	v_pk_fma_f32 v[2:3], v[94:95], v[2:3], v[138:139]
	v_pk_fma_f32 v[0:1], v[92:93], v[0:1], v[136:137]
	v_lshl_add_u64 v[118:119], v[172:173], 0, s[8:9]
	v_cvt_pk_bf16_f32 v0, v0, v1
	v_cvt_pk_bf16_f32 v1, v2, v3
	v_lshl_add_u64 v[2:3], v[102:103], 1, s[6:7]
	global_store_dwordx2 v[2:3], v[0:1], off
	v_lshlrev_b64 v[0:1], 2, v[120:121]
	v_lshl_add_u64 v[2:3], v[162:163], 0, v[0:1]
	v_lshl_add_u64 v[0:1], v[160:161], 0, v[0:1]
	global_load_dwordx4 v[92:95], v[2:3], off
	global_load_dwordx4 v[122:125], v[170:171], off offset:64
	global_load_dwordx4 v[100:103], v[0:1], off
	ds_read_b64 v[126:127], v177 offset:8192
	global_load_dwordx4 v[0:3], v[118:119], off offset:64
	v_lshl_add_u64 v[128:129], v[168:169], 0, v[120:121]
	s_waitcnt lgkmcnt(0)
	v_sub_f32_e32 v67, v67, v126
	v_sub_f32_e32 v66, v66, v126
	v_sub_f32_e32 v65, v65, v126
	v_sub_f32_e32 v64, v64, v126
	v_pk_mul_f32 v[130:131], v[126:127], v[64:65] op_sel:[1,0]
	v_pk_mul_f32 v[126:127], v[126:127], v[66:67] op_sel:[1,0]
	s_waitcnt vmcnt(0)
	v_pk_add_f32 v[64:65], v[122:123], 1.0 op_sel_hi:[1,0]
	v_pk_fma_f32 v[122:123], v[94:95], v[126:127], v[102:103]
	v_pk_fma_f32 v[126:127], v[92:93], v[130:131], v[100:101]
	v_pk_add_f32 v[66:67], v[124:125], 1.0 op_sel_hi:[1,0]
	v_cndmask_b32_e32 v125, v176, v123, vcc
	v_cndmask_b32_e32 v124, v176, v122, vcc
	v_cndmask_b32_e32 v123, v176, v127, vcc
	v_cndmask_b32_e32 v122, v176, v126, vcc
	global_store_dwordx4 v[142:143], v[122:125], off offset:64 sc0 sc1
	s_nop 1
	v_pk_fma_f32 v[124:125], v[66:67], v[124:125], v[2:3]
	v_pk_fma_f32 v[122:123], v[64:65], v[122:123], v[0:1]
	s_nop 0
	v_cvt_pk_bf16_f32 v122, v122, v123
	v_cvt_pk_bf16_f32 v123, v124, v125
	v_lshl_add_u64 v[124:125], v[128:129], 1, s[6:7]
	global_store_dwordx2 v[124:125], v[122:123], off
	ds_read_b64 v[122:123], v177 offset:8320
	v_lshl_add_u64 v[124:125], v[166:167], 0, v[120:121]
	s_waitcnt lgkmcnt(0)
	v_sub_f32_e32 v71, v71, v122
	v_sub_f32_e32 v70, v70, v122
	v_sub_f32_e32 v69, v69, v122
	v_sub_f32_e32 v68, v68, v122
	v_pk_mul_f32 v[68:69], v[122:123], v[68:69] op_sel:[1,0]
	v_pk_mul_f32 v[70:71], v[122:123], v[70:71] op_sel:[1,0]
	v_pk_fma_f32 v[68:69], v[92:93], v[68:69], v[100:101]
	v_pk_fma_f32 v[70:71], v[94:95], v[70:71], v[102:103]
	v_cndmask_b32_e32 v69, v176, v69, vcc
	v_cndmask_b32_e32 v71, v176, v71, vcc
	v_cndmask_b32_e32 v70, v176, v70, vcc
	v_cndmask_b32_e32 v68, v176, v68, vcc
	global_store_dwordx4 v[146:147], v[68:71], off offset:64 sc0 sc1
	v_lshl_add_u64 v[122:123], v[164:165], 0, v[120:121]
	s_nop 0
	v_pk_fma_f32 v[70:71], v[66:67], v[70:71], v[2:3]
	v_pk_fma_f32 v[68:69], v[64:65], v[68:69], v[0:1]
	s_nop 0
	v_cvt_pk_bf16_f32 v68, v68, v69
	v_cvt_pk_bf16_f32 v69, v70, v71
	v_lshl_add_u64 v[70:71], v[124:125], 1, s[6:7]
	global_store_dwordx2 v[70:71], v[68:69], off
	ds_read_b64 v[68:69], v177 offset:8448
	s_waitcnt lgkmcnt(0)
	v_sub_f32_e32 v71, v75, v68
	v_sub_f32_e32 v70, v74, v68
	v_sub_f32_e32 v73, v73, v68
	v_sub_f32_e32 v72, v72, v68
	v_pk_mul_f32 v[72:73], v[68:69], v[72:73] op_sel:[1,0]
	v_pk_mul_f32 v[68:69], v[68:69], v[70:71] op_sel:[1,0]
	v_pk_fma_f32 v[72:73], v[92:93], v[72:73], v[100:101]
	v_pk_fma_f32 v[68:69], v[94:95], v[68:69], v[102:103]
	s_nop 0
	v_cndmask_b32_e32 v71, v176, v69, vcc
	v_cndmask_b32_e32 v70, v176, v68, vcc
	v_cndmask_b32_e32 v69, v176, v73, vcc
	v_cndmask_b32_e32 v68, v176, v72, vcc
	global_store_dwordx4 v[148:149], v[68:71], off offset:64 sc0 sc1
	v_lshl_add_u64 v[72:73], v[104:105], 0, v[120:121]
	s_nop 0
	v_pk_fma_f32 v[70:71], v[66:67], v[70:71], v[2:3]
	v_pk_fma_f32 v[68:69], v[64:65], v[68:69], v[0:1]
	s_nop 0
	v_cvt_pk_bf16_f32 v68, v68, v69
	v_cvt_pk_bf16_f32 v69, v70, v71
	v_lshl_add_u64 v[70:71], v[122:123], 1, s[6:7]
	global_store_dwordx2 v[70:71], v[68:69], off
	ds_read_b64 v[68:69], v177 offset:8576
	s_waitcnt lgkmcnt(0)
; __device__ __forceinline__ unsigned cvt_pk_bf16(float lo, float hi) { unsigned r; asm volatile("v_cvt_pk_bf16_f32 %0, %1, %2" : "=v"(r) : "v"(lo), "v"(hi)); return r; }
;     __device__ __forceinline__ void fused(f32x4 (&acc)[2][2][4][2], const Unit& u, int wr, int wc, int fr, int fq, PG8_LAS unsigned char* lds, int wid, int lane) const {
;     ...
;         for (int bj = 0; bj < 2; ++bj)
; #pragma unroll
;             for (int n = 0; n < 2; ++n) {
;                 const int col = col0 + bj * HALF + n * 16;
;                 const f32x4 lg = *(const f32x4*)(lng + col), lb = *(const f32x4*)(lnb + col);
;                 f32x4 sc1 = (f32x4){1.f, 1.f, 1.f, 1.f}, sh = (f32x4){0.f, 0.f, 0.f, 0.f};
;                 if (DO_U) { sc1 = *(const f32x4*)(msc + mo + col) + 1.0f; sh = *(const f32x4*)(msh + mo + col); }
; #pragma unroll
;                 for (int ai = 0; ai < 2; ++ai)
; #pragma unroll
;                     for (int m = 0; m < 4; ++m) { const int r = ai * HALF + wr * 64 + m * 16 + fr; const f32x2v sr = S[r]; const size_t off = (size_t)(u.pm * BM + r) * 1024 + col;
;                         f32x4 y = (acc[ai][bj][m][n] - sr.x) * sr.y * lg + lb; if (bad) y = (f32x4){qnan, qnan, qnan, qnan};
;                         *(f32x4*)(out + off) = y;
;                         if (DO_U) { const f32x4 uu = y * sc1 + sh; u32x2v w; w.x = cvt_pk_bf16(uu[0], uu[1]); w.y = cvt_pk_bf16(uu[2], uu[3]); *(u32x2v*)(U + off) = w; } }
	v_sub_f32_e32 v71, v83, v68
	v_sub_f32_e32 v70, v82, v68
	v_sub_f32_e32 v75, v81, v68
	v_sub_f32_e32 v74, v80, v68
	v_pk_mul_f32 v[74:75], v[68:69], v[74:75] op_sel:[1,0]
	v_pk_mul_f32 v[68:69], v[68:69], v[70:71] op_sel:[1,0]
	v_pk_fma_f32 v[74:75], v[92:93], v[74:75], v[100:101]
	v_pk_fma_f32 v[68:69], v[94:95], v[68:69], v[102:103]
	v_or_b32_e32 v80, 0x80, v140
	v_cndmask_b32_e32 v71, v176, v69, vcc
	v_cndmask_b32_e32 v70, v176, v68, vcc
	v_cndmask_b32_e32 v69, v176, v75, vcc
	v_cndmask_b32_e32 v68, v176, v74, vcc
	global_store_dwordx4 v[150:151], v[68:71], off offset:64 sc0 sc1
	v_ashrrev_i32_e32 v81, 31, v80
	s_nop 0
	v_pk_fma_f32 v[70:71], v[66:67], v[70:71], v[2:3]
	v_pk_fma_f32 v[68:69], v[64:65], v[68:69], v[0:1]
	s_nop 0
	v_cvt_pk_bf16_f32 v68, v68, v69
	v_cvt_pk_bf16_f32 v69, v70, v71
	v_lshl_add_u64 v[70:71], v[72:73], 1, s[6:7]
	global_store_dwordx2 v[70:71], v[68:69], off
	ds_read_b64 v[68:69], v177 offset:9216
	v_lshl_add_u64 v[72:73], v[106:107], 0, v[120:121]
	s_waitcnt lgkmcnt(0)
	v_sub_f32_e32 v71, v87, v68
	v_sub_f32_e32 v70, v86, v68
	v_sub_f32_e32 v75, v85, v68
	v_sub_f32_e32 v74, v84, v68
	v_pk_mul_f32 v[74:75], v[68:69], v[74:75] op_sel:[1,0]
	v_pk_mul_f32 v[68:69], v[68:69], v[70:71] op_sel:[1,0]
	v_pk_fma_f32 v[74:75], v[92:93], v[74:75], v[100:101]
	v_pk_fma_f32 v[68:69], v[94:95], v[68:69], v[102:103]
	v_lshl_add_u64 v[84:85], v[168:169], 0, v[80:81]
	v_cndmask_b32_e32 v71, v176, v69, vcc
	v_cndmask_b32_e32 v70, v176, v68, vcc
	v_cndmask_b32_e32 v69, v176, v75, vcc
	v_cndmask_b32_e32 v68, v176, v74, vcc
	global_store_dwordx4 v[152:153], v[68:71], off offset:64 sc0 sc1
	s_nop 1
	v_pk_fma_f32 v[70:71], v[66:67], v[70:71], v[2:3]
	v_pk_fma_f32 v[68:69], v[64:65], v[68:69], v[0:1]
	s_nop 0
	v_cvt_pk_bf16_f32 v68, v68, v69
	v_cvt_pk_bf16_f32 v69, v70, v71
	v_lshl_add_u64 v[70:71], v[72:73], 1, s[6:7]
	global_store_dwordx2 v[70:71], v[68:69], off
	ds_read_b64 v[68:69], v177 offset:9344
	v_lshl_add_u64 v[72:73], v[112:113], 0, v[120:121]
	s_waitcnt lgkmcnt(0)
	v_sub_f32_e32 v71, v91, v68
	v_sub_f32_e32 v70, v90, v68
	v_sub_f32_e32 v75, v89, v68
	v_sub_f32_e32 v74, v88, v68
	v_pk_mul_f32 v[74:75], v[68:69], v[74:75] op_sel:[1,0]
	v_pk_mul_f32 v[68:69], v[68:69], v[70:71] op_sel:[1,0]
	v_pk_fma_f32 v[74:75], v[92:93], v[74:75], v[100:101]
	v_pk_fma_f32 v[68:69], v[94:95], v[68:69], v[102:103]
	s_nop 0
	v_cndmask_b32_e32 v71, v176, v69, vcc
	v_cndmask_b32_e32 v70, v176, v68, vcc
	v_cndmask_b32_e32 v69, v176, v75, vcc
	v_cndmask_b32_e32 v68, v176, v74, vcc
	global_store_dwordx4 v[154:155], v[68:71], off offset:64 sc0 sc1
	s_nop 1
	v_pk_fma_f32 v[70:71], v[66:67], v[70:71], v[2:3]
	v_pk_fma_f32 v[68:69], v[64:65], v[68:69], v[0:1]
	s_nop 0
	v_cvt_pk_bf16_f32 v68, v68, v69
	v_cvt_pk_bf16_f32 v69, v70, v71
	v_lshl_add_u64 v[70:71], v[72:73], 1, s[6:7]
	global_store_dwordx2 v[70:71], v[68:69], off
	ds_read_b64 v[68:69], v177 offset:9472
	v_lshl_add_u64 v[72:73], v[114:115], 0, v[120:121]
	s_waitcnt lgkmcnt(0)
	v_sub_f32_e32 v71, v99, v68
	v_sub_f32_e32 v70, v98, v68
	v_sub_f32_e32 v75, v97, v68
	v_sub_f32_e32 v74, v96, v68
	v_pk_mul_f32 v[74:75], v[68:69], v[74:75] op_sel:[1,0]
	v_pk_mul_f32 v[68:69], v[68:69], v[70:71] op_sel:[1,0]
	v_pk_fma_f32 v[74:75], v[92:93], v[74:75], v[100:101]
	v_pk_fma_f32 v[68:69], v[94:95], v[68:69], v[102:103]
	s_nop 0
	v_cndmask_b32_e32 v71, v176, v69, vcc
	v_cndmask_b32_e32 v70, v176, v68, vcc
	v_cndmask_b32_e32 v69, v176, v75, vcc
	v_cndmask_b32_e32 v68, v176, v74, vcc
	global_store_dwordx4 v[156:157], v[68:71], off offset:64 sc0 sc1
	s_nop 1
	v_pk_fma_f32 v[70:71], v[66:67], v[70:71], v[2:3]
	v_pk_fma_f32 v[68:69], v[64:65], v[68:69], v[0:1]
	s_nop 0
	v_cvt_pk_bf16_f32 v68, v68, v69
	v_cvt_pk_bf16_f32 v69, v70, v71
	v_lshl_add_u64 v[70:71], v[72:73], 1, s[6:7]
	global_store_dwordx2 v[70:71], v[68:69], off
	ds_read_b64 v[68:69], v177 offset:9600
	v_lshl_add_u64 v[72:73], v[116:117], 0, v[120:121]
	s_waitcnt lgkmcnt(0)
	v_sub_f32_e32 v71, v111, v68
	v_sub_f32_e32 v70, v110, v68
	v_sub_f32_e32 v75, v109, v68
	v_sub_f32_e32 v74, v108, v68
	v_pk_mul_f32 v[74:75], v[68:69], v[74:75] op_sel:[1,0]
	v_pk_mul_f32 v[68:69], v[68:69], v[70:71] op_sel:[1,0]
	v_pk_fma_f32 v[74:75], v[92:93], v[74:75], v[100:101]
	v_pk_fma_f32 v[68:69], v[94:95], v[68:69], v[102:103]
	s_nop 0
	v_cndmask_b32_e32 v71, v176, v69, vcc
	v_cndmask_b32_e32 v70, v176, v68, vcc
	v_cndmask_b32_e32 v69, v176, v75, vcc
	v_cndmask_b32_e32 v68, v176, v74, vcc
	v_pk_fma_f32 v[2:3], v[66:67], v[70:71], v[2:3]
	v_pk_fma_f32 v[0:1], v[64:65], v[68:69], v[0:1]
	global_store_dwordx4 v[158:159], v[68:71], off offset:64 sc0 sc1
	v_cvt_pk_bf16_f32 v0, v0, v1
	v_cvt_pk_bf16_f32 v1, v2, v3
	v_lshl_add_u64 v[2:3], v[72:73], 1, s[6:7]
	global_store_dwordx2 v[2:3], v[0:1], off
	v_lshlrev_b64 v[0:1], 2, v[80:81]
	v_lshl_add_u64 v[2:3], v[162:163], 0, v[0:1]
	global_load_dwordx4 v[64:67], v[2:3], off
	v_lshl_add_u64 v[0:1], v[160:161], 0, v[0:1]
	global_load_dwordx4 v[72:75], v[170:171], off offset:512
	global_load_dwordx4 v[68:71], v[0:1], off
	s_nop 0
	global_load_dwordx4 v[0:3], v[118:119], off offset:512
	ds_read_b64 v[82:83], v177 offset:8192
	s_waitcnt lgkmcnt(0)
	v_sub_f32_e32 v35, v35, v82
	v_sub_f32_e32 v34, v34, v82
	v_sub_f32_e32 v33, v33, v82
	v_sub_f32_e32 v32, v32, v82
	v_pk_mul_f32 v[32:33], v[82:83], v[32:33] op_sel:[1,0]
	v_pk_mul_f32 v[34:35], v[82:83], v[34:35] op_sel:[1,0]
	v_lshl_add_u64 v[82:83], v[166:167], 0, v[80:81]
	s_waitcnt vmcnt(0)
; __device__ __forceinline__ unsigned cvt_pk_bf16(float lo, float hi) { unsigned r; asm volatile("v_cvt_pk_bf16_f32 %0, %1, %2" : "=v"(r) : "v"(lo), "v"(hi)); return r; }
;     __device__ __forceinline__ void fused(f32x4 (&acc)[2][2][4][2], const Unit& u, int wr, int wc, int fr, int fq, PG8_LAS unsigned char* lds, int wid, int lane) const {
;     ...
;         for (int bj = 0; bj < 2; ++bj)
; #pragma unroll
;             for (int n = 0; n < 2; ++n) {
;                 const int col = col0 + bj * HALF + n * 16;
;                 const f32x4 lg = *(const f32x4*)(lng + col), lb = *(const f32x4*)(lnb + col);
;                 f32x4 sc1 = (f32x4){1.f, 1.f, 1.f, 1.f}, sh = (f32x4){0.f, 0.f, 0.f, 0.f};
;                 if (DO_U) { sc1 = *(const f32x4*)(msc + mo + col) + 1.0f; sh = *(const f32x4*)(msh + mo + col); }
; #pragma unroll
;                 for (int ai = 0; ai < 2; ++ai)
; #pragma unroll
;                     for (int m = 0; m < 4; ++m) { const int r = ai * HALF + wr * 64 + m * 16 + fr; const f32x2v sr = S[r]; const size_t off = (size_t)(u.pm * BM + r) * 1024 + col;
;                         f32x4 y = (acc[ai][bj][m][n] - sr.x) * sr.y * lg + lb; if (bad) y = (f32x4){qnan, qnan, qnan, qnan};
;                         *(f32x4*)(out + off) = y;
;                         if (DO_U) { const f32x4 uu = y * sc1 + sh; u32x2v w; w.x = cvt_pk_bf16(uu[0], uu[1]); w.y = cvt_pk_bf16(uu[2], uu[3]); *(u32x2v*)(U + off) = w; } }
	v_pk_fma_f32 v[34:35], v[66:67], v[34:35], v[70:71]
	v_pk_fma_f32 v[32:33], v[64:65], v[32:33], v[68:69]
	v_pk_add_f32 v[74:75], v[74:75], 1.0 op_sel_hi:[1,0]
	v_pk_add_f32 v[72:73], v[72:73], 1.0 op_sel_hi:[1,0]
	v_cndmask_b32_e32 v35, v176, v35, vcc
	v_cndmask_b32_e32 v34, v176, v34, vcc
	v_cndmask_b32_e32 v33, v176, v33, vcc
	v_cndmask_b32_e32 v32, v176, v32, vcc
	global_store_dwordx4 v[142:143], v[32:35], off offset:512 sc0 sc1
	s_nop 1
	v_pk_fma_f32 v[34:35], v[74:75], v[34:35], v[2:3]
	v_pk_fma_f32 v[32:33], v[72:73], v[32:33], v[0:1]
	s_nop 0
	v_cvt_pk_bf16_f32 v32, v32, v33
	v_cvt_pk_bf16_f32 v33, v34, v35
	v_lshl_add_u64 v[34:35], v[84:85], 1, s[6:7]
	global_store_dwordx2 v[34:35], v[32:33], off
	ds_read_b64 v[32:33], v177 offset:8320
	s_waitcnt lgkmcnt(0)
	v_sub_f32_e32 v35, v39, v32
	v_sub_f32_e32 v34, v38, v32
	v_sub_f32_e32 v37, v37, v32
	v_sub_f32_e32 v36, v36, v32
	v_pk_mul_f32 v[36:37], v[32:33], v[36:37] op_sel:[1,0]
	v_pk_mul_f32 v[32:33], v[32:33], v[34:35] op_sel:[1,0]
	v_pk_fma_f32 v[36:37], v[64:65], v[36:37], v[68:69]
	v_pk_fma_f32 v[32:33], v[66:67], v[32:33], v[70:71]
	s_nop 0
	v_cndmask_b32_e32 v35, v176, v33, vcc
	v_cndmask_b32_e32 v34, v176, v32, vcc
	v_cndmask_b32_e32 v33, v176, v37, vcc
	v_cndmask_b32_e32 v32, v176, v36, vcc
	global_store_dwordx4 v[146:147], v[32:35], off offset:512 sc0 sc1
	v_lshl_add_u64 v[36:37], v[164:165], 0, v[80:81]
	s_nop 0
	v_pk_fma_f32 v[34:35], v[74:75], v[34:35], v[2:3]
	v_pk_fma_f32 v[32:33], v[72:73], v[32:33], v[0:1]
	s_nop 0
	v_cvt_pk_bf16_f32 v32, v32, v33
	v_cvt_pk_bf16_f32 v33, v34, v35
	v_lshl_add_u64 v[34:35], v[82:83], 1, s[6:7]
	global_store_dwordx2 v[34:35], v[32:33], off
	ds_read_b64 v[32:33], v177 offset:8448
	s_waitcnt lgkmcnt(0)
	v_sub_f32_e32 v35, v43, v32
	v_sub_f32_e32 v34, v42, v32
	v_sub_f32_e32 v39, v41, v32
	v_sub_f32_e32 v38, v40, v32
	v_pk_mul_f32 v[38:39], v[32:33], v[38:39] op_sel:[1,0]
	v_pk_mul_f32 v[32:33], v[32:33], v[34:35] op_sel:[1,0]
	v_pk_fma_f32 v[38:39], v[64:65], v[38:39], v[68:69]
	v_pk_fma_f32 v[32:33], v[66:67], v[32:33], v[70:71]
	s_nop 0
	v_cndmask_b32_e32 v35, v176, v33, vcc
	v_cndmask_b32_e32 v34, v176, v32, vcc
	v_cndmask_b32_e32 v33, v176, v39, vcc
	v_cndmask_b32_e32 v32, v176, v38, vcc
	global_store_dwordx4 v[148:149], v[32:35], off offset:512 sc0 sc1
	s_nop 1
	v_pk_fma_f32 v[34:35], v[74:75], v[34:35], v[2:3]
	v_pk_fma_f32 v[32:33], v[72:73], v[32:33], v[0:1]
	s_nop 0
	v_cvt_pk_bf16_f32 v32, v32, v33
	v_cvt_pk_bf16_f32 v33, v34, v35
	v_lshl_add_u64 v[34:35], v[36:37], 1, s[6:7]
	global_store_dwordx2 v[34:35], v[32:33], off
	ds_read_b64 v[32:33], v177 offset:8576
	v_lshl_add_u64 v[36:37], v[104:105], 0, v[80:81]
	s_waitcnt lgkmcnt(0)
	v_sub_f32_e32 v35, v51, v32
	v_sub_f32_e32 v34, v50, v32
	v_sub_f32_e32 v39, v49, v32
	v_sub_f32_e32 v38, v48, v32
	v_pk_mul_f32 v[38:39], v[32:33], v[38:39] op_sel:[1,0]
	v_pk_mul_f32 v[32:33], v[32:33], v[34:35] op_sel:[1,0]
	v_pk_fma_f32 v[38:39], v[64:65], v[38:39], v[68:69]
	v_pk_fma_f32 v[32:33], v[66:67], v[32:33], v[70:71]
	v_or_b32_e32 v48, 0x90, v140
	v_cndmask_b32_e32 v35, v176, v33, vcc
	v_cndmask_b32_e32 v34, v176, v32, vcc
	v_cndmask_b32_e32 v33, v176, v39, vcc
	v_cndmask_b32_e32 v32, v176, v38, vcc
	global_store_dwordx4 v[150:151], v[32:35], off offset:512 sc0 sc1
	v_ashrrev_i32_e32 v49, 31, v48
	s_nop 0
	v_pk_fma_f32 v[34:35], v[74:75], v[34:35], v[2:3]
	v_pk_fma_f32 v[32:33], v[72:73], v[32:33], v[0:1]
	s_nop 0
	v_cvt_pk_bf16_f32 v32, v32, v33
	v_cvt_pk_bf16_f32 v33, v34, v35
	v_lshl_add_u64 v[34:35], v[36:37], 1, s[6:7]
	global_store_dwordx2 v[34:35], v[32:33], off
	ds_read_b64 v[32:33], v177 offset:9216
	v_lshl_add_u64 v[36:37], v[106:107], 0, v[80:81]
	s_waitcnt lgkmcnt(0)
	v_sub_f32_e32 v35, v55, v32
	v_sub_f32_e32 v34, v54, v32
	v_sub_f32_e32 v39, v53, v32
	v_sub_f32_e32 v38, v52, v32
	v_pk_mul_f32 v[38:39], v[32:33], v[38:39] op_sel:[1,0]
	v_pk_mul_f32 v[32:33], v[32:33], v[34:35] op_sel:[1,0]
	v_pk_fma_f32 v[38:39], v[64:65], v[38:39], v[68:69]
	v_pk_fma_f32 v[32:33], v[66:67], v[32:33], v[70:71]
	v_lshl_add_u64 v[52:53], v[168:169], 0, v[48:49]
	v_cndmask_b32_e32 v35, v176, v33, vcc
	v_cndmask_b32_e32 v34, v176, v32, vcc
	v_cndmask_b32_e32 v33, v176, v39, vcc
	v_cndmask_b32_e32 v32, v176, v38, vcc
	global_store_dwordx4 v[152:153], v[32:35], off offset:512 sc0 sc1
	s_nop 1
	v_pk_fma_f32 v[34:35], v[74:75], v[34:35], v[2:3]
	v_pk_fma_f32 v[32:33], v[72:73], v[32:33], v[0:1]
	s_nop 0
	v_cvt_pk_bf16_f32 v32, v32, v33
	v_cvt_pk_bf16_f32 v33, v34, v35
	v_lshl_add_u64 v[34:35], v[36:37], 1, s[6:7]
	global_store_dwordx2 v[34:35], v[32:33], off
	ds_read_b64 v[32:33], v177 offset:9344
	v_lshl_add_u64 v[36:37], v[112:113], 0, v[80:81]
	s_waitcnt lgkmcnt(0)
	v_sub_f32_e32 v35, v59, v32
	v_sub_f32_e32 v34, v58, v32
	v_sub_f32_e32 v39, v57, v32
	v_sub_f32_e32 v38, v56, v32
	v_pk_mul_f32 v[38:39], v[32:33], v[38:39] op_sel:[1,0]
	v_pk_mul_f32 v[32:33], v[32:33], v[34:35] op_sel:[1,0]
	v_pk_fma_f32 v[38:39], v[64:65], v[38:39], v[68:69]
	v_pk_fma_f32 v[32:33], v[66:67], v[32:33], v[70:71]
	s_nop 0
	v_cndmask_b32_e32 v35, v176, v33, vcc
	v_cndmask_b32_e32 v34, v176, v32, vcc
	v_cndmask_b32_e32 v33, v176, v39, vcc
	v_cndmask_b32_e32 v32, v176, v38, vcc
	global_store_dwordx4 v[154:155], v[32:35], off offset:512 sc0 sc1
	s_nop 1
	v_pk_fma_f32 v[34:35], v[74:75], v[34:35], v[2:3]
	v_pk_fma_f32 v[32:33], v[72:73], v[32:33], v[0:1]
	s_nop 0
	v_cvt_pk_bf16_f32 v32, v32, v33
	v_cvt_pk_bf16_f32 v33, v34, v35
	v_lshl_add_u64 v[34:35], v[36:37], 1, s[6:7]
	global_store_dwordx2 v[34:35], v[32:33], off
	ds_read_b64 v[32:33], v177 offset:9472
	v_lshl_add_u64 v[36:37], v[114:115], 0, v[80:81]
	s_waitcnt lgkmcnt(0)
; __device__ __forceinline__ unsigned cvt_pk_bf16(float lo, float hi) { unsigned r; asm volatile("v_cvt_pk_bf16_f32 %0, %1, %2" : "=v"(r) : "v"(lo), "v"(hi)); return r; }
;     __device__ __forceinline__ void fused(f32x4 (&acc)[2][2][4][2], const Unit& u, int wr, int wc, int fr, int fq, PG8_LAS unsigned char* lds, int wid, int lane) const {
;     ...
;         for (int bj = 0; bj < 2; ++bj)
; #pragma unroll
;             for (int n = 0; n < 2; ++n) {
;                 const int col = col0 + bj * HALF + n * 16;
;                 const f32x4 lg = *(const f32x4*)(lng + col), lb = *(const f32x4*)(lnb + col);
;                 f32x4 sc1 = (f32x4){1.f, 1.f, 1.f, 1.f}, sh = (f32x4){0.f, 0.f, 0.f, 0.f};
;                 if (DO_U) { sc1 = *(const f32x4*)(msc + mo + col) + 1.0f; sh = *(const f32x4*)(msh + mo + col); }
; #pragma unroll
;                 for (int ai = 0; ai < 2; ++ai)
; #pragma unroll
;                     for (int m = 0; m < 4; ++m) { const int r = ai * HALF + wr * 64 + m * 16 + fr; const f32x2v sr = S[r]; const size_t off = (size_t)(u.pm * BM + r) * 1024 + col;
;                         f32x4 y = (acc[ai][bj][m][n] - sr.x) * sr.y * lg + lb; if (bad) y = (f32x4){qnan, qnan, qnan, qnan};
;                         *(f32x4*)(out + off) = y;
;                         if (DO_U) { const f32x4 uu = y * sc1 + sh; u32x2v w; w.x = cvt_pk_bf16(uu[0], uu[1]); w.y = cvt_pk_bf16(uu[2], uu[3]); *(u32x2v*)(U + off) = w; } }
	v_sub_f32_e32 v35, v63, v32
	v_sub_f32_e32 v34, v62, v32
	v_sub_f32_e32 v39, v61, v32
	v_sub_f32_e32 v38, v60, v32
	v_pk_mul_f32 v[38:39], v[32:33], v[38:39] op_sel:[1,0]
	v_pk_mul_f32 v[32:33], v[32:33], v[34:35] op_sel:[1,0]
	v_pk_fma_f32 v[38:39], v[64:65], v[38:39], v[68:69]
	v_pk_fma_f32 v[32:33], v[66:67], v[32:33], v[70:71]
	s_nop 0
	v_cndmask_b32_e32 v35, v176, v33, vcc
	v_cndmask_b32_e32 v34, v176, v32, vcc
	v_cndmask_b32_e32 v33, v176, v39, vcc
	v_cndmask_b32_e32 v32, v176, v38, vcc
	global_store_dwordx4 v[156:157], v[32:35], off offset:512 sc0 sc1
	s_nop 1
	v_pk_fma_f32 v[34:35], v[74:75], v[34:35], v[2:3]
	v_pk_fma_f32 v[32:33], v[72:73], v[32:33], v[0:1]
	s_nop 0
	v_cvt_pk_bf16_f32 v32, v32, v33
	v_cvt_pk_bf16_f32 v33, v34, v35
	v_lshl_add_u64 v[34:35], v[36:37], 1, s[6:7]
	global_store_dwordx2 v[34:35], v[32:33], off
	ds_read_b64 v[32:33], v177 offset:9600
	v_lshl_add_u64 v[36:37], v[116:117], 0, v[80:81]
	s_waitcnt lgkmcnt(0)
	v_sub_f32_e32 v35, v79, v32
	v_sub_f32_e32 v34, v78, v32
	v_sub_f32_e32 v39, v77, v32
	v_sub_f32_e32 v38, v76, v32
	v_pk_mul_f32 v[38:39], v[32:33], v[38:39] op_sel:[1,0]
	v_pk_mul_f32 v[32:33], v[32:33], v[34:35] op_sel:[1,0]
	v_pk_fma_f32 v[38:39], v[64:65], v[38:39], v[68:69]
	v_pk_fma_f32 v[32:33], v[66:67], v[32:33], v[70:71]
	s_nop 0
	v_cndmask_b32_e32 v35, v176, v33, vcc
	v_cndmask_b32_e32 v34, v176, v32, vcc
	v_cndmask_b32_e32 v33, v176, v39, vcc
	v_cndmask_b32_e32 v32, v176, v38, vcc
	v_pk_fma_f32 v[2:3], v[74:75], v[34:35], v[2:3]
	v_pk_fma_f32 v[0:1], v[72:73], v[32:33], v[0:1]
	global_store_dwordx4 v[158:159], v[32:35], off offset:512 sc0 sc1
	v_cvt_pk_bf16_f32 v0, v0, v1
	v_cvt_pk_bf16_f32 v1, v2, v3
	v_lshl_add_u64 v[2:3], v[36:37], 1, s[6:7]
	global_store_dwordx2 v[2:3], v[0:1], off
	v_lshlrev_b64 v[0:1], 2, v[48:49]
	v_lshl_add_u64 v[2:3], v[162:163], 0, v[0:1]
	global_load_dwordx4 v[32:35], v[2:3], off
	v_lshl_add_u64 v[50:51], v[160:161], 0, v[0:1]
	global_load_dwordx4 v[40:43], v[170:171], off offset:576
	global_load_dwordx4 v[36:39], v[50:51], off
	global_load_dwordx4 v[0:3], v[118:119], off offset:576
	ds_read_b64 v[50:51], v177 offset:8192
	s_waitcnt lgkmcnt(0)
	v_sub_f32_e32 v7, v7, v50
	v_sub_f32_e32 v6, v6, v50
	v_sub_f32_e32 v5, v5, v50
	v_sub_f32_e32 v4, v4, v50
	v_pk_mul_f32 v[4:5], v[50:51], v[4:5] op_sel:[1,0]
	v_pk_mul_f32 v[6:7], v[50:51], v[6:7] op_sel:[1,0]
	v_lshl_add_u64 v[50:51], v[166:167], 0, v[48:49]
	s_waitcnt vmcnt(0)
	v_pk_fma_f32 v[6:7], v[34:35], v[6:7], v[38:39]
	v_pk_fma_f32 v[4:5], v[32:33], v[4:5], v[36:37]
	v_pk_add_f32 v[42:43], v[42:43], 1.0 op_sel_hi:[1,0]
	v_pk_add_f32 v[40:41], v[40:41], 1.0 op_sel_hi:[1,0]
	v_cndmask_b32_e32 v7, v176, v7, vcc
	v_cndmask_b32_e32 v6, v176, v6, vcc
	v_cndmask_b32_e32 v5, v176, v5, vcc
	v_cndmask_b32_e32 v4, v176, v4, vcc
	global_store_dwordx4 v[142:143], v[4:7], off offset:576 sc0 sc1
	s_nop 1
	v_pk_fma_f32 v[6:7], v[42:43], v[6:7], v[2:3]
	v_pk_fma_f32 v[4:5], v[40:41], v[4:5], v[0:1]
	s_nop 0
	v_cvt_pk_bf16_f32 v4, v4, v5
	v_cvt_pk_bf16_f32 v5, v6, v7
	v_lshl_add_u64 v[6:7], v[52:53], 1, s[6:7]
	global_store_dwordx2 v[6:7], v[4:5], off
	ds_read_b64 v[4:5], v177 offset:8320
	s_waitcnt lgkmcnt(0)
	v_sub_f32_e32 v7, v11, v4
	v_sub_f32_e32 v6, v10, v4
	v_sub_f32_e32 v9, v9, v4
	v_sub_f32_e32 v8, v8, v4
	v_pk_mul_f32 v[8:9], v[4:5], v[8:9] op_sel:[1,0]
	v_pk_mul_f32 v[4:5], v[4:5], v[6:7] op_sel:[1,0]
	v_pk_fma_f32 v[8:9], v[32:33], v[8:9], v[36:37]
	v_pk_fma_f32 v[4:5], v[34:35], v[4:5], v[38:39]
	s_nop 0
	v_cndmask_b32_e32 v7, v176, v5, vcc
	v_cndmask_b32_e32 v6, v176, v4, vcc
	v_cndmask_b32_e32 v5, v176, v9, vcc
	v_cndmask_b32_e32 v4, v176, v8, vcc
	global_store_dwordx4 v[146:147], v[4:7], off offset:576 sc0 sc1
	v_lshl_add_u64 v[8:9], v[164:165], 0, v[48:49]
	s_nop 0
	v_pk_fma_f32 v[6:7], v[42:43], v[6:7], v[2:3]
	v_pk_fma_f32 v[4:5], v[40:41], v[4:5], v[0:1]
	s_nop 0
	v_cvt_pk_bf16_f32 v4, v4, v5
	v_cvt_pk_bf16_f32 v5, v6, v7
	v_lshl_add_u64 v[6:7], v[50:51], 1, s[6:7]
	global_store_dwordx2 v[6:7], v[4:5], off
	ds_read_b64 v[4:5], v177 offset:8448
	s_waitcnt lgkmcnt(0)
	v_sub_f32_e32 v7, v15, v4
	v_sub_f32_e32 v6, v14, v4
	v_sub_f32_e32 v11, v13, v4
	v_sub_f32_e32 v10, v12, v4
	v_pk_mul_f32 v[10:11], v[4:5], v[10:11] op_sel:[1,0]
	v_pk_mul_f32 v[4:5], v[4:5], v[6:7] op_sel:[1,0]
	v_pk_fma_f32 v[10:11], v[32:33], v[10:11], v[36:37]
	v_pk_fma_f32 v[4:5], v[34:35], v[4:5], v[38:39]
	s_nop 0
	v_cndmask_b32_e32 v7, v176, v5, vcc
	v_cndmask_b32_e32 v6, v176, v4, vcc
	v_cndmask_b32_e32 v5, v176, v11, vcc
	v_cndmask_b32_e32 v4, v176, v10, vcc
	global_store_dwordx4 v[148:149], v[4:7], off offset:576 sc0 sc1
	s_nop 1
	v_pk_fma_f32 v[6:7], v[42:43], v[6:7], v[2:3]
	v_pk_fma_f32 v[4:5], v[40:41], v[4:5], v[0:1]
	s_nop 0
	v_cvt_pk_bf16_f32 v4, v4, v5
	v_cvt_pk_bf16_f32 v5, v6, v7
	v_lshl_add_u64 v[6:7], v[8:9], 1, s[6:7]
	global_store_dwordx2 v[6:7], v[4:5], off
	ds_read_b64 v[4:5], v177 offset:8576
	v_lshl_add_u64 v[8:9], v[104:105], 0, v[48:49]
	s_waitcnt lgkmcnt(0)
; __device__ __forceinline__ unsigned cvt_pk_bf16(float lo, float hi) { unsigned r; asm volatile("v_cvt_pk_bf16_f32 %0, %1, %2" : "=v"(r) : "v"(lo), "v"(hi)); return r; }
;     __device__ __forceinline__ void fused(f32x4 (&acc)[2][2][4][2], const Unit& u, int wr, int wc, int fr, int fq, PG8_LAS unsigned char* lds, int wid, int lane) const {
;     ...
;         for (int bj = 0; bj < 2; ++bj)
; #pragma unroll
;             for (int n = 0; n < 2; ++n) {
;                 const int col = col0 + bj * HALF + n * 16;
;                 const f32x4 lg = *(const f32x4*)(lng + col), lb = *(const f32x4*)(lnb + col);
;                 f32x4 sc1 = (f32x4){1.f, 1.f, 1.f, 1.f}, sh = (f32x4){0.f, 0.f, 0.f, 0.f};
;                 if (DO_U) { sc1 = *(const f32x4*)(msc + mo + col) + 1.0f; sh = *(const f32x4*)(msh + mo + col); }
; #pragma unroll
;                 for (int ai = 0; ai < 2; ++ai)
; #pragma unroll
;                     for (int m = 0; m < 4; ++m) { const int r = ai * HALF + wr * 64 + m * 16 + fr; const f32x2v sr = S[r]; const size_t off = (size_t)(u.pm * BM + r) * 1024 + col;
;                         f32x4 y = (acc[ai][bj][m][n] - sr.x) * sr.y * lg + lb; if (bad) y = (f32x4){qnan, qnan, qnan, qnan};
;                         *(f32x4*)(out + off) = y;
;                         if (DO_U) { const f32x4 uu = y * sc1 + sh; u32x2v w; w.x = cvt_pk_bf16(uu[0], uu[1]); w.y = cvt_pk_bf16(uu[2], uu[3]); *(u32x2v*)(U + off) = w; } }
	v_sub_f32_e32 v7, v19, v4
	v_sub_f32_e32 v6, v18, v4
	v_sub_f32_e32 v11, v17, v4
	v_sub_f32_e32 v10, v16, v4
	v_pk_mul_f32 v[10:11], v[4:5], v[10:11] op_sel:[1,0]
	v_pk_mul_f32 v[4:5], v[4:5], v[6:7] op_sel:[1,0]
	v_pk_fma_f32 v[10:11], v[32:33], v[10:11], v[36:37]
	v_pk_fma_f32 v[4:5], v[34:35], v[4:5], v[38:39]
	s_nop 0
	v_cndmask_b32_e32 v7, v176, v5, vcc
	v_cndmask_b32_e32 v6, v176, v4, vcc
	v_cndmask_b32_e32 v5, v176, v11, vcc
	v_cndmask_b32_e32 v4, v176, v10, vcc
	global_store_dwordx4 v[150:151], v[4:7], off offset:576 sc0 sc1
	s_nop 1
	v_pk_fma_f32 v[6:7], v[42:43], v[6:7], v[2:3]
	v_pk_fma_f32 v[4:5], v[40:41], v[4:5], v[0:1]
	s_nop 0
	v_cvt_pk_bf16_f32 v4, v4, v5
	v_cvt_pk_bf16_f32 v5, v6, v7
	v_lshl_add_u64 v[6:7], v[8:9], 1, s[6:7]
	global_store_dwordx2 v[6:7], v[4:5], off
	ds_read_b64 v[4:5], v177 offset:9216
	v_lshl_add_u64 v[8:9], v[106:107], 0, v[48:49]
	s_waitcnt lgkmcnt(0)
	v_sub_f32_e32 v7, v23, v4
	v_sub_f32_e32 v6, v22, v4
	v_sub_f32_e32 v11, v21, v4
	v_sub_f32_e32 v10, v20, v4
	v_pk_mul_f32 v[10:11], v[4:5], v[10:11] op_sel:[1,0]
	v_pk_mul_f32 v[4:5], v[4:5], v[6:7] op_sel:[1,0]
	v_pk_fma_f32 v[10:11], v[32:33], v[10:11], v[36:37]
	v_pk_fma_f32 v[4:5], v[34:35], v[4:5], v[38:39]
	s_nop 0
	v_cndmask_b32_e32 v7, v176, v5, vcc
	v_cndmask_b32_e32 v6, v176, v4, vcc
	v_cndmask_b32_e32 v5, v176, v11, vcc
	v_cndmask_b32_e32 v4, v176, v10, vcc
	global_store_dwordx4 v[152:153], v[4:7], off offset:576 sc0 sc1
	s_nop 1
	v_pk_fma_f32 v[6:7], v[42:43], v[6:7], v[2:3]
	v_pk_fma_f32 v[4:5], v[40:41], v[4:5], v[0:1]
	s_nop 0
	v_cvt_pk_bf16_f32 v4, v4, v5
	v_cvt_pk_bf16_f32 v5, v6, v7
	v_lshl_add_u64 v[6:7], v[8:9], 1, s[6:7]
	global_store_dwordx2 v[6:7], v[4:5], off
	ds_read_b64 v[4:5], v177 offset:9344
	v_lshl_add_u64 v[8:9], v[112:113], 0, v[48:49]
	s_waitcnt lgkmcnt(0)
	v_sub_f32_e32 v7, v27, v4
	v_sub_f32_e32 v6, v26, v4
	v_sub_f32_e32 v11, v25, v4
	v_sub_f32_e32 v10, v24, v4
	v_pk_mul_f32 v[10:11], v[4:5], v[10:11] op_sel:[1,0]
	v_pk_mul_f32 v[4:5], v[4:5], v[6:7] op_sel:[1,0]
	v_pk_fma_f32 v[10:11], v[32:33], v[10:11], v[36:37]
	v_pk_fma_f32 v[4:5], v[34:35], v[4:5], v[38:39]
	s_nop 0
	v_cndmask_b32_e32 v7, v176, v5, vcc
	v_cndmask_b32_e32 v6, v176, v4, vcc
	v_cndmask_b32_e32 v5, v176, v11, vcc
	v_cndmask_b32_e32 v4, v176, v10, vcc
	global_store_dwordx4 v[154:155], v[4:7], off offset:576 sc0 sc1
	s_nop 1
	v_pk_fma_f32 v[6:7], v[42:43], v[6:7], v[2:3]
	v_pk_fma_f32 v[4:5], v[40:41], v[4:5], v[0:1]
	s_nop 0
	v_cvt_pk_bf16_f32 v4, v4, v5
	v_cvt_pk_bf16_f32 v5, v6, v7
	v_lshl_add_u64 v[6:7], v[8:9], 1, s[6:7]
	global_store_dwordx2 v[6:7], v[4:5], off
	ds_read_b64 v[4:5], v177 offset:9472
	v_lshl_add_u64 v[8:9], v[114:115], 0, v[48:49]
	s_waitcnt lgkmcnt(0)
	v_sub_f32_e32 v7, v31, v4
	v_sub_f32_e32 v6, v30, v4
	v_sub_f32_e32 v11, v29, v4
	v_sub_f32_e32 v10, v28, v4
	v_pk_mul_f32 v[10:11], v[4:5], v[10:11] op_sel:[1,0]
	v_pk_mul_f32 v[4:5], v[4:5], v[6:7] op_sel:[1,0]
	v_pk_fma_f32 v[10:11], v[32:33], v[10:11], v[36:37]
	v_pk_fma_f32 v[4:5], v[34:35], v[4:5], v[38:39]
	s_nop 0
	v_cndmask_b32_e32 v7, v176, v5, vcc
	v_cndmask_b32_e32 v6, v176, v4, vcc
	v_cndmask_b32_e32 v5, v176, v11, vcc
	v_cndmask_b32_e32 v4, v176, v10, vcc
	global_store_dwordx4 v[156:157], v[4:7], off offset:576 sc0 sc1
	s_nop 1
	v_pk_fma_f32 v[6:7], v[42:43], v[6:7], v[2:3]
	v_pk_fma_f32 v[4:5], v[40:41], v[4:5], v[0:1]
	s_nop 0
	v_cvt_pk_bf16_f32 v4, v4, v5
	v_cvt_pk_bf16_f32 v5, v6, v7
	v_lshl_add_u64 v[6:7], v[8:9], 1, s[6:7]
	global_store_dwordx2 v[6:7], v[4:5], off
	ds_read_b64 v[4:5], v177 offset:9600
	v_lshl_add_u64 v[8:9], v[116:117], 0, v[48:49]
	s_waitcnt lgkmcnt(0)
	v_sub_f32_e32 v7, v47, v4
	v_sub_f32_e32 v6, v46, v4
	v_sub_f32_e32 v11, v45, v4
	v_sub_f32_e32 v10, v44, v4
	v_pk_mul_f32 v[10:11], v[4:5], v[10:11] op_sel:[1,0]
	v_pk_mul_f32 v[4:5], v[4:5], v[6:7] op_sel:[1,0]
	v_pk_fma_f32 v[10:11], v[32:33], v[10:11], v[36:37]
	v_pk_fma_f32 v[4:5], v[34:35], v[4:5], v[38:39]
	s_nop 0
	v_cndmask_b32_e32 v7, v176, v5, vcc
	v_cndmask_b32_e32 v6, v176, v4, vcc
	v_cndmask_b32_e32 v5, v176, v11, vcc
	v_cndmask_b32_e32 v4, v176, v10, vcc
	v_pk_fma_f32 v[2:3], v[42:43], v[6:7], v[2:3]
	v_pk_fma_f32 v[0:1], v[40:41], v[4:5], v[0:1]
	global_store_dwordx4 v[158:159], v[4:7], off offset:576 sc0 sc1
	v_cvt_pk_bf16_f32 v0, v0, v1
	v_cvt_pk_bf16_f32 v1, v2, v3
	v_lshl_add_u64 v[2:3], v[8:9], 1, s[6:7]
	global_store_dwordx2 v[2:3], v[0:1], off

; #define PG8_WAIT_V(n) asm volatile("s_waitcnt vmcnt(" #n ")" ::: "memory")
; template <class Epi, class Sched, bool ALIGN_EPI = false, bool SP2 = false>
; __device__ __forceinline__ void gemm_phase(PG8_LAS unsigned char* lds, const Gemm g, const Sched& S, const Epi& E) {
;     int tid_o = threadIdx.x; asm volatile("" : "+v"(tid_o));
;     const int tid = tid_o, wid = __builtin_amdgcn_readfirstlane(tid >> 6), lane = tid & 63, wr = wid >> 2, wc = wid & 3, fr = lane & 15, fq = lane >> 4;
;     const int K = g.K, nt = K / BK;
;     unsigned voffA[2], voffB[2];
; #pragma unroll
;     for (int i = 0; i < 2; ++i) { int R, C; stage_rc(tid * 16 + i * 8192, R, C); const int Rb = Epi::PERM ? ((R & ~31) + perm32(R & 31)) : R;
;         voffA[i] = (unsigned)(R * K + C) * 2u; voffB[i] = (unsigned)(Rb * K + C) * 2u; }
;     const size_t kstep = (size_t)(BK * 2);
;     const size_t hstep = (size_t)HALF * K * 2;
;     const size_t tstep = 2 * hstep;
;     const unsigned ldsw = (unsigned)wid * 1024u;
;     const int aoff = lds_byte(wr * 64 + fr, fq * 8), boff = lds_byte(wc * 32 + fr, fq * 8);
;     ...
;     Unit cur, nxt; int ui = 0;
;     if (!S.next(0, cur)) return;
;     f32x4 acc[2][2][4][2];
; #pragma unroll
;     for (int a = 0; a < 2; ++a)
; #pragma unroll
;         for (int b = 0; b < 2; ++b)
; #pragma unroll
;             for (int m = 0; m < 4; ++m)
; #pragma unroll
;                 for (int n = 0; n < 2; ++n) acc[a][b][m][n] = (f32x4){0.f, 0.f, 0.f, 0.f};
;     bf16x8 At[4][2], B0[2][2], B1[2][2];
;     const char* cA = (const char*)g.A + (size_t)cur.pm * tstep; const char* cB = (const char*)g.Bt + (size_t)cur.pn * tstep;
;     S.a_ready(cur);
;     if constexpr (SP2) {
;         PG8_STAGE(PG8_SB(0, 0), cB, voffB); PG8_STAGE(PG8_SB(0, 1), cB + hstep, voffB); PG8_STAGE(PG8_SA(0, 0), cA, voffA); PG8_STAGE(PG8_SA(0, 1), cA + hstep, voffA);
;         if (wr == 1) PG8_BAR;
;         PG8_WAIT_V(2); PG8_BAR;
;         PG8_STAGE(PG8_SB(1, 0), cB + kstep, voffB); PG8_STAGE(PG8_SA(1, 0), cA + kstep, voffA); PG8_STAGE(PG8_SB(1, 1), cB + hstep + kstep, voffB);
;         PG8_WAIT_V(6); PG8_BAR;
;     } else {
;         PG8_STAGE(PG8_SB(0, 0), cB, voffB); PG8_STAGE(PG8_SA(0, 0), cA, voffA); PG8_STAGE(PG8_SB(0, 1), cB + hstep, voffB); PG8_STAGE(PG8_SA(0, 1), cA + hstep, voffA);
;         if (wr == 1) PG8_BAR;
;         PG8_WAIT_V(4); PG8_BAR;
.LBB0_1392:
	s_or_b64 exec, exec, s[6:7]
	s_mov_b64 s[6:7], s[0:1]
	s_waitcnt lgkmcnt(0)
	s_barrier
	v_readlane_b32 s10, v250, 0
	s_waitcnt vmcnt(0)
	v_mov_b64_e32 v[0:1], s[6:7]
	global_load_dwordx2 v[0:1], v[0:1], off offset:200
	s_movk_i32 s6, 0x400
	v_mov_b32_e32 v12, v144
	v_readlane_b32 s11, v250, 1
	s_andn2_b64 vcc, exec, s[10:11]
	s_waitcnt vmcnt(0) lgkmcnt(0)
	v_readfirstlane_b32 s9, v1
	v_readfirstlane_b32 s8, v0
	s_nop 0
	v_readfirstlane_b32 s30, v12
	s_cbranch_vccnz .LBB0_1413
	v_lshlrev_b32_e32 v0, 4, v12
	v_add_u32_e32 v1, 0x2000, v0
	v_ashrrev_i32_e32 v2, 31, v1
	v_lshrrev_b32_e32 v2, 22, v2
	v_add_u32_e32 v2, v1, v2
	v_ashrrev_i32_e32 v2, 10, v2
	v_mul_i32_i24_e32 v3, 0x400, v2
	v_sub_u32_e32 v1, v1, v3
	v_lshrrev_b32_e32 v3, 4, v1
	v_bitop3_b32 v1, v3, v1, 32 bitop3:0x6c
	v_ashrrev_i32_e32 v3, 31, v1
	v_lshrrev_b32_e32 v3, 26, v3
	v_add_u32_e32 v3, v1, v3
	v_lshlrev_b32_e32 v5, 3, v2
	v_ashrrev_i32_e32 v4, 6, v3
	v_and_b32_e32 v5, -16, v5
	v_lshlrev_b32_e32 v2, 5, v2
	v_add_u32_e32 v5, v4, v5
	v_and_b32_e32 v13, 32, v2
	v_and_b32_e32 v2, 0xc0, v3
	v_and_b32_e32 v4, 3, v4
	s_mov_b32 s14, 0x7fffffe0
	v_lshrrev_b32_e32 v6, 2, v5
	v_lshlrev_b32_e32 v7, 1, v5
	v_sub_u32_e32 v1, v1, v2
	v_mov_b32_e32 v2, 1
	v_and_or_b32 v4, v5, s14, v4
	v_and_b32_e32 v6, 4, v6
	v_and_b32_e32 v7, 24, v7
	v_ashrrev_i16_sdwa v1, v2, sext(v1) dst_sel:DWORD dst_unused:UNUSED_PAD src0_sel:DWORD src1_sel:BYTE_0
	v_or3_b32 v4, v4, v6, v7
	v_bfe_i32 v14, v1, 0, 16
	v_mul_lo_u32 v4, v4, s6
	v_add_u32_e32 v1, v13, v14
	v_mul_lo_u32 v15, v5, s6
	v_add_lshl_u32 v128, v4, v1, 1
	v_add_lshl_u32 v130, v1, v15, 1
	v_bfe_i32 v1, v12, 27, 1
	v_lshrrev_b32_e32 v1, 22, v1
	v_add_u32_e32 v1, v0, v1
	v_and_b32_e32 v1, 0xfffffc00, v1
	v_sub_u32_e32 v0, v0, v1
	v_lshrrev_b32_e32 v1, 4, v0
	v_ashrrev_i32_e32 v4, 31, v12
	v_bitop3_b32 v0, v1, v0, 32 bitop3:0x6c
	v_lshrrev_b32_e32 v4, 26, v4
	v_ashrrev_i32_e32 v1, 31, v0
	v_add_u32_e32 v4, v12, v4
	s_add_u32 s3, s8, 0xd600000
	v_lshrrev_b32_e32 v1, 26, v1
	v_ashrrev_i32_e32 v4, 6, v4
	s_addc_u32 s40, s9, 0
	v_add_u32_e32 v1, v0, v1
	v_lshlrev_b32_e32 v5, 3, v4
	s_add_u32 s41, s8, 0x1200000
	v_ashrrev_i32_e32 v3, 6, v1
	v_and_b32_e32 v5, -16, v5
	s_addc_u32 s42, s9, 0
	v_add_u32_e32 v5, v3, v5
	v_and_b32_e32 v3, 3, v3
	s_ashr_i32 s44, s2, 31
	v_and_or_b32 v3, v5, s14, v3
	s_lshr_b32 s14, s44, 29
	s_add_i32 s14, s2, s14
	s_ashr_i32 s21, s30, 6
	s_ashr_i32 s7, s6, 31
	s_ashr_i32 s15, s14, 3
	s_and_b32 s14, s14, -8
	s_ashr_i32 s31, s30, 8
	s_lshl_b64 s[10:11], s[6:7], 8
	s_lshl_b64 s[12:13], s[6:7], 9
	s_lshl_b32 s43, s21, 10
	s_sub_i32 s14, s2, s14
	s_cmp_lt_i32 s14, 0
	s_movk_i32 s45, 0xb1
	s_cselect_b32 s16, s45, 0xb0
	s_mul_i32 s14, s14, s16
	s_add_i32 s14, s14, s15
	s_mul_hi_i32 s15, s14, 0x2e8ba2e9
	s_lshr_b32 s16, s15, 31
	s_ashr_i32 s15, s15, 5
	s_add_i32 s15, s15, s16
	s_lshl_b32 s16, s15, 3
	s_mulk_i32 s15, 0xb0
	s_sub_i32 s14, s14, s15
	s_sext_i32_i16 s15, s14
	s_bfe_u32 s15, s15, 0x3001c
	s_add_i32 s15, s14, s15
	s_sext_i32_i16 s18, s15
	s_and_b32 s15, s15, 0xfff8
	s_sub_i32 s14, s14, s15
	s_sext_i32_i16 s14, s14
	s_add_i32 s62, s16, s14
	s_ashr_i32 s14, s62, 31
	s_mul_i32 s14, s12, s14
	s_mul_hi_u32 s15, s12, s62
	s_add_i32 s16, s15, s14
	s_lshr_b64 s[14:15], s[6:7], 23
	s_lshr_b32 s20, s18, 3
	s_mul_i32 s15, s14, s62
	s_add_i32 s19, s16, s15
	s_bfe_i64 s[16:17], s[20:21], 0x100000
	s_ashr_i32 s15, s18, 3
	v_and_b32_e32 v1, 0xc0, v1
	s_mul_hi_u32 s16, s12, s15
	s_mul_i32 s17, s12, s17
	v_lshrrev_b32_e32 v6, 2, v5
	v_lshlrev_b32_e32 v7, 1, v5
	v_sub_u32_e32 v0, v0, v1
	s_add_i32 s16, s16, s17
	s_mul_i32 s14, s14, s15
	v_and_b32_e32 v6, 4, v6
	v_and_b32_e32 v7, 24, v7
	v_lshlrev_b32_e32 v4, 5, v4
	v_ashrrev_i16_sdwa v0, v2, sext(v0) dst_sel:DWORD dst_unused:UNUSED_PAD src0_sel:DWORD src1_sel:BYTE_0
	s_add_i32 s16, s16, s14
	s_mul_i32 s14, s12, s15
	v_or3_b32 v3, v3, v6, v7
	v_and_b32_e32 v16, 32, v4
	v_bfe_i32 v17, v0, 0, 16
	s_add_u32 s36, s41, s14
	v_mul_lo_u32 v3, v3, s6
	v_add_u32_e32 v0, v16, v17
	s_addc_u32 s37, s42, s16
	s_add_i32 s46, s43, 0
	v_add_lshl_u32 v132, v3, v0, 1
	s_add_i32 m0, s46, 0x10000
	s_mul_i32 s34, s12, s62
	global_load_lds_dwordx4 v132, s[36:37]
	s_add_i32 m0, s46, 0x12000
	s_add_u32 s14, s36, s10
	global_load_lds_dwordx4 v128, s[36:37]
	s_addc_u32 s15, s37, s11
	s_add_i32 m0, s46, 0x14000
	v_mul_lo_u32 v18, v5, s6
	global_load_lds_dwordx4 v132, s[14:15]
	s_add_i32 m0, s46, 0x16000
	s_add_u32 s38, s3, s34
	s_addc_u32 s39, s40, s19
	s_add_i32 s47, s46, 0x2000
	v_add_lshl_u32 v134, v0, v18, 1
	global_load_lds_dwordx4 v128, s[14:15]
	s_mov_b32 m0, s46
	s_add_u32 s16, s38, s10
	global_load_lds_dwordx4 v134, s[38:39]
	s_mov_b32 m0, s47
	s_addc_u32 s17, s39, s11
	s_add_i32 s48, s46, 0x4000
	global_load_lds_dwordx4 v130, s[38:39]
	s_mov_b32 m0, s48
	s_add_i32 s49, s46, 0x6000
	global_load_lds_dwordx4 v134, s[16:17]
	s_mov_b32 m0, s49
	v_mov_b32_e32 v133, 0
	global_load_lds_dwordx4 v130, s[16:17]
	v_mov_b32_e32 v129, v133
	v_mov_b32_e32 v135, v133
	v_mov_b32_e32 v131, v133
	s_cmp_eq_u32 s31, 1
	s_mov_b32 s50, 0
	v_lshl_add_u64 v[8:9], s[36:37], 0, v[132:133]
	v_lshl_add_u64 v[4:5], s[36:37], 0, v[128:129]
	v_lshl_add_u64 v[2:3], s[14:15], 0, v[132:133]
	v_lshl_add_u64 v[0:1], s[14:15], 0, v[128:129]
	v_lshl_add_u64 v[6:7], s[38:39], 0, v[134:135]
	s_cselect_b64 s[14:15], -1, 0
	s_cmp_lg_u32 s31, 1
	v_lshl_add_u64 v[10:11], s[38:39], 0, v[130:131]
	s_cbranch_scc1 .LBB0_1395
	s_barrier

; __device__ __forceinline__ unsigned cvt_pk_bf16(float lo, float hi) { unsigned r; asm volatile("v_cvt_pk_bf16_f32 %0, %1, %2" : "=v"(r) : "v"(lo), "v"(hi)); return r; }
;     __device__ __forceinline__ void operator()(const f32x4 (&acc)[2][2][4][2], const Unit& u, int wr, int wc, int fr, int fq) const {
;         const int row0 = u.pm * BM + wr * 64 + fr, col0 = u.pn * 128 + wc * 32 + 8 * fq;
; #pragma unroll
;         for (int ai = 0; ai < 2; ++ai)
; #pragma unroll
;             for (int m = 0; m < 4; ++m) {
;                 bf16_t* rowp = O + (size_t)(row0 + ai * HALF + m * 16) * ldc + col0;
;                 float h[8];
; #pragma unroll
;                 for (int n = 0; n < 2; ++n)
; #pragma unroll
;                     for (int e = 0; e < 4; ++e) { const float g = acc[ai][0][m][n][e], up = acc[ai][1][m][n][e]; h[4 * n + e] = g * __builtin_amdgcn_rcpf(1.f + __expf(-g)) * up; }
;                 u32x4 w; w.x = cvt_pk_bf16(h[0], h[1]); w.y = cvt_pk_bf16(h[2], h[3]); w.z = cvt_pk_bf16(h[4], h[5]); w.w = cvt_pk_bf16(h[6], h[7]);
;                 *(u32x4*)rowp = w;
;             }
;     }
.LBB0_1409:
	v_mul_f32_e32 v146, 0xbfb8aa3b, v124
	v_exp_f32_e32 v155, v146
	v_mul_f32_e32 v146, 0xbfb8aa3b, v125
	v_exp_f32_e32 v158, v146
	v_lshl_or_b32 v156, s63, 7, v150
	v_add_f32_e32 v155, 1.0, v155
	v_rcp_f32_e32 v155, v155
	v_add_f32_e32 v158, 1.0, v158
	v_rcp_f32_e32 v160, v158
	v_lshl_add_u32 v154, s62, 8, v148
	v_mul_f32_e32 v124, v124, v155
	v_mul_f32_e32 v120, v120, v124
	v_mul_f32_e32 v124, v125, v160
	v_mul_f32_e32 v125, 0xbfb8aa3b, v126
	v_exp_f32_e32 v125, v125
	v_mul_f32_e32 v155, 0xbfb8aa3b, v127
	v_exp_f32_e32 v155, v155
	v_mul_f32_e32 v121, v121, v124
	v_add_f32_e32 v124, 1.0, v125
	v_rcp_f32_e32 v124, v124
	v_add_f32_e32 v125, 1.0, v155
	v_mul_f32_e32 v155, 0xbfb8aa3b, v116
	v_rcp_f32_e32 v125, v125
	v_exp_f32_e32 v155, v155
	v_mul_f32_e32 v124, v126, v124
	v_mul_f32_e32 v122, v122, v124
	v_mul_f32_e32 v124, v127, v125
	v_add_f32_e32 v125, 1.0, v155
	v_rcp_f32_e32 v125, v125
	v_mul_f32_e32 v126, 0xbfb8aa3b, v117
	v_exp_f32_e32 v126, v126
	v_mul_f32_e32 v123, v123, v124
	v_mul_f32_e32 v116, v116, v125
	v_mul_f32_e32 v116, v112, v116
	v_add_f32_e32 v112, 1.0, v126
	v_mul_f32_e32 v124, 0xbfb8aa3b, v118
	v_rcp_f32_e32 v112, v112
	v_exp_f32_e32 v124, v124
	v_mul_f32_e32 v125, 0xbfb8aa3b, v119
	v_exp_f32_e32 v125, v125
	v_mul_f32_e32 v112, v117, v112
	v_add_f32_e32 v117, 1.0, v124
	v_rcp_f32_e32 v117, v117
	v_add_f32_e32 v124, 1.0, v125
	v_rcp_f32_e32 v124, v124
	v_mul_f32_e32 v125, v113, v112
	v_mul_f32_e32 v112, v118, v117
	v_ashrrev_i32_e32 v157, 31, v156
	v_mov_b64_e32 v[146:147], s[16:17]
	v_mul_f32_e32 v117, v114, v112
	v_mul_f32_e32 v112, v119, v124
	v_mad_i64_i32 v[158:159], s[36:37], v154, s59, v[146:147]
	v_mul_f32_e32 v124, v115, v112
	v_lshlrev_b64 v[112:113], 1, v[156:157]
	v_lshl_add_u64 v[118:119], v[158:159], 0, v[112:113]
	v_cvt_pk_bf16_f32 v114, v120, v121
	v_cvt_pk_bf16_f32 v115, v122, v123
	v_cvt_pk_bf16_f32 v116, v116, v125
	v_cvt_pk_bf16_f32 v117, v117, v124
	global_store_dwordx4 v[118:119], v[114:117], off sc0 sc1
	s_and_b64 vcc, exec, s[6:7]
	s_mov_b64 s[6:7], -1
	v_mul_f32_e32 v114, 0xbfb8aa3b, v108
	v_exp_f32_e32 v114, v114
	v_mul_f32_e32 v115, 0xbfb8aa3b, v109
	v_exp_f32_e32 v115, v115
	v_or_b32_e32 v116, 16, v154
	v_add_f32_e32 v114, 1.0, v114
	v_rcp_f32_e32 v117, v114
	v_add_f32_e32 v114, 1.0, v115
	v_rcp_f32_e32 v118, v114
	v_mad_i64_i32 v[114:115], s[36:37], v116, s59, v[146:147]
	v_mul_f32_e32 v108, v108, v117
	v_mul_f32_e32 v104, v104, v108
	v_mul_f32_e32 v108, v109, v118
	v_mul_f32_e32 v109, 0xbfb8aa3b, v110
	v_exp_f32_e32 v109, v109
	v_mul_f32_e32 v116, 0xbfb8aa3b, v111
	v_exp_f32_e32 v116, v116
	v_mul_f32_e32 v105, v105, v108
	v_add_f32_e32 v108, 1.0, v109
	v_rcp_f32_e32 v108, v108
	v_add_f32_e32 v109, 1.0, v116
	v_mul_f32_e32 v116, 0xbfb8aa3b, v100
	v_rcp_f32_e32 v109, v109
	v_exp_f32_e32 v116, v116
	v_mul_f32_e32 v108, v110, v108
	v_mul_f32_e32 v106, v106, v108
	v_mul_f32_e32 v108, v111, v109
	v_add_f32_e32 v109, 1.0, v116
	v_rcp_f32_e32 v109, v109
	v_mul_f32_e32 v110, 0xbfb8aa3b, v101
	v_exp_f32_e32 v110, v110
	v_mul_f32_e32 v107, v107, v108
	v_mul_f32_e32 v100, v100, v109
	v_mul_f32_e32 v108, v96, v100
	v_mul_f32_e32 v100, 0xbfb8aa3b, v102
	v_add_f32_e32 v96, 1.0, v110
	v_exp_f32_e32 v100, v100
	v_mul_f32_e32 v109, 0xbfb8aa3b, v103
	v_rcp_f32_e32 v96, v96
	v_exp_f32_e32 v109, v109
	v_add_f32_e32 v100, 1.0, v100
	v_rcp_f32_e32 v100, v100
	v_mul_f32_e32 v96, v101, v96
	v_add_f32_e32 v101, 1.0, v109
	v_rcp_f32_e32 v101, v101
	v_mul_f32_e32 v109, v97, v96
	v_mul_f32_e32 v96, v102, v100
	v_mul_f32_e32 v102, v98, v96
	v_mul_f32_e32 v96, v103, v101
	v_mul_f32_e32 v99, v99, v96
	v_lshl_add_u64 v[100:101], v[114:115], 0, v[112:113]
	v_cvt_pk_bf16_f32 v96, v104, v105
	v_cvt_pk_bf16_f32 v97, v106, v107
	v_cvt_pk_bf16_f32 v98, v108, v109
	v_cvt_pk_bf16_f32 v99, v102, v99
	global_store_dwordx4 v[100:101], v[96:99], off sc0 sc1
	s_nop 1
	v_mul_f32_e32 v96, 0xbfb8aa3b, v92
	v_exp_f32_e32 v96, v96
	v_mul_f32_e32 v97, 0xbfb8aa3b, v93
	v_exp_f32_e32 v97, v97
	v_or_b32_e32 v98, 32, v154
	v_add_f32_e32 v96, 1.0, v96
	v_rcp_f32_e32 v99, v96
	v_add_f32_e32 v96, 1.0, v97
	v_rcp_f32_e32 v100, v96
	v_mad_i64_i32 v[96:97], s[36:37], v98, s59, v[146:147]
	v_mul_f32_e32 v92, v92, v99
	v_mul_f32_e32 v88, v88, v92
	v_mul_f32_e32 v92, v93, v100
	v_mul_f32_e32 v93, 0xbfb8aa3b, v94
	v_exp_f32_e32 v93, v93
	v_mul_f32_e32 v98, 0xbfb8aa3b, v95
	v_exp_f32_e32 v98, v98
	v_mul_f32_e32 v89, v89, v92
	v_add_f32_e32 v92, 1.0, v93
	v_rcp_f32_e32 v92, v92
	v_add_f32_e32 v93, 1.0, v98
	v_mul_f32_e32 v98, 0xbfb8aa3b, v84
	v_rcp_f32_e32 v93, v93
	v_exp_f32_e32 v98, v98
	v_mul_f32_e32 v92, v94, v92
	v_mul_f32_e32 v90, v90, v92
	v_mul_f32_e32 v92, v95, v93
	v_add_f32_e32 v93, 1.0, v98
	v_rcp_f32_e32 v93, v93
	v_mul_f32_e32 v94, 0xbfb8aa3b, v85
	v_exp_f32_e32 v94, v94
	v_mul_f32_e32 v91, v91, v92
	v_mul_f32_e32 v84, v84, v93
	v_mul_f32_e32 v92, v80, v84
	v_mul_f32_e32 v84, 0xbfb8aa3b, v86
	v_add_f32_e32 v80, 1.0, v94
	v_exp_f32_e32 v84, v84
	v_mul_f32_e32 v93, 0xbfb8aa3b, v87
	v_rcp_f32_e32 v80, v80
	v_exp_f32_e32 v93, v93
	v_add_f32_e32 v84, 1.0, v84
	v_rcp_f32_e32 v84, v84
	v_mul_f32_e32 v80, v85, v80
	v_add_f32_e32 v85, 1.0, v93
	v_rcp_f32_e32 v85, v85
	v_mul_f32_e32 v93, v81, v80
	v_mul_f32_e32 v80, v86, v84
	v_mul_f32_e32 v86, v82, v80
	v_mul_f32_e32 v80, v87, v85
	v_mul_f32_e32 v83, v83, v80
	v_lshl_add_u64 v[84:85], v[96:97], 0, v[112:113]
	v_cvt_pk_bf16_f32 v80, v88, v89
	v_cvt_pk_bf16_f32 v81, v90, v91
	v_cvt_pk_bf16_f32 v82, v92, v93
	v_cvt_pk_bf16_f32 v83, v86, v83
	global_store_dwordx4 v[84:85], v[80:83], off sc0 sc1
	s_nop 1
	v_mul_f32_e32 v80, 0xbfb8aa3b, v76
	v_exp_f32_e32 v80, v80
	v_mul_f32_e32 v81, 0xbfb8aa3b, v77
; __device__ __forceinline__ unsigned cvt_pk_bf16(float lo, float hi) { unsigned r; asm volatile("v_cvt_pk_bf16_f32 %0, %1, %2" : "=v"(r) : "v"(lo), "v"(hi)); return r; }
;     __device__ __forceinline__ void operator()(const f32x4 (&acc)[2][2][4][2], const Unit& u, int wr, int wc, int fr, int fq) const {
;         const int row0 = u.pm * BM + wr * 64 + fr, col0 = u.pn * 128 + wc * 32 + 8 * fq;
; #pragma unroll
;         for (int ai = 0; ai < 2; ++ai)
; #pragma unroll
;             for (int m = 0; m < 4; ++m) {
;                 bf16_t* rowp = O + (size_t)(row0 + ai * HALF + m * 16) * ldc + col0;
;                 float h[8];
; #pragma unroll
;                 for (int n = 0; n < 2; ++n)
; #pragma unroll
;                     for (int e = 0; e < 4; ++e) { const float g = acc[ai][0][m][n][e], up = acc[ai][1][m][n][e]; h[4 * n + e] = g * __builtin_amdgcn_rcpf(1.f + __expf(-g)) * up; }
;                 u32x4 w; w.x = cvt_pk_bf16(h[0], h[1]); w.y = cvt_pk_bf16(h[2], h[3]); w.z = cvt_pk_bf16(h[4], h[5]); w.w = cvt_pk_bf16(h[6], h[7]);
;                 *(u32x4*)rowp = w;
;             }
;     }
	v_exp_f32_e32 v81, v81
	v_or_b32_e32 v82, 48, v154
	v_add_f32_e32 v80, 1.0, v80
	v_rcp_f32_e32 v83, v80
	v_add_f32_e32 v80, 1.0, v81
	v_rcp_f32_e32 v84, v80
	v_mad_i64_i32 v[80:81], s[36:37], v82, s59, v[146:147]
	v_mul_f32_e32 v76, v76, v83
	v_mul_f32_e32 v72, v72, v76
	v_mul_f32_e32 v76, v77, v84
	v_mul_f32_e32 v77, 0xbfb8aa3b, v78
	v_exp_f32_e32 v77, v77
	v_mul_f32_e32 v82, 0xbfb8aa3b, v79
	v_exp_f32_e32 v82, v82
	v_mul_f32_e32 v73, v73, v76
	v_add_f32_e32 v76, 1.0, v77
	v_rcp_f32_e32 v76, v76
	v_add_f32_e32 v77, 1.0, v82
	v_mul_f32_e32 v82, 0xbfb8aa3b, v68
	v_rcp_f32_e32 v77, v77
	v_exp_f32_e32 v82, v82
	v_mul_f32_e32 v76, v78, v76
	v_mul_f32_e32 v74, v74, v76
	v_mul_f32_e32 v76, v79, v77
	v_add_f32_e32 v77, 1.0, v82
	v_rcp_f32_e32 v77, v77
	v_mul_f32_e32 v78, 0xbfb8aa3b, v69
	v_exp_f32_e32 v78, v78
	v_mul_f32_e32 v75, v75, v76
	v_mul_f32_e32 v68, v68, v77
	v_mul_f32_e32 v76, v64, v68
	v_mul_f32_e32 v68, 0xbfb8aa3b, v70
	v_add_f32_e32 v64, 1.0, v78
	v_exp_f32_e32 v68, v68
	v_mul_f32_e32 v77, 0xbfb8aa3b, v71
	v_rcp_f32_e32 v64, v64
	v_exp_f32_e32 v77, v77
	v_add_f32_e32 v68, 1.0, v68
	v_rcp_f32_e32 v68, v68
	v_mul_f32_e32 v64, v69, v64
	v_add_f32_e32 v69, 1.0, v77
	v_rcp_f32_e32 v69, v69
	v_mul_f32_e32 v77, v65, v64
	v_mul_f32_e32 v64, v70, v68
	v_mul_f32_e32 v70, v66, v64
	v_mul_f32_e32 v64, v71, v69
	v_mul_f32_e32 v67, v67, v64
	v_lshl_add_u64 v[68:69], v[80:81], 0, v[112:113]
	v_cvt_pk_bf16_f32 v64, v72, v73
	v_cvt_pk_bf16_f32 v65, v74, v75
	v_cvt_pk_bf16_f32 v66, v76, v77
	v_cvt_pk_bf16_f32 v67, v70, v67
	global_store_dwordx4 v[68:69], v[64:67], off sc0 sc1
	s_nop 1
	v_mul_f32_e32 v64, 0xbfb8aa3b, v60
	v_exp_f32_e32 v64, v64
	v_mul_f32_e32 v65, 0xbfb8aa3b, v61
	v_exp_f32_e32 v65, v65
	v_add_u32_e32 v66, 0x80, v154
	v_add_f32_e32 v64, 1.0, v64
	v_rcp_f32_e32 v67, v64
	v_add_f32_e32 v64, 1.0, v65
	v_rcp_f32_e32 v68, v64
	v_mad_i64_i32 v[64:65], s[36:37], v66, s59, v[146:147]
	v_mul_f32_e32 v60, v60, v67
	v_mul_f32_e32 v56, v56, v60
	v_mul_f32_e32 v60, v61, v68
	v_mul_f32_e32 v61, 0xbfb8aa3b, v62
	v_exp_f32_e32 v61, v61
	v_mul_f32_e32 v66, 0xbfb8aa3b, v63
	v_exp_f32_e32 v66, v66
	v_mul_f32_e32 v57, v57, v60
	v_add_f32_e32 v60, 1.0, v61
	v_rcp_f32_e32 v60, v60
	v_add_f32_e32 v61, 1.0, v66
	v_mul_f32_e32 v66, 0xbfb8aa3b, v52
	v_rcp_f32_e32 v61, v61
	v_exp_f32_e32 v66, v66
	v_mul_f32_e32 v60, v62, v60
	v_mul_f32_e32 v58, v58, v60
	v_mul_f32_e32 v60, v63, v61
	v_add_f32_e32 v61, 1.0, v66
	v_rcp_f32_e32 v61, v61
	v_mul_f32_e32 v62, 0xbfb8aa3b, v53
	v_exp_f32_e32 v62, v62
	v_mul_f32_e32 v59, v59, v60
	v_mul_f32_e32 v52, v52, v61
	v_mul_f32_e32 v60, v48, v52
	v_mul_f32_e32 v52, 0xbfb8aa3b, v54
	v_add_f32_e32 v48, 1.0, v62
	v_exp_f32_e32 v52, v52
	v_mul_f32_e32 v61, 0xbfb8aa3b, v55
	v_rcp_f32_e32 v48, v48
	v_exp_f32_e32 v61, v61
	v_add_f32_e32 v52, 1.0, v52
	v_rcp_f32_e32 v52, v52
	v_mul_f32_e32 v48, v53, v48
	v_add_f32_e32 v53, 1.0, v61
	v_rcp_f32_e32 v53, v53
	v_mul_f32_e32 v61, v49, v48
	v_mul_f32_e32 v48, v54, v52
	v_mul_f32_e32 v54, v50, v48
	v_mul_f32_e32 v48, v55, v53
	v_mul_f32_e32 v51, v51, v48
	v_lshl_add_u64 v[52:53], v[64:65], 0, v[112:113]
	v_cvt_pk_bf16_f32 v48, v56, v57
	v_cvt_pk_bf16_f32 v49, v58, v59
	v_cvt_pk_bf16_f32 v50, v60, v61
	v_cvt_pk_bf16_f32 v51, v54, v51
	global_store_dwordx4 v[52:53], v[48:51], off sc0 sc1
	s_nop 1
	v_mul_f32_e32 v48, 0xbfb8aa3b, v44
	v_exp_f32_e32 v48, v48
	v_mul_f32_e32 v49, 0xbfb8aa3b, v45
	v_exp_f32_e32 v49, v49
	v_add_u32_e32 v50, 0x90, v154
	v_add_f32_e32 v48, 1.0, v48
	v_rcp_f32_e32 v51, v48
	v_add_f32_e32 v48, 1.0, v49
	v_rcp_f32_e32 v52, v48
	v_mad_i64_i32 v[48:49], s[36:37], v50, s59, v[146:147]
	v_mul_f32_e32 v44, v44, v51
	v_mul_f32_e32 v40, v40, v44
	v_mul_f32_e32 v44, v45, v52
	v_mul_f32_e32 v45, 0xbfb8aa3b, v46
	v_exp_f32_e32 v45, v45
	v_mul_f32_e32 v50, 0xbfb8aa3b, v47
	v_exp_f32_e32 v50, v50
	v_mul_f32_e32 v41, v41, v44
	v_add_f32_e32 v44, 1.0, v45
	v_rcp_f32_e32 v44, v44
	v_add_f32_e32 v45, 1.0, v50
	v_mul_f32_e32 v50, 0xbfb8aa3b, v36
	v_rcp_f32_e32 v45, v45
	v_exp_f32_e32 v50, v50
	v_mul_f32_e32 v44, v46, v44
	v_mul_f32_e32 v42, v42, v44
	v_mul_f32_e32 v44, v47, v45
	v_add_f32_e32 v45, 1.0, v50
	v_rcp_f32_e32 v45, v45
	v_mul_f32_e32 v46, 0xbfb8aa3b, v37
	v_exp_f32_e32 v46, v46
; __device__ __forceinline__ unsigned cvt_pk_bf16(float lo, float hi) { unsigned r; asm volatile("v_cvt_pk_bf16_f32 %0, %1, %2" : "=v"(r) : "v"(lo), "v"(hi)); return r; }
; #define PG8_BAR __builtin_amdgcn_s_barrier()
; template <class Epi, class Sched, bool ALIGN_EPI = false, bool SP2 = false>
; __device__ __forceinline__ void gemm_phase(PG8_LAS unsigned char* lds, const Gemm g, const Sched& S, const Epi& E) {
;     ...
;         if (!has_next) break;
; #pragma unroll
;         for (int a = 0; a < 2; ++a)
; #pragma unroll
;             for (int b = 0; b < 2; ++b)
; #pragma unroll
;                 for (int m = 0; m < 4; ++m)
; #pragma unroll
;                     for (int n = 0; n < 2; ++n) acc[a][b][m][n] = (f32x4){0.f, 0.f, 0.f, 0.f};
;         cur = nxt; cA = nA; cB = nB; ++ui;
;         if constexpr (ALIGN_EPI) { if (wr == 1) PG8_BAR; }
;     __device__ __forceinline__ void operator()(const f32x4 (&acc)[2][2][4][2], const Unit& u, int wr, int wc, int fr, int fq) const {
;         const int row0 = u.pm * BM + wr * 64 + fr, col0 = u.pn * 128 + wc * 32 + 8 * fq;
; #pragma unroll
;         for (int ai = 0; ai < 2; ++ai)
; #pragma unroll
;             for (int m = 0; m < 4; ++m) {
;                 bf16_t* rowp = O + (size_t)(row0 + ai * HALF + m * 16) * ldc + col0;
;                 float h[8];
; #pragma unroll
;                 for (int n = 0; n < 2; ++n)
; #pragma unroll
;                     for (int e = 0; e < 4; ++e) { const float g = acc[ai][0][m][n][e], up = acc[ai][1][m][n][e]; h[4 * n + e] = g * __builtin_amdgcn_rcpf(1.f + __expf(-g)) * up; }
;                 u32x4 w; w.x = cvt_pk_bf16(h[0], h[1]); w.y = cvt_pk_bf16(h[2], h[3]); w.z = cvt_pk_bf16(h[4], h[5]); w.w = cvt_pk_bf16(h[6], h[7]);
;                 *(u32x4*)rowp = w;
;             }
;     }
	v_mul_f32_e32 v43, v43, v44
	v_mul_f32_e32 v36, v36, v45
	v_mul_f32_e32 v44, v32, v36
	v_mul_f32_e32 v36, 0xbfb8aa3b, v38
	v_add_f32_e32 v32, 1.0, v46
	v_exp_f32_e32 v36, v36
	v_mul_f32_e32 v45, 0xbfb8aa3b, v39
	v_rcp_f32_e32 v32, v32
	v_exp_f32_e32 v45, v45
	v_add_f32_e32 v36, 1.0, v36
	v_rcp_f32_e32 v36, v36
	v_mul_f32_e32 v32, v37, v32
	v_add_f32_e32 v37, 1.0, v45
	v_rcp_f32_e32 v37, v37
	v_mul_f32_e32 v45, v33, v32
	v_mul_f32_e32 v32, v38, v36
	v_mul_f32_e32 v38, v34, v32
	v_mul_f32_e32 v32, v39, v37
	v_mul_f32_e32 v35, v35, v32
	v_lshl_add_u64 v[36:37], v[48:49], 0, v[112:113]
	v_cvt_pk_bf16_f32 v32, v40, v41
	v_cvt_pk_bf16_f32 v33, v42, v43
	v_cvt_pk_bf16_f32 v34, v44, v45
	v_cvt_pk_bf16_f32 v35, v38, v35
	global_store_dwordx4 v[36:37], v[32:35], off sc0 sc1
	s_nop 1
	v_mul_f32_e32 v32, 0xbfb8aa3b, v28
	v_exp_f32_e32 v32, v32
	v_mul_f32_e32 v33, 0xbfb8aa3b, v29
	v_exp_f32_e32 v33, v33
	v_add_u32_e32 v34, 0xa0, v154
	v_add_f32_e32 v32, 1.0, v32
	v_rcp_f32_e32 v35, v32
	v_add_f32_e32 v32, 1.0, v33
	v_rcp_f32_e32 v36, v32
	v_mad_i64_i32 v[32:33], s[36:37], v34, s59, v[146:147]
	v_mul_f32_e32 v28, v28, v35
	v_mul_f32_e32 v24, v24, v28
	v_mul_f32_e32 v28, v29, v36
	v_mul_f32_e32 v29, 0xbfb8aa3b, v30
	v_exp_f32_e32 v29, v29
	v_mul_f32_e32 v34, 0xbfb8aa3b, v31
	v_exp_f32_e32 v34, v34
	v_mul_f32_e32 v25, v25, v28
	v_add_f32_e32 v28, 1.0, v29
	v_rcp_f32_e32 v28, v28
	v_add_f32_e32 v29, 1.0, v34
	v_mul_f32_e32 v34, 0xbfb8aa3b, v20
	v_rcp_f32_e32 v29, v29
	v_exp_f32_e32 v34, v34
	v_mul_f32_e32 v28, v30, v28
	v_mul_f32_e32 v26, v26, v28
	v_mul_f32_e32 v28, v31, v29
	v_add_f32_e32 v29, 1.0, v34
	v_rcp_f32_e32 v29, v29
	v_mul_f32_e32 v30, 0xbfb8aa3b, v21
	v_exp_f32_e32 v30, v30
	v_mul_f32_e32 v27, v27, v28
	v_mul_f32_e32 v20, v20, v29
	v_mul_f32_e32 v28, v16, v20
	v_mul_f32_e32 v20, 0xbfb8aa3b, v22
	v_add_f32_e32 v16, 1.0, v30
	v_exp_f32_e32 v20, v20
	v_mul_f32_e32 v29, 0xbfb8aa3b, v23
	v_rcp_f32_e32 v16, v16
	v_exp_f32_e32 v29, v29
	v_add_f32_e32 v20, 1.0, v20
	v_rcp_f32_e32 v20, v20
	v_mul_f32_e32 v16, v21, v16
	v_add_f32_e32 v21, 1.0, v29
	v_rcp_f32_e32 v21, v21
	v_mul_f32_e32 v29, v17, v16
	v_mul_f32_e32 v16, v22, v20
	v_mul_f32_e32 v22, v18, v16
	v_mul_f32_e32 v16, v23, v21
	v_mul_f32_e32 v19, v19, v16
	v_lshl_add_u64 v[20:21], v[32:33], 0, v[112:113]
	v_cvt_pk_bf16_f32 v16, v24, v25
	v_cvt_pk_bf16_f32 v17, v26, v27
	v_cvt_pk_bf16_f32 v18, v28, v29
	v_cvt_pk_bf16_f32 v19, v22, v19
	global_store_dwordx4 v[20:21], v[16:19], off sc0 sc1
	s_nop 1
	v_mul_f32_e32 v16, 0xbfb8aa3b, v12
	v_exp_f32_e32 v16, v16
	v_mul_f32_e32 v17, 0xbfb8aa3b, v13
	v_exp_f32_e32 v17, v17
	v_add_u32_e32 v18, 0xb0, v154
	v_add_f32_e32 v16, 1.0, v16
	v_rcp_f32_e32 v19, v16
	v_add_f32_e32 v16, 1.0, v17
	v_rcp_f32_e32 v20, v16
	v_mad_i64_i32 v[16:17], s[36:37], v18, s59, v[146:147]
	v_mul_f32_e32 v12, v12, v19
	v_mul_f32_e32 v8, v8, v12
	v_mul_f32_e32 v12, v13, v20
	v_mul_f32_e32 v13, 0xbfb8aa3b, v14
	v_exp_f32_e32 v13, v13
	v_mul_f32_e32 v18, 0xbfb8aa3b, v15
	v_exp_f32_e32 v18, v18
	v_mul_f32_e32 v9, v9, v12
	v_add_f32_e32 v12, 1.0, v13
	v_rcp_f32_e32 v12, v12
	v_add_f32_e32 v13, 1.0, v18
	v_mul_f32_e32 v18, 0xbfb8aa3b, v4
	v_rcp_f32_e32 v13, v13
	v_exp_f32_e32 v18, v18
	v_mul_f32_e32 v12, v14, v12
	v_mul_f32_e32 v10, v10, v12
	v_mul_f32_e32 v12, v15, v13
	v_add_f32_e32 v13, 1.0, v18
	v_rcp_f32_e32 v13, v13
	v_mul_f32_e32 v14, 0xbfb8aa3b, v5
	v_exp_f32_e32 v14, v14
	v_mul_f32_e32 v11, v11, v12
	v_mul_f32_e32 v4, v4, v13
	v_mul_f32_e32 v12, v0, v4
	v_mul_f32_e32 v4, 0xbfb8aa3b, v6
	v_add_f32_e32 v0, 1.0, v14
	v_exp_f32_e32 v4, v4
	v_mul_f32_e32 v13, 0xbfb8aa3b, v7
	v_rcp_f32_e32 v0, v0
	v_exp_f32_e32 v13, v13
	v_add_f32_e32 v4, 1.0, v4
	v_rcp_f32_e32 v4, v4
	v_mul_f32_e32 v0, v5, v0
	v_add_f32_e32 v5, 1.0, v13
	v_rcp_f32_e32 v5, v5
	v_mul_f32_e32 v13, v1, v0
	v_mul_f32_e32 v0, v6, v4
	v_mul_f32_e32 v6, v2, v0
	v_mul_f32_e32 v0, v7, v5
	v_mul_f32_e32 v3, v3, v0
	v_lshl_add_u64 v[4:5], v[16:17], 0, v[112:113]
	v_cvt_pk_bf16_f32 v0, v8, v9
	v_cvt_pk_bf16_f32 v1, v10, v11
	v_cvt_pk_bf16_f32 v2, v12, v13
	v_cvt_pk_bf16_f32 v3, v6, v3
	global_store_dwordx4 v[4:5], v[0:3], off sc0 sc1
	s_cbranch_vccnz .LBB0_1397
	s_andn2_b64 vcc, exec, s[14:15]
	s_cbranch_vccnz .LBB0_1396
	s_barrier
	s_branch .LBB0_1396

;     __host__ __device__ bool next(int i, Unit& u) const {
;         const long L = (long)i * G + c; if (L >= nwg) return false;
;         int wgid = (int)L; { const int q = nwg / NXCD, r = nwg % NXCD, xcd = wgid % NXCD, off = wgid / NXCD; wgid = (xcd < r ? xcd * (q + 1) : r * (q + 1) + (xcd - r) * q) + off; }
;         const int nig = WGM * nN, gid = wgid / nig, fm = gid * WGM, gsz = (nM - fm) < WGM ? (nM - fm) : WGM;
;         u.pm = fm + ((wgid % nig) % gsz); u.pn = (wgid % nig) / gsz; return true;
;     }
; __global__ void __launch_bounds__(NTHREADS, 2) mega_fwd(Args a_unused) {
;     ...
;     { int Kq = FF; asm volatile("" : "+s"(Kq)); pg8::Gemm g{HFF, Wd2, M, D, Kq}; pg8::StaticOrder S; S.init(M, D, G, bx); pg8::EpiResidLn<false> E{XOUT, XOUT, mod + 8 * D, 0.5f, ap->in[4] + 2 * D, ap->in[5] + 2 * D, mod, mod, U2, {(unsigned*)(ws + WS_XCH), (unsigned*)(ws + WS_CTL) + (16384 * 2 + 16384) / 4, (unsigned*)(ws + WS_CTL) + 15360 / 4, 4, LN_EPS, 0x780u}};
;       pg8::gemm_phase<pg8::EpiResidLn<false>, pg8::StaticOrder, false, true>(lds, g, S, E); }
.LBB0_1465:
	s_or_b64 exec, exec, s[6:7]
	s_waitcnt lgkmcnt(0)
	s_barrier
	s_and_b64 vcc, exec, s[4:5]
	v_mov_b64_e32 v[4:5], s[0:1]
	global_load_dwordx2 v[0:1], v[4:5], off offset:200
	s_movk_i32 s0, 0xb00
	s_waitcnt vmcnt(0) lgkmcnt(0)
	v_readfirstlane_b32 s9, v1
	v_readfirstlane_b32 s8, v0
	global_load_dwordx2 v[136:137], v[4:5], off offset:192
	global_load_dwordx4 v[0:3], v[4:5], off offset:32
	s_nop 0
	v_readfirstlane_b32 s40, v144
	s_cbranch_vccnz .LBB0_1531
	s_ashr_i32 s43, s2, 31
	s_lshr_b32 s1, s43, 29
	s_add_i32 s3, s2, s1
	s_and_b32 s1, s3, -8
	s_sub_i32 s1, s2, s1
	s_cmp_gt_i32 s1, -1
	s_cbranch_scc0 .LBB0_1468
	s_lshl_b32 s6, s1, 5
	s_ashr_i32 s4, s3, 3
	s_cbranch_execz .LBB0_1469
	s_branch .LBB0_1470

; #define PG8_LAS __attribute__((address_space(3)))
;     __device__ __forceinline__ void fused(f32x4 (&acc)[2][2][4][2], const Unit& u, int wr, int wc, int fr, int fq, PG8_LAS unsigned char* lds, int wid, int lane) const {
;         typedef float f32x2v __attribute__((ext_vector_type(2))); typedef unsigned u32x2v __attribute__((ext_vector_type(2)));
;         const PG8_LAS f32x2v* S = (const PG8_LAS f32x2v*)(lds + 8192);
;         const int col0 = u.pn * BM + wc * 32 + 4 * fq; const int b = (u.pm * BM) >> 13; const size_t mo = (size_t)b * 9216;
; #pragma unroll
;         for (int bj = 0; bj < 2; ++bj)
; #pragma unroll
;             for (int n = 0; n < 2; ++n) { const f32x4 gv = (*(const f32x4*)(gate + mo + col0 + bj * HALF + n * 16) + 1.0f) * coef;
; #pragma unroll
;                 for (int ai = 0; ai < 2; ++ai)
; #pragma unroll
;                     for (int m = 0; m < 4; ++m) acc[ai][bj][m][n] = acc[ai][bj][m][n] * gv; }
; #pragma unroll
;         for (int ai = 0; ai < 2; ++ai)
; #pragma unroll
;             for (int m = 0; m < 4; ++m) { const size_t off = (size_t)(u.pm * BM + ai * HALF + wr * 64 + m * 16 + fr) * 1024 + col0;
; #pragma unroll
;                 for (int bj = 0; bj < 2; ++bj)
; #pragma unroll
;                     for (int n = 0; n < 2; ++n) { const f32x4 xv = *(const f32x4*)(xin + off + bj * HALF + n * 16); acc[ai][bj][m][n] = xv * ALPHA_ + acc[ai][bj][m][n]; }
;                 asm volatile("" : "+v"(acc[ai][0][m][0]), "+v"(acc[ai][0][m][1]), "+v"(acc[ai][1][m][0]), "+v"(acc[ai][1][m][1]));
;                 if (m & 1) asm volatile("" ::: "memory"); }
.LBB0_1491:
	s_lshl_b32 s0, s42, 5
	s_lshl_b32 s1, s10, 8
	s_or_b32 s0, s1, s0
	v_lshrrev_b32_e32 v4, 2, v144
	v_and_or_b32 v138, v4, 12, s0
	s_ashr_i32 s0, s41, 5
	s_mul_hi_i32 s1, s0, 0x9000
	s_mul_i32 s0, s0, 0x9000
	v_ashrrev_i32_e32 v139, 31, v138
	s_add_u32 s0, s8, s0
	s_addc_u32 s1, s9, s1
	v_lshlrev_b64 v[140:141], 2, v[138:139]
	v_lshl_add_u64 v[142:143], s[0:1], 0, v[140:141]
	s_mov_b32 s2, 0x8000
	s_mov_b64 s[0:1], 0x8000
	v_add_co_u32_e32 v4, vcc, s2, v142
	s_lshl_b32 s16, s41, 8
	s_nop 0
	v_addc_co_u32_e32 v5, vcc, 0, v143, vcc
	v_lshl_add_u64 v[142:143], v[142:143], 0, s[0:1]
	s_add_i32 s0, s16, s53
	v_or_b32_e32 v160, s0, v163
	v_ashrrev_i32_e32 v161, 31, v160
	s_barrier
	global_load_dwordx4 v[4:7], v[4:5], off
	s_nop 0
	global_load_dwordx4 v[146:149], v[142:143], off offset:64
	global_load_dwordx4 v[150:153], v[142:143], off offset:512
	global_load_dwordx4 v[154:157], v[142:143], off offset:576
	v_lshlrev_b64 v[142:143], 12, v[160:161]
	s_waitcnt vmcnt(0) lgkmcnt(0)
	v_lshl_add_u64 v[142:143], v[136:137], 0, v[142:143]
	v_lshl_add_u64 v[142:143], v[142:143], 0, v[140:141]
	global_load_dwordx4 v[164:167], v[142:143], off
	global_load_dwordx4 v[168:171], v[142:143], off offset:64
	global_load_dwordx4 v[172:175], v[142:143], off offset:512
	global_load_dwordx4 v[176:179], v[142:143], off offset:576
	v_or_b32_e32 v142, 16, v160
	v_ashrrev_i32_e32 v143, 31, v142
	v_lshlrev_b64 v[142:143], 12, v[142:143]
	s_mov_b32 s0, 0x3f9837f0
	v_lshl_add_u64 v[142:143], v[136:137], 0, v[142:143]
	v_lshl_add_u64 v[180:181], v[142:143], 0, v[140:141]
	v_pk_add_f32 v[148:149], v[148:149], 1.0 op_sel_hi:[1,0]
	v_pk_add_f32 v[6:7], v[6:7], 1.0 op_sel_hi:[1,0]
	v_pk_add_f32 v[4:5], v[4:5], 1.0 op_sel_hi:[1,0]
	v_pk_add_f32 v[158:159], v[146:147], 1.0 op_sel_hi:[1,0]
	v_pk_add_f32 v[152:153], v[152:153], 1.0 op_sel_hi:[1,0]
	v_pk_add_f32 v[182:183], v[150:151], 1.0 op_sel_hi:[1,0]
	v_pk_add_f32 v[156:157], v[156:157], 1.0 op_sel_hi:[1,0]
	v_pk_add_f32 v[184:185], v[154:155], 1.0 op_sel_hi:[1,0]
	v_pk_mul_f32 v[142:143], v[6:7], 0.5 op_sel_hi:[1,0]
	v_pk_mul_f32 v[146:147], v[4:5], 0.5 op_sel_hi:[1,0]
	v_pk_mul_f32 v[148:149], v[148:149], 0.5 op_sel_hi:[1,0]
	v_pk_mul_f32 v[150:151], v[158:159], 0.5 op_sel_hi:[1,0]
	v_pk_mul_f32 v[152:153], v[152:153], 0.5 op_sel_hi:[1,0]
	v_pk_mul_f32 v[154:155], v[182:183], 0.5 op_sel_hi:[1,0]
	v_pk_mul_f32 v[156:157], v[156:157], 0.5 op_sel_hi:[1,0]
	v_pk_mul_f32 v[158:159], v[184:185], 0.5 op_sel_hi:[1,0]
	s_waitcnt vmcnt(0) lgkmcnt(0)
	v_pk_mul_f32 v[4:5], v[166:167], s[0:1] op_sel_hi:[1,0]
	v_pk_mul_f32 v[6:7], v[164:165], s[0:1] op_sel_hi:[1,0]
	v_pk_mul_f32 v[164:165], v[170:171], s[0:1] op_sel_hi:[1,0]
	v_pk_mul_f32 v[166:167], v[168:169], s[0:1] op_sel_hi:[1,0]
	v_pk_mul_f32 v[168:169], v[174:175], s[0:1] op_sel_hi:[1,0]
	v_pk_mul_f32 v[170:171], v[172:173], s[0:1] op_sel_hi:[1,0]
	v_pk_mul_f32 v[172:173], v[178:179], s[0:1] op_sel_hi:[1,0]
	v_pk_mul_f32 v[174:175], v[176:177], s[0:1] op_sel_hi:[1,0]
	v_pk_fma_f32 v[82:83], v[82:83], v[142:143], v[4:5]
	v_pk_fma_f32 v[80:81], v[80:81], v[146:147], v[6:7]
	v_pk_fma_f32 v[46:47], v[46:47], v[148:149], v[164:165]
	v_pk_fma_f32 v[44:45], v[44:45], v[150:151], v[166:167]
	v_pk_fma_f32 v[22:23], v[22:23], v[152:153], v[168:169]
	v_pk_fma_f32 v[20:21], v[20:21], v[154:155], v[170:171]
	v_pk_fma_f32 v[6:7], v[134:135], v[156:157], v[172:173]
	v_pk_fma_f32 v[4:5], v[132:133], v[158:159], v[174:175]
	v_or_b32_e32 v176, 32, v160
	global_load_dwordx4 v[132:135], v[180:181], off
	global_load_dwordx4 v[164:167], v[180:181], off offset:64
	global_load_dwordx4 v[168:171], v[180:181], off offset:512
	global_load_dwordx4 v[172:175], v[180:181], off offset:576
	v_ashrrev_i32_e32 v177, 31, v176
	v_lshlrev_b64 v[176:177], 12, v[176:177]
	v_lshl_add_u64 v[176:177], v[136:137], 0, v[176:177]
	v_lshl_add_u64 v[176:177], v[176:177], 0, v[140:141]
	v_mov_b32_e32 v161, v82
	v_mov_b32_e32 v180, v80
	v_mov_b32_e32 v181, v83
	v_mov_b32_e32 v182, v45
	v_mov_b32_e32 v183, v46
	v_mov_b32_e32 v184, v44
	v_mov_b32_e32 v185, v47
	v_add_f32_e32 v187, v22, v23
	v_mov_b32_e32 v186, v5
	v_mov_b32_e32 v188, v7
	s_waitcnt vmcnt(0) lgkmcnt(0)
	v_pk_mul_f32 v[134:135], v[134:135], s[0:1] op_sel_hi:[1,0]
	v_pk_mul_f32 v[132:133], v[132:133], s[0:1] op_sel_hi:[1,0]
	v_pk_mul_f32 v[166:167], v[166:167], s[0:1] op_sel_hi:[1,0]
	v_pk_mul_f32 v[164:165], v[164:165], s[0:1] op_sel_hi:[1,0]
	v_pk_mul_f32 v[170:171], v[170:171], s[0:1] op_sel_hi:[1,0]
	v_pk_mul_f32 v[168:169], v[168:169], s[0:1] op_sel_hi:[1,0]
	v_pk_mul_f32 v[174:175], v[174:175], s[0:1] op_sel_hi:[1,0]
	v_pk_mul_f32 v[172:173], v[172:173], s[0:1] op_sel_hi:[1,0]
	v_pk_fma_f32 v[90:91], v[90:91], v[142:143], v[134:135]
	v_pk_fma_f32 v[88:89], v[88:89], v[146:147], v[132:133]
	v_pk_fma_f32 v[58:59], v[58:59], v[148:149], v[166:167]
	v_pk_fma_f32 v[56:57], v[56:57], v[150:151], v[164:165]
	v_pk_fma_f32 v[30:31], v[30:31], v[152:153], v[170:171]
	v_pk_fma_f32 v[28:29], v[28:29], v[154:155], v[168:169]
	v_pk_fma_f32 v[10:11], v[10:11], v[156:157], v[174:175]
	v_pk_fma_f32 v[8:9], v[8:9], v[158:159], v[172:173]
	s_nop 0
	global_load_dwordx4 v[132:135], v[176:177], off
	global_load_dwordx4 v[164:167], v[176:177], off offset:64
	global_load_dwordx4 v[168:171], v[176:177], off offset:512
	global_load_dwordx4 v[172:175], v[176:177], off offset:576
	v_or_b32_e32 v176, 48, v160
	v_ashrrev_i32_e32 v177, 31, v176
	v_lshlrev_b64 v[176:177], 12, v[176:177]
	v_lshl_add_u64 v[176:177], v[136:137], 0, v[176:177]
	v_lshl_add_u64 v[176:177], v[176:177], 0, v[140:141]
	s_waitcnt vmcnt(0) lgkmcnt(0)
;     __device__ __forceinline__ bool run(const f32x4 (&v)[2][2][4][2], const Unit& u, int wr, int wc, int fr, int fq, PG8_LAS unsigned char* lds, int wid, int lane) const {
;     ...
;                 float s = 0.f;
; #pragma unroll
;                 for (int bj = 0; bj < 2; ++bj)
; #pragma unroll
;                     for (int n = 0; n < 2; ++n) { const f32x4 x = v[ai][bj][m][n]; s += (x[0] + x[1]) + (x[2] + x[3]); }
;                 s += __shfl_xor(s, 16); s += __shfl_xor(s, 32);
;     __device__ __forceinline__ void fused(f32x4 (&acc)[2][2][4][2], const Unit& u, int wr, int wc, int fr, int fq, PG8_LAS unsigned char* lds, int wid, int lane) const {
;     ...
;         for (int ai = 0; ai < 2; ++ai)
; #pragma unroll
;             for (int m = 0; m < 4; ++m) { const size_t off = (size_t)(u.pm * BM + ai * HALF + wr * 64 + m * 16 + fr) * 1024 + col0;
; #pragma unroll
;                 for (int bj = 0; bj < 2; ++bj)
; #pragma unroll
;                     for (int n = 0; n < 2; ++n) { const f32x4 xv = *(const f32x4*)(xin + off + bj * HALF + n * 16); acc[ai][bj][m][n] = xv * ALPHA_ + acc[ai][bj][m][n]; }
;                 asm volatile("" : "+v"(acc[ai][0][m][0]), "+v"(acc[ai][0][m][1]), "+v"(acc[ai][1][m][0]), "+v"(acc[ai][1][m][1]));
;                 if (m & 1) asm volatile("" ::: "memory"); }
	v_pk_mul_f32 v[134:135], v[134:135], s[0:1] op_sel_hi:[1,0]
	v_pk_mul_f32 v[132:133], v[132:133], s[0:1] op_sel_hi:[1,0]
	v_pk_mul_f32 v[166:167], v[166:167], s[0:1] op_sel_hi:[1,0]
	v_pk_mul_f32 v[164:165], v[164:165], s[0:1] op_sel_hi:[1,0]
	v_pk_mul_f32 v[170:171], v[170:171], s[0:1] op_sel_hi:[1,0]
	v_pk_mul_f32 v[168:169], v[168:169], s[0:1] op_sel_hi:[1,0]
	v_pk_mul_f32 v[174:175], v[174:175], s[0:1] op_sel_hi:[1,0]
	v_pk_mul_f32 v[172:173], v[172:173], s[0:1] op_sel_hi:[1,0]
	v_pk_fma_f32 v[102:103], v[102:103], v[142:143], v[134:135]
	v_pk_fma_f32 v[100:101], v[100:101], v[146:147], v[132:133]
	v_pk_fma_f32 v[70:71], v[70:71], v[148:149], v[166:167]
	v_pk_fma_f32 v[68:69], v[68:69], v[150:151], v[164:165]
	v_pk_fma_f32 v[38:39], v[38:39], v[152:153], v[170:171]
	v_pk_fma_f32 v[36:37], v[36:37], v[154:155], v[168:169]
	v_pk_fma_f32 v[14:15], v[14:15], v[156:157], v[174:175]
	v_pk_fma_f32 v[12:13], v[12:13], v[158:159], v[172:173]
	s_nop 0
	global_load_dwordx4 v[132:135], v[176:177], off
	global_load_dwordx4 v[164:167], v[176:177], off offset:64
	global_load_dwordx4 v[168:171], v[176:177], off offset:512
	global_load_dwordx4 v[172:175], v[176:177], off offset:576
	v_add_u32_e32 v176, 0x80, v160
	v_ashrrev_i32_e32 v177, 31, v176
	v_lshlrev_b64 v[176:177], 12, v[176:177]
	v_lshl_add_u64 v[176:177], v[136:137], 0, v[176:177]
	v_lshl_add_u64 v[176:177], v[176:177], 0, v[140:141]
	s_waitcnt vmcnt(0) lgkmcnt(0)
	v_pk_mul_f32 v[134:135], v[134:135], s[0:1] op_sel_hi:[1,0]
	v_pk_mul_f32 v[132:133], v[132:133], s[0:1] op_sel_hi:[1,0]
	v_pk_mul_f32 v[166:167], v[166:167], s[0:1] op_sel_hi:[1,0]
	v_pk_mul_f32 v[164:165], v[164:165], s[0:1] op_sel_hi:[1,0]
	v_pk_mul_f32 v[170:171], v[170:171], s[0:1] op_sel_hi:[1,0]
	v_pk_mul_f32 v[168:169], v[168:169], s[0:1] op_sel_hi:[1,0]
	v_pk_mul_f32 v[174:175], v[174:175], s[0:1] op_sel_hi:[1,0]
	v_pk_mul_f32 v[172:173], v[172:173], s[0:1] op_sel_hi:[1,0]
	v_pk_fma_f32 v[106:107], v[106:107], v[142:143], v[134:135]
	v_pk_fma_f32 v[104:105], v[104:105], v[146:147], v[132:133]
	v_pk_fma_f32 v[74:75], v[74:75], v[148:149], v[166:167]
	v_pk_fma_f32 v[72:73], v[72:73], v[150:151], v[164:165]
	v_pk_fma_f32 v[42:43], v[42:43], v[152:153], v[170:171]
	v_pk_fma_f32 v[40:41], v[40:41], v[154:155], v[168:169]
	v_pk_fma_f32 v[18:19], v[18:19], v[156:157], v[174:175]
	v_pk_fma_f32 v[16:17], v[16:17], v[158:159], v[172:173]
	s_nop 0
	global_load_dwordx4 v[132:135], v[176:177], off
	global_load_dwordx4 v[164:167], v[176:177], off offset:64
	global_load_dwordx4 v[168:171], v[176:177], off offset:512
	global_load_dwordx4 v[172:175], v[176:177], off offset:576
	v_add_u32_e32 v176, 0x90, v160
	v_ashrrev_i32_e32 v177, 31, v176
	v_lshlrev_b64 v[176:177], 12, v[176:177]
	v_lshl_add_u64 v[176:177], v[136:137], 0, v[176:177]
	v_lshl_add_u64 v[176:177], v[176:177], 0, v[140:141]
	s_waitcnt vmcnt(0) lgkmcnt(0)
	v_pk_mul_f32 v[134:135], v[134:135], s[0:1] op_sel_hi:[1,0]
	v_pk_mul_f32 v[132:133], v[132:133], s[0:1] op_sel_hi:[1,0]
	v_pk_mul_f32 v[166:167], v[166:167], s[0:1] op_sel_hi:[1,0]
	v_pk_mul_f32 v[164:165], v[164:165], s[0:1] op_sel_hi:[1,0]
	v_pk_mul_f32 v[170:171], v[170:171], s[0:1] op_sel_hi:[1,0]
	v_pk_mul_f32 v[168:169], v[168:169], s[0:1] op_sel_hi:[1,0]
	v_pk_mul_f32 v[174:175], v[174:175], s[0:1] op_sel_hi:[1,0]
	v_pk_mul_f32 v[172:173], v[172:173], s[0:1] op_sel_hi:[1,0]
	v_pk_fma_f32 v[114:115], v[114:115], v[142:143], v[134:135]
	v_pk_fma_f32 v[112:113], v[112:113], v[146:147], v[132:133]
	v_pk_fma_f32 v[86:87], v[86:87], v[148:149], v[166:167]
	v_pk_fma_f32 v[84:85], v[84:85], v[150:151], v[164:165]
	v_pk_fma_f32 v[54:55], v[54:55], v[152:153], v[170:171]
	v_pk_fma_f32 v[52:53], v[52:53], v[154:155], v[168:169]
	v_pk_fma_f32 v[26:27], v[26:27], v[156:157], v[174:175]
	v_pk_fma_f32 v[24:25], v[24:25], v[158:159], v[172:173]
	s_nop 0
	global_load_dwordx4 v[132:135], v[176:177], off
	global_load_dwordx4 v[164:167], v[176:177], off offset:64
	global_load_dwordx4 v[168:171], v[176:177], off offset:512
	global_load_dwordx4 v[172:175], v[176:177], off offset:576
	v_add_u32_e32 v176, 0xa0, v160
	v_ashrrev_i32_e32 v177, 31, v176
	v_lshlrev_b64 v[176:177], 12, v[176:177]
	v_lshl_add_u64 v[176:177], v[136:137], 0, v[176:177]
	v_lshl_add_u64 v[176:177], v[176:177], 0, v[140:141]
	s_waitcnt vmcnt(0) lgkmcnt(0)
	v_pk_mul_f32 v[134:135], v[134:135], s[0:1] op_sel_hi:[1,0]
	v_pk_mul_f32 v[132:133], v[132:133], s[0:1] op_sel_hi:[1,0]
	v_pk_mul_f32 v[166:167], v[166:167], s[0:1] op_sel_hi:[1,0]
	v_pk_mul_f32 v[164:165], v[164:165], s[0:1] op_sel_hi:[1,0]
	v_pk_mul_f32 v[170:171], v[170:171], s[0:1] op_sel_hi:[1,0]
	v_pk_mul_f32 v[168:169], v[168:169], s[0:1] op_sel_hi:[1,0]
	v_pk_mul_f32 v[174:175], v[174:175], s[0:1] op_sel_hi:[1,0]
	v_pk_mul_f32 v[172:173], v[172:173], s[0:1] op_sel_hi:[1,0]
	v_pk_fma_f32 v[122:123], v[122:123], v[142:143], v[134:135]
	v_pk_fma_f32 v[120:121], v[120:121], v[146:147], v[132:133]
	v_pk_fma_f32 v[98:99], v[98:99], v[148:149], v[166:167]
	v_pk_fma_f32 v[96:97], v[96:97], v[150:151], v[164:165]
	v_pk_fma_f32 v[62:63], v[62:63], v[152:153], v[170:171]
	v_pk_fma_f32 v[60:61], v[60:61], v[154:155], v[168:169]
	v_pk_fma_f32 v[34:35], v[34:35], v[156:157], v[174:175]
	v_pk_fma_f32 v[32:33], v[32:33], v[158:159], v[172:173]
	v_mbcnt_hi_u32_b32 v133, -1, v145
	global_load_dwordx4 v[164:167], v[176:177], off
	global_load_dwordx4 v[168:171], v[176:177], off offset:64
	global_load_dwordx4 v[172:175], v[176:177], off offset:512
	s_nop 0
	global_load_dwordx4 v[176:179], v[176:177], off offset:576
	v_and_b32_e32 v134, 64, v133
	v_add_u32_e32 v139, 64, v134
	v_add_u32_e32 v134, 0xb0, v160
	v_ashrrev_i32_e32 v135, 31, v134
	v_lshlrev_b64 v[134:135], 12, v[134:135]
	v_lshl_add_u64 v[134:135], v[136:137], 0, v[134:135]
	v_lshl_add_u64 v[134:135], v[134:135], 0, v[140:141]
	v_mov_b32_e32 v160, v81
	v_pk_add_f32 v[160:161], v[160:161], v[180:181]
	v_pk_add_f32 v[180:181], v[182:183], v[184:185]
	v_add_f32_e32 v145, v160, v161
	v_pk_add_f32 v[160:161], v[180:181], v[180:181] op_sel_hi:[0,1]
	v_xor_b32_e32 v132, 16, v133
	v_add_f32_e32 v189, 0, v145
	v_mov_b32_e32 v160, v6
	v_cmp_lt_i32_e32 vcc, v132, v139
	v_pk_add_f32 v[160:161], v[160:161], v[188:189]
	v_xor_b32_e32 v145, 32, v133
	v_cndmask_b32_e32 v132, v133, v132, vcc
	v_lshlrev_b32_e32 v132, 2, v132
	v_cmp_lt_i32_e32 vcc, v145, v139
	s_waitcnt vmcnt(0) lgkmcnt(0)
;     __device__ __forceinline__ bool run(const f32x4 (&v)[2][2][4][2], const Unit& u, int wr, int wc, int fr, int fq, PG8_LAS unsigned char* lds, int wid, int lane) const {
;     ...
;                 float s = 0.f;
; #pragma unroll
;                 for (int bj = 0; bj < 2; ++bj)
; #pragma unroll
;                     for (int n = 0; n < 2; ++n) { const f32x4 x = v[ai][bj][m][n]; s += (x[0] + x[1]) + (x[2] + x[3]); }
;                 s += __shfl_xor(s, 16); s += __shfl_xor(s, 32);
;                 const float mw = s * (1.0f / 64.0f); float q = 0.f;
; #pragma unroll
;                 for (int bj = 0; bj < 2; ++bj)
; #pragma unroll
;                     for (int n = 0; n < 2; ++n) { const f32x4 d = v[ai][bj][m][n] - mw; q += (d[0] * d[0] + d[1] * d[1]) + (d[2] * d[2] + d[3] * d[3]); }
;                 q += __shfl_xor(q, 16); q += __shfl_xor(q, 32);
;                 if (fq == 0) P[(ai * HALF + wr * 64 + m * 16 + fr) * 4 + wc] = (f32x2v){mw, q};
;     __device__ __forceinline__ void fused(f32x4 (&acc)[2][2][4][2], const Unit& u, int wr, int wc, int fr, int fq, PG8_LAS unsigned char* lds, int wid, int lane) const {
;     ...
;         for (int ai = 0; ai < 2; ++ai)
; #pragma unroll
;             for (int m = 0; m < 4; ++m) { const size_t off = (size_t)(u.pm * BM + ai * HALF + wr * 64 + m * 16 + fr) * 1024 + col0;
; #pragma unroll
;                 for (int bj = 0; bj < 2; ++bj)
; #pragma unroll
;                     for (int n = 0; n < 2; ++n) { const f32x4 xv = *(const f32x4*)(xin + off + bj * HALF + n * 16); acc[ai][bj][m][n] = xv * ALPHA_ + acc[ai][bj][m][n]; }
;                 asm volatile("" : "+v"(acc[ai][0][m][0]), "+v"(acc[ai][0][m][1]), "+v"(acc[ai][1][m][0]), "+v"(acc[ai][1][m][1]));
;                 if (m & 1) asm volatile("" ::: "memory"); }
	v_pk_mul_f32 v[166:167], v[166:167], s[0:1] op_sel_hi:[1,0]
	v_pk_mul_f32 v[164:165], v[164:165], s[0:1] op_sel_hi:[1,0]
	v_pk_mul_f32 v[170:171], v[170:171], s[0:1] op_sel_hi:[1,0]
	v_pk_mul_f32 v[168:169], v[168:169], s[0:1] op_sel_hi:[1,0]
	v_pk_mul_f32 v[174:175], v[174:175], s[0:1] op_sel_hi:[1,0]
	v_pk_mul_f32 v[172:173], v[172:173], s[0:1] op_sel_hi:[1,0]
	v_pk_mul_f32 v[178:179], v[178:179], s[0:1] op_sel_hi:[1,0]
	v_pk_mul_f32 v[176:177], v[176:177], s[0:1] op_sel_hi:[1,0]
	v_pk_fma_f32 v[130:131], v[130:131], v[142:143], v[166:167]
	v_pk_fma_f32 v[128:129], v[128:129], v[146:147], v[164:165]
	v_pk_fma_f32 v[110:111], v[110:111], v[148:149], v[170:171]
	v_pk_fma_f32 v[108:109], v[108:109], v[150:151], v[168:169]
	v_pk_fma_f32 v[78:79], v[78:79], v[152:153], v[174:175]
	v_pk_fma_f32 v[76:77], v[76:77], v[154:155], v[172:173]
	v_pk_fma_f32 v[50:51], v[50:51], v[156:157], v[178:179]
	v_pk_fma_f32 v[48:49], v[48:49], v[158:159], v[176:177]
	v_cndmask_b32_e32 v133, v133, v145, vcc
	global_load_dwordx4 v[164:167], v[134:135], off
	global_load_dwordx4 v[168:171], v[134:135], off offset:64
	global_load_dwordx4 v[172:175], v[134:135], off offset:512
	global_load_dwordx4 v[176:179], v[134:135], off offset:576
	v_add_f32_e32 v135, v20, v21
	v_mov_b32_e32 v134, v4
	v_pk_add_f32 v[134:135], v[134:135], v[186:187]
	v_lshlrev_b32_e32 v133, 2, v133
	v_pk_add_f32 v[134:135], v[134:135], v[160:161]
	s_waitcnt vmcnt(0) lgkmcnt(0)
	v_pk_mul_f32 v[164:165], v[164:165], s[0:1] op_sel_hi:[1,0]
	v_add_f32_e32 v134, v134, v135
	ds_bpermute_b32 v135, v132, v134
	v_pk_mul_f32 v[168:169], v[168:169], s[0:1] op_sel_hi:[1,0]
	v_pk_mul_f32 v[172:173], v[172:173], s[0:1] op_sel_hi:[1,0]
	v_pk_mul_f32 v[176:177], v[176:177], s[0:1] op_sel_hi:[1,0]
	v_pk_fma_f32 v[124:125], v[124:125], v[146:147], v[164:165]
	s_waitcnt lgkmcnt(0)
	v_add_f32_e32 v134, v134, v135
	ds_bpermute_b32 v135, v133, v134
	v_pk_fma_f32 v[116:117], v[116:117], v[150:151], v[168:169]
	v_pk_fma_f32 v[92:93], v[92:93], v[154:155], v[172:173]
	v_pk_fma_f32 v[64:65], v[64:65], v[158:159], v[176:177]
	s_waitcnt lgkmcnt(0)
	v_add_f32_e32 v135, v134, v135
	v_fmamk_f32 v139, v135, 0xbc800000, v83
	v_fmamk_f32 v160, v135, 0xbc800000, v81
	v_fmamk_f32 v180, v135, 0xbc800000, v47
	v_fmamk_f32 v182, v135, 0xbc800000, v45
	v_fmamk_f32 v134, v135, 0xbc800000, v82
	v_fmamk_f32 v145, v135, 0xbc800000, v80
	v_fmamk_f32 v161, v135, 0xbc800000, v46
	v_fmamk_f32 v181, v135, 0xbc800000, v44
	v_fmamk_f32 v184, v135, 0xbc800000, v23
	v_fmamk_f32 v186, v135, 0xbc800000, v21
	v_mul_f32_e32 v160, v160, v160
	v_mul_f32_e32 v139, v139, v139
	v_mul_f32_e32 v182, v182, v182
	v_mul_f32_e32 v180, v180, v180
	v_fmamk_f32 v183, v135, 0xbc800000, v22
	v_fmamk_f32 v185, v135, 0xbc800000, v20
	v_fmamk_f32 v188, v135, 0xbc800000, v7
	v_fmamk_f32 v190, v135, 0xbc800000, v5
	v_mul_f32_e32 v186, v186, v186
	v_mul_f32_e32 v184, v184, v184
	v_fmac_f32_e32 v160, v145, v145
	v_fmac_f32_e32 v139, v134, v134
	v_fmac_f32_e32 v182, v181, v181
	v_fmac_f32_e32 v180, v161, v161
	v_fmamk_f32 v187, v135, 0xbc800000, v6
	v_fmamk_f32 v189, v135, 0xbc800000, v4
	v_mul_f32_e32 v190, v190, v190
	v_mul_f32_e32 v188, v188, v188
	v_fmac_f32_e32 v186, v185, v185
	v_fmac_f32_e32 v184, v183, v183
	v_add_f32_e32 v134, v160, v139
	v_add_f32_e32 v139, v182, v180
	v_fmac_f32_e32 v190, v189, v189
	v_fmac_f32_e32 v188, v187, v187
	v_add_f32_e32 v145, v186, v184
	v_add_f32_e32 v134, v134, v139
	v_add_f32_e32 v160, v190, v188
	v_add_f32_e32 v134, v145, v134
	v_add_f32_e32 v139, v160, v134
	ds_bpermute_b32 v145, v132, v139
	v_pk_mul_f32 v[160:161], v[166:167], s[0:1] op_sel_hi:[1,0]
	v_pk_mul_f32 v[166:167], v[170:171], s[0:1] op_sel_hi:[1,0]
	v_pk_mul_f32 v[170:171], v[174:175], s[0:1] op_sel_hi:[1,0]
	v_pk_mul_f32 v[174:175], v[178:179], s[0:1] op_sel_hi:[1,0]
	s_waitcnt lgkmcnt(0)
	v_add_f32_e32 v139, v139, v145
	ds_bpermute_b32 v145, v133, v139
	v_pk_fma_f32 v[126:127], v[126:127], v[142:143], v[160:161]
	v_pk_fma_f32 v[118:119], v[118:119], v[148:149], v[166:167]
	v_pk_fma_f32 v[94:95], v[94:95], v[152:153], v[170:171]
	v_pk_fma_f32 v[66:67], v[66:67], v[156:157], v[174:175]
	v_and_b32_e32 v134, 63, v144
	s_lshl_b32 s0, s42, 3
	v_cmp_gt_u32_e32 vcc, 16, v134
	s_add_i32 s2, s0, 0
	s_and_saveexec_b64 s[0:1], vcc
	s_cbranch_execz .LBB0_1493
	s_lshl_b32 s4, s3, 11
	s_add_i32 s4, s2, s4
	v_mul_f32_e32 v142, 0x3c800000, v135
	v_lshl_add_u32 v135, v163, 5, s4
	s_waitcnt lgkmcnt(0)
	v_add_f32_e32 v143, v139, v145
	ds_write_b64 v135, v[142:143]

;     __device__ __forceinline__ bool run(const f32x4 (&v)[2][2][4][2], const Unit& u, int wr, int wc, int fr, int fq, PG8_LAS unsigned char* lds, int wid, int lane) const {
;     ...
;         asm volatile("s_waitcnt lgkmcnt(0)" ::: "memory"); __builtin_amdgcn_s_barrier(); asm volatile("" ::: "memory");
;     ...
;         if (blockIdx.x >= 64) { const long long t0_ = clock64(); while (clock64() - t0_ < 60000) __builtin_amdgcn_s_sleep(8); }
;     ...
;         const int row = wid * 32 + (lane & 31);
;         if (lane < 32) {
;             const f32x2v a = P[row * 4 + 0], b = P[row * 4 + 1], c = P[row * 4 + 2], d = P[row * 4 + 3];
;             const float mt = (a.x + b.x + c.x + d.x) * 0.25f;
;             const float da = a.x - mt, db = b.x - mt, dc = c.x - mt, dd = d.x - mt;
;             const float m2 = (a.y + b.y) + (c.y + d.y) + 64.0f * ((da * da + db * db) + (dc * dc + dd * dd));
;             unsigned long long* slot = (unsigned long long*)xbuf + ((size_t)(u.pm * BM + row) * 4 + u.pn);
;             __hip_atomic_store(slot, ((unsigned long long)__float_as_uint(m2) << 32) | __float_as_uint(mt), __ATOMIC_RELAXED, __HIP_MEMORY_SCOPE_AGENT);
;         }
;         asm volatile("s_waitcnt vmcnt(0)" ::: "memory");
;         if (lane == 0) __hip_atomic_fetch_add(cnt + 64 * u.pm, 1u, __ATOMIC_RELAXED, __HIP_MEMORY_SCOPE_AGENT);
.LBB0_1507:
	s_or_b64 exec, exec, s[0:1]
	v_and_b32_e32 v132, 31, v144
	s_waitcnt lgkmcnt(0)
	s_barrier
	v_lshl_or_b32 v139, s11, 5, v132
	s_add_u32 s2, s8, 0x3780000
	v_add_u32_e32 v132, s16, v139
	s_addc_u32 s3, s9, 0
	v_cmp_gt_u32_e64 s[0:1], 32, v134
	s_waitcnt lgkmcnt(0)
	v_ashrrev_i32_e32 v133, 31, v132
	s_and_saveexec_b64 s[4:5], s[0:1]
	s_cbranch_execz .LBB0_1509
	v_lshl_add_u32 v135, v139, 5, 0
	ds_read_b128 v[142:145], v135
	ds_read_b128 v[146:149], v135 offset:16
	s_ashr_i32 s11, s10, 31
	s_waitcnt lgkmcnt(1)
	v_add_f32_e32 v135, v142, v144
	s_waitcnt lgkmcnt(0)
	v_add_f32_e32 v135, v135, v146
	v_add_f32_e32 v135, v135, v148
	v_fmamk_f32 v142, v135, 0xbe800000, v142
	v_fmac_f32_e32 v144, 0xbe800000, v135
	v_fmamk_f32 v146, v135, 0xbe800000, v146
	v_fmac_f32_e32 v148, 0xbe800000, v135
	v_mul_f32_e32 v153, v142, v142
	v_mul_f32_e32 v155, v144, v144
	v_mul_f32_e32 v157, v146, v146
	v_mul_f32_e32 v159, v148, v148
	v_mov_b32_e32 v152, v143
	v_mov_b32_e32 v154, v145
	v_mov_b32_e32 v156, v147
	v_mov_b32_e32 v158, v149
	v_pk_add_f32 v[142:143], v[152:153], v[154:155]
	v_pk_add_f32 v[144:145], v[156:157], v[158:159]
	v_mul_f32_e32 v150, 0x3e800000, v135
	v_pk_add_f32 v[142:143], v[142:143], v[144:145]
	s_nop 0
	v_fmamk_f32 v151, v143, 0x42800000, v142
	v_lshlrev_b64 v[142:143], 5, v[132:133]
	v_lshl_add_u64 v[142:143], s[2:3], 0, v[142:143]
	v_lshl_add_u64 v[142:143], s[10:11], 3, v[142:143]
	global_store_dwordx2 v[142:143], v[150:151], off sc1
.LBB0_1509:
	s_or_b64 exec, exec, s[4:5]
	s_waitcnt vmcnt(0)
	s_add_u32 s12, s8, 0xdc000
	s_addc_u32 s13, s9, 0
	v_cmp_ne_u32_e64 s[6:7], 0, v134
	v_cmp_eq_u32_e64 s[4:5], 0, v134
	s_and_saveexec_b64 s[10:11], s[4:5]
	s_cbranch_execz .LBB0_1511
	s_lshl_b32 s14, s41, 6
	s_ashr_i32 s15, s14, 31
	s_lshl_b64 s[14:15], s[14:15], 2
	s_add_u32 s14, s12, s14
	s_addc_u32 s15, s13, s15
	v_mov_b32_e32 v142, 1
	v_mov_b64_e32 v[134:135], s[14:15]
	global_atomic_add v[134:135], v142, off

;     __device__ __forceinline__ bool run(const f32x4 (&v)[2][2][4][2], const Unit& u, int wr, int wc, int fr, int fq, PG8_LAS unsigned char* lds, int wid, int lane) const {
;     ...
;         if (wid == 0) {
;             bool dead = false; const unsigned long long t0 = __builtin_amdgcn_s_memrealtime(); const unsigned want = 8u * (unsigned)ntn;
;             for (;;) {
;     ...
;                 break;
;     ...
;                 if ((unsigned)__builtin_amdgcn_readfirstlane(__hip_atomic_load(cnt + 64 * u.pm, __ATOMIC_RELAXED, __HIP_MEMORY_SCOPE_AGENT)) >= want) break;
;                 if (__builtin_amdgcn_s_memrealtime() - t0 > 2000000ull) {
;                     if (lane == 0) { unsigned expect = 0u; __hip_atomic_compare_exchange_strong(tmo + 1, &expect, code | (unsigned)(u.pm & 0xff), __ATOMIC_RELAXED, __ATOMIC_RELAXED, __HIP_MEMORY_SCOPE_AGENT);
;                                      __hip_atomic_store(tmo, 1u, __ATOMIC_RELAXED, __HIP_MEMORY_SCOPE_AGENT); }
;                     dead = true; break; }
;                 __builtin_amdgcn_s_sleep(2);
;             }
.LBB0_1515:
	global_load_dword v144, v[134:135], off sc1
	s_mov_b64 s[12:13], -1
	s_waitcnt vmcnt(0) lgkmcnt(0)
	v_readfirstlane_b32 s14, v144
	s_cmp_gt_u32 s14, 31
	s_mov_b64 s[14:15], -1
	s_cbranch_scc1 .LBB0_1514
	s_memrealtime s[12:13]
	s_waitcnt lgkmcnt(0)
	s_sub_u32 s12, s12, s10
	s_subb_u32 s13, s13, s11
	v_cmp_lt_u64_e32 vcc, s[12:13], v[142:143]
	s_cbranch_vccz .LBB0_1513
	s_mov_b64 s[14:15], 0
	s_sleep 2
	s_branch .LBB0_1513

;     __device__ __forceinline__ bool run(const f32x4 (&v)[2][2][4][2], const Unit& u, int wr, int wc, int fr, int fq, PG8_LAS unsigned char* lds, int wid, int lane) const {
;     ...
;                 if ((unsigned)__builtin_amdgcn_readfirstlane(__hip_atomic_load(cnt + 64 * u.pm, __ATOMIC_RELAXED, __HIP_MEMORY_SCOPE_AGENT)) >= want) break;
;                 if (__builtin_amdgcn_s_memrealtime() - t0 > 2000000ull) {
;                     if (lane == 0) { unsigned expect = 0u; __hip_atomic_compare_exchange_strong(tmo + 1, &expect, code | (unsigned)(u.pm & 0xff), __ATOMIC_RELAXED, __ATOMIC_RELAXED, __HIP_MEMORY_SCOPE_AGENT);
;                                      __hip_atomic_store(tmo, 1u, __ATOMIC_RELAXED, __HIP_MEMORY_SCOPE_AGENT); }
;                     dead = true; break; }
;                 __builtin_amdgcn_s_sleep(2);
;             }
;             __builtin_amdgcn_fence(__ATOMIC_ACQUIRE, "agent");
;             if (lane == 0) flag[0] = dead ? 1u : 0u;
.LBB0_1521:
	s_or_saveexec_b64 s[10:11], s[6:7]
	s_mov_b64 s[6:7], 0
	s_xor_b64 exec, exec, s[10:11]
	s_cbranch_execz .LBB0_1523
	s_and_b32 s12, s41, 0x7f
	v_mov_b32_e32 v134, s8
	s_or_b32 s12, s12, 0x780
	v_add_co_u32_e32 v134, vcc, 0xd3000, v134
	v_mov_b32_e32 v135, s9
	s_nop 0
	v_addc_co_u32_e32 v135, vcc, 0, v135, vcc
	v_mov_b32_e32 v142, s12
	v_mov_b32_e32 v143, 0
	global_atomic_cmpswap v[134:135], v[142:143], off offset:3076
	s_mov_b64 s[6:7], exec
	v_mov_b32_e32 v142, 1
	global_store_dword v[134:135], v142, off offset:3072 sc1

;     __device__ __forceinline__ bool run(const f32x4 (&v)[2][2][4][2], const Unit& u, int wr, int wc, int fr, int fq, PG8_LAS unsigned char* lds, int wid, int lane) const {
;     ...
;         asm volatile("s_waitcnt vmcnt(0) lgkmcnt(0)" ::: "memory"); __builtin_amdgcn_s_barrier(); asm volatile("" ::: "memory");
;         const bool bad = flag[0] != 0u;
;         if (lane < 32) {
;             const unsigned long long* slot = (const unsigned long long*)xbuf + (size_t)(u.pm * BM + row) * 4; float mt[4], m2[4]; float ms = 0.f;
; #pragma unroll
;             for (int t = 0; t < 4; ++t) { if (t < ntn) { const unsigned long long w = __hip_atomic_load(slot + t, __ATOMIC_RELAXED, __HIP_MEMORY_SCOPE_AGENT); mt[t] = __uint_as_float((unsigned)w); m2[t] = __uint_as_float((unsigned)(w >> 32)); } else { mt[t] = 0.f; m2[t] = 0.f; } ms += mt[t]; }
;             const float mean = ms / (float)ntn; float q = 0.f;
; #pragma unroll
;             for (int t = 0; t < 4; ++t) if (t < ntn) { const float dm = mt[t] - mean; q += m2[t] + 256.0f * dm * dm; }
;             S[row] = (f32x2v){mean, 1.0f / sqrtf(q / (256.0f * (float)ntn) + eps)};
;     __device__ __forceinline__ void fused(f32x4 (&acc)[2][2][4][2], const Unit& u, int wr, int wc, int fr, int fq, PG8_LAS unsigned char* lds, int wid, int lane) const {
;     ...
; #pragma unroll
;         for (int bj = 0; bj < 2; ++bj)
; #pragma unroll
;             for (int n = 0; n < 2; ++n) {
;                 const int col = col0 + bj * HALF + n * 16;
;                 const f32x4 lg = *(const f32x4*)(lng + col), lb = *(const f32x4*)(lnb + col);
;                 f32x4 sc1 = (f32x4){1.f, 1.f, 1.f, 1.f}, sh = (f32x4){0.f, 0.f, 0.f, 0.f};
;                 if (DO_U) { sc1 = *(const f32x4*)(msc + mo + col) + 1.0f; sh = *(const f32x4*)(msh + mo + col); }
; #pragma unroll
;                 for (int ai = 0; ai < 2; ++ai)
; #pragma unroll
;                     for (int m = 0; m < 4; ++m) { const int r = ai * HALF + wr * 64 + m * 16 + fr; const f32x2v sr = S[r]; const size_t off = (size_t)(u.pm * BM + r) * 1024 + col;
;                         f32x4 y = (acc[ai][bj][m][n] - sr.x) * sr.y * lg + lb; if (bad) y = (f32x4){qnan, qnan, qnan, qnan};
;                         *(f32x4*)(out + off) = y;
;                         if (DO_U) { const f32x4 uu = y * sc1 + sh; u32x2v w; w.x = cvt_pk_bf16(uu[0], uu[1]); w.y = cvt_pk_bf16(uu[2], uu[3]); *(u32x2v*)(U + off) = w; } }
.LBB0_1528:
	s_waitcnt vmcnt(0) lgkmcnt(0)
	s_barrier
	v_mov_b32_e32 v134, 0
	ds_read_b32 v146, v134 offset:10240
	s_and_saveexec_b64 s[4:5], s[0:1]
	s_cbranch_execz .LBB0_1530
	v_lshlrev_b64 v[132:133], 5, v[132:133]
	v_lshl_add_u64 v[132:133], s[2:3], 0, v[132:133]
	global_load_dwordx2 v[134:135], v[132:133], off sc1
	global_load_dwordx2 v[142:143], v[132:133], off offset:8 sc1
	global_load_dwordx2 v[144:145], v[132:133], off offset:16 sc1
	s_nop 0
	global_load_dwordx2 v[132:133], v[132:133], off offset:24 sc1
	v_mov_b32_e32 v147, 0x3727c5ac
	s_mov_b32 s0, 0xf800000
	s_waitcnt vmcnt(0) lgkmcnt(0)
	v_add_f32_e32 v148, 0, v134
	v_add_f32_e32 v148, v148, v142
	v_add_f32_e32 v148, v148, v144
	v_add_f32_e32 v148, v148, v132
	v_fmamk_f32 v134, v148, 0xbe800000, v134
	v_fmamk_f32 v142, v148, 0xbe800000, v142
	v_fmamk_f32 v132, v148, 0xbe800000, v132
	v_mul_f32_e32 v149, 0x43800000, v134
	v_fmamk_f32 v144, v148, 0xbe800000, v144
	v_mul_f32_e32 v150, 0x43800000, v142
	v_mul_f32_e32 v152, 0x43800000, v132
	v_fmac_f32_e32 v135, v134, v149
	v_mul_f32_e32 v151, 0x43800000, v144
	v_fmac_f32_e32 v143, v142, v150
	v_fmac_f32_e32 v133, v132, v152
	v_add_f32_e32 v132, 0, v135
	v_fmac_f32_e32 v145, v144, v151
	v_add_f32_e32 v132, v143, v132
	v_add_f32_e32 v132, v145, v132
	v_add_f32_e32 v132, v133, v132
	v_fmac_f32_e32 v147, 0x3a800000, v132
	v_mul_f32_e32 v132, 0x4f800000, v147
	v_cmp_gt_f32_e32 vcc, s0, v147
	v_mov_b32_e32 v134, 0x260
	s_nop 0
	v_cndmask_b32_e32 v132, v147, v132, vcc
	v_sqrt_f32_e32 v133, v132
	s_nop 0
	v_add_u32_e32 v135, -1, v133
	v_add_u32_e32 v142, 1, v133
	v_fma_f32 v143, -v135, v133, v132
	v_fma_f32 v144, -v142, v133, v132
	v_cmp_ge_f32_e64 s[0:1], 0, v143
	s_nop 1
	v_cndmask_b32_e64 v133, v133, v135, s[0:1]
	v_cmp_lt_f32_e64 s[0:1], 0, v144
	s_nop 1
	v_cndmask_b32_e64 v133, v133, v142, s[0:1]
	v_mul_f32_e32 v135, 0x37800000, v133
	v_cndmask_b32_e32 v133, v133, v135, vcc
	v_cmp_class_f32_e32 vcc, v132, v134
	s_nop 1
	v_cndmask_b32_e32 v133, v133, v132, vcc
	v_div_scale_f32 v134, s[0:1], v133, v133, 1.0
	v_rcp_f32_e32 v135, v134
	v_div_scale_f32 v142, vcc, 1.0, v133, 1.0
	v_mul_f32_e32 v132, 0x3e800000, v148
	v_fma_f32 v143, -v134, v135, 1.0
	v_fmac_f32_e32 v135, v143, v135
	v_mul_f32_e32 v143, v142, v135
	v_fma_f32 v144, -v134, v143, v142
	v_fmac_f32_e32 v143, v144, v135
	v_fma_f32 v134, -v134, v143, v142
	v_div_fmas_f32 v134, v134, v135, v143
	v_div_fixup_f32 v133, v134, v133, 1.0
	v_lshl_add_u32 v134, v139, 3, 0
	ds_write_b64 v134, v[132:133] offset:8192
.LBB0_1530:
	s_or_b64 exec, exec, s[4:5]
	s_mov_b64 s[0:1], 0x2000
	v_lshl_add_u64 v[144:145], v[0:1], 0, s[0:1]
	v_lshl_add_u64 v[142:143], v[2:3], 0, s[0:1]
	s_waitcnt lgkmcnt(0)
	s_barrier
	v_lshl_add_u64 v[0:1], v[144:145], 0, v[140:141]
	v_lshl_add_u64 v[132:133], v[142:143], 0, v[140:141]
	global_load_dwordx4 v[0:3], v[0:1], off
	v_lshl_add_u32 v139, v162, 3, 0
	global_load_dwordx4 v[132:135], v[132:133], off
	ds_read_b64 v[154:155], v139 offset:8192
	v_add_u32_e32 v150, s16, v162
	v_ashrrev_i32_e32 v151, 31, v150
	v_lshlrev_b64 v[148:149], 12, v[150:151]
	v_mov_b32_e32 v152, 0x7fc00000
	s_waitcnt lgkmcnt(0)
	v_sub_f32_e32 v83, v83, v154
	v_sub_f32_e32 v82, v82, v154
	v_sub_f32_e32 v81, v81, v154
	v_sub_f32_e32 v80, v80, v154
	v_pk_mul_f32 v[80:81], v[154:155], v[80:81] op_sel:[1,0]
	v_pk_mul_f32 v[82:83], v[154:155], v[82:83] op_sel:[1,0]
	v_lshl_add_u64 v[148:149], v[136:137], 0, v[148:149]
	v_cmp_eq_u32_e32 vcc, 0, v146
	v_lshl_add_u64 v[148:149], v[148:149], 0, v[140:141]
	v_add_u32_e32 v156, 16, v150
	v_ashrrev_i32_e32 v157, 31, v156
	v_add_u32_e32 v158, 32, v150
	v_ashrrev_i32_e32 v159, 31, v158
	v_add_u32_e32 v160, 48, v150
	v_ashrrev_i32_e32 v161, 31, v160
	v_add_u32_e32 v162, 0x80, v150
	v_ashrrev_i32_e32 v163, 31, v162
	v_add_u32_e32 v164, 0x90, v150
	v_ashrrev_i32_e32 v165, 31, v164
	s_waitcnt vmcnt(0)
	v_pk_fma_f32 v[82:83], v[2:3], v[82:83], v[134:135]
	v_pk_fma_f32 v[80:81], v[0:1], v[80:81], v[132:133]
	v_cndmask_b32_e32 v83, v152, v83, vcc
	v_cndmask_b32_e32 v82, v152, v82, vcc
	v_cndmask_b32_e32 v81, v152, v81, vcc
	v_cndmask_b32_e32 v80, v152, v80, vcc
	global_store_dwordx4 v[148:149], v[80:83], off sc0 sc1
	ds_read_b64 v[80:81], v139 offset:8320
	s_waitcnt lgkmcnt(0)
	v_sub_f32_e32 v89, v89, v80
	v_lshlrev_b64 v[82:83], 12, v[156:157]
	v_lshl_add_u64 v[82:83], v[136:137], 0, v[82:83]
	v_lshl_add_u64 v[146:147], v[82:83], 0, v[140:141]
	v_sub_f32_e32 v83, v91, v80
	v_sub_f32_e32 v82, v90, v80
	v_sub_f32_e32 v88, v88, v80
	v_pk_mul_f32 v[88:89], v[80:81], v[88:89] op_sel:[1,0]
	v_pk_mul_f32 v[80:81], v[80:81], v[82:83] op_sel:[1,0]
	v_pk_fma_f32 v[88:89], v[0:1], v[88:89], v[132:133]
	v_pk_fma_f32 v[80:81], v[2:3], v[80:81], v[134:135]
	s_nop 0
	v_cndmask_b32_e32 v83, v152, v81, vcc
	v_cndmask_b32_e32 v82, v152, v80, vcc
	v_cndmask_b32_e32 v81, v152, v89, vcc
	v_cndmask_b32_e32 v80, v152, v88, vcc
	global_store_dwordx4 v[146:147], v[80:83], off sc0 sc1
	ds_read_b64 v[80:81], v139 offset:8448
	s_waitcnt lgkmcnt(0)
	v_sub_f32_e32 v91, v101, v80
	v_lshlrev_b64 v[82:83], 12, v[158:159]
	v_lshl_add_u64 v[82:83], v[136:137], 0, v[82:83]
	v_lshl_add_u64 v[88:89], v[82:83], 0, v[140:141]
	v_sub_f32_e32 v83, v103, v80
	v_sub_f32_e32 v82, v102, v80
	v_sub_f32_e32 v90, v100, v80
	v_pk_mul_f32 v[90:91], v[80:81], v[90:91] op_sel:[1,0]
	v_pk_mul_f32 v[80:81], v[80:81], v[82:83] op_sel:[1,0]
	v_pk_fma_f32 v[90:91], v[0:1], v[90:91], v[132:133]
	v_pk_fma_f32 v[80:81], v[2:3], v[80:81], v[134:135]
	s_nop 0
	v_cndmask_b32_e32 v83, v152, v81, vcc
	v_cndmask_b32_e32 v82, v152, v80, vcc
	v_cndmask_b32_e32 v81, v152, v91, vcc
	v_cndmask_b32_e32 v80, v152, v90, vcc
	global_store_dwordx4 v[88:89], v[80:83], off sc0 sc1
	ds_read_b64 v[80:81], v139 offset:8576
	s_waitcnt lgkmcnt(0)
; __device__ __forceinline__ unsigned cvt_pk_bf16(float lo, float hi) { unsigned r; asm volatile("v_cvt_pk_bf16_f32 %0, %1, %2" : "=v"(r) : "v"(lo), "v"(hi)); return r; }
;     __device__ __forceinline__ void fused(f32x4 (&acc)[2][2][4][2], const Unit& u, int wr, int wc, int fr, int fq, PG8_LAS unsigned char* lds, int wid, int lane) const {
;     ...
; #pragma unroll
;         for (int bj = 0; bj < 2; ++bj)
; #pragma unroll
;             for (int n = 0; n < 2; ++n) {
;                 const int col = col0 + bj * HALF + n * 16;
;                 const f32x4 lg = *(const f32x4*)(lng + col), lb = *(const f32x4*)(lnb + col);
;                 f32x4 sc1 = (f32x4){1.f, 1.f, 1.f, 1.f}, sh = (f32x4){0.f, 0.f, 0.f, 0.f};
;                 if (DO_U) { sc1 = *(const f32x4*)(msc + mo + col) + 1.0f; sh = *(const f32x4*)(msh + mo + col); }
; #pragma unroll
;                 for (int ai = 0; ai < 2; ++ai)
; #pragma unroll
;                     for (int m = 0; m < 4; ++m) { const int r = ai * HALF + wr * 64 + m * 16 + fr; const f32x2v sr = S[r]; const size_t off = (size_t)(u.pm * BM + r) * 1024 + col;
;                         f32x4 y = (acc[ai][bj][m][n] - sr.x) * sr.y * lg + lb; if (bad) y = (f32x4){qnan, qnan, qnan, qnan};
;                         *(f32x4*)(out + off) = y;
;                         if (DO_U) { const f32x4 uu = y * sc1 + sh; u32x2v w; w.x = cvt_pk_bf16(uu[0], uu[1]); w.y = cvt_pk_bf16(uu[2], uu[3]); *(u32x2v*)(U + off) = w; } }
	v_sub_f32_e32 v91, v107, v80
	v_sub_f32_e32 v90, v106, v80
	v_sub_f32_e32 v101, v105, v80
	v_sub_f32_e32 v100, v104, v80
	v_lshlrev_b64 v[82:83], 12, v[160:161]
	v_pk_mul_f32 v[100:101], v[80:81], v[100:101] op_sel:[1,0]
	v_pk_mul_f32 v[80:81], v[80:81], v[90:91] op_sel:[1,0]
	v_lshl_add_u64 v[82:83], v[136:137], 0, v[82:83]
	v_pk_fma_f32 v[80:81], v[2:3], v[80:81], v[134:135]
	v_pk_fma_f32 v[90:91], v[0:1], v[100:101], v[132:133]
	v_lshl_add_u64 v[82:83], v[82:83], 0, v[140:141]
	v_cndmask_b32_e32 v103, v152, v81, vcc
	v_cndmask_b32_e32 v102, v152, v80, vcc
	v_cndmask_b32_e32 v101, v152, v91, vcc
	v_cndmask_b32_e32 v100, v152, v90, vcc
	global_store_dwordx4 v[82:83], v[100:103], off sc0 sc1
	ds_read_b64 v[90:91], v139 offset:9216
	v_lshlrev_b64 v[80:81], 12, v[162:163]
	v_lshl_add_u64 v[80:81], v[136:137], 0, v[80:81]
	v_lshl_add_u64 v[80:81], v[80:81], 0, v[140:141]
	s_waitcnt lgkmcnt(0)
	v_sub_f32_e32 v101, v115, v90
	v_sub_f32_e32 v100, v114, v90
	v_sub_f32_e32 v103, v113, v90
	v_sub_f32_e32 v102, v112, v90
	v_pk_mul_f32 v[102:103], v[90:91], v[102:103] op_sel:[1,0]
	v_pk_mul_f32 v[90:91], v[90:91], v[100:101] op_sel:[1,0]
	v_pk_fma_f32 v[100:101], v[0:1], v[102:103], v[132:133]
	v_pk_fma_f32 v[90:91], v[2:3], v[90:91], v[134:135]
	v_cndmask_b32_e32 v101, v152, v101, vcc
	v_cndmask_b32_e32 v103, v152, v91, vcc
	v_cndmask_b32_e32 v102, v152, v90, vcc
	v_cndmask_b32_e32 v100, v152, v100, vcc
	global_store_dwordx4 v[80:81], v[100:103], off sc0 sc1
	ds_read_b64 v[100:101], v139 offset:9344
	v_lshlrev_b64 v[90:91], 12, v[164:165]
	v_lshl_add_u64 v[90:91], v[136:137], 0, v[90:91]
	v_lshl_add_u64 v[90:91], v[90:91], 0, v[140:141]
	s_waitcnt lgkmcnt(0)
	v_sub_f32_e32 v103, v123, v100
	v_sub_f32_e32 v102, v122, v100
	v_sub_f32_e32 v105, v121, v100
	v_sub_f32_e32 v104, v120, v100
	v_pk_mul_f32 v[104:105], v[100:101], v[104:105] op_sel:[1,0]
	v_pk_mul_f32 v[100:101], v[100:101], v[102:103] op_sel:[1,0]
	v_pk_fma_f32 v[104:105], v[0:1], v[104:105], v[132:133]
	v_pk_fma_f32 v[100:101], v[2:3], v[100:101], v[134:135]
	s_nop 0
	v_cndmask_b32_e32 v103, v152, v101, vcc
	v_cndmask_b32_e32 v102, v152, v100, vcc
	v_cndmask_b32_e32 v101, v152, v105, vcc
	v_cndmask_b32_e32 v100, v152, v104, vcc
	global_store_dwordx4 v[90:91], v[100:103], off sc0 sc1
	ds_read_b64 v[100:101], v139 offset:9472
	s_waitcnt lgkmcnt(0)
	v_sub_f32_e32 v105, v129, v100
	v_add_u32_e32 v102, 0xa0, v150
	v_ashrrev_i32_e32 v103, 31, v102
	v_lshlrev_b64 v[102:103], 12, v[102:103]
	v_lshl_add_u64 v[106:107], v[136:137], 0, v[102:103]
	v_sub_f32_e32 v103, v131, v100
	v_sub_f32_e32 v102, v130, v100
	v_sub_f32_e32 v104, v128, v100
	v_pk_mul_f32 v[104:105], v[100:101], v[104:105] op_sel:[1,0]
	v_pk_mul_f32 v[100:101], v[100:101], v[102:103] op_sel:[1,0]
	v_pk_fma_f32 v[102:103], v[0:1], v[104:105], v[132:133]
	v_pk_fma_f32 v[100:101], v[2:3], v[100:101], v[134:135]
	v_cndmask_b32_e32 v103, v152, v103, vcc
	v_cndmask_b32_e32 v105, v152, v101, vcc
	v_cndmask_b32_e32 v104, v152, v100, vcc
	v_cndmask_b32_e32 v102, v152, v102, vcc
	v_lshl_add_u64 v[100:101], v[106:107], 0, v[140:141]
	global_store_dwordx4 v[100:101], v[102:105], off sc0 sc1
	ds_read_b64 v[102:103], v139 offset:9600
	v_add_u32_e32 v106, 0xb0, v150
	v_ashrrev_i32_e32 v107, 31, v106
	s_waitcnt lgkmcnt(0)
	v_sub_f32_e32 v105, v127, v102
	v_sub_f32_e32 v104, v126, v102
	v_sub_f32_e32 v113, v125, v102
	v_sub_f32_e32 v112, v124, v102
	v_pk_mul_f32 v[112:113], v[102:103], v[112:113] op_sel:[1,0]
	v_pk_mul_f32 v[102:103], v[102:103], v[104:105] op_sel:[1,0]
	v_pk_fma_f32 v[0:1], v[0:1], v[112:113], v[132:133]
	v_pk_fma_f32 v[2:3], v[2:3], v[102:103], v[134:135]
	v_cndmask_b32_e32 v103, v152, v1, vcc
	v_cndmask_b32_e32 v104, v152, v2, vcc
	v_cndmask_b32_e32 v102, v152, v0, vcc
	v_lshlrev_b64 v[0:1], 12, v[106:107]
	v_or_b32_e32 v2, 16, v138
	v_cndmask_b32_e32 v105, v152, v3, vcc
	v_lshl_add_u64 v[0:1], v[136:137], 0, v[0:1]
	v_ashrrev_i32_e32 v3, 31, v2
	v_lshl_add_u64 v[0:1], v[0:1], 0, v[140:141]
	v_lshlrev_b64 v[2:3], 2, v[2:3]
	global_store_dwordx4 v[0:1], v[102:105], off sc0 sc1
	s_nop 1
	v_lshl_add_u64 v[102:103], v[144:145], 0, v[2:3]
	v_lshl_add_u64 v[2:3], v[142:143], 0, v[2:3]
	global_load_dwordx4 v[102:105], v[102:103], off
	s_nop 0
	global_load_dwordx4 v[112:115], v[2:3], off
	ds_read_b64 v[2:3], v139 offset:8192
	s_waitcnt lgkmcnt(0)
	v_sub_f32_e32 v47, v47, v2
	v_sub_f32_e32 v46, v46, v2
	v_sub_f32_e32 v45, v45, v2
	v_sub_f32_e32 v44, v44, v2
	v_pk_mul_f32 v[44:45], v[2:3], v[44:45] op_sel:[1,0]
	v_pk_mul_f32 v[2:3], v[2:3], v[46:47] op_sel:[1,0]
	s_waitcnt vmcnt(0)
	v_pk_fma_f32 v[44:45], v[102:103], v[44:45], v[112:113]
	v_pk_fma_f32 v[2:3], v[104:105], v[2:3], v[114:115]
	v_cndmask_b32_e32 v45, v152, v45, vcc
	v_cndmask_b32_e32 v47, v152, v3, vcc
	v_cndmask_b32_e32 v46, v152, v2, vcc
	v_cndmask_b32_e32 v44, v152, v44, vcc
	global_store_dwordx4 v[148:149], v[44:47], off offset:64 sc0 sc1
	ds_read_b64 v[2:3], v139 offset:8320
	s_waitcnt lgkmcnt(0)
	v_sub_f32_e32 v45, v59, v2
	v_sub_f32_e32 v44, v58, v2
	v_sub_f32_e32 v47, v57, v2
	v_sub_f32_e32 v46, v56, v2
	v_pk_mul_f32 v[46:47], v[2:3], v[46:47] op_sel:[1,0]
	v_pk_mul_f32 v[2:3], v[2:3], v[44:45] op_sel:[1,0]
	v_pk_fma_f32 v[44:45], v[102:103], v[46:47], v[112:113]
	v_pk_fma_f32 v[2:3], v[104:105], v[2:3], v[114:115]
	v_cndmask_b32_e32 v45, v152, v45, vcc
	v_cndmask_b32_e32 v47, v152, v3, vcc
	v_cndmask_b32_e32 v46, v152, v2, vcc
	v_cndmask_b32_e32 v44, v152, v44, vcc
	global_store_dwordx4 v[146:147], v[44:47], off offset:64 sc0 sc1
	ds_read_b64 v[2:3], v139 offset:8448
	v_or_b32_e32 v56, 0x80, v138
	v_ashrrev_i32_e32 v57, 31, v56
	s_waitcnt lgkmcnt(0)
; __device__ __forceinline__ unsigned cvt_pk_bf16(float lo, float hi) { unsigned r; asm volatile("v_cvt_pk_bf16_f32 %0, %1, %2" : "=v"(r) : "v"(lo), "v"(hi)); return r; }
;     __device__ __forceinline__ void fused(f32x4 (&acc)[2][2][4][2], const Unit& u, int wr, int wc, int fr, int fq, PG8_LAS unsigned char* lds, int wid, int lane) const {
;     ...
; #pragma unroll
;         for (int bj = 0; bj < 2; ++bj)
; #pragma unroll
;             for (int n = 0; n < 2; ++n) {
;                 const int col = col0 + bj * HALF + n * 16;
;                 const f32x4 lg = *(const f32x4*)(lng + col), lb = *(const f32x4*)(lnb + col);
;                 f32x4 sc1 = (f32x4){1.f, 1.f, 1.f, 1.f}, sh = (f32x4){0.f, 0.f, 0.f, 0.f};
;                 if (DO_U) { sc1 = *(const f32x4*)(msc + mo + col) + 1.0f; sh = *(const f32x4*)(msh + mo + col); }
; #pragma unroll
;                 for (int ai = 0; ai < 2; ++ai)
; #pragma unroll
;                     for (int m = 0; m < 4; ++m) { const int r = ai * HALF + wr * 64 + m * 16 + fr; const f32x2v sr = S[r]; const size_t off = (size_t)(u.pm * BM + r) * 1024 + col;
;                         f32x4 y = (acc[ai][bj][m][n] - sr.x) * sr.y * lg + lb; if (bad) y = (f32x4){qnan, qnan, qnan, qnan};
;                         *(f32x4*)(out + off) = y;
;                         if (DO_U) { const f32x4 uu = y * sc1 + sh; u32x2v w; w.x = cvt_pk_bf16(uu[0], uu[1]); w.y = cvt_pk_bf16(uu[2], uu[3]); *(u32x2v*)(U + off) = w; } }
	v_sub_f32_e32 v45, v71, v2
	v_sub_f32_e32 v44, v70, v2
	v_sub_f32_e32 v47, v69, v2
	v_sub_f32_e32 v46, v68, v2
	v_pk_mul_f32 v[46:47], v[2:3], v[46:47] op_sel:[1,0]
	v_pk_mul_f32 v[2:3], v[2:3], v[44:45] op_sel:[1,0]
	v_pk_fma_f32 v[44:45], v[102:103], v[46:47], v[112:113]
	v_pk_fma_f32 v[2:3], v[104:105], v[2:3], v[114:115]
	v_cndmask_b32_e32 v45, v152, v45, vcc
	v_cndmask_b32_e32 v47, v152, v3, vcc
	v_cndmask_b32_e32 v46, v152, v2, vcc
	v_cndmask_b32_e32 v44, v152, v44, vcc
	global_store_dwordx4 v[88:89], v[44:47], off offset:64 sc0 sc1
	ds_read_b64 v[2:3], v139 offset:8576
	s_waitcnt lgkmcnt(0)
	v_sub_f32_e32 v45, v75, v2
	v_sub_f32_e32 v44, v74, v2
	v_sub_f32_e32 v47, v73, v2
	v_sub_f32_e32 v46, v72, v2
	v_pk_mul_f32 v[46:47], v[2:3], v[46:47] op_sel:[1,0]
	v_pk_mul_f32 v[2:3], v[2:3], v[44:45] op_sel:[1,0]
	v_pk_fma_f32 v[44:45], v[102:103], v[46:47], v[112:113]
	v_pk_fma_f32 v[2:3], v[104:105], v[2:3], v[114:115]
	v_cndmask_b32_e32 v45, v152, v45, vcc
	v_cndmask_b32_e32 v47, v152, v3, vcc
	v_cndmask_b32_e32 v46, v152, v2, vcc
	v_cndmask_b32_e32 v44, v152, v44, vcc
	global_store_dwordx4 v[82:83], v[44:47], off offset:64 sc0 sc1
	ds_read_b64 v[2:3], v139 offset:9216
	s_waitcnt lgkmcnt(0)
	v_sub_f32_e32 v45, v87, v2
	v_sub_f32_e32 v44, v86, v2
	v_sub_f32_e32 v47, v85, v2
	v_sub_f32_e32 v46, v84, v2
	v_pk_mul_f32 v[46:47], v[2:3], v[46:47] op_sel:[1,0]
	v_pk_mul_f32 v[2:3], v[2:3], v[44:45] op_sel:[1,0]
	v_pk_fma_f32 v[44:45], v[102:103], v[46:47], v[112:113]
	v_pk_fma_f32 v[2:3], v[104:105], v[2:3], v[114:115]
	v_cndmask_b32_e32 v45, v152, v45, vcc
	v_cndmask_b32_e32 v47, v152, v3, vcc
	v_cndmask_b32_e32 v46, v152, v2, vcc
	v_cndmask_b32_e32 v44, v152, v44, vcc
	global_store_dwordx4 v[80:81], v[44:47], off offset:64 sc0 sc1
	ds_read_b64 v[2:3], v139 offset:9344
	s_waitcnt lgkmcnt(0)
	v_sub_f32_e32 v45, v99, v2
	v_sub_f32_e32 v44, v98, v2
	v_sub_f32_e32 v47, v97, v2
	v_sub_f32_e32 v46, v96, v2
	v_pk_mul_f32 v[46:47], v[2:3], v[46:47] op_sel:[1,0]
	v_pk_mul_f32 v[2:3], v[2:3], v[44:45] op_sel:[1,0]
	v_pk_fma_f32 v[44:45], v[102:103], v[46:47], v[112:113]
	v_pk_fma_f32 v[2:3], v[104:105], v[2:3], v[114:115]
	v_cndmask_b32_e32 v45, v152, v45, vcc
	v_cndmask_b32_e32 v47, v152, v3, vcc
	v_cndmask_b32_e32 v46, v152, v2, vcc
	v_cndmask_b32_e32 v44, v152, v44, vcc
	global_store_dwordx4 v[90:91], v[44:47], off offset:64 sc0 sc1
	ds_read_b64 v[2:3], v139 offset:9472
	s_waitcnt lgkmcnt(0)
	v_sub_f32_e32 v45, v111, v2
	v_sub_f32_e32 v44, v110, v2
	v_sub_f32_e32 v47, v109, v2
	v_sub_f32_e32 v46, v108, v2
	v_pk_mul_f32 v[46:47], v[2:3], v[46:47] op_sel:[1,0]
	v_pk_mul_f32 v[2:3], v[2:3], v[44:45] op_sel:[1,0]
	v_pk_fma_f32 v[44:45], v[102:103], v[46:47], v[112:113]
	v_pk_fma_f32 v[2:3], v[104:105], v[2:3], v[114:115]
	v_cndmask_b32_e32 v45, v152, v45, vcc
	v_cndmask_b32_e32 v47, v152, v3, vcc
	v_cndmask_b32_e32 v46, v152, v2, vcc
	v_cndmask_b32_e32 v44, v152, v44, vcc
	global_store_dwordx4 v[100:101], v[44:47], off offset:64 sc0 sc1
	ds_read_b64 v[2:3], v139 offset:9600
	s_nop 0
	v_lshlrev_b64 v[44:45], 2, v[56:57]
	v_lshl_add_u64 v[56:57], v[144:145], 0, v[44:45]
	v_lshl_add_u64 v[58:59], v[142:143], 0, v[44:45]
	s_waitcnt lgkmcnt(0)
	v_sub_f32_e32 v45, v119, v2
	v_sub_f32_e32 v44, v118, v2
	v_sub_f32_e32 v47, v117, v2
	v_sub_f32_e32 v46, v116, v2
	v_pk_mul_f32 v[46:47], v[2:3], v[46:47] op_sel:[1,0]
	v_pk_mul_f32 v[2:3], v[2:3], v[44:45] op_sel:[1,0]
	v_pk_fma_f32 v[44:45], v[102:103], v[46:47], v[112:113]
	v_pk_fma_f32 v[2:3], v[104:105], v[2:3], v[114:115]
	v_cndmask_b32_e32 v45, v152, v45, vcc
	v_cndmask_b32_e32 v47, v152, v3, vcc
	v_cndmask_b32_e32 v46, v152, v2, vcc
	v_cndmask_b32_e32 v44, v152, v44, vcc
	global_store_dwordx4 v[0:1], v[44:47], off offset:64 sc0 sc1
	global_load_dwordx4 v[44:47], v[56:57], off
	s_nop 0
	global_load_dwordx4 v[56:59], v[58:59], off
	ds_read_b64 v[2:3], v139 offset:8192
	s_waitcnt lgkmcnt(0)
	v_sub_f32_e32 v23, v23, v2
	v_sub_f32_e32 v22, v22, v2
	v_sub_f32_e32 v21, v21, v2
	v_sub_f32_e32 v20, v20, v2
	v_pk_mul_f32 v[20:21], v[2:3], v[20:21] op_sel:[1,0]
	v_pk_mul_f32 v[2:3], v[2:3], v[22:23] op_sel:[1,0]
	s_waitcnt vmcnt(0)
	v_pk_fma_f32 v[20:21], v[44:45], v[20:21], v[56:57]
	v_pk_fma_f32 v[2:3], v[46:47], v[2:3], v[58:59]
	v_cndmask_b32_e32 v21, v152, v21, vcc
	v_cndmask_b32_e32 v23, v152, v3, vcc
	v_cndmask_b32_e32 v22, v152, v2, vcc
	v_cndmask_b32_e32 v20, v152, v20, vcc
	global_store_dwordx4 v[148:149], v[20:23], off offset:512 sc0 sc1
	ds_read_b64 v[2:3], v139 offset:8320
	s_waitcnt lgkmcnt(0)
	v_sub_f32_e32 v21, v31, v2
	v_sub_f32_e32 v20, v30, v2
	v_sub_f32_e32 v23, v29, v2
	v_sub_f32_e32 v22, v28, v2
	v_pk_mul_f32 v[22:23], v[2:3], v[22:23] op_sel:[1,0]
	v_pk_mul_f32 v[2:3], v[2:3], v[20:21] op_sel:[1,0]
	v_pk_fma_f32 v[20:21], v[44:45], v[22:23], v[56:57]
	v_pk_fma_f32 v[2:3], v[46:47], v[2:3], v[58:59]
	v_cndmask_b32_e32 v21, v152, v21, vcc
	v_cndmask_b32_e32 v23, v152, v3, vcc
	v_cndmask_b32_e32 v22, v152, v2, vcc
	v_cndmask_b32_e32 v20, v152, v20, vcc
	global_store_dwordx4 v[146:147], v[20:23], off offset:512 sc0 sc1
	ds_read_b64 v[2:3], v139 offset:8448
	v_or_b32_e32 v28, 0x90, v138
	v_ashrrev_i32_e32 v29, 31, v28
	s_waitcnt lgkmcnt(0)
	v_sub_f32_e32 v21, v39, v2
	v_sub_f32_e32 v20, v38, v2
	v_sub_f32_e32 v23, v37, v2
	v_sub_f32_e32 v22, v36, v2
	v_pk_mul_f32 v[22:23], v[2:3], v[22:23] op_sel:[1,0]
	v_pk_mul_f32 v[2:3], v[2:3], v[20:21] op_sel:[1,0]
	v_pk_fma_f32 v[20:21], v[44:45], v[22:23], v[56:57]
	v_pk_fma_f32 v[2:3], v[46:47], v[2:3], v[58:59]
	v_cndmask_b32_e32 v21, v152, v21, vcc
	v_cndmask_b32_e32 v23, v152, v3, vcc
	v_cndmask_b32_e32 v22, v152, v2, vcc
	v_cndmask_b32_e32 v20, v152, v20, vcc
	global_store_dwordx4 v[88:89], v[20:23], off offset:512 sc0 sc1
	ds_read_b64 v[2:3], v139 offset:8576
	s_waitcnt lgkmcnt(0)
; __device__ __forceinline__ unsigned cvt_pk_bf16(float lo, float hi) { unsigned r; asm volatile("v_cvt_pk_bf16_f32 %0, %1, %2" : "=v"(r) : "v"(lo), "v"(hi)); return r; }
;     __device__ __forceinline__ void fused(f32x4 (&acc)[2][2][4][2], const Unit& u, int wr, int wc, int fr, int fq, PG8_LAS unsigned char* lds, int wid, int lane) const {
;     ...
; #pragma unroll
;         for (int bj = 0; bj < 2; ++bj)
; #pragma unroll
;             for (int n = 0; n < 2; ++n) {
;                 const int col = col0 + bj * HALF + n * 16;
;                 const f32x4 lg = *(const f32x4*)(lng + col), lb = *(const f32x4*)(lnb + col);
;                 f32x4 sc1 = (f32x4){1.f, 1.f, 1.f, 1.f}, sh = (f32x4){0.f, 0.f, 0.f, 0.f};
;                 if (DO_U) { sc1 = *(const f32x4*)(msc + mo + col) + 1.0f; sh = *(const f32x4*)(msh + mo + col); }
; #pragma unroll
;                 for (int ai = 0; ai < 2; ++ai)
; #pragma unroll
;                     for (int m = 0; m < 4; ++m) { const int r = ai * HALF + wr * 64 + m * 16 + fr; const f32x2v sr = S[r]; const size_t off = (size_t)(u.pm * BM + r) * 1024 + col;
;                         f32x4 y = (acc[ai][bj][m][n] - sr.x) * sr.y * lg + lb; if (bad) y = (f32x4){qnan, qnan, qnan, qnan};
;                         *(f32x4*)(out + off) = y;
;                         if (DO_U) { const f32x4 uu = y * sc1 + sh; u32x2v w; w.x = cvt_pk_bf16(uu[0], uu[1]); w.y = cvt_pk_bf16(uu[2], uu[3]); *(u32x2v*)(U + off) = w; } }
	v_sub_f32_e32 v21, v43, v2
	v_sub_f32_e32 v20, v42, v2
	v_sub_f32_e32 v23, v41, v2
	v_sub_f32_e32 v22, v40, v2
	v_pk_mul_f32 v[22:23], v[2:3], v[22:23] op_sel:[1,0]
	v_pk_mul_f32 v[2:3], v[2:3], v[20:21] op_sel:[1,0]
	v_pk_fma_f32 v[20:21], v[44:45], v[22:23], v[56:57]
	v_pk_fma_f32 v[2:3], v[46:47], v[2:3], v[58:59]
	v_cndmask_b32_e32 v21, v152, v21, vcc
	v_cndmask_b32_e32 v23, v152, v3, vcc
	v_cndmask_b32_e32 v22, v152, v2, vcc
	v_cndmask_b32_e32 v20, v152, v20, vcc
	global_store_dwordx4 v[82:83], v[20:23], off offset:512 sc0 sc1
	ds_read_b64 v[2:3], v139 offset:9216
	s_waitcnt lgkmcnt(0)
	v_sub_f32_e32 v21, v55, v2
	v_sub_f32_e32 v20, v54, v2
	v_sub_f32_e32 v23, v53, v2
	v_sub_f32_e32 v22, v52, v2
	v_pk_mul_f32 v[22:23], v[2:3], v[22:23] op_sel:[1,0]
	v_pk_mul_f32 v[2:3], v[2:3], v[20:21] op_sel:[1,0]
	v_pk_fma_f32 v[20:21], v[44:45], v[22:23], v[56:57]
	v_pk_fma_f32 v[2:3], v[46:47], v[2:3], v[58:59]
	v_cndmask_b32_e32 v21, v152, v21, vcc
	v_cndmask_b32_e32 v23, v152, v3, vcc
	v_cndmask_b32_e32 v22, v152, v2, vcc
	v_cndmask_b32_e32 v20, v152, v20, vcc
	global_store_dwordx4 v[80:81], v[20:23], off offset:512 sc0 sc1
	ds_read_b64 v[2:3], v139 offset:9344
	s_waitcnt lgkmcnt(0)
	v_sub_f32_e32 v21, v63, v2
	v_sub_f32_e32 v20, v62, v2
	v_sub_f32_e32 v23, v61, v2
	v_sub_f32_e32 v22, v60, v2
	v_pk_mul_f32 v[22:23], v[2:3], v[22:23] op_sel:[1,0]
	v_pk_mul_f32 v[2:3], v[2:3], v[20:21] op_sel:[1,0]
	v_pk_fma_f32 v[20:21], v[44:45], v[22:23], v[56:57]
	v_pk_fma_f32 v[2:3], v[46:47], v[2:3], v[58:59]
	v_cndmask_b32_e32 v21, v152, v21, vcc
	v_cndmask_b32_e32 v23, v152, v3, vcc
	v_cndmask_b32_e32 v22, v152, v2, vcc
	v_cndmask_b32_e32 v20, v152, v20, vcc
	global_store_dwordx4 v[90:91], v[20:23], off offset:512 sc0 sc1
	ds_read_b64 v[2:3], v139 offset:9472
	s_waitcnt lgkmcnt(0)
	v_sub_f32_e32 v21, v79, v2
	v_sub_f32_e32 v20, v78, v2
	v_sub_f32_e32 v23, v77, v2
	v_sub_f32_e32 v22, v76, v2
	v_pk_mul_f32 v[22:23], v[2:3], v[22:23] op_sel:[1,0]
	v_pk_mul_f32 v[2:3], v[2:3], v[20:21] op_sel:[1,0]
	v_pk_fma_f32 v[20:21], v[44:45], v[22:23], v[56:57]
	v_pk_fma_f32 v[2:3], v[46:47], v[2:3], v[58:59]
	v_cndmask_b32_e32 v21, v152, v21, vcc
	v_cndmask_b32_e32 v23, v152, v3, vcc
	v_cndmask_b32_e32 v22, v152, v2, vcc
	v_cndmask_b32_e32 v20, v152, v20, vcc
	global_store_dwordx4 v[100:101], v[20:23], off offset:512 sc0 sc1
	ds_read_b64 v[2:3], v139 offset:9600
	s_nop 0
	v_lshlrev_b64 v[20:21], 2, v[28:29]
	v_lshl_add_u64 v[36:37], v[144:145], 0, v[20:21]
	v_lshl_add_u64 v[38:39], v[142:143], 0, v[20:21]
	s_waitcnt lgkmcnt(0)
	v_sub_f32_e32 v21, v95, v2
	v_sub_f32_e32 v20, v94, v2
	v_sub_f32_e32 v23, v93, v2
	v_sub_f32_e32 v22, v92, v2
	v_pk_mul_f32 v[22:23], v[2:3], v[22:23] op_sel:[1,0]
	v_pk_mul_f32 v[2:3], v[2:3], v[20:21] op_sel:[1,0]
	v_pk_fma_f32 v[20:21], v[44:45], v[22:23], v[56:57]
	v_pk_fma_f32 v[2:3], v[46:47], v[2:3], v[58:59]
	v_cndmask_b32_e32 v21, v152, v21, vcc
	v_cndmask_b32_e32 v23, v152, v3, vcc
	v_cndmask_b32_e32 v22, v152, v2, vcc
	v_cndmask_b32_e32 v20, v152, v20, vcc
	global_store_dwordx4 v[0:1], v[20:23], off offset:512 sc0 sc1
	global_load_dwordx4 v[20:23], v[36:37], off
	s_nop 0
	global_load_dwordx4 v[28:31], v[38:39], off
	ds_read_b64 v[2:3], v139 offset:8192
	s_waitcnt lgkmcnt(0)
	v_sub_f32_e32 v7, v7, v2
	v_sub_f32_e32 v6, v6, v2
	v_sub_f32_e32 v5, v5, v2
	v_sub_f32_e32 v4, v4, v2
	v_pk_mul_f32 v[4:5], v[2:3], v[4:5] op_sel:[1,0]
	v_pk_mul_f32 v[2:3], v[2:3], v[6:7] op_sel:[1,0]
	s_waitcnt vmcnt(0)
	v_pk_fma_f32 v[6:7], v[20:21], v[4:5], v[28:29]
	v_pk_fma_f32 v[2:3], v[22:23], v[2:3], v[30:31]
	s_nop 0
	v_cndmask_b32_e32 v5, v152, v3, vcc
	v_cndmask_b32_e32 v4, v152, v2, vcc
	v_cndmask_b32_e32 v3, v152, v7, vcc
	v_cndmask_b32_e32 v2, v152, v6, vcc
	global_store_dwordx4 v[148:149], v[2:5], off offset:576 sc0 sc1
	ds_read_b64 v[2:3], v139 offset:8320
	s_waitcnt lgkmcnt(0)
; __device__ __forceinline__ unsigned cvt_pk_bf16(float lo, float hi) { unsigned r; asm volatile("v_cvt_pk_bf16_f32 %0, %1, %2" : "=v"(r) : "v"(lo), "v"(hi)); return r; }
;     __device__ __forceinline__ void fused(f32x4 (&acc)[2][2][4][2], const Unit& u, int wr, int wc, int fr, int fq, PG8_LAS unsigned char* lds, int wid, int lane) const {
;     ...
; #pragma unroll
;         for (int bj = 0; bj < 2; ++bj)
; #pragma unroll
;             for (int n = 0; n < 2; ++n) {
;                 const int col = col0 + bj * HALF + n * 16;
;                 const f32x4 lg = *(const f32x4*)(lng + col), lb = *(const f32x4*)(lnb + col);
;                 f32x4 sc1 = (f32x4){1.f, 1.f, 1.f, 1.f}, sh = (f32x4){0.f, 0.f, 0.f, 0.f};
;                 if (DO_U) { sc1 = *(const f32x4*)(msc + mo + col) + 1.0f; sh = *(const f32x4*)(msh + mo + col); }
; #pragma unroll
;                 for (int ai = 0; ai < 2; ++ai)
; #pragma unroll
;                     for (int m = 0; m < 4; ++m) { const int r = ai * HALF + wr * 64 + m * 16 + fr; const f32x2v sr = S[r]; const size_t off = (size_t)(u.pm * BM + r) * 1024 + col;
;                         f32x4 y = (acc[ai][bj][m][n] - sr.x) * sr.y * lg + lb; if (bad) y = (f32x4){qnan, qnan, qnan, qnan};
;                         *(f32x4*)(out + off) = y;
;                         if (DO_U) { const f32x4 uu = y * sc1 + sh; u32x2v w; w.x = cvt_pk_bf16(uu[0], uu[1]); w.y = cvt_pk_bf16(uu[2], uu[3]); *(u32x2v*)(U + off) = w; } }
	v_sub_f32_e32 v7, v9, v2
	v_sub_f32_e32 v5, v11, v2
	v_sub_f32_e32 v4, v10, v2
	v_sub_f32_e32 v6, v8, v2
	v_pk_mul_f32 v[6:7], v[2:3], v[6:7] op_sel:[1,0]
	v_pk_mul_f32 v[2:3], v[2:3], v[4:5] op_sel:[1,0]
	v_pk_fma_f32 v[6:7], v[20:21], v[6:7], v[28:29]
	v_pk_fma_f32 v[2:3], v[22:23], v[2:3], v[30:31]
	s_nop 0
	v_cndmask_b32_e32 v5, v152, v3, vcc
	v_cndmask_b32_e32 v4, v152, v2, vcc
	v_cndmask_b32_e32 v3, v152, v7, vcc
	v_cndmask_b32_e32 v2, v152, v6, vcc
	global_store_dwordx4 v[146:147], v[2:5], off offset:576 sc0 sc1
	ds_read_b64 v[2:3], v139 offset:8448
	s_waitcnt lgkmcnt(0)
	v_sub_f32_e32 v7, v13, v2
	v_sub_f32_e32 v5, v15, v2
	v_sub_f32_e32 v4, v14, v2
	v_sub_f32_e32 v6, v12, v2
	v_pk_mul_f32 v[6:7], v[2:3], v[6:7] op_sel:[1,0]
	v_pk_mul_f32 v[2:3], v[2:3], v[4:5] op_sel:[1,0]
	v_pk_fma_f32 v[6:7], v[20:21], v[6:7], v[28:29]
	v_pk_fma_f32 v[2:3], v[22:23], v[2:3], v[30:31]
	s_nop 0
	v_cndmask_b32_e32 v5, v152, v3, vcc
	v_cndmask_b32_e32 v4, v152, v2, vcc
	v_cndmask_b32_e32 v3, v152, v7, vcc
	v_cndmask_b32_e32 v2, v152, v6, vcc
	global_store_dwordx4 v[88:89], v[2:5], off offset:576 sc0 sc1
	ds_read_b64 v[2:3], v139 offset:8576
	s_waitcnt lgkmcnt(0)
	v_sub_f32_e32 v7, v17, v2
	v_sub_f32_e32 v5, v19, v2
	v_sub_f32_e32 v4, v18, v2
	v_sub_f32_e32 v6, v16, v2
	v_pk_mul_f32 v[6:7], v[2:3], v[6:7] op_sel:[1,0]
	v_pk_mul_f32 v[2:3], v[2:3], v[4:5] op_sel:[1,0]
	v_pk_fma_f32 v[6:7], v[20:21], v[6:7], v[28:29]
	v_pk_fma_f32 v[2:3], v[22:23], v[2:3], v[30:31]
	s_nop 0
	v_cndmask_b32_e32 v5, v152, v3, vcc
	v_cndmask_b32_e32 v4, v152, v2, vcc
	v_cndmask_b32_e32 v3, v152, v7, vcc
	v_cndmask_b32_e32 v2, v152, v6, vcc
	global_store_dwordx4 v[82:83], v[2:5], off offset:576 sc0 sc1
	ds_read_b64 v[2:3], v139 offset:9216
	s_waitcnt lgkmcnt(0)
	v_sub_f32_e32 v7, v25, v2
	v_sub_f32_e32 v5, v27, v2
	v_sub_f32_e32 v4, v26, v2
	v_sub_f32_e32 v6, v24, v2
	v_pk_mul_f32 v[6:7], v[2:3], v[6:7] op_sel:[1,0]
	v_pk_mul_f32 v[2:3], v[2:3], v[4:5] op_sel:[1,0]
	v_pk_fma_f32 v[6:7], v[20:21], v[6:7], v[28:29]
	v_pk_fma_f32 v[2:3], v[22:23], v[2:3], v[30:31]
	s_nop 0
	v_cndmask_b32_e32 v5, v152, v3, vcc
	v_cndmask_b32_e32 v4, v152, v2, vcc
	v_cndmask_b32_e32 v3, v152, v7, vcc
	v_cndmask_b32_e32 v2, v152, v6, vcc
	global_store_dwordx4 v[80:81], v[2:5], off offset:576 sc0 sc1
	ds_read_b64 v[2:3], v139 offset:9344
	s_waitcnt lgkmcnt(0)
	v_sub_f32_e32 v7, v33, v2
	v_sub_f32_e32 v5, v35, v2
	v_sub_f32_e32 v4, v34, v2
	v_sub_f32_e32 v6, v32, v2
	v_pk_mul_f32 v[6:7], v[2:3], v[6:7] op_sel:[1,0]
	v_pk_mul_f32 v[2:3], v[2:3], v[4:5] op_sel:[1,0]
	v_pk_fma_f32 v[6:7], v[20:21], v[6:7], v[28:29]
	v_pk_fma_f32 v[2:3], v[22:23], v[2:3], v[30:31]
	s_nop 0
	v_cndmask_b32_e32 v5, v152, v3, vcc
	v_cndmask_b32_e32 v4, v152, v2, vcc
	v_cndmask_b32_e32 v3, v152, v7, vcc
	v_cndmask_b32_e32 v2, v152, v6, vcc
	global_store_dwordx4 v[90:91], v[2:5], off offset:576 sc0 sc1
	ds_read_b64 v[2:3], v139 offset:9472
	s_waitcnt lgkmcnt(0)
	v_sub_f32_e32 v7, v49, v2
	v_sub_f32_e32 v5, v51, v2
	v_sub_f32_e32 v4, v50, v2
	v_sub_f32_e32 v6, v48, v2
	v_pk_mul_f32 v[6:7], v[2:3], v[6:7] op_sel:[1,0]
	v_pk_mul_f32 v[2:3], v[2:3], v[4:5] op_sel:[1,0]
	v_pk_fma_f32 v[6:7], v[20:21], v[6:7], v[28:29]
	v_pk_fma_f32 v[2:3], v[22:23], v[2:3], v[30:31]
	s_nop 0
	v_cndmask_b32_e32 v5, v152, v3, vcc
	v_cndmask_b32_e32 v4, v152, v2, vcc
	v_cndmask_b32_e32 v3, v152, v7, vcc
	v_cndmask_b32_e32 v2, v152, v6, vcc
	global_store_dwordx4 v[100:101], v[2:5], off offset:576 sc0 sc1
	ds_read_b64 v[2:3], v139 offset:9600
	s_waitcnt lgkmcnt(0)
	v_sub_f32_e32 v7, v65, v2
	v_sub_f32_e32 v5, v67, v2
	v_sub_f32_e32 v4, v66, v2
	v_sub_f32_e32 v6, v64, v2
	v_pk_mul_f32 v[6:7], v[2:3], v[6:7] op_sel:[1,0]
	v_pk_mul_f32 v[2:3], v[2:3], v[4:5] op_sel:[1,0]
	v_pk_fma_f32 v[6:7], v[20:21], v[6:7], v[28:29]
	v_pk_fma_f32 v[2:3], v[22:23], v[2:3], v[30:31]
	s_nop 0
	v_cndmask_b32_e32 v5, v152, v3, vcc
	v_cndmask_b32_e32 v4, v152, v2, vcc
	v_cndmask_b32_e32 v3, v152, v7, vcc
	v_cndmask_b32_e32 v2, v152, v6, vcc
	global_store_dwordx4 v[0:1], v[2:5], off offset:576 sc0 sc1
